# LDS-read hoisting with counted waits in chain/FFT/S5/prep loops; EpiResid epilogue loads batched; prep solve pipelined
# speedup vs baseline: 1.0092x; 1.0092x over previous
.LBB0_28:
	ds_read2_b64 v[120:123], v1 offset1:17
	v_add_u32_e32 v110, s10, v63
	ds_read_b128 v[22:25], v73
	ds_read_b128 v[26:29], v73 offset:16
	ds_read_b128 v[30:33], v73 offset:32
	ds_read_b128 v[34:37], v73 offset:48
	ds_read_b128 v[38:41], v73 offset:64
	ds_read_b128 v[42:45], v73 offset:80
	ds_read_b128 v[46:49], v73 offset:96
	ds_read_b128 v[74:77], v73 offset:112
	ds_read_b128 v[78:81], v73 offset:128
	ds_read_b128 v[82:85], v73 offset:144
	ds_read_b128 v[86:89], v73 offset:160
	ds_read_b128 v[90:93], v73 offset:176
	ds_read_b128 v[94:97], v73 offset:192
	ds_read_b128 v[98:101], v73 offset:208
	s_waitcnt lgkmcnt(14)
	ds_read_b128 v[102:105], v73 offset:224
	s_waitcnt lgkmcnt(14)
	ds_read_b128 v[106:109], v73 offset:240
	s_waitcnt lgkmcnt(14)
	ds_read2_b64 v[110:113], v110 offset1:1
	v_xor_b32_e32 v116, 0x80000000, v121
	v_mov_b32_e32 v117, v120
	v_xor_b32_e32 v114, 0x80000000, v123
	v_mov_b32_e32 v115, v122
	v_mov_b32_e32 v118, v22
	v_mov_b32_e32 v22, v26
	s_waitcnt lgkmcnt(14)
	v_mov_b32_e32 v26, v30
	s_waitcnt lgkmcnt(13)
	v_mov_b32_e32 v30, v34
	s_waitcnt lgkmcnt(12)
	v_mov_b32_e32 v34, v38
	s_waitcnt lgkmcnt(11)
	v_mov_b32_e32 v38, v42
	s_waitcnt lgkmcnt(10)
	v_mov_b32_e32 v42, v46
	s_waitcnt lgkmcnt(9)
	v_mov_b32_e32 v46, v74
	s_waitcnt lgkmcnt(8)
	v_mov_b32_e32 v74, v78
	s_waitcnt lgkmcnt(7)
	v_mov_b32_e32 v78, v82
	s_waitcnt lgkmcnt(6)
	v_mov_b32_e32 v82, v86
	s_waitcnt lgkmcnt(5)
	v_mov_b32_e32 v86, v90
	s_waitcnt lgkmcnt(4)
	v_mov_b32_e32 v90, v94
	s_waitcnt lgkmcnt(3)
	v_mov_b32_e32 v94, v98
	s_waitcnt lgkmcnt(2)
	v_mov_b32_e32 v98, v102
	s_waitcnt lgkmcnt(1)
	v_mov_b32_e32 v102, v106
	s_waitcnt lgkmcnt(0)
	v_mov_b32_e32 v106, v113
	v_pk_mul_f32 v[116:117], v[110:111], v[116:117] op_sel:[1,0]
	v_mov_b32_e32 v119, v24
	v_mov_b32_e32 v24, v23
	v_mov_b32_e32 v23, v28
	v_mov_b32_e32 v28, v27
	v_mov_b32_e32 v27, v32
	v_mov_b32_e32 v32, v31
	v_mov_b32_e32 v31, v36
	v_mov_b32_e32 v36, v35
	v_mov_b32_e32 v35, v40
	v_mov_b32_e32 v40, v39
	v_mov_b32_e32 v39, v44
	v_mov_b32_e32 v44, v43
	v_mov_b32_e32 v43, v48
	v_mov_b32_e32 v48, v47
	v_mov_b32_e32 v47, v76
	v_mov_b32_e32 v76, v75
	v_mov_b32_e32 v75, v80
	v_mov_b32_e32 v80, v79
	v_mov_b32_e32 v79, v84
	v_mov_b32_e32 v84, v83
	v_mov_b32_e32 v83, v88
	v_mov_b32_e32 v88, v87
	v_mov_b32_e32 v87, v92
	v_mov_b32_e32 v92, v91
	v_mov_b32_e32 v91, v96
	v_mov_b32_e32 v96, v95
	v_mov_b32_e32 v95, v100
	v_mov_b32_e32 v100, v99
	v_mov_b32_e32 v99, v104
	v_mov_b32_e32 v104, v103
	v_mov_b32_e32 v103, v108
	v_mov_b32_e32 v108, v107
	v_pk_mul_f32 v[106:107], v[106:107], v[114:115] op_sel_hi:[0,1]
	v_pk_fma_f32 v[18:19], v[110:111], v[120:121], v[116:117] op_sel_hi:[0,1,1]
	v_pk_fma_f32 v[20:21], v[112:113], v[122:123], v[106:107] op_sel_hi:[0,1,1]
	v_pk_mul_f32 v[24:25], v[24:25], v[18:19] op_sel:[0,1]
	v_pk_mul_f32 v[28:29], v[28:29], v[18:19] op_sel:[0,1]
	v_pk_mul_f32 v[32:33], v[18:19], v[32:33] op_sel:[1,0]
	v_pk_mul_f32 v[36:37], v[18:19], v[36:37] op_sel:[1,0]
	v_pk_mul_f32 v[40:41], v[18:19], v[40:41] op_sel:[1,0]
	v_pk_mul_f32 v[44:45], v[18:19], v[44:45] op_sel:[1,0]
	v_pk_mul_f32 v[48:49], v[18:19], v[48:49] op_sel:[1,0]
	v_pk_mul_f32 v[76:77], v[18:19], v[76:77] op_sel:[1,0]
	v_pk_fma_f32 v[24:25], v[118:119], v[18:19], v[24:25] op_sel_hi:[1,0,1] neg_lo:[0,0,1] neg_hi:[0,0,1]
	v_pk_fma_f32 v[22:23], v[22:23], v[18:19], v[28:29] op_sel_hi:[1,0,1] neg_lo:[0,0,1] neg_hi:[0,0,1]
	v_pk_fma_f32 v[26:27], v[18:19], v[26:27], v[32:33] op_sel_hi:[0,1,1] neg_lo:[0,0,1] neg_hi:[0,0,1]
	v_pk_fma_f32 v[28:29], v[18:19], v[30:31], v[36:37] op_sel_hi:[0,1,1] neg_lo:[0,0,1] neg_hi:[0,0,1]
	v_pk_fma_f32 v[30:31], v[18:19], v[34:35], v[40:41] op_sel_hi:[0,1,1] neg_lo:[0,0,1] neg_hi:[0,0,1]
	v_pk_fma_f32 v[32:33], v[18:19], v[38:39], v[44:45] op_sel_hi:[0,1,1] neg_lo:[0,0,1] neg_hi:[0,0,1]
	v_pk_fma_f32 v[34:35], v[18:19], v[42:43], v[48:49] op_sel_hi:[0,1,1] neg_lo:[0,0,1] neg_hi:[0,0,1]
	v_pk_fma_f32 v[18:19], v[18:19], v[46:47], v[76:77] op_sel_hi:[0,1,1] neg_lo:[0,0,1] neg_hi:[0,0,1]
	v_pk_mul_f32 v[36:37], v[80:81], v[20:21] op_sel:[0,1]
	v_pk_mul_f32 v[38:39], v[84:85], v[20:21] op_sel:[0,1]
	v_pk_mul_f32 v[40:41], v[20:21], v[88:89] op_sel:[1,0]
	v_pk_mul_f32 v[42:43], v[20:21], v[92:93] op_sel:[1,0]
	v_pk_mul_f32 v[44:45], v[20:21], v[96:97] op_sel:[1,0]
	v_pk_mul_f32 v[46:47], v[20:21], v[100:101] op_sel:[1,0]
	v_pk_mul_f32 v[48:49], v[20:21], v[104:105] op_sel:[1,0]
	v_pk_mul_f32 v[76:77], v[20:21], v[108:109] op_sel:[1,0]
	s_add_i32 s10, s10, 16
	v_pk_add_f32 v[2:3], v[2:3], v[24:25]
	v_pk_add_f32 v[4:5], v[4:5], v[22:23]
	v_pk_add_f32 v[14:15], v[14:15], v[26:27]
	v_pk_add_f32 v[16:17], v[16:17], v[28:29]
	v_pk_add_f32 v[10:11], v[10:11], v[30:31]
	v_pk_add_f32 v[12:13], v[12:13], v[32:33]
	v_pk_add_f32 v[6:7], v[6:7], v[34:35]
	v_pk_add_f32 v[8:9], v[8:9], v[18:19]
	v_pk_fma_f32 v[18:19], v[74:75], v[20:21], v[36:37] op_sel_hi:[1,0,1] neg_lo:[0,0,1] neg_hi:[0,0,1]
	v_pk_fma_f32 v[22:23], v[78:79], v[20:21], v[38:39] op_sel_hi:[1,0,1] neg_lo:[0,0,1] neg_hi:[0,0,1]
	v_pk_fma_f32 v[24:25], v[20:21], v[82:83], v[40:41] op_sel_hi:[0,1,1] neg_lo:[0,0,1] neg_hi:[0,0,1]
	v_pk_fma_f32 v[26:27], v[20:21], v[86:87], v[42:43] op_sel_hi:[0,1,1] neg_lo:[0,0,1] neg_hi:[0,0,1]
	v_pk_fma_f32 v[28:29], v[20:21], v[90:91], v[44:45] op_sel_hi:[0,1,1] neg_lo:[0,0,1] neg_hi:[0,0,1]
	v_pk_fma_f32 v[30:31], v[20:21], v[94:95], v[46:47] op_sel_hi:[0,1,1] neg_lo:[0,0,1] neg_hi:[0,0,1]
	v_pk_fma_f32 v[32:33], v[20:21], v[98:99], v[48:49] op_sel_hi:[0,1,1] neg_lo:[0,0,1] neg_hi:[0,0,1]
	v_pk_fma_f32 v[20:21], v[20:21], v[102:103], v[76:77] op_sel_hi:[0,1,1] neg_lo:[0,0,1] neg_hi:[0,0,1]
	v_add_u32_e32 v73, 0x100, v73
	v_add_u32_e32 v1, 0x110, v1
	s_cmpk_lg_i32 s10, 0x200
	v_pk_add_f32 v[2:3], v[2:3], v[18:19]
	v_pk_add_f32 v[4:5], v[4:5], v[22:23]
	v_pk_add_f32 v[14:15], v[14:15], v[24:25]
	v_pk_add_f32 v[16:17], v[16:17], v[26:27]
	v_pk_add_f32 v[10:11], v[10:11], v[28:29]
	v_pk_add_f32 v[12:13], v[12:13], v[30:31]
	v_pk_add_f32 v[6:7], v[6:7], v[32:33]
	v_pk_add_f32 v[8:9], v[8:9], v[20:21]
	s_cbranch_scc1 .LBB0_28
	ds_write_b128 v68, v[2:5] offset:50432
	ds_write_b128 v68, v[14:17] offset:50448
	ds_write_b128 v68, v[10:13] offset:50464
	ds_write_b128 v68, v[6:9] offset:50480
	s_lshl_b32 s22, s75, 8
	v_lshlrev_b32_e32 v2, 1, v54
	s_waitcnt lgkmcnt(0)
	s_barrier
	s_and_saveexec_b64 s[12:13], s[4:5]
	s_cbranch_execz .LBB0_32
	s_load_dwordx16 s[44:59], s[0:1], 0x160
	s_and_b64 s[10:11], s[20:21], exec
	v_mov_b32_e32 v3, v0
	v_mov_b32_e32 v1, v51
	s_waitcnt lgkmcnt(0)
	s_cselect_b32 s11, s57, s51
	s_cselect_b32 s10, s56, s50
	s_lshl_b32 s14, s22, 9
	s_add_u32 s10, s10, s14
	s_addc_u32 s11, s11, 0
	v_lshl_add_u64 v[4:5], s[10:11], 0, v[2:3]
	s_mov_b64 s[14:15], 0
.LBB0_31:
	s_movk_i32 s10, 0x400
	v_bfe_u32 v3, v1, 4, 6
	v_ashrrev_i32_e32 v6, 10, v1
	v_cmp_gt_u32_e64 s[10:11], s10, v1
	v_lshl_or_b32 v9, v6, 6, v3
	v_add_u32_e32 v7, 0x200, v1
	v_cndmask_b32_e64 v8, v53, v55, s[10:11]
	s_movk_i32 s10, 0x88
	v_lshl_or_b32 v34, v6, 7, v3
	v_lshlrev_b32_e32 v3, 3, v8
	v_mul_lo_u32 v6, v9, s10
	v_lshl_add_u32 v36, v9, 7, 0
	ds_read_b128 v[120:123], v36 offset:17424
	ds_read_b128 v[124:127], v36 offset:17440
	ds_read_b128 v[128:131], v36 offset:17456
	ds_read_b128 v[132:135], v36 offset:17472
	ds_read_b128 v[136:139], v36 offset:17488
	ds_read_b128 v[140:143], v36 offset:17504
	ds_read_b128 v[144:147], v36 offset:17520
	v_cmp_lt_i32_e32 vcc, s72, v1
	v_mov_b32_e32 v1, v7
	v_ashrrev_i32_e32 v35, 31, v34
	v_add3_u32 v3, 0, v6, v3
	v_lshlrev_b64 v[38:39], 9, v[34:35]
	ds_read_b128 v[34:37], v36 offset:17408
	ds_read_b64 v[40:41], v3
	s_waitcnt lgkmcnt(8)
	v_xor_b32_e32 v44, 0x80000000, v121
	v_mov_b32_e32 v45, v120
	v_xor_b32_e32 v46, 0x80000000, v123
	v_mov_b32_e32 v47, v122
	s_waitcnt lgkmcnt(7)
	v_xor_b32_e32 v48, 0x80000000, v125
	v_mov_b32_e32 v49, v124
	v_xor_b32_e32 v74, 0x80000000, v127
	v_mov_b32_e32 v75, v126
	s_waitcnt lgkmcnt(6)
	v_xor_b32_e32 v76, 0x80000000, v129
	v_mov_b32_e32 v77, v128
	v_xor_b32_e32 v78, 0x80000000, v131
	v_mov_b32_e32 v79, v130
	s_waitcnt lgkmcnt(5)
	v_xor_b32_e32 v80, 0x80000000, v133
	v_mov_b32_e32 v81, v132
	v_xor_b32_e32 v82, 0x80000000, v135
	v_mov_b32_e32 v83, v134
	s_waitcnt lgkmcnt(4)
	v_xor_b32_e32 v84, 0x80000000, v137
	v_mov_b32_e32 v85, v136
	v_xor_b32_e32 v86, 0x80000000, v139
	v_mov_b32_e32 v87, v138
	s_waitcnt lgkmcnt(3)
	v_xor_b32_e32 v88, 0x80000000, v141
	v_mov_b32_e32 v89, v140
	v_xor_b32_e32 v90, 0x80000000, v143
	v_mov_b32_e32 v91, v142
	s_waitcnt lgkmcnt(2)
	v_xor_b32_e32 v92, 0x80000000, v145
	v_mov_b32_e32 v93, v144
	v_xor_b32_e32 v94, 0x80000000, v147
	v_mov_b32_e32 v95, v146
	s_waitcnt lgkmcnt(1)
	v_xor_b32_e32 v96, 0x80000000, v35
	v_mov_b32_e32 v97, v34
	v_xor_b32_e32 v98, 0x80000000, v37
	v_mov_b32_e32 v99, v36
	s_waitcnt lgkmcnt(0)
	v_pk_mul_f32 v[44:45], v[40:41], v[44:45] op_sel:[1,0]
	v_pk_mul_f32 v[46:47], v[40:41], v[46:47] op_sel:[1,0]
	v_pk_mul_f32 v[48:49], v[40:41], v[48:49] op_sel:[1,0]
	v_pk_mul_f32 v[74:75], v[40:41], v[74:75] op_sel:[1,0]
	v_pk_mul_f32 v[76:77], v[40:41], v[76:77] op_sel:[1,0]
	v_pk_mul_f32 v[78:79], v[40:41], v[78:79] op_sel:[1,0]
	v_pk_mul_f32 v[80:81], v[40:41], v[80:81] op_sel:[1,0]
	v_pk_mul_f32 v[82:83], v[40:41], v[82:83] op_sel:[1,0]
	v_pk_mul_f32 v[84:85], v[40:41], v[84:85] op_sel:[1,0]
	v_pk_mul_f32 v[86:87], v[40:41], v[86:87] op_sel:[1,0]
	v_pk_mul_f32 v[88:89], v[40:41], v[88:89] op_sel:[1,0]
	v_pk_mul_f32 v[90:91], v[40:41], v[90:91] op_sel:[1,0]
	v_pk_mul_f32 v[92:93], v[40:41], v[92:93] op_sel:[1,0]
	v_pk_mul_f32 v[94:95], v[40:41], v[94:95] op_sel:[1,0]
	v_lshl_add_u64 v[38:39], v[4:5], 0, v[38:39]
	v_pk_mul_f32 v[96:97], v[40:41], v[96:97] op_sel:[1,0]
	v_pk_mul_f32 v[98:99], v[40:41], v[98:99] op_sel:[1,0]
	v_pk_fma_f32 v[44:45], v[40:41], v[120:121], v[44:45] op_sel_hi:[0,1,1]
	v_pk_fma_f32 v[8:9], v[40:41], v[122:123], v[46:47] op_sel_hi:[0,1,1]
	v_pk_fma_f32 v[46:47], v[40:41], v[124:125], v[48:49] op_sel_hi:[0,1,1]
	v_pk_fma_f32 v[12:13], v[40:41], v[126:127], v[74:75] op_sel_hi:[0,1,1]
	v_pk_fma_f32 v[14:15], v[40:41], v[128:129], v[76:77] op_sel_hi:[0,1,1]
	v_pk_fma_f32 v[16:17], v[40:41], v[130:131], v[78:79] op_sel_hi:[0,1,1]
	v_pk_fma_f32 v[18:19], v[40:41], v[132:133], v[80:81] op_sel_hi:[0,1,1]
	v_pk_fma_f32 v[20:21], v[40:41], v[134:135], v[82:83] op_sel_hi:[0,1,1]
	v_pk_fma_f32 v[22:23], v[40:41], v[136:137], v[84:85] op_sel_hi:[0,1,1]
	v_pk_fma_f32 v[24:25], v[40:41], v[138:139], v[86:87] op_sel_hi:[0,1,1]
	v_pk_fma_f32 v[26:27], v[40:41], v[140:141], v[88:89] op_sel_hi:[0,1,1]
	v_pk_fma_f32 v[28:29], v[40:41], v[142:143], v[90:91] op_sel_hi:[0,1,1]
	v_pk_fma_f32 v[30:31], v[40:41], v[144:145], v[92:93] op_sel_hi:[0,1,1]
	v_pk_fma_f32 v[32:33], v[40:41], v[146:147], v[94:95] op_sel_hi:[0,1,1]
	s_or_b64 s[14:15], vcc, s[14:15]
	v_add_co_u32_e32 v42, vcc, 0x8000, v38
	v_pk_fma_f32 v[34:35], v[40:41], v[34:35], v[96:97] op_sel_hi:[0,1,1]
	v_pk_fma_f32 v[36:37], v[40:41], v[36:37], v[98:99] op_sel_hi:[0,1,1]
	v_cvt_pk_bf16_f32 v7, v44, v8
	v_cvt_pk_bf16_f32 v11, v45, v9
	v_cvt_pk_bf16_f32 v8, v46, v12
	v_cvt_pk_bf16_f32 v12, v47, v13
	v_cvt_pk_bf16_f32 v9, v14, v16
	v_cvt_pk_bf16_f32 v13, v15, v17
	v_cvt_pk_bf16_f32 v14, v18, v20
	v_cvt_pk_bf16_f32 v15, v22, v24
	v_cvt_pk_bf16_f32 v16, v26, v28
	v_cvt_pk_bf16_f32 v17, v30, v32
	v_addc_co_u32_e32 v43, vcc, 0, v39, vcc
	v_cvt_pk_bf16_f32 v18, v19, v21
	v_cvt_pk_bf16_f32 v19, v23, v25
	v_cvt_pk_bf16_f32 v20, v27, v29
	v_cvt_pk_bf16_f32 v21, v31, v33
	v_cvt_pk_bf16_f32 v6, v34, v36
	v_cvt_pk_bf16_f32 v10, v35, v37
	global_store_dwordx4 v[38:39], v[14:17], off offset:16
	global_store_dwordx4 v[42:43], v[18:21], off offset:16
	global_store_dwordx4 v[38:39], v[6:9], off
	global_store_dwordx4 v[42:43], v[10:13], off
	s_andn2_b64 exec, exec, s[14:15]
	s_cbranch_execnz .LBB0_31

.LBB0_35:
	v_mov_b32_e32 v2, v0
	v_mov_b32_e32 v3, v0
	v_mov_b32_e32 v4, v0
	v_mov_b32_e32 v5, v0
	v_mov_b32_e32 v6, v0
	v_mov_b32_e32 v7, v0
	v_mov_b32_e32 v8, v0
	v_mov_b32_e32 v9, v0
	v_mov_b32_e32 v10, v0
	v_mov_b32_e32 v11, v0
	v_mov_b32_e32 v12, v0
	v_mov_b32_e32 v13, v0
	v_mov_b32_e32 v14, v0
	v_mov_b32_e32 v15, v0
	v_bfe_u32 v21, v20, 4, 4
	v_ashrrev_i32_e32 v22, 8, v20
	v_mov_b32_e32 v1, v0
	v_mov_b64_e32 v[16:17], v[14:15]
	v_cmp_ge_i32_e32 vcc, v22, v53
	v_lshlrev_b32_e32 v23, 6, v21
	v_mov_b64_e32 v[14:15], v[12:13]
	v_mov_b64_e32 v[12:13], v[10:11]
	v_mov_b64_e32 v[10:11], v[8:9]
	v_mov_b64_e32 v[8:9], v[6:7]
	v_mov_b64_e32 v[6:7], v[4:5]
	v_mov_b64_e32 v[4:5], v[2:3]
	v_mov_b64_e32 v[2:3], v[0:1]
	s_and_saveexec_b64 s[22:23], vcc
	s_cbranch_execz .LBB0_37
	v_sub_u32_e32 v1, v22, v53
	v_lshlrev_b32_e32 v1, 10, v1
	v_add3_u32 v1, 0, v1, v23
	ds_read_b128 v[120:123], v1 offset:50480
	ds_read_b128 v[124:127], v1 offset:50464
	ds_read_b128 v[24:27], v1 offset:50448
	ds_read_b128 v[28:31], v1 offset:50432
	s_waitcnt lgkmcnt(3)
	v_pk_add_f32 v[16:17], v[122:123], 0 op_sel_hi:[1,0]
	s_waitcnt lgkmcnt(2)
	v_pk_add_f32 v[12:13], v[126:127], 0 op_sel_hi:[1,0]
	s_waitcnt lgkmcnt(1)
	v_pk_add_f32 v[8:9], v[26:27], 0 op_sel_hi:[1,0]
	s_waitcnt lgkmcnt(0)
	v_pk_add_f32 v[4:5], v[30:31], 0 op_sel_hi:[1,0]
	v_pk_add_f32 v[14:15], v[120:121], 0 op_sel_hi:[1,0]
	v_pk_add_f32 v[10:11], v[124:125], 0 op_sel_hi:[1,0]
	v_pk_add_f32 v[6:7], v[24:25], 0 op_sel_hi:[1,0]
	v_pk_add_f32 v[2:3], v[28:29], 0 op_sel_hi:[1,0]

.LBB0_42:
	v_bfe_u32 v3, v1, 3, 1
	v_bfe_u32 v2, v1, 4, 4
	v_ashrrev_i32_e32 v4, 8, v1
	v_cmp_lt_i32_e32 vcc, s73, v1
	v_add_u32_e32 v5, 0x200, v1
	v_add_u32_e32 v6, 1, v4
	v_sub_u32_e32 v7, 16, v4
	v_lshl_or_b32 v8, v3, 4, v2
	v_lshlrev_b32_e32 v9, 6, v3
	s_or_b64 s[14:15], vcc, s[14:15]
	v_cmp_eq_u32_e32 vcc, 0, v3
	v_lshl_or_b32 v2, v4, 4, v2
	v_mov_b32_e32 v1, v5
	v_cndmask_b32_e32 v4, v7, v6, vcc
	v_mad_u32_u24 v5, v8, s33, v60
	v_or_b32_e32 v6, v9, v56
	v_or_b32_e32 v7, v9, v57
	v_or_b32_e32 v8, v9, v58
	v_or_b32_e32 v9, v9, v59
	v_lshlrev_b32_e32 v18, 8, v3
	v_ashrrev_i32_e32 v3, 31, v2
	v_lshlrev_b32_e32 v24, 3, v4
	v_add_u32_e32 v4, 0x8400, v5
	v_mul_u32_u24_e32 v6, 17, v6
	v_mul_u32_u24_e32 v7, 17, v7
	v_mul_u32_u24_e32 v14, 17, v8
	v_mul_u32_u24_e32 v16, 17, v9
	v_add_u32_e32 v12, 0x8410, v5
	v_add_u32_e32 v13, 0x8420, v5
	ds_read2_b64 v[120:123], v13 offset1:1
	v_add_u32_e32 v15, 0x8430, v5
	v_lshlrev_b64 v[10:11], 10, v[2:3]
	v_add_u32_e32 v25, 0, v24
	ds_read2_b64 v[2:5], v4 offset1:1
	v_lshlrev_b32_e32 v26, 3, v6
	v_lshlrev_b32_e32 v27, 3, v7
	v_lshlrev_b32_e32 v28, 3, v14
	v_lshlrev_b32_e32 v29, 3, v16
	v_mov_b32_e32 v19, v0
	v_lshl_add_u64 v[22:23], s[12:13], 0, v[10:11]
	v_add_u32_e32 v30, v25, v26
	v_add3_u32 v26, 0, v26, v24
	v_add_u32_e32 v31, v25, v27
	v_add3_u32 v32, 0, v27, v24
	v_add_u32_e32 v33, v25, v28
	v_add3_u32 v34, 0, v28, v24
	v_add_u32_e32 v35, v25, v29
	v_add3_u32 v36, 0, v29, v24
	ds_read2_b64 v[10:13], v12 offset1:1
	ds_read2_b64 v[14:17], v15 offset1:1
	v_lshl_add_u64 v[18:19], v[22:23], 0, v[18:19]
	ds_read_b64 v[22:23], v30
	ds_read_b64 v[24:25], v26 offset:136
	ds_read_b64 v[26:27], v31
	ds_read_b64 v[28:29], v32 offset:136
	ds_read_b64 v[30:31], v33
	ds_read_b64 v[32:33], v34 offset:136
	ds_read_b64 v[34:35], v35
	ds_read_b64 v[36:37], v36 offset:136
	v_lshlrev_b32_e32 v20, 1, v56
	v_mov_b32_e32 v21, v0
	v_lshl_add_u64 v[18:19], v[18:19], 0, v[20:21]
	s_waitcnt lgkmcnt(10)
	v_mov_b32_e32 v20, v5
	s_waitcnt lgkmcnt(6)
	v_xor_b32_e32 v46, 0x80000000, v25
	v_mov_b32_e32 v47, v24
	v_mov_b32_e32 v40, v13
	v_xor_b32_e32 v44, 0x80000000, v23
	v_mov_b32_e32 v45, v22
	s_waitcnt lgkmcnt(5)
	v_xor_b32_e32 v48, 0x80000000, v27
	v_mov_b32_e32 v49, v26
	s_waitcnt lgkmcnt(4)
	v_xor_b32_e32 v74, 0x80000000, v29
	v_mov_b32_e32 v75, v28
	v_pk_mul_f32 v[20:21], v[20:21], v[46:47] op_sel_hi:[0,1]
	v_mov_b32_e32 v38, v123
	v_mov_b32_e32 v42, v17
	s_waitcnt lgkmcnt(3)
	v_xor_b32_e32 v76, 0x80000000, v31
	v_mov_b32_e32 v77, v30
	s_waitcnt lgkmcnt(2)
	v_xor_b32_e32 v78, 0x80000000, v33
	v_mov_b32_e32 v79, v32
	s_waitcnt lgkmcnt(1)
	v_xor_b32_e32 v80, 0x80000000, v35
	v_mov_b32_e32 v81, v34
	s_waitcnt lgkmcnt(0)
	v_xor_b32_e32 v82, 0x80000000, v37
	v_mov_b32_e32 v83, v36
	v_pk_mul_f32 v[44:45], v[2:3], v[44:45] op_sel:[1,0]
	v_pk_mul_f32 v[46:47], v[10:11], v[48:49] op_sel:[1,0]
	v_pk_mul_f32 v[40:41], v[40:41], v[74:75] op_sel_hi:[0,1]
	v_pk_fma_f32 v[4:5], v[4:5], v[24:25], v[20:21] op_sel_hi:[0,1,1]
	v_pk_mul_f32 v[48:49], v[120:121], v[76:77] op_sel:[1,0]
	v_pk_mul_f32 v[38:39], v[38:39], v[78:79] op_sel_hi:[0,1]
	v_pk_mul_f32 v[74:75], v[14:15], v[80:81] op_sel:[1,0]
	v_pk_mul_f32 v[42:43], v[42:43], v[82:83] op_sel_hi:[0,1]
	v_pk_fma_f32 v[2:3], v[2:3], v[22:23], v[44:45] op_sel_hi:[0,1,1]
	v_pk_fma_f32 v[10:11], v[10:11], v[26:27], v[46:47] op_sel_hi:[0,1,1]
	v_pk_fma_f32 v[12:13], v[12:13], v[28:29], v[40:41] op_sel_hi:[0,1,1]
	v_pk_add_f32 v[20:21], v[4:5], 0 neg_lo:[1,1] neg_hi:[1,1]
	v_pk_fma_f32 v[6:7], v[120:121], v[30:31], v[48:49] op_sel_hi:[0,1,1]
	v_pk_fma_f32 v[8:9], v[122:123], v[32:33], v[38:39] op_sel_hi:[0,1,1]
	v_pk_fma_f32 v[14:15], v[14:15], v[34:35], v[74:75] op_sel_hi:[0,1,1]
	v_pk_fma_f32 v[16:17], v[16:17], v[36:37], v[42:43] op_sel_hi:[0,1,1]
	v_xor_b32_e32 v22, 0x80000000, v3
	v_cvt_pk_bf16_f32 v3, v10, v12
	v_xor_b32_e32 v20, 0x80000000, v11
	v_pk_add_f32 v[10:11], v[12:13], 0 neg_lo:[1,1] neg_hi:[1,1]
	v_cvt_pk_bf16_f32 v2, v2, v4
	v_cvt_pk_bf16_f32 v4, v6, v8
	v_xor_b32_e32 v10, 0x80000000, v7
	v_pk_add_f32 v[8:9], v[8:9], 0 neg_lo:[1,1] neg_hi:[1,1]
	v_cvt_pk_bf16_f32 v5, v14, v16
	v_xor_b32_e32 v14, 0x80000000, v15
	v_pk_add_f32 v[12:13], v[16:17], 0 neg_lo:[1,1] neg_hi:[1,1]
	v_cvt_pk_bf16_f32 v6, v22, v21
	v_cvt_pk_bf16_f32 v7, v20, v11
	v_cvt_pk_bf16_f32 v8, v10, v9
	v_cvt_pk_bf16_f32 v9, v14, v13
	global_store_dwordx4 v[18:19], v[2:5], off offset:512
	global_store_dwordx4 v[18:19], v[6:9], off offset:640
	s_andn2_b64 exec, exec, s[14:15]
	s_cbranch_execnz .LBB0_42
	s_branch .LBB0_10

.LBB0_271:
	s_or_b64 exec, exec, s[6:7]
	s_lshr_b32 s14, s35, 3
	s_ashr_i32 s8, s35, 7
	s_lshl_b32 s6, s25, 17
	s_add_u32 s6, s64, s6
	s_addc_u32 s7, s65, 0
	s_mul_i32 s25, s25, 0x88100
	s_add_u32 s9, s62, s25
	s_addc_u32 s10, s63, 0
	s_mul_i32 s36, s8, 0x44000
	s_mul_hi_i32 s25, s8, 0x44000
	s_add_u32 s22, s9, s36
	s_addc_u32 s23, s10, s25
	v_lshl_add_u64 v[0:1], s[22:23], 0, v[80:81]
	v_lshl_add_u64 v[0:1], v[0:1], 0, v[74:75]
	global_load_dwordx4 v[110:113], v[0:1], off
	v_lshl_add_u64 v[0:1], s[6:7], 0, v[76:77]
	v_lshl_add_u64 v[32:33], v[0:1], 0, v[106:107]
	global_load_dwordx4 v[52:55], v[32:33], off
	v_lshl_add_u64 v[0:1], s[6:7], 0, v[78:79]
	v_lshl_add_u64 v[60:61], v[0:1], 0, v[106:107]
	global_load_dwordx4 v[56:59], v[60:61], off
	global_load_dwordx4 v[44:47], v[32:33], off offset:64
	global_load_dwordx4 v[48:51], v[60:61], off offset:64
	global_load_dwordx4 v[36:39], v[32:33], off offset:128
	global_load_dwordx4 v[40:43], v[60:61], off offset:128
	global_load_dwordx4 v[24:27], v[32:33], off offset:192
	global_load_dwordx4 v[28:31], v[60:61], off offset:192
	global_load_dwordx4 v[16:19], v[32:33], off offset:256
	global_load_dwordx4 v[20:23], v[60:61], off offset:256
	global_load_dwordx4 v[12:15], v[32:33], off offset:320
	global_load_dwordx4 v[0:3], v[60:61], off offset:320
	global_load_dwordx4 v[8:11], v[32:33], off offset:384
	global_load_dwordx4 v[4:7], v[60:61], off offset:384
	s_nop 0
	global_load_dwordx4 v[32:35], v[32:33], off offset:448
	v_add_u32_e32 v163, s16, v150
	global_load_dwordx4 v[60:63], v[60:61], off offset:448
	s_waitcnt lgkmcnt(0)
	s_barrier
	s_waitcnt vmcnt(17)
	v_mul_f32_e32 v67, 0x41800000, v67
	v_mul_f32_e32 v70, v68, v68
	v_mul_f32_e32 v126, v65, v67
	v_xor_b32_e32 v109, v66, v64
	v_fmamk_f32 v65, v70, 0xb94c1982, v157
	v_fmamk_f32 v66, v70, 0x37d75334, v158
	v_mul_f32_e32 v67, 0x3fb8aa3b, v126
	v_fmaak_f32 v65, v70, v65, 0xbe2aaa9d
	v_fmaak_f32 v66, v70, v66, 0x3d2aabf7
	v_fma_f32 v127, v126, s30, -v67
	v_rndne_f32_e32 v128, v67
	v_lshlrev_b32_e32 v71, 30, v69
	v_and_b32_e32 v69, 1, v69
	v_mul_f32_e32 v65, v70, v65
	v_fmaak_f32 v66, v70, v66, 0xbf000004
	v_fmac_f32_e32 v127, 0x32a5705f, v126
	v_sub_f32_e32 v67, v67, v128
	v_fmac_f32_e32 v68, v68, v65
	v_fma_f32 v65, v70, v66, 1.0
	v_add_f32_e32 v66, v67, v127
	v_cmp_eq_u32_e64 s[6:7], 0, v69
	v_and_b32_e32 v71, 0x80000000, v71
	v_cvt_i32_f32_e32 v128, v128
	v_cndmask_b32_e64 v70, v65, v68, s[6:7]
	v_xor_b32_e32 v70, v109, v70
	v_xor_b32_e32 v70, v70, v71
	s_cmp_eq_u32 s2, 1
	s_waitcnt vmcnt(16)
	ds_write_b128 v73, v[110:113]
	ds_write_b128 v73, v[110:113] offset:8448
	s_waitcnt lgkmcnt(0)
	s_barrier
	ds_read_b128 v[168:171], v163
	ds_read_b128 v[172:175], v163 offset:64
	s_waitcnt vmcnt(15)
	ds_read_b128 v[176:179], v163 offset:128
	s_waitcnt lgkmcnt(2)
	v_mfma_f32_16x16x32_bf16 v[118:121], v[168:171], v[52:55], 0
	s_waitcnt vmcnt(14)
	v_mfma_f32_16x16x32_bf16 v[110:113], v[168:171], v[56:59], 0
	s_waitcnt vmcnt(13)
	s_waitcnt lgkmcnt(1)
	v_mfma_f32_16x16x32_bf16 v[118:121], v[172:175], v[44:47], v[118:121]
	s_waitcnt vmcnt(12)
	ds_read_b128 v[168:171], v163 offset:192
	v_mfma_f32_16x16x32_bf16 v[110:113], v[172:175], v[48:51], v[110:113]
	s_waitcnt vmcnt(11)
	s_waitcnt lgkmcnt(1)
	v_mfma_f32_16x16x32_bf16 v[118:121], v[176:179], v[36:39], v[118:121]
	s_waitcnt vmcnt(10)
	ds_read_b128 v[172:175], v163 offset:256
	v_mfma_f32_16x16x32_bf16 v[110:113], v[176:179], v[40:43], v[110:113]
	s_waitcnt vmcnt(9)
	s_waitcnt lgkmcnt(1)
	v_mfma_f32_16x16x32_bf16 v[118:121], v[168:171], v[24:27], v[118:121]
	s_waitcnt vmcnt(8)
	ds_read_b128 v[176:179], v163 offset:320
	v_mfma_f32_16x16x32_bf16 v[110:113], v[168:171], v[28:31], v[110:113]
	s_waitcnt vmcnt(7)
	s_waitcnt lgkmcnt(1)
	v_mfma_f32_16x16x32_bf16 v[118:121], v[172:175], v[16:19], v[118:121]
	s_waitcnt vmcnt(6)
	v_mfma_f32_16x16x32_bf16 v[110:113], v[172:175], v[20:23], v[110:113]
	v_xor_b32_e32 v122, 0x80000000, v68
	v_exp_f32_e32 v124, v66
	ds_read_b128 v[66:69], v163 offset:384
	s_waitcnt vmcnt(5)
	s_waitcnt lgkmcnt(1)
	v_mfma_f32_16x16x32_bf16 v[118:121], v[176:179], v[12:15], v[118:121]
	v_cndmask_b32_e64 v65, v122, v65, s[6:7]
	s_movk_i32 s6, 0x1f8
	v_xor_b32_e32 v65, v65, v71
	s_waitcnt vmcnt(4)
	ds_read_b128 v[168:171], v163 offset:448
	v_mfma_f32_16x16x32_bf16 v[110:113], v[176:179], v[0:3], v[110:113]
	v_cmp_class_f32_e64 s[6:7], v64, s6
	s_waitcnt vmcnt(3)
	s_waitcnt lgkmcnt(1)
	v_mfma_f32_16x16x32_bf16 v[118:121], v[66:69], v[8:11], v[118:121]
	v_cndmask_b32_e64 v122, v162, v65, s[6:7]
	v_cndmask_b32_e64 v123, v162, v70, s[6:7]
	v_ldexp_f32 v70, v124, v128
	s_waitcnt vmcnt(2)
	v_mfma_f32_16x16x32_bf16 v[64:67], v[66:69], v[4:7], v[110:113]
	v_cmp_ngt_f32_e64 s[6:7], s31, v126
	s_nop 1
	v_cndmask_b32_e64 v68, 0, v70, s[6:7]
	v_cmp_nlt_f32_e64 s[6:7], s34, v126
	s_waitcnt vmcnt(0)
	s_waitcnt lgkmcnt(0)
	v_mfma_f32_16x16x32_bf16 v[64:67], v[168:171], v[60:63], v[64:67]
	v_cndmask_b32_e64 v110, v159, v68, s[6:7]
	s_cselect_b64 s[6:7], -1, 0
	v_mfma_f32_16x16x32_bf16 v[68:71], v[168:171], v[32:35], v[118:121]
	s_cmp_eq_u32 s2, 2
	s_cselect_b64 s[8:9], -1, 0
	s_cmp_eq_u32 s2, 3
	s_nop 1
	v_cndmask_b32_e64 v112, v64, v65, s[6:7]
	v_cndmask_b32_e64 v112, v112, v66, s[8:9]
	s_nop 0
	v_cndmask_b32_e64 v109, v68, v69, s[6:7]
	s_cselect_b64 s[6:7], -1, 0
	s_cmp_eq_u32 s3, 1
	v_cndmask_b32_e64 v109, v109, v70, s[8:9]
	s_cselect_b64 s[8:9], -1, 0
	s_cmp_eq_u32 s3, 2
	v_cndmask_b32_e64 v120, v109, v71, s[6:7]
	v_cndmask_b32_e64 v121, v112, v67, s[6:7]
	s_cselect_b64 s[6:7], -1, 0
	s_cmp_eq_u32 s3, 3
	v_cndmask_b32_e64 v113, v68, v69, s[8:9]
	v_cndmask_b32_e64 v109, v64, v65, s[8:9]
	s_cselect_b64 s[8:9], -1, 0
	s_cmp_eq_u32 s26, 1
	v_cndmask_b32_e64 v112, v113, v70, s[6:7]
	v_cndmask_b32_e64 v109, v109, v66, s[6:7]
	s_cselect_b64 s[6:7], -1, 0
	s_cmp_eq_u32 s26, 2
	v_cndmask_b32_e64 v136, v112, v71, s[8:9]
	v_cndmask_b32_e64 v112, v68, v69, s[6:7]
	v_cndmask_b32_e64 v137, v109, v67, s[8:9]
	s_cselect_b64 s[8:9], -1, 0
	s_cmp_eq_u32 s26, 3
	v_cndmask_b32_e64 v109, v112, v70, s[8:9]
	s_cselect_b64 s[10:11], -1, 0
	s_cmp_eq_u32 s27, 1
	v_cndmask_b32_e64 v131, v109, v71, s[10:11]
	v_cndmask_b32_e64 v109, v64, v65, s[6:7]
	s_cselect_b64 s[6:7], -1, 0
	s_cmp_eq_u32 s27, 2
	v_cndmask_b32_e64 v109, v109, v66, s[8:9]
	v_cndmask_b32_e64 v68, v68, v69, s[6:7]
	s_cselect_b64 s[8:9], -1, 0
	s_cmp_eq_u32 s27, 3
	v_cndmask_b32_e64 v64, v64, v65, s[6:7]
	v_cndmask_b32_e64 v130, v109, v67, s[10:11]
	v_cndmask_b32_e64 v68, v68, v70, s[8:9]
	s_cselect_b64 s[10:11], -1, 0
	v_cndmask_b32_e64 v64, v64, v66, s[8:9]
	v_pk_mul_f32 v[110:111], v[110:111], v[122:123] op_sel_hi:[0,1]
	v_cndmask_b32_e64 v70, v68, v71, s[10:11]
	v_cndmask_b32_e64 v71, v64, v67, s[10:11]
	v_mov_b32_e32 v66, v121
	v_mov_b32_e32 v67, v120
	v_pk_mul_f32 v[64:65], v[110:111], v[120:121]
	v_pk_mul_f32 v[66:67], v[110:111], v[66:67]
	v_sub_f32_e32 v64, v64, v65
	v_add_f32_e32 v65, v67, v66
	v_add_f32_e32 v66, v137, v65
	v_add_f32_e32 v64, v136, v64
	v_pk_mul_f32 v[66:67], v[110:111], v[66:67] op_sel_hi:[1,0]
	v_xor_b32_e32 v112, 0x80000000, v111
	v_pk_fma_f32 v[68:69], v[110:111], v[64:65], v[66:67] op_sel:[1,0,0] op_sel_hi:[0,1,1]
	v_pk_fma_f32 v[64:65], v[110:111], v[64:65], v[66:67] op_sel:[1,0,0] op_sel_hi:[0,0,1] neg_lo:[0,0,1] neg_hi:[0,0,1]
	v_mov_b32_e32 v69, v65
	v_pk_add_f32 v[64:65], v[130:131], v[68:69]
	v_mov_b32_e32 v113, v110
	v_pk_mul_f32 v[66:67], v[110:111], v[64:65] op_sel:[0,1] op_sel_hi:[1,0]
	v_pk_mul_f32 v[64:65], v[110:111], v[64:65]
	v_sub_f32_e32 v66, v66, v67
	v_add_f32_e32 v64, v64, v65
	v_add_f32_e32 v64, v71, v64
	v_add_f32_e32 v66, v70, v66
	ds_bpermute_b32 v123, v153, v64
	ds_bpermute_b32 v119, v154, v64
	ds_bpermute_b32 v117, v155, v64
	ds_bpermute_b32 v125, v156, v64
	v_lshl_add_u64 v[64:65], s[22:23], 0, v[74:75]
	ds_bpermute_b32 v122, v153, v66
	ds_bpermute_b32 v118, v154, v66
	ds_bpermute_b32 v116, v155, v66
	ds_bpermute_b32 v124, v156, v66
	v_lshl_add_u64 v[66:67], v[64:65], 0, v[82:83]
	v_lshl_add_u64 v[68:69], v[64:65], 0, v[84:85]
	global_load_dwordx4 v[64:67], v[66:67], off
	global_load_dwordx4 v[68:71], v[68:69], off
	v_pk_mul_f32 v[112:113], v[110:111], v[112:113] op_sel:[1,0]
	v_pk_mov_b32 v[114:115], v[110:111], v[110:111] op_sel:[1,0]
	v_pk_fma_f32 v[112:113], v[110:111], v[110:111], v[112:113] op_sel_hi:[0,1,1]
	v_xor_b32_e32 v126, 0x80000000, v113
	v_mov_b32_e32 v127, v112
	v_pk_mul_f32 v[126:127], v[112:113], v[126:127] op_sel:[1,0]
	v_cmp_lt_i32_e64 s[6:7], 0, v151
	v_pk_fma_f32 v[112:113], v[112:113], v[112:113], v[126:127] op_sel_hi:[1,0,1]
	s_mov_b64 s[8:9], 0
	v_mul_f32_e32 v109, 0, v112
	v_mul_f32_e32 v127, 0, v113
	v_sub_f32_e32 v126, v109, v127
	v_fmac_f32_e32 v127, 0, v112
	s_waitcnt lgkmcnt(3)
	v_pk_add_f32 v[122:123], v[126:127], v[122:123]
	s_and_saveexec_b64 s[10:11], s[6:7]
	s_xor_b64 s[10:11], exec, s[10:11]
	s_cbranch_execz .LBB0_275
	v_cmp_eq_u32_e64 s[6:7], 1, v151
	s_mov_b64 s[8:9], -1
	s_and_saveexec_b64 s[12:13], s[6:7]
	s_xor_b64 s[8:9], exec, -1
	v_mov_b32_e32 v133, v123
	v_mov_b32_e32 v132, v122
	s_or_b64 exec, exec, s[12:13]
	s_and_b64 s[8:9], s[8:9], exec

.LBB0_281:
	s_add_i32 s8, s36, -2
	s_and_b32 s8, s8, 2
	s_add_i32 s8, s8, s0
	s_mulk_i32 s8, 0x2100
	v_add_u32_e32 v109, s8, v150
	ds_read_b128 v[168:171], v109
	ds_read_b128 v[172:175], v109 offset:64
	ds_read_b128 v[176:179], v109 offset:128
	ds_read_b128 v[180:183], v109 offset:192
	ds_read_b128 v[184:187], v109 offset:256
	ds_read_b128 v[188:191], v109 offset:320
	ds_read_b128 v[192:195], v109 offset:448
	ds_read_b128 v[196:199], v109 offset:384
	s_cmp_eq_u32 s2, 1
	s_cselect_b64 s[8:9], -1, 0
	s_cmp_eq_u32 s2, 2
	s_waitcnt lgkmcnt(7)
	v_mfma_f32_16x16x32_bf16 v[136:139], v[168:171], v[52:55], 0
	s_cselect_b64 s[10:11], -1, 0
	s_cmp_eq_u32 s2, 3
	s_cselect_b64 s[12:13], -1, 0
	v_mfma_f32_16x16x32_bf16 v[64:67], v[168:171], v[56:59], 0
	s_cmp_eq_u32 s3, 1
	s_waitcnt lgkmcnt(6)
	v_mfma_f32_16x16x32_bf16 v[136:139], v[172:175], v[44:47], v[136:139]
	v_mfma_f32_16x16x32_bf16 v[64:67], v[172:175], v[48:51], v[64:67]
	s_waitcnt lgkmcnt(5)
	s_nop 1
	v_mfma_f32_16x16x32_bf16 v[136:139], v[176:179], v[36:39], v[136:139]
	v_mfma_f32_16x16x32_bf16 v[64:67], v[176:179], v[40:43], v[64:67]
	s_waitcnt lgkmcnt(4)
	v_mfma_f32_16x16x32_bf16 v[68:71], v[180:183], v[24:27], v[136:139]
	v_mfma_f32_16x16x32_bf16 v[64:67], v[180:183], v[28:31], v[64:67]
	s_waitcnt lgkmcnt(3)
	s_nop 6
	v_mfma_f32_16x16x32_bf16 v[68:71], v[184:187], v[16:19], v[68:71]
	v_mfma_f32_16x16x32_bf16 v[64:67], v[184:187], v[20:23], v[64:67]
	s_waitcnt lgkmcnt(2)
	s_nop 0
	v_mfma_f32_16x16x32_bf16 v[68:71], v[188:191], v[12:15], v[68:71]
	v_mfma_f32_16x16x32_bf16 v[64:67], v[188:191], v[0:3], v[64:67]
	s_waitcnt lgkmcnt(0)
	v_mfma_f32_16x16x32_bf16 v[68:71], v[196:199], v[8:11], v[68:71]
	v_mfma_f32_16x16x32_bf16 v[64:67], v[196:199], v[4:7], v[64:67]
	v_mfma_f32_16x16x32_bf16 v[68:71], v[192:195], v[32:35], v[68:71]
	v_mfma_f32_16x16x32_bf16 v[64:67], v[192:195], v[60:63], v[64:67]
	s_nop 6
	v_cndmask_b32_e64 v109, v68, v69, s[8:9]
	v_cndmask_b32_e64 v109, v109, v70, s[10:11]
	v_cndmask_b32_e64 v138, v109, v71, s[12:13]
	v_cndmask_b32_e64 v109, v64, v65, s[8:9]
	v_cndmask_b32_e64 v109, v109, v66, s[10:11]
	s_cselect_b64 s[8:9], -1, 0
	s_cmp_eq_u32 s3, 2
	v_cndmask_b32_e64 v139, v109, v67, s[12:13]
	v_cndmask_b32_e64 v109, v68, v69, s[8:9]
	s_cselect_b64 s[10:11], -1, 0
	s_cmp_eq_u32 s3, 3
	v_cndmask_b32_e64 v109, v109, v70, s[10:11]
	s_cselect_b64 s[12:13], -1, 0
	s_cmp_eq_u32 s26, 1
	v_cndmask_b32_e64 v121, v109, v71, s[12:13]
	v_cndmask_b32_e64 v109, v64, v65, s[8:9]
	s_cselect_b64 s[8:9], -1, 0
	s_cmp_eq_u32 s26, 2
	v_cndmask_b32_e64 v109, v109, v66, s[10:11]
	v_cndmask_b32_e64 v136, v68, v69, s[8:9]
	s_cselect_b64 s[10:11], -1, 0
	s_cmp_eq_u32 s26, 3
	v_cndmask_b32_e64 v109, v109, v67, s[12:13]
	v_cndmask_b32_e64 v136, v136, v70, s[10:11]
	s_cselect_b64 s[12:13], -1, 0
	s_cmp_eq_u32 s27, 1
	v_cndmask_b32_e64 v137, v136, v71, s[12:13]
	v_cndmask_b32_e64 v136, v64, v65, s[8:9]
	s_cselect_b64 s[8:9], -1, 0
	s_cmp_eq_u32 s27, 2
	v_cndmask_b32_e64 v136, v136, v66, s[10:11]
	v_cndmask_b32_e64 v68, v68, v69, s[8:9]
	s_cselect_b64 s[10:11], -1, 0
	s_cmp_eq_u32 s27, 3
	v_cndmask_b32_e64 v64, v64, v65, s[8:9]
	v_cndmask_b32_e64 v136, v136, v67, s[12:13]
	v_cndmask_b32_e64 v68, v68, v70, s[10:11]
	s_cselect_b64 s[12:13], -1, 0
	v_cndmask_b32_e64 v64, v64, v66, s[10:11]
	v_cndmask_b32_e64 v70, v68, v71, s[12:13]
	v_cndmask_b32_e64 v71, v64, v67, s[12:13]
	v_mov_b32_e32 v66, v139
	v_mov_b32_e32 v67, v138
	v_pk_mul_f32 v[64:65], v[110:111], v[138:139]
	v_pk_mul_f32 v[66:67], v[110:111], v[66:67]
	v_sub_f32_e32 v64, v64, v65
	v_add_f32_e32 v65, v67, v66
	v_add_f32_e32 v66, v109, v65
	v_add_f32_e32 v64, v121, v64
	v_pk_mul_f32 v[66:67], v[110:111], v[66:67] op_sel_hi:[1,0]
	v_cmp_lt_i32_e64 s[8:9], 0, v151
	v_pk_fma_f32 v[68:69], v[114:115], v[64:65], v[66:67]
	v_pk_fma_f32 v[64:65], v[114:115], v[64:65], v[66:67] op_sel_hi:[1,0,1] neg_lo:[0,0,1] neg_hi:[0,0,1]
	s_mov_b64 s[10:11], 0
	v_mov_b32_e32 v69, v65
	v_pk_add_f32 v[64:65], v[136:137], v[68:69]
	s_nop 0
	v_pk_mul_f32 v[66:67], v[110:111], v[64:65] op_sel:[0,1] op_sel_hi:[1,0]
	v_pk_mul_f32 v[64:65], v[110:111], v[64:65]
	v_sub_f32_e32 v66, v66, v67
	v_add_f32_e32 v64, v64, v65
	v_add_f32_e32 v66, v70, v66
	v_add_f32_e32 v64, v71, v64
	ds_bpermute_b32 v146, v153, v66
	ds_bpermute_b32 v147, v153, v64
	ds_bpermute_b32 v144, v154, v66
	ds_bpermute_b32 v145, v154, v64
	ds_bpermute_b32 v142, v155, v66
	ds_bpermute_b32 v143, v155, v64
	ds_bpermute_b32 v140, v156, v66
	ds_bpermute_b32 v141, v156, v64
	global_load_dwordx4 v[64:67], v[134:135], off
	global_load_dwordx4 v[68:71], v[132:133], off
	s_and_saveexec_b64 s[12:13], s[8:9]
	s_xor_b64 s[12:13], exec, s[12:13]
	s_cbranch_execz .LBB0_285
	v_cmp_eq_u32_e64 s[8:9], 1, v151
	s_mov_b64 s[10:11], -1
	s_and_saveexec_b64 s[24:25], s[8:9]
	s_xor_b64 s[10:11], exec, -1
	s_or_b64 exec, exec, s[24:25]
	s_and_b64 s[10:11], s[10:11], exec

.LBB0_289:
	ds_read_b128 v[168:171], v163
	ds_read_b128 v[172:175], v163 offset:448
	s_cmp_eq_u32 s2, 1
	s_cselect_b64 s[8:9], -1, 0
	s_cmp_eq_u32 s2, 2
	s_cselect_b64 s[10:11], -1, 0
	s_cmp_eq_u32 s2, 3
	s_cselect_b64 s[12:13], -1, 0
	s_cmp_eq_u32 s3, 1
	s_waitcnt lgkmcnt(1)
	v_mfma_f32_16x16x32_bf16 v[52:55], v[168:171], v[52:55], 0
	v_mfma_f32_16x16x32_bf16 v[56:59], v[168:171], v[56:59], 0
	ds_read_b128 v[64:67], v163 offset:64
	s_waitcnt lgkmcnt(0)
	v_mfma_f32_16x16x32_bf16 v[44:47], v[64:67], v[44:47], v[52:55]
	ds_read_b128 v[52:55], v163 offset:128
	s_waitcnt lgkmcnt(0)
	s_nop 3
	v_mfma_f32_16x16x32_bf16 v[36:39], v[52:55], v[36:39], v[44:47]
	ds_read_b128 v[44:47], v163 offset:192
	s_waitcnt lgkmcnt(0)
	s_nop 2
	v_mfma_f32_16x16x32_bf16 v[24:27], v[44:47], v[24:27], v[36:39]
	ds_read_b128 v[36:39], v163 offset:256
	s_waitcnt lgkmcnt(0)
	s_nop 2
	v_mfma_f32_16x16x32_bf16 v[16:19], v[36:39], v[16:19], v[24:27]
	ds_read_b128 v[24:27], v163 offset:320
	v_mfma_f32_16x16x32_bf16 v[48:51], v[64:67], v[48:51], v[56:59]
	v_mfma_f32_16x16x32_bf16 v[40:43], v[52:55], v[40:43], v[48:51]
	s_waitcnt lgkmcnt(0)
	s_nop 2
	v_mfma_f32_16x16x32_bf16 v[12:15], v[24:27], v[12:15], v[16:19]
	ds_read_b128 v[16:19], v163 offset:384
	v_mfma_f32_16x16x32_bf16 v[28:31], v[44:47], v[28:31], v[40:43]
	v_mfma_f32_16x16x32_bf16 v[20:23], v[36:39], v[20:23], v[28:31]
	s_waitcnt lgkmcnt(0)
	s_nop 2
	v_mfma_f32_16x16x32_bf16 v[8:11], v[16:19], v[8:11], v[12:15]
	s_nop 0
	v_mfma_f32_16x16x32_bf16 v[0:3], v[24:27], v[0:3], v[20:23]
	s_nop 0
	v_mfma_f32_16x16x32_bf16 v[0:3], v[16:19], v[4:7], v[0:3]
	s_nop 2
	v_mfma_f32_16x16x32_bf16 v[8:11], v[172:175], v[32:35], v[8:11]
	v_mfma_f32_16x16x32_bf16 v[12:15], v[172:175], v[60:63], v[0:3]
	s_nop 6
	v_cndmask_b32_e64 v28, v8, v9, s[8:9]
	v_cndmask_b32_e64 v0, v12, v13, s[8:9]
	v_cndmask_b32_e64 v0, v0, v14, s[10:11]
	s_cselect_b64 s[8:9], -1, 0
	s_cmp_eq_u32 s3, 2
	v_cndmask_b32_e64 v20, v28, v10, s[10:11]
	v_cndmask_b32_e64 v4, v0, v15, s[12:13]
	v_cndmask_b32_e64 v0, v8, v9, s[8:9]
	s_cselect_b64 s[10:11], -1, 0
	s_cmp_eq_u32 s3, 3
	v_cndmask_b32_e64 v6, v20, v11, s[12:13]
	v_cndmask_b32_e64 v0, v0, v10, s[10:11]
	s_cselect_b64 s[12:13], -1, 0
	v_cndmask_b32_e64 v3, v0, v11, s[12:13]
	v_cndmask_b32_e64 v0, v12, v13, s[8:9]
	s_cmp_eq_u32 s26, 1
	v_cndmask_b32_e64 v0, v0, v14, s[10:11]
	s_cselect_b64 s[8:9], -1, 0
	s_cmp_eq_u32 s26, 2
	v_cndmask_b32_e64 v2, v0, v15, s[12:13]
	v_cndmask_b32_e64 v0, v8, v9, s[8:9]
	s_cselect_b64 s[10:11], -1, 0
	s_cmp_eq_u32 s26, 3
	v_cndmask_b32_e64 v0, v0, v10, s[10:11]
	s_cselect_b64 s[12:13], -1, 0
	s_cmp_eq_u32 s27, 1
	v_cndmask_b32_e64 v1, v0, v11, s[12:13]
	v_cndmask_b32_e64 v0, v12, v13, s[8:9]
	s_cselect_b64 s[8:9], -1, 0
	s_cmp_eq_u32 s27, 2
	v_cndmask_b32_e64 v0, v0, v14, s[10:11]
	v_cndmask_b32_e64 v5, v8, v9, s[8:9]
	s_cselect_b64 s[10:11], -1, 0
	s_cmp_eq_u32 s27, 3
	v_cndmask_b32_e64 v0, v0, v15, s[12:13]
	v_cndmask_b32_e64 v5, v5, v10, s[10:11]
	s_cselect_b64 s[12:13], -1, 0
	v_cndmask_b32_e64 v7, v12, v13, s[8:9]
	v_cndmask_b32_e64 v5, v5, v11, s[12:13]
	v_cndmask_b32_e64 v7, v7, v14, s[10:11]
	v_cndmask_b32_e64 v7, v7, v15, s[12:13]
	v_pk_mul_f32 v[8:9], v[110:111], v[4:5] op_sel_hi:[1,0]
	v_cmp_lt_i32_e64 s[8:9], 0, v151
	v_pk_fma_f32 v[10:11], v[114:115], v[6:7], v[8:9]
	v_pk_fma_f32 v[8:9], v[114:115], v[6:7], v[8:9] op_sel_hi:[1,0,1] neg_lo:[0,0,1] neg_hi:[0,0,1]
	s_mov_b64 s[10:11], 0
	v_mov_b32_e32 v11, v9
	v_pk_add_f32 v[8:9], v[2:3], v[10:11]
	s_nop 0
	v_pk_mul_f32 v[10:11], v[128:129], v[8:9] op_sel:[0,1] op_sel_hi:[1,0]
	s_nop 0
	v_pk_fma_f32 v[12:13], v[126:127], v[8:9], v[10:11]
	v_pk_fma_f32 v[8:9], v[126:127], v[8:9], v[10:11] neg_lo:[0,0,1] neg_hi:[0,0,1]
	s_nop 0
	v_mov_b32_e32 v13, v9
	v_pk_add_f32 v[8:9], v[0:1], v[12:13]
	s_nop 0
	v_pk_mul_f32 v[10:11], v[110:111], v[8:9] op_sel:[0,1] op_sel_hi:[1,0]
	v_pk_mul_f32 v[8:9], v[110:111], v[8:9]
	v_sub_f32_e32 v10, v10, v11
	v_add_f32_e32 v8, v8, v9
	v_add_f32_e32 v5, v5, v10
	v_add_f32_e32 v7, v7, v8
	ds_bpermute_b32 v12, v153, v5
	ds_bpermute_b32 v13, v153, v7
	ds_bpermute_b32 v10, v154, v5
	ds_bpermute_b32 v11, v154, v7
	ds_bpermute_b32 v8, v155, v5
	ds_bpermute_b32 v9, v155, v7
	s_and_saveexec_b64 s[12:13], s[8:9]
	s_xor_b64 s[12:13], exec, s[12:13]
	s_cbranch_execz .LBB0_293
	v_cmp_eq_u32_e64 s[8:9], 1, v151
	s_mov_b64 s[10:11], -1
	s_and_saveexec_b64 s[24:25], s[8:9]
	s_xor_b64 s[10:11], exec, -1
	s_or_b64 exec, exec, s[24:25]
	s_and_b64 s[10:11], s[10:11], exec

.LBB0_352:
	s_add_i32 s28, s29, 1
	s_bitcmp1_b32 s29, 0
	s_cselect_b32 s29, 0x4100, 0
	v_add_u32_e32 v202, s29, v157
	ds_read_b128 v[224:227], v202
	ds_read_b128 v[228:231], v202 offset:64
	ds_read_b128 v[232:235], v202 offset:128
	global_load_dwordx4 v[128:131], v[150:151], off
	v_add_co_u32_e32 v152, vcc, 0xffffe000, v150
	s_waitcnt lgkmcnt(2)
	v_mfma_f32_16x16x32_bf16 v[186:189], v[224:227], v[112:115], 0
	v_addc_co_u32_e32 v153, vcc, -1, v151, vcc
	v_add_u32_e32 v194, s27, v158
	v_mfma_f32_16x16x32_bf16 v[178:181], v[224:227], v[124:127], 0
	ds_read_b128 v[224:227], v202 offset:192
	v_mov_b32_e32 v198, s26
	v_mov_b32_e32 v199, s25
	v_cmp_gt_i32_e32 vcc, s1, v194
	s_waitcnt lgkmcnt(2)
	v_mfma_f32_16x16x32_bf16 v[186:189], v[228:231], v[104:107], v[186:189]
	v_add_u32_e32 v195, s27, v177
	v_add_u32_e32 v196, s27, v176
	v_cndmask_b32_e32 v197, v198, v199, vcc
	v_mfma_f32_16x16x32_bf16 v[178:181], v[228:231], v[120:123], v[178:181]
	ds_read_b128 v[228:231], v202 offset:256
	v_add_u32_e32 v200, 1, v194
	v_add_u32_e32 v201, 0x2001, v195
	s_waitcnt lgkmcnt(2)
	s_nop 0
	v_mfma_f32_16x16x32_bf16 v[186:189], v[232:235], v[96:99], v[186:189]
	v_add_u32_e32 v203, 0xffffff01, v196
	v_add_u32_e32 v204, 16, v194
	v_add_u32_e32 v205, 17, v194
	v_mfma_f32_16x16x32_bf16 v[178:181], v[232:235], v[116:119], v[178:181]
	ds_read_b128 v[232:235], v202 offset:320
	v_add_u32_e32 v207, 0x2011, v195
	v_add_u32_e32 v208, 0xffffff11, v196
	v_add_u32_e32 v211, 32, v194
	s_waitcnt lgkmcnt(2)
	v_mfma_f32_16x16x32_bf16 v[182:185], v[224:227], v[88:91], v[186:189]
	v_add_u32_e32 v209, 33, v194
	v_add_u32_e32 v210, 0x2021, v195
	v_add_u32_e32 v212, 0xffffff21, v196
	v_mfma_f32_16x16x32_bf16 v[178:181], v[224:227], v[108:111], v[178:181]
	ds_read_b128 v[224:227], v202 offset:384
	v_add_u32_e32 v213, 48, v194
	v_add_u32_e32 v214, 49, v194
	s_waitcnt lgkmcnt(2)
	s_nop 0
	v_mfma_f32_16x16x32_bf16 v[182:185], v[228:231], v[80:83], v[182:185]
	v_add_u32_e32 v215, 0x2031, v195
	v_add_u32_e32 v216, 0xffffff31, v196
	v_cmp_gt_i32_e32 vcc, s1, v200
	v_mfma_f32_16x16x32_bf16 v[178:181], v[228:231], v[100:103], v[178:181]
	ds_read_b128 v[228:231], v202 offset:448
	global_load_dwordx4 v[186:189], v[152:153], off
	v_add_u32_e32 v152, v194, v197
	v_cndmask_b32_e32 v206, v203, v201, vcc
	s_waitcnt lgkmcnt(2)
	v_mfma_f32_16x16x32_bf16 v[182:185], v[232:235], v[72:75], v[182:185]
	v_cmp_gt_i32_e32 vcc, s1, v204
	s_bitcmp1_b32 s28, 0
	s_cselect_b32 s29, 0x4100, 0
	v_mfma_f32_16x16x32_bf16 v[178:181], v[232:235], v[92:95], v[178:181]
	ds_read_b128 v[232:235], v202 offset:512
	v_cndmask_b32_e32 v200, v198, v199, vcc
	v_cmp_gt_i32_e32 vcc, s1, v205
	s_waitcnt lgkmcnt(2)
	s_nop 0
	v_mfma_f32_16x16x32_bf16 v[182:185], v[224:227], v[64:67], v[182:185]
	v_cndmask_b32_e32 v208, v208, v207, vcc
	v_cmp_gt_i32_e32 vcc, s1, v211
	v_ashrrev_i32_e32 v207, 31, v206
	v_mfma_f32_16x16x32_bf16 v[178:181], v[224:227], v[84:87], v[178:181]
	ds_read_b128 v[224:227], v202 offset:576
	v_cndmask_b32_e32 v201, v198, v199, vcc
	v_cmp_gt_i32_e32 vcc, s1, v209
	v_ashrrev_i32_e32 v209, 31, v208
	s_waitcnt lgkmcnt(2)
	v_mfma_f32_16x16x32_bf16 v[182:185], v[228:231], v[56:59], v[182:185]
	v_cndmask_b32_e32 v210, v212, v210, vcc
	v_cmp_gt_i32_e32 vcc, s1, v213
	v_lshlrev_b64 v[206:207], 12, v[206:207]
	v_mfma_f32_16x16x32_bf16 v[178:181], v[228:231], v[76:79], v[178:181]
	ds_read_b128 v[228:231], v202 offset:640
	s_nop 0
	v_cndmask_b32_e32 v198, v198, v199, vcc
	v_cmp_gt_i32_e32 vcc, s1, v214
	s_waitcnt lgkmcnt(2)
	v_mfma_f32_16x16x32_bf16 v[182:185], v[232:235], v[52:55], v[182:185]
	v_cndmask_b32_e32 v212, v216, v215, vcc
	v_add_u32_e32 v214, v204, v200
	v_add_u32_e32 v216, v211, v201
	v_mfma_f32_16x16x32_bf16 v[178:181], v[232:235], v[68:71], v[178:181]
	ds_read_b128 v[232:235], v202 offset:704
	v_add_u32_e32 v218, v213, v198
	v_ashrrev_i32_e32 v211, 31, v210
	v_ashrrev_i32_e32 v215, 31, v214
	s_waitcnt lgkmcnt(2)
	v_mfma_f32_16x16x32_bf16 v[182:185], v[224:227], v[44:47], v[182:185]
	v_lshlrev_b64 v[208:209], 12, v[208:209]
	v_ashrrev_i32_e32 v217, 31, v216
	v_ashrrev_i32_e32 v219, 31, v218
	v_mfma_f32_16x16x32_bf16 v[178:181], v[224:227], v[60:63], v[178:181]
	ds_read_b128 v[224:227], v202 offset:768
	v_ashrrev_i32_e32 v213, 31, v212
	s_add_i32 s29, s29, 0
	s_waitcnt lgkmcnt(2)
	s_nop 0
	v_mfma_f32_16x16x32_bf16 v[182:185], v[228:231], v[36:39], v[182:185]
	v_ashrrev_i32_e32 v153, 31, v152
	v_lshlrev_b64 v[152:153], 12, v[152:153]
	v_lshl_add_u64 v[152:153], v[148:149], 0, v[152:153]
	v_mfma_f32_16x16x32_bf16 v[178:181], v[228:231], v[48:51], v[178:181]
	ds_read_b128 v[228:231], v202 offset:832
	s_mov_b64 s[30:31], 0x4000
	s_addk_i32 s27, 0x100
	s_waitcnt lgkmcnt(2)
	s_nop 0
	v_mfma_f32_16x16x32_bf16 v[182:185], v[232:235], v[28:31], v[182:185]
	v_lshl_add_u64 v[150:151], v[150:151], 0, s[30:31]
	s_cmpk_eq_i32 s27, 0x1000
	v_mfma_f32_16x16x32_bf16 v[178:181], v[232:235], v[40:43], v[178:181]
	ds_read_b128 v[232:235], v202 offset:896
	ds_read_b128 v[202:205], v202 offset:960
	s_waitcnt lgkmcnt(3)
	v_mfma_f32_16x16x32_bf16 v[182:185], v[224:227], v[20:23], v[182:185]
	v_mfma_f32_16x16x32_bf16 v[178:181], v[224:227], v[32:35], v[178:181]
	v_lshlrev_b64 v[190:191], 12, v[210:211]
	v_lshlrev_b64 v[210:211], 12, v[218:219]
	v_lshlrev_b64 v[192:193], 12, v[212:213]
	s_waitcnt lgkmcnt(2)
	v_mfma_f32_16x16x32_bf16 v[182:185], v[228:231], v[12:15], v[182:185]
	v_add3_u32 v212, s29, v175, v136
	s_waitcnt vmcnt(1)
	ds_write_b128 v212, v[128:131]
	v_add3_u32 v213, s29, v154, v136
	v_mfma_f32_16x16x32_bf16 v[178:181], v[228:231], v[24:27], v[178:181]
	v_lshl_add_u64 v[198:199], v[148:149], 0, v[206:207]
	v_lshlrev_b64 v[200:201], 12, v[214:215]
	v_lshl_add_u64 v[206:207], v[148:149], 0, v[208:209]
	s_waitcnt lgkmcnt(2)
	v_mfma_f32_16x16x32_bf16 v[182:185], v[232:235], v[4:7], v[182:185]
	v_lshlrev_b64 v[208:209], 12, v[216:217]
	v_lshl_add_u64 v[190:191], v[148:149], 0, v[190:191]
	v_lshl_add_u64 v[192:193], v[148:149], 0, v[192:193]
	v_mfma_f32_16x16x32_bf16 v[178:181], v[232:235], v[16:19], v[178:181]
	v_lshl_add_u64 v[194:195], v[148:149], 0, v[200:201]
	v_lshl_add_u64 v[196:197], v[148:149], 0, v[208:209]
	v_lshl_add_u64 v[200:201], v[148:149], 0, v[210:211]
	s_waitcnt lgkmcnt(1)
	v_mfma_f32_16x16x32_bf16 v[182:185], v[202:205], v[0:3], v[182:185]
	s_waitcnt vmcnt(0)
	ds_write_b128 v213, v[186:189]
	s_mov_b32 s29, s28
	v_mfma_f32_16x16x32_bf16 v[178:181], v[202:205], v[8:11], v[178:181]
	s_nop 3
	v_mul_f32_e32 v202, 0x3d372713, v182
	s_nop 2
	v_mul_f32_e32 v204, 0x3d372713, v178
	v_mul_f32_e32 v208, 0x3d372713, v183
	v_mul_f32_e32 v210, 0x3d372713, v179
	v_mul_f32_e32 v214, 0x3d372713, v184
	v_mul_f32_e32 v216, 0x3d372713, v180
	v_mul_f32_e32 v218, 0x3d372713, v185
	v_mul_f32_e32 v220, 0x3d372713, v181
	v_mul_f32_e32 v202, v182, v202
	v_mul_f32_e32 v203, 0.5, v182
	v_mul_f32_e32 v204, v178, v204
	v_mul_f32_e32 v208, v183, v208
	v_mul_f32_e32 v210, v179, v210
	v_mul_f32_e32 v214, v184, v214
	v_mul_f32_e32 v216, v180, v216
	v_mul_f32_e32 v218, v185, v218
	v_mul_f32_e32 v220, v181, v220
	v_fma_f32 v182, v182, v202, v182
	v_mul_f32_e32 v205, 0.5, v178
	v_mul_f32_e32 v209, 0.5, v183
	v_mul_f32_e32 v211, 0.5, v179
	v_mul_f32_e32 v215, 0.5, v184
	v_mul_f32_e32 v217, 0.5, v180
	v_mul_f32_e32 v219, 0.5, v185
	v_mul_f32_e32 v221, 0.5, v181
	v_fma_f32 v178, v178, v204, v178
	v_fma_f32 v183, v183, v208, v183
	v_fma_f32 v179, v179, v210, v179
	v_fma_f32 v184, v184, v214, v184
	v_fma_f32 v180, v180, v216, v180
	v_fma_f32 v185, v185, v218, v185
	v_fma_f32 v181, v181, v220, v181
	v_mul_f32_e32 v182, 0x3f4c422a, v182
	v_mul_f32_e32 v178, 0x3f4c422a, v178
	v_mul_f32_e32 v183, 0x3f4c422a, v183
	v_mul_f32_e32 v179, 0x3f4c422a, v179
	v_mul_f32_e32 v184, 0x3f4c422a, v184
	v_mul_f32_e32 v180, 0x3f4c422a, v180
	v_mul_f32_e32 v185, 0x3f4c422a, v185
	v_mul_f32_e32 v181, 0x3f4c422a, v181
	v_add_f32_e32 v128, v182, v182
	v_add_f32_e32 v129, v178, v178
	v_add_f32_e32 v130, v183, v183
	v_add_f32_e32 v131, v179, v179
	v_add_f32_e32 v178, v184, v184
	v_add_f32_e32 v179, v180, v180
	v_add_f32_e32 v180, v185, v185
	v_add_f32_e32 v181, v181, v181
	v_mul_f32_e32 v128, 0x3fb8aa3b, v128
	v_mul_f32_e32 v129, 0x3fb8aa3b, v129
	v_mul_f32_e32 v130, 0x3fb8aa3b, v130
	v_mul_f32_e32 v131, 0x3fb8aa3b, v131
	v_mul_f32_e32 v178, 0x3fb8aa3b, v178
	v_mul_f32_e32 v179, 0x3fb8aa3b, v179
	v_mul_f32_e32 v180, 0x3fb8aa3b, v180
	v_mul_f32_e32 v181, 0x3fb8aa3b, v181
	v_exp_f32_e32 v128, v128
	v_exp_f32_e32 v129, v129
	v_exp_f32_e32 v130, v130
	v_exp_f32_e32 v131, v131
	v_exp_f32_e32 v178, v178
	v_exp_f32_e32 v179, v179
	v_exp_f32_e32 v180, v180
	v_exp_f32_e32 v181, v181
	v_add_f32_e32 v128, 1.0, v128
	v_add_f32_e32 v129, 1.0, v129
	v_add_f32_e32 v130, 1.0, v130
	v_add_f32_e32 v131, 1.0, v131
	v_add_f32_e32 v178, 1.0, v178
	v_add_f32_e32 v179, 1.0, v179
	v_add_f32_e32 v180, 1.0, v180
	v_add_f32_e32 v181, 1.0, v181
	v_rcp_f32_e32 v128, v128
	v_rcp_f32_e32 v129, v129
	v_rcp_f32_e32 v130, v130
	v_rcp_f32_e32 v131, v131
	v_rcp_f32_e32 v178, v178
	v_rcp_f32_e32 v179, v179
	v_rcp_f32_e32 v180, v180
	v_rcp_f32_e32 v181, v181
	v_fma_f32 v128, v128, -2.0, 1.0
	v_fma_f32 v129, v129, -2.0, 1.0
	v_fma_f32 v130, v130, -2.0, 1.0
	v_fma_f32 v131, v131, -2.0, 1.0
	v_fma_f32 v178, v178, -2.0, 1.0
	v_fma_f32 v179, v179, -2.0, 1.0
	v_fma_f32 v180, v180, -2.0, 1.0
	v_fma_f32 v181, v181, -2.0, 1.0
	v_add_f32_e32 v128, 1.0, v128
	v_add_f32_e32 v129, 1.0, v129
	v_add_f32_e32 v130, 1.0, v130
	v_add_f32_e32 v131, 1.0, v131
	v_add_f32_e32 v178, 1.0, v178
	v_add_f32_e32 v179, 1.0, v179
	v_add_f32_e32 v180, 1.0, v180
	v_add_f32_e32 v181, 1.0, v181
	v_mul_f32_e32 v128, v203, v128
	v_mul_f32_e32 v129, v205, v129
	v_mul_f32_e32 v130, v209, v130
	v_mul_f32_e32 v131, v211, v131
	v_mul_f32_e32 v178, v215, v178
	v_mul_f32_e32 v179, v217, v179
	v_mul_f32_e32 v180, v219, v180
	v_mul_f32_e32 v181, v221, v181
	v_cvt_pk_bf16_f32 v128, v128, s0
	v_cvt_pk_bf16_f32 v129, v129, s0
	v_cvt_pk_bf16_f32 v130, v130, s0
	v_cvt_pk_bf16_f32 v131, v131, s0
	v_cvt_pk_bf16_f32 v178, v178, s0
	v_cvt_pk_bf16_f32 v179, v179, s0
	v_cvt_pk_bf16_f32 v180, v180, s0
	v_cvt_pk_bf16_f32 v181, v181, s0
	global_store_short v[152:153], v128, off
	global_store_short v[198:199], v129, off
	global_store_short v[194:195], v130, off
	global_store_short v[206:207], v131, off
	global_store_short v[196:197], v178, off
	global_store_short v[190:191], v179, off
	global_store_short v[200:201], v180, off
	global_store_short v[192:193], v181, off
	s_waitcnt lgkmcnt(0)
	s_barrier
	s_cbranch_scc0 .LBB0_352
	ds_read_b128 v[224:227], v157
	s_add_i32 s24, s24, s33
	s_add_i32 s2, s2, s3
	s_cmpk_gt_i32 s24, 0xff
	s_waitcnt lgkmcnt(0)
	v_mfma_f32_16x16x32_bf16 v[112:115], v[224:227], v[112:115], 0
	v_mfma_f32_16x16x32_bf16 v[124:127], v[224:227], v[124:127], 0
	ds_read_b128 v[128:131], v157 offset:64
	s_waitcnt lgkmcnt(0)
	v_mfma_f32_16x16x32_bf16 v[104:107], v[128:131], v[104:107], v[112:115]
	v_mfma_f32_16x16x32_bf16 v[112:115], v[128:131], v[120:123], v[124:127]
	ds_read_b128 v[120:123], v157 offset:128
	s_waitcnt lgkmcnt(0)
	v_mfma_f32_16x16x32_bf16 v[96:99], v[120:123], v[96:99], v[104:107]
	v_mfma_f32_16x16x32_bf16 v[104:107], v[120:123], v[116:119], v[112:115]
	ds_read_b128 v[112:115], v157 offset:192
	s_waitcnt lgkmcnt(0)
	s_nop 3
	v_mfma_f32_16x16x32_bf16 v[88:91], v[112:115], v[88:91], v[96:99]
	v_mfma_f32_16x16x32_bf16 v[96:99], v[112:115], v[108:111], v[104:107]
	ds_read_b128 v[104:107], v157 offset:256
	s_waitcnt lgkmcnt(0)
	s_nop 2
	v_mfma_f32_16x16x32_bf16 v[80:83], v[104:107], v[80:83], v[88:91]
	v_mfma_f32_16x16x32_bf16 v[88:91], v[104:107], v[100:103], v[96:99]
	ds_read_b128 v[96:99], v157 offset:320
	s_waitcnt lgkmcnt(0)
	s_nop 2
	v_mfma_f32_16x16x32_bf16 v[72:75], v[96:99], v[72:75], v[80:83]
	v_mfma_f32_16x16x32_bf16 v[80:83], v[96:99], v[92:95], v[88:91]
	ds_read_b128 v[88:91], v157 offset:384
	s_waitcnt lgkmcnt(0)
	s_nop 2
	v_mfma_f32_16x16x32_bf16 v[64:67], v[88:91], v[64:67], v[72:75]
	v_mfma_f32_16x16x32_bf16 v[72:75], v[88:91], v[84:87], v[80:83]
	ds_read_b128 v[80:83], v157 offset:448
	s_waitcnt lgkmcnt(0)
	s_nop 2
	v_mfma_f32_16x16x32_bf16 v[56:59], v[80:83], v[56:59], v[64:67]
	v_mfma_f32_16x16x32_bf16 v[64:67], v[80:83], v[76:79], v[72:75]
	ds_read_b128 v[72:75], v157 offset:512
	s_waitcnt lgkmcnt(0)
	s_nop 2
	v_mfma_f32_16x16x32_bf16 v[52:55], v[72:75], v[52:55], v[56:59]
	v_mfma_f32_16x16x32_bf16 v[56:59], v[72:75], v[68:71], v[64:67]
	ds_read_b128 v[64:67], v157 offset:576
	s_waitcnt lgkmcnt(0)
	s_nop 2
	v_mfma_f32_16x16x32_bf16 v[44:47], v[64:67], v[44:47], v[52:55]
	v_mfma_f32_16x16x32_bf16 v[52:55], v[64:67], v[60:63], v[56:59]
	ds_read_b128 v[56:59], v157 offset:640
	s_waitcnt lgkmcnt(0)
	s_nop 2
	v_mfma_f32_16x16x32_bf16 v[36:39], v[56:59], v[36:39], v[44:47]
	v_mfma_f32_16x16x32_bf16 v[44:47], v[56:59], v[48:51], v[52:55]
	ds_read_b128 v[48:51], v157 offset:704
	s_waitcnt lgkmcnt(0)
	v_mfma_f32_16x16x32_bf16 v[28:31], v[48:51], v[28:31], v[36:39]
	v_mfma_f32_16x16x32_bf16 v[36:39], v[48:51], v[40:43], v[44:47]
	ds_read_b128 v[40:43], v157 offset:768
	s_waitcnt lgkmcnt(0)
	v_mfma_f32_16x16x32_bf16 v[20:23], v[40:43], v[20:23], v[28:31]
	v_mfma_f32_16x16x32_bf16 v[28:31], v[40:43], v[32:35], v[36:39]
	ds_read_b128 v[32:35], v157 offset:832
	s_waitcnt lgkmcnt(0)
	v_mfma_f32_16x16x32_bf16 v[12:15], v[32:35], v[12:15], v[20:23]
	v_mfma_f32_16x16x32_bf16 v[20:23], v[32:35], v[24:27], v[28:31]
	ds_read_b128 v[24:27], v157 offset:896
	s_waitcnt lgkmcnt(0)
	v_mfma_f32_16x16x32_bf16 v[4:7], v[24:27], v[4:7], v[12:15]
	v_mfma_f32_16x16x32_bf16 v[12:15], v[24:27], v[16:19], v[20:23]
	ds_read_b128 v[16:19], v157 offset:960
	s_waitcnt lgkmcnt(0)
	v_mfma_f32_16x16x32_bf16 v[4:7], v[16:19], v[0:3], v[4:7]
	v_mfma_f32_16x16x32_bf16 v[0:3], v[16:19], v[8:11], v[12:15]
	v_add_u32_e32 v8, s25, v159
	v_add_u32_e32 v9, s22, v160
	v_cndmask_b32_e64 v8, v9, v8, s[4:5]
	s_nop 3
	v_mul_f32_e32 v9, 0x3d372713, v4
	v_mul_f32_e32 v9, v4, v9
	v_fma_f32 v9, v4, v9, v4
	v_mul_f32_e32 v9, 0x3f4c422a, v9
	v_add_f32_e32 v9, v9, v9
	v_mul_f32_e32 v9, 0x3fb8aa3b, v9
	v_exp_f32_e32 v9, v9
	v_mul_f32_e32 v4, 0.5, v4
	v_add_f32_e32 v9, 1.0, v9
	v_rcp_f32_e32 v9, v9
	s_nop 0
	v_fma_f32 v9, v9, -2.0, 1.0
	v_add_f32_e32 v9, 1.0, v9
	v_mul_f32_e32 v4, v4, v9
	v_ashrrev_i32_e32 v9, 31, v8
	v_lshlrev_b64 v[8:9], 12, v[8:9]
	v_cvt_pk_bf16_f32 v4, v4, s0
	v_lshl_add_u64 v[8:9], v[148:149], 0, v[8:9]
	global_store_short v[8:9], v4, off
	v_add_u32_e32 v4, s25, v161
	v_add_u32_e32 v8, s22, v162
	v_cndmask_b32_e64 v8, v8, v4, s[6:7]
	v_mul_f32_e32 v4, 0x3d372713, v0
	v_mul_f32_e32 v4, v0, v4
	v_fma_f32 v4, v0, v4, v0
	v_mul_f32_e32 v4, 0x3f4c422a, v4
	v_add_f32_e32 v4, v4, v4
	v_mul_f32_e32 v4, 0x3fb8aa3b, v4
	v_exp_f32_e32 v4, v4
	v_mul_f32_e32 v0, 0.5, v0
	v_ashrrev_i32_e32 v9, 31, v8
	v_lshlrev_b64 v[8:9], 12, v[8:9]
	v_add_f32_e32 v4, 1.0, v4
	v_rcp_f32_e32 v4, v4
	v_lshl_add_u64 v[8:9], v[148:149], 0, v[8:9]
	v_fma_f32 v4, v4, -2.0, 1.0
	v_add_f32_e32 v4, 1.0, v4
	v_mul_f32_e32 v0, v0, v4
	v_cvt_pk_bf16_f32 v0, v0, s0
	global_store_short v[8:9], v0, off
	v_add_u32_e32 v0, s25, v163
	v_add_u32_e32 v4, s22, v164
	v_cndmask_b32_e64 v4, v4, v0, s[8:9]
	v_mul_f32_e32 v0, 0x3d372713, v5
	v_mul_f32_e32 v0, v5, v0
	v_fma_f32 v0, v5, v0, v5
	v_mul_f32_e32 v0, 0x3f4c422a, v0
	v_add_f32_e32 v0, v0, v0
	v_mul_f32_e32 v0, 0x3fb8aa3b, v0
	v_exp_f32_e32 v0, v0
	v_mul_f32_e32 v5, 0.5, v5
	v_add_f32_e32 v0, 1.0, v0
	v_rcp_f32_e32 v0, v0
	s_nop 0
	v_fma_f32 v0, v0, -2.0, 1.0
	v_add_f32_e32 v0, 1.0, v0
	v_mul_f32_e32 v0, v5, v0
	v_ashrrev_i32_e32 v5, 31, v4
	v_lshlrev_b64 v[4:5], 12, v[4:5]
	v_cvt_pk_bf16_f32 v0, v0, s0
	v_lshl_add_u64 v[4:5], v[148:149], 0, v[4:5]
	global_store_short v[4:5], v0, off
	v_add_u32_e32 v0, s25, v165
	v_add_u32_e32 v4, s22, v166
	v_cndmask_b32_e64 v0, v4, v0, s[10:11]
	v_mul_f32_e32 v4, 0x3d372713, v1
	v_mul_f32_e32 v4, v1, v4
	v_fma_f32 v4, v1, v4, v1
	v_mul_f32_e32 v4, 0x3f4c422a, v4
	v_add_f32_e32 v4, v4, v4
	v_mul_f32_e32 v4, 0x3fb8aa3b, v4
	v_exp_f32_e32 v4, v4
	v_mul_f32_e32 v1, 0.5, v1
	v_add_f32_e32 v4, 1.0, v4
	v_rcp_f32_e32 v4, v4
	s_nop 0
	v_fma_f32 v4, v4, -2.0, 1.0
	v_add_f32_e32 v4, 1.0, v4
	v_mul_f32_e32 v1, v1, v4
	v_cvt_pk_bf16_f32 v4, v1, s0
	v_ashrrev_i32_e32 v1, 31, v0
	v_lshlrev_b64 v[0:1], 12, v[0:1]
	v_lshl_add_u64 v[0:1], v[148:149], 0, v[0:1]
	global_store_short v[0:1], v4, off
	v_add_u32_e32 v0, s25, v167
	v_add_u32_e32 v1, s22, v168
	v_cndmask_b32_e64 v0, v1, v0, s[12:13]
	v_mul_f32_e32 v1, 0x3d372713, v6
	v_mul_f32_e32 v1, v6, v1
	v_fma_f32 v1, v6, v1, v6
	v_mul_f32_e32 v1, 0x3f4c422a, v1
	v_add_f32_e32 v1, v1, v1
	v_mul_f32_e32 v1, 0x3fb8aa3b, v1
	v_exp_f32_e32 v1, v1
	v_mul_f32_e32 v4, 0.5, v6
	v_add_f32_e32 v1, 1.0, v1
	v_rcp_f32_e32 v1, v1
	s_nop 0
	v_fma_f32 v1, v1, -2.0, 1.0
	v_add_f32_e32 v1, 1.0, v1
	v_mul_f32_e32 v1, v4, v1
	v_cvt_pk_bf16_f32 v4, v1, s0
	v_ashrrev_i32_e32 v1, 31, v0
	v_lshlrev_b64 v[0:1], 12, v[0:1]
	v_lshl_add_u64 v[0:1], v[148:149], 0, v[0:1]
	global_store_short v[0:1], v4, off
	v_add_u32_e32 v0, s25, v169
	v_add_u32_e32 v1, s22, v170
	v_cndmask_b32_e64 v0, v1, v0, s[14:15]
	v_mul_f32_e32 v1, 0x3d372713, v2
	v_mul_f32_e32 v1, v2, v1
	v_fma_f32 v1, v2, v1, v2
	v_mul_f32_e32 v1, 0x3f4c422a, v1
	v_add_f32_e32 v1, v1, v1
	v_mul_f32_e32 v1, 0x3fb8aa3b, v1
	v_exp_f32_e32 v1, v1
	v_mul_f32_e32 v2, 0.5, v2
	v_add_f32_e32 v1, 1.0, v1
	v_rcp_f32_e32 v1, v1
	s_nop 0
	v_fma_f32 v1, v1, -2.0, 1.0
	v_add_f32_e32 v1, 1.0, v1
	v_mul_f32_e32 v1, v2, v1
	v_cvt_pk_bf16_f32 v2, v1, s0
	v_ashrrev_i32_e32 v1, 31, v0
	v_lshlrev_b64 v[0:1], 12, v[0:1]
	v_lshl_add_u64 v[0:1], v[148:149], 0, v[0:1]
	global_store_short v[0:1], v2, off
	v_add_u32_e32 v0, s25, v171
	v_add_u32_e32 v1, s22, v172
	v_cndmask_b32_e64 v0, v1, v0, s[16:17]
	v_mul_f32_e32 v1, 0x3d372713, v7
	v_mul_f32_e32 v1, v7, v1
	v_fma_f32 v1, v7, v1, v7
	v_mul_f32_e32 v1, 0x3f4c422a, v1
	v_add_f32_e32 v1, v1, v1
	v_mul_f32_e32 v1, 0x3fb8aa3b, v1
	v_exp_f32_e32 v1, v1
	v_mul_f32_e32 v2, 0.5, v7
	v_add_f32_e32 v1, 1.0, v1
	v_rcp_f32_e32 v1, v1
	s_nop 0
	v_fma_f32 v1, v1, -2.0, 1.0
	v_add_f32_e32 v1, 1.0, v1
	v_mul_f32_e32 v1, v2, v1
	v_cvt_pk_bf16_f32 v2, v1, s0
	v_ashrrev_i32_e32 v1, 31, v0
	v_lshlrev_b64 v[0:1], 12, v[0:1]
	v_lshl_add_u64 v[0:1], v[148:149], 0, v[0:1]
	global_store_short v[0:1], v2, off
	v_add_u32_e32 v0, s25, v173
	v_add_u32_e32 v1, s22, v174
	v_cndmask_b32_e64 v0, v1, v0, s[18:19]
	v_mul_f32_e32 v1, 0x3d372713, v3
	v_mul_f32_e32 v1, v3, v1
	v_fma_f32 v1, v3, v1, v3
	v_mul_f32_e32 v1, 0x3f4c422a, v1
	v_add_f32_e32 v1, v1, v1
	v_mul_f32_e32 v1, 0x3fb8aa3b, v1
	v_exp_f32_e32 v1, v1
	v_mul_f32_e32 v2, 0.5, v3
	v_add_f32_e32 v1, 1.0, v1
	v_rcp_f32_e32 v1, v1
	s_nop 0
	v_fma_f32 v1, v1, -2.0, 1.0
	v_add_f32_e32 v1, 1.0, v1
	v_mul_f32_e32 v1, v2, v1
	v_cvt_pk_bf16_f32 v2, v1, s0
	v_ashrrev_i32_e32 v1, 31, v0
	v_lshlrev_b64 v[0:1], 12, v[0:1]
	v_lshl_add_u64 v[0:1], v[148:149], 0, v[0:1]
	global_store_short v[0:1], v2, off
	s_waitcnt lgkmcnt(0)
	s_barrier
	s_cbranch_scc0 .LBB0_351

.LBB0_682:
	ds_read_b128 v[128:131], v151
	ds_read_b128 v[144:147], v151 offset:1024
	ds_read_b128 v[154:157], v151 offset:2048
	ds_read_b128 v[158:161], v151 offset:3072
	s_add_u32 s16, s14, 0x100
	s_addc_u32 s17, s15, 0
	s_cmpk_eq_i32 s40, 0x54
	s_cselect_b32 s21, s9, s17
	s_cselect_b32 s20, s8, s16
	s_cselect_b32 s19, s11, s39
	s_cselect_b32 s18, s10, s38
	v_lshl_add_u64 v[194:195], s[14:15], 0, v[136:137]
	s_add_i32 m0, s4, 0xc000
	ds_read_b128 v[162:165], v152
	ds_read_b128 v[166:169], v152 offset:1024
	ds_read_b128 v[170:173], v152 offset:2048
	ds_read_b128 v[174:177], v152 offset:3072
	ds_read_b128 v[178:181], v152 offset:4096
	ds_read_b128 v[182:185], v152 offset:5120
	ds_read_b128 v[186:189], v152 offset:6144
	ds_read_b128 v[190:193], v152 offset:7168
	global_load_lds_dwordx4 v[194:195], off
	v_lshl_add_u64 v[194:195], s[14:15], 0, v[138:139]
	s_add_i32 m0, s4, 0xe000
	s_nop 0
	global_load_lds_dwordx4 v[194:195], off
	s_waitcnt lgkmcnt(8)
	s_barrier
	s_waitcnt lgkmcnt(0)
	s_setprio 1
	s_waitcnt lgkmcnt(0)
	v_mfma_f32_16x16x32_bf16 v[124:127], v[128:131], v[162:165], v[124:127]
	v_mfma_f32_16x16x32_bf16 v[92:95], v[154:157], v[162:165], v[92:95]
	v_mfma_f32_16x16x32_bf16 v[120:123], v[128:131], v[170:173], v[120:123]
	v_mfma_f32_16x16x32_bf16 v[88:91], v[154:157], v[170:173], v[88:91]
	v_mfma_f32_16x16x32_bf16 v[116:119], v[128:131], v[178:181], v[116:119]
	v_mfma_f32_16x16x32_bf16 v[84:87], v[154:157], v[178:181], v[84:87]
	v_mfma_f32_16x16x32_bf16 v[112:115], v[128:131], v[186:189], v[112:115]
	v_mfma_f32_16x16x32_bf16 v[80:83], v[154:157], v[186:189], v[80:83]
	v_mfma_f32_16x16x32_bf16 v[124:127], v[144:147], v[166:169], v[124:127]
	v_mfma_f32_16x16x32_bf16 v[92:95], v[158:161], v[166:169], v[92:95]
	v_mfma_f32_16x16x32_bf16 v[120:123], v[144:147], v[174:177], v[120:123]
	v_mfma_f32_16x16x32_bf16 v[88:91], v[158:161], v[174:177], v[88:91]
	v_mfma_f32_16x16x32_bf16 v[116:119], v[144:147], v[182:185], v[116:119]
	v_mfma_f32_16x16x32_bf16 v[84:87], v[158:161], v[182:185], v[84:87]
	v_mfma_f32_16x16x32_bf16 v[112:115], v[144:147], v[190:193], v[112:115]
	v_mfma_f32_16x16x32_bf16 v[80:83], v[158:161], v[190:193], v[80:83]
	s_setprio 0
	s_barrier
	s_add_i32 s14, s30, s3
	v_lshl_add_u64 v[210:211], s[18:19], 0, v[132:133]
	s_mov_b32 m0, s14
	ds_read_b128 v[194:197], v153
	ds_read_b128 v[198:201], v153 offset:1024
	ds_read_b128 v[202:205], v153 offset:2048
	ds_read_b128 v[206:209], v153 offset:3072
	global_load_lds_dwordx4 v[210:211], off
	v_lshl_add_u64 v[212:213], s[18:19], 0, v[134:135]
	s_add_i32 m0, s14, 0x2000
	s_nop 0
	global_load_lds_dwordx4 v[212:213], off
	s_barrier
	s_waitcnt lgkmcnt(0)
	s_setprio 1
	s_waitcnt lgkmcnt(0)
	v_mfma_f32_16x16x32_bf16 v[76:79], v[194:197], v[162:165], v[76:79]
	v_mfma_f32_16x16x32_bf16 v[48:51], v[202:205], v[162:165], v[48:51]
	v_mfma_f32_16x16x32_bf16 v[68:71], v[194:197], v[170:173], v[68:71]
	v_mfma_f32_16x16x32_bf16 v[40:43], v[202:205], v[170:173], v[40:43]
	v_mfma_f32_16x16x32_bf16 v[60:63], v[194:197], v[178:181], v[60:63]
	v_mfma_f32_16x16x32_bf16 v[36:39], v[202:205], v[178:181], v[36:39]
	v_mfma_f32_16x16x32_bf16 v[52:55], v[194:197], v[186:189], v[52:55]
	v_mfma_f32_16x16x32_bf16 v[28:31], v[202:205], v[186:189], v[28:31]
	v_mfma_f32_16x16x32_bf16 v[76:79], v[198:201], v[166:169], v[76:79]
	v_mfma_f32_16x16x32_bf16 v[48:51], v[206:209], v[166:169], v[48:51]
	v_mfma_f32_16x16x32_bf16 v[68:71], v[198:201], v[174:177], v[68:71]
	v_mfma_f32_16x16x32_bf16 v[40:43], v[206:209], v[174:177], v[40:43]
	v_mfma_f32_16x16x32_bf16 v[60:63], v[198:201], v[182:185], v[60:63]
	v_mfma_f32_16x16x32_bf16 v[36:39], v[206:209], v[182:185], v[36:39]
	v_mfma_f32_16x16x32_bf16 v[52:55], v[198:201], v[190:193], v[52:55]
	v_mfma_f32_16x16x32_bf16 v[28:31], v[206:209], v[190:193], v[28:31]
	s_setprio 0
	s_mov_b32 m0, s4
	v_lshl_add_u64 v[214:215], s[20:21], 0, v[132:133]
	s_barrier
	ds_read_b128 v[162:165], v152 offset:16384
	ds_read_b128 v[166:169], v152 offset:17408
	ds_read_b128 v[170:173], v152 offset:18432
	ds_read_b128 v[174:177], v152 offset:19456
	ds_read_b128 v[178:181], v152 offset:20480
	ds_read_b128 v[182:185], v152 offset:21504
	ds_read_b128 v[186:189], v152 offset:22528
	ds_read_b128 v[190:193], v152 offset:23552
	global_load_lds_dwordx4 v[214:215], off
	v_lshl_add_u64 v[216:217], s[20:21], 0, v[134:135]
	s_mov_b32 m0, s5
	s_nop 0
	global_load_lds_dwordx4 v[216:217], off
	s_barrier
	s_waitcnt lgkmcnt(0)
	s_setprio 1
	s_waitcnt lgkmcnt(0)
	v_mfma_f32_16x16x32_bf16 v[108:111], v[128:131], v[162:165], v[108:111]
	v_mfma_f32_16x16x32_bf16 v[72:75], v[154:157], v[162:165], v[72:75]
	v_mfma_f32_16x16x32_bf16 v[104:107], v[128:131], v[170:173], v[104:107]
	v_mfma_f32_16x16x32_bf16 v[64:67], v[154:157], v[170:173], v[64:67]
	v_mfma_f32_16x16x32_bf16 v[100:103], v[128:131], v[178:181], v[100:103]
	v_mfma_f32_16x16x32_bf16 v[56:59], v[154:157], v[178:181], v[56:59]
	v_mfma_f32_16x16x32_bf16 v[96:99], v[128:131], v[186:189], v[96:99]
	v_mfma_f32_16x16x32_bf16 v[44:47], v[154:157], v[186:189], v[44:47]
	v_mfma_f32_16x16x32_bf16 v[108:111], v[144:147], v[166:169], v[108:111]
	v_mfma_f32_16x16x32_bf16 v[72:75], v[158:161], v[166:169], v[72:75]
	v_mfma_f32_16x16x32_bf16 v[104:107], v[144:147], v[174:177], v[104:107]
	v_mfma_f32_16x16x32_bf16 v[64:67], v[158:161], v[174:177], v[64:67]
	v_mfma_f32_16x16x32_bf16 v[100:103], v[144:147], v[182:185], v[100:103]
	v_mfma_f32_16x16x32_bf16 v[56:59], v[158:161], v[182:185], v[56:59]
	v_mfma_f32_16x16x32_bf16 v[96:99], v[144:147], v[190:193], v[96:99]
	v_mfma_f32_16x16x32_bf16 v[44:47], v[158:161], v[190:193], v[44:47]
	s_setprio 0
	s_barrier
	s_add_u32 s14, s18, 0x160000
	s_addc_u32 s15, s19, 0
	s_add_i32 s41, s31, s3
	v_lshl_add_u64 v[128:129], s[14:15], 0, v[132:133]
	s_mov_b32 m0, s41
	s_nop 0
	global_load_lds_dwordx4 v[128:129], off
	v_lshl_add_u64 v[128:129], s[14:15], 0, v[134:135]
	s_add_i32 m0, s41, 0x2000
	s_nop 0
	global_load_lds_dwordx4 v[128:129], off
	s_waitcnt vmcnt(6)
	s_barrier
	s_setprio 1
	v_mfma_f32_16x16x32_bf16 v[32:35], v[194:197], v[162:165], v[32:35]
	v_mfma_f32_16x16x32_bf16 v[12:15], v[202:205], v[162:165], v[12:15]
	v_mfma_f32_16x16x32_bf16 v[24:27], v[194:197], v[170:173], v[24:27]
	v_mfma_f32_16x16x32_bf16 v[8:11], v[202:205], v[170:173], v[8:11]
	v_mfma_f32_16x16x32_bf16 v[20:23], v[194:197], v[178:181], v[20:23]
	v_mfma_f32_16x16x32_bf16 v[4:7], v[202:205], v[178:181], v[4:7]
	v_mfma_f32_16x16x32_bf16 v[16:19], v[194:197], v[186:189], v[16:19]
	v_mfma_f32_16x16x32_bf16 v[0:3], v[202:205], v[186:189], v[0:3]
	v_mfma_f32_16x16x32_bf16 v[32:35], v[198:201], v[166:169], v[32:35]
	v_mfma_f32_16x16x32_bf16 v[12:15], v[206:209], v[166:169], v[12:15]
	v_mfma_f32_16x16x32_bf16 v[24:27], v[198:201], v[174:177], v[24:27]
	v_mfma_f32_16x16x32_bf16 v[8:11], v[206:209], v[174:177], v[8:11]
	v_mfma_f32_16x16x32_bf16 v[20:23], v[198:201], v[182:185], v[20:23]
	v_mfma_f32_16x16x32_bf16 v[4:7], v[206:209], v[182:185], v[4:7]
	v_mfma_f32_16x16x32_bf16 v[16:19], v[198:201], v[190:193], v[16:19]
	v_mfma_f32_16x16x32_bf16 v[0:3], v[206:209], v[190:193], v[0:3]
	s_setprio 0
	s_add_i32 s41, 0, 0x18000
	v_add_u32_e32 v158, s41, v149
	s_barrier
	ds_read_b128 v[128:131], v158
	ds_read_b128 v[144:147], v158 offset:1024
	ds_read_b128 v[154:157], v158 offset:2048
	ds_read_b128 v[158:161], v158 offset:3072
	s_add_u32 s14, s20, 0x160000
	s_addc_u32 s15, s21, 0
	s_mov_b32 m0, s22
	v_lshl_add_u64 v[194:195], s[14:15], 0, v[132:133]
	ds_read_b128 v[162:165], v152 offset:32768
	ds_read_b128 v[166:169], v152 offset:33792
	ds_read_b128 v[170:173], v152 offset:34816
	ds_read_b128 v[174:177], v152 offset:35840
	ds_read_b128 v[178:181], v152 offset:36864
	ds_read_b128 v[182:185], v152 offset:37888
	ds_read_b128 v[186:189], v152 offset:38912
	ds_read_b128 v[190:193], v152 offset:39936
	global_load_lds_dwordx4 v[194:195], off
	v_lshl_add_u64 v[194:195], s[14:15], 0, v[134:135]
	s_mov_b32 m0, s23
	s_nop 0
	global_load_lds_dwordx4 v[194:195], off
	s_waitcnt lgkmcnt(8)
	s_barrier
	s_waitcnt lgkmcnt(0)
	s_setprio 1
	s_waitcnt lgkmcnt(0)
	v_mfma_f32_16x16x32_bf16 v[124:127], v[128:131], v[162:165], v[124:127]
	v_mfma_f32_16x16x32_bf16 v[92:95], v[154:157], v[162:165], v[92:95]
	v_mfma_f32_16x16x32_bf16 v[120:123], v[128:131], v[170:173], v[120:123]
	v_mfma_f32_16x16x32_bf16 v[88:91], v[154:157], v[170:173], v[88:91]
	v_mfma_f32_16x16x32_bf16 v[116:119], v[128:131], v[178:181], v[116:119]
	v_mfma_f32_16x16x32_bf16 v[84:87], v[154:157], v[178:181], v[84:87]
	v_mfma_f32_16x16x32_bf16 v[112:115], v[128:131], v[186:189], v[112:115]
	v_mfma_f32_16x16x32_bf16 v[80:83], v[154:157], v[186:189], v[80:83]
	v_mfma_f32_16x16x32_bf16 v[124:127], v[144:147], v[166:169], v[124:127]
	v_mfma_f32_16x16x32_bf16 v[92:95], v[158:161], v[166:169], v[92:95]
	v_mfma_f32_16x16x32_bf16 v[120:123], v[144:147], v[174:177], v[120:123]
	v_mfma_f32_16x16x32_bf16 v[88:91], v[158:161], v[174:177], v[88:91]
	v_mfma_f32_16x16x32_bf16 v[116:119], v[144:147], v[182:185], v[116:119]
	v_mfma_f32_16x16x32_bf16 v[84:87], v[158:161], v[182:185], v[84:87]
	v_mfma_f32_16x16x32_bf16 v[112:115], v[144:147], v[190:193], v[112:115]
	v_mfma_f32_16x16x32_bf16 v[80:83], v[158:161], v[190:193], v[80:83]
	s_setprio 0
	s_barrier
	s_add_i32 s20, 0, 0x1c000
	s_add_i32 s14, s41, s3
	v_add_u32_e32 v206, s20, v149
	v_lshl_add_u64 v[210:211], v[210:211], 0, s[12:13]
	s_mov_b32 m0, s14
	ds_read_b128 v[194:197], v206
	ds_read_b128 v[198:201], v206 offset:1024
	ds_read_b128 v[202:205], v206 offset:2048
	ds_read_b128 v[206:209], v206 offset:3072
	global_load_lds_dwordx4 v[210:211], off
	v_lshl_add_u64 v[210:211], v[212:213], 0, s[12:13]
	s_add_i32 m0, s14, 0x2000
	s_nop 0
	global_load_lds_dwordx4 v[210:211], off
	s_barrier
	s_waitcnt lgkmcnt(0)
	s_setprio 1
	s_waitcnt lgkmcnt(0)
	v_mfma_f32_16x16x32_bf16 v[76:79], v[194:197], v[162:165], v[76:79]
	v_mfma_f32_16x16x32_bf16 v[48:51], v[202:205], v[162:165], v[48:51]
	v_mfma_f32_16x16x32_bf16 v[68:71], v[194:197], v[170:173], v[68:71]
	v_mfma_f32_16x16x32_bf16 v[40:43], v[202:205], v[170:173], v[40:43]
	v_mfma_f32_16x16x32_bf16 v[60:63], v[194:197], v[178:181], v[60:63]
	v_mfma_f32_16x16x32_bf16 v[36:39], v[202:205], v[178:181], v[36:39]
	v_mfma_f32_16x16x32_bf16 v[52:55], v[194:197], v[186:189], v[52:55]
	v_mfma_f32_16x16x32_bf16 v[28:31], v[202:205], v[186:189], v[28:31]
	v_mfma_f32_16x16x32_bf16 v[76:79], v[198:201], v[166:169], v[76:79]
	v_mfma_f32_16x16x32_bf16 v[48:51], v[206:209], v[166:169], v[48:51]
	v_mfma_f32_16x16x32_bf16 v[68:71], v[198:201], v[174:177], v[68:71]
	v_mfma_f32_16x16x32_bf16 v[40:43], v[206:209], v[174:177], v[40:43]
	v_mfma_f32_16x16x32_bf16 v[60:63], v[198:201], v[182:185], v[60:63]
	v_mfma_f32_16x16x32_bf16 v[36:39], v[206:209], v[182:185], v[36:39]
	v_mfma_f32_16x16x32_bf16 v[52:55], v[198:201], v[190:193], v[52:55]
	v_mfma_f32_16x16x32_bf16 v[28:31], v[206:209], v[190:193], v[28:31]
	s_setprio 0
	s_mov_b32 m0, s25
	v_lshl_add_u64 v[210:211], v[214:215], 0, s[12:13]
	s_barrier
	ds_read_b128 v[162:165], v152 offset:49152
	ds_read_b128 v[166:169], v152 offset:50176
	ds_read_b128 v[170:173], v152 offset:51200
	ds_read_b128 v[174:177], v152 offset:52224
	ds_read_b128 v[178:181], v152 offset:53248
	ds_read_b128 v[182:185], v152 offset:54272
	ds_read_b128 v[186:189], v152 offset:55296
	ds_read_b128 v[190:193], v152 offset:56320
	global_load_lds_dwordx4 v[210:211], off
	v_lshl_add_u64 v[210:211], v[216:217], 0, s[12:13]
	s_mov_b32 m0, s26
	s_nop 0
	global_load_lds_dwordx4 v[210:211], off
	s_barrier
	s_waitcnt lgkmcnt(0)
	s_setprio 1
	s_waitcnt lgkmcnt(0)
	v_mfma_f32_16x16x32_bf16 v[108:111], v[128:131], v[162:165], v[108:111]
	v_mfma_f32_16x16x32_bf16 v[72:75], v[154:157], v[162:165], v[72:75]
	v_mfma_f32_16x16x32_bf16 v[104:107], v[128:131], v[170:173], v[104:107]
	v_mfma_f32_16x16x32_bf16 v[64:67], v[154:157], v[170:173], v[64:67]
	v_mfma_f32_16x16x32_bf16 v[100:103], v[128:131], v[178:181], v[100:103]
	v_mfma_f32_16x16x32_bf16 v[56:59], v[154:157], v[178:181], v[56:59]
	v_mfma_f32_16x16x32_bf16 v[96:99], v[128:131], v[186:189], v[96:99]
	v_mfma_f32_16x16x32_bf16 v[44:47], v[154:157], v[186:189], v[44:47]
	v_mfma_f32_16x16x32_bf16 v[108:111], v[144:147], v[166:169], v[108:111]
	v_mfma_f32_16x16x32_bf16 v[72:75], v[158:161], v[166:169], v[72:75]
	v_mfma_f32_16x16x32_bf16 v[104:107], v[144:147], v[174:177], v[104:107]
	v_mfma_f32_16x16x32_bf16 v[64:67], v[158:161], v[174:177], v[64:67]
	v_mfma_f32_16x16x32_bf16 v[100:103], v[144:147], v[182:185], v[100:103]
	v_mfma_f32_16x16x32_bf16 v[56:59], v[158:161], v[182:185], v[56:59]
	v_mfma_f32_16x16x32_bf16 v[96:99], v[144:147], v[190:193], v[96:99]
	v_mfma_f32_16x16x32_bf16 v[44:47], v[158:161], v[190:193], v[44:47]
	s_setprio 0
	s_barrier
	s_add_u32 s14, s18, 0x160080
	s_addc_u32 s15, s19, 0
	s_add_i32 s18, s20, s3
	v_lshl_add_u64 v[128:129], s[14:15], 0, v[132:133]
	s_mov_b32 m0, s18
	s_nop 0
	global_load_lds_dwordx4 v[128:129], off
	v_lshl_add_u64 v[128:129], s[14:15], 0, v[134:135]
	s_add_i32 m0, s18, 0x2000
	s_nop 0
	global_load_lds_dwordx4 v[128:129], off
	s_waitcnt vmcnt(6)
	s_barrier
	s_setprio 1
	v_mfma_f32_16x16x32_bf16 v[32:35], v[194:197], v[162:165], v[32:35]
	v_mfma_f32_16x16x32_bf16 v[12:15], v[202:205], v[162:165], v[12:15]
	v_mfma_f32_16x16x32_bf16 v[24:27], v[194:197], v[170:173], v[24:27]
	v_mfma_f32_16x16x32_bf16 v[8:11], v[202:205], v[170:173], v[8:11]
	v_mfma_f32_16x16x32_bf16 v[20:23], v[194:197], v[178:181], v[20:23]
	v_mfma_f32_16x16x32_bf16 v[4:7], v[202:205], v[178:181], v[4:7]
	v_mfma_f32_16x16x32_bf16 v[16:19], v[194:197], v[186:189], v[16:19]
	v_mfma_f32_16x16x32_bf16 v[0:3], v[202:205], v[186:189], v[0:3]
	v_mfma_f32_16x16x32_bf16 v[32:35], v[198:201], v[166:169], v[32:35]
	v_mfma_f32_16x16x32_bf16 v[12:15], v[206:209], v[166:169], v[12:15]
	v_mfma_f32_16x16x32_bf16 v[24:27], v[198:201], v[174:177], v[24:27]
	v_mfma_f32_16x16x32_bf16 v[8:11], v[206:209], v[174:177], v[8:11]
	v_mfma_f32_16x16x32_bf16 v[20:23], v[198:201], v[182:185], v[20:23]
	v_mfma_f32_16x16x32_bf16 v[4:7], v[206:209], v[182:185], v[4:7]
	v_mfma_f32_16x16x32_bf16 v[16:19], v[198:201], v[190:193], v[16:19]
	v_mfma_f32_16x16x32_bf16 v[0:3], v[206:209], v[190:193], v[0:3]
	s_setprio 0
	s_add_i32 s40, s40, 2
	s_add_u32 s38, s38, 0x100
	s_addc_u32 s39, s39, 0
	s_cmpk_gt_u32 s40, 0x55
	s_mov_b64 s[14:15], s[16:17]
	s_barrier
	s_cbranch_scc0 .LBB0_682
	s_cmp_lt_u32 s36, 32
	s_movk_i32 s14, 0x3000
	s_cselect_b32 s14, s14, 0x6000
	s_cmp_gt_i32 s36, 15
	v_lshl_add_u32 v158, s36, 8, v148
	s_cselect_b32 s14, s14, 0
	v_lshl_or_b32 v128, s37, 8, v150
	s_lshl_b32 s14, s14, 2
	v_ashrrev_i32_e32 v159, 31, v158
	s_add_u32 s14, s28, s14
	v_ashrrev_i32_e32 v129, 31, v128
	v_lshlrev_b64 v[146:147], 13, v[158:159]
	s_addc_u32 s15, s29, 0
	v_lshlrev_b64 v[160:161], 2, v[128:129]
	v_lshl_add_u64 v[146:147], s[56:57], 0, v[146:147]
	v_lshl_add_u64 v[144:145], s[14:15], 0, v[160:161]
	v_lshl_add_u64 v[146:147], v[146:147], 0, v[160:161]
	s_mov_b64 s[14:15], 0x100000
	s_mov_b32 s37, s34
	s_mov_b32 s36, s35
	s_mov_b64 s[16:17], s[10:11]
	v_or_b32_e32 v162, 16, v158
	v_ashrrev_i32_e32 v163, 31, v162
	v_lshlrev_b64 v[164:165], 13, v[162:163]
	v_lshl_add_u64 v[162:163], s[56:57], 0, v[164:165]
	v_lshl_add_u64 v[164:165], v[162:163], 0, v[160:161]
	v_or_b32_e32 v162, 32, v158
	v_ashrrev_i32_e32 v163, 31, v162
	v_lshlrev_b64 v[166:167], 13, v[162:163]
	v_lshl_add_u64 v[162:163], s[56:57], 0, v[166:167]
	v_lshl_add_u64 v[166:167], v[162:163], 0, v[160:161]
	v_or_b32_e32 v162, 48, v158
	v_ashrrev_i32_e32 v163, 31, v162
	v_lshlrev_b64 v[168:169], 13, v[162:163]
	v_lshl_add_u64 v[162:163], s[56:57], 0, v[168:169]
	v_lshl_add_u64 v[168:169], v[162:163], 0, v[160:161]
	v_lshl_add_u64 v[162:163], v[146:147], 0, s[14:15]
	s_mov_b32 s14, 0x100000
	v_add_co_u32_e32 v170, vcc, s14, v146
	s_mov_b64 s[14:15], 0x120000
	s_nop 0
	v_addc_co_u32_e32 v171, vcc, 0, v147, vcc
	v_lshl_add_u64 v[172:173], v[146:147], 0, s[14:15]
	s_mov_b32 s14, 0x120000
	v_add_co_u32_e32 v174, vcc, s14, v146
	s_mov_b64 s[14:15], 0x140000
	s_nop 0
	v_addc_co_u32_e32 v175, vcc, 0, v147, vcc
	v_lshl_add_u64 v[176:177], v[146:147], 0, s[14:15]
	s_mov_b32 s14, 0x140000
	v_add_co_u32_e32 v178, vcc, s14, v146
	s_mov_b64 s[14:15], 0x160000
	s_nop 0
	v_addc_co_u32_e32 v179, vcc, 0, v147, vcc
	v_lshl_add_u64 v[180:181], v[146:147], 0, s[14:15]
	s_mov_b32 s14, 0x160000
	v_add_co_u32_e32 v182, vcc, s14, v146
	s_mov_b64 s[14:15], s[8:9]
	s_nop 0
	v_addc_co_u32_e32 v183, vcc, 0, v147, vcc
	s_and_b64 vcc, exec, s[6:7]
	global_load_dwordx4 v[184:187], v[144:145], off
	global_load_dwordx4 v[188:191], v[146:147], off
	v_pk_add_f32 v[126:127], v[126:127], 0 op_sel_hi:[1,0]
	v_pk_add_f32 v[124:125], v[124:125], 0 op_sel_hi:[1,0]
	v_pk_add_f32 v[122:123], v[122:123], 0 op_sel_hi:[1,0]
	v_pk_add_f32 v[120:121], v[120:121], 0 op_sel_hi:[1,0]
	v_pk_add_f32 v[118:119], v[118:119], 0 op_sel_hi:[1,0]
	v_pk_add_f32 v[116:117], v[116:117], 0 op_sel_hi:[1,0]
	v_pk_add_f32 v[114:115], v[114:115], 0 op_sel_hi:[1,0]
	v_pk_add_f32 v[112:113], v[112:113], 0 op_sel_hi:[1,0]
	v_pk_add_f32 v[110:111], v[110:111], 0 op_sel_hi:[1,0]
	v_pk_add_f32 v[108:109], v[108:109], 0 op_sel_hi:[1,0]
	v_pk_add_f32 v[106:107], v[106:107], 0 op_sel_hi:[1,0]
	v_pk_add_f32 v[104:105], v[104:105], 0 op_sel_hi:[1,0]
	v_pk_add_f32 v[102:103], v[102:103], 0 op_sel_hi:[1,0]
	v_pk_add_f32 v[100:101], v[100:101], 0 op_sel_hi:[1,0]
	v_pk_add_f32 v[98:99], v[98:99], 0 op_sel_hi:[1,0]
	v_pk_add_f32 v[96:97], v[96:97], 0 op_sel_hi:[1,0]
	v_pk_add_f32 v[94:95], v[94:95], 0 op_sel_hi:[1,0]
	v_pk_add_f32 v[92:93], v[92:93], 0 op_sel_hi:[1,0]
	v_pk_add_f32 v[90:91], v[90:91], 0 op_sel_hi:[1,0]
	v_pk_add_f32 v[88:89], v[88:89], 0 op_sel_hi:[1,0]
	v_pk_add_f32 v[86:87], v[86:87], 0 op_sel_hi:[1,0]
	v_pk_add_f32 v[84:85], v[84:85], 0 op_sel_hi:[1,0]
	v_pk_add_f32 v[82:83], v[82:83], 0 op_sel_hi:[1,0]
	v_pk_add_f32 v[80:81], v[80:81], 0 op_sel_hi:[1,0]
	v_pk_add_f32 v[74:75], v[74:75], 0 op_sel_hi:[1,0]
	v_pk_add_f32 v[72:73], v[72:73], 0 op_sel_hi:[1,0]
	v_pk_add_f32 v[66:67], v[66:67], 0 op_sel_hi:[1,0]
	v_pk_add_f32 v[64:65], v[64:65], 0 op_sel_hi:[1,0]
	v_pk_add_f32 v[58:59], v[58:59], 0 op_sel_hi:[1,0]
	v_pk_add_f32 v[56:57], v[56:57], 0 op_sel_hi:[1,0]
	v_pk_add_f32 v[46:47], v[46:47], 0 op_sel_hi:[1,0]
	v_pk_add_f32 v[44:45], v[44:45], 0 op_sel_hi:[1,0]
	v_pk_add_f32 v[62:63], v[62:63], 0 op_sel_hi:[1,0]
	v_pk_add_f32 v[60:61], v[60:61], 0 op_sel_hi:[1,0]
	v_pk_add_f32 v[54:55], v[54:55], 0 op_sel_hi:[1,0]
	v_pk_add_f32 v[52:53], v[52:53], 0 op_sel_hi:[1,0]
	v_pk_add_f32 v[34:35], v[34:35], 0 op_sel_hi:[1,0]
	v_pk_add_f32 v[32:33], v[32:33], 0 op_sel_hi:[1,0]
	v_pk_add_f32 v[26:27], v[26:27], 0 op_sel_hi:[1,0]
	v_pk_add_f32 v[24:25], v[24:25], 0 op_sel_hi:[1,0]
	v_pk_add_f32 v[22:23], v[22:23], 0 op_sel_hi:[1,0]
	v_pk_add_f32 v[20:21], v[20:21], 0 op_sel_hi:[1,0]
	v_pk_add_f32 v[18:19], v[18:19], 0 op_sel_hi:[1,0]
	v_pk_add_f32 v[16:17], v[16:17], 0 op_sel_hi:[1,0]
	v_pk_add_f32 v[14:15], v[14:15], 0 op_sel_hi:[1,0]
	v_pk_add_f32 v[12:13], v[12:13], 0 op_sel_hi:[1,0]
	v_pk_add_f32 v[10:11], v[10:11], 0 op_sel_hi:[1,0]
	v_pk_add_f32 v[8:9], v[8:9], 0 op_sel_hi:[1,0]
	v_pk_add_f32 v[6:7], v[6:7], 0 op_sel_hi:[1,0]
	v_pk_add_f32 v[4:5], v[4:5], 0 op_sel_hi:[1,0]
	v_pk_add_f32 v[2:3], v[2:3], 0 op_sel_hi:[1,0]
	v_pk_add_f32 v[0:1], v[0:1], 0 op_sel_hi:[1,0]
	s_waitcnt vmcnt(0)
	v_pk_fma_f32 v[126:127], v[126:127], v[186:187], v[190:191]
	v_pk_fma_f32 v[124:125], v[124:125], v[184:185], v[188:189]
	global_store_dwordx4 v[146:147], v[124:127], off
	global_load_dwordx4 v[188:191], v[164:165], off
	global_load_dwordx4 v[192:195], v[166:167], off
	global_load_dwordx4 v[196:199], v[168:169], off
	global_load_dwordx4 v[200:203], v[170:171], off
	global_load_dwordx4 v[204:207], v[174:175], off
	global_load_dwordx4 v[208:211], v[178:179], off
	global_load_dwordx4 v[212:215], v[182:183], off
	global_load_dwordx4 v[216:219], v[144:145], off offset:64
	global_load_dwordx4 v[220:223], v[146:147], off offset:64
	global_load_dwordx4 v[224:227], v[164:165], off offset:64
	global_load_dwordx4 v[228:231], v[166:167], off offset:64
	global_load_dwordx4 v[232:235], v[168:169], off offset:64
	s_waitcnt vmcnt(11)
	v_pk_fma_f32 v[122:123], v[122:123], v[186:187], v[190:191]
	v_pk_fma_f32 v[120:121], v[120:121], v[184:185], v[188:189]
	global_store_dwordx4 v[164:165], v[120:123], off
	global_load_dwordx4 v[188:191], v[162:163], off offset:64
	s_waitcnt vmcnt(12)
	v_pk_fma_f32 v[118:119], v[118:119], v[186:187], v[194:195]
	v_pk_fma_f32 v[116:117], v[116:117], v[184:185], v[192:193]
	global_store_dwordx4 v[166:167], v[116:119], off
	global_load_dwordx4 v[192:195], v[172:173], off offset:64
	s_waitcnt vmcnt(13)
	v_pk_fma_f32 v[114:115], v[114:115], v[186:187], v[198:199]
	v_pk_fma_f32 v[112:113], v[112:113], v[184:185], v[196:197]
	global_store_dwordx4 v[168:169], v[112:115], off
	global_load_dwordx4 v[196:199], v[176:177], off offset:64
	s_waitcnt vmcnt(14)
	v_pk_fma_f32 v[110:111], v[110:111], v[186:187], v[202:203]
	v_pk_fma_f32 v[108:109], v[108:109], v[184:185], v[200:201]
	global_store_dwordx4 v[170:171], v[108:111], off
	global_load_dwordx4 v[200:203], v[180:181], off offset:64
	s_waitcnt vmcnt(15)
	v_pk_fma_f32 v[106:107], v[106:107], v[186:187], v[206:207]
	v_pk_fma_f32 v[104:105], v[104:105], v[184:185], v[204:205]
	global_store_dwordx4 v[174:175], v[104:107], off
	global_load_dwordx4 v[204:207], v[144:145], off offset:512
	s_waitcnt vmcnt(16)
	v_pk_fma_f32 v[102:103], v[102:103], v[186:187], v[210:211]
	v_pk_fma_f32 v[100:101], v[100:101], v[184:185], v[208:209]
	global_store_dwordx4 v[178:179], v[100:103], off
	global_load_dwordx4 v[208:211], v[146:147], off offset:512
	s_waitcnt vmcnt(17)
	v_pk_fma_f32 v[98:99], v[98:99], v[186:187], v[214:215]
	v_pk_fma_f32 v[96:97], v[96:97], v[184:185], v[212:213]
	global_store_dwordx4 v[182:183], v[96:99], off
	global_load_dwordx4 v[184:187], v[164:165], off offset:512
	s_waitcnt vmcnt(17)
	v_pk_fma_f32 v[94:95], v[94:95], v[218:219], v[222:223]
	v_pk_fma_f32 v[92:93], v[92:93], v[216:217], v[220:221]
	global_store_dwordx4 v[146:147], v[92:95], off offset:64
	global_load_dwordx4 v[212:215], v[166:167], off offset:512
	global_load_dwordx4 v[220:223], v[168:169], off offset:512
	s_waitcnt vmcnt(19)
	v_pk_fma_f32 v[90:91], v[90:91], v[218:219], v[226:227]
	v_pk_fma_f32 v[88:89], v[88:89], v[216:217], v[224:225]
	global_store_dwordx4 v[164:165], v[88:91], off offset:64
	global_load_dwordx4 v[224:227], v[162:163], off offset:512
	s_waitcnt vmcnt(20)
	v_pk_fma_f32 v[86:87], v[86:87], v[218:219], v[230:231]
	v_pk_fma_f32 v[84:85], v[84:85], v[216:217], v[228:229]
	global_store_dwordx4 v[166:167], v[84:87], off offset:64
	global_load_dwordx4 v[228:231], v[172:173], off offset:512
	s_waitcnt vmcnt(21)
	v_pk_fma_f32 v[82:83], v[82:83], v[218:219], v[234:235]
	v_pk_fma_f32 v[80:81], v[80:81], v[216:217], v[232:233]
	global_store_dwordx4 v[168:169], v[80:83], off offset:64
	global_load_dwordx4 v[232:235], v[176:177], off offset:512
	s_waitcnt vmcnt(21)
	v_pk_fma_f32 v[74:75], v[74:75], v[218:219], v[190:191]
	v_pk_fma_f32 v[72:73], v[72:73], v[216:217], v[188:189]
	global_store_dwordx4 v[162:163], v[72:75], off offset:64
	global_load_dwordx4 v[188:191], v[180:181], off offset:512
	s_waitcnt vmcnt(21)
	v_pk_fma_f32 v[66:67], v[66:67], v[218:219], v[194:195]
	v_pk_fma_f32 v[64:65], v[64:65], v[216:217], v[192:193]
	global_store_dwordx4 v[172:173], v[64:67], off offset:64
	global_load_dwordx4 v[192:195], v[144:145], off offset:576
	s_waitcnt vmcnt(21)
	v_pk_fma_f32 v[58:59], v[58:59], v[218:219], v[198:199]
	v_pk_fma_f32 v[56:57], v[56:57], v[216:217], v[196:197]
	global_store_dwordx4 v[176:177], v[56:59], off offset:64
	global_load_dwordx4 v[196:199], v[146:147], off offset:576
	v_pk_add_f32 v[64:65], v[78:79], 0 op_sel_hi:[1,0]
	v_pk_add_f32 v[66:67], v[76:77], 0 op_sel_hi:[1,0]
	s_waitcnt vmcnt(21)
	v_pk_fma_f32 v[46:47], v[46:47], v[218:219], v[202:203]
	v_pk_fma_f32 v[44:45], v[44:45], v[216:217], v[200:201]
	global_store_dwordx4 v[180:181], v[44:47], off offset:64
	global_load_dwordx4 v[200:203], v[164:165], off offset:576
	s_waitcnt vmcnt(19)
	v_pk_fma_f32 v[58:59], v[64:65], v[206:207], v[210:211]
	v_pk_fma_f32 v[56:57], v[66:67], v[204:205], v[208:209]
	global_store_dwordx4 v[146:147], v[56:59], off offset:512
	global_load_dwordx4 v[208:211], v[166:167], off offset:576
	global_load_dwordx4 v[216:219], v[168:169], off offset:576
	v_pk_add_f32 v[64:65], v[70:71], 0 op_sel_hi:[1,0]
	v_pk_add_f32 v[66:67], v[68:69], 0 op_sel_hi:[1,0]
	s_waitcnt vmcnt(20)
	v_pk_fma_f32 v[58:59], v[64:65], v[206:207], v[186:187]
	v_pk_fma_f32 v[56:57], v[66:67], v[204:205], v[184:185]
	global_store_dwordx4 v[164:165], v[56:59], off offset:512
	global_load_dwordx4 v[184:187], v[162:163], off offset:576
	s_waitcnt vmcnt(20)
	v_pk_fma_f32 v[58:59], v[62:63], v[206:207], v[214:215]
	v_pk_fma_f32 v[56:57], v[60:61], v[204:205], v[212:213]
	global_store_dwordx4 v[166:167], v[56:59], off offset:512
	global_load_dwordx4 v[212:215], v[172:173], off offset:576
	s_waitcnt vmcnt(21)
	v_pk_fma_f32 v[54:55], v[54:55], v[206:207], v[222:223]
	v_pk_fma_f32 v[52:53], v[52:53], v[204:205], v[220:221]
	global_store_dwordx4 v[168:169], v[52:55], off offset:512
	global_load_dwordx4 v[220:223], v[176:177], off offset:576
	s_waitcnt vmcnt(21)
	v_pk_fma_f32 v[34:35], v[34:35], v[206:207], v[226:227]
	v_pk_fma_f32 v[32:33], v[32:33], v[204:205], v[224:225]
	global_store_dwordx4 v[162:163], v[32:35], off offset:512
	global_load_dwordx4 v[224:227], v[180:181], off offset:576
	s_waitcnt vmcnt(21)
	v_pk_fma_f32 v[26:27], v[26:27], v[206:207], v[230:231]
	v_pk_fma_f32 v[24:25], v[24:25], v[204:205], v[228:229]
	global_store_dwordx4 v[172:173], v[24:27], off offset:512
	s_waitcnt vmcnt(20)
	v_pk_fma_f32 v[22:23], v[22:23], v[206:207], v[234:235]
	v_pk_fma_f32 v[20:21], v[20:21], v[204:205], v[232:233]
	global_store_dwordx4 v[176:177], v[20:23], off offset:512
	v_pk_add_f32 v[24:25], v[50:51], 0 op_sel_hi:[1,0]
	v_pk_add_f32 v[26:27], v[48:49], 0 op_sel_hi:[1,0]
	s_waitcnt vmcnt(19)
	v_pk_fma_f32 v[18:19], v[18:19], v[206:207], v[190:191]
	v_pk_fma_f32 v[16:17], v[16:17], v[204:205], v[188:189]
	global_store_dwordx4 v[180:181], v[16:19], off offset:512
	s_waitcnt vmcnt(16)
	v_pk_fma_f32 v[22:23], v[24:25], v[194:195], v[198:199]
	v_pk_fma_f32 v[20:21], v[26:27], v[192:193], v[196:197]
	global_store_dwordx4 v[146:147], v[20:23], off offset:576
	v_pk_add_f32 v[24:25], v[42:43], 0 op_sel_hi:[1,0]
	v_pk_add_f32 v[26:27], v[40:41], 0 op_sel_hi:[1,0]
	s_waitcnt vmcnt(15)
	v_pk_fma_f32 v[22:23], v[24:25], v[194:195], v[202:203]
	v_pk_fma_f32 v[20:21], v[26:27], v[192:193], v[200:201]
	global_store_dwordx4 v[164:165], v[20:23], off offset:576
	v_pk_add_f32 v[24:25], v[38:39], 0 op_sel_hi:[1,0]
	v_pk_add_f32 v[26:27], v[36:37], 0 op_sel_hi:[1,0]
	s_waitcnt vmcnt(14)
	v_pk_fma_f32 v[22:23], v[24:25], v[194:195], v[210:211]
	v_pk_fma_f32 v[20:21], v[26:27], v[192:193], v[208:209]
	global_store_dwordx4 v[166:167], v[20:23], off offset:576
	v_pk_add_f32 v[24:25], v[30:31], 0 op_sel_hi:[1,0]
	v_pk_add_f32 v[26:27], v[28:29], 0 op_sel_hi:[1,0]
	s_waitcnt vmcnt(14)
	v_pk_fma_f32 v[22:23], v[24:25], v[194:195], v[218:219]
	v_pk_fma_f32 v[20:21], v[26:27], v[192:193], v[216:217]
	global_store_dwordx4 v[168:169], v[20:23], off offset:576
	s_waitcnt vmcnt(13)
	v_pk_fma_f32 v[14:15], v[14:15], v[194:195], v[186:187]
	v_pk_fma_f32 v[12:13], v[12:13], v[192:193], v[184:185]
	global_store_dwordx4 v[162:163], v[12:15], off offset:576
	s_waitcnt vmcnt(12)
	v_pk_fma_f32 v[10:11], v[10:11], v[194:195], v[214:215]
	v_pk_fma_f32 v[8:9], v[8:9], v[192:193], v[212:213]
	global_store_dwordx4 v[172:173], v[8:11], off offset:576
	s_waitcnt vmcnt(11)
	v_pk_fma_f32 v[6:7], v[6:7], v[194:195], v[222:223]
	v_pk_fma_f32 v[4:5], v[4:5], v[192:193], v[220:221]
	global_store_dwordx4 v[176:177], v[4:7], off offset:576
	s_waitcnt vmcnt(10)
	v_pk_fma_f32 v[2:3], v[2:3], v[194:195], v[226:227]
	v_pk_fma_f32 v[0:1], v[0:1], v[192:193], v[224:225]
	global_store_dwordx4 v[180:181], v[0:3], off offset:576
	s_cbranch_vccz .LBB0_671
	s_waitcnt vmcnt(0)
	s_cmpk_gt_u32 s1, 0xff
	s_cbranch_scc1 .LBB0_686
	s_barrier

.LBB0_760:
	s_waitcnt vmcnt(7)
	v_mul_f32_e32 v32, v29, v29
	s_waitcnt vmcnt(6)
	v_mul_f32_e32 v33, v25, v25
	v_fmac_f32_e32 v32, v28, v28
	v_fmac_f32_e32 v33, v24, v24
	v_fmac_f32_e32 v32, v30, v30
	v_fmac_f32_e32 v33, v26, v26
	v_fmac_f32_e32 v32, v31, v31
	v_fmac_f32_e32 v33, v27, v27
	v_add_f32_e32 v32, v32, v33
	s_waitcnt vmcnt(5)
	v_mul_f32_e32 v33, v21, v21
	v_fmac_f32_e32 v33, v20, v20
	v_fmac_f32_e32 v33, v22, v22
	v_fmac_f32_e32 v33, v23, v23
	v_add_f32_e32 v32, v33, v32
	s_waitcnt vmcnt(4)
	v_mul_f32_e32 v33, v17, v17
	v_fmac_f32_e32 v33, v16, v16
	v_fmac_f32_e32 v33, v18, v18
	v_fmac_f32_e32 v33, v19, v19
	v_add_f32_e32 v32, v33, v32
	s_waitcnt vmcnt(3)
	v_mul_f32_e32 v33, v13, v13
	v_fmac_f32_e32 v33, v12, v12
	v_fmac_f32_e32 v33, v14, v14
	v_fmac_f32_e32 v33, v15, v15
	v_add_f32_e32 v32, v33, v32
	s_waitcnt vmcnt(2)
	v_mul_f32_e32 v33, v9, v9
	v_fmac_f32_e32 v33, v8, v8
	v_fmac_f32_e32 v33, v10, v10
	v_fmac_f32_e32 v33, v11, v11
	v_add_f32_e32 v32, v33, v32
	s_waitcnt vmcnt(1)
	v_mul_f32_e32 v33, v5, v5
	v_fmac_f32_e32 v33, v4, v4
	v_fmac_f32_e32 v33, v6, v6
	v_fmac_f32_e32 v33, v7, v7
	v_add_f32_e32 v32, v33, v32
	s_waitcnt vmcnt(0)
	v_mul_f32_e32 v33, v1, v1
	v_fmac_f32_e32 v33, v0, v0
	v_fmac_f32_e32 v33, v2, v2
	v_fmac_f32_e32 v33, v3, v3
	v_add_f32_e32 v32, v33, v32
	v_mbcnt_lo_u32_b32 v33, -1, 0
	v_mbcnt_hi_u32_b32 v33, -1, v33
	s_andn2_b64 vcc, exec, s[6:7]
	v_lshlrev_b32_e32 v33, 2, v33
	v_xor_b32_e32 v34, 0x80, v33
	ds_bpermute_b32 v34, v34, v32
	s_waitcnt lgkmcnt(0)
	v_add_f32_e32 v32, v32, v34
	v_xor_b32_e32 v34, 64, v33
	ds_bpermute_b32 v34, v34, v32
	s_waitcnt lgkmcnt(0)
	v_add_f32_e32 v32, v32, v34
	v_xor_b32_e32 v34, 32, v33
	ds_bpermute_b32 v34, v34, v32
	s_waitcnt lgkmcnt(0)
	v_add_f32_e32 v32, v32, v34
	v_xor_b32_e32 v34, 16, v33
	ds_bpermute_b32 v34, v34, v32
	s_waitcnt lgkmcnt(0)
	v_add_f32_e32 v32, v32, v34
	v_xor_b32_e32 v34, 8, v33
	ds_bpermute_b32 v34, v34, v32
	s_waitcnt lgkmcnt(0)
	v_add_f32_e32 v34, v32, v34
	v_xor_b32_e32 v32, 4, v33
	ds_bpermute_b32 v35, v32, v34
	s_cbranch_vccnz .LBB0_757
	s_ashr_i32 s3, s2, 31
	s_lshr_b32 s3, s3, 20
	s_add_i32 s3, s2, s3
	s_ashr_i32 s3, s3, 12
	s_cmpk_lt_i32 s2, 0x2000
	s_cselect_b32 s3, s3, 2
	s_mul_hi_i32 s5, s3, 0xc000
	s_mul_i32 s3, s3, 0xc000
	s_add_u32 s4, s14, s3
	s_addc_u32 s5, s15, s5
	v_lshl_add_u64 v[48:49], v[56:57], 2, s[4:5]
	s_movk_i32 s3, 0x3000
	v_add_co_u32_e32 v32, vcc, s3, v48
	global_load_dwordx4 v[36:39], v[62:63], off
	s_nop 0
	v_addc_co_u32_e32 v33, vcc, 0, v49, vcc
	global_load_dwordx4 v[40:43], v[32:33], off offset:-4096
	global_load_dwordx4 v[44:47], v[48:49], off
	s_waitcnt lgkmcnt(0)
	v_add_f32_e32 v34, v34, v35
	v_fmamk_f32 v34, v34, 0x3a000000, v106
	s_mov_b32 s3, 0x800000
	v_mul_f32_e32 v35, 0x4b800000, v34
	v_cmp_gt_f32_e32 vcc, s3, v34
	s_mov_b64 s[4:5], 0x2000
	v_lshl_add_u64 v[50:51], v[48:49], 0, s[4:5]
	v_cndmask_b32_e32 v34, v34, v35, vcc
	v_rsq_f32_e32 v34, v34
	s_nop 0
	v_mul_f32_e32 v35, 0x45800000, v34
	v_cndmask_b32_e32 v34, v34, v35, vcc
	v_pk_mul_f32 v[28:29], v[28:29], v[34:35] op_sel_hi:[1,0]
	v_pk_mul_f32 v[30:31], v[30:31], v[34:35] op_sel_hi:[1,0]
	v_pk_mul_f32 v[24:25], v[24:25], v[34:35] op_sel_hi:[1,0]
	v_pk_mul_f32 v[26:27], v[26:27], v[34:35] op_sel_hi:[1,0]
	v_pk_mul_f32 v[20:21], v[20:21], v[34:35] op_sel_hi:[1,0]
	v_pk_mul_f32 v[22:23], v[22:23], v[34:35] op_sel_hi:[1,0]
	v_pk_mul_f32 v[16:17], v[16:17], v[34:35] op_sel_hi:[1,0]
	v_pk_mul_f32 v[18:19], v[18:19], v[34:35] op_sel_hi:[1,0]
	v_pk_mul_f32 v[12:13], v[12:13], v[34:35] op_sel_hi:[1,0]
	v_pk_mul_f32 v[14:15], v[14:15], v[34:35] op_sel_hi:[1,0]
	v_pk_mul_f32 v[8:9], v[8:9], v[34:35] op_sel_hi:[1,0]
	v_pk_mul_f32 v[10:11], v[10:11], v[34:35] op_sel_hi:[1,0]
	v_pk_mul_f32 v[4:5], v[4:5], v[34:35] op_sel_hi:[1,0]
	v_pk_mul_f32 v[6:7], v[6:7], v[34:35] op_sel_hi:[1,0]
	v_pk_mul_f32 v[0:1], v[0:1], v[34:35] op_sel_hi:[1,0]
	v_pk_mul_f32 v[2:3], v[2:3], v[34:35] op_sel_hi:[1,0]
	s_waitcnt vmcnt(2)
	v_pk_mul_f32 v[28:29], v[28:29], v[36:37]
	v_pk_mul_f32 v[30:31], v[30:31], v[38:39]
	s_waitcnt vmcnt(1)
	v_pk_add_f32 v[36:37], v[40:41], 1.0 op_sel_hi:[1,0]
	v_pk_add_f32 v[38:39], v[42:43], 1.0 op_sel_hi:[1,0]
	s_waitcnt vmcnt(0)
	v_pk_fma_f32 v[28:29], v[36:37], v[28:29], v[44:45]
	v_pk_fma_f32 v[30:31], v[38:39], v[30:31], v[46:47]
	v_cvt_pk_bf16_f32 v28, v28, v29
	v_cvt_pk_bf16_f32 v29, v30, v31
	global_store_dwordx2 v[82:83], v[28:29], off offset:-2048
	global_load_dwordx4 v[28:31], v[50:51], off offset:1024
	s_nop 0
	global_load_dwordx4 v[36:39], v[62:63], off offset:1024
	global_load_dwordx4 v[40:43], v[48:49], off offset:1024
	s_waitcnt vmcnt(2)
	v_pk_add_f32 v[28:29], v[28:29], 1.0 op_sel_hi:[1,0]
	s_waitcnt vmcnt(1)
	v_pk_mul_f32 v[24:25], v[24:25], v[36:37]
	v_pk_add_f32 v[30:31], v[30:31], 1.0 op_sel_hi:[1,0]
	v_pk_mul_f32 v[26:27], v[26:27], v[38:39]
	s_waitcnt vmcnt(0)
	v_pk_fma_f32 v[24:25], v[28:29], v[24:25], v[40:41]
	v_pk_fma_f32 v[26:27], v[30:31], v[26:27], v[42:43]
	v_cvt_pk_bf16_f32 v24, v24, v25
	v_cvt_pk_bf16_f32 v25, v26, v27
	global_store_dwordx2 v[82:83], v[24:25], off offset:-1536
	global_load_dwordx4 v[24:27], v[50:51], off offset:2048
	s_nop 0
	global_load_dwordx4 v[28:31], v[62:63], off offset:2048
	global_load_dwordx4 v[36:39], v[48:49], off offset:2048
	s_waitcnt vmcnt(2)
	v_pk_add_f32 v[24:25], v[24:25], 1.0 op_sel_hi:[1,0]
	s_waitcnt vmcnt(1)
	v_pk_mul_f32 v[20:21], v[20:21], v[28:29]
	v_pk_add_f32 v[26:27], v[26:27], 1.0 op_sel_hi:[1,0]
	v_pk_mul_f32 v[22:23], v[22:23], v[30:31]
	s_waitcnt vmcnt(0)
	v_pk_fma_f32 v[20:21], v[24:25], v[20:21], v[36:37]
	v_pk_fma_f32 v[22:23], v[26:27], v[22:23], v[38:39]
	v_cvt_pk_bf16_f32 v20, v20, v21
	v_cvt_pk_bf16_f32 v21, v22, v23
	global_store_dwordx2 v[82:83], v[20:21], off offset:-1024
	global_load_dwordx4 v[20:23], v[50:51], off offset:3072
	s_nop 0
	global_load_dwordx4 v[24:27], v[62:63], off offset:3072
	global_load_dwordx4 v[28:31], v[48:49], off offset:3072
	s_waitcnt vmcnt(2)
	v_pk_add_f32 v[20:21], v[20:21], 1.0 op_sel_hi:[1,0]
	s_waitcnt vmcnt(1)
	v_pk_mul_f32 v[16:17], v[16:17], v[24:25]
	v_pk_add_f32 v[22:23], v[22:23], 1.0 op_sel_hi:[1,0]
	v_pk_mul_f32 v[18:19], v[18:19], v[26:27]
	s_waitcnt vmcnt(0)
	v_pk_fma_f32 v[16:17], v[20:21], v[16:17], v[28:29]
	v_pk_fma_f32 v[18:19], v[22:23], v[18:19], v[30:31]
	v_cvt_pk_bf16_f32 v16, v16, v17
	v_cvt_pk_bf16_f32 v17, v18, v19
	global_store_dwordx2 v[82:83], v[16:17], off offset:-512
	v_add_co_u32_e32 v28, vcc, s1, v48
	global_load_dwordx4 v[16:19], v[32:33], off
	global_load_dwordx4 v[20:23], v[72:73], off
	v_addc_co_u32_e32 v29, vcc, 0, v49, vcc
	global_load_dwordx4 v[24:27], v[28:29], off
	s_waitcnt vmcnt(2)
	v_pk_add_f32 v[16:17], v[16:17], 1.0 op_sel_hi:[1,0]
	s_waitcnt vmcnt(1)
	v_pk_mul_f32 v[12:13], v[12:13], v[20:21]
	v_pk_add_f32 v[18:19], v[18:19], 1.0 op_sel_hi:[1,0]
	v_pk_mul_f32 v[14:15], v[14:15], v[22:23]
	s_waitcnt vmcnt(0)
	v_pk_fma_f32 v[12:13], v[16:17], v[12:13], v[24:25]
	v_pk_fma_f32 v[14:15], v[18:19], v[14:15], v[26:27]
	v_cvt_pk_bf16_f32 v12, v12, v13
	v_cvt_pk_bf16_f32 v13, v14, v15
	global_store_dwordx2 v[82:83], v[12:13], off
	global_load_dwordx4 v[12:15], v[32:33], off offset:1024
	s_nop 0
	global_load_dwordx4 v[16:19], v[74:75], off
	global_load_dwordx4 v[20:23], v[28:29], off offset:1024
	s_waitcnt vmcnt(2)
	v_pk_add_f32 v[12:13], v[12:13], 1.0 op_sel_hi:[1,0]
	s_waitcnt vmcnt(1)
	v_pk_mul_f32 v[8:9], v[8:9], v[16:17]
	v_pk_add_f32 v[14:15], v[14:15], 1.0 op_sel_hi:[1,0]
	v_pk_mul_f32 v[10:11], v[10:11], v[18:19]
	s_waitcnt vmcnt(0)
	v_pk_fma_f32 v[8:9], v[12:13], v[8:9], v[20:21]
	v_pk_fma_f32 v[10:11], v[14:15], v[10:11], v[22:23]
	v_cvt_pk_bf16_f32 v8, v8, v9
	v_cvt_pk_bf16_f32 v9, v10, v11
	global_store_dwordx2 v[82:83], v[8:9], off offset:512
	global_load_dwordx4 v[8:11], v[32:33], off offset:2048
	s_nop 0
	global_load_dwordx4 v[12:15], v[76:77], off
	global_load_dwordx4 v[16:19], v[28:29], off offset:2048
	s_waitcnt vmcnt(2)
	v_pk_add_f32 v[8:9], v[8:9], 1.0 op_sel_hi:[1,0]
	s_waitcnt vmcnt(1)
	v_pk_mul_f32 v[4:5], v[4:5], v[12:13]
	v_pk_add_f32 v[10:11], v[10:11], 1.0 op_sel_hi:[1,0]
	v_pk_mul_f32 v[6:7], v[6:7], v[14:15]
	s_waitcnt vmcnt(0)
	v_pk_fma_f32 v[4:5], v[8:9], v[4:5], v[16:17]
	v_pk_fma_f32 v[6:7], v[10:11], v[6:7], v[18:19]
	v_cvt_pk_bf16_f32 v4, v4, v5
	v_cvt_pk_bf16_f32 v5, v6, v7
	global_store_dwordx2 v[82:83], v[4:5], off offset:1024
	global_load_dwordx4 v[4:7], v[32:33], off offset:3072
	s_nop 0
	global_load_dwordx4 v[8:11], v[78:79], off
	global_load_dwordx4 v[12:15], v[28:29], off offset:3072
	s_waitcnt vmcnt(2)
	v_pk_add_f32 v[4:5], v[4:5], 1.0 op_sel_hi:[1,0]
	s_waitcnt vmcnt(1)
	v_pk_mul_f32 v[0:1], v[0:1], v[8:9]
	v_pk_add_f32 v[6:7], v[6:7], 1.0 op_sel_hi:[1,0]
	v_pk_mul_f32 v[2:3], v[2:3], v[10:11]
	s_waitcnt vmcnt(0)
	v_pk_fma_f32 v[0:1], v[4:5], v[0:1], v[12:13]
	v_pk_fma_f32 v[2:3], v[6:7], v[2:3], v[14:15]
	v_cvt_pk_bf16_f32 v0, v0, v1
	v_cvt_pk_bf16_f32 v1, v2, v3
	global_store_dwordx2 v[82:83], v[0:1], off offset:1536
	s_branch .LBB0_757

.LBB0_847:
	s_or_b64 exec, exec, s[6:7]
	v_mul_f32_e32 v25, v24, v24
	v_fmamk_f32 v37, v25, 0xb94c1982, v32
	v_fmaak_f32 v37, v25, v37, 0xbe2aaa9d
	v_mul_f32_e32 v37, v25, v37
	v_add_u32_e32 v22, -1, v22
	v_fmac_f32_e32 v24, v24, v37
	v_fmamk_f32 v37, v25, 0x37d75334, v33
	v_cvt_f64_u32_e32 v[40:41], v22
	v_fmaak_f32 v37, v25, v37, 0x3d2aabf7
	v_div_scale_f64 v[42:43], s[6:7], v[40:41], v[40:41], v[16:17]
	v_fmaak_f32 v37, v25, v37, 0xbf000004
	v_rcp_f64_e32 v[44:45], v[42:43]
	v_fma_f32 v25, v25, v37, 1.0
	v_and_b32_e32 v37, 1, v23
	v_cmp_eq_u32_e32 vcc, 0, v37
	v_lshlrev_b32_e32 v23, 30, v23
	s_brev_b32 s6, 1
	v_cndmask_b32_e64 v22, -v24, v25, vcc
	v_bitop3_b32 v37, v23, v22, s6 bitop3:0x6c
	v_fma_f64 v[22:23], -v[42:43], v[44:45], 1.0
	v_fmac_f64_e32 v[44:45], v[44:45], v[22:23]
	v_fma_f64 v[22:23], -v[42:43], v[44:45], 1.0
	v_fmac_f64_e32 v[44:45], v[44:45], v[22:23]
	v_div_scale_f64 v[22:23], vcc, v[16:17], v[40:41], v[16:17]
	v_mul_f64 v[24:25], v[22:23], v[44:45]
	v_fma_f64 v[22:23], -v[42:43], v[24:25], v[22:23]
	s_nop 1
	v_div_fmas_f64 v[22:23], v[22:23], v[44:45], v[24:25]
	v_div_fixup_f64 v[22:23], v[22:23], v[40:41], v[16:17]
	s_waitcnt vmcnt(1)
	v_cvt_f64_f32_e32 v[16:17], v15
	v_mul_f32_e32 v15, v38, v38
	s_waitcnt vmcnt(0)
	ds_read2st64_b32 v[128:129], v27 offset0:17 offset1:18
	ds_read2st64_b32 v[130:131], v27 offset0:19 offset1:20
	ds_read2st64_b32 v[132:133], v27 offset0:21 offset1:22
	ds_read2st64_b32 v[134:135], v27 offset0:23 offset1:24
	ds_read2st64_b32 v[136:137], v27 offset0:33 offset1:34
	ds_read2st64_b32 v[138:139], v27 offset0:35 offset1:36
	ds_read2st64_b32 v[140:141], v27 offset0:37 offset1:38
	ds_read2st64_b32 v[142:143], v27 offset0:39 offset1:40
	ds_read2st64_b32 v[144:145], v27 offset0:25 offset1:26
	ds_read2st64_b32 v[146:147], v27 offset0:41 offset1:42
	ds_read2st64_b32 v[148:149], v27 offset0:27 offset1:28
	ds_read2st64_b32 v[150:151], v27 offset0:29 offset1:30
	ds_read2st64_b32 v[152:153], v27 offset0:31 offset1:32
	v_cvt_f64_f32_e32 v[24:25], v18
	v_fmamk_f32 v18, v15, 0xb94c1982, v32
	v_fmaak_f32 v18, v15, v18, 0xbe2aaa9d
	v_mul_f32_e32 v18, v15, v18
	v_fmac_f32_e32 v38, v38, v18
	v_fmamk_f32 v18, v15, 0x37d75334, v33
	v_fmaak_f32 v18, v15, v18, 0x3d2aabf7
	v_fmaak_f32 v18, v15, v18, 0xbf000004
	v_fma_f32 v15, v15, v18, 1.0
	v_and_b32_e32 v18, 1, v0
	v_lshlrev_b32_e32 v0, 30, v0
	v_cvt_f64_f32_e32 v[40:41], v21
	v_cmp_eq_u32_e32 vcc, 0, v18
	v_and_b32_e32 v0, 0x80000000, v0
	v_xor_b32_e32 v18, v20, v19
	v_fmac_f64_e32 v[24:25], v[22:23], v[40:41]
	v_cndmask_b32_e32 v15, v15, v38, vcc
	v_xor_b32_e32 v0, v18, v0
	v_cmp_class_f32_e64 vcc, v19, s29
	v_xor_b32_e32 v0, v0, v15
	s_nop 2
	v_cndmask_b32_e32 v0, v36, v0, vcc
	v_cndmask_b32_e32 v15, v36, v37, vcc
	v_readlane_b32 s7, v0, 0
	v_readlane_b32 s6, v15, 0
	s_waitcnt lgkmcnt(8)
	v_cvt_f64_f32_e32 v[54:55], v136
	v_cvt_f64_f32_e32 v[46:47], s7
	v_cvt_f64_f32_e32 v[20:21], s6
	v_cvt_f64_f32_e32 v[42:43], v128
	v_mul_f64 v[46:47], v[46:47], v[54:55]
	v_readlane_b32 s7, v0, 1
	v_fma_f64 v[20:21], v[20:21], v[42:43], -v[46:47]
	v_readlane_b32 s6, v15, 1
	v_cvt_f64_f32_e32 v[42:43], s7
	v_cvt_f64_f32_e32 v[44:45], v137
	v_add_f64 v[20:21], v[24:25], v[20:21]
	v_cvt_f64_f32_e32 v[24:25], s6
	v_cvt_f64_f32_e32 v[18:19], v129
	v_mul_f64 v[42:43], v[42:43], v[44:45]
	v_readlane_b32 s7, v0, 2
	v_fma_f64 v[18:19], v[24:25], v[18:19], -v[42:43]
	v_readlane_b32 s6, v15, 2
	v_cvt_f64_f32_e32 v[42:43], s7
	s_waitcnt lgkmcnt(7)
	v_cvt_f64_f32_e32 v[44:45], v138
	v_add_f64 v[18:19], v[20:21], v[18:19]
	v_cvt_f64_f32_e32 v[20:21], s6
	v_cvt_f64_f32_e32 v[24:25], v130
	v_mul_f64 v[42:43], v[42:43], v[44:45]
	v_readlane_b32 s7, v0, 3
	v_fma_f64 v[20:21], v[20:21], v[24:25], -v[42:43]
	v_readlane_b32 s6, v15, 3
	v_cvt_f64_f32_e32 v[24:25], s7
	v_cvt_f64_f32_e32 v[42:43], v139
	v_add_f64 v[18:19], v[18:19], v[20:21]
	v_cvt_f64_f32_e32 v[20:21], s6
	v_cvt_f64_f32_e32 v[22:23], v131
	v_mul_f64 v[24:25], v[24:25], v[42:43]
	v_readlane_b32 s7, v0, 4
	v_fma_f64 v[20:21], v[20:21], v[22:23], -v[24:25]
	v_readlane_b32 s6, v15, 4
	v_cvt_f64_f32_e32 v[24:25], s7
	s_waitcnt lgkmcnt(6)
	v_cvt_f64_f32_e32 v[42:43], v140
	v_add_f64 v[18:19], v[18:19], v[20:21]
	v_cvt_f64_f32_e32 v[20:21], s6
	v_cvt_f64_f32_e32 v[22:23], v132
	v_mul_f64 v[24:25], v[24:25], v[42:43]
	v_readlane_b32 s7, v0, 5
	v_fma_f64 v[20:21], v[20:21], v[22:23], -v[24:25]
	v_readlane_b32 s6, v15, 5
	v_cvt_f64_f32_e32 v[22:23], v133
	v_cvt_f64_f32_e32 v[24:25], s7
	v_cvt_f64_f32_e32 v[38:39], v141
	v_add_f64 v[18:19], v[18:19], v[20:21]
	v_cvt_f64_f32_e32 v[20:21], s6
	v_mul_f64 v[24:25], v[24:25], v[38:39]
	v_readlane_b32 s7, v0, 6
	v_fma_f64 v[20:21], v[20:21], v[22:23], -v[24:25]
	v_readlane_b32 s6, v15, 6
	v_cvt_f64_f32_e32 v[24:25], s7
	s_waitcnt lgkmcnt(5)
	v_cvt_f64_f32_e32 v[38:39], v142
	v_add_f64 v[18:19], v[18:19], v[20:21]
	v_cvt_f64_f32_e32 v[20:21], s6
	v_cvt_f64_f32_e32 v[22:23], v134
	v_mul_f64 v[24:25], v[24:25], v[38:39]
	v_readlane_b32 s7, v0, 7
	v_fma_f64 v[20:21], v[20:21], v[22:23], -v[24:25]
	v_readlane_b32 s6, v15, 7
	v_cvt_f64_f32_e32 v[24:25], s7
	v_cvt_f64_f32_e32 v[38:39], v143
	v_add_f64 v[18:19], v[18:19], v[20:21]
	v_cvt_f64_f32_e32 v[20:21], s6
	v_cvt_f64_f32_e32 v[22:23], v135
	v_mul_f64 v[24:25], v[24:25], v[38:39]
	v_fma_f64 v[20:21], v[20:21], v[22:23], -v[24:25]
	v_add_f64 v[18:19], v[18:19], v[20:21]
	v_readlane_b32 s7, v0, 8
	v_readlane_b32 s6, v15, 8
	v_readlane_b32 s9, v0, 9
	s_nop 1
	v_cvt_f64_f32_e32 v[50:51], s7
	ds_read2st64_b32 v[52:53], v27 offset0:43 offset1:44
	ds_read2st64_b32 v[54:55], v27 offset0:45 offset1:46
	ds_read2st64_b32 v[56:57], v27 offset0:47 offset1:48
	s_waitcnt lgkmcnt(6)
	v_cvt_f64_f32_e32 v[58:59], v147
	v_cvt_f64_f32_e32 v[22:23], v146
	v_readlane_b32 s8, v15, 9
	v_cvt_f64_f32_e32 v[24:25], s6
	v_cvt_f64_f32_e32 v[46:47], v144
	v_cvt_f64_f32_e32 v[48:49], s9
	v_mul_f64 v[22:23], v[50:51], v[22:23]
	v_cvt_f64_f32_e32 v[38:39], s8
	v_cvt_f64_f32_e32 v[20:21], v145
	v_mul_f64 v[48:49], v[48:49], v[58:59]
	v_fma_f64 v[22:23], v[24:25], v[46:47], -v[22:23]
	v_readlane_b32 s7, v0, 10
	v_readlane_b32 s9, v0, 11
	v_fma_f64 v[20:21], v[38:39], v[20:21], -v[48:49]
	v_add_f64 v[18:19], v[18:19], v[22:23]
	v_readlane_b32 s6, v15, 10
	v_readlane_b32 s8, v15, 11
	s_waitcnt lgkmcnt(5)
	v_cvt_f64_f32_e32 v[24:25], v148
	v_cvt_f64_f32_e32 v[38:39], v149
	v_cvt_f64_f32_e32 v[40:41], s9
	v_cvt_f64_f32_e32 v[46:47], s7
	s_waitcnt lgkmcnt(2)
	v_cvt_f64_f32_e32 v[48:49], v53
	v_cvt_f64_f32_e32 v[50:51], v52
	v_add_f64 v[18:19], v[18:19], v[20:21]
	v_cvt_f64_f32_e32 v[20:21], s6
	v_cvt_f64_f32_e32 v[22:23], s8
	v_mul_f64 v[46:47], v[46:47], v[50:51]
	v_mul_f64 v[40:41], v[40:41], v[48:49]
	v_readlane_b32 s7, v0, 12
	v_fma_f64 v[22:23], v[22:23], v[38:39], -v[40:41]
	v_fma_f64 v[20:21], v[20:21], v[24:25], -v[46:47]
	v_readlane_b32 s6, v15, 12
	v_readlane_b32 s9, v0, 13
	v_cvt_f64_f32_e32 v[24:25], v150
	v_cvt_f64_f32_e32 v[38:39], v151
	v_cvt_f64_f32_e32 v[42:43], s7
	s_waitcnt lgkmcnt(1)
	v_cvt_f64_f32_e32 v[48:49], v54
	v_add_f64 v[18:19], v[18:19], v[20:21]
	v_readlane_b32 s8, v15, 13
	v_cvt_f64_f32_e32 v[20:21], s6
	v_cvt_f64_f32_e32 v[40:41], s9
	v_cvt_f64_f32_e32 v[46:47], v55
	v_mul_f64 v[42:43], v[42:43], v[48:49]
	v_readlane_b32 s7, v0, 14
	v_add_f64 v[18:19], v[18:19], v[22:23]
	v_cvt_f64_f32_e32 v[22:23], s8
	v_mul_f64 v[40:41], v[40:41], v[46:47]
	v_fma_f64 v[20:21], v[20:21], v[24:25], -v[42:43]
	v_readlane_b32 s6, v15, 14
	v_readlane_b32 s9, v0, 15
	v_cvt_f64_f32_e32 v[42:43], s7
	s_waitcnt lgkmcnt(0)
	v_cvt_f64_f32_e32 v[46:47], v56
	v_fma_f64 v[22:23], v[22:23], v[38:39], -v[40:41]
	v_add_f64 v[18:19], v[18:19], v[20:21]
	v_readlane_b32 s8, v15, 15
	v_cvt_f64_f32_e32 v[20:21], s6
	v_cvt_f64_f32_e32 v[24:25], v152
	v_cvt_f64_f32_e32 v[38:39], v153
	v_cvt_f64_f32_e32 v[40:41], s9
	v_cvt_f64_f32_e32 v[44:45], v57
	v_mul_f64 v[42:43], v[42:43], v[46:47]
	v_add_f64 v[18:19], v[18:19], v[22:23]
	v_cvt_f64_f32_e32 v[22:23], s8
	v_mul_f64 v[40:41], v[40:41], v[44:45]
	v_fma_f64 v[20:21], v[20:21], v[24:25], -v[42:43]
	v_fma_f64 v[22:23], v[22:23], v[38:39], -v[40:41]
	v_add_f64 v[18:19], v[18:19], v[20:21]
	v_add_f64 v[18:19], v[18:19], v[22:23]
	v_mul_f64 v[18:19], v[18:19], v[16:17]
	v_mul_f64 v[20:21], v[18:19], s[16:17]
	v_rndne_f64_e32 v[20:21], v[20:21]
	v_fmac_f64_e32 v[18:19], s[14:15], v[20:21]
	v_cvt_f32_f64_e32 v15, v[18:19]
	v_and_b32_e32 v18, 0x7fffffff, v15
	v_cmp_nlt_f32_e64 s[6:7], |v15|, s2
	s_and_saveexec_b64 s[8:9], s[6:7]
	s_xor_b64 s[18:19], exec, s[8:9]
	s_cbranch_execz .LBB0_849
	v_lshrrev_b32_e32 v0, 23, v18
	v_add_u32_e32 v0, 0xffffff88, v0
	v_cmp_lt_u32_e32 vcc, 63, v0
	s_nop 1
	v_cndmask_b32_e32 v19, 0, v34, vcc
	v_add_u32_e32 v0, v19, v0
	v_cmp_lt_u32_e64 s[6:7], 31, v0
	s_nop 1
	v_cndmask_b32_e64 v19, 0, v35, s[6:7]
	v_add_u32_e32 v0, v19, v0
	v_cmp_lt_u32_e64 s[8:9], 31, v0
	s_nop 1
	v_cndmask_b32_e64 v19, 0, v35, s[8:9]
	v_add_u32_e32 v19, v19, v0
	v_and_b32_e32 v0, 0x7fffff, v18
	v_or_b32_e32 v37, 0x800000, v0
	v_mad_u64_u32 v[20:21], s[10:11], v37, s3, 0
	v_mov_b32_e32 v0, v21
	v_mad_u64_u32 v[22:23], s[10:11], v37, s4, v[0:1]
	v_mov_b32_e32 v0, v23
	v_mad_u64_u32 v[24:25], s[10:11], v37, s5, v[0:1]
	v_mov_b32_e32 v0, v25
	v_mad_u64_u32 v[38:39], s[10:11], v37, s22, v[0:1]
	v_mov_b32_e32 v0, v39
	v_mad_u64_u32 v[40:41], s[10:11], v37, s23, v[0:1]
	v_mov_b32_e32 v0, v41
	v_mad_u64_u32 v[42:43], s[10:11], v37, s24, v[0:1]
	v_mov_b32_e32 v0, v43
	v_mad_u64_u32 v[44:45], s[10:11], v37, s25, v[0:1]
	v_cndmask_b32_e32 v21, v42, v38, vcc
	v_cndmask_b32_e32 v0, v44, v40, vcc
	v_cndmask_b32_e32 v25, v45, v42, vcc
	v_cndmask_b32_e64 v23, v0, v21, s[6:7]
	v_cndmask_b32_e64 v0, v25, v0, s[6:7]
	v_cndmask_b32_e32 v25, v40, v24, vcc
	v_cndmask_b32_e64 v21, v21, v25, s[6:7]
	v_sub_u32_e32 v37, 32, v19
	v_cmp_eq_u32_e64 s[10:11], 0, v19
	v_cndmask_b32_e32 v19, v38, v22, vcc
	v_cndmask_b32_e64 v0, v0, v23, s[8:9]
	v_cndmask_b32_e64 v23, v23, v21, s[8:9]
	v_cndmask_b32_e64 v22, v25, v19, s[6:7]
	v_alignbit_b32 v39, v0, v23, v37
	v_cndmask_b32_e64 v21, v21, v22, s[8:9]
	v_cndmask_b32_e64 v0, v39, v0, s[10:11]
	v_alignbit_b32 v25, v23, v21, v37
	v_cndmask_b32_e32 v20, v24, v20, vcc
	v_cndmask_b32_e64 v23, v25, v23, s[10:11]
	v_bfe_u32 v39, v0, 29, 1
	v_cndmask_b32_e64 v19, v19, v20, s[6:7]
	v_alignbit_b32 v25, v0, v23, 30
	v_sub_u32_e32 v40, 0, v39
	v_cndmask_b32_e64 v19, v22, v19, s[8:9]
	v_xor_b32_e32 v25, v25, v40
	v_alignbit_b32 v20, v21, v19, v37
	v_cndmask_b32_e64 v20, v20, v21, s[10:11]
	v_ffbh_u32_e32 v22, v25
	v_alignbit_b32 v21, v23, v20, 30
	v_min_u32_e32 v22, 32, v22
	v_alignbit_b32 v19, v20, v19, 30
	v_xor_b32_e32 v21, v21, v40
	v_sub_u32_e32 v23, 31, v22
	v_xor_b32_e32 v19, v19, v40
	v_alignbit_b32 v24, v25, v21, v23
	v_alignbit_b32 v19, v21, v19, v23
	v_alignbit_b32 v20, v24, v19, 9
	v_ffbh_u32_e32 v21, v20
	v_min_u32_e32 v21, 32, v21
	v_lshrrev_b32_e32 v38, 29, v0
	v_not_b32_e32 v23, v21
	v_alignbit_b32 v19, v20, v19, v23
	v_lshlrev_b32_e32 v20, 31, v38
	v_or_b32_e32 v23, 0x33000000, v20
	v_add_lshl_u32 v21, v21, v22, 23
	v_lshrrev_b32_e32 v19, 9, v19
	v_sub_u32_e32 v21, v23, v21
	v_or_b32_e32 v20, 0.5, v20
	v_lshlrev_b32_e32 v22, 23, v22
	v_or_b32_e32 v19, v21, v19
	v_lshrrev_b32_e32 v21, 9, v24
	v_sub_u32_e32 v20, v20, v22
	v_or_b32_e32 v20, v21, v20
	v_mul_f32_e32 v21, 0x3fc90fda, v20
	v_fma_f32 v22, v20, s26, -v21
	v_fmac_f32_e32 v22, 0x33a22168, v20
	v_fmac_f32_e32 v22, 0x3fc90fda, v19
	v_lshrrev_b32_e32 v0, 30, v0
	v_add_f32_e32 v19, v21, v22
	v_add_u32_e32 v0, v39, v0
.LBB0_849:
	s_andn2_saveexec_b64 s[6:7], s[18:19]
	v_mul_f32_e64 v0, |v15|, s27
	v_rndne_f32_e32 v20, v0
	v_cvt_i32_f32_e32 v0, v20
	v_fma_f32 v19, v20, s28, |v15|
	v_fmac_f32_e32 v19, 0xb3a22168, v20
	v_fmac_f32_e32 v19, 0xa7c234c4, v20
	s_or_b64 exec, exec, s[6:7]
	v_mul_f32_e32 v20, v19, v19
	v_fmamk_f32 v21, v20, 0xb94c1982, v32
	v_fmaak_f32 v21, v20, v21, 0xbe2aaa9d
	v_mul_f32_e32 v21, v20, v21
	v_fmac_f32_e32 v19, v19, v21
	v_fmamk_f32 v21, v20, 0x37d75334, v33
	v_fmaak_f32 v21, v20, v21, 0x3d2aabf7
	v_fmaak_f32 v21, v20, v21, 0xbf000004
	v_fma_f32 v20, v20, v21, 1.0
	v_and_b32_e32 v21, 1, v0
	v_lshlrev_b32_e32 v0, 30, v0
	v_cmp_eq_u32_e32 vcc, 0, v21
	v_and_b32_e32 v0, 0x80000000, v0
	v_xor_b32_e32 v18, v18, v15
	v_cndmask_b32_e32 v19, v20, v19, vcc
	v_xor_b32_e32 v0, v18, v0
	v_xor_b32_e32 v0, v0, v19
	v_cmp_class_f32_e64 vcc, v15, s29
	s_nop 1
	v_cndmask_b32_e32 v0, v36, v0, vcc
	v_cvt_f64_f32_e32 v[18:19], v0
	ds_write_b64 v29, v[18:19]
	s_waitcnt lgkmcnt(0)
	s_barrier
	ds_read_b128 v[128:131], v28
	ds_read_b128 v[132:135], v28 offset:16
	ds_read_b128 v[136:139], v28 offset:32
	ds_read2st64_b32 v[140:141], v27 offset0:49 offset1:50
	global_load_dword v0, v[8:9], off
	ds_read_b128 v[46:49], v28 offset:48
	s_waitcnt lgkmcnt(1)
	v_cvt_f64_f32_e32 v[50:51], v140
	s_waitcnt vmcnt(0)
	ds_read2st64_b32 v[142:143], v27 offset0:51 offset1:52
	ds_read2st64_b32 v[144:145], v27 offset0:53 offset1:54
	ds_read2st64_b32 v[146:147], v27 offset0:55 offset1:56
	ds_read_b128 v[148:151], v28 offset:64
	ds_read2st64_b32 v[152:153], v27 offset0:57 offset1:58
	ds_read_b128 v[156:159], v28 offset:80
	ds_read2st64_b32 v[154:155], v27 offset0:59 offset1:60
	ds_read_b128 v[164:167], v28 offset:96
	ds_read2st64_b32 v[160:161], v27 offset0:61 offset1:62
	ds_read_b128 v[168:171], v28 offset:112
	ds_read2st64_b32 v[172:173], v27 offset0:63 offset1:64
	v_cvt_f64_f32_e32 v[18:19], v0
	v_fmac_f64_e32 v[18:19], v[128:129], v[50:51]
	v_cvt_f64_f32_e32 v[20:21], v141
	ds_read_b128 v[176:179], v28 offset:128
	v_fma_f64 v[20:21], v[130:131], v[20:21], 0
	ds_read2st64_b32 v[128:129], v27 offset0:65 offset1:66
	s_waitcnt lgkmcnt(12)
	v_cvt_f64_f32_e32 v[22:23], v142
	v_fma_f64 v[22:23], v[132:133], v[22:23], 0
	v_cvt_f64_f32_e32 v[24:25], v143
	ds_read_b128 v[140:143], v28 offset:144
	v_fma_f64 v[24:25], v[134:135], v[24:25], 0
	ds_read2st64_b32 v[130:131], v27 offset0:67 offset1:68
	s_waitcnt lgkmcnt(13)
	v_cvt_f64_f32_e32 v[40:41], v144
	v_cvt_f64_f32_e32 v[38:39], v145
	ds_read_b128 v[132:135], v28 offset:160
	v_fmac_f64_e32 v[20:21], v[138:139], v[38:39]
	v_fmac_f64_e32 v[18:19], v[136:137], v[40:41]
	ds_read2st64_b32 v[136:137], v27 offset0:69 offset1:70
	s_waitcnt lgkmcnt(14)
	v_cvt_f64_f32_e32 v[40:41], v146
	v_cvt_f64_f32_e32 v[38:39], v147
	ds_read_b128 v[144:147], v28 offset:176
	v_fmac_f64_e32 v[22:23], v[46:47], v[40:41]
	v_fmac_f64_e32 v[24:25], v[48:49], v[38:39]
	s_waitcnt lgkmcnt(13)
	v_cvt_f64_f32_e32 v[44:45], v152
	v_fmac_f64_e32 v[18:19], v[148:149], v[44:45]
	v_cvt_f64_f32_e32 v[38:39], v153
	ds_read2st64_b32 v[138:139], v27 offset0:71 offset1:72
	v_fmac_f64_e32 v[20:21], v[150:151], v[38:39]
	ds_read_b128 v[148:151], v28 offset:192
	s_waitcnt lgkmcnt(13)
	v_cvt_f64_f32_e32 v[44:45], v154
	v_fmac_f64_e32 v[22:23], v[156:157], v[44:45]
	v_cvt_f64_f32_e32 v[38:39], v155
	ds_read2st64_b32 v[152:153], v27 offset0:73 offset1:74
	v_fmac_f64_e32 v[24:25], v[158:159], v[38:39]
	ds_read_b128 v[156:159], v28 offset:208
	s_waitcnt lgkmcnt(13)
	v_cvt_f64_f32_e32 v[44:45], v160
	v_fmac_f64_e32 v[18:19], v[164:165], v[44:45]
	v_cvt_f64_f32_e32 v[38:39], v161
	ds_read2st64_b32 v[154:155], v27 offset0:75 offset1:76
	v_fmac_f64_e32 v[20:21], v[166:167], v[38:39]
	ds_read_b128 v[164:167], v28 offset:224
	s_waitcnt lgkmcnt(13)
	v_cvt_f64_f32_e32 v[44:45], v172
	v_fmac_f64_e32 v[22:23], v[168:169], v[44:45]
	v_cvt_f64_f32_e32 v[38:39], v173
	ds_read2st64_b32 v[160:161], v27 offset0:77 offset1:78
	v_fmac_f64_e32 v[24:25], v[170:171], v[38:39]
	ds_read_b128 v[168:171], v28 offset:240
	s_waitcnt lgkmcnt(13)
	v_cvt_f64_f32_e32 v[44:45], v128
	v_fmac_f64_e32 v[18:19], v[176:177], v[44:45]
	v_cvt_f64_f32_e32 v[38:39], v129
	ds_read2st64_b32 v[128:129], v27 offset0:79 offset1:80
	v_fmac_f64_e32 v[20:21], v[178:179], v[38:39]
	ds_read_b128 v[172:175], v28 offset:256
	s_waitcnt lgkmcnt(13)
	v_cvt_f64_f32_e32 v[44:45], v130
	v_fmac_f64_e32 v[22:23], v[140:141], v[44:45]
	v_cvt_f64_f32_e32 v[38:39], v131
	ds_read2st64_b32 v[130:131], v27 offset0:81 offset1:82
	v_fmac_f64_e32 v[24:25], v[142:143], v[38:39]
	ds_read_b128 v[140:143], v28 offset:272
	s_waitcnt lgkmcnt(13)
	v_cvt_f64_f32_e32 v[44:45], v136
	v_fmac_f64_e32 v[18:19], v[132:133], v[44:45]
	v_cvt_f64_f32_e32 v[38:39], v137
	ds_read2st64_b32 v[136:137], v27 offset0:83 offset1:84
	v_fmac_f64_e32 v[20:21], v[134:135], v[38:39]
	ds_read_b128 v[132:135], v28 offset:288
	s_waitcnt lgkmcnt(13)
	v_cvt_f64_f32_e32 v[44:45], v138
	v_fmac_f64_e32 v[22:23], v[144:145], v[44:45]
	v_cvt_f64_f32_e32 v[38:39], v139
	ds_read2st64_b32 v[138:139], v27 offset0:85 offset1:86
	v_fmac_f64_e32 v[24:25], v[146:147], v[38:39]
	ds_read_b128 v[144:147], v28 offset:304
	s_waitcnt lgkmcnt(13)
	v_cvt_f64_f32_e32 v[44:45], v152
	v_fmac_f64_e32 v[18:19], v[148:149], v[44:45]
	v_cvt_f64_f32_e32 v[38:39], v153
	ds_read2st64_b32 v[152:153], v27 offset0:87 offset1:88
	v_fmac_f64_e32 v[20:21], v[150:151], v[38:39]
	ds_read_b128 v[148:151], v28 offset:320
	s_waitcnt lgkmcnt(13)
	v_cvt_f64_f32_e32 v[44:45], v154
	v_fmac_f64_e32 v[22:23], v[156:157], v[44:45]
	v_cvt_f64_f32_e32 v[38:39], v155
	ds_read2st64_b32 v[154:155], v27 offset0:89 offset1:90
	v_fmac_f64_e32 v[24:25], v[158:159], v[38:39]
	ds_read_b128 v[156:159], v28 offset:336
	s_waitcnt lgkmcnt(13)
	v_cvt_f64_f32_e32 v[44:45], v160
	v_fmac_f64_e32 v[18:19], v[164:165], v[44:45]
	v_cvt_f64_f32_e32 v[38:39], v161
	ds_read2st64_b32 v[160:161], v27 offset0:91 offset1:92
	v_fmac_f64_e32 v[20:21], v[166:167], v[38:39]
	ds_read_b128 v[164:167], v28 offset:352
	s_waitcnt lgkmcnt(13)
	v_cvt_f64_f32_e32 v[44:45], v128
	v_fmac_f64_e32 v[22:23], v[168:169], v[44:45]
	v_cvt_f64_f32_e32 v[38:39], v129
	ds_read2st64_b32 v[128:129], v27 offset0:93 offset1:94
	v_fmac_f64_e32 v[24:25], v[170:171], v[38:39]
	ds_read_b128 v[168:171], v28 offset:368
	s_waitcnt lgkmcnt(13)
	v_cvt_f64_f32_e32 v[44:45], v130
	v_fmac_f64_e32 v[18:19], v[172:173], v[44:45]
	v_cvt_f64_f32_e32 v[38:39], v131
	ds_read2st64_b32 v[130:131], v27 offset0:95 offset1:96
	v_fmac_f64_e32 v[20:21], v[174:175], v[38:39]
	ds_read_b128 v[172:175], v28 offset:384
	s_waitcnt lgkmcnt(13)
	v_cvt_f64_f32_e32 v[44:45], v136
	v_fmac_f64_e32 v[22:23], v[140:141], v[44:45]
	v_cvt_f64_f32_e32 v[38:39], v137
	ds_read2st64_b32 v[136:137], v27 offset0:97 offset1:98
	v_fmac_f64_e32 v[24:25], v[142:143], v[38:39]
	ds_read_b128 v[140:143], v28 offset:400
	s_waitcnt lgkmcnt(13)
	v_cvt_f64_f32_e32 v[44:45], v138
	v_fmac_f64_e32 v[18:19], v[132:133], v[44:45]
	v_cvt_f64_f32_e32 v[38:39], v139
	ds_read2st64_b32 v[138:139], v27 offset0:99 offset1:100
	v_fmac_f64_e32 v[20:21], v[134:135], v[38:39]
	ds_read_b128 v[132:135], v28 offset:416
	s_waitcnt lgkmcnt(13)
	v_cvt_f64_f32_e32 v[44:45], v152
	v_fmac_f64_e32 v[22:23], v[144:145], v[44:45]
	v_cvt_f64_f32_e32 v[38:39], v153
	ds_read2st64_b32 v[152:153], v27 offset0:101 offset1:102
	v_fmac_f64_e32 v[24:25], v[146:147], v[38:39]
	ds_read_b128 v[144:147], v28 offset:432
	s_waitcnt lgkmcnt(13)
	v_cvt_f64_f32_e32 v[44:45], v154
	v_fmac_f64_e32 v[18:19], v[148:149], v[44:45]
	v_cvt_f64_f32_e32 v[38:39], v155
	ds_read2st64_b32 v[154:155], v27 offset0:103 offset1:104
	v_fmac_f64_e32 v[20:21], v[150:151], v[38:39]
	ds_read_b128 v[148:151], v28 offset:448
	s_waitcnt lgkmcnt(13)
	v_cvt_f64_f32_e32 v[44:45], v160
	v_fmac_f64_e32 v[22:23], v[156:157], v[44:45]
	v_cvt_f64_f32_e32 v[38:39], v161
	ds_read2st64_b32 v[160:161], v27 offset0:105 offset1:106
	v_fmac_f64_e32 v[24:25], v[158:159], v[38:39]
	ds_read_b128 v[156:159], v28 offset:464
	s_waitcnt lgkmcnt(13)
	v_cvt_f64_f32_e32 v[44:45], v128
	v_fmac_f64_e32 v[18:19], v[164:165], v[44:45]
	v_cvt_f64_f32_e32 v[38:39], v129
	ds_read2st64_b32 v[128:129], v27 offset0:107 offset1:108
	v_fmac_f64_e32 v[20:21], v[166:167], v[38:39]
	ds_read_b128 v[164:167], v28 offset:480
	s_waitcnt lgkmcnt(13)
	v_cvt_f64_f32_e32 v[44:45], v130
	v_fmac_f64_e32 v[22:23], v[168:169], v[44:45]
	v_cvt_f64_f32_e32 v[38:39], v131
	ds_read2st64_b32 v[130:131], v27 offset0:109 offset1:110
	v_fmac_f64_e32 v[24:25], v[170:171], v[38:39]
	s_waitcnt lgkmcnt(12)
	v_cvt_f64_f32_e32 v[44:45], v136
	v_fmac_f64_e32 v[18:19], v[172:173], v[44:45]
	v_cvt_f64_f32_e32 v[38:39], v137
	v_fmac_f64_e32 v[20:21], v[174:175], v[38:39]
	s_waitcnt lgkmcnt(10)
	v_cvt_f64_f32_e32 v[44:45], v138
	v_fmac_f64_e32 v[22:23], v[140:141], v[44:45]
	v_cvt_f64_f32_e32 v[38:39], v139
	v_fmac_f64_e32 v[24:25], v[142:143], v[38:39]
	s_waitcnt lgkmcnt(8)
	v_cvt_f64_f32_e32 v[44:45], v152
	v_fmac_f64_e32 v[18:19], v[132:133], v[44:45]
	v_cvt_f64_f32_e32 v[38:39], v153
	v_fmac_f64_e32 v[20:21], v[134:135], v[38:39]
	s_waitcnt lgkmcnt(6)
	v_cvt_f64_f32_e32 v[44:45], v154
	v_fmac_f64_e32 v[22:23], v[144:145], v[44:45]
	v_cvt_f64_f32_e32 v[38:39], v155
	v_fmac_f64_e32 v[24:25], v[146:147], v[38:39]
	s_waitcnt lgkmcnt(4)
	v_cvt_f64_f32_e32 v[44:45], v160
	v_fmac_f64_e32 v[18:19], v[148:149], v[44:45]
	v_cvt_f64_f32_e32 v[38:39], v161
	v_fmac_f64_e32 v[20:21], v[150:151], v[38:39]
	s_waitcnt lgkmcnt(2)
	v_cvt_f64_f32_e32 v[44:45], v128
	v_fmac_f64_e32 v[22:23], v[156:157], v[44:45]
	v_cvt_f64_f32_e32 v[38:39], v129
	v_fmac_f64_e32 v[24:25], v[158:159], v[38:39]
	s_waitcnt lgkmcnt(0)
	v_cvt_f64_f32_e32 v[44:45], v130
	v_fmac_f64_e32 v[18:19], v[164:165], v[44:45]
	v_cvt_f64_f32_e32 v[38:39], v131
	v_fmac_f64_e32 v[20:21], v[166:167], v[38:39]
	ds_read_b128 v[38:41], v28 offset:496
	ds_read2st64_b32 v[42:43], v27 offset0:111 offset1:112
	v_add_f64 v[18:19], v[18:19], v[20:21]
	s_waitcnt lgkmcnt(0)
	v_cvt_f64_f32_e32 v[44:45], v42
	v_fmac_f64_e32 v[22:23], v[38:39], v[44:45]
	v_cvt_f64_f32_e32 v[38:39], v43
	v_fmac_f64_e32 v[24:25], v[40:41], v[38:39]
	v_add_f64 v[20:21], v[22:23], v[24:25]
	v_add_f64 v[18:19], v[18:19], v[20:21]
	v_mul_f64 v[18:19], v[18:19], v[16:17]
	v_mul_f64 v[20:21], v[18:19], s[16:17]
	v_rndne_f64_e32 v[20:21], v[20:21]
	v_fmac_f64_e32 v[18:19], s[14:15], v[20:21]
	v_cvt_f32_f64_e32 v15, v[18:19]
	v_and_b32_e32 v18, 0x7fffffff, v15
	v_cmp_nlt_f32_e64 s[6:7], |v15|, s2
	s_and_saveexec_b64 s[8:9], s[6:7]
	s_xor_b64 s[18:19], exec, s[8:9]
	s_cbranch_execz .LBB0_853
	v_lshrrev_b32_e32 v0, 23, v18
	v_add_u32_e32 v0, 0xffffff88, v0
	v_cmp_lt_u32_e32 vcc, 63, v0
	s_nop 1
	v_cndmask_b32_e32 v19, 0, v34, vcc
	v_add_u32_e32 v0, v19, v0
	v_cmp_lt_u32_e64 s[6:7], 31, v0
	s_nop 1
	v_cndmask_b32_e64 v19, 0, v35, s[6:7]
	v_add_u32_e32 v0, v19, v0
	v_cmp_lt_u32_e64 s[8:9], 31, v0
	s_nop 1
	v_cndmask_b32_e64 v19, 0, v35, s[8:9]
	v_add_u32_e32 v19, v19, v0
	v_and_b32_e32 v0, 0x7fffff, v18
	v_or_b32_e32 v37, 0x800000, v0
	v_mad_u64_u32 v[20:21], s[10:11], v37, s3, 0
	v_mov_b32_e32 v0, v21
	v_mad_u64_u32 v[22:23], s[10:11], v37, s4, v[0:1]
	v_mov_b32_e32 v0, v23
	v_mad_u64_u32 v[24:25], s[10:11], v37, s5, v[0:1]
	v_mov_b32_e32 v0, v25
	v_mad_u64_u32 v[38:39], s[10:11], v37, s22, v[0:1]
	v_mov_b32_e32 v0, v39
	v_mad_u64_u32 v[40:41], s[10:11], v37, s23, v[0:1]
	v_mov_b32_e32 v0, v41
	v_mad_u64_u32 v[42:43], s[10:11], v37, s24, v[0:1]
	v_mov_b32_e32 v0, v43
	v_mad_u64_u32 v[44:45], s[10:11], v37, s25, v[0:1]
	v_cndmask_b32_e32 v21, v42, v38, vcc
	v_cndmask_b32_e32 v0, v44, v40, vcc
	v_cndmask_b32_e32 v25, v45, v42, vcc
	v_cndmask_b32_e64 v23, v0, v21, s[6:7]
	v_cndmask_b32_e64 v0, v25, v0, s[6:7]
	v_cndmask_b32_e32 v25, v40, v24, vcc
	v_cndmask_b32_e64 v21, v21, v25, s[6:7]
	v_sub_u32_e32 v37, 32, v19
	v_cmp_eq_u32_e64 s[10:11], 0, v19
	v_cndmask_b32_e32 v19, v38, v22, vcc
	v_cndmask_b32_e64 v0, v0, v23, s[8:9]
	v_cndmask_b32_e64 v23, v23, v21, s[8:9]
	v_cndmask_b32_e64 v22, v25, v19, s[6:7]
	v_alignbit_b32 v39, v0, v23, v37
	v_cndmask_b32_e64 v21, v21, v22, s[8:9]
	v_cndmask_b32_e64 v0, v39, v0, s[10:11]
	v_alignbit_b32 v25, v23, v21, v37
	v_cndmask_b32_e32 v20, v24, v20, vcc
	v_cndmask_b32_e64 v23, v25, v23, s[10:11]
	v_bfe_u32 v39, v0, 29, 1
	v_cndmask_b32_e64 v19, v19, v20, s[6:7]
	v_alignbit_b32 v25, v0, v23, 30
	v_sub_u32_e32 v40, 0, v39
	v_cndmask_b32_e64 v19, v22, v19, s[8:9]
	v_xor_b32_e32 v25, v25, v40
	v_alignbit_b32 v20, v21, v19, v37
	v_cndmask_b32_e64 v20, v20, v21, s[10:11]
	v_ffbh_u32_e32 v22, v25
	v_alignbit_b32 v21, v23, v20, 30
	v_min_u32_e32 v22, 32, v22
	v_alignbit_b32 v19, v20, v19, 30
	v_xor_b32_e32 v21, v21, v40
	v_sub_u32_e32 v23, 31, v22
	v_xor_b32_e32 v19, v19, v40
	v_alignbit_b32 v24, v25, v21, v23
	v_alignbit_b32 v19, v21, v19, v23
	v_alignbit_b32 v20, v24, v19, 9
	v_ffbh_u32_e32 v21, v20
	v_min_u32_e32 v21, 32, v21
	v_lshrrev_b32_e32 v38, 29, v0
	v_not_b32_e32 v23, v21
	v_alignbit_b32 v19, v20, v19, v23
	v_lshlrev_b32_e32 v20, 31, v38
	v_or_b32_e32 v23, 0x33000000, v20
	v_add_lshl_u32 v21, v21, v22, 23
	v_lshrrev_b32_e32 v19, 9, v19
	v_sub_u32_e32 v21, v23, v21
	v_or_b32_e32 v20, 0.5, v20
	v_lshlrev_b32_e32 v22, 23, v22
	v_or_b32_e32 v19, v21, v19
	v_lshrrev_b32_e32 v21, 9, v24
	v_sub_u32_e32 v20, v20, v22
	v_or_b32_e32 v20, v21, v20
	v_mul_f32_e32 v21, 0x3fc90fda, v20
	v_fma_f32 v22, v20, s26, -v21
	v_fmac_f32_e32 v22, 0x33a22168, v20
	v_fmac_f32_e32 v22, 0x3fc90fda, v19
	v_lshrrev_b32_e32 v0, 30, v0
	v_add_f32_e32 v19, v21, v22
	v_add_u32_e32 v0, v39, v0
.LBB0_853:
	s_andn2_saveexec_b64 s[6:7], s[18:19]
	v_mul_f32_e64 v0, |v15|, s27
	v_rndne_f32_e32 v20, v0
	v_cvt_i32_f32_e32 v0, v20
	v_fma_f32 v19, v20, s28, |v15|
	v_fmac_f32_e32 v19, 0xb3a22168, v20
	v_fmac_f32_e32 v19, 0xa7c234c4, v20
	s_or_b64 exec, exec, s[6:7]
	v_mul_f32_e32 v20, v19, v19
	v_fmamk_f32 v21, v20, 0xb94c1982, v32
	v_fmaak_f32 v21, v20, v21, 0xbe2aaa9d
	v_mul_f32_e32 v21, v20, v21
	v_fmac_f32_e32 v19, v19, v21
	v_fmamk_f32 v21, v20, 0x37d75334, v33
	v_fmaak_f32 v21, v20, v21, 0x3d2aabf7
	v_fmaak_f32 v21, v20, v21, 0xbf000004
	v_fma_f32 v20, v20, v21, 1.0
	v_and_b32_e32 v21, 1, v0
	v_lshlrev_b32_e32 v0, 30, v0
	v_cmp_eq_u32_e32 vcc, 0, v21
	v_and_b32_e32 v0, 0x80000000, v0
	v_xor_b32_e32 v18, v18, v15
	v_cndmask_b32_e32 v19, v20, v19, vcc
	v_xor_b32_e32 v0, v18, v0
	v_xor_b32_e32 v0, v0, v19
	v_cmp_class_f32_e64 vcc, v15, s29
	s_barrier
	s_nop 0
	v_cndmask_b32_e32 v0, v36, v0, vcc
	v_cvt_f64_f32_e32 v[18:19], v0
	ds_write_b64 v29, v[18:19]
	s_waitcnt lgkmcnt(0)
	s_barrier
	ds_read_b128 v[128:131], v28
	ds_read_b128 v[132:135], v28 offset:16
	ds_read_b128 v[136:139], v28 offset:32
	ds_read2st64_b32 v[140:141], v27 offset0:113 offset1:114
	global_load_dword v0, v[10:11], off
	ds_read_b128 v[46:49], v28 offset:48
	s_waitcnt lgkmcnt(1)
	v_cvt_f64_f32_e32 v[50:51], v140
	s_waitcnt vmcnt(0)
	ds_read2st64_b32 v[142:143], v27 offset0:115 offset1:116
	ds_read2st64_b32 v[144:145], v27 offset0:117 offset1:118
	ds_read2st64_b32 v[146:147], v27 offset0:119 offset1:120
	ds_read_b128 v[148:151], v28 offset:64
	ds_read2st64_b32 v[152:153], v27 offset0:121 offset1:122
	ds_read_b128 v[156:159], v28 offset:80
	ds_read2st64_b32 v[154:155], v27 offset0:123 offset1:124
	ds_read_b128 v[164:167], v28 offset:96
	ds_read2st64_b32 v[160:161], v27 offset0:125 offset1:126
	ds_read_b128 v[168:171], v28 offset:112
	ds_read2st64_b32 v[172:173], v27 offset0:127 offset1:128
	v_cvt_f64_f32_e32 v[18:19], v0
	v_fmac_f64_e32 v[18:19], v[128:129], v[50:51]
	v_cvt_f64_f32_e32 v[20:21], v141
	ds_read_b128 v[176:179], v28 offset:128
	v_fma_f64 v[20:21], v[130:131], v[20:21], 0
	ds_read2st64_b32 v[128:129], v27 offset0:129 offset1:130
	s_waitcnt lgkmcnt(12)
	v_cvt_f64_f32_e32 v[22:23], v142
	v_fma_f64 v[22:23], v[132:133], v[22:23], 0
	v_cvt_f64_f32_e32 v[24:25], v143
	ds_read_b128 v[140:143], v28 offset:144
	v_fma_f64 v[24:25], v[134:135], v[24:25], 0
	ds_read2st64_b32 v[130:131], v27 offset0:131 offset1:132
	s_waitcnt lgkmcnt(13)
	v_cvt_f64_f32_e32 v[40:41], v144
	v_cvt_f64_f32_e32 v[38:39], v145
	ds_read_b128 v[132:135], v28 offset:160
	v_fmac_f64_e32 v[20:21], v[138:139], v[38:39]
	v_fmac_f64_e32 v[18:19], v[136:137], v[40:41]
	ds_read2st64_b32 v[136:137], v27 offset0:133 offset1:134
	s_waitcnt lgkmcnt(14)
	v_cvt_f64_f32_e32 v[40:41], v146
	v_cvt_f64_f32_e32 v[38:39], v147
	ds_read_b128 v[144:147], v28 offset:176
	v_fmac_f64_e32 v[22:23], v[46:47], v[40:41]
	v_fmac_f64_e32 v[24:25], v[48:49], v[38:39]
	s_waitcnt lgkmcnt(13)
	v_cvt_f64_f32_e32 v[44:45], v152
	v_fmac_f64_e32 v[18:19], v[148:149], v[44:45]
	v_cvt_f64_f32_e32 v[38:39], v153
	ds_read2st64_b32 v[138:139], v27 offset0:135 offset1:136
	v_fmac_f64_e32 v[20:21], v[150:151], v[38:39]
	ds_read_b128 v[148:151], v28 offset:192
	s_waitcnt lgkmcnt(13)
	v_cvt_f64_f32_e32 v[44:45], v154
	v_fmac_f64_e32 v[22:23], v[156:157], v[44:45]
	v_cvt_f64_f32_e32 v[38:39], v155
	ds_read2st64_b32 v[152:153], v27 offset0:137 offset1:138
	v_fmac_f64_e32 v[24:25], v[158:159], v[38:39]
	ds_read_b128 v[156:159], v28 offset:208
	s_waitcnt lgkmcnt(13)
	v_cvt_f64_f32_e32 v[44:45], v160
	v_fmac_f64_e32 v[18:19], v[164:165], v[44:45]
	v_cvt_f64_f32_e32 v[38:39], v161
	ds_read2st64_b32 v[154:155], v27 offset0:139 offset1:140
	v_fmac_f64_e32 v[20:21], v[166:167], v[38:39]
	ds_read_b128 v[164:167], v28 offset:224
	s_waitcnt lgkmcnt(13)
	v_cvt_f64_f32_e32 v[44:45], v172
	v_fmac_f64_e32 v[22:23], v[168:169], v[44:45]
	v_cvt_f64_f32_e32 v[38:39], v173
	ds_read2st64_b32 v[160:161], v27 offset0:141 offset1:142
	v_fmac_f64_e32 v[24:25], v[170:171], v[38:39]
	ds_read_b128 v[168:171], v28 offset:240
	s_waitcnt lgkmcnt(13)
	v_cvt_f64_f32_e32 v[44:45], v128
	v_fmac_f64_e32 v[18:19], v[176:177], v[44:45]
	v_cvt_f64_f32_e32 v[38:39], v129
	ds_read2st64_b32 v[128:129], v27 offset0:143 offset1:144
	v_fmac_f64_e32 v[20:21], v[178:179], v[38:39]
	ds_read_b128 v[172:175], v28 offset:256
	s_waitcnt lgkmcnt(13)
	v_cvt_f64_f32_e32 v[44:45], v130
	v_fmac_f64_e32 v[22:23], v[140:141], v[44:45]
	v_cvt_f64_f32_e32 v[38:39], v131
	ds_read2st64_b32 v[130:131], v27 offset0:145 offset1:146
	v_fmac_f64_e32 v[24:25], v[142:143], v[38:39]
	ds_read_b128 v[140:143], v28 offset:272
	s_waitcnt lgkmcnt(13)
	v_cvt_f64_f32_e32 v[44:45], v136
	v_fmac_f64_e32 v[18:19], v[132:133], v[44:45]
	v_cvt_f64_f32_e32 v[38:39], v137
	ds_read2st64_b32 v[136:137], v27 offset0:147 offset1:148
	v_fmac_f64_e32 v[20:21], v[134:135], v[38:39]
	ds_read_b128 v[132:135], v28 offset:288
	s_waitcnt lgkmcnt(13)
	v_cvt_f64_f32_e32 v[44:45], v138
	v_fmac_f64_e32 v[22:23], v[144:145], v[44:45]
	v_cvt_f64_f32_e32 v[38:39], v139
	ds_read2st64_b32 v[138:139], v27 offset0:149 offset1:150
	v_fmac_f64_e32 v[24:25], v[146:147], v[38:39]
	ds_read_b128 v[144:147], v28 offset:304
	s_waitcnt lgkmcnt(13)
	v_cvt_f64_f32_e32 v[44:45], v152
	v_fmac_f64_e32 v[18:19], v[148:149], v[44:45]
	v_cvt_f64_f32_e32 v[38:39], v153
	ds_read2st64_b32 v[152:153], v27 offset0:151 offset1:152
	v_fmac_f64_e32 v[20:21], v[150:151], v[38:39]
	ds_read_b128 v[148:151], v28 offset:320
	s_waitcnt lgkmcnt(13)
	v_cvt_f64_f32_e32 v[44:45], v154
	v_fmac_f64_e32 v[22:23], v[156:157], v[44:45]
	v_cvt_f64_f32_e32 v[38:39], v155
	ds_read2st64_b32 v[154:155], v27 offset0:153 offset1:154
	v_fmac_f64_e32 v[24:25], v[158:159], v[38:39]
	ds_read_b128 v[156:159], v28 offset:336
	s_waitcnt lgkmcnt(13)
	v_cvt_f64_f32_e32 v[44:45], v160
	v_fmac_f64_e32 v[18:19], v[164:165], v[44:45]
	v_cvt_f64_f32_e32 v[38:39], v161
	ds_read2st64_b32 v[160:161], v27 offset0:155 offset1:156
	v_fmac_f64_e32 v[20:21], v[166:167], v[38:39]
	ds_read_b128 v[164:167], v28 offset:352
	s_waitcnt lgkmcnt(13)
	v_cvt_f64_f32_e32 v[44:45], v128
	v_fmac_f64_e32 v[22:23], v[168:169], v[44:45]
	v_cvt_f64_f32_e32 v[38:39], v129
	ds_read2st64_b32 v[128:129], v27 offset0:157 offset1:158
	v_fmac_f64_e32 v[24:25], v[170:171], v[38:39]
	ds_read_b128 v[168:171], v28 offset:368
	s_waitcnt lgkmcnt(13)
	v_cvt_f64_f32_e32 v[44:45], v130
	v_fmac_f64_e32 v[18:19], v[172:173], v[44:45]
	v_cvt_f64_f32_e32 v[38:39], v131
	ds_read2st64_b32 v[130:131], v27 offset0:159 offset1:160
	v_fmac_f64_e32 v[20:21], v[174:175], v[38:39]
	ds_read_b128 v[172:175], v28 offset:384
	s_waitcnt lgkmcnt(13)
	v_cvt_f64_f32_e32 v[44:45], v136
	v_fmac_f64_e32 v[22:23], v[140:141], v[44:45]
	v_cvt_f64_f32_e32 v[38:39], v137
	ds_read2st64_b32 v[136:137], v27 offset0:161 offset1:162
	v_fmac_f64_e32 v[24:25], v[142:143], v[38:39]
	ds_read_b128 v[140:143], v28 offset:400
	s_waitcnt lgkmcnt(13)
	v_cvt_f64_f32_e32 v[44:45], v138
	v_fmac_f64_e32 v[18:19], v[132:133], v[44:45]
	v_cvt_f64_f32_e32 v[38:39], v139
	ds_read2st64_b32 v[138:139], v27 offset0:163 offset1:164
	v_fmac_f64_e32 v[20:21], v[134:135], v[38:39]
	ds_read_b128 v[132:135], v28 offset:416
	s_waitcnt lgkmcnt(13)
	v_cvt_f64_f32_e32 v[44:45], v152
	v_fmac_f64_e32 v[22:23], v[144:145], v[44:45]
	v_cvt_f64_f32_e32 v[38:39], v153
	ds_read2st64_b32 v[152:153], v27 offset0:165 offset1:166
	v_fmac_f64_e32 v[24:25], v[146:147], v[38:39]
	ds_read_b128 v[144:147], v28 offset:432
	s_waitcnt lgkmcnt(13)
	v_cvt_f64_f32_e32 v[44:45], v154
	v_fmac_f64_e32 v[18:19], v[148:149], v[44:45]
	v_cvt_f64_f32_e32 v[38:39], v155
	ds_read2st64_b32 v[154:155], v27 offset0:167 offset1:168
	v_fmac_f64_e32 v[20:21], v[150:151], v[38:39]
	ds_read_b128 v[148:151], v28 offset:448
	s_waitcnt lgkmcnt(13)
	v_cvt_f64_f32_e32 v[44:45], v160
	v_fmac_f64_e32 v[22:23], v[156:157], v[44:45]
	v_cvt_f64_f32_e32 v[38:39], v161
	ds_read2st64_b32 v[160:161], v27 offset0:169 offset1:170
	v_fmac_f64_e32 v[24:25], v[158:159], v[38:39]
	ds_read_b128 v[156:159], v28 offset:464
	s_waitcnt lgkmcnt(13)
	v_cvt_f64_f32_e32 v[44:45], v128
	v_fmac_f64_e32 v[18:19], v[164:165], v[44:45]
	v_cvt_f64_f32_e32 v[38:39], v129
	ds_read2st64_b32 v[128:129], v27 offset0:171 offset1:172
	v_fmac_f64_e32 v[20:21], v[166:167], v[38:39]
	ds_read_b128 v[164:167], v28 offset:480
	s_waitcnt lgkmcnt(13)
	v_cvt_f64_f32_e32 v[44:45], v130
	v_fmac_f64_e32 v[22:23], v[168:169], v[44:45]
	v_cvt_f64_f32_e32 v[38:39], v131
	ds_read2st64_b32 v[130:131], v27 offset0:173 offset1:174
	v_fmac_f64_e32 v[24:25], v[170:171], v[38:39]
	s_waitcnt lgkmcnt(12)
	v_cvt_f64_f32_e32 v[44:45], v136
	v_fmac_f64_e32 v[18:19], v[172:173], v[44:45]
	v_cvt_f64_f32_e32 v[38:39], v137
	v_fmac_f64_e32 v[20:21], v[174:175], v[38:39]
	s_waitcnt lgkmcnt(10)
	v_cvt_f64_f32_e32 v[44:45], v138
	v_fmac_f64_e32 v[22:23], v[140:141], v[44:45]
	v_cvt_f64_f32_e32 v[38:39], v139
	v_fmac_f64_e32 v[24:25], v[142:143], v[38:39]
	s_waitcnt lgkmcnt(8)
	v_cvt_f64_f32_e32 v[44:45], v152
	v_fmac_f64_e32 v[18:19], v[132:133], v[44:45]
	v_cvt_f64_f32_e32 v[38:39], v153
	v_fmac_f64_e32 v[20:21], v[134:135], v[38:39]
	s_waitcnt lgkmcnt(6)
	v_cvt_f64_f32_e32 v[44:45], v154
	v_fmac_f64_e32 v[22:23], v[144:145], v[44:45]
	v_cvt_f64_f32_e32 v[38:39], v155
	v_fmac_f64_e32 v[24:25], v[146:147], v[38:39]
	s_waitcnt lgkmcnt(4)
	v_cvt_f64_f32_e32 v[44:45], v160
	v_fmac_f64_e32 v[18:19], v[148:149], v[44:45]
	v_cvt_f64_f32_e32 v[38:39], v161
	v_fmac_f64_e32 v[20:21], v[150:151], v[38:39]
	s_waitcnt lgkmcnt(2)
	v_cvt_f64_f32_e32 v[44:45], v128
	v_fmac_f64_e32 v[22:23], v[156:157], v[44:45]
	v_cvt_f64_f32_e32 v[38:39], v129
	v_fmac_f64_e32 v[24:25], v[158:159], v[38:39]
	s_waitcnt lgkmcnt(0)
	v_cvt_f64_f32_e32 v[44:45], v130
	v_fmac_f64_e32 v[18:19], v[164:165], v[44:45]
	v_cvt_f64_f32_e32 v[38:39], v131
	v_fmac_f64_e32 v[20:21], v[166:167], v[38:39]
	ds_read_b128 v[38:41], v28 offset:496
	ds_read2st64_b32 v[42:43], v27 offset0:175 offset1:176
	v_add_f64 v[18:19], v[18:19], v[20:21]
	s_waitcnt lgkmcnt(0)
	v_cvt_f64_f32_e32 v[44:45], v42
	v_fmac_f64_e32 v[22:23], v[38:39], v[44:45]
	v_cvt_f64_f32_e32 v[38:39], v43
	v_fmac_f64_e32 v[24:25], v[40:41], v[38:39]
	v_add_f64 v[20:21], v[22:23], v[24:25]
	v_add_f64 v[18:19], v[18:19], v[20:21]
	v_mul_f64 v[16:17], v[18:19], v[16:17]
	v_mul_f64 v[18:19], v[16:17], s[16:17]
	v_rndne_f64_e32 v[18:19], v[18:19]
	v_fmac_f64_e32 v[16:17], s[14:15], v[18:19]
	v_cvt_f32_f64_e32 v15, v[16:17]
	v_and_b32_e32 v16, 0x7fffffff, v15
	v_cmp_nlt_f32_e64 s[6:7], |v15|, s2
	s_and_saveexec_b64 s[8:9], s[6:7]
	s_xor_b64 s[18:19], exec, s[8:9]
	s_cbranch_execz .LBB0_857
	v_lshrrev_b32_e32 v0, 23, v16
	v_add_u32_e32 v0, 0xffffff88, v0
	v_cmp_lt_u32_e32 vcc, 63, v0
	s_nop 1
	v_cndmask_b32_e32 v17, 0, v34, vcc
	v_add_u32_e32 v0, v17, v0
	v_cmp_lt_u32_e64 s[6:7], 31, v0
	s_nop 1
	v_cndmask_b32_e64 v17, 0, v35, s[6:7]
	v_add_u32_e32 v0, v17, v0
	v_cmp_lt_u32_e64 s[8:9], 31, v0
	s_nop 1
	v_cndmask_b32_e64 v17, 0, v35, s[8:9]
	v_add_u32_e32 v17, v17, v0
	v_and_b32_e32 v0, 0x7fffff, v16
	v_or_b32_e32 v37, 0x800000, v0
	v_mad_u64_u32 v[18:19], s[10:11], v37, s3, 0
	v_mov_b32_e32 v0, v19
	v_mad_u64_u32 v[20:21], s[10:11], v37, s4, v[0:1]
	v_mov_b32_e32 v0, v21
	v_mad_u64_u32 v[22:23], s[10:11], v37, s5, v[0:1]
	v_mov_b32_e32 v0, v23
	v_mad_u64_u32 v[24:25], s[10:11], v37, s22, v[0:1]
	v_mov_b32_e32 v0, v25
	v_mad_u64_u32 v[38:39], s[10:11], v37, s23, v[0:1]
	v_mov_b32_e32 v0, v39
	v_mad_u64_u32 v[40:41], s[10:11], v37, s24, v[0:1]
	v_mov_b32_e32 v0, v41
	v_mad_u64_u32 v[42:43], s[10:11], v37, s25, v[0:1]
	v_cndmask_b32_e32 v19, v40, v24, vcc
	v_cndmask_b32_e32 v0, v42, v38, vcc
	v_cndmask_b32_e32 v23, v43, v40, vcc
	v_cndmask_b32_e64 v21, v0, v19, s[6:7]
	v_cndmask_b32_e64 v0, v23, v0, s[6:7]
	v_cndmask_b32_e32 v23, v38, v22, vcc
	v_cndmask_b32_e64 v19, v19, v23, s[6:7]
	v_sub_u32_e32 v25, 32, v17
	v_cmp_eq_u32_e64 s[10:11], 0, v17
	v_cndmask_b32_e32 v17, v24, v20, vcc
	v_cndmask_b32_e64 v0, v0, v21, s[8:9]
	v_cndmask_b32_e64 v21, v21, v19, s[8:9]
	v_cndmask_b32_e64 v20, v23, v17, s[6:7]
	v_alignbit_b32 v37, v0, v21, v25
	v_cndmask_b32_e64 v19, v19, v20, s[8:9]
	v_cndmask_b32_e64 v0, v37, v0, s[10:11]
	v_alignbit_b32 v23, v21, v19, v25
	v_cndmask_b32_e32 v18, v22, v18, vcc
	v_cndmask_b32_e64 v21, v23, v21, s[10:11]
	v_bfe_u32 v37, v0, 29, 1
	v_cndmask_b32_e64 v17, v17, v18, s[6:7]
	v_alignbit_b32 v23, v0, v21, 30
	v_sub_u32_e32 v38, 0, v37
	v_cndmask_b32_e64 v17, v20, v17, s[8:9]
	v_xor_b32_e32 v23, v23, v38
	v_alignbit_b32 v18, v19, v17, v25
	v_cndmask_b32_e64 v18, v18, v19, s[10:11]
	v_ffbh_u32_e32 v20, v23
	v_alignbit_b32 v19, v21, v18, 30
	v_min_u32_e32 v20, 32, v20
	v_alignbit_b32 v17, v18, v17, 30
	v_xor_b32_e32 v19, v19, v38
	v_sub_u32_e32 v21, 31, v20
	v_xor_b32_e32 v17, v17, v38
	v_alignbit_b32 v22, v23, v19, v21
	v_alignbit_b32 v17, v19, v17, v21
	v_alignbit_b32 v18, v22, v17, 9
	v_ffbh_u32_e32 v19, v18
	v_min_u32_e32 v19, 32, v19
	v_lshrrev_b32_e32 v24, 29, v0
	v_not_b32_e32 v21, v19
	v_alignbit_b32 v17, v18, v17, v21
	v_lshlrev_b32_e32 v18, 31, v24
	v_or_b32_e32 v21, 0x33000000, v18
	v_add_lshl_u32 v19, v19, v20, 23
	v_lshrrev_b32_e32 v17, 9, v17
	v_sub_u32_e32 v19, v21, v19
	v_or_b32_e32 v18, 0.5, v18
	v_lshlrev_b32_e32 v20, 23, v20
	v_or_b32_e32 v17, v19, v17
	v_lshrrev_b32_e32 v19, 9, v22
	v_sub_u32_e32 v18, v18, v20
	v_or_b32_e32 v18, v19, v18
	v_mul_f32_e32 v19, 0x3fc90fda, v18
	v_fma_f32 v20, v18, s26, -v19
	v_fmac_f32_e32 v20, 0x33a22168, v18
	v_fmac_f32_e32 v20, 0x3fc90fda, v17
	v_lshrrev_b32_e32 v0, 30, v0
	v_add_f32_e32 v17, v19, v20
	v_add_u32_e32 v0, v37, v0

.LBB0_1549:
	v_mov_b32_e32 v64, v35
	s_mul_i32 s10, s40, 0x4400
	s_mul_hi_i32 s2, s40, 0x4400
	s_add_u32 s6, s92, s10
	v_ashrrev_i32_e32 v65, 31, v64
	s_addc_u32 s7, s93, s2
	s_waitcnt vmcnt(10)
	v_lshlrev_b64 v[16:17], 2, v[64:65]
	s_waitcnt vmcnt(5)
	v_lshl_add_u64 v[12:13], s[6:7], 0, v[16:17]
	s_add_i32 s2, s40, 0x800
	s_add_i32 s12, s10, 0x2200000
	s_add_i32 s42, s40, 0x1000
	s_add_i32 s8, s10, 0x4400000
	s_waitcnt vmcnt(4)
	v_add_co_u32_e32 v6, vcc, s69, v12
	s_mul_hi_i32 s9, s42, 0x4400
	s_add_u32 s8, s92, s8
	s_waitcnt vmcnt(0)
	v_addc_co_u32_e32 v7, vcc, 0, v13, vcc
	s_addc_u32 s9, s93, s9
	v_add_co_u32_e32 v10, vcc, s73, v12
	v_lshl_add_u64 v[14:15], s[8:9], 0, v[16:17]
	s_nop 0
	v_addc_co_u32_e32 v11, vcc, 0, v13, vcc
	v_add_co_u32_e32 v8, vcc, s69, v14
	s_add_i32 s13, s40, 0x1800
	s_nop 0
	v_addc_co_u32_e32 v9, vcc, 0, v15, vcc
	v_add_co_u32_e32 v18, vcc, s73, v14
	s_add_i32 s10, s10, 0x6600000
	s_nop 0
	v_addc_co_u32_e32 v19, vcc, 0, v15, vcc
	s_mul_hi_i32 s13, s13, 0x4400
	s_add_u32 s10, s92, s10
	global_load_dword v0, v[12:13], off
	global_load_dword v1, v[14:15], off
	global_load_dword v2, v[12:13], off offset:2048
	global_load_dword v3, v[14:15], off offset:2048
	global_load_dword v4, v[10:11], off offset:-4096
	global_load_dword v5, v[18:19], off offset:-4096
	s_nop 0
	global_load_dword v6, v[6:7], off offset:2048
	s_nop 0
	global_load_dword v7, v[8:9], off offset:2048
	s_nop 0
	global_load_dword v8, v[10:11], off
	global_load_dword v9, v[18:19], off
	s_nop 0
	global_load_dword v10, v[10:11], off offset:2048
	s_nop 0
	global_load_dword v11, v[18:19], off offset:2048
	v_add_co_u32_e32 v18, vcc, s94, v12
	s_addc_u32 s13, s93, s13
	s_nop 0
	v_addc_co_u32_e32 v19, vcc, 0, v13, vcc
	s_mul_hi_i32 s11, s2, 0x4400
	v_add_co_u32_e32 v20, vcc, s94, v14
	s_add_u32 s6, s92, s12
	s_nop 0
	v_addc_co_u32_e32 v21, vcc, 0, v15, vcc
	s_addc_u32 s7, s93, s11
	global_load_dword v12, v[18:19], off
	global_load_dword v13, v[20:21], off
	global_load_dword v14, v[18:19], off offset:2048
	global_load_dword v15, v[20:21], off offset:2048
	v_sub_co_u32_e32 v26, vcc, s6, v16
	v_mov_b32_e32 v18, s7
	s_nop 0
	v_subb_co_u32_e32 v27, vcc, v18, v17, vcc
	v_sub_co_u32_e32 v30, vcc, s10, v16
	v_mov_b32_e32 v16, s13
	s_nop 0
	v_subb_co_u32_e32 v31, vcc, v16, v17, vcc
	v_add_co_u32_e32 v16, vcc, s1, v26
	v_lshl_add_u64 v[20:21], v[26:27], 0, s[48:49]
	s_nop 0
	v_addc_co_u32_e32 v17, vcc, 0, v27, vcc
	global_load_dword v44, v[16:17], off
	v_add_co_u32_e32 v16, vcc, s1, v30
	v_lshl_add_u64 v[22:23], v[30:31], 0, s[48:49]
	s_nop 0
	v_addc_co_u32_e32 v17, vcc, 0, v31, vcc
	global_load_dword v45, v[16:17], off
	global_load_dword v18, v[20:21], off offset:-2048
	global_load_dword v19, v[22:23], off offset:-2048
	s_nop 0
	global_load_dword v16, v[20:21], off offset:-4096
	global_load_dword v17, v[22:23], off offset:-4096
	v_add_co_u32_e32 v22, vcc, s73, v26
	v_add_u32_e32 v34, 0x200, v64
	s_nop 0
	v_addc_co_u32_e32 v23, vcc, 0, v27, vcc
	global_load_dword v20, v[22:23], off offset:2048
	v_add_co_u32_e32 v24, vcc, s73, v30
	v_add_u32_e32 v36, 0x400, v64
	s_nop 0
	v_addc_co_u32_e32 v25, vcc, 0, v31, vcc
	global_load_dword v21, v[24:25], off offset:2048
	s_nop 0
	global_load_dword v22, v[22:23], off
	s_nop 0
	global_load_dword v23, v[24:25], off
	v_add_co_u32_e32 v28, vcc, s69, v26
	v_add_u32_e32 v37, 0x600, v64
	s_nop 0
	v_addc_co_u32_e32 v29, vcc, 0, v27, vcc
	global_load_dword v24, v[28:29], off offset:2048
	v_add_co_u32_e32 v32, vcc, s69, v30
	v_add_u32_e32 v38, 0x800, v64
	s_nop 0
	v_addc_co_u32_e32 v33, vcc, 0, v31, vcc
	global_load_dword v25, v[32:33], off offset:2048
	s_nop 0
	global_load_dword v28, v[28:29], off
	s_nop 0
	global_load_dword v29, v[32:33], off
	s_nop 0
	global_load_dword v26, v[26:27], off offset:2048
	s_nop 0
	global_load_dword v27, v[30:31], off offset:2048
	v_ashrrev_i32_e32 v32, 4, v64
	v_lshlrev_b32_e32 v30, 3, v32
	v_lshlrev_b32_e32 v33, 3, v64
	v_add3_u32 v30, s3, v30, v33
	v_cmp_eq_u32_e32 vcc, 0, v64
	v_add_u32_e32 v40, 0xa00, v64
	v_add_u32_e32 v41, 0xc00, v64
	v_add_u32_e32 v42, 0xe00, v64
	s_waitcnt vmcnt(30)
	ds_write_b64 v30, v[0:1]
	s_waitcnt vmcnt(15)
	v_cndmask_b32_e64 v30, v44, 0, vcc
	v_add_u32_e32 v44, 0x1000, v64
	v_ashrrev_i32_e32 v44, 4, v44
	v_lshlrev_b32_e32 v44, 3, v44
	s_waitcnt vmcnt(14)
	v_cndmask_b32_e64 v31, v45, 0, vcc
	v_add3_u32 v44, s3, v44, v33
	ds_write_b64 v44, v[30:31] offset:32768
	v_add_f32_e64 v0, |v0|, |v30|
	v_ashrrev_i32_e32 v30, 4, v34
	v_lshlrev_b32_e32 v30, 3, v30
	v_add3_u32 v30, s3, v30, v33
	ds_write_b64 v30, v[2:3] offset:4096
	v_add_f32_e64 v0, |v2|, v0
	v_add_u32_e32 v2, 0x1200, v64
	v_ashrrev_i32_e32 v2, 4, v2
	v_lshlrev_b32_e32 v2, 3, v2
	v_add3_u32 v2, s3, v2, v33
	s_waitcnt vmcnt(12)
	ds_write_b64 v2, v[18:19] offset:36864
	v_ashrrev_i32_e32 v2, 4, v36
	v_lshlrev_b32_e32 v2, 3, v2
	v_add3_u32 v2, s3, v2, v33
	ds_write_b64 v2, v[4:5] offset:8192
	v_add_u32_e32 v2, 0x1400, v64
	v_ashrrev_i32_e32 v2, 4, v2
	v_lshlrev_b32_e32 v2, 3, v2
	v_add3_u32 v2, s3, v2, v33
	s_waitcnt vmcnt(10)
	ds_write_b64 v2, v[16:17] offset:40960
	v_ashrrev_i32_e32 v2, 4, v37
	v_lshlrev_b32_e32 v2, 3, v2
	v_add3_u32 v2, s3, v2, v33
	ds_write_b64 v2, v[6:7] offset:12288
	v_add_u32_e32 v2, 0x1600, v64
	v_ashrrev_i32_e32 v2, 4, v2
	v_lshlrev_b32_e32 v2, 3, v2
	v_add3_u32 v2, s3, v2, v33
	s_waitcnt vmcnt(8)
	ds_write_b64 v2, v[20:21] offset:45056
	v_ashrrev_i32_e32 v2, 4, v38
	v_lshlrev_b32_e32 v2, 3, v2
	v_add3_u32 v2, s3, v2, v33
	ds_write_b64 v2, v[8:9] offset:16384
	v_add_u32_e32 v2, 0x1800, v64
	v_ashrrev_i32_e32 v2, 4, v2
	v_lshlrev_b32_e32 v2, 3, v2
	v_add3_u32 v2, s3, v2, v33
	s_waitcnt vmcnt(6)
	ds_write_b64 v2, v[22:23] offset:49152
	v_ashrrev_i32_e32 v2, 4, v40
	v_lshlrev_b32_e32 v2, 3, v2
	v_add3_u32 v2, s3, v2, v33
	ds_write_b64 v2, v[10:11] offset:20480
	v_add_u32_e32 v2, 0x1a00, v64
	v_ashrrev_i32_e32 v2, 4, v2
	v_lshlrev_b32_e32 v2, 3, v2
	v_add3_u32 v2, s3, v2, v33
	s_waitcnt vmcnt(4)
	ds_write_b64 v2, v[24:25] offset:53248
	v_ashrrev_i32_e32 v2, 4, v41
	v_lshlrev_b32_e32 v2, 3, v2
	v_add3_u32 v2, s3, v2, v33
	ds_write_b64 v2, v[12:13] offset:24576
	v_add_u32_e32 v2, 0x1c00, v64
	v_add_f32_e64 v0, |v18|, v0
	v_ashrrev_i32_e32 v2, 4, v2
	v_add_f32_e64 v0, |v4|, v0
	v_lshlrev_b32_e32 v2, 3, v2
	v_add_f32_e64 v0, |v16|, v0
	v_add3_u32 v2, s3, v2, v33
	v_add_f32_e64 v0, |v6|, v0
	s_waitcnt vmcnt(2)
	ds_write_b64 v2, v[28:29] offset:57344
	v_ashrrev_i32_e32 v2, 4, v42
	v_add_f32_e64 v0, |v20|, v0
	v_lshlrev_b32_e32 v2, 3, v2
	v_add_f32_e64 v0, |v8|, v0
	v_add3_u32 v2, s3, v2, v33
	v_add_f32_e64 v0, |v22|, v0
	ds_write_b64 v2, v[14:15] offset:28672
	v_add_u32_e32 v2, 0x1e00, v64
	v_add_f32_e64 v0, |v10|, v0
	v_ashrrev_i32_e32 v2, 4, v2
	v_add_f32_e64 v0, |v24|, v0
	v_lshlrev_b32_e32 v2, 3, v2
	v_add_f32_e64 v0, |v12|, v0
	v_add3_u32 v2, s3, v2, v33
	v_add_f32_e64 v0, |v28|, v0
	s_waitcnt vmcnt(0)
	ds_write_b64 v2, v[26:27] offset:61440
	v_mbcnt_lo_u32_b32 v2, -1, 0
	v_mbcnt_hi_u32_b32 v2, -1, v2
	v_add_f32_e64 v0, |v14|, v0
	v_add_f32_e64 v0, |v26|, v0
	v_lshlrev_b32_e32 v4, 2, v2
	v_xor_b32_e32 v2, 0x80, v4
	ds_bpermute_b32 v2, v2, v0
	s_waitcnt lgkmcnt(0)
	v_add_f32_e32 v0, v0, v2
	v_xor_b32_e32 v2, 64, v4
	ds_bpermute_b32 v2, v2, v0
	s_waitcnt lgkmcnt(0)
	v_add_f32_e32 v0, v0, v2
	v_xor_b32_e32 v2, 32, v4
	ds_bpermute_b32 v2, v2, v0
	s_waitcnt lgkmcnt(0)
	v_add_f32_e32 v0, v0, v2
	v_xor_b32_e32 v2, 16, v4
	ds_bpermute_b32 v2, v2, v0
	s_waitcnt lgkmcnt(0)
	v_add_f32_e32 v0, v0, v2
	v_xor_b32_e32 v2, 8, v4
	ds_bpermute_b32 v2, v2, v0
	s_waitcnt lgkmcnt(0)
	v_add_f32_e32 v2, v0, v2
	v_xor_b32_e32 v0, 4, v4
	ds_bpermute_b32 v4, v0, v2
	global_load_ushort v0, v39, s[44:45]
	s_barrier
	s_waitcnt vmcnt(0)
	v_readfirstlane_b32 s8, v0
	v_and_b32_e32 v0, 63, v64
	v_cmp_eq_u32_e32 vcc, 0, v0
	v_add_u32_e32 v0, 0, v32
	v_add_u32_e32 v0, 0x22000, v0
	s_and_saveexec_b64 s[6:7], vcc
	v_add_f32_e32 v2, v2, v4
	ds_write_b32 v0, v2
	s_or_b64 exec, exec, s[6:7]
	s_and_b32 s8, 0xffff, s8
	s_lshr_b32 s10, s8, 6
	s_cmp_gt_u32 s8, 63
	s_cselect_b64 s[6:7], -1, 0
	s_cmp_lt_u32 s8, 64
	v_mov_b32_e32 v59, 0
	s_waitcnt lgkmcnt(0)
	s_barrier
	s_cbranch_scc1 .LBB0_1560
	s_add_i32 s8, s10, -1
	s_and_b32 s8, s8, 0xffff
	s_cmp_lt_u32 s8, 7
	s_cbranch_scc1 .LBB0_1556
	s_add_i32 s9, 0, 0x22000
	s_and_b32 s8, s10, 0x3f8
	s_mov_b32 s11, 0
	v_mov_b32_e32 v2, 0

.LBB0_1560:
	v_and_b32_e32 v1, 0x7fffffff, v1
	v_and_b32_e32 v2, 0x7fffffff, v31
	v_and_b32_e32 v3, 0x7fffffff, v3
	v_add_f32_e32 v1, v1, v2
	v_and_b32_e32 v4, 0x7fffffff, v19
	v_add_f32_e32 v1, v3, v1
	v_and_b32_e32 v5, 0x7fffffff, v5
	v_add_f32_e32 v1, v4, v1
	v_and_b32_e32 v6, 0x7fffffff, v17
	v_add_f32_e32 v1, v5, v1
	v_and_b32_e32 v7, 0x7fffffff, v7
	v_add_f32_e32 v1, v6, v1
	v_and_b32_e32 v8, 0x7fffffff, v21
	v_add_f32_e32 v1, v7, v1
	v_and_b32_e32 v9, 0x7fffffff, v9
	v_add_f32_e32 v1, v8, v1
	v_and_b32_e32 v10, 0x7fffffff, v23
	v_add_f32_e32 v1, v9, v1
	v_and_b32_e32 v11, 0x7fffffff, v11
	v_add_f32_e32 v1, v10, v1
	v_and_b32_e32 v12, 0x7fffffff, v25
	v_add_f32_e32 v1, v11, v1
	v_and_b32_e32 v13, 0x7fffffff, v13
	v_add_f32_e32 v1, v12, v1
	v_and_b32_e32 v14, 0x7fffffff, v29
	v_add_f32_e32 v1, v13, v1
	v_mbcnt_lo_u32_b32 v2, -1, 0
	v_mbcnt_hi_u32_b32 v2, -1, v2
	v_and_b32_e32 v15, 0x7fffffff, v15
	v_add_f32_e32 v1, v14, v1
	v_and_b32_e32 v16, 0x7fffffff, v27
	v_add_f32_e32 v1, v15, v1
	v_lshlrev_b32_e32 v2, 2, v2
	v_add_f32_e32 v1, v16, v1
	v_xor_b32_e32 v3, 0x80, v2
	ds_bpermute_b32 v3, v3, v1
	v_xor_b32_e32 v4, 32, v2
	s_ashr_i32 s41, s40, 31
	s_waitcnt lgkmcnt(0)
	s_barrier
	v_add_f32_e32 v1, v1, v3
	v_xor_b32_e32 v3, 64, v2
	ds_bpermute_b32 v3, v3, v1
	s_waitcnt lgkmcnt(0)
	v_add_f32_e32 v1, v1, v3
	ds_bpermute_b32 v172, v4, v1
	v_xor_b32_e32 v4, 16, v2
	s_waitcnt lgkmcnt(0)
	v_add_f32_e32 v1, v1, v172
	ds_bpermute_b32 v172, v4, v1
	v_xor_b32_e32 v4, 8, v2
	v_xor_b32_e32 v2, 4, v2
	s_waitcnt lgkmcnt(0)
	v_add_f32_e32 v1, v1, v172
	ds_bpermute_b32 v3, v4, v1
	s_waitcnt lgkmcnt(0)
	v_add_f32_e32 v1, v1, v3
	ds_bpermute_b32 v2, v2, v1
	s_and_saveexec_b64 s[8:9], vcc
	s_cbranch_execz .LBB0_1562
	s_waitcnt lgkmcnt(0)
	v_add_f32_e32 v1, v1, v2
	ds_write_b32 v0, v1

.LBB0_1571:
	v_readlane_b32 s4, v239, 35
	s_lshl_b64 s[60:61], s[40:41], 2
	v_readlane_b32 s6, v239, 37
	v_readlane_b32 s8, v239, 39
	v_readlane_b32 s7, v239, 38
	v_readlane_b32 s9, v239, 40
	s_add_u32 s8, s6, s60
	s_waitcnt lgkmcnt(0)
	s_barrier
	v_readlane_b32 s5, v239, 36
	v_readlane_b32 s10, v239, 41
	v_readlane_b32 s11, v239, 42
	v_readlane_b32 s12, v239, 43
	v_readlane_b32 s13, v239, 44
	v_readlane_b32 s14, v239, 45
	v_readlane_b32 s15, v239, 46
	v_readlane_b32 s16, v239, 47
	v_readlane_b32 s17, v239, 48
	v_readlane_b32 s18, v239, 49
	v_readlane_b32 s19, v239, 50
	s_addc_u32 s9, s7, s61
	global_load_dword v66, v39, s[8:9]
	global_load_dword v3, v43, s[8:9]
	v_readlane_b32 s4, v240, 22
	s_mul_i32 s23, s40, 0x8800
	v_readlane_b32 s8, v240, 26
	v_readlane_b32 s12, v240, 30
	s_mul_hi_i32 s41, s40, 0x8800
	v_readlane_b32 s9, v240, 27
	v_readlane_b32 s13, v240, 31
	s_add_u32 s8, s12, s23
	s_addc_u32 s9, s13, s41
	v_lshl_add_u64 v[4:5], v[64:65], 2, s[8:9]
	v_add_co_u32_e32 v0, vcc, s94, v4
	global_load_dwordx3 v[56:58], v[4:5], off offset:-4
	global_load_dwordx3 v[52:54], v[4:5], off offset:2044
	v_addc_co_u32_e32 v1, vcc, 0, v5, vcc
	v_add_co_u32_e32 v8, vcc, s1, v4
	v_mov_b32_e32 v114, v64
	s_nop 0
	v_addc_co_u32_e32 v9, vcc, 0, v5, vcc
	v_add_co_u32_e32 v10, vcc, s69, v4
	global_load_dwordx3 v[60:62], v[0:1], off offset:4092
	global_load_dwordx3 v[48:50], v[8:9], off offset:2044
	v_addc_co_u32_e32 v11, vcc, 0, v5, vcc
	global_load_dwordx3 v[40:42], v[8:9], off offset:4092
	global_load_dwordx3 v[36:38], v[10:11], off offset:2044
	v_add_co_u32_e32 v8, vcc, s24, v4
	v_mov_b32_e32 v100, 0
	s_nop 0
	v_addc_co_u32_e32 v9, vcc, 0, v5, vcc
	global_load_dwordx3 v[32:34], v[8:9], off offset:2044
	global_load_dwordx3 v[28:30], v[10:11], off offset:4092
	v_add_co_u32_e32 v10, vcc, s73, v4
	v_mov_b32_e32 v101, 0
	s_nop 0
	v_addc_co_u32_e32 v11, vcc, 0, v5, vcc
	global_load_dwordx3 v[24:26], v[8:9], off offset:4092
	global_load_dwordx3 v[20:22], v[10:11], off offset:2044
	v_add_co_u32_e32 v8, vcc, s46, v4
	v_mov_b32_e32 v74, 0
	s_nop 0
	v_addc_co_u32_e32 v9, vcc, 0, v5, vcc
	global_load_dwordx3 v[16:18], v[8:9], off offset:2044
	global_load_dwordx3 v[12:14], v[10:11], off offset:4092
	global_load_dwordx3 v[44:46], v[4:5], off offset:4092
	s_nop 0
	global_load_dwordx3 v[0:2], v[0:1], off offset:2044
	v_add_co_u32_e32 v4, vcc, s47, v4
	v_mov_b32_e32 v75, v100
	s_nop 0
	v_addc_co_u32_e32 v5, vcc, 0, v5, vcc
	global_load_dwordx3 v[8:10], v[8:9], off offset:4092
	s_nop 0
	global_load_dwordx3 v[4:6], v[4:5], off offset:2044
	v_mov_b32_e32 v82, v100
	v_add_u32_e32 v23, 0x1000, v114
	v_lshl_add_u32 v122, v114, 3, s3
	v_ashrrev_i32_e32 v23, 4, v23
	v_lshl_add_u32 v116, v23, 3, v122
	v_add_u32_e32 v23, 0x1200, v114
	v_ashrrev_i32_e32 v23, 4, v23
	v_lshl_add_u32 v113, v23, 3, v122
	v_add_u32_e32 v23, 0x1400, v114
	v_ashrrev_i32_e32 v23, 4, v23
	v_lshl_add_u32 v111, v23, 3, v122
	v_add_u32_e32 v23, 0x1600, v114
	v_ashrrev_i32_e32 v23, 4, v23
	v_add_u32_e32 v112, 0x200, v114
	v_lshl_add_u32 v108, v23, 3, v122
	v_add_u32_e32 v23, 0x1800, v114
	v_ashrrev_i32_e32 v11, 4, v112
	v_add_u32_e32 v110, 0x400, v114
	v_ashrrev_i32_e32 v23, 4, v23
	v_lshl_add_u32 v109, v11, 3, v122
	v_ashrrev_i32_e32 v11, 4, v110
	v_add_u32_e32 v107, 0x600, v114
	v_lshl_add_u32 v105, v23, 3, v122
	v_add_u32_e32 v23, 0x1a00, v114
	v_lshl_add_u32 v106, v11, 3, v122
	v_ashrrev_i32_e32 v11, 4, v107
	v_add_u32_e32 v104, 0x800, v114
	v_ashrrev_i32_e32 v23, 4, v23
	v_lshl_add_u32 v103, v11, 3, v122
	v_ashrrev_i32_e32 v11, 4, v104
	v_add_u32_e32 v67, 0xa00, v114
	v_lshl_add_u32 v102, v23, 3, v122
	v_add_u32_e32 v23, 0x1c00, v114
	v_lshl_add_u32 v65, v11, 3, v122
	v_ashrrev_i32_e32 v11, 4, v67
	v_add_u32_e32 v31, 0xc00, v114
	v_ashrrev_i32_e32 v23, 4, v23
	v_lshl_add_u32 v27, v11, 3, v122
	v_ashrrev_i32_e32 v11, 4, v31
	v_add_u32_e32 v19, 0xe00, v114
	v_lshl_add_u32 v63, v23, 3, v122
	v_add_u32_e32 v23, 0x1e00, v114
	v_ashrrev_i32_e32 v115, 4, v114
	v_lshl_add_u32 v15, v11, 3, v122
	v_ashrrev_i32_e32 v11, 4, v19
	v_ashrrev_i32_e32 v23, 4, v23
	v_cmp_gt_i32_e32 vcc, s70, v114
	v_lshl_add_u32 v117, v115, 3, v122
	v_lshl_add_u32 v11, v11, 3, v122
	v_lshl_add_u32 v23, v23, 3, v122
	v_mov_b32_e32 v83, v100
	v_mov_b32_e32 v90, v100
	v_mov_b32_e32 v91, v100
	v_mov_b32_e32 v96, v100
	v_mov_b32_e32 v97, v100
	v_mov_b32_e32 v72, v100
	v_mov_b32_e32 v73, v100
	v_mov_b32_e32 v80, v100
	v_mov_b32_e32 v81, v100
	v_mov_b32_e32 v88, v100
	v_mov_b32_e32 v89, v100
	v_mov_b32_e32 v94, v100
	v_mov_b32_e32 v95, v100
	v_mov_b32_e32 v70, v100
	v_mov_b32_e32 v71, v100
	v_mov_b32_e32 v78, v100
	v_mov_b32_e32 v79, v100
	v_mov_b32_e32 v86, v100
	v_mov_b32_e32 v87, v100
	v_mov_b32_e32 v92, v100
	v_mov_b32_e32 v93, v100
	v_mov_b32_e32 v68, v100
	v_mov_b32_e32 v69, v100
	v_mov_b32_e32 v76, v100
	v_mov_b32_e32 v77, v100
	v_mov_b32_e32 v84, v100
	v_mov_b32_e32 v85, v100
	v_mov_b32_e32 v98, v100
	v_mov_b32_e32 v99, v100
	v_readlane_b32 s5, v240, 23
	v_readlane_b32 s6, v240, 24
	v_readlane_b32 s7, v240, 25
	v_readlane_b32 s10, v240, 28
	v_readlane_b32 s11, v240, 29
	v_readlane_b32 s14, v240, 32
	v_readlane_b32 s15, v240, 33
	v_readlane_b32 s16, v240, 34
	v_readlane_b32 s17, v240, 35
	v_readlane_b32 s18, v240, 36
	v_readlane_b32 s19, v240, 37
	s_and_saveexec_b64 s[8:9], vcc
	s_cbranch_execz .LBB0_1573
	ds_read_b64 v[172:173], v117
	ds_read_b64 v[174:175], v109 offset:4096
	ds_read_b64 v[176:177], v106 offset:8192
	ds_read_b64 v[178:179], v103 offset:12288
	ds_read_b64 v[180:181], v65 offset:16384
	ds_read_b64 v[182:183], v27 offset:20480
	ds_read_b64 v[184:185], v15 offset:24576
	ds_read_b64 v[186:187], v11 offset:28672
	ds_read_b64 v[188:189], v116 offset:32768
	ds_read_b64 v[190:191], v113 offset:36864
	ds_read_b64 v[192:193], v111 offset:40960
	ds_read_b64 v[194:195], v108 offset:45056
	ds_read_b64 v[196:197], v105 offset:49152
	ds_read_b64 v[198:199], v102 offset:53248
	ds_read_b64 v[200:201], v63 offset:57344
	s_waitcnt lgkmcnt(14)
	ds_read_b64 v[202:203], v23 offset:61440
	s_waitcnt lgkmcnt(7)
	v_pk_add_f32 v[100:101], v[172:173], v[188:189]
	v_pk_add_f32 v[124:125], v[172:173], v[188:189] neg_lo:[0,1] neg_hi:[0,1]
	s_waitcnt lgkmcnt(3)
	v_pk_add_f32 v[68:69], v[180:181], v[196:197]
	v_pk_add_f32 v[76:77], v[180:181], v[196:197] neg_lo:[0,1] neg_hi:[0,1]
	v_pk_add_f32 v[84:85], v[100:101], v[68:69]
	v_pk_add_f32 v[92:93], v[100:101], v[68:69] neg_lo:[0,1] neg_hi:[0,1]
	v_pk_add_f32 v[68:69], v[174:175], v[190:191]
	v_pk_add_f32 v[126:127], v[174:175], v[190:191] neg_lo:[0,1] neg_hi:[0,1]
	s_waitcnt lgkmcnt(2)
	v_pk_add_f32 v[70:71], v[182:183], v[198:199]
	v_pk_add_f32 v[78:79], v[182:183], v[198:199] neg_lo:[0,1] neg_hi:[0,1]
	v_pk_add_f32 v[86:87], v[68:69], v[70:71]
	v_pk_add_f32 v[94:95], v[68:69], v[70:71] neg_lo:[0,1] neg_hi:[0,1]
	v_pk_add_f32 v[68:69], v[176:177], v[192:193]
	s_waitcnt lgkmcnt(1)
	v_pk_add_f32 v[70:71], v[184:185], v[200:201]
	v_pk_add_f32 v[130:131], v[176:177], v[192:193] neg_lo:[0,1] neg_hi:[0,1]
	v_pk_add_f32 v[72:73], v[184:185], v[200:201] neg_lo:[0,1] neg_hi:[0,1]
	v_pk_add_f32 v[80:81], v[68:69], v[70:71]
	v_pk_add_f32 v[88:89], v[68:69], v[70:71] neg_lo:[0,1] neg_hi:[0,1]
	v_pk_add_f32 v[68:69], v[178:179], v[194:195]
	s_waitcnt lgkmcnt(0)
	v_pk_add_f32 v[70:71], v[186:187], v[202:203]
	v_xor_b32_e32 v97, 0x80000000, v72
	v_mov_b32_e32 v96, v73
	v_pk_add_f32 v[134:135], v[178:179], v[194:195] neg_lo:[0,1] neg_hi:[0,1]
	v_pk_add_f32 v[72:73], v[186:187], v[202:203] neg_lo:[0,1] neg_hi:[0,1]
	v_pk_add_f32 v[74:75], v[68:69], v[70:71]
	v_xor_b32_e32 v129, 0x80000000, v78
	v_mov_b32_e32 v128, v79
	v_pk_add_f32 v[90:91], v[68:69], v[70:71] neg_lo:[0,1] neg_hi:[0,1]
	v_xor_b32_e32 v99, 0x80000000, v72
	v_mov_b32_e32 v98, v73
	v_pk_add_f32 v[68:69], v[84:85], v[80:81]
	v_pk_add_f32 v[70:71], v[86:87], v[74:75]
	v_pk_add_f32 v[72:73], v[86:87], v[74:75] neg_lo:[0,1] neg_hi:[0,1]
	v_pk_add_f32 v[78:79], v[126:127], v[128:129]
	v_pk_add_f32 v[80:81], v[84:85], v[80:81] neg_lo:[0,1] neg_hi:[0,1]
	v_pk_add_f32 v[74:75], v[68:69], v[70:71]
	v_pk_add_f32 v[70:71], v[68:69], v[70:71] neg_lo:[0,1] neg_hi:[0,1]
	v_xor_b32_e32 v69, 0x80000000, v72
	v_mov_b32_e32 v68, v73
	s_mov_b32 s29, s26
	v_pk_add_f32 v[132:133], v[130:131], v[96:97]
	v_pk_add_f32 v[82:83], v[134:135], v[98:99]
	v_pk_add_f32 v[72:73], v[80:81], v[68:69]
	v_pk_add_f32 v[68:69], v[80:81], v[68:69] neg_lo:[0,1] neg_hi:[0,1]
	v_pk_mul_f32 v[80:81], v[78:79], s[28:29] op_sel:[1,0]
	s_mov_b32 s10, s26
	s_mov_b32 s11, s28
	v_xor_b32_e32 v101, 0x80000000, v76
	v_mov_b32_e32 v100, v77
	v_pk_fma_f32 v[78:79], v[78:79], s[26:27], v[80:81] op_sel_hi:[0,1,1]
	v_mul_f32_e32 v80, 0x3f3504f3, v133
	s_mov_b32 s29, s34
	v_pk_mul_f32 v[84:85], v[82:83], s[10:11] op_sel:[1,0]
	v_pk_add_f32 v[76:77], v[124:125], v[100:101]
	v_pk_fma_f32 v[80:81], v[132:133], s[30:31], v[80:81] op_sel_hi:[0,1,0]
	v_pk_fma_f32 v[82:83], v[82:83], s[28:29], v[84:85] op_sel_hi:[0,1,1]
	v_pk_add_f32 v[84:85], v[76:77], v[80:81]
	v_pk_add_f32 v[76:77], v[76:77], v[80:81] neg_lo:[0,1] neg_hi:[0,1]
	v_pk_add_f32 v[80:81], v[78:79], v[82:83]
	v_pk_add_f32 v[86:87], v[78:79], v[82:83] neg_lo:[0,1] neg_hi:[0,1]
	s_mov_b32 s37, s20
	v_pk_add_f32 v[82:83], v[84:85], v[80:81]
	v_pk_add_f32 v[78:79], v[84:85], v[80:81] neg_lo:[0,1] neg_hi:[0,1]
	v_xor_b32_e32 v85, 0x80000000, v86
	v_mov_b32_e32 v84, v87
	v_pk_mul_f32 v[86:87], v[88:89], s[36:37] op_sel:[1,0]
	v_pk_add_f32 v[80:81], v[76:77], v[84:85]
	v_pk_add_f32 v[76:77], v[76:77], v[84:85] neg_lo:[0,1] neg_hi:[0,1]
	v_mul_f32_e32 v84, 0x3f3504f3, v95
	v_pk_fma_f32 v[86:87], v[88:89], s[20:21], v[86:87] op_sel_hi:[0,1,1]
	v_mul_f32_e32 v88, 0xbf3504f3, v90
	v_pk_fma_f32 v[84:85], v[94:95], s[30:31], v[84:85] op_sel_hi:[0,1,0]
	v_pk_fma_f32 v[88:89], v[90:91], s[30:31], v[88:89] op_sel:[1,0,0] op_sel_hi:[1,1,0]
	v_pk_add_f32 v[94:95], v[92:93], v[86:87]
	v_pk_add_f32 v[92:93], v[92:93], v[86:87] neg_lo:[0,1] neg_hi:[0,1]
	v_pk_add_f32 v[86:87], v[84:85], v[88:89]
	v_pk_add_f32 v[84:85], v[84:85], v[88:89] neg_lo:[0,1] neg_hi:[0,1]
	v_pk_add_f32 v[90:91], v[94:95], v[86:87]
	v_pk_add_f32 v[86:87], v[94:95], v[86:87] neg_lo:[0,1] neg_hi:[0,1]
	v_xor_b32_e32 v95, 0x80000000, v84
	v_mov_b32_e32 v94, v85
	v_pk_add_f32 v[88:89], v[92:93], v[94:95]
	v_pk_add_f32 v[84:85], v[92:93], v[94:95] neg_lo:[0,1] neg_hi:[0,1]
	v_pk_add_f32 v[92:93], v[134:135], v[98:99] neg_lo:[0,1] neg_hi:[0,1]
	s_mov_b32 s12, s27
	s_mov_b32 s13, s34
	s_mov_b32 s35, s28
	v_pk_mul_f32 v[94:95], v[92:93], s[12:13] op_sel:[1,0]
	v_pk_add_f32 v[98:99], v[126:127], v[128:129] neg_lo:[0,1] neg_hi:[0,1]
	v_pk_fma_f32 v[92:93], v[92:93], s[34:35], v[94:95] op_sel_hi:[0,1,1]
	v_pk_add_f32 v[94:95], v[124:125], v[100:101] neg_lo:[0,1] neg_hi:[0,1]
	v_pk_mul_f32 v[100:101], v[98:99], s[10:11] op_sel:[1,0]
	v_pk_add_f32 v[96:97], v[130:131], v[96:97] neg_lo:[0,1] neg_hi:[0,1]
	v_pk_fma_f32 v[98:99], v[98:99], s[28:29], v[100:101] op_sel_hi:[0,1,1]
	v_mul_f32_e32 v100, 0xbf3504f3, v96
	v_pk_fma_f32 v[96:97], v[96:97], s[30:31], v[100:101] op_sel:[1,0,0] op_sel_hi:[1,1,0]
	s_nop 0
	v_pk_add_f32 v[100:101], v[94:95], v[96:97]
	v_pk_add_f32 v[124:125], v[94:95], v[96:97] neg_lo:[0,1] neg_hi:[0,1]
	v_pk_add_f32 v[94:95], v[98:99], v[92:93]
	v_pk_add_f32 v[98:99], v[98:99], v[92:93] neg_lo:[0,1] neg_hi:[0,1]
	v_pk_add_f32 v[96:97], v[100:101], v[94:95]
	v_pk_add_f32 v[92:93], v[100:101], v[94:95] neg_lo:[0,1] neg_hi:[0,1]
	v_xor_b32_e32 v101, 0x80000000, v98
	v_mov_b32_e32 v100, v99
	v_pk_add_f32 v[94:95], v[124:125], v[100:101]
	v_pk_add_f32 v[100:101], v[124:125], v[100:101] neg_lo:[0,1] neg_hi:[0,1]
	s_nop 0
	v_mov_b32_e32 v98, v100
	v_mov_b32_e32 v99, v101

.LBB0_1575:
	s_or_b64 exec, exec, s[8:9]
	s_waitcnt lgkmcnt(0)
	s_barrier
	s_and_saveexec_b64 s[8:9], vcc
	s_cbranch_execz .LBB0_1577
	ds_read_b64 v[172:173], v23 offset:61440
	ds_read_b64 v[174:175], v63 offset:57344
	ds_read_b64 v[176:177], v102 offset:53248
	ds_read_b64 v[178:179], v105 offset:49152
	ds_read_b64 v[180:181], v108 offset:45056
	ds_read_b64 v[182:183], v111 offset:40960
	ds_read_b64 v[184:185], v117
	ds_read_b64 v[186:187], v109 offset:4096
	ds_read_b64 v[188:189], v106 offset:8192
	ds_read_b64 v[190:191], v103 offset:12288
	ds_read_b64 v[192:193], v65 offset:16384
	ds_read_b64 v[194:195], v27 offset:20480
	ds_read_b64 v[196:197], v15 offset:24576
	ds_read_b64 v[198:199], v11 offset:28672
	ds_read_b64 v[200:201], v116 offset:32768
	v_and_b32_e32 v68, 15, v114
	v_cvt_f32_ubyte0_e32 v68, v68
	v_mul_f32_e32 v68, 0x3b800000, v68
	v_cos_f32_e32 v84, v68
	v_sin_f32_e32 v92, v68
	s_mov_b32 s29, s26
	v_mov_b32_e32 v93, v84
	v_xor_b32_e32 v85, 0x80000000, v92
	v_pk_mul_f32 v[68:69], v[92:93], v[92:93] op_sel_hi:[1,0] neg_lo:[0,1] neg_hi:[0,1]
	s_mov_b32 s10, s26
	v_pk_fma_f32 v[90:91], v[84:85], v[84:85], v[68:69] op_sel_hi:[1,0,1]
	s_mov_b32 s11, s28
	v_pk_mul_f32 v[68:69], v[92:93], v[90:91] op_sel:[0,1]
	s_mov_b32 s37, s20
	v_pk_fma_f32 v[86:87], v[84:85], v[90:91], v[68:69] op_sel_hi:[1,0,1]
	s_mov_b32 s12, s27
	v_pk_mul_f32 v[68:69], v[92:93], v[86:87] op_sel:[0,1]
	s_mov_b32 s13, s34
	v_pk_fma_f32 v[82:83], v[84:85], v[86:87], v[68:69] op_sel_hi:[1,0,1]
	s_mov_b32 s35, s28
	v_pk_mul_f32 v[68:69], v[92:93], v[82:83] op_sel:[0,1]
	s_nop 0
	v_pk_fma_f32 v[80:81], v[84:85], v[82:83], v[68:69] op_sel_hi:[1,0,1]
	s_nop 0
	v_pk_mul_f32 v[68:69], v[92:93], v[80:81] op_sel:[0,1]
	s_nop 0
	v_pk_fma_f32 v[78:79], v[84:85], v[80:81], v[68:69] op_sel_hi:[1,0,1]
	s_nop 0
	v_pk_mul_f32 v[68:69], v[92:93], v[78:79] op_sel:[0,1]
	s_nop 0
	v_pk_fma_f32 v[76:77], v[84:85], v[78:79], v[68:69] op_sel_hi:[1,0,1]
	s_nop 0
	v_pk_mul_f32 v[68:69], v[92:93], v[76:77] op_sel:[0,1]
	s_nop 0
	v_pk_fma_f32 v[70:71], v[84:85], v[76:77], v[68:69] op_sel_hi:[1,0,1]
	s_nop 0
	v_pk_mul_f32 v[68:69], v[92:93], v[70:71] op_sel:[0,1]
	s_nop 0
	v_pk_fma_f32 v[68:69], v[84:85], v[70:71], v[68:69] op_sel_hi:[1,0,1]
	s_nop 0
	v_pk_mul_f32 v[72:73], v[92:93], v[68:69] op_sel:[0,1]
	s_nop 0
	v_pk_fma_f32 v[96:97], v[84:85], v[68:69], v[72:73] op_sel_hi:[1,0,1]
	s_nop 0
	v_pk_mul_f32 v[72:73], v[92:93], v[96:97] op_sel:[0,1]
	s_nop 0
	v_pk_fma_f32 v[94:95], v[84:85], v[96:97], v[72:73] op_sel_hi:[1,0,1]
	s_nop 0
	v_pk_mul_f32 v[72:73], v[92:93], v[94:95] op_sel:[0,1]
	s_nop 0
	v_pk_fma_f32 v[98:99], v[84:85], v[94:95], v[72:73] op_sel_hi:[1,0,1]
	s_nop 0
	v_pk_mul_f32 v[72:73], v[92:93], v[98:99] op_sel:[0,1]
	s_nop 0
	v_pk_fma_f32 v[88:89], v[84:85], v[98:99], v[72:73] op_sel_hi:[1,0,1]
	s_nop 0
	v_pk_mul_f32 v[72:73], v[92:93], v[88:89] op_sel:[0,1]
	s_nop 0
	v_pk_fma_f32 v[74:75], v[84:85], v[88:89], v[72:73] op_sel_hi:[1,0,1]
	s_nop 0
	v_pk_mul_f32 v[72:73], v[92:93], v[74:75] op_sel:[0,1]
	s_nop 0
	v_pk_fma_f32 v[72:73], v[84:85], v[74:75], v[72:73] op_sel_hi:[1,0,1]
	s_nop 0
	v_xor_b32_e32 v122, 0x80000000, v73
	v_mov_b32_e32 v123, v72
	s_waitcnt lgkmcnt(14)
	v_pk_mul_f32 v[122:123], v[122:123], v[172:173] op_sel:[0,1]
	s_nop 0
	v_pk_fma_f32 v[72:73], v[72:73], v[172:173], v[122:123] op_sel_hi:[1,0,1]
	ds_read_b64 v[172:173], v113 offset:36864
	v_xor_b32_e32 v122, 0x80000000, v75
	v_mov_b32_e32 v123, v74
	s_waitcnt lgkmcnt(14)
	v_pk_mul_f32 v[122:123], v[122:123], v[174:175] op_sel:[0,1]
	s_nop 0
	v_pk_fma_f32 v[74:75], v[74:75], v[174:175], v[122:123] op_sel_hi:[1,0,1]
	v_xor_b32_e32 v122, 0x80000000, v89
	v_mov_b32_e32 v123, v88
	s_waitcnt lgkmcnt(13)
	v_pk_mul_f32 v[122:123], v[122:123], v[176:177] op_sel:[0,1]
	s_nop 0
	v_pk_fma_f32 v[88:89], v[88:89], v[176:177], v[122:123] op_sel_hi:[1,0,1]
	v_xor_b32_e32 v122, 0x80000000, v99
	v_mov_b32_e32 v123, v98
	s_waitcnt lgkmcnt(12)
	v_pk_mul_f32 v[122:123], v[122:123], v[178:179] op_sel:[0,1]
	s_nop 0
	v_pk_fma_f32 v[98:99], v[98:99], v[178:179], v[122:123] op_sel_hi:[1,0,1]
	v_xor_b32_e32 v122, 0x80000000, v95
	v_mov_b32_e32 v123, v94
	s_waitcnt lgkmcnt(11)
	v_pk_mul_f32 v[122:123], v[122:123], v[180:181] op_sel:[0,1]
	s_nop 0
	v_pk_fma_f32 v[94:95], v[94:95], v[180:181], v[122:123] op_sel_hi:[1,0,1]
	v_xor_b32_e32 v122, 0x80000000, v97
	v_mov_b32_e32 v123, v96
	s_waitcnt lgkmcnt(10)
	v_pk_mul_f32 v[122:123], v[122:123], v[182:183] op_sel:[0,1]
	s_nop 0
	v_pk_fma_f32 v[96:97], v[96:97], v[182:183], v[122:123] op_sel_hi:[1,0,1]
	s_waitcnt lgkmcnt(8)
	v_pk_mul_f32 v[92:93], v[92:93], v[186:187] op_sel:[0,1]
	s_nop 0
	v_pk_fma_f32 v[92:93], v[84:85], v[186:187], v[92:93] op_sel_hi:[1,0,1]
	v_xor_b32_e32 v122, 0x80000000, v91
	v_mov_b32_e32 v123, v90
	s_waitcnt lgkmcnt(7)
	v_pk_mul_f32 v[122:123], v[122:123], v[188:189] op_sel:[0,1]
	s_nop 0
	v_pk_fma_f32 v[90:91], v[90:91], v[188:189], v[122:123] op_sel_hi:[1,0,1]
	v_xor_b32_e32 v122, 0x80000000, v87
	v_mov_b32_e32 v123, v86
	s_waitcnt lgkmcnt(6)
	v_pk_mul_f32 v[122:123], v[122:123], v[190:191] op_sel:[0,1]
	s_nop 0
	v_pk_fma_f32 v[84:85], v[86:87], v[190:191], v[122:123] op_sel_hi:[1,0,1]
	v_xor_b32_e32 v122, 0x80000000, v83
	v_mov_b32_e32 v123, v82
	s_waitcnt lgkmcnt(5)
	v_pk_mul_f32 v[122:123], v[122:123], v[192:193] op_sel:[0,1]
	s_nop 0
	v_pk_fma_f32 v[82:83], v[82:83], v[192:193], v[122:123] op_sel_hi:[1,0,1]
	v_xor_b32_e32 v122, 0x80000000, v81
	v_mov_b32_e32 v123, v80
	s_waitcnt lgkmcnt(4)
	v_pk_mul_f32 v[122:123], v[122:123], v[194:195] op_sel:[0,1]
	s_nop 0
	v_pk_fma_f32 v[80:81], v[80:81], v[194:195], v[122:123] op_sel_hi:[1,0,1]
	v_xor_b32_e32 v122, 0x80000000, v79
	v_mov_b32_e32 v123, v78
	s_waitcnt lgkmcnt(3)
	v_pk_mul_f32 v[122:123], v[122:123], v[196:197] op_sel:[0,1]
	s_nop 0
	v_pk_fma_f32 v[78:79], v[78:79], v[196:197], v[122:123] op_sel_hi:[1,0,1]
	v_xor_b32_e32 v122, 0x80000000, v77
	v_mov_b32_e32 v123, v76
	s_waitcnt lgkmcnt(2)
	v_pk_mul_f32 v[122:123], v[122:123], v[198:199] op_sel:[0,1]
	s_nop 0
	v_pk_fma_f32 v[76:77], v[76:77], v[198:199], v[122:123] op_sel_hi:[1,0,1]
	v_xor_b32_e32 v122, 0x80000000, v71
	v_mov_b32_e32 v123, v70
	s_waitcnt lgkmcnt(1)
	v_pk_mul_f32 v[122:123], v[122:123], v[200:201] op_sel:[0,1]
	s_nop 0
	v_pk_fma_f32 v[70:71], v[70:71], v[200:201], v[122:123] op_sel_hi:[1,0,1]
	v_xor_b32_e32 v122, 0x80000000, v69
	v_mov_b32_e32 v123, v68
	s_waitcnt lgkmcnt(0)
	v_pk_mul_f32 v[122:123], v[122:123], v[172:173] op_sel:[0,1]
	s_nop 0
	v_pk_fma_f32 v[68:69], v[68:69], v[172:173], v[122:123] op_sel_hi:[1,0,1]
	v_pk_add_f32 v[86:87], v[184:185], v[70:71]
	v_pk_add_f32 v[100:101], v[184:185], v[70:71] neg_lo:[0,1] neg_hi:[0,1]
	v_pk_add_f32 v[70:71], v[98:99], v[82:83]
	v_pk_add_f32 v[82:83], v[82:83], v[98:99] neg_lo:[0,1] neg_hi:[0,1]
	v_pk_add_f32 v[98:99], v[70:71], v[86:87]
	v_pk_add_f32 v[86:87], v[86:87], v[70:71] neg_lo:[0,1] neg_hi:[0,1]
	v_pk_add_f32 v[70:71], v[92:93], v[68:69]
	v_pk_add_f32 v[92:93], v[92:93], v[68:69] neg_lo:[0,1] neg_hi:[0,1]
	v_pk_add_f32 v[68:69], v[88:89], v[80:81]
	v_pk_add_f32 v[80:81], v[80:81], v[88:89] neg_lo:[0,1] neg_hi:[0,1]
	v_pk_add_f32 v[88:89], v[68:69], v[70:71]
	v_pk_add_f32 v[124:125], v[70:71], v[68:69] neg_lo:[0,1] neg_hi:[0,1]
	v_pk_add_f32 v[68:69], v[96:97], v[90:91]
	v_pk_add_f32 v[70:71], v[74:75], v[78:79]
	v_pk_add_f32 v[96:97], v[90:91], v[96:97] neg_lo:[0,1] neg_hi:[0,1]
	v_pk_add_f32 v[74:75], v[78:79], v[74:75] neg_lo:[0,1] neg_hi:[0,1]
	v_pk_add_f32 v[78:79], v[68:69], v[70:71]
	v_pk_add_f32 v[90:91], v[68:69], v[70:71] neg_lo:[0,1] neg_hi:[0,1]
	v_pk_add_f32 v[68:69], v[94:95], v[84:85]
	v_pk_add_f32 v[70:71], v[72:73], v[76:77]
	v_xor_b32_e32 v129, 0x80000000, v74
	v_mov_b32_e32 v128, v75
	v_pk_add_f32 v[72:73], v[76:77], v[72:73] neg_lo:[0,1] neg_hi:[0,1]
	v_pk_add_f32 v[74:75], v[68:69], v[70:71]
	v_xor_b32_e32 v127, 0x80000000, v80
	v_mov_b32_e32 v126, v81
	v_pk_add_f32 v[94:95], v[84:85], v[94:95] neg_lo:[0,1] neg_hi:[0,1]
	v_pk_add_f32 v[84:85], v[68:69], v[70:71] neg_lo:[0,1] neg_hi:[0,1]
	v_xor_b32_e32 v133, 0x80000000, v72
	v_mov_b32_e32 v132, v73
	v_pk_add_f32 v[68:69], v[78:79], v[98:99]
	v_pk_add_f32 v[70:71], v[74:75], v[88:89]
	v_pk_add_f32 v[72:73], v[88:89], v[74:75] neg_lo:[0,1] neg_hi:[0,1]
	v_pk_add_f32 v[80:81], v[126:127], v[92:93]
	v_pk_add_f32 v[78:79], v[98:99], v[78:79] neg_lo:[0,1] neg_hi:[0,1]
	v_pk_add_f32 v[74:75], v[68:69], v[70:71]
	v_pk_add_f32 v[70:71], v[68:69], v[70:71] neg_lo:[0,1] neg_hi:[0,1]
	v_xor_b32_e32 v69, 0x80000000, v72
	v_mov_b32_e32 v68, v73
	v_pk_add_f32 v[130:131], v[96:97], v[128:129]
	v_pk_add_f32 v[76:77], v[94:95], v[132:133]
	v_pk_add_f32 v[72:73], v[78:79], v[68:69]
	v_pk_add_f32 v[68:69], v[78:79], v[68:69] neg_lo:[0,1] neg_hi:[0,1]
	v_pk_mul_f32 v[78:79], v[80:81], s[28:29] op_sel:[1,0]
	v_xor_b32_e32 v123, 0x80000000, v82
	v_mov_b32_e32 v122, v83
	v_pk_fma_f32 v[78:79], v[80:81], s[26:27], v[78:79] op_sel_hi:[0,1,1]
	v_mul_f32_e32 v80, 0x3f3504f3, v131
	s_mov_b32 s29, s34
	v_pk_mul_f32 v[88:89], v[76:77], s[10:11] op_sel:[1,0]
	v_pk_add_f32 v[82:83], v[122:123], v[100:101]
	v_pk_fma_f32 v[80:81], v[130:131], s[30:31], v[80:81] op_sel_hi:[0,1,0]
	v_pk_fma_f32 v[76:77], v[76:77], s[28:29], v[88:89] op_sel_hi:[0,1,1]
	v_pk_add_f32 v[88:89], v[82:83], v[80:81]
	v_pk_add_f32 v[98:99], v[82:83], v[80:81] neg_lo:[0,1] neg_hi:[0,1]
	v_pk_add_f32 v[80:81], v[78:79], v[76:77]
	v_pk_add_f32 v[76:77], v[78:79], v[76:77] neg_lo:[0,1] neg_hi:[0,1]
	v_pk_add_f32 v[82:83], v[88:89], v[80:81]
	v_pk_add_f32 v[78:79], v[88:89], v[80:81] neg_lo:[0,1] neg_hi:[0,1]
	v_xor_b32_e32 v89, 0x80000000, v76
	v_mov_b32_e32 v88, v77
	v_pk_add_f32 v[80:81], v[98:99], v[88:89]
	v_pk_add_f32 v[76:77], v[98:99], v[88:89] neg_lo:[0,1] neg_hi:[0,1]
	v_pk_mul_f32 v[98:99], v[90:91], s[36:37] op_sel:[1,0]
	v_mul_f32_e32 v88, 0x3f3504f3, v125
	v_pk_fma_f32 v[90:91], v[90:91], s[20:21], v[98:99] op_sel_hi:[0,1,1]
	v_mul_f32_e32 v98, 0xbf3504f3, v84
	v_pk_fma_f32 v[88:89], v[124:125], s[30:31], v[88:89] op_sel_hi:[0,1,0]
	v_pk_fma_f32 v[84:85], v[84:85], s[30:31], v[98:99] op_sel:[1,0,0] op_sel_hi:[1,1,0]
	v_pk_add_f32 v[98:99], v[86:87], v[90:91]
	v_pk_add_f32 v[124:125], v[86:87], v[90:91] neg_lo:[0,1] neg_hi:[0,1]
	v_pk_add_f32 v[86:87], v[84:85], v[88:89]
	v_pk_add_f32 v[84:85], v[88:89], v[84:85] neg_lo:[0,1] neg_hi:[0,1]
	v_pk_add_f32 v[90:91], v[98:99], v[86:87]
	v_pk_add_f32 v[86:87], v[98:99], v[86:87] neg_lo:[0,1] neg_hi:[0,1]
	v_xor_b32_e32 v99, 0x80000000, v84
	v_mov_b32_e32 v98, v85
	v_pk_add_f32 v[94:95], v[94:95], v[132:133] neg_lo:[0,1] neg_hi:[0,1]
	v_pk_add_f32 v[88:89], v[124:125], v[98:99]
	v_pk_add_f32 v[84:85], v[124:125], v[98:99] neg_lo:[0,1] neg_hi:[0,1]
	v_pk_mul_f32 v[98:99], v[94:95], s[12:13] op_sel:[1,0]
	v_pk_add_f32 v[92:93], v[92:93], v[126:127] neg_lo:[0,1] neg_hi:[0,1]
	v_pk_fma_f32 v[94:95], v[94:95], s[34:35], v[98:99] op_sel_hi:[0,1,1]
	v_pk_add_f32 v[98:99], v[100:101], v[122:123] neg_lo:[0,1] neg_hi:[0,1]
	v_pk_mul_f32 v[100:101], v[92:93], s[10:11] op_sel:[1,0]
	v_pk_add_f32 v[96:97], v[96:97], v[128:129] neg_lo:[0,1] neg_hi:[0,1]
	v_pk_fma_f32 v[92:93], v[92:93], s[28:29], v[100:101] op_sel_hi:[0,1,1]
	v_mul_f32_e32 v100, 0xbf3504f3, v96
	v_pk_fma_f32 v[96:97], v[96:97], s[30:31], v[100:101] op_sel:[1,0,0] op_sel_hi:[1,1,0]
	v_pk_add_f32 v[122:123], v[92:93], v[94:95]
	v_pk_add_f32 v[100:101], v[98:99], v[96:97]
	v_pk_add_f32 v[94:95], v[92:93], v[94:95] neg_lo:[0,1] neg_hi:[0,1]
	v_pk_add_f32 v[98:99], v[98:99], v[96:97] neg_lo:[0,1] neg_hi:[0,1]
	v_pk_add_f32 v[96:97], v[100:101], v[122:123]
	v_pk_add_f32 v[92:93], v[100:101], v[122:123] neg_lo:[0,1] neg_hi:[0,1]
	v_xor_b32_e32 v101, 0x80000000, v94
	v_mov_b32_e32 v100, v95
	v_pk_add_f32 v[94:95], v[98:99], v[100:101]
	v_pk_add_f32 v[98:99], v[98:99], v[100:101] neg_lo:[0,1] neg_hi:[0,1]

.LBB0_1579:
	s_or_b64 exec, exec, s[8:9]
	s_waitcnt lgkmcnt(0)
	s_barrier
	s_and_saveexec_b64 s[8:9], vcc
	s_cbranch_execz .LBB0_1581
	ds_read_b64 v[172:173], v23 offset:61440
	ds_read_b64 v[174:175], v63 offset:57344
	ds_read_b64 v[176:177], v102 offset:53248
	ds_read_b64 v[178:179], v105 offset:49152
	ds_read_b64 v[180:181], v108 offset:45056
	ds_read_b64 v[182:183], v111 offset:40960
	ds_read_b64 v[184:185], v117
	ds_read_b64 v[186:187], v109 offset:4096
	ds_read_b64 v[188:189], v106 offset:8192
	ds_read_b64 v[190:191], v103 offset:12288
	ds_read_b64 v[192:193], v65 offset:16384
	ds_read_b64 v[194:195], v27 offset:20480
	ds_read_b64 v[196:197], v15 offset:24576
	ds_read_b64 v[198:199], v11 offset:28672
	ds_read_b64 v[200:201], v116 offset:32768
	v_cvt_f32_ubyte0_e32 v68, v114
	v_mul_f32_e32 v68, 0x39800000, v68
	v_cos_f32_e32 v84, v68
	v_sin_f32_e32 v92, v68
	s_mov_b32 s29, s26
	v_mov_b32_e32 v93, v84
	v_xor_b32_e32 v85, 0x80000000, v92
	v_pk_mul_f32 v[68:69], v[92:93], v[92:93] op_sel_hi:[1,0] neg_lo:[0,1] neg_hi:[0,1]
	s_mov_b32 s10, s26
	v_pk_fma_f32 v[90:91], v[84:85], v[84:85], v[68:69] op_sel_hi:[1,0,1]
	s_mov_b32 s11, s28
	v_pk_mul_f32 v[68:69], v[92:93], v[90:91] op_sel:[0,1]
	s_mov_b32 s37, s20
	v_pk_fma_f32 v[86:87], v[84:85], v[90:91], v[68:69] op_sel_hi:[1,0,1]
	s_mov_b32 s12, s27
	v_pk_mul_f32 v[68:69], v[92:93], v[86:87] op_sel:[0,1]
	s_mov_b32 s13, s34
	v_pk_fma_f32 v[82:83], v[84:85], v[86:87], v[68:69] op_sel_hi:[1,0,1]
	s_mov_b32 s35, s28
	v_pk_mul_f32 v[68:69], v[92:93], v[82:83] op_sel:[0,1]
	s_nop 0
	v_pk_fma_f32 v[80:81], v[84:85], v[82:83], v[68:69] op_sel_hi:[1,0,1]
	s_nop 0
	v_pk_mul_f32 v[68:69], v[92:93], v[80:81] op_sel:[0,1]
	s_nop 0
	v_pk_fma_f32 v[78:79], v[84:85], v[80:81], v[68:69] op_sel_hi:[1,0,1]
	s_nop 0
	v_pk_mul_f32 v[68:69], v[92:93], v[78:79] op_sel:[0,1]
	s_nop 0
	v_pk_fma_f32 v[76:77], v[84:85], v[78:79], v[68:69] op_sel_hi:[1,0,1]
	s_nop 0
	v_pk_mul_f32 v[68:69], v[92:93], v[76:77] op_sel:[0,1]
	s_nop 0
	v_pk_fma_f32 v[70:71], v[84:85], v[76:77], v[68:69] op_sel_hi:[1,0,1]
	s_nop 0
	v_pk_mul_f32 v[68:69], v[92:93], v[70:71] op_sel:[0,1]
	s_nop 0
	v_pk_fma_f32 v[68:69], v[84:85], v[70:71], v[68:69] op_sel_hi:[1,0,1]
	s_nop 0
	v_pk_mul_f32 v[72:73], v[92:93], v[68:69] op_sel:[0,1]
	s_nop 0
	v_pk_fma_f32 v[96:97], v[84:85], v[68:69], v[72:73] op_sel_hi:[1,0,1]
	s_nop 0
	v_pk_mul_f32 v[72:73], v[92:93], v[96:97] op_sel:[0,1]
	s_nop 0
	v_pk_fma_f32 v[94:95], v[84:85], v[96:97], v[72:73] op_sel_hi:[1,0,1]
	s_nop 0
	v_pk_mul_f32 v[72:73], v[92:93], v[94:95] op_sel:[0,1]
	s_nop 0
	v_pk_fma_f32 v[98:99], v[84:85], v[94:95], v[72:73] op_sel_hi:[1,0,1]
	s_nop 0
	v_pk_mul_f32 v[72:73], v[92:93], v[98:99] op_sel:[0,1]
	s_nop 0
	v_pk_fma_f32 v[88:89], v[84:85], v[98:99], v[72:73] op_sel_hi:[1,0,1]
	s_nop 0
	v_pk_mul_f32 v[72:73], v[92:93], v[88:89] op_sel:[0,1]
	s_nop 0
	v_pk_fma_f32 v[74:75], v[84:85], v[88:89], v[72:73] op_sel_hi:[1,0,1]
	s_nop 0
	v_pk_mul_f32 v[72:73], v[92:93], v[74:75] op_sel:[0,1]
	s_nop 0
	v_pk_fma_f32 v[72:73], v[84:85], v[74:75], v[72:73] op_sel_hi:[1,0,1]
	s_nop 0
	v_xor_b32_e32 v124, 0x80000000, v73
	v_mov_b32_e32 v125, v72
	s_waitcnt lgkmcnt(14)
	v_pk_mul_f32 v[124:125], v[124:125], v[172:173] op_sel:[0,1]
	s_nop 0
	v_pk_fma_f32 v[72:73], v[72:73], v[172:173], v[124:125] op_sel_hi:[1,0,1]
	ds_read_b64 v[172:173], v113 offset:36864
	v_xor_b32_e32 v124, 0x80000000, v75
	v_mov_b32_e32 v125, v74
	s_waitcnt lgkmcnt(14)
	v_pk_mul_f32 v[124:125], v[124:125], v[174:175] op_sel:[0,1]
	s_nop 0
	v_pk_fma_f32 v[74:75], v[74:75], v[174:175], v[124:125] op_sel_hi:[1,0,1]
	v_xor_b32_e32 v124, 0x80000000, v89
	v_mov_b32_e32 v125, v88
	s_waitcnt lgkmcnt(13)
	v_pk_mul_f32 v[124:125], v[124:125], v[176:177] op_sel:[0,1]
	s_nop 0
	v_pk_fma_f32 v[88:89], v[88:89], v[176:177], v[124:125] op_sel_hi:[1,0,1]
	v_xor_b32_e32 v124, 0x80000000, v99
	v_mov_b32_e32 v125, v98
	s_waitcnt lgkmcnt(12)
	v_pk_mul_f32 v[124:125], v[124:125], v[178:179] op_sel:[0,1]
	s_nop 0
	v_pk_fma_f32 v[98:99], v[98:99], v[178:179], v[124:125] op_sel_hi:[1,0,1]
	v_xor_b32_e32 v124, 0x80000000, v95
	v_mov_b32_e32 v125, v94
	s_waitcnt lgkmcnt(11)
	v_pk_mul_f32 v[124:125], v[124:125], v[180:181] op_sel:[0,1]
	s_nop 0
	v_pk_fma_f32 v[94:95], v[94:95], v[180:181], v[124:125] op_sel_hi:[1,0,1]
	v_xor_b32_e32 v124, 0x80000000, v97
	v_mov_b32_e32 v125, v96
	s_waitcnt lgkmcnt(10)
	v_pk_mul_f32 v[124:125], v[124:125], v[182:183] op_sel:[0,1]
	s_nop 0
	v_pk_fma_f32 v[96:97], v[96:97], v[182:183], v[124:125] op_sel_hi:[1,0,1]
	s_waitcnt lgkmcnt(8)
	v_pk_mul_f32 v[92:93], v[92:93], v[186:187] op_sel:[0,1]
	s_nop 0
	v_pk_fma_f32 v[92:93], v[84:85], v[186:187], v[92:93] op_sel_hi:[1,0,1]
	v_xor_b32_e32 v124, 0x80000000, v91
	v_mov_b32_e32 v125, v90
	s_waitcnt lgkmcnt(7)
	v_pk_mul_f32 v[124:125], v[124:125], v[188:189] op_sel:[0,1]
	s_nop 0
	v_pk_fma_f32 v[90:91], v[90:91], v[188:189], v[124:125] op_sel_hi:[1,0,1]
	v_xor_b32_e32 v124, 0x80000000, v87
	v_mov_b32_e32 v125, v86
	s_waitcnt lgkmcnt(6)
	v_pk_mul_f32 v[124:125], v[124:125], v[190:191] op_sel:[0,1]
	s_nop 0
	v_pk_fma_f32 v[84:85], v[86:87], v[190:191], v[124:125] op_sel_hi:[1,0,1]
	v_xor_b32_e32 v124, 0x80000000, v83
	v_mov_b32_e32 v125, v82
	s_waitcnt lgkmcnt(5)
	v_pk_mul_f32 v[124:125], v[124:125], v[192:193] op_sel:[0,1]
	s_nop 0
	v_pk_fma_f32 v[82:83], v[82:83], v[192:193], v[124:125] op_sel_hi:[1,0,1]
	v_xor_b32_e32 v124, 0x80000000, v81
	v_mov_b32_e32 v125, v80
	s_waitcnt lgkmcnt(4)
	v_pk_mul_f32 v[124:125], v[124:125], v[194:195] op_sel:[0,1]
	s_nop 0
	v_pk_fma_f32 v[80:81], v[80:81], v[194:195], v[124:125] op_sel_hi:[1,0,1]
	v_xor_b32_e32 v124, 0x80000000, v79
	v_mov_b32_e32 v125, v78
	s_waitcnt lgkmcnt(3)
	v_pk_mul_f32 v[124:125], v[124:125], v[196:197] op_sel:[0,1]
	s_nop 0
	v_pk_fma_f32 v[78:79], v[78:79], v[196:197], v[124:125] op_sel_hi:[1,0,1]
	v_xor_b32_e32 v124, 0x80000000, v77
	v_mov_b32_e32 v125, v76
	s_waitcnt lgkmcnt(2)
	v_pk_mul_f32 v[124:125], v[124:125], v[198:199] op_sel:[0,1]
	s_nop 0
	v_pk_fma_f32 v[76:77], v[76:77], v[198:199], v[124:125] op_sel_hi:[1,0,1]
	v_xor_b32_e32 v124, 0x80000000, v71
	v_mov_b32_e32 v125, v70
	s_waitcnt lgkmcnt(1)
	v_pk_mul_f32 v[124:125], v[124:125], v[200:201] op_sel:[0,1]
	s_nop 0
	v_pk_fma_f32 v[70:71], v[70:71], v[200:201], v[124:125] op_sel_hi:[1,0,1]
	v_xor_b32_e32 v124, 0x80000000, v69
	v_mov_b32_e32 v125, v68
	s_waitcnt lgkmcnt(0)
	v_pk_mul_f32 v[124:125], v[124:125], v[172:173] op_sel:[0,1]
	s_nop 0
	v_pk_fma_f32 v[68:69], v[68:69], v[172:173], v[124:125] op_sel_hi:[1,0,1]
	v_pk_add_f32 v[86:87], v[184:185], v[70:71]
	v_pk_add_f32 v[100:101], v[184:185], v[70:71] neg_lo:[0,1] neg_hi:[0,1]
	v_pk_add_f32 v[70:71], v[98:99], v[82:83]
	v_pk_add_f32 v[82:83], v[82:83], v[98:99] neg_lo:[0,1] neg_hi:[0,1]
	v_pk_add_f32 v[98:99], v[70:71], v[86:87]
	v_pk_add_f32 v[86:87], v[86:87], v[70:71] neg_lo:[0,1] neg_hi:[0,1]
	v_pk_add_f32 v[70:71], v[92:93], v[68:69]
	v_pk_add_f32 v[92:93], v[92:93], v[68:69] neg_lo:[0,1] neg_hi:[0,1]
	v_pk_add_f32 v[68:69], v[88:89], v[80:81]
	v_pk_add_f32 v[80:81], v[80:81], v[88:89] neg_lo:[0,1] neg_hi:[0,1]
	v_pk_add_f32 v[88:89], v[68:69], v[70:71]
	v_pk_add_f32 v[126:127], v[70:71], v[68:69] neg_lo:[0,1] neg_hi:[0,1]
	v_pk_add_f32 v[68:69], v[96:97], v[90:91]
	v_pk_add_f32 v[70:71], v[74:75], v[78:79]
	v_pk_add_f32 v[96:97], v[90:91], v[96:97] neg_lo:[0,1] neg_hi:[0,1]
	v_pk_add_f32 v[74:75], v[78:79], v[74:75] neg_lo:[0,1] neg_hi:[0,1]
	v_pk_add_f32 v[78:79], v[68:69], v[70:71]
	v_pk_add_f32 v[90:91], v[68:69], v[70:71] neg_lo:[0,1] neg_hi:[0,1]
	v_pk_add_f32 v[68:69], v[94:95], v[84:85]
	v_pk_add_f32 v[70:71], v[72:73], v[76:77]
	v_xor_b32_e32 v131, 0x80000000, v74
	v_mov_b32_e32 v130, v75
	v_pk_add_f32 v[72:73], v[76:77], v[72:73] neg_lo:[0,1] neg_hi:[0,1]
	v_pk_add_f32 v[74:75], v[68:69], v[70:71]
	v_xor_b32_e32 v129, 0x80000000, v80
	v_mov_b32_e32 v128, v81
	v_pk_add_f32 v[94:95], v[84:85], v[94:95] neg_lo:[0,1] neg_hi:[0,1]
	v_pk_add_f32 v[84:85], v[68:69], v[70:71] neg_lo:[0,1] neg_hi:[0,1]
	v_xor_b32_e32 v135, 0x80000000, v72
	v_mov_b32_e32 v134, v73
	v_pk_add_f32 v[68:69], v[78:79], v[98:99]
	v_pk_add_f32 v[70:71], v[74:75], v[88:89]
	v_pk_add_f32 v[72:73], v[88:89], v[74:75] neg_lo:[0,1] neg_hi:[0,1]
	v_pk_add_f32 v[80:81], v[128:129], v[92:93]
	v_pk_add_f32 v[78:79], v[98:99], v[78:79] neg_lo:[0,1] neg_hi:[0,1]
	v_pk_add_f32 v[74:75], v[68:69], v[70:71]
	v_pk_add_f32 v[70:71], v[68:69], v[70:71] neg_lo:[0,1] neg_hi:[0,1]
	v_xor_b32_e32 v69, 0x80000000, v72
	v_mov_b32_e32 v68, v73
	v_pk_add_f32 v[132:133], v[96:97], v[130:131]
	v_pk_add_f32 v[76:77], v[94:95], v[134:135]
	v_pk_add_f32 v[72:73], v[78:79], v[68:69]
	v_pk_add_f32 v[68:69], v[78:79], v[68:69] neg_lo:[0,1] neg_hi:[0,1]
	v_pk_mul_f32 v[78:79], v[80:81], s[28:29] op_sel:[1,0]
	v_xor_b32_e32 v125, 0x80000000, v82
	v_mov_b32_e32 v124, v83
	v_pk_fma_f32 v[78:79], v[80:81], s[26:27], v[78:79] op_sel_hi:[0,1,1]
	v_mul_f32_e32 v80, 0x3f3504f3, v133
	s_mov_b32 s29, s34
	v_pk_mul_f32 v[88:89], v[76:77], s[10:11] op_sel:[1,0]
	v_pk_add_f32 v[82:83], v[124:125], v[100:101]
	v_pk_fma_f32 v[80:81], v[132:133], s[30:31], v[80:81] op_sel_hi:[0,1,0]
	v_pk_fma_f32 v[76:77], v[76:77], s[28:29], v[88:89] op_sel_hi:[0,1,1]
	v_pk_add_f32 v[88:89], v[82:83], v[80:81]
	v_pk_add_f32 v[98:99], v[82:83], v[80:81] neg_lo:[0,1] neg_hi:[0,1]
	v_pk_add_f32 v[80:81], v[78:79], v[76:77]
	v_pk_add_f32 v[76:77], v[78:79], v[76:77] neg_lo:[0,1] neg_hi:[0,1]
	v_pk_add_f32 v[82:83], v[88:89], v[80:81]
	v_pk_add_f32 v[78:79], v[88:89], v[80:81] neg_lo:[0,1] neg_hi:[0,1]
	v_xor_b32_e32 v89, 0x80000000, v76
	v_mov_b32_e32 v88, v77
	v_pk_add_f32 v[80:81], v[98:99], v[88:89]
	v_pk_add_f32 v[76:77], v[98:99], v[88:89] neg_lo:[0,1] neg_hi:[0,1]
	v_pk_mul_f32 v[98:99], v[90:91], s[36:37] op_sel:[1,0]
	v_mul_f32_e32 v88, 0x3f3504f3, v127
	v_pk_fma_f32 v[90:91], v[90:91], s[20:21], v[98:99] op_sel_hi:[0,1,1]
	v_mul_f32_e32 v98, 0xbf3504f3, v84
	v_pk_fma_f32 v[88:89], v[126:127], s[30:31], v[88:89] op_sel_hi:[0,1,0]
	v_pk_fma_f32 v[84:85], v[84:85], s[30:31], v[98:99] op_sel:[1,0,0] op_sel_hi:[1,1,0]
	v_pk_add_f32 v[98:99], v[86:87], v[90:91]
	v_pk_add_f32 v[126:127], v[86:87], v[90:91] neg_lo:[0,1] neg_hi:[0,1]
	v_pk_add_f32 v[86:87], v[84:85], v[88:89]
	v_pk_add_f32 v[84:85], v[88:89], v[84:85] neg_lo:[0,1] neg_hi:[0,1]
	v_pk_add_f32 v[90:91], v[98:99], v[86:87]
	v_pk_add_f32 v[86:87], v[98:99], v[86:87] neg_lo:[0,1] neg_hi:[0,1]
	v_xor_b32_e32 v99, 0x80000000, v84
	v_mov_b32_e32 v98, v85
	v_pk_add_f32 v[94:95], v[94:95], v[134:135] neg_lo:[0,1] neg_hi:[0,1]
	v_pk_add_f32 v[88:89], v[126:127], v[98:99]
	v_pk_add_f32 v[84:85], v[126:127], v[98:99] neg_lo:[0,1] neg_hi:[0,1]
	v_pk_mul_f32 v[98:99], v[94:95], s[12:13] op_sel:[1,0]
	v_pk_add_f32 v[92:93], v[92:93], v[128:129] neg_lo:[0,1] neg_hi:[0,1]
	v_pk_fma_f32 v[94:95], v[94:95], s[34:35], v[98:99] op_sel_hi:[0,1,1]
	v_pk_add_f32 v[98:99], v[100:101], v[124:125] neg_lo:[0,1] neg_hi:[0,1]
	v_pk_mul_f32 v[100:101], v[92:93], s[10:11] op_sel:[1,0]
	v_pk_add_f32 v[96:97], v[96:97], v[130:131] neg_lo:[0,1] neg_hi:[0,1]
	v_pk_fma_f32 v[92:93], v[92:93], s[28:29], v[100:101] op_sel_hi:[0,1,1]
	v_mul_f32_e32 v100, 0xbf3504f3, v96
	v_pk_fma_f32 v[96:97], v[96:97], s[30:31], v[100:101] op_sel:[1,0,0] op_sel_hi:[1,1,0]
	v_pk_add_f32 v[124:125], v[92:93], v[94:95]
	v_pk_add_f32 v[100:101], v[98:99], v[96:97]
	v_pk_add_f32 v[94:95], v[92:93], v[94:95] neg_lo:[0,1] neg_hi:[0,1]
	v_pk_add_f32 v[98:99], v[98:99], v[96:97] neg_lo:[0,1] neg_hi:[0,1]
	v_pk_add_f32 v[96:97], v[100:101], v[124:125]
	v_pk_add_f32 v[92:93], v[100:101], v[124:125] neg_lo:[0,1] neg_hi:[0,1]
	v_xor_b32_e32 v101, 0x80000000, v94
	v_mov_b32_e32 v100, v95
	v_pk_add_f32 v[94:95], v[98:99], v[100:101]
	v_pk_add_f32 v[98:99], v[98:99], v[100:101] neg_lo:[0,1] neg_hi:[0,1]

.LBB0_1583:
	s_or_b64 exec, exec, s[8:9]
	s_waitcnt lgkmcnt(0)
	s_barrier
	s_and_saveexec_b64 s[8:9], vcc
	s_cbranch_execz .LBB0_1585
	ds_read_b64 v[172:173], v116 offset:32768
	v_cvt_f32_i32_e32 v70, v114
	v_lshlrev_b32_e32 v71, 3, v115
	v_lshlrev_b32_e32 v73, 3, v114
	v_mul_f32_e32 v72, 0x39000000, v70
	v_sin_f32_e32 v70, v72
	v_cos_f32_e32 v72, v72
	v_add3_u32 v76, s3, v71, v73
	ds_read_b64 v[174:175], v76
	v_xor_b32_e32 v73, 0x80000000, v70
	v_mov_b32_e32 v71, v72
	s_waitcnt lgkmcnt(1)
	v_pk_mul_f32 v[70:71], v[70:71], v[172:173] op_sel:[0,1]
	v_cvt_f32_i32_e32 v67, v67
	v_pk_fma_f32 v[68:69], v[72:73], v[172:173], v[70:71] op_sel_hi:[1,0,1]
	v_cvt_f32_i32_e32 v72, v112
	s_waitcnt lgkmcnt(0)
	v_pk_add_f32 v[70:71], v[174:175], v[68:69]
	v_pk_add_f32 v[68:69], v[174:175], v[68:69] neg_lo:[0,1] neg_hi:[0,1]
	ds_write_b64 v76, v[70:71]
	ds_write_b64 v116, v[68:69] offset:32768
	ds_read_b64 v[172:173], v113 offset:36864
	ds_read_b64 v[174:175], v109 offset:4096
	v_mul_f32_e32 v69, 0x39000000, v72
	v_cos_f32_e32 v68, v69
	v_sin_f32_e32 v70, v69
	v_cvt_f32_i32_e32 v31, v31
	v_mov_b32_e32 v71, v68
	v_xor_b32_e32 v69, 0x80000000, v70
	s_waitcnt lgkmcnt(1)
	v_pk_mul_f32 v[70:71], v[70:71], v[172:173] op_sel:[0,1]
	v_cvt_f32_i32_e32 v19, v19
	v_pk_fma_f32 v[68:69], v[68:69], v[172:173], v[70:71] op_sel_hi:[1,0,1]
	v_cvt_f32_i32_e32 v72, v110
	s_waitcnt lgkmcnt(0)
	v_pk_add_f32 v[70:71], v[174:175], v[68:69]
	v_pk_add_f32 v[68:69], v[174:175], v[68:69] neg_lo:[0,1] neg_hi:[0,1]
	ds_write_b64 v109, v[70:71] offset:4096
	ds_write_b64 v113, v[68:69] offset:36864
	ds_read_b64 v[172:173], v111 offset:40960
	ds_read_b64 v[174:175], v106 offset:8192
	v_mul_f32_e32 v69, 0x39000000, v72
	v_cos_f32_e32 v68, v69
	v_sin_f32_e32 v70, v69
	v_mov_b32_e32 v71, v68
	v_xor_b32_e32 v69, 0x80000000, v70
	s_waitcnt lgkmcnt(1)
	v_pk_mul_f32 v[70:71], v[70:71], v[172:173] op_sel:[0,1]
	s_nop 0
	v_pk_fma_f32 v[68:69], v[68:69], v[172:173], v[70:71] op_sel_hi:[1,0,1]
	v_cvt_f32_i32_e32 v72, v107
	s_waitcnt lgkmcnt(0)
	v_pk_add_f32 v[70:71], v[174:175], v[68:69]
	v_pk_add_f32 v[68:69], v[174:175], v[68:69] neg_lo:[0,1] neg_hi:[0,1]
	ds_write_b64 v106, v[70:71] offset:8192
	ds_write_b64 v111, v[68:69] offset:40960
	ds_read_b64 v[172:173], v108 offset:45056
	ds_read_b64 v[174:175], v103 offset:12288
	v_mul_f32_e32 v69, 0x39000000, v72
	v_cos_f32_e32 v68, v69
	v_sin_f32_e32 v70, v69
	v_mov_b32_e32 v71, v68
	v_xor_b32_e32 v69, 0x80000000, v70
	s_waitcnt lgkmcnt(1)
	v_pk_mul_f32 v[70:71], v[70:71], v[172:173] op_sel:[0,1]
	s_nop 0
	v_pk_fma_f32 v[68:69], v[68:69], v[172:173], v[70:71] op_sel_hi:[1,0,1]
	v_cvt_f32_i32_e32 v72, v104
	s_waitcnt lgkmcnt(0)
	v_pk_add_f32 v[70:71], v[174:175], v[68:69]
	v_pk_add_f32 v[68:69], v[174:175], v[68:69] neg_lo:[0,1] neg_hi:[0,1]
	ds_write_b64 v103, v[70:71] offset:12288
	ds_write_b64 v108, v[68:69] offset:45056
	ds_read_b64 v[172:173], v105 offset:49152
	ds_read_b64 v[174:175], v65 offset:16384
	v_mul_f32_e32 v69, 0x39000000, v72
	v_cos_f32_e32 v68, v69
	v_sin_f32_e32 v70, v69
	v_mov_b32_e32 v71, v68
	v_xor_b32_e32 v69, 0x80000000, v70
	s_waitcnt lgkmcnt(1)
	v_pk_mul_f32 v[70:71], v[70:71], v[172:173] op_sel:[0,1]
	s_nop 0
	v_pk_fma_f32 v[68:69], v[68:69], v[172:173], v[70:71] op_sel_hi:[1,0,1]
	s_waitcnt lgkmcnt(0)
	v_pk_add_f32 v[70:71], v[174:175], v[68:69]
	ds_write_b64 v65, v[70:71] offset:16384
	v_pk_add_f32 v[68:69], v[174:175], v[68:69] neg_lo:[0,1] neg_hi:[0,1]
	v_mul_f32_e32 v65, 0x39000000, v67
	ds_write_b64 v105, v[68:69] offset:49152
	ds_read_b64 v[172:173], v102 offset:53248
	ds_read_b64 v[174:175], v27 offset:20480
	v_cos_f32_e32 v68, v65
	v_sin_f32_e32 v70, v65
	v_mov_b32_e32 v71, v68
	v_xor_b32_e32 v69, 0x80000000, v70
	s_waitcnt lgkmcnt(1)
	v_pk_mul_f32 v[70:71], v[70:71], v[172:173] op_sel:[0,1]
	s_nop 0
	v_pk_fma_f32 v[68:69], v[68:69], v[172:173], v[70:71] op_sel_hi:[1,0,1]
	s_waitcnt lgkmcnt(0)
	v_pk_add_f32 v[70:71], v[174:175], v[68:69]
	ds_write_b64 v27, v[70:71] offset:20480
	v_pk_add_f32 v[68:69], v[174:175], v[68:69] neg_lo:[0,1] neg_hi:[0,1]
	v_mul_f32_e32 v27, 0x39000000, v31
	ds_write_b64 v102, v[68:69] offset:53248
	ds_read_b64 v[172:173], v63 offset:57344
	ds_read_b64 v[174:175], v15 offset:24576
	v_cos_f32_e32 v68, v27
	v_sin_f32_e32 v70, v27
	v_mov_b32_e32 v71, v68
	v_xor_b32_e32 v69, 0x80000000, v70
	s_waitcnt lgkmcnt(1)
	v_pk_mul_f32 v[70:71], v[70:71], v[172:173] op_sel:[0,1]
	s_nop 0
	v_pk_fma_f32 v[68:69], v[68:69], v[172:173], v[70:71] op_sel_hi:[1,0,1]
	s_waitcnt lgkmcnt(0)
	v_pk_add_f32 v[70:71], v[174:175], v[68:69]
	ds_write_b64 v15, v[70:71] offset:24576
	v_pk_add_f32 v[68:69], v[174:175], v[68:69] neg_lo:[0,1] neg_hi:[0,1]
	v_mul_f32_e32 v15, 0x39000000, v19
	ds_write_b64 v63, v[68:69] offset:57344
	v_cos_f32_e32 v68, v15
	v_sin_f32_e32 v70, v15
	ds_read_b64 v[72:73], v23 offset:61440
	ds_read_b64 v[74:75], v11 offset:28672
	v_mov_b32_e32 v71, v68
	v_xor_b32_e32 v69, 0x80000000, v70
	s_waitcnt lgkmcnt(1)
	v_pk_mul_f32 v[70:71], v[70:71], v[72:73] op_sel:[0,1]
	s_nop 0
	v_pk_fma_f32 v[68:69], v[68:69], v[72:73], v[70:71] op_sel_hi:[1,0,1]
	s_waitcnt lgkmcnt(0)
	v_pk_add_f32 v[70:71], v[74:75], v[68:69]
	v_pk_add_f32 v[68:69], v[74:75], v[68:69] neg_lo:[0,1] neg_hi:[0,1]
	ds_write_b64 v11, v[70:71] offset:28672
	ds_write_b64 v23, v[68:69] offset:61440
.LBB0_1585:
	s_or_b64 exec, exec, s[8:9]
	v_readlane_b32 s4, v240, 49
	v_readlane_b32 s18, v240, 63
	v_readlane_b32 s5, v240, 50
	v_readlane_b32 s6, v240, 51
	v_readlane_b32 s7, v240, 52
	v_readlane_b32 s8, v240, 53
	v_readlane_b32 s9, v240, 54
	v_readlane_b32 s10, v240, 55
	v_readlane_b32 s11, v240, 56
	v_readlane_b32 s12, v240, 57
	v_readlane_b32 s13, v240, 58
	v_readlane_b32 s14, v240, 59
	v_readlane_b32 s15, v240, 60
	v_readlane_b32 s16, v240, 61
	v_readlane_b32 s17, v240, 62
	v_readlane_b32 s19, v239, 0
	s_add_u32 s62, s18, s60
	s_addc_u32 s63, s19, s61
	v_readlane_b32 s4, v239, 19
	v_readlane_b32 s5, v239, 20
	s_add_u32 s64, s4, s60
	s_addc_u32 s65, s5, s61
	s_waitcnt lgkmcnt(0)
	s_barrier
	global_load_dword v84, v39, s[62:63]
	global_load_dword v85, v47, s[62:63]
	global_load_dword v11, v51, s[62:63]
	global_load_dword v15, v39, s[64:65]
	v_readlane_b32 s6, v239, 21
	v_readlane_b32 s7, v239, 22
	v_cmp_lt_i32_e32 vcc, 0, v64
	v_cmp_gt_i32_e64 s[6:7], s51, v64
	v_readlane_b32 s8, v239, 23
	s_waitcnt vmcnt(19)
	v_cndmask_b32_e32 v19, 0, v56, vcc
	v_readlane_b32 s9, v239, 24
	v_readlane_b32 s10, v239, 25
	v_readlane_b32 s11, v239, 26
	v_readlane_b32 s12, v239, 27
	v_readlane_b32 s13, v239, 28
	v_readlane_b32 s14, v239, 29
	v_readlane_b32 s15, v239, 30
	v_readlane_b32 s16, v239, 31
	v_readlane_b32 s17, v239, 32
	v_readlane_b32 s18, v239, 33
	v_readlane_b32 s19, v239, 34
	s_waitcnt vmcnt(0)
	v_fma_f32 v82, v57, v85, v15
	v_fmac_f32_e32 v82, v84, v19
	v_cndmask_b32_e64 v19, 0, v58, s[6:7]
	v_fmac_f32_e32 v82, v19, v11
	v_fma_f32 v83, v61, v85, v15
	v_cndmask_b32_e32 v19, 0, v60, vcc
	v_fmac_f32_e32 v83, v84, v19
	v_cndmask_b32_e64 v19, 0, v62, s[6:7]
	v_fmac_f32_e32 v83, v19, v11
	v_cmp_gt_i32_e32 vcc, s69, v64
	v_lshlrev_b32_e32 v19, 3, v64
	s_and_saveexec_b64 s[6:7], vcc
	v_ashrrev_i32_e32 v23, 4, v64
	v_lshlrev_b32_e32 v23, 3, v23
	v_add3_u32 v23, 0, v23, v19
	ds_write_b64 v23, v[82:83]
	s_or_b64 exec, exec, s[6:7]
	s_movk_i32 s4, 0xfe00
	v_cmp_lt_i32_e32 vcc, s4, v64
	s_movk_i32 s4, 0xdff
	v_cmp_gt_i32_e64 s[6:7], s4, v64
	v_cndmask_b32_e32 v52, 0, v52, vcc
	v_pk_mul_f32 v[52:53], v[84:85], v[52:53]
	v_cndmask_b32_e32 v48, 0, v48, vcc
	v_add_f32_e32 v23, v53, v15
	v_add_f32_e32 v80, v52, v23
	v_cndmask_b32_e64 v23, 0, v54, s[6:7]
	v_pk_mul_f32 v[48:49], v[84:85], v[48:49]
	v_fmac_f32_e32 v80, v23, v11
	v_add_f32_e32 v23, v49, v15
	v_add_f32_e32 v81, v48, v23
	v_cndmask_b32_e64 v23, 0, v50, s[6:7]
	v_fmac_f32_e32 v81, v23, v11
	v_cmp_gt_i32_e32 vcc, s95, v64
	s_and_saveexec_b64 s[6:7], vcc
	v_add_u32_e32 v23, 0x200, v64
	v_ashrrev_i32_e32 v23, 4, v23
	v_lshlrev_b32_e32 v23, 3, v23
	v_add3_u32 v23, 0, v23, v19
	ds_write_b64 v23, v[80:81] offset:4096
	s_or_b64 exec, exec, s[6:7]
	s_movk_i32 s4, 0xfc00
	v_cmp_lt_i32_e32 vcc, s4, v64
	s_movk_i32 s4, 0xbff
	v_cmp_gt_i32_e64 s[6:7], s4, v64
	v_cndmask_b32_e32 v44, 0, v44, vcc
	v_pk_mul_f32 v[44:45], v[84:85], v[44:45]
	v_cndmask_b32_e32 v40, 0, v40, vcc
	v_add_f32_e32 v23, v45, v15
	v_add_f32_e32 v78, v44, v23
	v_cndmask_b32_e64 v23, 0, v46, s[6:7]
	v_pk_mul_f32 v[40:41], v[84:85], v[40:41]
	v_fmac_f32_e32 v78, v23, v11
	v_add_f32_e32 v23, v41, v15
	v_add_f32_e32 v79, v40, v23
	v_cndmask_b32_e64 v23, 0, v42, s[6:7]
	v_fmac_f32_e32 v79, v23, v11
	v_cmp_gt_i32_e32 vcc, s75, v64
	s_and_saveexec_b64 s[6:7], vcc
	v_add_u32_e32 v23, 0x400, v64
	v_ashrrev_i32_e32 v23, 4, v23
	v_lshlrev_b32_e32 v23, 3, v23
	v_add3_u32 v23, 0, v23, v19
	ds_write_b64 v23, v[78:79] offset:8192
	s_or_b64 exec, exec, s[6:7]
	s_movk_i32 s4, 0xfa00
	v_cmp_lt_i32_e32 vcc, s4, v64
	s_movk_i32 s4, 0x9ff
	v_cmp_gt_i32_e64 s[6:7], s4, v64
	v_cndmask_b32_e32 v36, 0, v36, vcc
	v_pk_mul_f32 v[36:37], v[84:85], v[36:37]
	v_cndmask_b32_e32 v32, 0, v32, vcc
	v_add_f32_e32 v23, v37, v15
	v_add_f32_e32 v76, v36, v23
	v_cndmask_b32_e64 v23, 0, v38, s[6:7]
	v_pk_mul_f32 v[32:33], v[84:85], v[32:33]
	v_fmac_f32_e32 v76, v23, v11
	v_add_f32_e32 v23, v33, v15
	v_add_f32_e32 v77, v32, v23
	v_cndmask_b32_e64 v23, 0, v34, s[6:7]
	v_fmac_f32_e32 v77, v23, v11
	v_cmp_gt_i32_e32 vcc, s74, v64
	s_and_saveexec_b64 s[6:7], vcc
	v_add_u32_e32 v23, 0x600, v64
	v_ashrrev_i32_e32 v23, 4, v23
	v_lshlrev_b32_e32 v23, 3, v23
	v_add3_u32 v23, 0, v23, v19
	ds_write_b64 v23, v[76:77] offset:12288
	s_or_b64 exec, exec, s[6:7]
	s_movk_i32 s4, 0xf800
	v_cmp_lt_i32_e32 vcc, s4, v64
	v_cmp_gt_i32_e64 s[6:7], s43, v64
	s_nop 0
	v_cndmask_b32_e32 v28, 0, v28, vcc
	v_pk_mul_f32 v[28:29], v[84:85], v[28:29]
	v_cndmask_b32_e32 v24, 0, v24, vcc
	v_add_f32_e32 v23, v29, v15
	v_add_f32_e32 v74, v28, v23
	v_cndmask_b32_e64 v23, 0, v30, s[6:7]
	v_pk_mul_f32 v[24:25], v[84:85], v[24:25]
	v_fmac_f32_e32 v74, v23, v11
	v_add_f32_e32 v23, v25, v15
	v_add_f32_e32 v75, v24, v23
	v_cndmask_b32_e64 v23, 0, v26, s[6:7]
	v_fmac_f32_e32 v75, v23, v11
	v_cmp_gt_i32_e32 vcc, s68, v64
	s_and_saveexec_b64 s[6:7], vcc
	v_add_u32_e32 v23, 0x800, v64
	v_ashrrev_i32_e32 v23, 4, v23
	v_lshlrev_b32_e32 v23, 3, v23
	v_add3_u32 v23, 0, v23, v19
	ds_write_b64 v23, v[74:75] offset:16384
	s_or_b64 exec, exec, s[6:7]
	s_movk_i32 s4, 0xf600
	v_cmp_lt_i32_e32 vcc, s4, v64
	s_movk_i32 s4, 0x5ff
	v_cmp_gt_i32_e64 s[6:7], s4, v64
	v_cndmask_b32_e32 v20, 0, v20, vcc
	v_cndmask_b32_e32 v16, 0, v16, vcc
	v_pk_mul_f32 v[20:21], v[84:85], v[20:21]
	v_pk_mul_f32 v[16:17], v[84:85], v[16:17]
	v_add_f32_e32 v21, v21, v15
	v_add_f32_e32 v17, v17, v15
	v_add_f32_e32 v72, v20, v21
	v_cndmask_b32_e64 v20, 0, v22, s[6:7]
	v_add_f32_e32 v73, v16, v17
	v_cndmask_b32_e64 v16, 0, v18, s[6:7]
	v_fmac_f32_e32 v72, v20, v11
	v_fmac_f32_e32 v73, v16, v11
	v_cmp_gt_i32_e32 vcc, s72, v64
	s_and_saveexec_b64 s[6:7], vcc
	v_add_u32_e32 v16, 0xa00, v64
	v_ashrrev_i32_e32 v16, 4, v16
	v_lshlrev_b32_e32 v16, 3, v16
	v_add3_u32 v16, 0, v16, v19
	ds_write_b64 v16, v[72:73] offset:20480
	s_or_b64 exec, exec, s[6:7]
	s_movk_i32 s4, 0xf400
	v_cmp_lt_i32_e32 vcc, s4, v64
	s_movk_i32 s4, 0x3ff
	v_cmp_gt_i32_e64 s[6:7], s4, v64
	v_cndmask_b32_e32 v12, 0, v12, vcc
	v_cndmask_b32_e32 v8, 0, v8, vcc
	v_pk_mul_f32 v[12:13], v[84:85], v[12:13]
	v_pk_mul_f32 v[8:9], v[84:85], v[8:9]
	v_add_f32_e32 v13, v13, v15
	v_add_f32_e32 v9, v9, v15
	v_add_f32_e32 v68, v12, v13
	v_cndmask_b32_e64 v12, 0, v14, s[6:7]
	v_add_f32_e32 v69, v8, v9
	v_cndmask_b32_e64 v8, 0, v10, s[6:7]
	v_fmac_f32_e32 v68, v12, v11
	v_fmac_f32_e32 v69, v8, v11
	v_cmp_gt_i32_e32 vcc, s71, v64
	s_and_saveexec_b64 s[6:7], vcc
	v_add_u32_e32 v8, 0xc00, v64
	v_ashrrev_i32_e32 v8, 4, v8
	v_lshlrev_b32_e32 v8, 3, v8
	v_add3_u32 v8, 0, v8, v19
	ds_write_b64 v8, v[68:69] offset:24576
	s_or_b64 exec, exec, s[6:7]
	s_movk_i32 s4, 0xf200
	v_cmp_lt_i32_e32 vcc, s4, v64
	v_cmp_gt_i32_e64 s[6:7], s25, v64
	s_nop 0
	v_cndmask_b32_e32 v0, 0, v0, vcc
	v_cndmask_b32_e32 v4, 0, v4, vcc
	v_pk_mul_f32 v[4:5], v[84:85], v[4:5]
	v_pk_mul_f32 v[0:1], v[84:85], v[0:1]
	v_add_f32_e32 v5, v5, v15
	v_add_f32_e32 v1, v1, v15
	v_cndmask_b32_e64 v2, 0, v2, s[6:7]
	v_cndmask_b32_e64 v6, 0, v6, s[6:7]
	v_add_f32_e32 v71, v4, v5
	v_add_f32_e32 v70, v0, v1
	v_fmac_f32_e32 v70, v2, v11
	v_fmac_f32_e32 v71, v6, v11
	v_cmp_gt_i32_e32 vcc, s70, v64
	s_and_saveexec_b64 s[6:7], vcc
	v_add_u32_e32 v0, 0xe00, v64
	v_ashrrev_i32_e32 v0, 4, v0
	v_lshlrev_b32_e32 v0, 3, v0
	v_add3_u32 v0, 0, v0, v19
	ds_write_b64 v0, v[70:71] offset:28672
	s_or_b64 exec, exec, s[6:7]
	v_readlane_b32 s76, v240, 22
	v_readlane_b32 s80, v240, 26
	v_readlane_b32 s81, v240, 27
	v_readlane_b32 s82, v240, 28
	v_readlane_b32 s83, v240, 29
	v_readlane_b32 s84, v240, 30
	v_readlane_b32 s85, v240, 31
	v_readlane_b32 s86, v240, 32
	v_readlane_b32 s87, v240, 33
	v_readlane_b32 s88, v240, 34
	v_readlane_b32 s89, v240, 35
	v_readlane_b32 s90, v240, 36
	v_readlane_b32 s91, v240, 37
	s_mov_b64 s[8:9], s[80:81]
	s_mul_hi_i32 s7, s2, 0x8800
	s_mul_i32 s2, s2, 0x8800
	s_mov_b64 s[12:13], s[84:85]
	s_add_u32 s6, s12, s2
	s_addc_u32 s7, s13, s7
	v_ashrrev_i32_e32 v65, 31, v64
	v_lshl_add_u64 v[4:5], v[64:65], 2, s[6:7]
	v_add_co_u32_e32 v0, vcc, s94, v4
	global_load_dwordx3 v[56:58], v[4:5], off offset:-4
	global_load_dwordx3 v[48:50], v[4:5], off offset:2044
	v_addc_co_u32_e32 v1, vcc, 0, v5, vcc
	v_add_co_u32_e32 v8, vcc, s1, v4
	v_mov_b32_e32 v128, v64
	s_nop 0
	v_addc_co_u32_e32 v9, vcc, 0, v5, vcc
	v_add_co_u32_e32 v10, vcc, s69, v4
	global_load_dwordx3 v[60:62], v[0:1], off offset:4092
	global_load_dwordx3 v[52:54], v[8:9], off offset:2044
	v_addc_co_u32_e32 v11, vcc, 0, v5, vcc
	global_load_dwordx3 v[40:42], v[8:9], off offset:4092
	global_load_dwordx3 v[32:34], v[10:11], off offset:2044
	v_add_co_u32_e32 v8, vcc, s24, v4
	v_mov_b32_e32 v116, 0
	s_nop 0
	v_addc_co_u32_e32 v9, vcc, 0, v5, vcc
	global_load_dwordx3 v[36:38], v[8:9], off offset:2044
	global_load_dwordx3 v[24:26], v[10:11], off offset:4092
	v_add_co_u32_e32 v10, vcc, s73, v4
	v_mov_b32_e32 v117, 0
	s_nop 0
	v_addc_co_u32_e32 v11, vcc, 0, v5, vcc
	v_add_co_u32_e32 v12, vcc, s46, v4
	global_load_dwordx3 v[28:30], v[8:9], off offset:4092
	global_load_dwordx3 v[16:18], v[10:11], off offset:2044
	v_addc_co_u32_e32 v13, vcc, 0, v5, vcc
	global_load_dwordx3 v[20:22], v[12:13], off offset:2044
	s_nop 0
	global_load_dwordx3 v[8:10], v[10:11], off offset:4092
	s_nop 0
	global_load_dwordx3 v[44:46], v[4:5], off offset:4092
	s_nop 0
	global_load_dwordx3 v[0:2], v[0:1], off offset:2044
	v_add_co_u32_e32 v4, vcc, s47, v4
	v_mov_b32_e32 v90, 0
	s_nop 0
	v_addc_co_u32_e32 v5, vcc, 0, v5, vcc
	global_load_dwordx3 v[12:14], v[12:13], off offset:4092
	s_nop 0
	global_load_dwordx3 v[4:6], v[4:5], off offset:2044
	s_waitcnt lgkmcnt(0)
	s_barrier
	v_mov_b32_e32 v91, v116
	v_add_u32_e32 v126, 0x200, v128
	v_lshl_add_u32 v129, v128, 3, 0
	v_ashrrev_i32_e32 v11, 4, v126
	v_add_u32_e32 v125, 0x400, v128
	v_lshl_add_u32 v124, v11, 3, v129
	v_ashrrev_i32_e32 v11, 4, v125
	v_add_u32_e32 v123, 0x600, v128
	v_lshl_add_u32 v122, v11, 3, v129
	v_ashrrev_i32_e32 v11, 4, v123
	v_add_u32_e32 v67, 0x800, v128
	v_lshl_add_u32 v65, v11, 3, v129
	v_ashrrev_i32_e32 v11, 4, v67
	v_add_u32_e32 v63, 0xa00, v128
	v_lshl_add_u32 v31, v11, 3, v129
	v_ashrrev_i32_e32 v11, 4, v63
	v_add_u32_e32 v27, 0xc00, v128
	v_lshl_add_u32 v23, v11, 3, v129
	v_ashrrev_i32_e32 v11, 4, v27
	v_add_u32_e32 v19, 0xe00, v128
	v_ashrrev_i32_e32 v127, 4, v128
	v_lshl_add_u32 v15, v11, 3, v129
	v_ashrrev_i32_e32 v11, 4, v19
	v_cmp_gt_i32_e32 vcc, s70, v128
	v_lshl_add_u32 v136, v127, 3, v129
	v_lshl_add_u32 v11, v11, 3, v129
	v_mov_b32_e32 v98, v116
	v_mov_b32_e32 v99, v116
	v_mov_b32_e32 v106, v116
	v_mov_b32_e32 v107, v116
	v_mov_b32_e32 v112, v116
	v_mov_b32_e32 v113, v116
	v_mov_b32_e32 v88, v116
	v_mov_b32_e32 v89, v116
	v_mov_b32_e32 v96, v116
	v_mov_b32_e32 v97, v116
	v_mov_b32_e32 v104, v116
	v_mov_b32_e32 v105, v116
	v_mov_b32_e32 v110, v116
	v_mov_b32_e32 v111, v116
	v_mov_b32_e32 v86, v116
	v_mov_b32_e32 v87, v116
	v_mov_b32_e32 v94, v116
	v_mov_b32_e32 v95, v116
	v_mov_b32_e32 v102, v116
	v_mov_b32_e32 v103, v116
	v_mov_b32_e32 v108, v116
	v_mov_b32_e32 v109, v116
	v_mov_b32_e32 v84, v116
	v_mov_b32_e32 v85, v116
	v_mov_b32_e32 v92, v116
	v_mov_b32_e32 v93, v116
	v_mov_b32_e32 v100, v116
	v_mov_b32_e32 v101, v116
	v_mov_b32_e32 v114, v116
	v_mov_b32_e32 v115, v116
	v_readlane_b32 s77, v240, 23
	v_readlane_b32 s78, v240, 24
	v_readlane_b32 s79, v240, 25
	s_mov_b64 s[10:11], s[82:83]
	s_mov_b64 s[14:15], s[86:87]
	s_mov_b64 s[16:17], s[88:89]
	s_mov_b64 s[18:19], s[90:91]
	s_and_saveexec_b64 s[6:7], vcc
	s_xor_b64 s[6:7], exec, s[6:7]
	s_cbranch_execz .LBB0_1603
	ds_read_b64 v[172:173], v136
	ds_read_b64 v[174:175], v124 offset:4096
	ds_read_b64 v[176:177], v122 offset:8192
	ds_read_b64 v[178:179], v65 offset:12288
	ds_read_b64 v[180:181], v31 offset:16384
	ds_read_b64 v[182:183], v23 offset:20480
	ds_read_b64 v[184:185], v15 offset:24576
	ds_read_b64 v[186:187], v11 offset:28672
	s_waitcnt lgkmcnt(7)
	v_pk_add_f32 v[92:93], v[172:173], 0 op_sel_hi:[1,0]
	s_waitcnt lgkmcnt(3)
	v_pk_add_f32 v[94:95], v[180:181], 0 op_sel_hi:[1,0]
	v_xor_b32_e32 v117, 0x80000000, v180
	v_pk_add_f32 v[96:97], v[92:93], v[94:95]
	v_pk_add_f32 v[100:101], v[92:93], v[94:95] neg_lo:[0,1] neg_hi:[0,1]
	v_mov_b32_e32 v116, v181
	v_pk_add_f32 v[84:85], v[174:175], 0 op_sel_hi:[1,0]
	s_waitcnt lgkmcnt(2)
	v_pk_add_f32 v[94:95], v[182:183], 0 op_sel_hi:[1,0]
	v_xor_b32_e32 v131, 0x80000000, v182
	v_pk_add_f32 v[98:99], v[84:85], v[94:95]
	v_pk_add_f32 v[102:103], v[84:85], v[94:95] neg_lo:[0,1] neg_hi:[0,1]
	v_mov_b32_e32 v130, v183
	v_pk_add_f32 v[84:85], v[176:177], 0 op_sel_hi:[1,0]
	s_waitcnt lgkmcnt(1)
	v_pk_add_f32 v[86:87], v[184:185], 0 op_sel_hi:[1,0]
	v_xor_b32_e32 v133, 0x80000000, v184
	v_pk_add_f32 v[104:105], v[84:85], v[86:87]
	v_pk_add_f32 v[106:107], v[84:85], v[86:87] neg_lo:[0,1] neg_hi:[0,1]
	v_pk_add_f32 v[84:85], v[178:179], 0 op_sel_hi:[1,0]
	s_waitcnt lgkmcnt(0)
	v_pk_add_f32 v[86:87], v[186:187], 0 op_sel_hi:[1,0]
	v_mov_b32_e32 v132, v185
	v_pk_add_f32 v[88:89], v[84:85], v[86:87]
	v_pk_add_f32 v[138:139], v[84:85], v[86:87] neg_lo:[0,1] neg_hi:[0,1]
	v_pk_add_f32 v[84:85], v[96:97], v[104:105]
	v_pk_add_f32 v[86:87], v[98:99], v[88:89]
	v_pk_add_f32 v[88:89], v[98:99], v[88:89] neg_lo:[0,1] neg_hi:[0,1]
	v_pk_add_f32 v[94:95], v[174:175], v[130:131]
	v_xor_b32_e32 v141, 0x80000000, v186
	v_mov_b32_e32 v140, v187
	v_pk_add_f32 v[96:97], v[96:97], v[104:105] neg_lo:[0,1] neg_hi:[0,1]
	v_pk_add_f32 v[90:91], v[84:85], v[86:87]
	v_pk_add_f32 v[86:87], v[84:85], v[86:87] neg_lo:[0,1] neg_hi:[0,1]
	v_xor_b32_e32 v85, 0x80000000, v88
	v_mov_b32_e32 v84, v89
	s_mov_b32 s29, s26
	v_pk_add_f32 v[134:135], v[176:177], v[132:133]
	v_pk_add_f32 v[142:143], v[178:179], v[140:141]
	v_pk_add_f32 v[88:89], v[96:97], v[84:85]
	v_pk_add_f32 v[84:85], v[96:97], v[84:85] neg_lo:[0,1] neg_hi:[0,1]
	v_pk_mul_f32 v[96:97], v[94:95], s[28:29] op_sel:[1,0]
	s_mov_b32 s8, s26
	s_mov_b32 s9, s28
	v_pk_fma_f32 v[94:95], v[94:95], s[26:27], v[96:97] op_sel_hi:[0,1,1]
	v_mul_f32_e32 v96, 0x3f3504f3, v135
	s_mov_b32 s29, s34
	v_pk_mul_f32 v[98:99], v[142:143], s[8:9] op_sel:[1,0]
	v_pk_add_f32 v[92:93], v[172:173], v[116:117]
	v_pk_fma_f32 v[96:97], v[134:135], s[30:31], v[96:97] op_sel_hi:[0,1,0]
	v_pk_fma_f32 v[98:99], v[142:143], s[28:29], v[98:99] op_sel_hi:[0,1,1]
	v_pk_add_f32 v[104:105], v[92:93], v[96:97]
	v_pk_add_f32 v[92:93], v[92:93], v[96:97] neg_lo:[0,1] neg_hi:[0,1]
	v_pk_add_f32 v[96:97], v[94:95], v[98:99]
	v_pk_add_f32 v[134:135], v[94:95], v[98:99] neg_lo:[0,1] neg_hi:[0,1]
	v_pk_add_f32 v[98:99], v[104:105], v[96:97]
	v_pk_add_f32 v[94:95], v[104:105], v[96:97] neg_lo:[0,1] neg_hi:[0,1]
	v_xor_b32_e32 v105, 0x80000000, v134
	v_mov_b32_e32 v104, v135
	v_pk_add_f32 v[96:97], v[92:93], v[104:105]
	v_pk_add_f32 v[92:93], v[92:93], v[104:105] neg_lo:[0,1] neg_hi:[0,1]
	v_mul_f32_e32 v104, 0x3f3504f3, v103
	s_mov_b32 s37, s20
	v_pk_fma_f32 v[102:103], v[102:103], s[30:31], v[104:105] op_sel_hi:[0,1,0]
	v_pk_mul_f32 v[104:105], v[106:107], s[36:37] op_sel:[1,0]
	v_pk_add_f32 v[110:111], v[174:175], v[130:131] neg_lo:[0,1] neg_hi:[0,1]
	v_pk_fma_f32 v[104:105], v[106:107], s[20:21], v[104:105] op_sel_hi:[0,1,1]
	v_mul_f32_e32 v106, 0xbf3504f3, v138
	v_pk_fma_f32 v[106:107], v[138:139], s[30:31], v[106:107] op_sel:[1,0,0] op_sel_hi:[1,1,0]
	v_pk_add_f32 v[134:135], v[100:101], v[104:105]
	v_pk_add_f32 v[100:101], v[100:101], v[104:105] neg_lo:[0,1] neg_hi:[0,1]
	v_pk_add_f32 v[104:105], v[102:103], v[106:107]
	v_pk_add_f32 v[138:139], v[102:103], v[106:107] neg_lo:[0,1] neg_hi:[0,1]
	v_pk_add_f32 v[106:107], v[134:135], v[104:105]
	v_pk_add_f32 v[102:103], v[134:135], v[104:105] neg_lo:[0,1] neg_hi:[0,1]
	v_xor_b32_e32 v135, 0x80000000, v138
	v_mov_b32_e32 v134, v139
	v_pk_add_f32 v[114:115], v[178:179], v[140:141] neg_lo:[0,1] neg_hi:[0,1]
	s_mov_b32 s10, s27
	s_mov_b32 s11, s34
	v_pk_add_f32 v[108:109], v[172:173], v[116:117] neg_lo:[0,1] neg_hi:[0,1]
	v_pk_mul_f32 v[116:117], v[110:111], s[8:9] op_sel:[1,0]
	v_pk_add_f32 v[112:113], v[176:177], v[132:133] neg_lo:[0,1] neg_hi:[0,1]
	v_pk_add_f32 v[104:105], v[100:101], v[134:135]
	v_pk_add_f32 v[100:101], v[100:101], v[134:135] neg_lo:[0,1] neg_hi:[0,1]
	s_mov_b32 s35, s28
	v_pk_mul_f32 v[134:135], v[114:115], s[10:11] op_sel:[1,0]
	v_pk_fma_f32 v[110:111], v[110:111], s[28:29], v[116:117] op_sel_hi:[0,1,1]
	v_mul_f32_e32 v116, 0xbf3504f3, v112
	v_pk_fma_f32 v[114:115], v[114:115], s[34:35], v[134:135] op_sel_hi:[0,1,1]
	v_pk_fma_f32 v[112:113], v[112:113], s[30:31], v[116:117] op_sel:[1,0,0] op_sel_hi:[1,1,0]
	s_nop 0
	v_pk_add_f32 v[116:117], v[108:109], v[112:113]
	v_pk_add_f32 v[130:131], v[108:109], v[112:113] neg_lo:[0,1] neg_hi:[0,1]
	v_pk_add_f32 v[108:109], v[110:111], v[114:115]
	v_pk_add_f32 v[110:111], v[110:111], v[114:115] neg_lo:[0,1] neg_hi:[0,1]
	v_pk_add_f32 v[112:113], v[116:117], v[108:109]
	v_xor_b32_e32 v115, 0x80000000, v110
	v_mov_b32_e32 v114, v111
	v_pk_add_f32 v[108:109], v[116:117], v[108:109] neg_lo:[0,1] neg_hi:[0,1]
	v_pk_add_f32 v[116:117], v[130:131], v[114:115] neg_lo:[0,1] neg_hi:[0,1]
	v_pk_add_f32 v[110:111], v[130:131], v[114:115]
	v_mov_b32_e32 v114, v116
	v_mov_b32_e32 v115, v117

.LBB0_1605:
	s_or_b64 exec, exec, s[6:7]
	v_add_u32_e32 v116, 0x1000, v128
	v_ashrrev_i32_e32 v116, 4, v116
	v_lshlrev_b32_e32 v116, 3, v116
	v_lshlrev_b32_e32 v135, 3, v128
	v_add3_u32 v134, 0, v116, v135
	v_add_u32_e32 v116, 0x1200, v128
	v_ashrrev_i32_e32 v116, 4, v116
	v_lshlrev_b32_e32 v116, 3, v116
	v_add3_u32 v133, 0, v116, v135
	v_add_u32_e32 v116, 0x1400, v128
	v_ashrrev_i32_e32 v116, 4, v116
	v_lshlrev_b32_e32 v116, 3, v116
	v_add3_u32 v132, 0, v116, v135
	v_add_u32_e32 v116, 0x1600, v128
	v_ashrrev_i32_e32 v116, 4, v116
	v_lshlrev_b32_e32 v116, 3, v116
	v_add3_u32 v131, 0, v116, v135
	v_add_u32_e32 v116, 0x1800, v128
	v_ashrrev_i32_e32 v116, 4, v116
	v_lshlrev_b32_e32 v116, 3, v116
	v_add3_u32 v130, 0, v116, v135
	v_add_u32_e32 v116, 0x1a00, v128
	v_ashrrev_i32_e32 v116, 4, v116
	v_lshlrev_b32_e32 v116, 3, v116
	v_add3_u32 v129, 0, v116, v135
	v_add_u32_e32 v116, 0x1c00, v128
	v_ashrrev_i32_e32 v116, 4, v116
	v_lshlrev_b32_e32 v116, 3, v116
	v_add3_u32 v117, 0, v116, v135
	v_add_u32_e32 v116, 0x1e00, v128
	v_ashrrev_i32_e32 v116, 4, v116
	s_waitcnt lgkmcnt(0)
	s_barrier
	v_lshlrev_b32_e32 v116, 3, v116
	v_add3_u32 v116, 0, v116, v135
	s_and_saveexec_b64 s[6:7], vcc
	s_cbranch_execz .LBB0_1607
	ds_read_b64 v[172:173], v136
	ds_read_b64 v[174:175], v124 offset:4096
	ds_read_b64 v[176:177], v122 offset:8192
	ds_read_b64 v[178:179], v65 offset:12288
	ds_read_b64 v[180:181], v31 offset:16384
	ds_read_b64 v[182:183], v23 offset:20480
	ds_read_b64 v[184:185], v15 offset:24576
	ds_read_b64 v[186:187], v11 offset:28672
	ds_read_b64 v[188:189], v134 offset:32768
	ds_read_b64 v[190:191], v133 offset:36864
	ds_read_b64 v[192:193], v132 offset:40960
	ds_read_b64 v[194:195], v131 offset:45056
	ds_read_b64 v[196:197], v130 offset:49152
	ds_read_b64 v[198:199], v129 offset:53248
	ds_read_b64 v[200:201], v117 offset:57344
	v_and_b32_e32 v108, 15, v128
	v_cvt_f32_ubyte0_e32 v108, v108
	v_mul_f32_e32 v109, 0x3b800000, v108
	v_cos_f32_e32 v108, v109
	v_sin_f32_e32 v110, v109
	s_waitcnt lgkmcnt(14)
	ds_read_b64 v[202:203], v116 offset:61440
	v_mov_b32_e32 v111, v108
	v_xor_b32_e32 v109, 0x80000000, v110
	v_pk_mul_f32 v[142:143], v[110:111], v[110:111] op_sel_hi:[1,0] neg_lo:[0,1] neg_hi:[0,1]
	s_mov_b32 s29, s26
	v_pk_fma_f32 v[142:143], v[108:109], v[108:109], v[142:143] op_sel_hi:[1,0,1]
	s_mov_b32 s8, s26
	v_pk_mul_f32 v[144:145], v[110:111], v[142:143] op_sel:[0,1]
	s_mov_b32 s9, s28
	v_pk_fma_f32 v[144:145], v[108:109], v[142:143], v[144:145] op_sel_hi:[1,0,1]
	s_mov_b32 s37, s20
	v_pk_mul_f32 v[146:147], v[110:111], v[144:145] op_sel:[0,1]
	s_mov_b32 s10, s27
	v_pk_fma_f32 v[146:147], v[108:109], v[144:145], v[146:147] op_sel_hi:[1,0,1]
	s_mov_b32 s11, s34
	v_pk_mul_f32 v[148:149], v[110:111], v[146:147] op_sel:[0,1]
	s_mov_b32 s35, s28
	v_pk_fma_f32 v[148:149], v[108:109], v[146:147], v[148:149] op_sel_hi:[1,0,1]
	s_nop 0
	v_pk_mul_f32 v[150:151], v[110:111], v[148:149] op_sel:[0,1]
	s_nop 0
	v_pk_fma_f32 v[150:151], v[108:109], v[148:149], v[150:151] op_sel_hi:[1,0,1]
	s_nop 0
	v_pk_mul_f32 v[152:153], v[110:111], v[150:151] op_sel:[0,1]
	s_nop 0
	v_pk_fma_f32 v[152:153], v[108:109], v[150:151], v[152:153] op_sel_hi:[1,0,1]
	s_nop 0
	v_pk_mul_f32 v[154:155], v[110:111], v[152:153] op_sel:[0,1]
	s_nop 0
	v_pk_fma_f32 v[154:155], v[108:109], v[152:153], v[154:155] op_sel_hi:[1,0,1]
	s_nop 0
	v_pk_mul_f32 v[156:157], v[110:111], v[154:155] op_sel:[0,1]
	s_nop 0
	v_pk_fma_f32 v[156:157], v[108:109], v[154:155], v[156:157] op_sel_hi:[1,0,1]
	s_nop 0
	v_pk_mul_f32 v[158:159], v[110:111], v[156:157] op_sel:[0,1]
	s_nop 0
	v_pk_fma_f32 v[158:159], v[108:109], v[156:157], v[158:159] op_sel_hi:[1,0,1]
	s_nop 0
	v_pk_mul_f32 v[160:161], v[110:111], v[158:159] op_sel:[0,1]
	s_nop 0
	v_pk_fma_f32 v[160:161], v[108:109], v[158:159], v[160:161] op_sel_hi:[1,0,1]
	s_nop 0
	v_pk_mul_f32 v[162:163], v[110:111], v[160:161] op_sel:[0,1]
	s_nop 0
	v_pk_fma_f32 v[162:163], v[108:109], v[160:161], v[162:163] op_sel_hi:[1,0,1]
	s_nop 0
	v_pk_mul_f32 v[164:165], v[110:111], v[162:163] op_sel:[0,1]
	s_nop 0
	v_pk_fma_f32 v[164:165], v[108:109], v[162:163], v[164:165] op_sel_hi:[1,0,1]
	s_nop 0
	v_pk_mul_f32 v[166:167], v[110:111], v[164:165] op_sel:[0,1]
	s_nop 0
	v_pk_fma_f32 v[166:167], v[108:109], v[164:165], v[166:167] op_sel_hi:[1,0,1]
	s_nop 0
	v_pk_mul_f32 v[168:169], v[110:111], v[166:167] op_sel:[0,1]
	s_waitcnt lgkmcnt(14)
	v_pk_mul_f32 v[110:111], v[110:111], v[174:175] op_sel:[0,1]
	v_pk_fma_f32 v[168:169], v[108:109], v[166:167], v[168:169] op_sel_hi:[1,0,1]
	v_pk_fma_f32 v[86:87], v[108:109], v[174:175], v[110:111] op_sel_hi:[1,0,1]
	v_xor_b32_e32 v170, 0x80000000, v169
	v_mov_b32_e32 v171, v168
	s_waitcnt lgkmcnt(0)
	v_pk_mul_f32 v[170:171], v[170:171], v[202:203] op_sel:[0,1]
	s_nop 0
	v_pk_fma_f32 v[140:141], v[168:169], v[202:203], v[170:171] op_sel_hi:[1,0,1]
	v_xor_b32_e32 v168, 0x80000000, v167
	v_mov_b32_e32 v169, v166
	v_pk_mul_f32 v[168:169], v[168:169], v[200:201] op_sel:[0,1]
	s_nop 0
	v_pk_fma_f32 v[138:139], v[166:167], v[200:201], v[168:169] op_sel_hi:[1,0,1]
	v_xor_b32_e32 v166, 0x80000000, v165
	v_mov_b32_e32 v167, v164
	v_pk_mul_f32 v[166:167], v[166:167], v[198:199] op_sel:[0,1]
	s_nop 0
	v_pk_fma_f32 v[114:115], v[164:165], v[198:199], v[166:167] op_sel_hi:[1,0,1]
	v_xor_b32_e32 v164, 0x80000000, v163
	v_mov_b32_e32 v165, v162
	v_pk_mul_f32 v[164:165], v[164:165], v[196:197] op_sel:[0,1]
	s_nop 0
	v_pk_fma_f32 v[112:113], v[162:163], v[196:197], v[164:165] op_sel_hi:[1,0,1]
	v_xor_b32_e32 v162, 0x80000000, v161
	v_mov_b32_e32 v163, v160
	v_pk_mul_f32 v[162:163], v[162:163], v[194:195] op_sel:[0,1]
	s_nop 0
	v_pk_fma_f32 v[106:107], v[160:161], v[194:195], v[162:163] op_sel_hi:[1,0,1]
	v_xor_b32_e32 v160, 0x80000000, v159
	v_mov_b32_e32 v161, v158
	v_pk_mul_f32 v[160:161], v[160:161], v[192:193] op_sel:[0,1]
	s_nop 0
	v_pk_fma_f32 v[104:105], v[158:159], v[192:193], v[160:161] op_sel_hi:[1,0,1]
	v_xor_b32_e32 v158, 0x80000000, v157
	v_mov_b32_e32 v159, v156
	v_pk_mul_f32 v[158:159], v[158:159], v[190:191] op_sel:[0,1]
	s_nop 0
	v_pk_fma_f32 v[102:103], v[156:157], v[190:191], v[158:159] op_sel_hi:[1,0,1]
	v_xor_b32_e32 v156, 0x80000000, v155
	v_mov_b32_e32 v157, v154
	v_pk_mul_f32 v[156:157], v[156:157], v[188:189] op_sel:[0,1]
	s_nop 0
	v_pk_fma_f32 v[100:101], v[154:155], v[188:189], v[156:157] op_sel_hi:[1,0,1]
	v_xor_b32_e32 v154, 0x80000000, v153
	v_mov_b32_e32 v155, v152
	v_pk_mul_f32 v[154:155], v[154:155], v[186:187] op_sel:[0,1]
	v_pk_add_f32 v[108:109], v[172:173], v[100:101]
	v_pk_fma_f32 v[98:99], v[152:153], v[186:187], v[154:155] op_sel_hi:[1,0,1]
	v_xor_b32_e32 v152, 0x80000000, v151
	v_mov_b32_e32 v153, v150
	v_pk_mul_f32 v[152:153], v[152:153], v[184:185] op_sel:[0,1]
	v_pk_add_f32 v[110:111], v[172:173], v[100:101] neg_lo:[0,1] neg_hi:[0,1]
	v_pk_fma_f32 v[96:97], v[150:151], v[184:185], v[152:153] op_sel_hi:[1,0,1]
	v_xor_b32_e32 v150, 0x80000000, v149
	v_mov_b32_e32 v151, v148
	v_pk_mul_f32 v[150:151], v[150:151], v[182:183] op_sel:[0,1]
	s_nop 0
	v_pk_fma_f32 v[94:95], v[148:149], v[182:183], v[150:151] op_sel_hi:[1,0,1]
	v_xor_b32_e32 v148, 0x80000000, v147
	v_mov_b32_e32 v149, v146
	v_pk_mul_f32 v[148:149], v[148:149], v[180:181] op_sel:[0,1]
	s_nop 0
	v_pk_fma_f32 v[92:93], v[146:147], v[180:181], v[148:149] op_sel_hi:[1,0,1]
	v_xor_b32_e32 v146, 0x80000000, v145
	v_mov_b32_e32 v147, v144
	v_pk_mul_f32 v[146:147], v[146:147], v[178:179] op_sel:[0,1]
	v_pk_add_f32 v[84:85], v[92:93], v[112:113]
	v_pk_fma_f32 v[90:91], v[144:145], v[178:179], v[146:147] op_sel_hi:[1,0,1]
	v_xor_b32_e32 v144, 0x80000000, v143
	v_mov_b32_e32 v145, v142
	v_pk_mul_f32 v[144:145], v[144:145], v[176:177] op_sel:[0,1]
	v_pk_add_f32 v[100:101], v[108:109], v[84:85]
	v_pk_fma_f32 v[88:89], v[142:143], v[176:177], v[144:145] op_sel_hi:[1,0,1]
	v_pk_add_f32 v[108:109], v[108:109], v[84:85] neg_lo:[0,1] neg_hi:[0,1]
	v_pk_add_f32 v[84:85], v[86:87], v[102:103]
	v_pk_add_f32 v[142:143], v[86:87], v[102:103] neg_lo:[0,1] neg_hi:[0,1]
	v_pk_add_f32 v[86:87], v[94:95], v[114:115]
	v_pk_add_f32 v[94:95], v[94:95], v[114:115] neg_lo:[0,1] neg_hi:[0,1]
	v_pk_add_f32 v[102:103], v[84:85], v[86:87]
	v_pk_add_f32 v[114:115], v[84:85], v[86:87] neg_lo:[0,1] neg_hi:[0,1]
	v_pk_add_f32 v[84:85], v[88:89], v[104:105]
	v_pk_add_f32 v[86:87], v[96:97], v[138:139]
	v_pk_add_f32 v[146:147], v[88:89], v[104:105] neg_lo:[0,1] neg_hi:[0,1]
	v_pk_add_f32 v[88:89], v[96:97], v[138:139] neg_lo:[0,1] neg_hi:[0,1]
	v_pk_add_f32 v[96:97], v[84:85], v[86:87]
	v_pk_add_f32 v[104:105], v[84:85], v[86:87] neg_lo:[0,1] neg_hi:[0,1]
	v_pk_add_f32 v[84:85], v[90:91], v[106:107]
	v_pk_add_f32 v[86:87], v[98:99], v[140:141]
	v_xor_b32_e32 v139, 0x80000000, v88
	v_mov_b32_e32 v138, v89
	v_pk_add_f32 v[150:151], v[90:91], v[106:107] neg_lo:[0,1] neg_hi:[0,1]
	v_pk_add_f32 v[88:89], v[98:99], v[140:141] neg_lo:[0,1] neg_hi:[0,1]
	v_pk_add_f32 v[90:91], v[84:85], v[86:87]
	v_xor_b32_e32 v145, 0x80000000, v94
	v_mov_b32_e32 v144, v95
	v_pk_add_f32 v[106:107], v[84:85], v[86:87] neg_lo:[0,1] neg_hi:[0,1]
	v_xor_b32_e32 v141, 0x80000000, v88
	v_mov_b32_e32 v140, v89
	v_pk_add_f32 v[84:85], v[100:101], v[96:97]
	v_pk_add_f32 v[86:87], v[102:103], v[90:91]
	v_pk_add_f32 v[88:89], v[102:103], v[90:91] neg_lo:[0,1] neg_hi:[0,1]
	v_pk_add_f32 v[94:95], v[142:143], v[144:145]
	v_pk_add_f32 v[96:97], v[100:101], v[96:97] neg_lo:[0,1] neg_hi:[0,1]
	v_pk_add_f32 v[90:91], v[84:85], v[86:87]
	v_pk_add_f32 v[86:87], v[84:85], v[86:87] neg_lo:[0,1] neg_hi:[0,1]
	v_xor_b32_e32 v85, 0x80000000, v88
	v_mov_b32_e32 v84, v89
	v_pk_add_f32 v[92:93], v[92:93], v[112:113] neg_lo:[0,1] neg_hi:[0,1]
	v_pk_add_f32 v[148:149], v[146:147], v[138:139]
	v_pk_add_f32 v[98:99], v[150:151], v[140:141]
	v_pk_add_f32 v[88:89], v[96:97], v[84:85]
	v_pk_add_f32 v[84:85], v[96:97], v[84:85] neg_lo:[0,1] neg_hi:[0,1]
	v_pk_mul_f32 v[96:97], v[94:95], s[28:29] op_sel:[1,0]
	v_xor_b32_e32 v113, 0x80000000, v92
	v_mov_b32_e32 v112, v93
	v_pk_fma_f32 v[94:95], v[94:95], s[26:27], v[96:97] op_sel_hi:[0,1,1]
	v_mul_f32_e32 v96, 0x3f3504f3, v149
	s_mov_b32 s29, s34
	v_pk_mul_f32 v[100:101], v[98:99], s[8:9] op_sel:[1,0]
	v_pk_add_f32 v[92:93], v[110:111], v[112:113]
	v_pk_fma_f32 v[96:97], v[148:149], s[30:31], v[96:97] op_sel_hi:[0,1,0]
	v_pk_fma_f32 v[98:99], v[98:99], s[28:29], v[100:101] op_sel_hi:[0,1,1]
	v_pk_add_f32 v[100:101], v[92:93], v[96:97]
	v_pk_add_f32 v[92:93], v[92:93], v[96:97] neg_lo:[0,1] neg_hi:[0,1]
	v_pk_add_f32 v[96:97], v[94:95], v[98:99]
	v_pk_add_f32 v[102:103], v[94:95], v[98:99] neg_lo:[0,1] neg_hi:[0,1]
	v_pk_add_f32 v[98:99], v[100:101], v[96:97]
	v_pk_add_f32 v[94:95], v[100:101], v[96:97] neg_lo:[0,1] neg_hi:[0,1]
	v_xor_b32_e32 v101, 0x80000000, v102
	v_mov_b32_e32 v100, v103
	v_pk_mul_f32 v[102:103], v[104:105], s[36:37] op_sel:[1,0]
	v_pk_add_f32 v[96:97], v[92:93], v[100:101]
	v_pk_add_f32 v[92:93], v[92:93], v[100:101] neg_lo:[0,1] neg_hi:[0,1]
	v_mul_f32_e32 v100, 0x3f3504f3, v115
	v_pk_fma_f32 v[102:103], v[104:105], s[20:21], v[102:103] op_sel_hi:[0,1,1]
	v_mul_f32_e32 v104, 0xbf3504f3, v106
	v_pk_fma_f32 v[100:101], v[114:115], s[30:31], v[100:101] op_sel_hi:[0,1,0]
	v_pk_fma_f32 v[104:105], v[106:107], s[30:31], v[104:105] op_sel:[1,0,0] op_sel_hi:[1,1,0]
	v_pk_add_f32 v[114:115], v[108:109], v[102:103]
	v_pk_add_f32 v[108:109], v[108:109], v[102:103] neg_lo:[0,1] neg_hi:[0,1]
	v_pk_add_f32 v[102:103], v[100:101], v[104:105]
	v_pk_add_f32 v[100:101], v[100:101], v[104:105] neg_lo:[0,1] neg_hi:[0,1]
	v_pk_add_f32 v[106:107], v[114:115], v[102:103]
	v_pk_add_f32 v[102:103], v[114:115], v[102:103] neg_lo:[0,1] neg_hi:[0,1]
	v_xor_b32_e32 v115, 0x80000000, v100
	v_mov_b32_e32 v114, v101
	v_pk_add_f32 v[104:105], v[108:109], v[114:115]
	v_pk_add_f32 v[100:101], v[108:109], v[114:115] neg_lo:[0,1] neg_hi:[0,1]
	v_pk_add_f32 v[108:109], v[150:151], v[140:141] neg_lo:[0,1] neg_hi:[0,1]
	v_pk_add_f32 v[110:111], v[110:111], v[112:113] neg_lo:[0,1] neg_hi:[0,1]
	v_pk_mul_f32 v[114:115], v[108:109], s[10:11] op_sel:[1,0]
	v_pk_add_f32 v[112:113], v[142:143], v[144:145] neg_lo:[0,1] neg_hi:[0,1]
	v_pk_fma_f32 v[108:109], v[108:109], s[34:35], v[114:115] op_sel_hi:[0,1,1]
	v_pk_mul_f32 v[114:115], v[112:113], s[8:9] op_sel:[1,0]
	s_nop 0
	v_pk_fma_f32 v[112:113], v[112:113], s[28:29], v[114:115] op_sel_hi:[0,1,1]
	v_pk_add_f32 v[114:115], v[146:147], v[138:139] neg_lo:[0,1] neg_hi:[0,1]
	v_pk_add_f32 v[140:141], v[112:113], v[108:109] neg_lo:[0,1] neg_hi:[0,1]
	v_mul_f32_e32 v138, 0xbf3504f3, v114
	v_pk_fma_f32 v[114:115], v[114:115], s[30:31], v[138:139] op_sel:[1,0,0] op_sel_hi:[1,1,0]
	s_nop 0
	v_pk_add_f32 v[138:139], v[110:111], v[114:115]
	v_pk_add_f32 v[114:115], v[110:111], v[114:115] neg_lo:[0,1] neg_hi:[0,1]
	v_pk_add_f32 v[110:111], v[112:113], v[108:109]
	s_nop 0
	v_pk_add_f32 v[112:113], v[138:139], v[110:111]
	v_pk_add_f32 v[108:109], v[138:139], v[110:111] neg_lo:[0,1] neg_hi:[0,1]
	v_xor_b32_e32 v139, 0x80000000, v140
	v_mov_b32_e32 v138, v141
	v_pk_add_f32 v[110:111], v[114:115], v[138:139]
	v_pk_add_f32 v[114:115], v[114:115], v[138:139] neg_lo:[0,1] neg_hi:[0,1]

.LBB0_1609:
	s_or_b64 exec, exec, s[6:7]
	s_waitcnt lgkmcnt(0)
	s_barrier
	s_and_saveexec_b64 s[6:7], vcc
	s_cbranch_execz .LBB0_1611
	ds_read_b64 v[172:173], v136
	ds_read_b64 v[174:175], v124 offset:4096
	ds_read_b64 v[176:177], v122 offset:8192
	ds_read_b64 v[178:179], v65 offset:12288
	ds_read_b64 v[180:181], v31 offset:16384
	ds_read_b64 v[182:183], v23 offset:20480
	ds_read_b64 v[184:185], v15 offset:24576
	ds_read_b64 v[186:187], v11 offset:28672
	ds_read_b64 v[188:189], v134 offset:32768
	ds_read_b64 v[190:191], v133 offset:36864
	ds_read_b64 v[192:193], v132 offset:40960
	ds_read_b64 v[194:195], v131 offset:45056
	ds_read_b64 v[196:197], v130 offset:49152
	ds_read_b64 v[198:199], v129 offset:53248
	ds_read_b64 v[200:201], v117 offset:57344
	v_cvt_f32_ubyte0_e32 v108, v128
	v_mul_f32_e32 v109, 0x39800000, v108
	v_cos_f32_e32 v108, v109
	v_sin_f32_e32 v110, v109
	s_waitcnt lgkmcnt(14)
	ds_read_b64 v[202:203], v116 offset:61440
	v_mov_b32_e32 v111, v108
	v_xor_b32_e32 v109, 0x80000000, v110
	v_pk_mul_f32 v[142:143], v[110:111], v[110:111] op_sel_hi:[1,0] neg_lo:[0,1] neg_hi:[0,1]
	s_mov_b32 s29, s26
	v_pk_fma_f32 v[142:143], v[108:109], v[108:109], v[142:143] op_sel_hi:[1,0,1]
	s_mov_b32 s8, s26
	v_pk_mul_f32 v[144:145], v[110:111], v[142:143] op_sel:[0,1]
	s_mov_b32 s9, s28
	v_pk_fma_f32 v[144:145], v[108:109], v[142:143], v[144:145] op_sel_hi:[1,0,1]
	s_mov_b32 s37, s20
	v_pk_mul_f32 v[146:147], v[110:111], v[144:145] op_sel:[0,1]
	s_mov_b32 s10, s27
	v_pk_fma_f32 v[146:147], v[108:109], v[144:145], v[146:147] op_sel_hi:[1,0,1]
	s_mov_b32 s11, s34
	v_pk_mul_f32 v[148:149], v[110:111], v[146:147] op_sel:[0,1]
	s_mov_b32 s35, s28
	v_pk_fma_f32 v[148:149], v[108:109], v[146:147], v[148:149] op_sel_hi:[1,0,1]
	s_nop 0
	v_pk_mul_f32 v[150:151], v[110:111], v[148:149] op_sel:[0,1]
	s_nop 0
	v_pk_fma_f32 v[150:151], v[108:109], v[148:149], v[150:151] op_sel_hi:[1,0,1]
	s_nop 0
	v_pk_mul_f32 v[152:153], v[110:111], v[150:151] op_sel:[0,1]
	s_nop 0
	v_pk_fma_f32 v[152:153], v[108:109], v[150:151], v[152:153] op_sel_hi:[1,0,1]
	s_nop 0
	v_pk_mul_f32 v[154:155], v[110:111], v[152:153] op_sel:[0,1]
	s_nop 0
	v_pk_fma_f32 v[154:155], v[108:109], v[152:153], v[154:155] op_sel_hi:[1,0,1]
	s_nop 0
	v_pk_mul_f32 v[156:157], v[110:111], v[154:155] op_sel:[0,1]
	s_nop 0
	v_pk_fma_f32 v[156:157], v[108:109], v[154:155], v[156:157] op_sel_hi:[1,0,1]
	s_nop 0
	v_pk_mul_f32 v[158:159], v[110:111], v[156:157] op_sel:[0,1]
	s_nop 0
	v_pk_fma_f32 v[158:159], v[108:109], v[156:157], v[158:159] op_sel_hi:[1,0,1]
	s_nop 0
	v_pk_mul_f32 v[160:161], v[110:111], v[158:159] op_sel:[0,1]
	s_nop 0
	v_pk_fma_f32 v[160:161], v[108:109], v[158:159], v[160:161] op_sel_hi:[1,0,1]
	s_nop 0
	v_pk_mul_f32 v[162:163], v[110:111], v[160:161] op_sel:[0,1]
	s_nop 0
	v_pk_fma_f32 v[162:163], v[108:109], v[160:161], v[162:163] op_sel_hi:[1,0,1]
	s_nop 0
	v_pk_mul_f32 v[164:165], v[110:111], v[162:163] op_sel:[0,1]
	s_nop 0
	v_pk_fma_f32 v[164:165], v[108:109], v[162:163], v[164:165] op_sel_hi:[1,0,1]
	s_nop 0
	v_pk_mul_f32 v[166:167], v[110:111], v[164:165] op_sel:[0,1]
	s_nop 0
	v_pk_fma_f32 v[166:167], v[108:109], v[164:165], v[166:167] op_sel_hi:[1,0,1]
	s_nop 0
	v_pk_mul_f32 v[168:169], v[110:111], v[166:167] op_sel:[0,1]
	s_waitcnt lgkmcnt(14)
	v_pk_mul_f32 v[110:111], v[110:111], v[174:175] op_sel:[0,1]
	v_pk_fma_f32 v[168:169], v[108:109], v[166:167], v[168:169] op_sel_hi:[1,0,1]
	v_pk_fma_f32 v[86:87], v[108:109], v[174:175], v[110:111] op_sel_hi:[1,0,1]
	v_xor_b32_e32 v170, 0x80000000, v169
	v_mov_b32_e32 v171, v168
	s_waitcnt lgkmcnt(0)
	v_pk_mul_f32 v[170:171], v[170:171], v[202:203] op_sel:[0,1]
	s_nop 0
	v_pk_fma_f32 v[140:141], v[168:169], v[202:203], v[170:171] op_sel_hi:[1,0,1]
	v_xor_b32_e32 v168, 0x80000000, v167
	v_mov_b32_e32 v169, v166
	v_pk_mul_f32 v[168:169], v[168:169], v[200:201] op_sel:[0,1]
	s_nop 0
	v_pk_fma_f32 v[138:139], v[166:167], v[200:201], v[168:169] op_sel_hi:[1,0,1]
	v_xor_b32_e32 v166, 0x80000000, v165
	v_mov_b32_e32 v167, v164
	v_pk_mul_f32 v[166:167], v[166:167], v[198:199] op_sel:[0,1]
	s_nop 0
	v_pk_fma_f32 v[114:115], v[164:165], v[198:199], v[166:167] op_sel_hi:[1,0,1]
	v_xor_b32_e32 v164, 0x80000000, v163
	v_mov_b32_e32 v165, v162
	v_pk_mul_f32 v[164:165], v[164:165], v[196:197] op_sel:[0,1]
	s_nop 0
	v_pk_fma_f32 v[112:113], v[162:163], v[196:197], v[164:165] op_sel_hi:[1,0,1]
	v_xor_b32_e32 v162, 0x80000000, v161
	v_mov_b32_e32 v163, v160
	v_pk_mul_f32 v[162:163], v[162:163], v[194:195] op_sel:[0,1]
	s_nop 0
	v_pk_fma_f32 v[106:107], v[160:161], v[194:195], v[162:163] op_sel_hi:[1,0,1]
	v_xor_b32_e32 v160, 0x80000000, v159
	v_mov_b32_e32 v161, v158
	v_pk_mul_f32 v[160:161], v[160:161], v[192:193] op_sel:[0,1]
	s_nop 0
	v_pk_fma_f32 v[104:105], v[158:159], v[192:193], v[160:161] op_sel_hi:[1,0,1]
	v_xor_b32_e32 v158, 0x80000000, v157
	v_mov_b32_e32 v159, v156
	v_pk_mul_f32 v[158:159], v[158:159], v[190:191] op_sel:[0,1]
	s_nop 0
	v_pk_fma_f32 v[102:103], v[156:157], v[190:191], v[158:159] op_sel_hi:[1,0,1]
	v_xor_b32_e32 v156, 0x80000000, v155
	v_mov_b32_e32 v157, v154
	v_pk_mul_f32 v[156:157], v[156:157], v[188:189] op_sel:[0,1]
	s_nop 0
	v_pk_fma_f32 v[100:101], v[154:155], v[188:189], v[156:157] op_sel_hi:[1,0,1]
	v_xor_b32_e32 v154, 0x80000000, v153
	v_mov_b32_e32 v155, v152
	v_pk_mul_f32 v[154:155], v[154:155], v[186:187] op_sel:[0,1]
	v_pk_add_f32 v[108:109], v[172:173], v[100:101]
	v_pk_fma_f32 v[98:99], v[152:153], v[186:187], v[154:155] op_sel_hi:[1,0,1]
	v_xor_b32_e32 v152, 0x80000000, v151
	v_mov_b32_e32 v153, v150
	v_pk_mul_f32 v[152:153], v[152:153], v[184:185] op_sel:[0,1]
	v_pk_add_f32 v[110:111], v[172:173], v[100:101] neg_lo:[0,1] neg_hi:[0,1]
	v_pk_fma_f32 v[96:97], v[150:151], v[184:185], v[152:153] op_sel_hi:[1,0,1]
	v_xor_b32_e32 v150, 0x80000000, v149
	v_mov_b32_e32 v151, v148
	v_pk_mul_f32 v[150:151], v[150:151], v[182:183] op_sel:[0,1]
	s_nop 0
	v_pk_fma_f32 v[94:95], v[148:149], v[182:183], v[150:151] op_sel_hi:[1,0,1]
	v_xor_b32_e32 v148, 0x80000000, v147
	v_mov_b32_e32 v149, v146
	v_pk_mul_f32 v[148:149], v[148:149], v[180:181] op_sel:[0,1]
	s_nop 0
	v_pk_fma_f32 v[92:93], v[146:147], v[180:181], v[148:149] op_sel_hi:[1,0,1]
	v_xor_b32_e32 v146, 0x80000000, v145
	v_mov_b32_e32 v147, v144
	v_pk_mul_f32 v[146:147], v[146:147], v[178:179] op_sel:[0,1]
	v_pk_add_f32 v[84:85], v[92:93], v[112:113]
	v_pk_fma_f32 v[90:91], v[144:145], v[178:179], v[146:147] op_sel_hi:[1,0,1]
	v_xor_b32_e32 v144, 0x80000000, v143
	v_mov_b32_e32 v145, v142
	v_pk_mul_f32 v[144:145], v[144:145], v[176:177] op_sel:[0,1]
	v_pk_add_f32 v[100:101], v[108:109], v[84:85]
	v_pk_fma_f32 v[88:89], v[142:143], v[176:177], v[144:145] op_sel_hi:[1,0,1]
	v_pk_add_f32 v[108:109], v[108:109], v[84:85] neg_lo:[0,1] neg_hi:[0,1]
	v_pk_add_f32 v[84:85], v[86:87], v[102:103]
	v_pk_add_f32 v[142:143], v[86:87], v[102:103] neg_lo:[0,1] neg_hi:[0,1]
	v_pk_add_f32 v[86:87], v[94:95], v[114:115]
	v_pk_add_f32 v[94:95], v[94:95], v[114:115] neg_lo:[0,1] neg_hi:[0,1]
	v_pk_add_f32 v[102:103], v[84:85], v[86:87]
	v_pk_add_f32 v[114:115], v[84:85], v[86:87] neg_lo:[0,1] neg_hi:[0,1]
	v_pk_add_f32 v[84:85], v[88:89], v[104:105]
	v_pk_add_f32 v[86:87], v[96:97], v[138:139]
	v_pk_add_f32 v[146:147], v[88:89], v[104:105] neg_lo:[0,1] neg_hi:[0,1]
	v_pk_add_f32 v[88:89], v[96:97], v[138:139] neg_lo:[0,1] neg_hi:[0,1]
	v_pk_add_f32 v[96:97], v[84:85], v[86:87]
	v_pk_add_f32 v[104:105], v[84:85], v[86:87] neg_lo:[0,1] neg_hi:[0,1]
	v_pk_add_f32 v[84:85], v[90:91], v[106:107]
	v_pk_add_f32 v[86:87], v[98:99], v[140:141]
	v_xor_b32_e32 v139, 0x80000000, v88
	v_mov_b32_e32 v138, v89
	v_pk_add_f32 v[150:151], v[90:91], v[106:107] neg_lo:[0,1] neg_hi:[0,1]
	v_pk_add_f32 v[88:89], v[98:99], v[140:141] neg_lo:[0,1] neg_hi:[0,1]
	v_pk_add_f32 v[90:91], v[84:85], v[86:87]
	v_xor_b32_e32 v145, 0x80000000, v94
	v_mov_b32_e32 v144, v95
	v_pk_add_f32 v[106:107], v[84:85], v[86:87] neg_lo:[0,1] neg_hi:[0,1]
	v_xor_b32_e32 v141, 0x80000000, v88
	v_mov_b32_e32 v140, v89
	v_pk_add_f32 v[84:85], v[100:101], v[96:97]
	v_pk_add_f32 v[86:87], v[102:103], v[90:91]
	v_pk_add_f32 v[88:89], v[102:103], v[90:91] neg_lo:[0,1] neg_hi:[0,1]
	v_pk_add_f32 v[94:95], v[142:143], v[144:145]
	v_pk_add_f32 v[96:97], v[100:101], v[96:97] neg_lo:[0,1] neg_hi:[0,1]
	v_pk_add_f32 v[90:91], v[84:85], v[86:87]
	v_pk_add_f32 v[86:87], v[84:85], v[86:87] neg_lo:[0,1] neg_hi:[0,1]
	v_xor_b32_e32 v85, 0x80000000, v88
	v_mov_b32_e32 v84, v89
	v_pk_add_f32 v[92:93], v[92:93], v[112:113] neg_lo:[0,1] neg_hi:[0,1]
	v_pk_add_f32 v[148:149], v[146:147], v[138:139]
	v_pk_add_f32 v[98:99], v[150:151], v[140:141]
	v_pk_add_f32 v[88:89], v[96:97], v[84:85]
	v_pk_add_f32 v[84:85], v[96:97], v[84:85] neg_lo:[0,1] neg_hi:[0,1]
	v_pk_mul_f32 v[96:97], v[94:95], s[28:29] op_sel:[1,0]
	v_xor_b32_e32 v113, 0x80000000, v92
	v_mov_b32_e32 v112, v93
	v_pk_fma_f32 v[94:95], v[94:95], s[26:27], v[96:97] op_sel_hi:[0,1,1]
	v_mul_f32_e32 v96, 0x3f3504f3, v149
	s_mov_b32 s29, s34
	v_pk_mul_f32 v[100:101], v[98:99], s[8:9] op_sel:[1,0]
	v_pk_add_f32 v[92:93], v[110:111], v[112:113]
	v_pk_fma_f32 v[96:97], v[148:149], s[30:31], v[96:97] op_sel_hi:[0,1,0]
	v_pk_fma_f32 v[98:99], v[98:99], s[28:29], v[100:101] op_sel_hi:[0,1,1]
	v_pk_add_f32 v[100:101], v[92:93], v[96:97]
	v_pk_add_f32 v[92:93], v[92:93], v[96:97] neg_lo:[0,1] neg_hi:[0,1]
	v_pk_add_f32 v[96:97], v[94:95], v[98:99]
	v_pk_add_f32 v[102:103], v[94:95], v[98:99] neg_lo:[0,1] neg_hi:[0,1]
	v_pk_add_f32 v[98:99], v[100:101], v[96:97]
	v_pk_add_f32 v[94:95], v[100:101], v[96:97] neg_lo:[0,1] neg_hi:[0,1]
	v_xor_b32_e32 v101, 0x80000000, v102
	v_mov_b32_e32 v100, v103
	v_pk_mul_f32 v[102:103], v[104:105], s[36:37] op_sel:[1,0]
	v_pk_add_f32 v[96:97], v[92:93], v[100:101]
	v_pk_add_f32 v[92:93], v[92:93], v[100:101] neg_lo:[0,1] neg_hi:[0,1]
	v_mul_f32_e32 v100, 0x3f3504f3, v115
	v_pk_fma_f32 v[102:103], v[104:105], s[20:21], v[102:103] op_sel_hi:[0,1,1]
	v_mul_f32_e32 v104, 0xbf3504f3, v106
	v_pk_fma_f32 v[100:101], v[114:115], s[30:31], v[100:101] op_sel_hi:[0,1,0]
	v_pk_fma_f32 v[104:105], v[106:107], s[30:31], v[104:105] op_sel:[1,0,0] op_sel_hi:[1,1,0]
	v_pk_add_f32 v[114:115], v[108:109], v[102:103]
	v_pk_add_f32 v[108:109], v[108:109], v[102:103] neg_lo:[0,1] neg_hi:[0,1]
	v_pk_add_f32 v[102:103], v[100:101], v[104:105]
	v_pk_add_f32 v[100:101], v[100:101], v[104:105] neg_lo:[0,1] neg_hi:[0,1]
	v_pk_add_f32 v[106:107], v[114:115], v[102:103]
	v_pk_add_f32 v[102:103], v[114:115], v[102:103] neg_lo:[0,1] neg_hi:[0,1]
	v_xor_b32_e32 v115, 0x80000000, v100
	v_mov_b32_e32 v114, v101
	v_pk_add_f32 v[104:105], v[108:109], v[114:115]
	v_pk_add_f32 v[100:101], v[108:109], v[114:115] neg_lo:[0,1] neg_hi:[0,1]
	v_pk_add_f32 v[108:109], v[150:151], v[140:141] neg_lo:[0,1] neg_hi:[0,1]
	v_pk_add_f32 v[110:111], v[110:111], v[112:113] neg_lo:[0,1] neg_hi:[0,1]
	v_pk_mul_f32 v[114:115], v[108:109], s[10:11] op_sel:[1,0]
	v_pk_add_f32 v[112:113], v[142:143], v[144:145] neg_lo:[0,1] neg_hi:[0,1]
	v_pk_fma_f32 v[108:109], v[108:109], s[34:35], v[114:115] op_sel_hi:[0,1,1]
	v_pk_mul_f32 v[114:115], v[112:113], s[8:9] op_sel:[1,0]
	s_nop 0
	v_pk_fma_f32 v[112:113], v[112:113], s[28:29], v[114:115] op_sel_hi:[0,1,1]
	v_pk_add_f32 v[114:115], v[146:147], v[138:139] neg_lo:[0,1] neg_hi:[0,1]
	v_pk_add_f32 v[140:141], v[112:113], v[108:109] neg_lo:[0,1] neg_hi:[0,1]
	v_mul_f32_e32 v136, 0xbf3504f3, v114
	v_pk_fma_f32 v[114:115], v[114:115], s[30:31], v[136:137] op_sel:[1,0,0] op_sel_hi:[1,1,0]
	s_nop 0
	v_pk_add_f32 v[138:139], v[110:111], v[114:115]
	v_pk_add_f32 v[114:115], v[110:111], v[114:115] neg_lo:[0,1] neg_hi:[0,1]
	v_pk_add_f32 v[110:111], v[112:113], v[108:109]
	s_nop 0
	v_pk_add_f32 v[112:113], v[138:139], v[110:111]
	v_pk_add_f32 v[108:109], v[138:139], v[110:111] neg_lo:[0,1] neg_hi:[0,1]
	v_xor_b32_e32 v139, 0x80000000, v140
	v_mov_b32_e32 v138, v141
	v_pk_add_f32 v[110:111], v[114:115], v[138:139]
	v_pk_add_f32 v[114:115], v[114:115], v[138:139] neg_lo:[0,1] neg_hi:[0,1]

.LBB0_1613:
	s_or_b64 exec, exec, s[6:7]
	s_waitcnt lgkmcnt(0)
	s_barrier
	s_and_saveexec_b64 s[6:7], vcc
	s_cbranch_execz .LBB0_1615
	ds_read_b64 v[172:173], v134 offset:32768
	v_cvt_f32_i32_e32 v86, v128
	v_lshlrev_b32_e32 v87, 3, v127
	v_add3_u32 v92, 0, v87, v135
	ds_read_b64 v[174:175], v92
	v_mul_f32_e32 v88, 0x39000000, v86
	v_sin_f32_e32 v86, v88
	v_cos_f32_e32 v88, v88
	v_cvt_f32_i32_e32 v67, v67
	v_xor_b32_e32 v89, 0x80000000, v86
	v_mov_b32_e32 v87, v88
	s_waitcnt lgkmcnt(1)
	v_pk_mul_f32 v[86:87], v[86:87], v[172:173] op_sel:[0,1]
	v_cvt_f32_i32_e32 v63, v63
	v_pk_fma_f32 v[84:85], v[88:89], v[172:173], v[86:87] op_sel_hi:[1,0,1]
	v_cvt_f32_i32_e32 v88, v126
	s_waitcnt lgkmcnt(0)
	v_pk_add_f32 v[86:87], v[174:175], v[84:85]
	v_pk_add_f32 v[84:85], v[174:175], v[84:85] neg_lo:[0,1] neg_hi:[0,1]
	ds_write_b64 v92, v[86:87]
	ds_write_b64 v134, v[84:85] offset:32768
	ds_read_b64 v[172:173], v133 offset:36864
	ds_read_b64 v[174:175], v124 offset:4096
	v_mul_f32_e32 v85, 0x39000000, v88
	v_cos_f32_e32 v84, v85
	v_sin_f32_e32 v86, v85
	v_cvt_f32_i32_e32 v27, v27
	v_mov_b32_e32 v87, v84
	v_xor_b32_e32 v85, 0x80000000, v86
	s_waitcnt lgkmcnt(1)
	v_pk_mul_f32 v[86:87], v[86:87], v[172:173] op_sel:[0,1]
	v_cvt_f32_i32_e32 v19, v19
	v_pk_fma_f32 v[84:85], v[84:85], v[172:173], v[86:87] op_sel_hi:[1,0,1]
	v_cvt_f32_i32_e32 v88, v125
	s_waitcnt lgkmcnt(0)
	v_pk_add_f32 v[86:87], v[174:175], v[84:85]
	v_pk_add_f32 v[84:85], v[174:175], v[84:85] neg_lo:[0,1] neg_hi:[0,1]
	ds_write_b64 v124, v[86:87] offset:4096
	ds_write_b64 v133, v[84:85] offset:36864
	ds_read_b64 v[172:173], v132 offset:40960
	ds_read_b64 v[174:175], v122 offset:8192
	v_mul_f32_e32 v85, 0x39000000, v88
	v_cos_f32_e32 v84, v85
	v_sin_f32_e32 v86, v85
	v_mov_b32_e32 v87, v84
	v_xor_b32_e32 v85, 0x80000000, v86
	s_waitcnt lgkmcnt(1)
	v_pk_mul_f32 v[86:87], v[86:87], v[172:173] op_sel:[0,1]
	s_nop 0
	v_pk_fma_f32 v[84:85], v[84:85], v[172:173], v[86:87] op_sel_hi:[1,0,1]
	v_cvt_f32_i32_e32 v88, v123
	s_waitcnt lgkmcnt(0)
	v_pk_add_f32 v[86:87], v[174:175], v[84:85]
	v_pk_add_f32 v[84:85], v[174:175], v[84:85] neg_lo:[0,1] neg_hi:[0,1]
	ds_write_b64 v122, v[86:87] offset:8192
	ds_write_b64 v132, v[84:85] offset:40960
	ds_read_b64 v[172:173], v131 offset:45056
	ds_read_b64 v[174:175], v65 offset:12288
	v_mul_f32_e32 v85, 0x39000000, v88
	v_cos_f32_e32 v84, v85
	v_sin_f32_e32 v86, v85
	v_mov_b32_e32 v87, v84
	v_xor_b32_e32 v85, 0x80000000, v86
	s_waitcnt lgkmcnt(1)
	v_pk_mul_f32 v[86:87], v[86:87], v[172:173] op_sel:[0,1]
	s_nop 0
	v_pk_fma_f32 v[84:85], v[84:85], v[172:173], v[86:87] op_sel_hi:[1,0,1]
	s_waitcnt lgkmcnt(0)
	v_pk_add_f32 v[86:87], v[174:175], v[84:85]
	ds_write_b64 v65, v[86:87] offset:12288
	v_pk_add_f32 v[84:85], v[174:175], v[84:85] neg_lo:[0,1] neg_hi:[0,1]
	v_mul_f32_e32 v65, 0x39000000, v67
	ds_write_b64 v131, v[84:85] offset:45056
	ds_read_b64 v[172:173], v130 offset:49152
	ds_read_b64 v[174:175], v31 offset:16384
	v_cos_f32_e32 v84, v65
	v_sin_f32_e32 v86, v65
	v_mov_b32_e32 v87, v84
	v_xor_b32_e32 v85, 0x80000000, v86
	s_waitcnt lgkmcnt(1)
	v_pk_mul_f32 v[86:87], v[86:87], v[172:173] op_sel:[0,1]
	s_nop 0
	v_pk_fma_f32 v[84:85], v[84:85], v[172:173], v[86:87] op_sel_hi:[1,0,1]
	s_waitcnt lgkmcnt(0)
	v_pk_add_f32 v[86:87], v[174:175], v[84:85]
	ds_write_b64 v31, v[86:87] offset:16384
	v_pk_add_f32 v[84:85], v[174:175], v[84:85] neg_lo:[0,1] neg_hi:[0,1]
	v_mul_f32_e32 v31, 0x39000000, v63
	ds_write_b64 v130, v[84:85] offset:49152
	ds_read_b64 v[172:173], v129 offset:53248
	ds_read_b64 v[174:175], v23 offset:20480
	v_cos_f32_e32 v84, v31
	v_sin_f32_e32 v86, v31
	v_mov_b32_e32 v87, v84
	v_xor_b32_e32 v85, 0x80000000, v86
	s_waitcnt lgkmcnt(1)
	v_pk_mul_f32 v[86:87], v[86:87], v[172:173] op_sel:[0,1]
	s_nop 0
	v_pk_fma_f32 v[84:85], v[84:85], v[172:173], v[86:87] op_sel_hi:[1,0,1]
	s_waitcnt lgkmcnt(0)
	v_pk_add_f32 v[86:87], v[174:175], v[84:85]
	ds_write_b64 v23, v[86:87] offset:20480
	v_pk_add_f32 v[84:85], v[174:175], v[84:85] neg_lo:[0,1] neg_hi:[0,1]
	v_mul_f32_e32 v23, 0x39000000, v27
	ds_write_b64 v129, v[84:85] offset:53248
	ds_read_b64 v[172:173], v117 offset:57344
	ds_read_b64 v[174:175], v15 offset:24576
	v_cos_f32_e32 v84, v23
	v_sin_f32_e32 v86, v23
	v_mov_b32_e32 v87, v84
	v_xor_b32_e32 v85, 0x80000000, v86
	s_waitcnt lgkmcnt(1)
	v_pk_mul_f32 v[86:87], v[86:87], v[172:173] op_sel:[0,1]
	s_nop 0
	v_pk_fma_f32 v[84:85], v[84:85], v[172:173], v[86:87] op_sel_hi:[1,0,1]
	s_waitcnt lgkmcnt(0)
	v_pk_add_f32 v[86:87], v[174:175], v[84:85]
	ds_write_b64 v15, v[86:87] offset:24576
	v_pk_add_f32 v[84:85], v[174:175], v[84:85] neg_lo:[0,1] neg_hi:[0,1]
	v_mul_f32_e32 v15, 0x39000000, v19
	ds_write_b64 v117, v[84:85] offset:57344
	v_cos_f32_e32 v84, v15
	v_sin_f32_e32 v86, v15
	ds_read_b64 v[88:89], v116 offset:61440
	ds_read_b64 v[90:91], v11 offset:28672
	v_mov_b32_e32 v87, v84
	v_xor_b32_e32 v85, 0x80000000, v86
	s_waitcnt lgkmcnt(1)
	v_pk_mul_f32 v[86:87], v[86:87], v[88:89] op_sel:[0,1]
	s_nop 0
	v_pk_fma_f32 v[84:85], v[84:85], v[88:89], v[86:87] op_sel_hi:[1,0,1]
	s_waitcnt lgkmcnt(0)
	v_pk_add_f32 v[86:87], v[90:91], v[84:85]
	v_pk_add_f32 v[84:85], v[90:91], v[84:85] neg_lo:[0,1] neg_hi:[0,1]
	ds_write_b64 v11, v[86:87] offset:28672
	ds_write_b64 v116, v[84:85] offset:61440

.LBB0_1617:
	v_ashrrev_i32_e32 v19, 4, v15
	v_add_lshl_u32 v19, v15, v19, 3
	v_add_u32_e32 v23, s3, v19
	ds_read_b64 v[172:173], v23
	v_and_b32_e32 v23, 0x1fff, v11
	v_lshrrev_b32_e32 v27, 1, v11
	v_and_b32_e32 v27, 0xff8, v27
	v_lshlrev_b32_e32 v23, 3, v23
	v_add3_u32 v23, s3, v27, v23
	ds_read_b64 v[174:175], v23
	v_add_u32_e32 v19, 0, v19
	v_cmp_lt_i32_e32 vcc, s22, v15
	v_add_u32_e32 v11, 0xfffffe00, v11
	s_or_b64 s[8:9], vcc, s[8:9]
	s_waitcnt lgkmcnt(0)
	v_pk_add_f32 v[90:91], v[172:173], v[174:175]
	v_pk_add_f32 v[86:87], v[172:173], v[174:175] neg_lo:[0,1] neg_hi:[0,1]
	ds_read_b64 v[88:89], v19
	v_mov_b32_e32 v91, v87
	v_pk_mul_f32 v[86:87], v[90:91], 0.5 op_sel_hi:[1,0]
	s_nop 0
	v_pk_mul_f32 v[86:87], v[84:85], v[86:87]
	s_nop 0
	v_xor_b32_e32 v90, 0x80000000, v87
	v_mov_b32_e32 v91, v86
	s_waitcnt lgkmcnt(0)
	v_pk_mul_f32 v[90:91], v[88:89], v[90:91] op_sel:[1,0]
	s_nop 0
	v_pk_fma_f32 v[86:87], v[88:89], v[86:87], v[90:91] op_sel_hi:[0,1,1]
	ds_write_b64 v19, v[86:87]
	v_add_u32_e32 v19, 0x200, v15
	v_mov_b32_e32 v15, v19
	s_andn2_b64 exec, exec, s[8:9]
	s_cbranch_execnz .LBB0_1617
.LBB0_1618:
	s_or_b64 exec, exec, s[6:7]
	v_mov_b32_e32 v132, v64
	s_waitcnt lgkmcnt(0)
	s_barrier
	v_mov_b32_e32 v116, 0
	v_add_u32_e32 v31, 0x1000, v132
	v_lshl_add_u32 v137, v132, 3, 0
	v_ashrrev_i32_e32 v31, 4, v31
	v_lshl_add_u32 v135, v31, 3, v137
	v_add_u32_e32 v31, 0x1200, v132
	v_ashrrev_i32_e32 v31, 4, v31
	v_lshl_add_u32 v134, v31, 3, v137
	v_add_u32_e32 v31, 0x1400, v132
	v_ashrrev_i32_e32 v31, 4, v31
	v_lshl_add_u32 v131, v31, 3, v137
	v_add_u32_e32 v31, 0x1600, v132
	v_ashrrev_i32_e32 v31, 4, v31
	v_add_u32_e32 v130, 0x200, v132
	v_lshl_add_u32 v129, v31, 3, v137
	v_add_u32_e32 v31, 0x1800, v132
	v_ashrrev_i32_e32 v11, 4, v130
	v_add_u32_e32 v128, 0x400, v132
	v_ashrrev_i32_e32 v31, 4, v31
	v_lshl_add_u32 v127, v11, 3, v137
	v_ashrrev_i32_e32 v11, 4, v128
	v_add_u32_e32 v125, 0x600, v132
	v_lshl_add_u32 v126, v31, 3, v137
	v_add_u32_e32 v31, 0x1a00, v132
	v_lshl_add_u32 v124, v11, 3, v137
	v_ashrrev_i32_e32 v11, 4, v125
	v_add_u32_e32 v122, 0x800, v132
	v_ashrrev_i32_e32 v31, 4, v31
	v_lshl_add_u32 v67, v11, 3, v137
	v_ashrrev_i32_e32 v11, 4, v122
	v_add_u32_e32 v63, 0xa00, v132
	v_lshl_add_u32 v123, v31, 3, v137
	v_add_u32_e32 v31, 0x1c00, v132
	v_lshl_add_u32 v59, v11, 3, v137
	v_ashrrev_i32_e32 v11, 4, v63
	v_add_u32_e32 v27, 0xc00, v132
	v_ashrrev_i32_e32 v31, 4, v31
	v_lshl_add_u32 v23, v11, 3, v137
	v_ashrrev_i32_e32 v11, 4, v27
	v_add_u32_e32 v19, 0xe00, v132
	v_lshl_add_u32 v65, v31, 3, v137
	v_add_u32_e32 v31, 0x1e00, v132
	v_ashrrev_i32_e32 v133, 4, v132
	v_lshl_add_u32 v15, v11, 3, v137
	v_ashrrev_i32_e32 v11, 4, v19
	v_ashrrev_i32_e32 v31, 4, v31
	v_cmp_gt_i32_e32 vcc, s70, v132
	v_lshl_add_u32 v136, v133, 3, v137
	v_lshl_add_u32 v11, v11, 3, v137
	v_lshl_add_u32 v31, v31, 3, v137
	v_mov_b32_e32 v117, 0
	v_mov_b32_e32 v88, 0
	v_mov_b32_e32 v89, v116
	v_mov_b32_e32 v96, v116
	v_mov_b32_e32 v97, v116
	v_mov_b32_e32 v104, v116
	v_mov_b32_e32 v105, v116
	v_mov_b32_e32 v110, v116
	v_mov_b32_e32 v111, v116
	v_mov_b32_e32 v90, v116
	v_mov_b32_e32 v91, v116
	v_mov_b32_e32 v98, v116
	v_mov_b32_e32 v99, v116
	v_mov_b32_e32 v106, v116
	v_mov_b32_e32 v107, v116
	v_mov_b32_e32 v112, v116
	v_mov_b32_e32 v113, v116
	v_mov_b32_e32 v86, v116
	v_mov_b32_e32 v87, v116
	v_mov_b32_e32 v94, v116
	v_mov_b32_e32 v95, v116
	v_mov_b32_e32 v102, v116
	v_mov_b32_e32 v103, v116
	v_mov_b32_e32 v108, v116
	v_mov_b32_e32 v109, v116
	v_mov_b32_e32 v84, v116
	v_mov_b32_e32 v85, v116
	v_mov_b32_e32 v92, v116
	v_mov_b32_e32 v93, v116
	v_mov_b32_e32 v100, v116
	v_mov_b32_e32 v101, v116
	v_mov_b32_e32 v114, v116
	v_mov_b32_e32 v115, v116
	s_and_saveexec_b64 s[6:7], vcc
	s_cbranch_execz .LBB0_1620
	ds_read_b64 v[172:173], v136
	ds_read_b64 v[174:175], v127 offset:4096
	ds_read_b64 v[176:177], v124 offset:8192
	ds_read_b64 v[178:179], v67 offset:12288
	ds_read_b64 v[180:181], v59 offset:16384
	ds_read_b64 v[182:183], v23 offset:20480
	ds_read_b64 v[184:185], v15 offset:24576
	ds_read_b64 v[186:187], v11 offset:28672
	ds_read_b64 v[188:189], v135 offset:32768
	ds_read_b64 v[190:191], v134 offset:36864
	ds_read_b64 v[192:193], v131 offset:40960
	ds_read_b64 v[194:195], v129 offset:45056
	ds_read_b64 v[196:197], v126 offset:49152
	ds_read_b64 v[198:199], v123 offset:53248
	ds_read_b64 v[200:201], v65 offset:57344
	s_waitcnt lgkmcnt(14)
	ds_read_b64 v[202:203], v31 offset:61440
	s_waitcnt lgkmcnt(7)
	v_pk_add_f32 v[116:117], v[172:173], v[188:189]
	v_pk_add_f32 v[138:139], v[172:173], v[188:189] neg_lo:[0,1] neg_hi:[0,1]
	s_waitcnt lgkmcnt(3)
	v_pk_add_f32 v[84:85], v[180:181], v[196:197]
	v_pk_add_f32 v[92:93], v[180:181], v[196:197] neg_lo:[0,1] neg_hi:[0,1]
	v_pk_add_f32 v[100:101], v[116:117], v[84:85]
	v_pk_add_f32 v[108:109], v[116:117], v[84:85] neg_lo:[0,1] neg_hi:[0,1]
	v_pk_add_f32 v[84:85], v[174:175], v[190:191]
	v_pk_add_f32 v[140:141], v[174:175], v[190:191] neg_lo:[0,1] neg_hi:[0,1]
	s_waitcnt lgkmcnt(2)
	v_pk_add_f32 v[86:87], v[182:183], v[198:199]
	v_pk_add_f32 v[94:95], v[182:183], v[198:199] neg_lo:[0,1] neg_hi:[0,1]
	v_pk_add_f32 v[102:103], v[84:85], v[86:87]
	v_pk_add_f32 v[110:111], v[84:85], v[86:87] neg_lo:[0,1] neg_hi:[0,1]
	v_pk_add_f32 v[84:85], v[176:177], v[192:193]
	s_waitcnt lgkmcnt(1)
	v_pk_add_f32 v[86:87], v[184:185], v[200:201]
	v_pk_add_f32 v[144:145], v[176:177], v[192:193] neg_lo:[0,1] neg_hi:[0,1]
	v_pk_add_f32 v[88:89], v[184:185], v[200:201] neg_lo:[0,1] neg_hi:[0,1]
	v_pk_add_f32 v[96:97], v[84:85], v[86:87]
	v_pk_add_f32 v[104:105], v[84:85], v[86:87] neg_lo:[0,1] neg_hi:[0,1]
	v_pk_add_f32 v[84:85], v[178:179], v[194:195]
	s_waitcnt lgkmcnt(0)
	v_pk_add_f32 v[86:87], v[186:187], v[202:203]
	v_pk_add_f32 v[148:149], v[178:179], v[194:195] neg_lo:[0,1] neg_hi:[0,1]
	v_pk_add_f32 v[90:91], v[84:85], v[86:87]
	v_xor_b32_e32 v143, 0x80000000, v94
	v_mov_b32_e32 v142, v95
	v_xor_b32_e32 v113, 0x80000000, v88
	v_mov_b32_e32 v112, v89
	v_pk_add_f32 v[88:89], v[186:187], v[202:203] neg_lo:[0,1] neg_hi:[0,1]
	v_pk_add_f32 v[106:107], v[84:85], v[86:87] neg_lo:[0,1] neg_hi:[0,1]
	v_pk_add_f32 v[86:87], v[102:103], v[90:91]
	v_pk_add_f32 v[90:91], v[102:103], v[90:91] neg_lo:[0,1] neg_hi:[0,1]
	v_pk_add_f32 v[94:95], v[140:141], v[142:143] neg_lo:[0,1] neg_hi:[0,1]
	v_xor_b32_e32 v115, 0x80000000, v88
	v_mov_b32_e32 v114, v89
	v_pk_add_f32 v[84:85], v[100:101], v[96:97]
	v_pk_add_f32 v[96:97], v[100:101], v[96:97] neg_lo:[0,1] neg_hi:[0,1]
	v_xor_b32_e32 v101, 0x80000000, v90
	v_mov_b32_e32 v100, v91
	s_mov_b32 s10, s27
	s_mov_b32 s11, s26
	v_pk_add_f32 v[146:147], v[144:145], v[112:113] neg_lo:[0,1] neg_hi:[0,1]
	v_pk_add_f32 v[98:99], v[148:149], v[114:115] neg_lo:[0,1] neg_hi:[0,1]
	v_pk_add_f32 v[88:89], v[84:85], v[86:87]
	v_pk_add_f32 v[86:87], v[84:85], v[86:87] neg_lo:[0,1] neg_hi:[0,1]
	v_pk_add_f32 v[84:85], v[96:97], v[100:101]
	v_pk_add_f32 v[90:91], v[96:97], v[100:101] neg_lo:[0,1] neg_hi:[0,1]
	s_mov_b32 s8, s26
	s_mov_b32 s9, s28
	v_pk_mul_f32 v[96:97], v[94:95], s[10:11] op_sel:[1,0]
	s_mov_b32 s35, s28
	v_xor_b32_e32 v117, 0x80000000, v92
	v_mov_b32_e32 v116, v93
	v_pk_fma_f32 v[94:95], v[94:95], s[8:9], v[96:97] op_sel_hi:[0,1,1]
	v_mul_f32_e32 v96, 0x3f3504f3, v146
	s_mov_b32 s8, s31
	s_mov_b32 s9, s30
	s_mov_b32 s29, s26
	v_pk_mul_f32 v[100:101], v[98:99], s[34:35] op_sel:[1,0]
	v_pk_add_f32 v[92:93], v[138:139], v[116:117] neg_lo:[0,1] neg_hi:[0,1]
	v_pk_fma_f32 v[96:97], v[146:147], s[8:9], v[96:97] op_sel:[1,0,0] op_sel_hi:[1,1,0]
	v_pk_fma_f32 v[98:99], v[98:99], s[28:29], v[100:101] op_sel_hi:[0,1,1]
	v_pk_add_f32 v[100:101], v[92:93], v[96:97]
	v_pk_add_f32 v[102:103], v[92:93], v[96:97] neg_lo:[0,1] neg_hi:[0,1]
	v_pk_add_f32 v[92:93], v[94:95], v[98:99]
	v_pk_add_f32 v[98:99], v[94:95], v[98:99] neg_lo:[0,1] neg_hi:[0,1]
	v_pk_add_f32 v[96:97], v[100:101], v[92:93]
	v_pk_add_f32 v[94:95], v[100:101], v[92:93] neg_lo:[0,1] neg_hi:[0,1]
	v_xor_b32_e32 v101, 0x80000000, v98
	v_mov_b32_e32 v100, v99
	s_mov_b32 s12, s21
	s_mov_b32 s13, s20
	v_pk_add_f32 v[92:93], v[102:103], v[100:101]
	v_pk_add_f32 v[98:99], v[102:103], v[100:101] neg_lo:[0,1] neg_hi:[0,1]
	s_mov_b32 s10, s20
	s_mov_b32 s11, s36
	v_pk_mul_f32 v[102:103], v[104:105], s[12:13] op_sel:[1,0]
	v_mul_f32_e32 v100, 0x3f3504f3, v110
	v_pk_fma_f32 v[102:103], v[104:105], s[10:11], v[102:103] op_sel_hi:[0,1,1]
	v_mul_f32_e32 v104, 0xbf3504f3, v107
	v_pk_fma_f32 v[100:101], v[110:111], s[8:9], v[100:101] op_sel:[1,0,0] op_sel_hi:[1,1,0]
	v_pk_fma_f32 v[104:105], v[106:107], s[8:9], v[104:105] op_sel_hi:[0,1,0]
	v_pk_add_f32 v[106:107], v[108:109], v[102:103]
	v_pk_add_f32 v[108:109], v[108:109], v[102:103] neg_lo:[0,1] neg_hi:[0,1]
	v_pk_add_f32 v[102:103], v[100:101], v[104:105]
	v_pk_add_f32 v[100:101], v[100:101], v[104:105] neg_lo:[0,1] neg_hi:[0,1]
	v_pk_add_f32 v[104:105], v[106:107], v[102:103]
	v_pk_add_f32 v[102:103], v[106:107], v[102:103] neg_lo:[0,1] neg_hi:[0,1]
	v_xor_b32_e32 v107, 0x80000000, v100
	v_mov_b32_e32 v106, v101
	v_pk_add_f32 v[100:101], v[108:109], v[106:107]
	v_pk_add_f32 v[106:107], v[108:109], v[106:107] neg_lo:[0,1] neg_hi:[0,1]
	v_pk_add_f32 v[108:109], v[148:149], v[114:115]
	s_mov_b32 s12, s28
	s_mov_b32 s13, s34
	s_mov_b32 s10, s34
	s_mov_b32 s11, s27
	v_pk_mul_f32 v[110:111], v[108:109], s[12:13] op_sel:[1,0]
	v_pk_add_f32 v[114:115], v[140:141], v[142:143]
	v_pk_fma_f32 v[108:109], v[108:109], s[10:11], v[110:111] op_sel_hi:[0,1,1]
	v_pk_add_f32 v[110:111], v[138:139], v[116:117]
	v_pk_mul_f32 v[116:117], v[114:115], s[34:35] op_sel:[1,0]
	v_pk_add_f32 v[112:113], v[144:145], v[112:113]
	v_pk_fma_f32 v[114:115], v[114:115], s[28:29], v[116:117] op_sel_hi:[0,1,1]
	v_mul_f32_e32 v116, 0xbf3504f3, v113
	v_pk_fma_f32 v[112:113], v[112:113], s[8:9], v[116:117] op_sel_hi:[0,1,0]
	v_pk_add_f32 v[116:117], v[110:111], v[112:113]
	v_pk_add_f32 v[138:139], v[114:115], v[108:109]
	v_pk_add_f32 v[114:115], v[114:115], v[108:109] neg_lo:[0,1] neg_hi:[0,1]
	v_pk_add_f32 v[112:113], v[110:111], v[112:113] neg_lo:[0,1] neg_hi:[0,1]
	v_pk_add_f32 v[110:111], v[116:117], v[138:139]
	v_pk_add_f32 v[108:109], v[116:117], v[138:139] neg_lo:[0,1] neg_hi:[0,1]
	v_xor_b32_e32 v139, 0x80000000, v114
	v_mov_b32_e32 v138, v115
	v_pk_add_f32 v[116:117], v[112:113], v[138:139]
	v_pk_add_f32 v[112:113], v[112:113], v[138:139] neg_lo:[0,1] neg_hi:[0,1]
	v_mov_b32_e32 v114, v116
	v_mov_b32_e32 v115, v117

.LBB0_1622:
	s_or_b64 exec, exec, s[6:7]
	s_waitcnt lgkmcnt(0)
	s_barrier
	s_and_saveexec_b64 s[6:7], vcc
	s_cbranch_execz .LBB0_1624
	ds_read_b64 v[172:173], v31 offset:61440
	ds_read_b64 v[174:175], v65 offset:57344
	ds_read_b64 v[176:177], v123 offset:53248
	ds_read_b64 v[178:179], v126 offset:49152
	ds_read_b64 v[180:181], v129 offset:45056
	ds_read_b64 v[182:183], v131 offset:40960
	ds_read_b64 v[184:185], v136
	ds_read_b64 v[186:187], v127 offset:4096
	ds_read_b64 v[188:189], v124 offset:8192
	ds_read_b64 v[190:191], v67 offset:12288
	ds_read_b64 v[192:193], v59 offset:16384
	ds_read_b64 v[194:195], v23 offset:20480
	ds_read_b64 v[196:197], v15 offset:24576
	ds_read_b64 v[198:199], v11 offset:28672
	ds_read_b64 v[200:201], v135 offset:32768
	v_and_b32_e32 v84, 15, v132
	v_cvt_f32_ubyte0_e32 v84, v84
	v_mul_f32_e32 v84, 0x3b800000, v84
	v_cos_f32_e32 v98, v84
	v_sin_f32_e32 v99, v84
	s_mov_b32 s10, s27
	v_mov_b32_e32 v101, v98
	v_xor_b32_e32 v100, 0x80000000, v99
	v_mov_b32_e32 v84, v99
	v_pk_mul_f32 v[84:85], v[100:101], v[84:85] op_sel_hi:[1,0]
	s_mov_b32 s11, s26
	v_pk_fma_f32 v[106:107], v[98:99], v[98:99], v[84:85] op_sel_hi:[1,0,1]
	s_mov_b32 s8, s26
	v_pk_mul_f32 v[84:85], v[100:101], v[106:107] op_sel:[0,1]
	s_mov_b32 s9, s28
	v_pk_fma_f32 v[110:111], v[98:99], v[106:107], v[84:85] op_sel_hi:[1,0,1]
	s_mov_b32 s35, s28
	v_pk_mul_f32 v[84:85], v[100:101], v[110:111] op_sel:[0,1]
	s_mov_b32 s29, s26
	v_pk_fma_f32 v[112:113], v[98:99], v[110:111], v[84:85] op_sel_hi:[1,0,1]
	s_mov_b32 s12, s21
	v_pk_mul_f32 v[84:85], v[100:101], v[112:113] op_sel:[0,1]
	s_mov_b32 s13, s20
	v_pk_fma_f32 v[114:115], v[98:99], v[112:113], v[84:85] op_sel_hi:[1,0,1]
	s_nop 0
	v_pk_mul_f32 v[84:85], v[100:101], v[114:115] op_sel:[0,1]
	s_nop 0
	v_pk_fma_f32 v[116:117], v[98:99], v[114:115], v[84:85] op_sel_hi:[1,0,1]
	s_nop 0
	v_pk_mul_f32 v[84:85], v[100:101], v[116:117] op_sel:[0,1]
	s_nop 0
	v_pk_fma_f32 v[138:139], v[98:99], v[116:117], v[84:85] op_sel_hi:[1,0,1]
	s_nop 0
	v_pk_mul_f32 v[84:85], v[100:101], v[138:139] op_sel:[0,1]
	s_nop 0
	v_pk_fma_f32 v[102:103], v[98:99], v[138:139], v[84:85] op_sel_hi:[1,0,1]
	s_nop 0
	v_pk_mul_f32 v[84:85], v[100:101], v[102:103] op_sel:[0,1]
	s_nop 0
	v_pk_fma_f32 v[86:87], v[98:99], v[102:103], v[84:85] op_sel_hi:[1,0,1]
	s_nop 0
	v_pk_mul_f32 v[84:85], v[100:101], v[86:87] op_sel:[0,1]
	s_nop 0
	v_pk_fma_f32 v[96:97], v[98:99], v[86:87], v[84:85] op_sel_hi:[1,0,1]
	s_nop 0
	v_pk_mul_f32 v[84:85], v[100:101], v[96:97] op_sel:[0,1]
	s_nop 0
	v_pk_fma_f32 v[92:93], v[98:99], v[96:97], v[84:85] op_sel_hi:[1,0,1]
	s_nop 0
	v_pk_mul_f32 v[84:85], v[100:101], v[92:93] op_sel:[0,1]
	s_nop 0
	v_pk_fma_f32 v[94:95], v[98:99], v[92:93], v[84:85] op_sel_hi:[1,0,1]
	s_nop 0
	v_pk_mul_f32 v[84:85], v[100:101], v[94:95] op_sel:[0,1]
	s_nop 0
	v_pk_fma_f32 v[90:91], v[98:99], v[94:95], v[84:85] op_sel_hi:[1,0,1]
	s_nop 0
	v_pk_mul_f32 v[84:85], v[100:101], v[90:91] op_sel:[0,1]
	s_nop 0
	v_pk_fma_f32 v[88:89], v[98:99], v[90:91], v[84:85] op_sel_hi:[1,0,1]
	s_nop 0
	v_pk_mul_f32 v[84:85], v[100:101], v[88:89] op_sel:[0,1]
	s_nop 0
	v_pk_fma_f32 v[84:85], v[98:99], v[88:89], v[84:85] op_sel_hi:[1,0,1]
	s_nop 0
	v_xor_b32_e32 v108, 0x80000000, v85
	v_mov_b32_e32 v109, v84
	s_waitcnt lgkmcnt(14)
	v_pk_mul_f32 v[108:109], v[108:109], v[172:173] op_sel:[0,1]
	s_nop 0
	v_pk_fma_f32 v[84:85], v[84:85], v[172:173], v[108:109] op_sel_hi:[1,0,1]
	ds_read_b64 v[172:173], v134 offset:36864
	v_xor_b32_e32 v108, 0x80000000, v89
	v_mov_b32_e32 v109, v88
	s_waitcnt lgkmcnt(14)
	v_pk_mul_f32 v[108:109], v[108:109], v[174:175] op_sel:[0,1]
	s_nop 0
	v_pk_fma_f32 v[88:89], v[88:89], v[174:175], v[108:109] op_sel_hi:[1,0,1]
	v_xor_b32_e32 v108, 0x80000000, v91
	v_mov_b32_e32 v109, v90
	s_waitcnt lgkmcnt(13)
	v_pk_mul_f32 v[108:109], v[108:109], v[176:177] op_sel:[0,1]
	s_nop 0
	v_pk_fma_f32 v[90:91], v[90:91], v[176:177], v[108:109] op_sel_hi:[1,0,1]
	v_xor_b32_e32 v108, 0x80000000, v95
	v_mov_b32_e32 v109, v94
	s_waitcnt lgkmcnt(12)
	v_pk_mul_f32 v[108:109], v[108:109], v[178:179] op_sel:[0,1]
	s_nop 0
	v_pk_fma_f32 v[94:95], v[94:95], v[178:179], v[108:109] op_sel_hi:[1,0,1]
	v_xor_b32_e32 v108, 0x80000000, v93
	v_mov_b32_e32 v109, v92
	s_waitcnt lgkmcnt(11)
	v_pk_mul_f32 v[108:109], v[108:109], v[180:181] op_sel:[0,1]
	s_nop 0
	v_pk_fma_f32 v[92:93], v[92:93], v[180:181], v[108:109] op_sel_hi:[1,0,1]
	v_xor_b32_e32 v108, 0x80000000, v97
	v_mov_b32_e32 v109, v96
	s_waitcnt lgkmcnt(10)
	v_pk_mul_f32 v[108:109], v[108:109], v[182:183] op_sel:[0,1]
	s_nop 0
	v_pk_fma_f32 v[96:97], v[96:97], v[182:183], v[108:109] op_sel_hi:[1,0,1]
	s_waitcnt lgkmcnt(8)
	v_pk_mul_f32 v[100:101], v[100:101], v[186:187] op_sel:[0,1]
	s_nop 0
	v_pk_fma_f32 v[104:105], v[98:99], v[186:187], v[100:101] op_sel_hi:[1,0,1]
	v_xor_b32_e32 v100, 0x80000000, v107
	v_mov_b32_e32 v101, v106
	s_waitcnt lgkmcnt(7)
	v_pk_mul_f32 v[100:101], v[100:101], v[188:189] op_sel:[0,1]
	s_nop 0
	v_pk_fma_f32 v[100:101], v[106:107], v[188:189], v[100:101] op_sel_hi:[1,0,1]
	v_xor_b32_e32 v106, 0x80000000, v111
	v_mov_b32_e32 v107, v110
	v_pk_add_f32 v[144:145], v[100:101], v[96:97] neg_lo:[0,1] neg_hi:[0,1]
	s_waitcnt lgkmcnt(6)
	v_pk_mul_f32 v[106:107], v[106:107], v[190:191] op_sel:[0,1]
	s_nop 0
	v_pk_fma_f32 v[98:99], v[110:111], v[190:191], v[106:107] op_sel_hi:[1,0,1]
	v_xor_b32_e32 v110, 0x80000000, v113
	v_mov_b32_e32 v111, v112
	v_pk_add_f32 v[148:149], v[98:99], v[92:93] neg_lo:[0,1] neg_hi:[0,1]
	s_waitcnt lgkmcnt(5)
	v_pk_mul_f32 v[110:111], v[110:111], v[192:193] op_sel:[0,1]
	s_nop 0
	v_pk_fma_f32 v[110:111], v[112:113], v[192:193], v[110:111] op_sel_hi:[1,0,1]
	v_xor_b32_e32 v112, 0x80000000, v115
	v_mov_b32_e32 v113, v114
	s_waitcnt lgkmcnt(4)
	v_pk_mul_f32 v[112:113], v[112:113], v[194:195] op_sel:[0,1]
	s_nop 0
	v_pk_fma_f32 v[112:113], v[114:115], v[194:195], v[112:113] op_sel_hi:[1,0,1]
	v_xor_b32_e32 v114, 0x80000000, v117
	v_mov_b32_e32 v115, v116
	s_waitcnt lgkmcnt(3)
	v_pk_mul_f32 v[114:115], v[114:115], v[196:197] op_sel:[0,1]
	s_nop 0
	v_pk_fma_f32 v[114:115], v[116:117], v[196:197], v[114:115] op_sel_hi:[1,0,1]
	v_xor_b32_e32 v116, 0x80000000, v139
	v_mov_b32_e32 v117, v138
	s_waitcnt lgkmcnt(2)
	v_pk_mul_f32 v[116:117], v[116:117], v[198:199] op_sel:[0,1]
	s_nop 0
	v_pk_fma_f32 v[106:107], v[138:139], v[198:199], v[116:117] op_sel_hi:[1,0,1]
	v_xor_b32_e32 v138, 0x80000000, v103
	v_mov_b32_e32 v139, v102
	s_waitcnt lgkmcnt(1)
	v_pk_mul_f32 v[138:139], v[138:139], v[200:201] op_sel:[0,1]
	s_nop 0
	v_pk_fma_f32 v[102:103], v[102:103], v[200:201], v[138:139] op_sel_hi:[1,0,1]
	v_xor_b32_e32 v138, 0x80000000, v87
	v_mov_b32_e32 v139, v86
	s_waitcnt lgkmcnt(0)
	v_pk_mul_f32 v[138:139], v[138:139], v[172:173] op_sel:[0,1]
	s_nop 0
	v_pk_fma_f32 v[86:87], v[86:87], v[172:173], v[138:139] op_sel_hi:[1,0,1]
	v_pk_add_f32 v[116:117], v[184:185], v[102:103]
	v_pk_add_f32 v[138:139], v[104:105], v[86:87]
	v_pk_add_f32 v[140:141], v[104:105], v[86:87] neg_lo:[0,1] neg_hi:[0,1]
	v_pk_add_f32 v[86:87], v[90:91], v[112:113]
	v_pk_add_f32 v[90:91], v[112:113], v[90:91] neg_lo:[0,1] neg_hi:[0,1]
	v_pk_add_f32 v[104:105], v[86:87], v[138:139]
	v_pk_add_f32 v[112:113], v[138:139], v[86:87] neg_lo:[0,1] neg_hi:[0,1]
	v_xor_b32_e32 v139, 0x80000000, v90
	v_mov_b32_e32 v138, v91
	v_pk_add_f32 v[86:87], v[96:97], v[100:101]
	v_pk_add_f32 v[90:91], v[88:89], v[114:115]
	v_pk_add_f32 v[88:89], v[114:115], v[88:89] neg_lo:[0,1] neg_hi:[0,1]
	v_pk_add_f32 v[96:97], v[86:87], v[90:91]
	v_pk_add_f32 v[100:101], v[86:87], v[90:91] neg_lo:[0,1] neg_hi:[0,1]
	v_xor_b32_e32 v115, 0x80000000, v88
	v_mov_b32_e32 v114, v89
	v_pk_add_f32 v[86:87], v[92:93], v[98:99]
	v_pk_add_f32 v[88:89], v[84:85], v[106:107]
	v_pk_add_f32 v[108:109], v[184:185], v[102:103] neg_lo:[0,1] neg_hi:[0,1]
	v_pk_add_f32 v[102:103], v[94:95], v[110:111]
	v_pk_add_f32 v[90:91], v[86:87], v[88:89]
	v_pk_add_f32 v[94:95], v[110:111], v[94:95] neg_lo:[0,1] neg_hi:[0,1]
	v_pk_add_f32 v[110:111], v[102:103], v[116:117]
	v_pk_add_f32 v[84:85], v[106:107], v[84:85] neg_lo:[0,1] neg_hi:[0,1]
	v_pk_add_f32 v[106:107], v[86:87], v[88:89] neg_lo:[0,1] neg_hi:[0,1]
	v_pk_add_f32 v[86:87], v[90:91], v[104:105]
	v_pk_add_f32 v[90:91], v[104:105], v[90:91] neg_lo:[0,1] neg_hi:[0,1]
	v_pk_add_f32 v[142:143], v[140:141], v[138:139] neg_lo:[0,1] neg_hi:[0,1]
	v_xor_b32_e32 v151, 0x80000000, v84
	v_mov_b32_e32 v150, v85
	v_pk_add_f32 v[84:85], v[96:97], v[110:111]
	v_pk_add_f32 v[96:97], v[110:111], v[96:97] neg_lo:[0,1] neg_hi:[0,1]
	v_xor_b32_e32 v99, 0x80000000, v90
	v_mov_b32_e32 v98, v91
	v_pk_add_f32 v[146:147], v[144:145], v[114:115] neg_lo:[0,1] neg_hi:[0,1]
	v_pk_add_f32 v[92:93], v[148:149], v[150:151] neg_lo:[0,1] neg_hi:[0,1]
	v_pk_add_f32 v[88:89], v[84:85], v[86:87]
	v_pk_add_f32 v[86:87], v[84:85], v[86:87] neg_lo:[0,1] neg_hi:[0,1]
	v_pk_add_f32 v[84:85], v[96:97], v[98:99]
	v_pk_add_f32 v[90:91], v[96:97], v[98:99] neg_lo:[0,1] neg_hi:[0,1]
	v_pk_mul_f32 v[96:97], v[142:143], s[10:11] op_sel:[1,0]
	v_pk_add_f32 v[102:103], v[116:117], v[102:103] neg_lo:[0,1] neg_hi:[0,1]
	v_xor_b32_e32 v117, 0x80000000, v94
	v_mov_b32_e32 v116, v95
	v_pk_fma_f32 v[96:97], v[142:143], s[8:9], v[96:97] op_sel_hi:[0,1,1]
	v_mul_f32_e32 v98, 0x3f3504f3, v146
	s_mov_b32 s8, s31
	s_mov_b32 s9, s30
	v_pk_mul_f32 v[104:105], v[92:93], s[34:35] op_sel:[1,0]
	v_pk_add_f32 v[94:95], v[108:109], v[116:117] neg_lo:[0,1] neg_hi:[0,1]
	v_pk_fma_f32 v[98:99], v[146:147], s[8:9], v[98:99] op_sel:[1,0,0] op_sel_hi:[1,1,0]
	v_pk_fma_f32 v[92:93], v[92:93], s[28:29], v[104:105] op_sel_hi:[0,1,1]
	v_pk_add_f32 v[104:105], v[94:95], v[98:99]
	v_pk_add_f32 v[98:99], v[94:95], v[98:99] neg_lo:[0,1] neg_hi:[0,1]
	v_pk_add_f32 v[94:95], v[96:97], v[92:93]
	v_pk_add_f32 v[92:93], v[96:97], v[92:93] neg_lo:[0,1] neg_hi:[0,1]
	v_pk_add_f32 v[96:97], v[104:105], v[94:95]
	v_pk_add_f32 v[94:95], v[104:105], v[94:95] neg_lo:[0,1] neg_hi:[0,1]
	v_xor_b32_e32 v105, 0x80000000, v92
	v_mov_b32_e32 v104, v93
	s_mov_b32 s10, s20
	s_mov_b32 s11, s36
	v_pk_mul_f32 v[110:111], v[100:101], s[12:13] op_sel:[1,0]
	v_pk_add_f32 v[92:93], v[98:99], v[104:105]
	v_pk_add_f32 v[98:99], v[98:99], v[104:105] neg_lo:[0,1] neg_hi:[0,1]
	v_mul_f32_e32 v104, 0x3f3504f3, v112
	v_pk_fma_f32 v[100:101], v[100:101], s[10:11], v[110:111] op_sel_hi:[0,1,1]
	v_mul_f32_e32 v110, 0xbf3504f3, v107
	v_pk_fma_f32 v[104:105], v[112:113], s[8:9], v[104:105] op_sel:[1,0,0] op_sel_hi:[1,1,0]
	v_pk_fma_f32 v[106:107], v[106:107], s[8:9], v[110:111] op_sel_hi:[0,1,0]
	v_pk_add_f32 v[110:111], v[102:103], v[100:101]
	v_pk_add_f32 v[112:113], v[102:103], v[100:101] neg_lo:[0,1] neg_hi:[0,1]
	v_pk_add_f32 v[100:101], v[106:107], v[104:105]
	v_pk_add_f32 v[106:107], v[104:105], v[106:107] neg_lo:[0,1] neg_hi:[0,1]
	v_pk_add_f32 v[104:105], v[110:111], v[100:101]
	v_pk_add_f32 v[102:103], v[110:111], v[100:101] neg_lo:[0,1] neg_hi:[0,1]
	v_xor_b32_e32 v111, 0x80000000, v106
	v_mov_b32_e32 v110, v107
	v_pk_add_f32 v[100:101], v[112:113], v[110:111]
	v_pk_add_f32 v[106:107], v[112:113], v[110:111] neg_lo:[0,1] neg_hi:[0,1]
	v_pk_add_f32 v[110:111], v[148:149], v[150:151]
	s_mov_b32 s12, s28
	s_mov_b32 s13, s34
	s_mov_b32 s10, s34
	s_mov_b32 s11, s27
	v_pk_mul_f32 v[112:113], v[110:111], s[12:13] op_sel:[1,0]
	v_pk_add_f32 v[108:109], v[116:117], v[108:109]
	v_pk_fma_f32 v[110:111], v[110:111], s[10:11], v[112:113] op_sel_hi:[0,1,1]
	v_pk_add_f32 v[112:113], v[138:139], v[140:141]
	v_pk_add_f32 v[114:115], v[144:145], v[114:115]
	v_pk_mul_f32 v[116:117], v[112:113], s[34:35] op_sel:[1,0]
	s_nop 0
	v_pk_fma_f32 v[112:113], v[112:113], s[28:29], v[116:117] op_sel_hi:[0,1,1]
	v_mul_f32_e32 v116, 0xbf3504f3, v115
	v_pk_fma_f32 v[114:115], v[114:115], s[8:9], v[116:117] op_sel_hi:[0,1,0]
	v_pk_add_f32 v[116:117], v[108:109], v[114:115]
	v_pk_add_f32 v[138:139], v[108:109], v[114:115] neg_lo:[0,1] neg_hi:[0,1]
	v_pk_add_f32 v[108:109], v[112:113], v[110:111]
	v_pk_add_f32 v[112:113], v[112:113], v[110:111] neg_lo:[0,1] neg_hi:[0,1]
	v_pk_add_f32 v[110:111], v[116:117], v[108:109]
	v_pk_add_f32 v[108:109], v[116:117], v[108:109] neg_lo:[0,1] neg_hi:[0,1]
	v_xor_b32_e32 v117, 0x80000000, v112
	v_mov_b32_e32 v116, v113
	v_pk_add_f32 v[114:115], v[138:139], v[116:117]
	v_pk_add_f32 v[112:113], v[138:139], v[116:117] neg_lo:[0,1] neg_hi:[0,1]

.LBB0_1626:
	s_or_b64 exec, exec, s[6:7]
	s_waitcnt lgkmcnt(0)
	s_barrier
	s_and_saveexec_b64 s[6:7], vcc
	s_cbranch_execz .LBB0_1628
	ds_read_b64 v[172:173], v31 offset:61440
	ds_read_b64 v[174:175], v65 offset:57344
	ds_read_b64 v[176:177], v123 offset:53248
	ds_read_b64 v[178:179], v126 offset:49152
	ds_read_b64 v[180:181], v129 offset:45056
	ds_read_b64 v[182:183], v131 offset:40960
	ds_read_b64 v[184:185], v136
	ds_read_b64 v[186:187], v127 offset:4096
	ds_read_b64 v[188:189], v124 offset:8192
	ds_read_b64 v[190:191], v67 offset:12288
	ds_read_b64 v[192:193], v59 offset:16384
	ds_read_b64 v[194:195], v23 offset:20480
	ds_read_b64 v[196:197], v15 offset:24576
	ds_read_b64 v[198:199], v11 offset:28672
	ds_read_b64 v[200:201], v135 offset:32768
	v_cvt_f32_ubyte0_e32 v84, v132
	v_mul_f32_e32 v84, 0x39800000, v84
	v_cos_f32_e32 v98, v84
	v_sin_f32_e32 v99, v84
	s_mov_b32 s10, s27
	v_mov_b32_e32 v101, v98
	v_xor_b32_e32 v100, 0x80000000, v99
	v_mov_b32_e32 v84, v99
	v_pk_mul_f32 v[84:85], v[100:101], v[84:85] op_sel_hi:[1,0]
	s_mov_b32 s11, s26
	v_pk_fma_f32 v[106:107], v[98:99], v[98:99], v[84:85] op_sel_hi:[1,0,1]
	s_mov_b32 s8, s26
	v_pk_mul_f32 v[84:85], v[100:101], v[106:107] op_sel:[0,1]
	s_mov_b32 s9, s28
	v_pk_fma_f32 v[110:111], v[98:99], v[106:107], v[84:85] op_sel_hi:[1,0,1]
	s_mov_b32 s35, s28
	v_pk_mul_f32 v[84:85], v[100:101], v[110:111] op_sel:[0,1]
	s_mov_b32 s29, s26
	v_pk_fma_f32 v[112:113], v[98:99], v[110:111], v[84:85] op_sel_hi:[1,0,1]
	s_mov_b32 s12, s21
	v_pk_mul_f32 v[84:85], v[100:101], v[112:113] op_sel:[0,1]
	s_mov_b32 s13, s20
	v_pk_fma_f32 v[114:115], v[98:99], v[112:113], v[84:85] op_sel_hi:[1,0,1]
	s_nop 0
	v_pk_mul_f32 v[84:85], v[100:101], v[114:115] op_sel:[0,1]
	s_nop 0
	v_pk_fma_f32 v[138:139], v[98:99], v[114:115], v[84:85] op_sel_hi:[1,0,1]
	s_nop 0
	v_pk_mul_f32 v[84:85], v[100:101], v[138:139] op_sel:[0,1]
	s_nop 0
	v_pk_fma_f32 v[140:141], v[98:99], v[138:139], v[84:85] op_sel_hi:[1,0,1]
	s_nop 0
	v_pk_mul_f32 v[84:85], v[100:101], v[140:141] op_sel:[0,1]
	v_mov_b32_e32 v137, v140
	v_pk_fma_f32 v[102:103], v[98:99], v[140:141], v[84:85] op_sel_hi:[1,0,1]
	s_nop 0
	v_pk_mul_f32 v[84:85], v[100:101], v[102:103] op_sel:[0,1]
	s_nop 0
	v_pk_fma_f32 v[86:87], v[98:99], v[102:103], v[84:85] op_sel_hi:[1,0,1]
	s_nop 0
	v_pk_mul_f32 v[84:85], v[100:101], v[86:87] op_sel:[0,1]
	s_nop 0
	v_pk_fma_f32 v[96:97], v[98:99], v[86:87], v[84:85] op_sel_hi:[1,0,1]
	s_nop 0
	v_pk_mul_f32 v[84:85], v[100:101], v[96:97] op_sel:[0,1]
	s_nop 0
	v_pk_fma_f32 v[92:93], v[98:99], v[96:97], v[84:85] op_sel_hi:[1,0,1]
	s_nop 0
	v_pk_mul_f32 v[84:85], v[100:101], v[92:93] op_sel:[0,1]
	s_nop 0
	v_pk_fma_f32 v[94:95], v[98:99], v[92:93], v[84:85] op_sel_hi:[1,0,1]
	s_nop 0
	v_pk_mul_f32 v[84:85], v[100:101], v[94:95] op_sel:[0,1]
	s_nop 0
	v_pk_fma_f32 v[90:91], v[98:99], v[94:95], v[84:85] op_sel_hi:[1,0,1]
	s_nop 0
	v_pk_mul_f32 v[84:85], v[100:101], v[90:91] op_sel:[0,1]
	s_nop 0
	v_pk_fma_f32 v[88:89], v[98:99], v[90:91], v[84:85] op_sel_hi:[1,0,1]
	s_nop 0
	v_pk_mul_f32 v[84:85], v[100:101], v[88:89] op_sel:[0,1]
	s_nop 0
	v_pk_fma_f32 v[84:85], v[98:99], v[88:89], v[84:85] op_sel_hi:[1,0,1]
	s_nop 0
	v_xor_b32_e32 v108, 0x80000000, v85
	v_mov_b32_e32 v109, v84
	s_waitcnt lgkmcnt(14)
	v_pk_mul_f32 v[108:109], v[108:109], v[172:173] op_sel:[0,1]
	s_nop 0
	v_pk_fma_f32 v[84:85], v[84:85], v[172:173], v[108:109] op_sel_hi:[1,0,1]
	ds_read_b64 v[172:173], v134 offset:36864
	v_xor_b32_e32 v108, 0x80000000, v89
	v_mov_b32_e32 v109, v88
	s_waitcnt lgkmcnt(14)
	v_pk_mul_f32 v[108:109], v[108:109], v[174:175] op_sel:[0,1]
	s_nop 0
	v_pk_fma_f32 v[88:89], v[88:89], v[174:175], v[108:109] op_sel_hi:[1,0,1]
	v_xor_b32_e32 v108, 0x80000000, v91
	v_mov_b32_e32 v109, v90
	s_waitcnt lgkmcnt(13)
	v_pk_mul_f32 v[108:109], v[108:109], v[176:177] op_sel:[0,1]
	s_nop 0
	v_pk_fma_f32 v[90:91], v[90:91], v[176:177], v[108:109] op_sel_hi:[1,0,1]
	v_xor_b32_e32 v108, 0x80000000, v95
	v_mov_b32_e32 v109, v94
	s_waitcnt lgkmcnt(12)
	v_pk_mul_f32 v[108:109], v[108:109], v[178:179] op_sel:[0,1]
	s_nop 0
	v_pk_fma_f32 v[94:95], v[94:95], v[178:179], v[108:109] op_sel_hi:[1,0,1]
	v_xor_b32_e32 v108, 0x80000000, v93
	v_mov_b32_e32 v109, v92
	s_waitcnt lgkmcnt(11)
	v_pk_mul_f32 v[108:109], v[108:109], v[180:181] op_sel:[0,1]
	s_nop 0
	v_pk_fma_f32 v[92:93], v[92:93], v[180:181], v[108:109] op_sel_hi:[1,0,1]
	v_xor_b32_e32 v108, 0x80000000, v97
	v_mov_b32_e32 v109, v96
	s_waitcnt lgkmcnt(10)
	v_pk_mul_f32 v[108:109], v[108:109], v[182:183] op_sel:[0,1]
	s_nop 0
	v_pk_fma_f32 v[96:97], v[96:97], v[182:183], v[108:109] op_sel_hi:[1,0,1]
	v_xor_b32_e32 v136, 0x80000000, v141
	s_waitcnt lgkmcnt(8)
	v_pk_mul_f32 v[100:101], v[100:101], v[186:187] op_sel:[0,1]
	s_nop 0
	v_pk_fma_f32 v[104:105], v[98:99], v[186:187], v[100:101] op_sel_hi:[1,0,1]
	v_xor_b32_e32 v100, 0x80000000, v107
	v_mov_b32_e32 v101, v106
	s_waitcnt lgkmcnt(7)
	v_pk_mul_f32 v[100:101], v[100:101], v[188:189] op_sel:[0,1]
	s_nop 0
	v_pk_fma_f32 v[100:101], v[106:107], v[188:189], v[100:101] op_sel_hi:[1,0,1]
	v_xor_b32_e32 v106, 0x80000000, v111
	v_mov_b32_e32 v107, v110
	v_pk_add_f32 v[144:145], v[100:101], v[96:97] neg_lo:[0,1] neg_hi:[0,1]
	s_waitcnt lgkmcnt(6)
	v_pk_mul_f32 v[106:107], v[106:107], v[190:191] op_sel:[0,1]
	s_nop 0
	v_pk_fma_f32 v[98:99], v[110:111], v[190:191], v[106:107] op_sel_hi:[1,0,1]
	v_xor_b32_e32 v110, 0x80000000, v113
	v_mov_b32_e32 v111, v112
	v_pk_add_f32 v[148:149], v[98:99], v[92:93] neg_lo:[0,1] neg_hi:[0,1]
	s_waitcnt lgkmcnt(5)
	v_pk_mul_f32 v[110:111], v[110:111], v[192:193] op_sel:[0,1]
	s_nop 0
	v_pk_fma_f32 v[110:111], v[112:113], v[192:193], v[110:111] op_sel_hi:[1,0,1]
	v_xor_b32_e32 v112, 0x80000000, v115
	v_mov_b32_e32 v113, v114
	s_waitcnt lgkmcnt(4)
	v_pk_mul_f32 v[112:113], v[112:113], v[194:195] op_sel:[0,1]
	s_nop 0
	v_pk_fma_f32 v[112:113], v[114:115], v[194:195], v[112:113] op_sel_hi:[1,0,1]
	v_xor_b32_e32 v114, 0x80000000, v139
	v_mov_b32_e32 v115, v138
	s_waitcnt lgkmcnt(3)
	v_pk_mul_f32 v[114:115], v[114:115], v[196:197] op_sel:[0,1]
	s_nop 0
	v_pk_fma_f32 v[114:115], v[138:139], v[196:197], v[114:115] op_sel_hi:[1,0,1]
	v_xor_b32_e32 v138, 0x80000000, v103
	v_mov_b32_e32 v139, v102
	s_waitcnt lgkmcnt(2)
	v_pk_mul_f32 v[136:137], v[136:137], v[198:199] op_sel:[0,1]
	s_nop 0
	v_pk_fma_f32 v[106:107], v[140:141], v[198:199], v[136:137] op_sel_hi:[1,0,1]
	s_waitcnt lgkmcnt(1)
	v_pk_mul_f32 v[138:139], v[138:139], v[200:201] op_sel:[0,1]
	s_nop 0
	v_pk_fma_f32 v[102:103], v[102:103], v[200:201], v[138:139] op_sel_hi:[1,0,1]
	v_xor_b32_e32 v138, 0x80000000, v87
	v_mov_b32_e32 v139, v86
	s_waitcnt lgkmcnt(0)
	v_pk_mul_f32 v[138:139], v[138:139], v[172:173] op_sel:[0,1]
	s_nop 0
	v_pk_fma_f32 v[86:87], v[86:87], v[172:173], v[138:139] op_sel_hi:[1,0,1]
	v_pk_add_f32 v[136:137], v[184:185], v[102:103]
	v_pk_add_f32 v[138:139], v[104:105], v[86:87]
	v_pk_add_f32 v[140:141], v[104:105], v[86:87] neg_lo:[0,1] neg_hi:[0,1]
	v_pk_add_f32 v[86:87], v[90:91], v[112:113]
	v_pk_add_f32 v[90:91], v[112:113], v[90:91] neg_lo:[0,1] neg_hi:[0,1]
	v_pk_add_f32 v[104:105], v[86:87], v[138:139]
	v_pk_add_f32 v[112:113], v[138:139], v[86:87] neg_lo:[0,1] neg_hi:[0,1]
	v_xor_b32_e32 v139, 0x80000000, v90
	v_mov_b32_e32 v138, v91
	v_pk_add_f32 v[86:87], v[96:97], v[100:101]
	v_pk_add_f32 v[90:91], v[88:89], v[114:115]
	v_pk_add_f32 v[88:89], v[114:115], v[88:89] neg_lo:[0,1] neg_hi:[0,1]
	v_pk_add_f32 v[96:97], v[86:87], v[90:91]
	v_pk_add_f32 v[100:101], v[86:87], v[90:91] neg_lo:[0,1] neg_hi:[0,1]
	v_xor_b32_e32 v115, 0x80000000, v88
	v_mov_b32_e32 v114, v89
	v_pk_add_f32 v[86:87], v[92:93], v[98:99]
	v_pk_add_f32 v[88:89], v[84:85], v[106:107]
	v_pk_add_f32 v[108:109], v[184:185], v[102:103] neg_lo:[0,1] neg_hi:[0,1]
	v_pk_add_f32 v[102:103], v[94:95], v[110:111]
	v_pk_add_f32 v[90:91], v[86:87], v[88:89]
	v_pk_add_f32 v[94:95], v[110:111], v[94:95] neg_lo:[0,1] neg_hi:[0,1]
	v_pk_add_f32 v[110:111], v[102:103], v[136:137]
	v_pk_add_f32 v[84:85], v[106:107], v[84:85] neg_lo:[0,1] neg_hi:[0,1]
	v_pk_add_f32 v[106:107], v[86:87], v[88:89] neg_lo:[0,1] neg_hi:[0,1]
	v_pk_add_f32 v[86:87], v[90:91], v[104:105]
	v_pk_add_f32 v[90:91], v[104:105], v[90:91] neg_lo:[0,1] neg_hi:[0,1]
	v_pk_add_f32 v[142:143], v[140:141], v[138:139] neg_lo:[0,1] neg_hi:[0,1]
	v_xor_b32_e32 v151, 0x80000000, v84
	v_mov_b32_e32 v150, v85
	v_pk_add_f32 v[84:85], v[96:97], v[110:111]
	v_pk_add_f32 v[96:97], v[110:111], v[96:97] neg_lo:[0,1] neg_hi:[0,1]
	v_xor_b32_e32 v99, 0x80000000, v90
	v_mov_b32_e32 v98, v91
	v_pk_add_f32 v[146:147], v[144:145], v[114:115] neg_lo:[0,1] neg_hi:[0,1]
	v_pk_add_f32 v[92:93], v[148:149], v[150:151] neg_lo:[0,1] neg_hi:[0,1]
	v_pk_add_f32 v[88:89], v[84:85], v[86:87]
	v_pk_add_f32 v[86:87], v[84:85], v[86:87] neg_lo:[0,1] neg_hi:[0,1]
	v_pk_add_f32 v[84:85], v[96:97], v[98:99]
	v_pk_add_f32 v[90:91], v[96:97], v[98:99] neg_lo:[0,1] neg_hi:[0,1]
	v_pk_mul_f32 v[96:97], v[142:143], s[10:11] op_sel:[1,0]
	v_pk_add_f32 v[102:103], v[136:137], v[102:103] neg_lo:[0,1] neg_hi:[0,1]
	v_xor_b32_e32 v137, 0x80000000, v94
	v_mov_b32_e32 v136, v95
	v_pk_fma_f32 v[96:97], v[142:143], s[8:9], v[96:97] op_sel_hi:[0,1,1]
	v_mul_f32_e32 v98, 0x3f3504f3, v146
	s_mov_b32 s8, s31
	s_mov_b32 s9, s30
	v_pk_mul_f32 v[104:105], v[92:93], s[34:35] op_sel:[1,0]
	v_pk_add_f32 v[94:95], v[108:109], v[136:137] neg_lo:[0,1] neg_hi:[0,1]
	v_pk_fma_f32 v[98:99], v[146:147], s[8:9], v[98:99] op_sel:[1,0,0] op_sel_hi:[1,1,0]
	v_pk_fma_f32 v[92:93], v[92:93], s[28:29], v[104:105] op_sel_hi:[0,1,1]
	v_pk_add_f32 v[104:105], v[94:95], v[98:99]
	v_pk_add_f32 v[98:99], v[94:95], v[98:99] neg_lo:[0,1] neg_hi:[0,1]
	v_pk_add_f32 v[94:95], v[96:97], v[92:93]
	v_pk_add_f32 v[92:93], v[96:97], v[92:93] neg_lo:[0,1] neg_hi:[0,1]
	v_pk_add_f32 v[96:97], v[104:105], v[94:95]
	v_pk_add_f32 v[94:95], v[104:105], v[94:95] neg_lo:[0,1] neg_hi:[0,1]
	v_xor_b32_e32 v105, 0x80000000, v92
	v_mov_b32_e32 v104, v93
	s_mov_b32 s10, s20
	s_mov_b32 s11, s36
	v_pk_mul_f32 v[110:111], v[100:101], s[12:13] op_sel:[1,0]
	v_pk_add_f32 v[92:93], v[98:99], v[104:105]
	v_pk_add_f32 v[98:99], v[98:99], v[104:105] neg_lo:[0,1] neg_hi:[0,1]
	v_mul_f32_e32 v104, 0x3f3504f3, v112
	v_pk_fma_f32 v[100:101], v[100:101], s[10:11], v[110:111] op_sel_hi:[0,1,1]
	v_mul_f32_e32 v110, 0xbf3504f3, v107
	v_pk_fma_f32 v[104:105], v[112:113], s[8:9], v[104:105] op_sel:[1,0,0] op_sel_hi:[1,1,0]
	v_pk_fma_f32 v[106:107], v[106:107], s[8:9], v[110:111] op_sel_hi:[0,1,0]
	v_pk_add_f32 v[110:111], v[102:103], v[100:101]
	v_pk_add_f32 v[112:113], v[102:103], v[100:101] neg_lo:[0,1] neg_hi:[0,1]
	v_pk_add_f32 v[100:101], v[106:107], v[104:105]
	v_pk_add_f32 v[106:107], v[104:105], v[106:107] neg_lo:[0,1] neg_hi:[0,1]
	v_pk_add_f32 v[104:105], v[110:111], v[100:101]
	v_pk_add_f32 v[102:103], v[110:111], v[100:101] neg_lo:[0,1] neg_hi:[0,1]
	v_xor_b32_e32 v111, 0x80000000, v106
	v_mov_b32_e32 v110, v107
	v_pk_add_f32 v[100:101], v[112:113], v[110:111]
	v_pk_add_f32 v[106:107], v[112:113], v[110:111] neg_lo:[0,1] neg_hi:[0,1]
	v_pk_add_f32 v[110:111], v[148:149], v[150:151]
	s_mov_b32 s12, s28
	s_mov_b32 s13, s34
	s_mov_b32 s10, s34
	s_mov_b32 s11, s27
	v_pk_mul_f32 v[112:113], v[110:111], s[12:13] op_sel:[1,0]
	v_pk_add_f32 v[108:109], v[136:137], v[108:109]
	v_pk_fma_f32 v[110:111], v[110:111], s[10:11], v[112:113] op_sel_hi:[0,1,1]
	v_pk_add_f32 v[112:113], v[138:139], v[140:141]
	v_pk_add_f32 v[114:115], v[144:145], v[114:115]
	v_pk_mul_f32 v[136:137], v[112:113], s[34:35] op_sel:[1,0]
	s_nop 0
	v_pk_fma_f32 v[112:113], v[112:113], s[28:29], v[136:137] op_sel_hi:[0,1,1]
	v_mul_f32_e32 v136, 0xbf3504f3, v115
	v_pk_fma_f32 v[114:115], v[114:115], s[8:9], v[136:137] op_sel_hi:[0,1,0]
	v_pk_add_f32 v[136:137], v[108:109], v[114:115]
	v_pk_add_f32 v[138:139], v[108:109], v[114:115] neg_lo:[0,1] neg_hi:[0,1]
	v_pk_add_f32 v[108:109], v[112:113], v[110:111]
	v_pk_add_f32 v[112:113], v[112:113], v[110:111] neg_lo:[0,1] neg_hi:[0,1]
	v_pk_add_f32 v[110:111], v[136:137], v[108:109]
	v_pk_add_f32 v[108:109], v[136:137], v[108:109] neg_lo:[0,1] neg_hi:[0,1]
	v_xor_b32_e32 v137, 0x80000000, v112
	v_mov_b32_e32 v136, v113
	v_pk_add_f32 v[114:115], v[138:139], v[136:137]
	v_pk_add_f32 v[112:113], v[138:139], v[136:137] neg_lo:[0,1] neg_hi:[0,1]

.LBB0_1630:
	s_or_b64 exec, exec, s[6:7]
	s_waitcnt lgkmcnt(0)
	s_barrier
	s_and_saveexec_b64 s[6:7], vcc
	s_cbranch_execz .LBB0_1632
	ds_read_b64 v[172:173], v135 offset:32768
	v_cvt_f32_i32_e32 v86, v132
	v_lshlrev_b32_e32 v88, 3, v133
	v_lshlrev_b32_e32 v89, 3, v132
	v_mul_f32_e32 v86, 0x39000000, v86
	v_sin_f32_e32 v87, v86
	v_cos_f32_e32 v86, v86
	v_add3_u32 v92, 0, v88, v89
	ds_read_b64 v[174:175], v92
	v_xor_b32_e32 v90, 0x80000000, v87
	v_mov_b32_e32 v91, v86
	v_cvt_f32_i32_e32 v93, v130
	s_waitcnt lgkmcnt(1)
	v_pk_mul_f32 v[90:91], v[90:91], v[172:173] op_sel:[0,1]
	v_cvt_f32_i32_e32 v63, v63
	v_pk_fma_f32 v[84:85], v[86:87], v[172:173], v[90:91] op_sel_hi:[1,0,1]
	v_cvt_f32_i32_e32 v27, v27
	s_waitcnt lgkmcnt(0)
	v_pk_add_f32 v[84:85], v[174:175], v[84:85]
	ds_write_b64 v92, v[84:85]
	ds_read_b64 v[172:173], v134 offset:36864
	ds_read_b64 v[174:175], v127 offset:4096
	v_mul_f32_e32 v85, 0x39000000, v93
	v_cos_f32_e32 v84, v85
	v_sin_f32_e32 v85, v85
	v_cvt_f32_i32_e32 v92, v128
	v_mov_b32_e32 v91, v84
	v_xor_b32_e32 v90, 0x80000000, v85
	s_waitcnt lgkmcnt(1)
	v_pk_mul_f32 v[90:91], v[90:91], v[172:173] op_sel:[0,1]
	v_cvt_f32_i32_e32 v19, v19
	v_pk_fma_f32 v[84:85], v[84:85], v[172:173], v[90:91] op_sel_hi:[1,0,1]
	s_waitcnt lgkmcnt(0)
	v_pk_add_f32 v[84:85], v[174:175], v[84:85]
	ds_write_b64 v127, v[84:85] offset:4096
	ds_read_b64 v[172:173], v131 offset:40960
	ds_read_b64 v[174:175], v124 offset:8192
	v_mul_f32_e32 v85, 0x39000000, v92
	v_cos_f32_e32 v84, v85
	v_sin_f32_e32 v85, v85
	v_cvt_f32_i32_e32 v92, v125
	v_mov_b32_e32 v91, v84
	v_xor_b32_e32 v90, 0x80000000, v85
	s_waitcnt lgkmcnt(1)
	v_pk_mul_f32 v[90:91], v[90:91], v[172:173] op_sel:[0,1]
	s_nop 0
	v_pk_fma_f32 v[84:85], v[84:85], v[172:173], v[90:91] op_sel_hi:[1,0,1]
	s_waitcnt lgkmcnt(0)
	v_pk_add_f32 v[84:85], v[174:175], v[84:85]
	ds_write_b64 v124, v[84:85] offset:8192
	ds_read_b64 v[172:173], v129 offset:45056
	ds_read_b64 v[174:175], v67 offset:12288
	v_mul_f32_e32 v85, 0x39000000, v92
	v_cos_f32_e32 v84, v85
	v_sin_f32_e32 v85, v85
	v_cvt_f32_i32_e32 v92, v122
	v_mov_b32_e32 v91, v84
	v_xor_b32_e32 v90, 0x80000000, v85
	s_waitcnt lgkmcnt(1)
	v_pk_mul_f32 v[90:91], v[90:91], v[172:173] op_sel:[0,1]
	s_nop 0
	v_pk_fma_f32 v[84:85], v[84:85], v[172:173], v[90:91] op_sel_hi:[1,0,1]
	s_waitcnt lgkmcnt(0)
	v_pk_add_f32 v[84:85], v[174:175], v[84:85]
	ds_write_b64 v67, v[84:85] offset:12288
	ds_read_b64 v[172:173], v126 offset:49152
	ds_read_b64 v[174:175], v59 offset:16384
	v_mul_f32_e32 v67, 0x39000000, v92
	v_cos_f32_e32 v84, v67
	v_sin_f32_e32 v85, v67
	v_mov_b32_e32 v91, v84
	v_xor_b32_e32 v90, 0x80000000, v85
	s_waitcnt lgkmcnt(1)
	v_pk_mul_f32 v[90:91], v[90:91], v[172:173] op_sel:[0,1]
	s_nop 0
	v_pk_fma_f32 v[84:85], v[84:85], v[172:173], v[90:91] op_sel_hi:[1,0,1]
	s_waitcnt lgkmcnt(0)
	v_pk_add_f32 v[84:85], v[174:175], v[84:85]
	ds_write_b64 v59, v[84:85] offset:16384
	ds_read_b64 v[172:173], v123 offset:53248
	ds_read_b64 v[174:175], v23 offset:20480
	v_mul_f32_e32 v59, 0x39000000, v63
	v_cos_f32_e32 v84, v59
	v_sin_f32_e32 v85, v59
	v_mov_b32_e32 v91, v84
	v_xor_b32_e32 v90, 0x80000000, v85
	s_waitcnt lgkmcnt(1)
	v_pk_mul_f32 v[90:91], v[90:91], v[172:173] op_sel:[0,1]
	s_nop 0
	v_pk_fma_f32 v[84:85], v[84:85], v[172:173], v[90:91] op_sel_hi:[1,0,1]
	s_waitcnt lgkmcnt(0)
	v_pk_add_f32 v[84:85], v[174:175], v[84:85]
	ds_write_b64 v23, v[84:85] offset:20480
	ds_read_b64 v[172:173], v65 offset:57344
	ds_read_b64 v[174:175], v15 offset:24576
	v_mul_f32_e32 v23, 0x39000000, v27
	v_cos_f32_e32 v84, v23
	v_sin_f32_e32 v85, v23
	v_mov_b32_e32 v91, v84
	v_xor_b32_e32 v90, 0x80000000, v85
	s_waitcnt lgkmcnt(1)
	v_pk_mul_f32 v[90:91], v[90:91], v[172:173] op_sel:[0,1]
	s_nop 0
	v_pk_fma_f32 v[84:85], v[84:85], v[172:173], v[90:91] op_sel_hi:[1,0,1]
	s_waitcnt lgkmcnt(0)
	v_pk_add_f32 v[84:85], v[174:175], v[84:85]
	ds_write_b64 v15, v[84:85] offset:24576
	v_mul_f32_e32 v15, 0x39000000, v19
	v_cos_f32_e32 v84, v15
	v_sin_f32_e32 v85, v15
	ds_read_b64 v[86:87], v31 offset:61440
	ds_read_b64 v[88:89], v11 offset:28672
	v_mov_b32_e32 v91, v84
	v_xor_b32_e32 v90, 0x80000000, v85
	s_waitcnt lgkmcnt(1)
	v_pk_mul_f32 v[90:91], v[90:91], v[86:87] op_sel:[0,1]
	s_nop 0
	v_pk_fma_f32 v[84:85], v[84:85], v[86:87], v[90:91] op_sel_hi:[1,0,1]
	s_waitcnt lgkmcnt(0)
	v_pk_add_f32 v[84:85], v[88:89], v[84:85]
	ds_write_b64 v11, v[84:85] offset:28672
.LBB0_1632:
	s_or_b64 exec, exec, s[6:7]
	s_waitcnt lgkmcnt(0)
	s_barrier
	global_load_dword v84, v43, s[62:63]
	global_load_dword v88, v55, s[62:63]
	global_load_dword v86, v118, s[62:63]
	global_load_dword v90, v43, s[64:65]
	v_cmp_gt_i32_e64 s[6:7], s69, v64
	v_cmp_lt_i32_e32 vcc, 0, v64
	s_waitcnt vmcnt(19)
	v_mov_b32_e32 v92, v57
	v_cndmask_b32_e64 v15, 0, v64, s[6:7]
	s_waitcnt vmcnt(17)
	v_mov_b32_e32 v93, v61
	v_cmp_gt_i32_e64 s[8:9], s51, v64
	v_ashrrev_i32_e32 v19, 4, v15
	v_cndmask_b32_e32 v57, 0, v60, vcc
	v_cndmask_b32_e32 v56, 0, v56, vcc
	v_cvt_pkrtz_f16_f32 v11, v82, v83
	v_lshlrev_b32_e32 v19, 3, v19
	v_lshlrev_b32_e32 v15, 3, v15
	v_cndmask_b32_e64 v59, 0, v62, s[8:9]
	v_cndmask_b32_e64 v58, 0, v58, s[8:9]
	v_add_u32_e32 v65, 0x200, v64
	v_cmp_gt_i32_e64 s[18:19], s95, v64
	v_add3_u32 v15, 0, v19, v15
	ds_read_b64 v[172:173], v15
	v_add_u32_e32 v31, 0x400, v64
	v_cmp_gt_i32_e64 s[16:17], s75, v64
	v_add_u32_e32 v27, 0x600, v64
	v_cmp_gt_i32_e64 s[14:15], s74, v64
	v_add_u32_e32 v23, 0x800, v64
	v_cmp_gt_i32_e64 s[12:13], s68, v64
	v_add_u32_e32 v19, 0xa00, v64
	v_cmp_gt_i32_e64 s[8:9], s72, v64
	v_cmp_gt_i32_e32 vcc, s71, v64
	v_cmp_gt_i32_e64 s[10:11], s70, v64
	v_lshlrev_b32_e32 v98, 3, v64
	s_waitcnt vmcnt(0)
	v_pk_fma_f32 v[92:93], v[92:93], v[88:89], v[90:91] op_sel_hi:[1,0,0]
	s_nop 0
	v_pk_fma_f32 v[56:57], v[84:85], v[56:57], v[92:93] op_sel_hi:[0,1,1]
	v_pk_fma_f32 v[56:57], v[58:59], v[86:87], v[56:57] op_sel_hi:[1,0,1]
	v_cvt_f32_f16_e32 v58, v11
	v_cvt_f32_f16_sdwa v59, v11 dst_sel:DWORD dst_unused:UNUSED_PAD src0_sel:WORD_1
	v_cndmask_b32_e64 v11, 0, v65, s[18:19]
	v_ashrrev_i32_e32 v15, 4, v11
	v_lshlrev_b32_e32 v15, 3, v15
	v_lshlrev_b32_e32 v11, 3, v11
	v_add3_u32 v11, 0, v15, v11
	ds_read_b64 v[94:95], v11
	v_cndmask_b32_e64 v11, 0, v31, s[16:17]
	v_ashrrev_i32_e32 v15, 4, v11
	v_lshlrev_b32_e32 v15, 3, v15
	v_lshlrev_b32_e32 v11, 3, v11
	v_add3_u32 v11, 0, v15, v11
	ds_read_b64 v[92:93], v11
	v_cndmask_b32_e64 v11, 0, v27, s[14:15]
	v_ashrrev_i32_e32 v15, 4, v11
	v_lshlrev_b32_e32 v15, 3, v15
	v_lshlrev_b32_e32 v11, 3, v11
	v_add3_u32 v11, 0, v15, v11
	ds_read_b64 v[62:63], v11
	v_cndmask_b32_e64 v11, 0, v23, s[12:13]
	v_ashrrev_i32_e32 v15, 4, v11
	v_lshlrev_b32_e32 v15, 3, v15
	v_lshlrev_b32_e32 v11, 3, v11
	v_add3_u32 v11, 0, v15, v11
	ds_read_b64 v[60:61], v11
	v_cndmask_b32_e64 v11, 0, v19, s[8:9]
	v_ashrrev_i32_e32 v15, 4, v11
	v_lshlrev_b32_e32 v15, 3, v15
	v_lshlrev_b32_e32 v11, 3, v11
	s_waitcnt lgkmcnt(4)
	v_pk_fma_f32 v[58:59], v[66:67], v[58:59], v[172:173] op_sel_hi:[0,1,1]
	v_add3_u32 v11, 0, v15, v11
	v_add_u32_e32 v15, 0xc00, v64
	v_pk_mul_f32 v[82:83], v[56:57], v[58:59]
	ds_read_b64 v[58:59], v11
	v_cndmask_b32_e32 v11, 0, v15, vcc
	v_ashrrev_i32_e32 v56, 4, v11
	v_lshlrev_b32_e32 v56, 3, v56
	v_lshlrev_b32_e32 v11, 3, v11
	v_add3_u32 v11, 0, v56, v11
	ds_read_b64 v[56:57], v11
	v_add_u32_e32 v11, 0xe00, v64
	v_cndmask_b32_e64 v67, 0, v11, s[10:11]
	v_ashrrev_i32_e32 v85, 4, v67
	v_lshlrev_b32_e32 v85, 3, v85
	v_lshlrev_b32_e32 v67, 3, v67
	v_add3_u32 v67, 0, v85, v67
	ds_read_b64 v[96:97], v67
	s_waitcnt lgkmcnt(0)
	s_barrier
	s_and_saveexec_b64 s[66:67], s[6:7]
	v_ashrrev_i32_e32 v67, 4, v64
	v_lshlrev_b32_e32 v67, 3, v67
	v_add3_u32 v67, 0, v67, v98
	ds_write_b64 v67, v[82:83]
	s_or_b64 exec, exec, s[66:67]
	s_movk_i32 s2, 0xfe00
	v_cvt_pkrtz_f16_f32 v99, v80, v81
	v_cmp_lt_i32_e64 s[6:7], s2, v64
	v_mov_b32_e32 v80, v49
	v_mov_b32_e32 v81, v53
	v_cndmask_b32_e64 v49, 0, v52, s[6:7]
	v_cvt_f32_f16_e32 v52, v99
	v_cvt_f32_f16_sdwa v53, v99 dst_sel:DWORD dst_unused:UNUSED_PAD src0_sel:WORD_1
	v_mov_b32_e32 v89, v88
	v_mov_b32_e32 v91, v90
	s_movk_i32 s2, 0xdff
	v_mov_b32_e32 v85, v84
	v_pk_fma_f32 v[80:81], v[80:81], v[88:89], v[90:91]
	v_cndmask_b32_e64 v48, 0, v48, s[6:7]
	v_cmp_gt_i32_e64 s[6:7], s2, v64
	v_mov_b32_e32 v87, v86
	v_mov_b32_e32 v67, v66
	v_pk_fma_f32 v[48:49], v[84:85], v[48:49], v[80:81]
	v_cndmask_b32_e64 v81, 0, v54, s[6:7]
	v_cndmask_b32_e64 v80, 0, v50, s[6:7]
	v_pk_fma_f32 v[48:49], v[80:81], v[86:87], v[48:49]
	s_waitcnt lgkmcnt(6)
	v_pk_fma_f32 v[52:53], v[66:67], v[52:53], v[94:95]
	s_nop 0
	v_pk_mul_f32 v[80:81], v[48:49], v[52:53]
	s_and_saveexec_b64 s[6:7], s[18:19]
	v_ashrrev_i32_e32 v48, 4, v65
	v_lshlrev_b32_e32 v48, 3, v48
	v_add3_u32 v48, 0, v48, v98
	ds_write_b64 v48, v[80:81] offset:4096
	s_or_b64 exec, exec, s[6:7]
	s_movk_i32 s2, 0xfc00
	v_cvt_pkrtz_f16_f32 v50, v78, v79
	v_cmp_lt_i32_e64 s[6:7], s2, v64
	v_mov_b32_e32 v48, v45
	v_mov_b32_e32 v49, v41
	v_cndmask_b32_e64 v41, 0, v40, s[6:7]
	v_cndmask_b32_e64 v40, 0, v44, s[6:7]
	v_cvt_f32_f16_e32 v44, v50
	v_cvt_f32_f16_sdwa v45, v50 dst_sel:DWORD dst_unused:UNUSED_PAD src0_sel:WORD_1
	s_movk_i32 s2, 0xbff
	v_pk_fma_f32 v[48:49], v[48:49], v[88:89], v[90:91]
	v_cmp_gt_i32_e64 s[6:7], s2, v64
	v_pk_fma_f32 v[40:41], v[84:85], v[40:41], v[48:49]
	s_waitcnt lgkmcnt(5)
	v_pk_fma_f32 v[44:45], v[66:67], v[44:45], v[92:93]
	v_cndmask_b32_e64 v49, 0, v42, s[6:7]
	v_cndmask_b32_e64 v48, 0, v46, s[6:7]
	v_pk_fma_f32 v[40:41], v[48:49], v[86:87], v[40:41]
	s_nop 0
	v_pk_mul_f32 v[78:79], v[40:41], v[44:45]
	s_and_saveexec_b64 s[6:7], s[16:17]
	v_ashrrev_i32_e32 v31, 4, v31
	v_lshlrev_b32_e32 v31, 3, v31
	v_add3_u32 v31, 0, v31, v98
	ds_write_b64 v31, v[78:79] offset:8192
	s_or_b64 exec, exec, s[6:7]
	s_movk_i32 s2, 0xfa00
	v_cvt_pkrtz_f16_f32 v31, v76, v77
	v_cmp_lt_i32_e64 s[6:7], s2, v64
	v_mov_b32_e32 v40, v33
	v_mov_b32_e32 v41, v37
	v_cndmask_b32_e64 v33, 0, v36, s[6:7]
	v_cvt_f32_f16_e32 v36, v31
	v_cvt_f32_f16_sdwa v37, v31 dst_sel:DWORD dst_unused:UNUSED_PAD src0_sel:WORD_1
	s_movk_i32 s2, 0x9ff
	v_pk_fma_f32 v[40:41], v[40:41], v[88:89], v[90:91]
	v_cndmask_b32_e64 v32, 0, v32, s[6:7]
	v_cmp_gt_i32_e64 s[6:7], s2, v64
	v_pk_fma_f32 v[32:33], v[84:85], v[32:33], v[40:41]
	s_waitcnt lgkmcnt(4)
	v_pk_fma_f32 v[36:37], v[66:67], v[36:37], v[62:63]
	v_cndmask_b32_e64 v41, 0, v38, s[6:7]
	v_cndmask_b32_e64 v40, 0, v34, s[6:7]
	v_pk_fma_f32 v[32:33], v[40:41], v[86:87], v[32:33]
	s_nop 0
	v_pk_mul_f32 v[76:77], v[32:33], v[36:37]
	s_and_saveexec_b64 s[6:7], s[14:15]
	v_ashrrev_i32_e32 v27, 4, v27
	v_lshlrev_b32_e32 v27, 3, v27
	v_add3_u32 v27, 0, v27, v98
	ds_write_b64 v27, v[76:77] offset:12288
	s_or_b64 exec, exec, s[6:7]
	s_movk_i32 s2, 0xf800
	v_cvt_pkrtz_f16_f32 v27, v74, v75
	v_cmp_lt_i32_e64 s[6:7], s2, v64
	v_mov_b32_e32 v32, v25
	v_mov_b32_e32 v33, v29
	v_cndmask_b32_e64 v25, 0, v28, s[6:7]
	v_cvt_f32_f16_e32 v28, v27
	v_cvt_f32_f16_sdwa v29, v27 dst_sel:DWORD dst_unused:UNUSED_PAD src0_sel:WORD_1
	v_pk_fma_f32 v[32:33], v[32:33], v[88:89], v[90:91]
	v_cndmask_b32_e64 v24, 0, v24, s[6:7]
	v_cmp_gt_i32_e64 s[6:7], s43, v64
	v_pk_fma_f32 v[24:25], v[84:85], v[24:25], v[32:33]
	s_nop 0
	v_cndmask_b32_e64 v27, 0, v30, s[6:7]
	v_cndmask_b32_e64 v26, 0, v26, s[6:7]
	v_pk_fma_f32 v[24:25], v[26:27], v[86:87], v[24:25]
	s_waitcnt lgkmcnt(3)
	v_pk_fma_f32 v[26:27], v[66:67], v[28:29], v[60:61]
	s_nop 0
	v_pk_mul_f32 v[74:75], v[24:25], v[26:27]
	s_and_saveexec_b64 s[6:7], s[12:13]
	v_ashrrev_i32_e32 v23, 4, v23
	v_lshlrev_b32_e32 v23, 3, v23
	v_add3_u32 v23, 0, v23, v98
	ds_write_b64 v23, v[74:75] offset:16384
	s_or_b64 exec, exec, s[6:7]
	s_movk_i32 s2, 0xf600
	v_cvt_pkrtz_f16_f32 v23, v72, v73
	v_cmp_lt_i32_e64 s[6:7], s2, v64
	v_mov_b32_e32 v24, v17
	v_mov_b32_e32 v25, v21
	v_cndmask_b32_e64 v17, 0, v20, s[6:7]
	v_cvt_f32_f16_e32 v20, v23
	v_cvt_f32_f16_sdwa v21, v23 dst_sel:DWORD dst_unused:UNUSED_PAD src0_sel:WORD_1
	s_movk_i32 s2, 0x5ff
	v_pk_fma_f32 v[24:25], v[24:25], v[88:89], v[90:91]
	v_cndmask_b32_e64 v16, 0, v16, s[6:7]
	v_cmp_gt_i32_e64 s[6:7], s2, v64
	v_pk_fma_f32 v[16:17], v[84:85], v[16:17], v[24:25]
	s_waitcnt lgkmcnt(2)
	v_pk_fma_f32 v[20:21], v[66:67], v[20:21], v[58:59]
	v_cndmask_b32_e64 v23, 0, v22, s[6:7]
	v_cndmask_b32_e64 v22, 0, v18, s[6:7]
	v_pk_fma_f32 v[16:17], v[22:23], v[86:87], v[16:17]
	s_nop 0
	v_pk_mul_f32 v[72:73], v[16:17], v[20:21]
	s_and_saveexec_b64 s[6:7], s[8:9]
	v_ashrrev_i32_e32 v16, 4, v19
	v_lshlrev_b32_e32 v16, 3, v16
	v_add3_u32 v16, 0, v16, v98
	ds_write_b64 v16, v[72:73] offset:20480
	s_or_b64 exec, exec, s[6:7]
	s_movk_i32 s2, 0xf400
	v_cvt_pkrtz_f16_f32 v18, v68, v69
	v_cmp_lt_i32_e64 s[6:7], s2, v64
	v_mov_b32_e32 v16, v9
	v_mov_b32_e32 v17, v13
	v_cndmask_b32_e64 v9, 0, v12, s[6:7]
	v_cvt_f32_f16_e32 v12, v18
	v_cvt_f32_f16_sdwa v13, v18 dst_sel:DWORD dst_unused:UNUSED_PAD src0_sel:WORD_1
	s_movk_i32 s2, 0x3ff
	v_pk_fma_f32 v[16:17], v[16:17], v[88:89], v[90:91]
	v_cndmask_b32_e64 v8, 0, v8, s[6:7]
	v_cmp_gt_i32_e64 s[6:7], s2, v64
	v_pk_fma_f32 v[8:9], v[84:85], v[8:9], v[16:17]
	s_waitcnt lgkmcnt(1)
	v_pk_fma_f32 v[12:13], v[66:67], v[12:13], v[56:57]
	v_cndmask_b32_e64 v17, 0, v14, s[6:7]
	v_cndmask_b32_e64 v16, 0, v10, s[6:7]
	v_pk_fma_f32 v[8:9], v[16:17], v[86:87], v[8:9]
	s_nop 0
	v_pk_mul_f32 v[68:69], v[8:9], v[12:13]
	s_and_saveexec_b64 s[6:7], vcc
	v_ashrrev_i32_e32 v8, 4, v15
	v_lshlrev_b32_e32 v8, 3, v8
	v_add3_u32 v8, 0, v8, v98
	ds_write_b64 v8, v[68:69] offset:24576
	s_or_b64 exec, exec, s[6:7]
	s_movk_i32 s2, 0xf200
	v_cvt_pkrtz_f16_f32 v10, v70, v71
	v_cmp_lt_i32_e32 vcc, s2, v64
	s_nop 1
	v_cndmask_b32_e32 v9, 0, v4, vcc
	v_cndmask_b32_e32 v8, 0, v0, vcc
	v_mov_b32_e32 v4, v1
	v_cvt_f32_f16_e32 v0, v10
	v_cvt_f32_f16_sdwa v1, v10 dst_sel:DWORD dst_unused:UNUSED_PAD src0_sel:WORD_1
	v_cmp_gt_i32_e32 vcc, s25, v64
	v_pk_fma_f32 v[4:5], v[4:5], v[88:89], v[90:91]
	s_waitcnt lgkmcnt(0)
	v_pk_fma_f32 v[0:1], v[66:67], v[0:1], v[96:97]
	v_cndmask_b32_e32 v13, 0, v6, vcc
	v_cndmask_b32_e32 v12, 0, v2, vcc
	v_pk_fma_f32 v[4:5], v[84:85], v[8:9], v[4:5]
	s_nop 0
	v_pk_fma_f32 v[4:5], v[12:13], v[86:87], v[4:5]
	s_nop 0
	v_pk_mul_f32 v[66:67], v[4:5], v[0:1]
	s_and_saveexec_b64 s[6:7], s[10:11]
	v_ashrrev_i32_e32 v0, 4, v11
	v_lshlrev_b32_e32 v0, 3, v0
	v_add3_u32 v0, 0, v0, v98
	ds_write_b64 v0, v[66:67] offset:28672
	s_or_b64 exec, exec, s[6:7]
	v_readlane_b32 s4, v240, 22
	s_mul_hi_i32 s2, s42, 0x8800
	s_mul_i32 s42, s42, 0x8800
	v_readlane_b32 s6, v240, 24
	v_readlane_b32 s12, v240, 30
	v_readlane_b32 s7, v240, 25
	v_readlane_b32 s13, v240, 31
	s_add_u32 s6, s12, s42
	s_addc_u32 s7, s13, s2
	v_ashrrev_i32_e32 v65, 31, v64
	v_lshl_add_u64 v[4:5], v[64:65], 2, s[6:7]
	v_add_co_u32_e32 v0, vcc, s94, v4
	global_load_dwordx3 v[56:58], v[4:5], off offset:-4
	global_load_dwordx3 v[48:50], v[4:5], off offset:2044
	v_addc_co_u32_e32 v1, vcc, 0, v5, vcc
	v_add_co_u32_e32 v8, vcc, s1, v4
	v_mov_b32_e32 v126, v64
	s_nop 0
	v_addc_co_u32_e32 v9, vcc, 0, v5, vcc
	v_add_co_u32_e32 v10, vcc, s69, v4
	global_load_dwordx3 v[60:62], v[0:1], off offset:4092
	global_load_dwordx3 v[52:54], v[8:9], off offset:2044
	v_addc_co_u32_e32 v11, vcc, 0, v5, vcc
	global_load_dwordx3 v[40:42], v[8:9], off offset:4092
	global_load_dwordx3 v[32:34], v[10:11], off offset:2044
	v_add_co_u32_e32 v8, vcc, s24, v4
	v_mov_b32_e32 v114, 0
	s_nop 0
	v_addc_co_u32_e32 v9, vcc, 0, v5, vcc
	global_load_dwordx3 v[36:38], v[8:9], off offset:2044
	global_load_dwordx3 v[28:30], v[10:11], off offset:4092
	v_add_co_u32_e32 v10, vcc, s73, v4
	v_mov_b32_e32 v115, 0
	s_nop 0
	v_addc_co_u32_e32 v11, vcc, 0, v5, vcc
	v_add_co_u32_e32 v12, vcc, s46, v4
	global_load_dwordx3 v[24:26], v[8:9], off offset:4092
	global_load_dwordx3 v[16:18], v[10:11], off offset:2044
	v_addc_co_u32_e32 v13, vcc, 0, v5, vcc
	global_load_dwordx3 v[20:22], v[12:13], off offset:2044
	s_nop 0
	global_load_dwordx3 v[8:10], v[10:11], off offset:4092
	s_nop 0
	global_load_dwordx3 v[44:46], v[4:5], off offset:4092
	s_nop 0
	global_load_dwordx3 v[0:2], v[0:1], off offset:2044
	v_add_co_u32_e32 v4, vcc, s47, v4
	v_mov_b32_e32 v88, 0
	s_nop 0
	v_addc_co_u32_e32 v5, vcc, 0, v5, vcc
	global_load_dwordx3 v[12:14], v[12:13], off offset:4092
	s_nop 0
	global_load_dwordx3 v[4:6], v[4:5], off offset:2044
	s_waitcnt lgkmcnt(0)
	s_barrier
	v_mov_b32_e32 v89, v114
	v_add_u32_e32 v124, 0x200, v126
	v_lshl_add_u32 v127, v126, 3, 0
	v_ashrrev_i32_e32 v11, 4, v124
	v_add_u32_e32 v123, 0x400, v126
	v_lshl_add_u32 v122, v11, 3, v127
	v_ashrrev_i32_e32 v11, 4, v123
	v_add_u32_e32 v117, 0x600, v126
	v_lshl_add_u32 v116, v11, 3, v127
	v_ashrrev_i32_e32 v11, 4, v117
	v_add_u32_e32 v65, 0x800, v126
	v_lshl_add_u32 v63, v11, 3, v127
	v_ashrrev_i32_e32 v11, 4, v65
	v_add_u32_e32 v59, 0xa00, v126
	v_lshl_add_u32 v31, v11, 3, v127
	v_ashrrev_i32_e32 v11, 4, v59
	v_add_u32_e32 v27, 0xc00, v126
	v_lshl_add_u32 v23, v11, 3, v127
	v_ashrrev_i32_e32 v11, 4, v27
	v_add_u32_e32 v19, 0xe00, v126
	v_ashrrev_i32_e32 v125, 4, v126
	v_lshl_add_u32 v15, v11, 3, v127
	v_ashrrev_i32_e32 v11, 4, v19
	v_cmp_gt_i32_e32 vcc, s70, v126
	v_lshl_add_u32 v134, v125, 3, v127
	v_lshl_add_u32 v11, v11, 3, v127
	v_mov_b32_e32 v96, v114
	v_mov_b32_e32 v97, v114
	v_mov_b32_e32 v104, v114
	v_mov_b32_e32 v105, v114
	v_mov_b32_e32 v110, v114
	v_mov_b32_e32 v111, v114
	v_mov_b32_e32 v86, v114
	v_mov_b32_e32 v87, v114
	v_mov_b32_e32 v94, v114
	v_mov_b32_e32 v95, v114
	v_mov_b32_e32 v102, v114
	v_mov_b32_e32 v103, v114
	v_mov_b32_e32 v108, v114
	v_mov_b32_e32 v109, v114
	v_mov_b32_e32 v84, v114
	v_mov_b32_e32 v85, v114
	v_mov_b32_e32 v92, v114
	v_mov_b32_e32 v93, v114
	v_mov_b32_e32 v100, v114
	v_mov_b32_e32 v101, v114
	v_mov_b32_e32 v106, v114
	v_mov_b32_e32 v107, v114
	v_mov_b32_e32 v70, v114
	v_mov_b32_e32 v71, v114
	v_mov_b32_e32 v90, v114
	v_mov_b32_e32 v91, v114
	v_mov_b32_e32 v98, v114
	v_mov_b32_e32 v99, v114
	v_mov_b32_e32 v112, v114
	v_mov_b32_e32 v113, v114
	v_readlane_b32 s5, v240, 23
	v_readlane_b32 s8, v240, 26
	v_readlane_b32 s9, v240, 27
	v_readlane_b32 s10, v240, 28
	v_readlane_b32 s11, v240, 29
	v_readlane_b32 s14, v240, 32
	v_readlane_b32 s15, v240, 33
	v_readlane_b32 s16, v240, 34
	v_readlane_b32 s17, v240, 35
	v_readlane_b32 s18, v240, 36
	v_readlane_b32 s19, v240, 37
	s_and_saveexec_b64 s[6:7], vcc
	s_xor_b64 s[6:7], exec, s[6:7]
	s_cbranch_execz .LBB0_1650
	ds_read_b64 v[172:173], v134
	ds_read_b64 v[174:175], v122 offset:4096
	ds_read_b64 v[176:177], v116 offset:8192
	ds_read_b64 v[178:179], v63 offset:12288
	ds_read_b64 v[180:181], v31 offset:16384
	ds_read_b64 v[182:183], v23 offset:20480
	ds_read_b64 v[184:185], v15 offset:24576
	ds_read_b64 v[186:187], v11 offset:28672
	s_waitcnt lgkmcnt(7)
	v_pk_add_f32 v[90:91], v[172:173], 0 op_sel_hi:[1,0]
	s_waitcnt lgkmcnt(3)
	v_pk_add_f32 v[92:93], v[180:181], 0 op_sel_hi:[1,0]
	v_xor_b32_e32 v115, 0x80000000, v180
	v_pk_add_f32 v[94:95], v[90:91], v[92:93]
	v_pk_add_f32 v[98:99], v[90:91], v[92:93] neg_lo:[0,1] neg_hi:[0,1]
	v_mov_b32_e32 v114, v181
	v_pk_add_f32 v[70:71], v[174:175], 0 op_sel_hi:[1,0]
	s_waitcnt lgkmcnt(2)
	v_pk_add_f32 v[92:93], v[182:183], 0 op_sel_hi:[1,0]
	v_xor_b32_e32 v129, 0x80000000, v182
	v_pk_add_f32 v[96:97], v[70:71], v[92:93]
	v_pk_add_f32 v[100:101], v[70:71], v[92:93] neg_lo:[0,1] neg_hi:[0,1]
	v_mov_b32_e32 v128, v183
	v_pk_add_f32 v[70:71], v[176:177], 0 op_sel_hi:[1,0]
	s_waitcnt lgkmcnt(1)
	v_pk_add_f32 v[84:85], v[184:185], 0 op_sel_hi:[1,0]
	v_xor_b32_e32 v131, 0x80000000, v184
	v_pk_add_f32 v[102:103], v[70:71], v[84:85]
	v_pk_add_f32 v[104:105], v[70:71], v[84:85] neg_lo:[0,1] neg_hi:[0,1]
	v_pk_add_f32 v[70:71], v[178:179], 0 op_sel_hi:[1,0]
	s_waitcnt lgkmcnt(0)
	v_pk_add_f32 v[84:85], v[186:187], 0 op_sel_hi:[1,0]
	v_mov_b32_e32 v130, v185
	v_pk_add_f32 v[86:87], v[70:71], v[84:85]
	v_pk_add_f32 v[136:137], v[70:71], v[84:85] neg_lo:[0,1] neg_hi:[0,1]
	v_pk_add_f32 v[70:71], v[94:95], v[102:103]
	v_pk_add_f32 v[84:85], v[96:97], v[86:87]
	v_pk_add_f32 v[86:87], v[96:97], v[86:87] neg_lo:[0,1] neg_hi:[0,1]
	v_pk_add_f32 v[92:93], v[174:175], v[128:129]
	v_xor_b32_e32 v139, 0x80000000, v186
	v_mov_b32_e32 v138, v187
	v_pk_add_f32 v[94:95], v[94:95], v[102:103] neg_lo:[0,1] neg_hi:[0,1]
	v_pk_add_f32 v[88:89], v[70:71], v[84:85]
	v_pk_add_f32 v[84:85], v[70:71], v[84:85] neg_lo:[0,1] neg_hi:[0,1]
	v_xor_b32_e32 v71, 0x80000000, v86
	v_mov_b32_e32 v70, v87
	s_mov_b32 s29, s26
	v_pk_add_f32 v[132:133], v[176:177], v[130:131]
	v_pk_add_f32 v[140:141], v[178:179], v[138:139]
	v_pk_add_f32 v[86:87], v[94:95], v[70:71]
	v_pk_add_f32 v[70:71], v[94:95], v[70:71] neg_lo:[0,1] neg_hi:[0,1]
	v_pk_mul_f32 v[94:95], v[92:93], s[28:29] op_sel:[1,0]
	s_mov_b32 s8, s26
	s_mov_b32 s9, s28
	v_pk_fma_f32 v[92:93], v[92:93], s[26:27], v[94:95] op_sel_hi:[0,1,1]
	v_mul_f32_e32 v94, 0x3f3504f3, v133
	s_mov_b32 s29, s34
	v_pk_mul_f32 v[96:97], v[140:141], s[8:9] op_sel:[1,0]
	v_pk_add_f32 v[90:91], v[172:173], v[114:115]
	v_pk_fma_f32 v[94:95], v[132:133], s[30:31], v[94:95] op_sel_hi:[0,1,0]
	v_pk_fma_f32 v[96:97], v[140:141], s[28:29], v[96:97] op_sel_hi:[0,1,1]
	v_pk_add_f32 v[102:103], v[90:91], v[94:95]
	v_pk_add_f32 v[90:91], v[90:91], v[94:95] neg_lo:[0,1] neg_hi:[0,1]
	v_pk_add_f32 v[94:95], v[92:93], v[96:97]
	v_pk_add_f32 v[132:133], v[92:93], v[96:97] neg_lo:[0,1] neg_hi:[0,1]
	v_pk_add_f32 v[96:97], v[102:103], v[94:95]
	v_pk_add_f32 v[92:93], v[102:103], v[94:95] neg_lo:[0,1] neg_hi:[0,1]
	v_xor_b32_e32 v103, 0x80000000, v132
	v_mov_b32_e32 v102, v133
	v_pk_add_f32 v[94:95], v[90:91], v[102:103]
	v_pk_add_f32 v[90:91], v[90:91], v[102:103] neg_lo:[0,1] neg_hi:[0,1]
	v_mul_f32_e32 v102, 0x3f3504f3, v101
	s_mov_b32 s37, s20
	v_pk_fma_f32 v[100:101], v[100:101], s[30:31], v[102:103] op_sel_hi:[0,1,0]
	v_pk_mul_f32 v[102:103], v[104:105], s[36:37] op_sel:[1,0]
	v_pk_add_f32 v[108:109], v[174:175], v[128:129] neg_lo:[0,1] neg_hi:[0,1]
	v_pk_fma_f32 v[102:103], v[104:105], s[20:21], v[102:103] op_sel_hi:[0,1,1]
	v_mul_f32_e32 v104, 0xbf3504f3, v136
	v_pk_fma_f32 v[104:105], v[136:137], s[30:31], v[104:105] op_sel:[1,0,0] op_sel_hi:[1,1,0]
	v_pk_add_f32 v[132:133], v[98:99], v[102:103]
	v_pk_add_f32 v[98:99], v[98:99], v[102:103] neg_lo:[0,1] neg_hi:[0,1]
	v_pk_add_f32 v[102:103], v[100:101], v[104:105]
	v_pk_add_f32 v[136:137], v[100:101], v[104:105] neg_lo:[0,1] neg_hi:[0,1]
	v_pk_add_f32 v[104:105], v[132:133], v[102:103]
	v_pk_add_f32 v[100:101], v[132:133], v[102:103] neg_lo:[0,1] neg_hi:[0,1]
	v_xor_b32_e32 v133, 0x80000000, v136
	v_mov_b32_e32 v132, v137
	v_pk_add_f32 v[112:113], v[178:179], v[138:139] neg_lo:[0,1] neg_hi:[0,1]
	s_mov_b32 s10, s27
	s_mov_b32 s11, s34
	v_pk_add_f32 v[106:107], v[172:173], v[114:115] neg_lo:[0,1] neg_hi:[0,1]
	v_pk_mul_f32 v[114:115], v[108:109], s[8:9] op_sel:[1,0]
	v_pk_add_f32 v[110:111], v[176:177], v[130:131] neg_lo:[0,1] neg_hi:[0,1]
	v_pk_add_f32 v[102:103], v[98:99], v[132:133]
	v_pk_add_f32 v[98:99], v[98:99], v[132:133] neg_lo:[0,1] neg_hi:[0,1]
	s_mov_b32 s35, s28
	v_pk_mul_f32 v[132:133], v[112:113], s[10:11] op_sel:[1,0]
	v_pk_fma_f32 v[108:109], v[108:109], s[28:29], v[114:115] op_sel_hi:[0,1,1]
	v_mul_f32_e32 v114, 0xbf3504f3, v110
	v_pk_fma_f32 v[112:113], v[112:113], s[34:35], v[132:133] op_sel_hi:[0,1,1]
	v_pk_fma_f32 v[110:111], v[110:111], s[30:31], v[114:115] op_sel:[1,0,0] op_sel_hi:[1,1,0]
	s_nop 0
	v_pk_add_f32 v[114:115], v[106:107], v[110:111]
	v_pk_add_f32 v[128:129], v[106:107], v[110:111] neg_lo:[0,1] neg_hi:[0,1]
	v_pk_add_f32 v[106:107], v[108:109], v[112:113]
	v_pk_add_f32 v[108:109], v[108:109], v[112:113] neg_lo:[0,1] neg_hi:[0,1]
	v_pk_add_f32 v[110:111], v[114:115], v[106:107]
	v_xor_b32_e32 v113, 0x80000000, v108
	v_mov_b32_e32 v112, v109
	v_pk_add_f32 v[106:107], v[114:115], v[106:107] neg_lo:[0,1] neg_hi:[0,1]
	v_pk_add_f32 v[114:115], v[128:129], v[112:113] neg_lo:[0,1] neg_hi:[0,1]
	v_pk_add_f32 v[108:109], v[128:129], v[112:113]
	v_mov_b32_e32 v112, v114
	v_mov_b32_e32 v113, v115

.LBB0_1652:
	s_or_b64 exec, exec, s[6:7]
	v_add_u32_e32 v114, 0x1000, v126
	v_ashrrev_i32_e32 v114, 4, v114
	v_lshlrev_b32_e32 v114, 3, v114
	v_lshlrev_b32_e32 v133, 3, v126
	v_add3_u32 v132, 0, v114, v133
	v_add_u32_e32 v114, 0x1200, v126
	v_ashrrev_i32_e32 v114, 4, v114
	v_lshlrev_b32_e32 v114, 3, v114
	v_add3_u32 v131, 0, v114, v133
	v_add_u32_e32 v114, 0x1400, v126
	v_ashrrev_i32_e32 v114, 4, v114
	v_lshlrev_b32_e32 v114, 3, v114
	v_add3_u32 v130, 0, v114, v133
	v_add_u32_e32 v114, 0x1600, v126
	v_ashrrev_i32_e32 v114, 4, v114
	v_lshlrev_b32_e32 v114, 3, v114
	v_add3_u32 v129, 0, v114, v133
	v_add_u32_e32 v114, 0x1800, v126
	v_ashrrev_i32_e32 v114, 4, v114
	v_lshlrev_b32_e32 v114, 3, v114
	v_add3_u32 v128, 0, v114, v133
	v_add_u32_e32 v114, 0x1a00, v126
	v_ashrrev_i32_e32 v114, 4, v114
	v_lshlrev_b32_e32 v114, 3, v114
	v_add3_u32 v127, 0, v114, v133
	v_add_u32_e32 v114, 0x1c00, v126
	v_ashrrev_i32_e32 v114, 4, v114
	v_lshlrev_b32_e32 v114, 3, v114
	v_add3_u32 v115, 0, v114, v133
	v_add_u32_e32 v114, 0x1e00, v126
	v_ashrrev_i32_e32 v114, 4, v114
	s_waitcnt lgkmcnt(0)
	s_barrier
	v_lshlrev_b32_e32 v114, 3, v114
	v_add3_u32 v114, 0, v114, v133
	s_and_saveexec_b64 s[6:7], vcc
	s_cbranch_execz .LBB0_1654
	ds_read_b64 v[172:173], v134
	ds_read_b64 v[174:175], v122 offset:4096
	ds_read_b64 v[176:177], v116 offset:8192
	ds_read_b64 v[178:179], v63 offset:12288
	ds_read_b64 v[180:181], v31 offset:16384
	ds_read_b64 v[182:183], v23 offset:20480
	ds_read_b64 v[184:185], v15 offset:24576
	ds_read_b64 v[186:187], v11 offset:28672
	ds_read_b64 v[188:189], v132 offset:32768
	ds_read_b64 v[190:191], v131 offset:36864
	ds_read_b64 v[192:193], v130 offset:40960
	ds_read_b64 v[194:195], v129 offset:45056
	ds_read_b64 v[196:197], v128 offset:49152
	ds_read_b64 v[198:199], v127 offset:53248
	ds_read_b64 v[200:201], v115 offset:57344
	v_and_b32_e32 v106, 15, v126
	v_cvt_f32_ubyte0_e32 v106, v106
	v_mul_f32_e32 v107, 0x3b800000, v106
	v_cos_f32_e32 v106, v107
	v_sin_f32_e32 v108, v107
	s_waitcnt lgkmcnt(14)
	ds_read_b64 v[202:203], v114 offset:61440
	v_mov_b32_e32 v109, v106
	v_xor_b32_e32 v107, 0x80000000, v108
	v_pk_mul_f32 v[140:141], v[108:109], v[108:109] op_sel_hi:[1,0] neg_lo:[0,1] neg_hi:[0,1]
	s_mov_b32 s29, s26
	v_pk_fma_f32 v[140:141], v[106:107], v[106:107], v[140:141] op_sel_hi:[1,0,1]
	s_mov_b32 s8, s26
	v_pk_mul_f32 v[142:143], v[108:109], v[140:141] op_sel:[0,1]
	s_mov_b32 s9, s28
	v_pk_fma_f32 v[142:143], v[106:107], v[140:141], v[142:143] op_sel_hi:[1,0,1]
	s_mov_b32 s37, s20
	v_pk_mul_f32 v[144:145], v[108:109], v[142:143] op_sel:[0,1]
	s_mov_b32 s10, s27
	v_pk_fma_f32 v[144:145], v[106:107], v[142:143], v[144:145] op_sel_hi:[1,0,1]
	s_mov_b32 s11, s34
	v_pk_mul_f32 v[146:147], v[108:109], v[144:145] op_sel:[0,1]
	s_mov_b32 s35, s28
	v_pk_fma_f32 v[146:147], v[106:107], v[144:145], v[146:147] op_sel_hi:[1,0,1]
	s_nop 0
	v_pk_mul_f32 v[148:149], v[108:109], v[146:147] op_sel:[0,1]
	s_nop 0
	v_pk_fma_f32 v[148:149], v[106:107], v[146:147], v[148:149] op_sel_hi:[1,0,1]
	s_nop 0
	v_pk_mul_f32 v[150:151], v[108:109], v[148:149] op_sel:[0,1]
	s_nop 0
	v_pk_fma_f32 v[150:151], v[106:107], v[148:149], v[150:151] op_sel_hi:[1,0,1]
	s_nop 0
	v_pk_mul_f32 v[152:153], v[108:109], v[150:151] op_sel:[0,1]
	s_nop 0
	v_pk_fma_f32 v[152:153], v[106:107], v[150:151], v[152:153] op_sel_hi:[1,0,1]
	s_nop 0
	v_pk_mul_f32 v[154:155], v[108:109], v[152:153] op_sel:[0,1]
	s_nop 0
	v_pk_fma_f32 v[154:155], v[106:107], v[152:153], v[154:155] op_sel_hi:[1,0,1]
	s_nop 0
	v_pk_mul_f32 v[156:157], v[108:109], v[154:155] op_sel:[0,1]
	s_nop 0
	v_pk_fma_f32 v[156:157], v[106:107], v[154:155], v[156:157] op_sel_hi:[1,0,1]
	s_nop 0
	v_pk_mul_f32 v[158:159], v[108:109], v[156:157] op_sel:[0,1]
	s_nop 0
	v_pk_fma_f32 v[158:159], v[106:107], v[156:157], v[158:159] op_sel_hi:[1,0,1]
	s_nop 0
	v_pk_mul_f32 v[160:161], v[108:109], v[158:159] op_sel:[0,1]
	s_nop 0
	v_pk_fma_f32 v[160:161], v[106:107], v[158:159], v[160:161] op_sel_hi:[1,0,1]
	s_nop 0
	v_pk_mul_f32 v[162:163], v[108:109], v[160:161] op_sel:[0,1]
	s_nop 0
	v_pk_fma_f32 v[162:163], v[106:107], v[160:161], v[162:163] op_sel_hi:[1,0,1]
	s_nop 0
	v_pk_mul_f32 v[164:165], v[108:109], v[162:163] op_sel:[0,1]
	s_nop 0
	v_pk_fma_f32 v[164:165], v[106:107], v[162:163], v[164:165] op_sel_hi:[1,0,1]
	s_nop 0
	v_pk_mul_f32 v[166:167], v[108:109], v[164:165] op_sel:[0,1]
	s_waitcnt lgkmcnt(14)
	v_pk_mul_f32 v[108:109], v[108:109], v[174:175] op_sel:[0,1]
	v_pk_fma_f32 v[166:167], v[106:107], v[164:165], v[166:167] op_sel_hi:[1,0,1]
	v_pk_fma_f32 v[84:85], v[106:107], v[174:175], v[108:109] op_sel_hi:[1,0,1]
	v_xor_b32_e32 v168, 0x80000000, v167
	v_mov_b32_e32 v169, v166
	s_waitcnt lgkmcnt(0)
	v_pk_mul_f32 v[168:169], v[168:169], v[202:203] op_sel:[0,1]
	s_nop 0
	v_pk_fma_f32 v[138:139], v[166:167], v[202:203], v[168:169] op_sel_hi:[1,0,1]
	v_xor_b32_e32 v166, 0x80000000, v165
	v_mov_b32_e32 v167, v164
	v_pk_mul_f32 v[166:167], v[166:167], v[200:201] op_sel:[0,1]
	s_nop 0
	v_pk_fma_f32 v[136:137], v[164:165], v[200:201], v[166:167] op_sel_hi:[1,0,1]
	v_xor_b32_e32 v164, 0x80000000, v163
	v_mov_b32_e32 v165, v162
	v_pk_mul_f32 v[164:165], v[164:165], v[198:199] op_sel:[0,1]
	s_nop 0
	v_pk_fma_f32 v[112:113], v[162:163], v[198:199], v[164:165] op_sel_hi:[1,0,1]
	v_xor_b32_e32 v162, 0x80000000, v161
	v_mov_b32_e32 v163, v160
	v_pk_mul_f32 v[162:163], v[162:163], v[196:197] op_sel:[0,1]
	s_nop 0
	v_pk_fma_f32 v[110:111], v[160:161], v[196:197], v[162:163] op_sel_hi:[1,0,1]
	v_xor_b32_e32 v160, 0x80000000, v159
	v_mov_b32_e32 v161, v158
	v_pk_mul_f32 v[160:161], v[160:161], v[194:195] op_sel:[0,1]
	s_nop 0
	v_pk_fma_f32 v[104:105], v[158:159], v[194:195], v[160:161] op_sel_hi:[1,0,1]
	v_xor_b32_e32 v158, 0x80000000, v157
	v_mov_b32_e32 v159, v156
	v_pk_mul_f32 v[158:159], v[158:159], v[192:193] op_sel:[0,1]
	s_nop 0
	v_pk_fma_f32 v[102:103], v[156:157], v[192:193], v[158:159] op_sel_hi:[1,0,1]
	v_xor_b32_e32 v156, 0x80000000, v155
	v_mov_b32_e32 v157, v154
	v_pk_mul_f32 v[156:157], v[156:157], v[190:191] op_sel:[0,1]
	s_nop 0
	v_pk_fma_f32 v[100:101], v[154:155], v[190:191], v[156:157] op_sel_hi:[1,0,1]
	v_xor_b32_e32 v154, 0x80000000, v153
	v_mov_b32_e32 v155, v152
	v_pk_mul_f32 v[154:155], v[154:155], v[188:189] op_sel:[0,1]
	s_nop 0
	v_pk_fma_f32 v[98:99], v[152:153], v[188:189], v[154:155] op_sel_hi:[1,0,1]
	v_xor_b32_e32 v152, 0x80000000, v151
	v_mov_b32_e32 v153, v150
	v_pk_mul_f32 v[152:153], v[152:153], v[186:187] op_sel:[0,1]
	v_pk_add_f32 v[106:107], v[172:173], v[98:99]
	v_pk_fma_f32 v[96:97], v[150:151], v[186:187], v[152:153] op_sel_hi:[1,0,1]
	v_xor_b32_e32 v150, 0x80000000, v149
	v_mov_b32_e32 v151, v148
	v_pk_mul_f32 v[150:151], v[150:151], v[184:185] op_sel:[0,1]
	v_pk_add_f32 v[108:109], v[172:173], v[98:99] neg_lo:[0,1] neg_hi:[0,1]
	v_pk_fma_f32 v[94:95], v[148:149], v[184:185], v[150:151] op_sel_hi:[1,0,1]
	v_xor_b32_e32 v148, 0x80000000, v147
	v_mov_b32_e32 v149, v146
	v_pk_mul_f32 v[148:149], v[148:149], v[182:183] op_sel:[0,1]
	s_nop 0
	v_pk_fma_f32 v[92:93], v[146:147], v[182:183], v[148:149] op_sel_hi:[1,0,1]
	v_xor_b32_e32 v146, 0x80000000, v145
	v_mov_b32_e32 v147, v144
	v_pk_mul_f32 v[146:147], v[146:147], v[180:181] op_sel:[0,1]
	s_nop 0
	v_pk_fma_f32 v[90:91], v[144:145], v[180:181], v[146:147] op_sel_hi:[1,0,1]
	v_xor_b32_e32 v144, 0x80000000, v143
	v_mov_b32_e32 v145, v142
	v_pk_mul_f32 v[144:145], v[144:145], v[178:179] op_sel:[0,1]
	v_pk_add_f32 v[70:71], v[90:91], v[110:111]
	v_pk_fma_f32 v[88:89], v[142:143], v[178:179], v[144:145] op_sel_hi:[1,0,1]
	v_xor_b32_e32 v142, 0x80000000, v141
	v_mov_b32_e32 v143, v140
	v_pk_mul_f32 v[142:143], v[142:143], v[176:177] op_sel:[0,1]
	v_pk_add_f32 v[98:99], v[106:107], v[70:71]
	v_pk_fma_f32 v[86:87], v[140:141], v[176:177], v[142:143] op_sel_hi:[1,0,1]
	v_pk_add_f32 v[106:107], v[106:107], v[70:71] neg_lo:[0,1] neg_hi:[0,1]
	v_pk_add_f32 v[70:71], v[84:85], v[100:101]
	v_pk_add_f32 v[140:141], v[84:85], v[100:101] neg_lo:[0,1] neg_hi:[0,1]
	v_pk_add_f32 v[84:85], v[92:93], v[112:113]
	v_pk_add_f32 v[92:93], v[92:93], v[112:113] neg_lo:[0,1] neg_hi:[0,1]
	v_pk_add_f32 v[100:101], v[70:71], v[84:85]
	v_pk_add_f32 v[112:113], v[70:71], v[84:85] neg_lo:[0,1] neg_hi:[0,1]
	v_pk_add_f32 v[70:71], v[86:87], v[102:103]
	v_pk_add_f32 v[84:85], v[94:95], v[136:137]
	v_pk_add_f32 v[144:145], v[86:87], v[102:103] neg_lo:[0,1] neg_hi:[0,1]
	v_pk_add_f32 v[86:87], v[94:95], v[136:137] neg_lo:[0,1] neg_hi:[0,1]
	v_pk_add_f32 v[94:95], v[70:71], v[84:85]
	v_pk_add_f32 v[102:103], v[70:71], v[84:85] neg_lo:[0,1] neg_hi:[0,1]
	v_pk_add_f32 v[70:71], v[88:89], v[104:105]
	v_pk_add_f32 v[84:85], v[96:97], v[138:139]
	v_xor_b32_e32 v137, 0x80000000, v86
	v_mov_b32_e32 v136, v87
	v_pk_add_f32 v[148:149], v[88:89], v[104:105] neg_lo:[0,1] neg_hi:[0,1]
	v_pk_add_f32 v[86:87], v[96:97], v[138:139] neg_lo:[0,1] neg_hi:[0,1]
	v_pk_add_f32 v[88:89], v[70:71], v[84:85]
	v_xor_b32_e32 v143, 0x80000000, v92
	v_mov_b32_e32 v142, v93
	v_pk_add_f32 v[104:105], v[70:71], v[84:85] neg_lo:[0,1] neg_hi:[0,1]
	v_xor_b32_e32 v139, 0x80000000, v86
	v_mov_b32_e32 v138, v87
	v_pk_add_f32 v[70:71], v[98:99], v[94:95]
	v_pk_add_f32 v[84:85], v[100:101], v[88:89]
	v_pk_add_f32 v[86:87], v[100:101], v[88:89] neg_lo:[0,1] neg_hi:[0,1]
	v_pk_add_f32 v[92:93], v[140:141], v[142:143]
	v_pk_add_f32 v[94:95], v[98:99], v[94:95] neg_lo:[0,1] neg_hi:[0,1]
	v_pk_add_f32 v[88:89], v[70:71], v[84:85]
	v_pk_add_f32 v[84:85], v[70:71], v[84:85] neg_lo:[0,1] neg_hi:[0,1]
	v_xor_b32_e32 v71, 0x80000000, v86
	v_mov_b32_e32 v70, v87
	v_pk_add_f32 v[90:91], v[90:91], v[110:111] neg_lo:[0,1] neg_hi:[0,1]
	v_pk_add_f32 v[146:147], v[144:145], v[136:137]
	v_pk_add_f32 v[96:97], v[148:149], v[138:139]
	v_pk_add_f32 v[86:87], v[94:95], v[70:71]
	v_pk_add_f32 v[70:71], v[94:95], v[70:71] neg_lo:[0,1] neg_hi:[0,1]
	v_pk_mul_f32 v[94:95], v[92:93], s[28:29] op_sel:[1,0]
	v_xor_b32_e32 v111, 0x80000000, v90
	v_mov_b32_e32 v110, v91
	v_pk_fma_f32 v[92:93], v[92:93], s[26:27], v[94:95] op_sel_hi:[0,1,1]
	v_mul_f32_e32 v94, 0x3f3504f3, v147
	s_mov_b32 s29, s34
	v_pk_mul_f32 v[98:99], v[96:97], s[8:9] op_sel:[1,0]
	v_pk_add_f32 v[90:91], v[108:109], v[110:111]
	v_pk_fma_f32 v[94:95], v[146:147], s[30:31], v[94:95] op_sel_hi:[0,1,0]
	v_pk_fma_f32 v[96:97], v[96:97], s[28:29], v[98:99] op_sel_hi:[0,1,1]
	v_pk_add_f32 v[98:99], v[90:91], v[94:95]
	v_pk_add_f32 v[90:91], v[90:91], v[94:95] neg_lo:[0,1] neg_hi:[0,1]
	v_pk_add_f32 v[94:95], v[92:93], v[96:97]
	v_pk_add_f32 v[100:101], v[92:93], v[96:97] neg_lo:[0,1] neg_hi:[0,1]
	v_pk_add_f32 v[96:97], v[98:99], v[94:95]
	v_pk_add_f32 v[92:93], v[98:99], v[94:95] neg_lo:[0,1] neg_hi:[0,1]
	v_xor_b32_e32 v99, 0x80000000, v100
	v_mov_b32_e32 v98, v101
	v_pk_mul_f32 v[100:101], v[102:103], s[36:37] op_sel:[1,0]
	v_pk_add_f32 v[94:95], v[90:91], v[98:99]
	v_pk_add_f32 v[90:91], v[90:91], v[98:99] neg_lo:[0,1] neg_hi:[0,1]
	v_mul_f32_e32 v98, 0x3f3504f3, v113
	v_pk_fma_f32 v[100:101], v[102:103], s[20:21], v[100:101] op_sel_hi:[0,1,1]
	v_mul_f32_e32 v102, 0xbf3504f3, v104
	v_pk_fma_f32 v[98:99], v[112:113], s[30:31], v[98:99] op_sel_hi:[0,1,0]
	v_pk_fma_f32 v[102:103], v[104:105], s[30:31], v[102:103] op_sel:[1,0,0] op_sel_hi:[1,1,0]
	v_pk_add_f32 v[112:113], v[106:107], v[100:101]
	v_pk_add_f32 v[106:107], v[106:107], v[100:101] neg_lo:[0,1] neg_hi:[0,1]
	v_pk_add_f32 v[100:101], v[98:99], v[102:103]
	v_pk_add_f32 v[98:99], v[98:99], v[102:103] neg_lo:[0,1] neg_hi:[0,1]
	v_pk_add_f32 v[104:105], v[112:113], v[100:101]
	v_pk_add_f32 v[100:101], v[112:113], v[100:101] neg_lo:[0,1] neg_hi:[0,1]
	v_xor_b32_e32 v113, 0x80000000, v98
	v_mov_b32_e32 v112, v99
	v_pk_add_f32 v[102:103], v[106:107], v[112:113]
	v_pk_add_f32 v[98:99], v[106:107], v[112:113] neg_lo:[0,1] neg_hi:[0,1]
	v_pk_add_f32 v[106:107], v[148:149], v[138:139] neg_lo:[0,1] neg_hi:[0,1]
	v_pk_add_f32 v[108:109], v[108:109], v[110:111] neg_lo:[0,1] neg_hi:[0,1]
	v_pk_mul_f32 v[112:113], v[106:107], s[10:11] op_sel:[1,0]
	v_pk_add_f32 v[110:111], v[140:141], v[142:143] neg_lo:[0,1] neg_hi:[0,1]
	v_pk_fma_f32 v[106:107], v[106:107], s[34:35], v[112:113] op_sel_hi:[0,1,1]
	v_pk_mul_f32 v[112:113], v[110:111], s[8:9] op_sel:[1,0]
	s_nop 0
	v_pk_fma_f32 v[110:111], v[110:111], s[28:29], v[112:113] op_sel_hi:[0,1,1]
	v_pk_add_f32 v[112:113], v[144:145], v[136:137] neg_lo:[0,1] neg_hi:[0,1]
	v_pk_add_f32 v[138:139], v[110:111], v[106:107] neg_lo:[0,1] neg_hi:[0,1]
	v_mul_f32_e32 v136, 0xbf3504f3, v112
	v_pk_fma_f32 v[112:113], v[112:113], s[30:31], v[136:137] op_sel:[1,0,0] op_sel_hi:[1,1,0]
	s_nop 0
	v_pk_add_f32 v[136:137], v[108:109], v[112:113]
	v_pk_add_f32 v[112:113], v[108:109], v[112:113] neg_lo:[0,1] neg_hi:[0,1]
	v_pk_add_f32 v[108:109], v[110:111], v[106:107]
	s_nop 0
	v_pk_add_f32 v[110:111], v[136:137], v[108:109]
	v_pk_add_f32 v[106:107], v[136:137], v[108:109] neg_lo:[0,1] neg_hi:[0,1]
	v_xor_b32_e32 v137, 0x80000000, v138
	v_mov_b32_e32 v136, v139
	v_pk_add_f32 v[108:109], v[112:113], v[136:137]
	v_pk_add_f32 v[112:113], v[112:113], v[136:137] neg_lo:[0,1] neg_hi:[0,1]

.LBB0_1656:
	s_or_b64 exec, exec, s[6:7]
	s_waitcnt lgkmcnt(0)
	s_barrier
	s_and_saveexec_b64 s[6:7], vcc
	s_cbranch_execz .LBB0_1658
	ds_read_b64 v[172:173], v134
	ds_read_b64 v[174:175], v122 offset:4096
	ds_read_b64 v[176:177], v116 offset:8192
	ds_read_b64 v[178:179], v63 offset:12288
	ds_read_b64 v[180:181], v31 offset:16384
	ds_read_b64 v[182:183], v23 offset:20480
	ds_read_b64 v[184:185], v15 offset:24576
	ds_read_b64 v[186:187], v11 offset:28672
	ds_read_b64 v[188:189], v132 offset:32768
	ds_read_b64 v[190:191], v131 offset:36864
	ds_read_b64 v[192:193], v130 offset:40960
	ds_read_b64 v[194:195], v129 offset:45056
	ds_read_b64 v[196:197], v128 offset:49152
	ds_read_b64 v[198:199], v127 offset:53248
	ds_read_b64 v[200:201], v115 offset:57344
	v_cvt_f32_ubyte0_e32 v106, v126
	v_mul_f32_e32 v107, 0x39800000, v106
	v_cos_f32_e32 v106, v107
	v_sin_f32_e32 v108, v107
	s_waitcnt lgkmcnt(14)
	ds_read_b64 v[202:203], v114 offset:61440
	v_mov_b32_e32 v109, v106
	v_xor_b32_e32 v107, 0x80000000, v108
	v_pk_mul_f32 v[140:141], v[108:109], v[108:109] op_sel_hi:[1,0] neg_lo:[0,1] neg_hi:[0,1]
	s_mov_b32 s29, s26
	v_pk_fma_f32 v[140:141], v[106:107], v[106:107], v[140:141] op_sel_hi:[1,0,1]
	s_mov_b32 s8, s26
	v_pk_mul_f32 v[142:143], v[108:109], v[140:141] op_sel:[0,1]
	s_mov_b32 s9, s28
	v_pk_fma_f32 v[142:143], v[106:107], v[140:141], v[142:143] op_sel_hi:[1,0,1]
	s_mov_b32 s37, s20
	v_pk_mul_f32 v[144:145], v[108:109], v[142:143] op_sel:[0,1]
	s_mov_b32 s10, s27
	v_pk_fma_f32 v[144:145], v[106:107], v[142:143], v[144:145] op_sel_hi:[1,0,1]
	s_mov_b32 s11, s34
	v_pk_mul_f32 v[146:147], v[108:109], v[144:145] op_sel:[0,1]
	s_mov_b32 s35, s28
	v_pk_fma_f32 v[146:147], v[106:107], v[144:145], v[146:147] op_sel_hi:[1,0,1]
	s_nop 0
	v_pk_mul_f32 v[148:149], v[108:109], v[146:147] op_sel:[0,1]
	s_nop 0
	v_pk_fma_f32 v[148:149], v[106:107], v[146:147], v[148:149] op_sel_hi:[1,0,1]
	s_nop 0
	v_pk_mul_f32 v[150:151], v[108:109], v[148:149] op_sel:[0,1]
	s_nop 0
	v_pk_fma_f32 v[150:151], v[106:107], v[148:149], v[150:151] op_sel_hi:[1,0,1]
	s_nop 0
	v_pk_mul_f32 v[152:153], v[108:109], v[150:151] op_sel:[0,1]
	s_nop 0
	v_pk_fma_f32 v[152:153], v[106:107], v[150:151], v[152:153] op_sel_hi:[1,0,1]
	s_nop 0
	v_pk_mul_f32 v[154:155], v[108:109], v[152:153] op_sel:[0,1]
	s_nop 0
	v_pk_fma_f32 v[154:155], v[106:107], v[152:153], v[154:155] op_sel_hi:[1,0,1]
	s_nop 0
	v_pk_mul_f32 v[156:157], v[108:109], v[154:155] op_sel:[0,1]
	s_nop 0
	v_pk_fma_f32 v[156:157], v[106:107], v[154:155], v[156:157] op_sel_hi:[1,0,1]
	s_nop 0
	v_pk_mul_f32 v[158:159], v[108:109], v[156:157] op_sel:[0,1]
	s_nop 0
	v_pk_fma_f32 v[158:159], v[106:107], v[156:157], v[158:159] op_sel_hi:[1,0,1]
	s_nop 0
	v_pk_mul_f32 v[160:161], v[108:109], v[158:159] op_sel:[0,1]
	s_nop 0
	v_pk_fma_f32 v[160:161], v[106:107], v[158:159], v[160:161] op_sel_hi:[1,0,1]
	s_nop 0
	v_pk_mul_f32 v[162:163], v[108:109], v[160:161] op_sel:[0,1]
	s_nop 0
	v_pk_fma_f32 v[162:163], v[106:107], v[160:161], v[162:163] op_sel_hi:[1,0,1]
	s_nop 0
	v_pk_mul_f32 v[164:165], v[108:109], v[162:163] op_sel:[0,1]
	s_nop 0
	v_pk_fma_f32 v[164:165], v[106:107], v[162:163], v[164:165] op_sel_hi:[1,0,1]
	s_nop 0
	v_pk_mul_f32 v[166:167], v[108:109], v[164:165] op_sel:[0,1]
	s_waitcnt lgkmcnt(14)
	v_pk_mul_f32 v[108:109], v[108:109], v[174:175] op_sel:[0,1]
	v_pk_fma_f32 v[166:167], v[106:107], v[164:165], v[166:167] op_sel_hi:[1,0,1]
	v_pk_fma_f32 v[84:85], v[106:107], v[174:175], v[108:109] op_sel_hi:[1,0,1]
	v_xor_b32_e32 v168, 0x80000000, v167
	v_mov_b32_e32 v169, v166
	s_waitcnt lgkmcnt(0)
	v_pk_mul_f32 v[168:169], v[168:169], v[202:203] op_sel:[0,1]
	s_nop 0
	v_pk_fma_f32 v[138:139], v[166:167], v[202:203], v[168:169] op_sel_hi:[1,0,1]
	v_xor_b32_e32 v166, 0x80000000, v165
	v_mov_b32_e32 v167, v164
	v_pk_mul_f32 v[166:167], v[166:167], v[200:201] op_sel:[0,1]
	s_nop 0
	v_pk_fma_f32 v[136:137], v[164:165], v[200:201], v[166:167] op_sel_hi:[1,0,1]
	v_xor_b32_e32 v164, 0x80000000, v163
	v_mov_b32_e32 v165, v162
	v_pk_mul_f32 v[164:165], v[164:165], v[198:199] op_sel:[0,1]
	s_nop 0
	v_pk_fma_f32 v[112:113], v[162:163], v[198:199], v[164:165] op_sel_hi:[1,0,1]
	v_xor_b32_e32 v162, 0x80000000, v161
	v_mov_b32_e32 v163, v160
	v_pk_mul_f32 v[162:163], v[162:163], v[196:197] op_sel:[0,1]
	s_nop 0
	v_pk_fma_f32 v[110:111], v[160:161], v[196:197], v[162:163] op_sel_hi:[1,0,1]
	v_xor_b32_e32 v160, 0x80000000, v159
	v_mov_b32_e32 v161, v158
	v_pk_mul_f32 v[160:161], v[160:161], v[194:195] op_sel:[0,1]
	s_nop 0
	v_pk_fma_f32 v[104:105], v[158:159], v[194:195], v[160:161] op_sel_hi:[1,0,1]
	v_xor_b32_e32 v158, 0x80000000, v157
	v_mov_b32_e32 v159, v156
	v_pk_mul_f32 v[158:159], v[158:159], v[192:193] op_sel:[0,1]
	s_nop 0
	v_pk_fma_f32 v[102:103], v[156:157], v[192:193], v[158:159] op_sel_hi:[1,0,1]
	v_xor_b32_e32 v156, 0x80000000, v155
	v_mov_b32_e32 v157, v154
	v_pk_mul_f32 v[156:157], v[156:157], v[190:191] op_sel:[0,1]
	s_nop 0
	v_pk_fma_f32 v[100:101], v[154:155], v[190:191], v[156:157] op_sel_hi:[1,0,1]
	v_xor_b32_e32 v154, 0x80000000, v153
	v_mov_b32_e32 v155, v152
	v_pk_mul_f32 v[154:155], v[154:155], v[188:189] op_sel:[0,1]
	s_nop 0
	v_pk_fma_f32 v[98:99], v[152:153], v[188:189], v[154:155] op_sel_hi:[1,0,1]
	v_xor_b32_e32 v152, 0x80000000, v151
	v_mov_b32_e32 v153, v150
	v_pk_mul_f32 v[152:153], v[152:153], v[186:187] op_sel:[0,1]
	v_pk_add_f32 v[106:107], v[172:173], v[98:99]
	v_pk_fma_f32 v[96:97], v[150:151], v[186:187], v[152:153] op_sel_hi:[1,0,1]
	v_xor_b32_e32 v150, 0x80000000, v149
	v_mov_b32_e32 v151, v148
	v_pk_mul_f32 v[150:151], v[150:151], v[184:185] op_sel:[0,1]
	v_pk_add_f32 v[108:109], v[172:173], v[98:99] neg_lo:[0,1] neg_hi:[0,1]
	v_pk_fma_f32 v[94:95], v[148:149], v[184:185], v[150:151] op_sel_hi:[1,0,1]
	v_xor_b32_e32 v148, 0x80000000, v147
	v_mov_b32_e32 v149, v146
	v_pk_mul_f32 v[148:149], v[148:149], v[182:183] op_sel:[0,1]
	s_nop 0
	v_pk_fma_f32 v[92:93], v[146:147], v[182:183], v[148:149] op_sel_hi:[1,0,1]
	v_xor_b32_e32 v146, 0x80000000, v145
	v_mov_b32_e32 v147, v144
	v_pk_mul_f32 v[146:147], v[146:147], v[180:181] op_sel:[0,1]
	s_nop 0
	v_pk_fma_f32 v[90:91], v[144:145], v[180:181], v[146:147] op_sel_hi:[1,0,1]
	v_xor_b32_e32 v144, 0x80000000, v143
	v_mov_b32_e32 v145, v142
	v_pk_mul_f32 v[144:145], v[144:145], v[178:179] op_sel:[0,1]
	v_pk_add_f32 v[70:71], v[90:91], v[110:111]
	v_pk_fma_f32 v[88:89], v[142:143], v[178:179], v[144:145] op_sel_hi:[1,0,1]
	v_xor_b32_e32 v142, 0x80000000, v141
	v_mov_b32_e32 v143, v140
	v_pk_mul_f32 v[142:143], v[142:143], v[176:177] op_sel:[0,1]
	v_pk_add_f32 v[98:99], v[106:107], v[70:71]
	v_pk_fma_f32 v[86:87], v[140:141], v[176:177], v[142:143] op_sel_hi:[1,0,1]
	v_pk_add_f32 v[106:107], v[106:107], v[70:71] neg_lo:[0,1] neg_hi:[0,1]
	v_pk_add_f32 v[70:71], v[84:85], v[100:101]
	v_pk_add_f32 v[140:141], v[84:85], v[100:101] neg_lo:[0,1] neg_hi:[0,1]
	v_pk_add_f32 v[84:85], v[92:93], v[112:113]
	v_pk_add_f32 v[92:93], v[92:93], v[112:113] neg_lo:[0,1] neg_hi:[0,1]
	v_pk_add_f32 v[100:101], v[70:71], v[84:85]
	v_pk_add_f32 v[112:113], v[70:71], v[84:85] neg_lo:[0,1] neg_hi:[0,1]
	v_pk_add_f32 v[70:71], v[86:87], v[102:103]
	v_pk_add_f32 v[84:85], v[94:95], v[136:137]
	v_pk_add_f32 v[144:145], v[86:87], v[102:103] neg_lo:[0,1] neg_hi:[0,1]
	v_pk_add_f32 v[86:87], v[94:95], v[136:137] neg_lo:[0,1] neg_hi:[0,1]
	v_pk_add_f32 v[94:95], v[70:71], v[84:85]
	v_pk_add_f32 v[102:103], v[70:71], v[84:85] neg_lo:[0,1] neg_hi:[0,1]
	v_pk_add_f32 v[70:71], v[88:89], v[104:105]
	v_pk_add_f32 v[84:85], v[96:97], v[138:139]
	v_xor_b32_e32 v137, 0x80000000, v86
	v_mov_b32_e32 v136, v87
	v_pk_add_f32 v[148:149], v[88:89], v[104:105] neg_lo:[0,1] neg_hi:[0,1]
	v_pk_add_f32 v[86:87], v[96:97], v[138:139] neg_lo:[0,1] neg_hi:[0,1]
	v_pk_add_f32 v[88:89], v[70:71], v[84:85]
	v_xor_b32_e32 v143, 0x80000000, v92
	v_mov_b32_e32 v142, v93
	v_pk_add_f32 v[104:105], v[70:71], v[84:85] neg_lo:[0,1] neg_hi:[0,1]
	v_xor_b32_e32 v139, 0x80000000, v86
	v_mov_b32_e32 v138, v87
	v_pk_add_f32 v[70:71], v[98:99], v[94:95]
	v_pk_add_f32 v[84:85], v[100:101], v[88:89]
	v_pk_add_f32 v[86:87], v[100:101], v[88:89] neg_lo:[0,1] neg_hi:[0,1]
	v_pk_add_f32 v[92:93], v[140:141], v[142:143]
	v_pk_add_f32 v[94:95], v[98:99], v[94:95] neg_lo:[0,1] neg_hi:[0,1]
	v_pk_add_f32 v[88:89], v[70:71], v[84:85]
	v_pk_add_f32 v[84:85], v[70:71], v[84:85] neg_lo:[0,1] neg_hi:[0,1]
	v_xor_b32_e32 v71, 0x80000000, v86
	v_mov_b32_e32 v70, v87
	v_pk_add_f32 v[90:91], v[90:91], v[110:111] neg_lo:[0,1] neg_hi:[0,1]
	v_pk_add_f32 v[146:147], v[144:145], v[136:137]
	v_pk_add_f32 v[96:97], v[148:149], v[138:139]
	v_pk_add_f32 v[86:87], v[94:95], v[70:71]
	v_pk_add_f32 v[70:71], v[94:95], v[70:71] neg_lo:[0,1] neg_hi:[0,1]
	v_pk_mul_f32 v[94:95], v[92:93], s[28:29] op_sel:[1,0]
	v_xor_b32_e32 v111, 0x80000000, v90
	v_mov_b32_e32 v110, v91
	v_pk_fma_f32 v[92:93], v[92:93], s[26:27], v[94:95] op_sel_hi:[0,1,1]
	v_mul_f32_e32 v94, 0x3f3504f3, v147
	s_mov_b32 s29, s34
	v_pk_mul_f32 v[98:99], v[96:97], s[8:9] op_sel:[1,0]
	v_pk_add_f32 v[90:91], v[108:109], v[110:111]
	v_pk_fma_f32 v[94:95], v[146:147], s[30:31], v[94:95] op_sel_hi:[0,1,0]
	v_pk_fma_f32 v[96:97], v[96:97], s[28:29], v[98:99] op_sel_hi:[0,1,1]
	v_pk_add_f32 v[98:99], v[90:91], v[94:95]
	v_pk_add_f32 v[90:91], v[90:91], v[94:95] neg_lo:[0,1] neg_hi:[0,1]
	v_pk_add_f32 v[94:95], v[92:93], v[96:97]
	v_pk_add_f32 v[100:101], v[92:93], v[96:97] neg_lo:[0,1] neg_hi:[0,1]
	v_pk_add_f32 v[96:97], v[98:99], v[94:95]
	v_pk_add_f32 v[92:93], v[98:99], v[94:95] neg_lo:[0,1] neg_hi:[0,1]
	v_xor_b32_e32 v99, 0x80000000, v100
	v_mov_b32_e32 v98, v101
	v_pk_mul_f32 v[100:101], v[102:103], s[36:37] op_sel:[1,0]
	v_pk_add_f32 v[94:95], v[90:91], v[98:99]
	v_pk_add_f32 v[90:91], v[90:91], v[98:99] neg_lo:[0,1] neg_hi:[0,1]
	v_mul_f32_e32 v98, 0x3f3504f3, v113
	v_pk_fma_f32 v[100:101], v[102:103], s[20:21], v[100:101] op_sel_hi:[0,1,1]
	v_mul_f32_e32 v102, 0xbf3504f3, v104
	v_pk_fma_f32 v[98:99], v[112:113], s[30:31], v[98:99] op_sel_hi:[0,1,0]
	v_pk_fma_f32 v[102:103], v[104:105], s[30:31], v[102:103] op_sel:[1,0,0] op_sel_hi:[1,1,0]
	v_pk_add_f32 v[112:113], v[106:107], v[100:101]
	v_pk_add_f32 v[106:107], v[106:107], v[100:101] neg_lo:[0,1] neg_hi:[0,1]
	v_pk_add_f32 v[100:101], v[98:99], v[102:103]
	v_pk_add_f32 v[98:99], v[98:99], v[102:103] neg_lo:[0,1] neg_hi:[0,1]
	v_pk_add_f32 v[104:105], v[112:113], v[100:101]
	v_pk_add_f32 v[100:101], v[112:113], v[100:101] neg_lo:[0,1] neg_hi:[0,1]
	v_xor_b32_e32 v113, 0x80000000, v98
	v_mov_b32_e32 v112, v99
	v_pk_add_f32 v[102:103], v[106:107], v[112:113]
	v_pk_add_f32 v[98:99], v[106:107], v[112:113] neg_lo:[0,1] neg_hi:[0,1]
	v_pk_add_f32 v[106:107], v[148:149], v[138:139] neg_lo:[0,1] neg_hi:[0,1]
	v_pk_add_f32 v[108:109], v[108:109], v[110:111] neg_lo:[0,1] neg_hi:[0,1]
	v_pk_mul_f32 v[112:113], v[106:107], s[10:11] op_sel:[1,0]
	v_pk_add_f32 v[110:111], v[140:141], v[142:143] neg_lo:[0,1] neg_hi:[0,1]
	v_pk_fma_f32 v[106:107], v[106:107], s[34:35], v[112:113] op_sel_hi:[0,1,1]
	v_pk_mul_f32 v[112:113], v[110:111], s[8:9] op_sel:[1,0]
	s_nop 0
	v_pk_fma_f32 v[110:111], v[110:111], s[28:29], v[112:113] op_sel_hi:[0,1,1]
	v_pk_add_f32 v[112:113], v[144:145], v[136:137] neg_lo:[0,1] neg_hi:[0,1]
	v_pk_add_f32 v[138:139], v[110:111], v[106:107] neg_lo:[0,1] neg_hi:[0,1]
	v_mul_f32_e32 v134, 0xbf3504f3, v112
	v_pk_fma_f32 v[112:113], v[112:113], s[30:31], v[134:135] op_sel:[1,0,0] op_sel_hi:[1,1,0]
	s_nop 0
	v_pk_add_f32 v[136:137], v[108:109], v[112:113]
	v_pk_add_f32 v[112:113], v[108:109], v[112:113] neg_lo:[0,1] neg_hi:[0,1]
	v_pk_add_f32 v[108:109], v[110:111], v[106:107]
	s_nop 0
	v_pk_add_f32 v[110:111], v[136:137], v[108:109]
	v_pk_add_f32 v[106:107], v[136:137], v[108:109] neg_lo:[0,1] neg_hi:[0,1]
	v_xor_b32_e32 v137, 0x80000000, v138
	v_mov_b32_e32 v136, v139
	v_pk_add_f32 v[108:109], v[112:113], v[136:137]
	v_pk_add_f32 v[112:113], v[112:113], v[136:137] neg_lo:[0,1] neg_hi:[0,1]

.LBB0_1660:
	s_or_b64 exec, exec, s[6:7]
	s_waitcnt lgkmcnt(0)
	s_barrier
	s_and_saveexec_b64 s[6:7], vcc
	s_cbranch_execz .LBB0_1662
	ds_read_b64 v[172:173], v132 offset:32768
	v_cvt_f32_i32_e32 v84, v126
	v_lshlrev_b32_e32 v85, 3, v125
	v_add3_u32 v90, 0, v85, v133
	ds_read_b64 v[174:175], v90
	v_mul_f32_e32 v86, 0x39000000, v84
	v_sin_f32_e32 v84, v86
	v_cos_f32_e32 v86, v86
	v_cvt_f32_i32_e32 v65, v65
	v_xor_b32_e32 v87, 0x80000000, v84
	v_mov_b32_e32 v85, v86
	s_waitcnt lgkmcnt(1)
	v_pk_mul_f32 v[84:85], v[84:85], v[172:173] op_sel:[0,1]
	v_cvt_f32_i32_e32 v59, v59
	v_pk_fma_f32 v[70:71], v[86:87], v[172:173], v[84:85] op_sel_hi:[1,0,1]
	v_cvt_f32_i32_e32 v86, v124
	s_waitcnt lgkmcnt(0)
	v_pk_add_f32 v[84:85], v[174:175], v[70:71]
	v_pk_add_f32 v[70:71], v[174:175], v[70:71] neg_lo:[0,1] neg_hi:[0,1]
	ds_write_b64 v90, v[84:85]
	ds_write_b64 v132, v[70:71] offset:32768
	ds_read_b64 v[172:173], v131 offset:36864
	ds_read_b64 v[174:175], v122 offset:4096
	v_mul_f32_e32 v71, 0x39000000, v86
	v_cos_f32_e32 v70, v71
	v_sin_f32_e32 v84, v71
	v_cvt_f32_i32_e32 v27, v27
	v_mov_b32_e32 v85, v70
	v_xor_b32_e32 v71, 0x80000000, v84
	s_waitcnt lgkmcnt(1)
	v_pk_mul_f32 v[84:85], v[84:85], v[172:173] op_sel:[0,1]
	v_cvt_f32_i32_e32 v19, v19
	v_pk_fma_f32 v[70:71], v[70:71], v[172:173], v[84:85] op_sel_hi:[1,0,1]
	v_cvt_f32_i32_e32 v86, v123
	s_waitcnt lgkmcnt(0)
	v_pk_add_f32 v[84:85], v[174:175], v[70:71]
	v_pk_add_f32 v[70:71], v[174:175], v[70:71] neg_lo:[0,1] neg_hi:[0,1]
	ds_write_b64 v122, v[84:85] offset:4096
	ds_write_b64 v131, v[70:71] offset:36864
	ds_read_b64 v[172:173], v130 offset:40960
	ds_read_b64 v[174:175], v116 offset:8192
	v_mul_f32_e32 v71, 0x39000000, v86
	v_cos_f32_e32 v70, v71
	v_sin_f32_e32 v84, v71
	v_mov_b32_e32 v85, v70
	v_xor_b32_e32 v71, 0x80000000, v84
	s_waitcnt lgkmcnt(1)
	v_pk_mul_f32 v[84:85], v[84:85], v[172:173] op_sel:[0,1]
	s_nop 0
	v_pk_fma_f32 v[70:71], v[70:71], v[172:173], v[84:85] op_sel_hi:[1,0,1]
	v_cvt_f32_i32_e32 v86, v117
	s_waitcnt lgkmcnt(0)
	v_pk_add_f32 v[84:85], v[174:175], v[70:71]
	v_pk_add_f32 v[70:71], v[174:175], v[70:71] neg_lo:[0,1] neg_hi:[0,1]
	ds_write_b64 v116, v[84:85] offset:8192
	ds_write_b64 v130, v[70:71] offset:40960
	ds_read_b64 v[172:173], v129 offset:45056
	ds_read_b64 v[174:175], v63 offset:12288
	v_mul_f32_e32 v71, 0x39000000, v86
	v_cos_f32_e32 v70, v71
	v_sin_f32_e32 v84, v71
	v_mov_b32_e32 v85, v70
	v_xor_b32_e32 v71, 0x80000000, v84
	s_waitcnt lgkmcnt(1)
	v_pk_mul_f32 v[84:85], v[84:85], v[172:173] op_sel:[0,1]
	s_nop 0
	v_pk_fma_f32 v[70:71], v[70:71], v[172:173], v[84:85] op_sel_hi:[1,0,1]
	s_waitcnt lgkmcnt(0)
	v_pk_add_f32 v[84:85], v[174:175], v[70:71]
	ds_write_b64 v63, v[84:85] offset:12288
	v_pk_add_f32 v[70:71], v[174:175], v[70:71] neg_lo:[0,1] neg_hi:[0,1]
	v_mul_f32_e32 v63, 0x39000000, v65
	ds_write_b64 v129, v[70:71] offset:45056
	ds_read_b64 v[172:173], v128 offset:49152
	ds_read_b64 v[174:175], v31 offset:16384
	v_cos_f32_e32 v70, v63
	v_sin_f32_e32 v84, v63
	v_mov_b32_e32 v85, v70
	v_xor_b32_e32 v71, 0x80000000, v84
	s_waitcnt lgkmcnt(1)
	v_pk_mul_f32 v[84:85], v[84:85], v[172:173] op_sel:[0,1]
	s_nop 0
	v_pk_fma_f32 v[70:71], v[70:71], v[172:173], v[84:85] op_sel_hi:[1,0,1]
	s_waitcnt lgkmcnt(0)
	v_pk_add_f32 v[84:85], v[174:175], v[70:71]
	ds_write_b64 v31, v[84:85] offset:16384
	v_pk_add_f32 v[70:71], v[174:175], v[70:71] neg_lo:[0,1] neg_hi:[0,1]
	v_mul_f32_e32 v31, 0x39000000, v59
	ds_write_b64 v128, v[70:71] offset:49152
	ds_read_b64 v[172:173], v127 offset:53248
	ds_read_b64 v[174:175], v23 offset:20480
	v_cos_f32_e32 v70, v31
	v_sin_f32_e32 v84, v31
	v_mov_b32_e32 v85, v70
	v_xor_b32_e32 v71, 0x80000000, v84
	s_waitcnt lgkmcnt(1)
	v_pk_mul_f32 v[84:85], v[84:85], v[172:173] op_sel:[0,1]
	s_nop 0
	v_pk_fma_f32 v[70:71], v[70:71], v[172:173], v[84:85] op_sel_hi:[1,0,1]
	s_waitcnt lgkmcnt(0)
	v_pk_add_f32 v[84:85], v[174:175], v[70:71]
	ds_write_b64 v23, v[84:85] offset:20480
	v_pk_add_f32 v[70:71], v[174:175], v[70:71] neg_lo:[0,1] neg_hi:[0,1]
	v_mul_f32_e32 v23, 0x39000000, v27
	ds_write_b64 v127, v[70:71] offset:53248
	ds_read_b64 v[172:173], v115 offset:57344
	ds_read_b64 v[174:175], v15 offset:24576
	v_cos_f32_e32 v70, v23
	v_sin_f32_e32 v84, v23
	v_mov_b32_e32 v85, v70
	v_xor_b32_e32 v71, 0x80000000, v84
	s_waitcnt lgkmcnt(1)
	v_pk_mul_f32 v[84:85], v[84:85], v[172:173] op_sel:[0,1]
	s_nop 0
	v_pk_fma_f32 v[70:71], v[70:71], v[172:173], v[84:85] op_sel_hi:[1,0,1]
	s_waitcnt lgkmcnt(0)
	v_pk_add_f32 v[84:85], v[174:175], v[70:71]
	ds_write_b64 v15, v[84:85] offset:24576
	v_pk_add_f32 v[70:71], v[174:175], v[70:71] neg_lo:[0,1] neg_hi:[0,1]
	v_mul_f32_e32 v15, 0x39000000, v19
	ds_write_b64 v115, v[70:71] offset:57344
	v_cos_f32_e32 v70, v15
	v_sin_f32_e32 v84, v15
	ds_read_b64 v[86:87], v114 offset:61440
	ds_read_b64 v[88:89], v11 offset:28672
	v_mov_b32_e32 v85, v70
	v_xor_b32_e32 v71, 0x80000000, v84
	s_waitcnt lgkmcnt(1)
	v_pk_mul_f32 v[84:85], v[84:85], v[86:87] op_sel:[0,1]
	s_nop 0
	v_pk_fma_f32 v[70:71], v[70:71], v[86:87], v[84:85] op_sel_hi:[1,0,1]
	s_waitcnt lgkmcnt(0)
	v_pk_add_f32 v[84:85], v[88:89], v[70:71]
	v_pk_add_f32 v[70:71], v[88:89], v[70:71] neg_lo:[0,1] neg_hi:[0,1]
	ds_write_b64 v11, v[84:85] offset:28672
	ds_write_b64 v114, v[70:71] offset:61440

.LBB0_1664:
	v_ashrrev_i32_e32 v15, 4, v11
	v_add_lshl_u32 v15, v11, v15, 3
	v_add_u32_e32 v19, s3, v15
	ds_read_b64 v[172:173], v19
	v_and_b32_e32 v19, 0x1fff, v7
	v_lshrrev_b32_e32 v23, 1, v7
	v_and_b32_e32 v23, 0xff8, v23
	v_lshlrev_b32_e32 v19, 3, v19
	v_add3_u32 v19, s3, v23, v19
	ds_read_b64 v[174:175], v19
	v_add_u32_e32 v15, 0, v15
	v_cmp_lt_i32_e32 vcc, s22, v11
	v_add_u32_e32 v7, 0xfffffe00, v7
	s_or_b64 s[8:9], vcc, s[8:9]
	s_waitcnt lgkmcnt(0)
	v_pk_add_f32 v[88:89], v[172:173], v[174:175]
	v_pk_add_f32 v[84:85], v[172:173], v[174:175] neg_lo:[0,1] neg_hi:[0,1]
	ds_read_b64 v[86:87], v15
	v_pk_mov_b32 v[84:85], v[88:89], v[84:85] op_sel:[1,0]
	s_nop 0
	v_pk_mul_f32 v[84:85], v[84:85], s[38:39]
	s_nop 0
	v_pk_mul_f32 v[84:85], v[70:71], v[84:85]
	s_nop 0
	v_xor_b32_e32 v88, 0x80000000, v85
	v_mov_b32_e32 v89, v84
	s_waitcnt lgkmcnt(0)
	v_pk_mul_f32 v[88:89], v[86:87], v[88:89] op_sel:[1,0]
	s_nop 0
	v_pk_fma_f32 v[84:85], v[86:87], v[84:85], v[88:89] op_sel_hi:[0,1,1]
	ds_write_b64 v15, v[84:85]
	v_add_u32_e32 v15, 0x200, v11
	v_mov_b32_e32 v11, v15
	s_andn2_b64 exec, exec, s[8:9]
	s_cbranch_execnz .LBB0_1664
.LBB0_1665:
	s_or_b64 exec, exec, s[6:7]
	v_mov_b32_e32 v130, v64
	s_waitcnt lgkmcnt(0)
	s_barrier
	v_mov_b32_e32 v114, 0
	v_add_u32_e32 v27, 0x1000, v130
	v_lshl_add_u32 v135, v130, 3, 0
	v_ashrrev_i32_e32 v27, 4, v27
	v_lshl_add_u32 v133, v27, 3, v135
	v_add_u32_e32 v27, 0x1200, v130
	v_ashrrev_i32_e32 v27, 4, v27
	v_lshl_add_u32 v132, v27, 3, v135
	v_add_u32_e32 v27, 0x1400, v130
	v_ashrrev_i32_e32 v27, 4, v27
	v_lshl_add_u32 v129, v27, 3, v135
	v_add_u32_e32 v27, 0x1600, v130
	v_ashrrev_i32_e32 v27, 4, v27
	v_add_u32_e32 v128, 0x200, v130
	v_lshl_add_u32 v127, v27, 3, v135
	v_add_u32_e32 v27, 0x1800, v130
	v_ashrrev_i32_e32 v7, 4, v128
	v_add_u32_e32 v126, 0x400, v130
	v_ashrrev_i32_e32 v27, 4, v27
	v_lshl_add_u32 v125, v7, 3, v135
	v_ashrrev_i32_e32 v7, 4, v126
	v_add_u32_e32 v123, 0x600, v130
	v_lshl_add_u32 v124, v27, 3, v135
	v_add_u32_e32 v27, 0x1a00, v130
	v_lshl_add_u32 v122, v7, 3, v135
	v_ashrrev_i32_e32 v7, 4, v123
	v_add_u32_e32 v116, 0x800, v130
	v_ashrrev_i32_e32 v27, 4, v27
	v_lshl_add_u32 v65, v7, 3, v135
	v_ashrrev_i32_e32 v7, 4, v116
	v_add_u32_e32 v59, 0xa00, v130
	v_lshl_add_u32 v117, v27, 3, v135
	v_add_u32_e32 v27, 0x1c00, v130
	v_lshl_add_u32 v31, v7, 3, v135
	v_ashrrev_i32_e32 v7, 4, v59
	v_add_u32_e32 v23, 0xc00, v130
	v_ashrrev_i32_e32 v27, 4, v27
	v_lshl_add_u32 v19, v7, 3, v135
	v_ashrrev_i32_e32 v7, 4, v23
	v_add_u32_e32 v15, 0xe00, v130
	v_lshl_add_u32 v63, v27, 3, v135
	v_add_u32_e32 v27, 0x1e00, v130
	v_ashrrev_i32_e32 v131, 4, v130
	v_lshl_add_u32 v11, v7, 3, v135
	v_ashrrev_i32_e32 v7, 4, v15
	v_ashrrev_i32_e32 v27, 4, v27
	v_cmp_gt_i32_e32 vcc, s70, v130
	v_lshl_add_u32 v134, v131, 3, v135
	v_lshl_add_u32 v7, v7, 3, v135
	v_lshl_add_u32 v27, v27, 3, v135
	v_mov_b32_e32 v115, 0
	v_mov_b32_e32 v86, 0
	v_mov_b32_e32 v87, v114
	v_mov_b32_e32 v94, v114
	v_mov_b32_e32 v95, v114
	v_mov_b32_e32 v102, v114
	v_mov_b32_e32 v103, v114
	v_mov_b32_e32 v108, v114
	v_mov_b32_e32 v109, v114
	v_mov_b32_e32 v88, v114
	v_mov_b32_e32 v89, v114
	v_mov_b32_e32 v96, v114
	v_mov_b32_e32 v97, v114
	v_mov_b32_e32 v104, v114
	v_mov_b32_e32 v105, v114
	v_mov_b32_e32 v110, v114
	v_mov_b32_e32 v111, v114
	v_mov_b32_e32 v84, v114
	v_mov_b32_e32 v85, v114
	v_mov_b32_e32 v92, v114
	v_mov_b32_e32 v93, v114
	v_mov_b32_e32 v100, v114
	v_mov_b32_e32 v101, v114
	v_mov_b32_e32 v106, v114
	v_mov_b32_e32 v107, v114
	v_mov_b32_e32 v70, v114
	v_mov_b32_e32 v71, v114
	v_mov_b32_e32 v90, v114
	v_mov_b32_e32 v91, v114
	v_mov_b32_e32 v98, v114
	v_mov_b32_e32 v99, v114
	v_mov_b32_e32 v112, v114
	v_mov_b32_e32 v113, v114
	s_and_saveexec_b64 s[6:7], vcc
	s_cbranch_execz .LBB0_1667
	ds_read_b64 v[172:173], v134
	ds_read_b64 v[174:175], v125 offset:4096
	ds_read_b64 v[176:177], v122 offset:8192
	ds_read_b64 v[178:179], v65 offset:12288
	ds_read_b64 v[180:181], v31 offset:16384
	ds_read_b64 v[182:183], v19 offset:20480
	ds_read_b64 v[184:185], v11 offset:24576
	ds_read_b64 v[186:187], v7 offset:28672
	ds_read_b64 v[188:189], v133 offset:32768
	ds_read_b64 v[190:191], v132 offset:36864
	ds_read_b64 v[192:193], v129 offset:40960
	ds_read_b64 v[194:195], v127 offset:45056
	ds_read_b64 v[196:197], v124 offset:49152
	ds_read_b64 v[198:199], v117 offset:53248
	ds_read_b64 v[200:201], v63 offset:57344
	s_waitcnt lgkmcnt(14)
	ds_read_b64 v[202:203], v27 offset:61440
	s_waitcnt lgkmcnt(7)
	v_pk_add_f32 v[114:115], v[172:173], v[188:189]
	v_pk_add_f32 v[136:137], v[172:173], v[188:189] neg_lo:[0,1] neg_hi:[0,1]
	s_waitcnt lgkmcnt(3)
	v_pk_add_f32 v[70:71], v[180:181], v[196:197]
	v_pk_add_f32 v[90:91], v[180:181], v[196:197] neg_lo:[0,1] neg_hi:[0,1]
	v_pk_add_f32 v[98:99], v[114:115], v[70:71]
	v_pk_add_f32 v[106:107], v[114:115], v[70:71] neg_lo:[0,1] neg_hi:[0,1]
	v_pk_add_f32 v[70:71], v[174:175], v[190:191]
	v_pk_add_f32 v[138:139], v[174:175], v[190:191] neg_lo:[0,1] neg_hi:[0,1]
	s_waitcnt lgkmcnt(2)
	v_pk_add_f32 v[84:85], v[182:183], v[198:199]
	v_pk_add_f32 v[92:93], v[182:183], v[198:199] neg_lo:[0,1] neg_hi:[0,1]
	v_pk_add_f32 v[100:101], v[70:71], v[84:85]
	v_pk_add_f32 v[108:109], v[70:71], v[84:85] neg_lo:[0,1] neg_hi:[0,1]
	v_pk_add_f32 v[70:71], v[176:177], v[192:193]
	s_waitcnt lgkmcnt(1)
	v_pk_add_f32 v[84:85], v[184:185], v[200:201]
	v_pk_add_f32 v[142:143], v[176:177], v[192:193] neg_lo:[0,1] neg_hi:[0,1]
	v_pk_add_f32 v[86:87], v[184:185], v[200:201] neg_lo:[0,1] neg_hi:[0,1]
	v_pk_add_f32 v[94:95], v[70:71], v[84:85]
	v_pk_add_f32 v[102:103], v[70:71], v[84:85] neg_lo:[0,1] neg_hi:[0,1]
	v_pk_add_f32 v[70:71], v[178:179], v[194:195]
	s_waitcnt lgkmcnt(0)
	v_pk_add_f32 v[84:85], v[186:187], v[202:203]
	v_pk_add_f32 v[146:147], v[178:179], v[194:195] neg_lo:[0,1] neg_hi:[0,1]
	v_pk_add_f32 v[88:89], v[70:71], v[84:85]
	v_xor_b32_e32 v141, 0x80000000, v92
	v_mov_b32_e32 v140, v93
	v_xor_b32_e32 v111, 0x80000000, v86
	v_mov_b32_e32 v110, v87
	v_pk_add_f32 v[86:87], v[186:187], v[202:203] neg_lo:[0,1] neg_hi:[0,1]
	v_pk_add_f32 v[104:105], v[70:71], v[84:85] neg_lo:[0,1] neg_hi:[0,1]
	v_pk_add_f32 v[84:85], v[100:101], v[88:89]
	v_pk_add_f32 v[88:89], v[100:101], v[88:89] neg_lo:[0,1] neg_hi:[0,1]
	v_pk_add_f32 v[92:93], v[138:139], v[140:141] neg_lo:[0,1] neg_hi:[0,1]
	v_xor_b32_e32 v113, 0x80000000, v86
	v_mov_b32_e32 v112, v87
	v_pk_add_f32 v[70:71], v[98:99], v[94:95]
	v_pk_add_f32 v[94:95], v[98:99], v[94:95] neg_lo:[0,1] neg_hi:[0,1]
	v_xor_b32_e32 v99, 0x80000000, v88
	v_mov_b32_e32 v98, v89
	s_mov_b32 s10, s27
	s_mov_b32 s11, s26
	v_pk_add_f32 v[144:145], v[142:143], v[110:111] neg_lo:[0,1] neg_hi:[0,1]
	v_pk_add_f32 v[96:97], v[146:147], v[112:113] neg_lo:[0,1] neg_hi:[0,1]
	v_pk_add_f32 v[86:87], v[70:71], v[84:85]
	v_pk_add_f32 v[84:85], v[70:71], v[84:85] neg_lo:[0,1] neg_hi:[0,1]
	v_pk_add_f32 v[70:71], v[94:95], v[98:99]
	v_pk_add_f32 v[88:89], v[94:95], v[98:99] neg_lo:[0,1] neg_hi:[0,1]
	s_mov_b32 s8, s26
	s_mov_b32 s9, s28
	v_pk_mul_f32 v[94:95], v[92:93], s[10:11] op_sel:[1,0]
	s_mov_b32 s35, s28
	v_xor_b32_e32 v115, 0x80000000, v90
	v_mov_b32_e32 v114, v91
	v_pk_fma_f32 v[92:93], v[92:93], s[8:9], v[94:95] op_sel_hi:[0,1,1]
	v_mul_f32_e32 v94, 0x3f3504f3, v144
	s_mov_b32 s8, s31
	s_mov_b32 s9, s30
	s_mov_b32 s29, s26
	v_pk_mul_f32 v[98:99], v[96:97], s[34:35] op_sel:[1,0]
	v_pk_add_f32 v[90:91], v[136:137], v[114:115] neg_lo:[0,1] neg_hi:[0,1]
	v_pk_fma_f32 v[94:95], v[144:145], s[8:9], v[94:95] op_sel:[1,0,0] op_sel_hi:[1,1,0]
	v_pk_fma_f32 v[96:97], v[96:97], s[28:29], v[98:99] op_sel_hi:[0,1,1]
	v_pk_add_f32 v[98:99], v[90:91], v[94:95]
	v_pk_add_f32 v[100:101], v[90:91], v[94:95] neg_lo:[0,1] neg_hi:[0,1]
	v_pk_add_f32 v[90:91], v[92:93], v[96:97]
	v_pk_add_f32 v[96:97], v[92:93], v[96:97] neg_lo:[0,1] neg_hi:[0,1]
	v_pk_add_f32 v[94:95], v[98:99], v[90:91]
	v_pk_add_f32 v[92:93], v[98:99], v[90:91] neg_lo:[0,1] neg_hi:[0,1]
	v_xor_b32_e32 v99, 0x80000000, v96
	v_mov_b32_e32 v98, v97
	s_mov_b32 s12, s21
	s_mov_b32 s13, s20
	v_pk_add_f32 v[90:91], v[100:101], v[98:99]
	v_pk_add_f32 v[96:97], v[100:101], v[98:99] neg_lo:[0,1] neg_hi:[0,1]
	s_mov_b32 s10, s20
	s_mov_b32 s11, s36
	v_pk_mul_f32 v[100:101], v[102:103], s[12:13] op_sel:[1,0]
	v_mul_f32_e32 v98, 0x3f3504f3, v108
	v_pk_fma_f32 v[100:101], v[102:103], s[10:11], v[100:101] op_sel_hi:[0,1,1]
	v_mul_f32_e32 v102, 0xbf3504f3, v105
	v_pk_fma_f32 v[98:99], v[108:109], s[8:9], v[98:99] op_sel:[1,0,0] op_sel_hi:[1,1,0]
	v_pk_fma_f32 v[102:103], v[104:105], s[8:9], v[102:103] op_sel_hi:[0,1,0]
	v_pk_add_f32 v[104:105], v[106:107], v[100:101]
	v_pk_add_f32 v[106:107], v[106:107], v[100:101] neg_lo:[0,1] neg_hi:[0,1]
	v_pk_add_f32 v[100:101], v[98:99], v[102:103]
	v_pk_add_f32 v[98:99], v[98:99], v[102:103] neg_lo:[0,1] neg_hi:[0,1]
	v_pk_add_f32 v[102:103], v[104:105], v[100:101]
	v_pk_add_f32 v[100:101], v[104:105], v[100:101] neg_lo:[0,1] neg_hi:[0,1]
	v_xor_b32_e32 v105, 0x80000000, v98
	v_mov_b32_e32 v104, v99
	v_pk_add_f32 v[98:99], v[106:107], v[104:105]
	v_pk_add_f32 v[104:105], v[106:107], v[104:105] neg_lo:[0,1] neg_hi:[0,1]
	v_pk_add_f32 v[106:107], v[146:147], v[112:113]
	s_mov_b32 s12, s28
	s_mov_b32 s13, s34
	s_mov_b32 s10, s34
	s_mov_b32 s11, s27
	v_pk_mul_f32 v[108:109], v[106:107], s[12:13] op_sel:[1,0]
	v_pk_add_f32 v[112:113], v[138:139], v[140:141]
	v_pk_fma_f32 v[106:107], v[106:107], s[10:11], v[108:109] op_sel_hi:[0,1,1]
	v_pk_add_f32 v[108:109], v[136:137], v[114:115]
	v_pk_mul_f32 v[114:115], v[112:113], s[34:35] op_sel:[1,0]
	v_pk_add_f32 v[110:111], v[142:143], v[110:111]
	v_pk_fma_f32 v[112:113], v[112:113], s[28:29], v[114:115] op_sel_hi:[0,1,1]
	v_mul_f32_e32 v114, 0xbf3504f3, v111
	v_pk_fma_f32 v[110:111], v[110:111], s[8:9], v[114:115] op_sel_hi:[0,1,0]
	v_pk_add_f32 v[114:115], v[108:109], v[110:111]
	v_pk_add_f32 v[136:137], v[112:113], v[106:107]
	v_pk_add_f32 v[112:113], v[112:113], v[106:107] neg_lo:[0,1] neg_hi:[0,1]
	v_pk_add_f32 v[110:111], v[108:109], v[110:111] neg_lo:[0,1] neg_hi:[0,1]
	v_pk_add_f32 v[108:109], v[114:115], v[136:137]
	v_pk_add_f32 v[106:107], v[114:115], v[136:137] neg_lo:[0,1] neg_hi:[0,1]
	v_xor_b32_e32 v137, 0x80000000, v112
	v_mov_b32_e32 v136, v113
	v_pk_add_f32 v[114:115], v[110:111], v[136:137]
	v_pk_add_f32 v[110:111], v[110:111], v[136:137] neg_lo:[0,1] neg_hi:[0,1]
	v_mov_b32_e32 v112, v114
	v_mov_b32_e32 v113, v115

.LBB0_1669:
	s_or_b64 exec, exec, s[6:7]
	s_waitcnt lgkmcnt(0)
	s_barrier
	s_and_saveexec_b64 s[6:7], vcc
	s_cbranch_execz .LBB0_1671
	ds_read_b64 v[172:173], v27 offset:61440
	ds_read_b64 v[174:175], v63 offset:57344
	ds_read_b64 v[176:177], v117 offset:53248
	ds_read_b64 v[178:179], v124 offset:49152
	ds_read_b64 v[180:181], v127 offset:45056
	ds_read_b64 v[182:183], v129 offset:40960
	ds_read_b64 v[184:185], v134
	ds_read_b64 v[186:187], v125 offset:4096
	ds_read_b64 v[188:189], v122 offset:8192
	ds_read_b64 v[190:191], v65 offset:12288
	ds_read_b64 v[192:193], v31 offset:16384
	ds_read_b64 v[194:195], v19 offset:20480
	ds_read_b64 v[196:197], v11 offset:24576
	ds_read_b64 v[198:199], v7 offset:28672
	ds_read_b64 v[200:201], v133 offset:32768
	v_and_b32_e32 v70, 15, v130
	v_cvt_f32_ubyte0_e32 v70, v70
	v_mul_f32_e32 v70, 0x3b800000, v70
	v_cos_f32_e32 v96, v70
	v_sin_f32_e32 v97, v70
	s_mov_b32 s10, s27
	v_mov_b32_e32 v99, v96
	v_xor_b32_e32 v98, 0x80000000, v97
	v_mov_b32_e32 v70, v97
	v_pk_mul_f32 v[70:71], v[98:99], v[70:71] op_sel_hi:[1,0]
	s_mov_b32 s11, s26
	v_pk_fma_f32 v[104:105], v[96:97], v[96:97], v[70:71] op_sel_hi:[1,0,1]
	s_mov_b32 s8, s26
	v_pk_mul_f32 v[70:71], v[98:99], v[104:105] op_sel:[0,1]
	s_mov_b32 s9, s28
	v_pk_fma_f32 v[108:109], v[96:97], v[104:105], v[70:71] op_sel_hi:[1,0,1]
	s_mov_b32 s35, s28
	v_pk_mul_f32 v[70:71], v[98:99], v[108:109] op_sel:[0,1]
	s_mov_b32 s29, s26
	v_pk_fma_f32 v[110:111], v[96:97], v[108:109], v[70:71] op_sel_hi:[1,0,1]
	s_mov_b32 s12, s21
	v_pk_mul_f32 v[70:71], v[98:99], v[110:111] op_sel:[0,1]
	s_mov_b32 s13, s20
	v_pk_fma_f32 v[112:113], v[96:97], v[110:111], v[70:71] op_sel_hi:[1,0,1]
	s_nop 0
	v_pk_mul_f32 v[70:71], v[98:99], v[112:113] op_sel:[0,1]
	s_nop 0
	v_pk_fma_f32 v[114:115], v[96:97], v[112:113], v[70:71] op_sel_hi:[1,0,1]
	s_nop 0
	v_pk_mul_f32 v[70:71], v[98:99], v[114:115] op_sel:[0,1]
	s_nop 0
	v_pk_fma_f32 v[136:137], v[96:97], v[114:115], v[70:71] op_sel_hi:[1,0,1]
	s_nop 0
	v_pk_mul_f32 v[70:71], v[98:99], v[136:137] op_sel:[0,1]
	s_nop 0
	v_pk_fma_f32 v[100:101], v[96:97], v[136:137], v[70:71] op_sel_hi:[1,0,1]
	s_nop 0
	v_pk_mul_f32 v[70:71], v[98:99], v[100:101] op_sel:[0,1]
	s_nop 0
	v_pk_fma_f32 v[84:85], v[96:97], v[100:101], v[70:71] op_sel_hi:[1,0,1]
	s_nop 0
	v_pk_mul_f32 v[70:71], v[98:99], v[84:85] op_sel:[0,1]
	s_nop 0
	v_pk_fma_f32 v[94:95], v[96:97], v[84:85], v[70:71] op_sel_hi:[1,0,1]
	s_nop 0
	v_pk_mul_f32 v[70:71], v[98:99], v[94:95] op_sel:[0,1]
	s_nop 0
	v_pk_fma_f32 v[90:91], v[96:97], v[94:95], v[70:71] op_sel_hi:[1,0,1]
	s_nop 0
	v_pk_mul_f32 v[70:71], v[98:99], v[90:91] op_sel:[0,1]
	s_nop 0
	v_pk_fma_f32 v[92:93], v[96:97], v[90:91], v[70:71] op_sel_hi:[1,0,1]
	s_nop 0
	v_pk_mul_f32 v[70:71], v[98:99], v[92:93] op_sel:[0,1]
	s_nop 0
	v_pk_fma_f32 v[88:89], v[96:97], v[92:93], v[70:71] op_sel_hi:[1,0,1]
	s_nop 0
	v_pk_mul_f32 v[70:71], v[98:99], v[88:89] op_sel:[0,1]
	s_nop 0
	v_pk_fma_f32 v[86:87], v[96:97], v[88:89], v[70:71] op_sel_hi:[1,0,1]
	s_nop 0
	v_pk_mul_f32 v[70:71], v[98:99], v[86:87] op_sel:[0,1]
	s_nop 0
	v_pk_fma_f32 v[70:71], v[96:97], v[86:87], v[70:71] op_sel_hi:[1,0,1]
	s_nop 0
	v_xor_b32_e32 v106, 0x80000000, v71
	v_mov_b32_e32 v107, v70
	s_waitcnt lgkmcnt(14)
	v_pk_mul_f32 v[106:107], v[106:107], v[172:173] op_sel:[0,1]
	s_nop 0
	v_pk_fma_f32 v[70:71], v[70:71], v[172:173], v[106:107] op_sel_hi:[1,0,1]
	ds_read_b64 v[172:173], v132 offset:36864
	v_xor_b32_e32 v106, 0x80000000, v87
	v_mov_b32_e32 v107, v86
	s_waitcnt lgkmcnt(14)
	v_pk_mul_f32 v[106:107], v[106:107], v[174:175] op_sel:[0,1]
	s_nop 0
	v_pk_fma_f32 v[86:87], v[86:87], v[174:175], v[106:107] op_sel_hi:[1,0,1]
	v_xor_b32_e32 v106, 0x80000000, v89
	v_mov_b32_e32 v107, v88
	s_waitcnt lgkmcnt(13)
	v_pk_mul_f32 v[106:107], v[106:107], v[176:177] op_sel:[0,1]
	s_nop 0
	v_pk_fma_f32 v[88:89], v[88:89], v[176:177], v[106:107] op_sel_hi:[1,0,1]
	v_xor_b32_e32 v106, 0x80000000, v93
	v_mov_b32_e32 v107, v92
	s_waitcnt lgkmcnt(12)
	v_pk_mul_f32 v[106:107], v[106:107], v[178:179] op_sel:[0,1]
	s_nop 0
	v_pk_fma_f32 v[92:93], v[92:93], v[178:179], v[106:107] op_sel_hi:[1,0,1]
	v_xor_b32_e32 v106, 0x80000000, v91
	v_mov_b32_e32 v107, v90
	s_waitcnt lgkmcnt(11)
	v_pk_mul_f32 v[106:107], v[106:107], v[180:181] op_sel:[0,1]
	s_nop 0
	v_pk_fma_f32 v[90:91], v[90:91], v[180:181], v[106:107] op_sel_hi:[1,0,1]
	v_xor_b32_e32 v106, 0x80000000, v95
	v_mov_b32_e32 v107, v94
	s_waitcnt lgkmcnt(10)
	v_pk_mul_f32 v[106:107], v[106:107], v[182:183] op_sel:[0,1]
	s_nop 0
	v_pk_fma_f32 v[94:95], v[94:95], v[182:183], v[106:107] op_sel_hi:[1,0,1]
	s_waitcnt lgkmcnt(8)
	v_pk_mul_f32 v[98:99], v[98:99], v[186:187] op_sel:[0,1]
	s_nop 0
	v_pk_fma_f32 v[102:103], v[96:97], v[186:187], v[98:99] op_sel_hi:[1,0,1]
	v_xor_b32_e32 v98, 0x80000000, v105
	v_mov_b32_e32 v99, v104
	s_waitcnt lgkmcnt(7)
	v_pk_mul_f32 v[98:99], v[98:99], v[188:189] op_sel:[0,1]
	s_nop 0
	v_pk_fma_f32 v[98:99], v[104:105], v[188:189], v[98:99] op_sel_hi:[1,0,1]
	v_xor_b32_e32 v104, 0x80000000, v109
	v_mov_b32_e32 v105, v108
	v_pk_add_f32 v[142:143], v[98:99], v[94:95] neg_lo:[0,1] neg_hi:[0,1]
	s_waitcnt lgkmcnt(6)
	v_pk_mul_f32 v[104:105], v[104:105], v[190:191] op_sel:[0,1]
	s_nop 0
	v_pk_fma_f32 v[96:97], v[108:109], v[190:191], v[104:105] op_sel_hi:[1,0,1]
	v_xor_b32_e32 v108, 0x80000000, v111
	v_mov_b32_e32 v109, v110
	v_pk_add_f32 v[146:147], v[96:97], v[90:91] neg_lo:[0,1] neg_hi:[0,1]
	s_waitcnt lgkmcnt(5)
	v_pk_mul_f32 v[108:109], v[108:109], v[192:193] op_sel:[0,1]
	s_nop 0
	v_pk_fma_f32 v[108:109], v[110:111], v[192:193], v[108:109] op_sel_hi:[1,0,1]
	v_xor_b32_e32 v110, 0x80000000, v113
	v_mov_b32_e32 v111, v112
	s_waitcnt lgkmcnt(4)
	v_pk_mul_f32 v[110:111], v[110:111], v[194:195] op_sel:[0,1]
	s_nop 0
	v_pk_fma_f32 v[110:111], v[112:113], v[194:195], v[110:111] op_sel_hi:[1,0,1]
	v_xor_b32_e32 v112, 0x80000000, v115
	v_mov_b32_e32 v113, v114
	s_waitcnt lgkmcnt(3)
	v_pk_mul_f32 v[112:113], v[112:113], v[196:197] op_sel:[0,1]
	s_nop 0
	v_pk_fma_f32 v[112:113], v[114:115], v[196:197], v[112:113] op_sel_hi:[1,0,1]
	v_xor_b32_e32 v114, 0x80000000, v137
	v_mov_b32_e32 v115, v136
	s_waitcnt lgkmcnt(2)
	v_pk_mul_f32 v[114:115], v[114:115], v[198:199] op_sel:[0,1]
	s_nop 0
	v_pk_fma_f32 v[104:105], v[136:137], v[198:199], v[114:115] op_sel_hi:[1,0,1]
	v_xor_b32_e32 v136, 0x80000000, v101
	v_mov_b32_e32 v137, v100
	s_waitcnt lgkmcnt(1)
	v_pk_mul_f32 v[136:137], v[136:137], v[200:201] op_sel:[0,1]
	s_nop 0
	v_pk_fma_f32 v[100:101], v[100:101], v[200:201], v[136:137] op_sel_hi:[1,0,1]
	v_xor_b32_e32 v136, 0x80000000, v85
	v_mov_b32_e32 v137, v84
	s_waitcnt lgkmcnt(0)
	v_pk_mul_f32 v[136:137], v[136:137], v[172:173] op_sel:[0,1]
	s_nop 0
	v_pk_fma_f32 v[84:85], v[84:85], v[172:173], v[136:137] op_sel_hi:[1,0,1]
	v_pk_add_f32 v[114:115], v[184:185], v[100:101]
	v_pk_add_f32 v[136:137], v[102:103], v[84:85]
	v_pk_add_f32 v[138:139], v[102:103], v[84:85] neg_lo:[0,1] neg_hi:[0,1]
	v_pk_add_f32 v[84:85], v[88:89], v[110:111]
	v_pk_add_f32 v[88:89], v[110:111], v[88:89] neg_lo:[0,1] neg_hi:[0,1]
	v_pk_add_f32 v[102:103], v[84:85], v[136:137]
	v_pk_add_f32 v[110:111], v[136:137], v[84:85] neg_lo:[0,1] neg_hi:[0,1]
	v_xor_b32_e32 v137, 0x80000000, v88
	v_mov_b32_e32 v136, v89
	v_pk_add_f32 v[84:85], v[94:95], v[98:99]
	v_pk_add_f32 v[88:89], v[86:87], v[112:113]
	v_pk_add_f32 v[86:87], v[112:113], v[86:87] neg_lo:[0,1] neg_hi:[0,1]
	v_pk_add_f32 v[94:95], v[84:85], v[88:89]
	v_pk_add_f32 v[98:99], v[84:85], v[88:89] neg_lo:[0,1] neg_hi:[0,1]
	v_xor_b32_e32 v113, 0x80000000, v86
	v_mov_b32_e32 v112, v87
	v_pk_add_f32 v[84:85], v[90:91], v[96:97]
	v_pk_add_f32 v[86:87], v[70:71], v[104:105]
	v_pk_add_f32 v[106:107], v[184:185], v[100:101] neg_lo:[0,1] neg_hi:[0,1]
	v_pk_add_f32 v[100:101], v[92:93], v[108:109]
	v_pk_add_f32 v[88:89], v[84:85], v[86:87]
	v_pk_add_f32 v[92:93], v[108:109], v[92:93] neg_lo:[0,1] neg_hi:[0,1]
	v_pk_add_f32 v[108:109], v[100:101], v[114:115]
	v_pk_add_f32 v[70:71], v[104:105], v[70:71] neg_lo:[0,1] neg_hi:[0,1]
	v_pk_add_f32 v[104:105], v[84:85], v[86:87] neg_lo:[0,1] neg_hi:[0,1]
	v_pk_add_f32 v[84:85], v[88:89], v[102:103]
	v_pk_add_f32 v[88:89], v[102:103], v[88:89] neg_lo:[0,1] neg_hi:[0,1]
	v_pk_add_f32 v[140:141], v[138:139], v[136:137] neg_lo:[0,1] neg_hi:[0,1]
	v_xor_b32_e32 v149, 0x80000000, v70
	v_mov_b32_e32 v148, v71
	v_pk_add_f32 v[70:71], v[94:95], v[108:109]
	v_pk_add_f32 v[94:95], v[108:109], v[94:95] neg_lo:[0,1] neg_hi:[0,1]
	v_xor_b32_e32 v97, 0x80000000, v88
	v_mov_b32_e32 v96, v89
	v_pk_add_f32 v[144:145], v[142:143], v[112:113] neg_lo:[0,1] neg_hi:[0,1]
	v_pk_add_f32 v[90:91], v[146:147], v[148:149] neg_lo:[0,1] neg_hi:[0,1]
	v_pk_add_f32 v[86:87], v[70:71], v[84:85]
	v_pk_add_f32 v[84:85], v[70:71], v[84:85] neg_lo:[0,1] neg_hi:[0,1]
	v_pk_add_f32 v[70:71], v[94:95], v[96:97]
	v_pk_add_f32 v[88:89], v[94:95], v[96:97] neg_lo:[0,1] neg_hi:[0,1]
	v_pk_mul_f32 v[94:95], v[140:141], s[10:11] op_sel:[1,0]
	v_pk_add_f32 v[100:101], v[114:115], v[100:101] neg_lo:[0,1] neg_hi:[0,1]
	v_xor_b32_e32 v115, 0x80000000, v92
	v_mov_b32_e32 v114, v93
	v_pk_fma_f32 v[94:95], v[140:141], s[8:9], v[94:95] op_sel_hi:[0,1,1]
	v_mul_f32_e32 v96, 0x3f3504f3, v144
	s_mov_b32 s8, s31
	s_mov_b32 s9, s30
	v_pk_mul_f32 v[102:103], v[90:91], s[34:35] op_sel:[1,0]
	v_pk_add_f32 v[92:93], v[106:107], v[114:115] neg_lo:[0,1] neg_hi:[0,1]
	v_pk_fma_f32 v[96:97], v[144:145], s[8:9], v[96:97] op_sel:[1,0,0] op_sel_hi:[1,1,0]
	v_pk_fma_f32 v[90:91], v[90:91], s[28:29], v[102:103] op_sel_hi:[0,1,1]
	v_pk_add_f32 v[102:103], v[92:93], v[96:97]
	v_pk_add_f32 v[96:97], v[92:93], v[96:97] neg_lo:[0,1] neg_hi:[0,1]
	v_pk_add_f32 v[92:93], v[94:95], v[90:91]
	v_pk_add_f32 v[90:91], v[94:95], v[90:91] neg_lo:[0,1] neg_hi:[0,1]
	v_pk_add_f32 v[94:95], v[102:103], v[92:93]
	v_pk_add_f32 v[92:93], v[102:103], v[92:93] neg_lo:[0,1] neg_hi:[0,1]
	v_xor_b32_e32 v103, 0x80000000, v90
	v_mov_b32_e32 v102, v91
	s_mov_b32 s10, s20
	s_mov_b32 s11, s36
	v_pk_mul_f32 v[108:109], v[98:99], s[12:13] op_sel:[1,0]
	v_pk_add_f32 v[90:91], v[96:97], v[102:103]
	v_pk_add_f32 v[96:97], v[96:97], v[102:103] neg_lo:[0,1] neg_hi:[0,1]
	v_mul_f32_e32 v102, 0x3f3504f3, v110
	v_pk_fma_f32 v[98:99], v[98:99], s[10:11], v[108:109] op_sel_hi:[0,1,1]
	v_mul_f32_e32 v108, 0xbf3504f3, v105
	v_pk_fma_f32 v[102:103], v[110:111], s[8:9], v[102:103] op_sel:[1,0,0] op_sel_hi:[1,1,0]
	v_pk_fma_f32 v[104:105], v[104:105], s[8:9], v[108:109] op_sel_hi:[0,1,0]
	v_pk_add_f32 v[108:109], v[100:101], v[98:99]
	v_pk_add_f32 v[110:111], v[100:101], v[98:99] neg_lo:[0,1] neg_hi:[0,1]
	v_pk_add_f32 v[98:99], v[104:105], v[102:103]
	v_pk_add_f32 v[104:105], v[102:103], v[104:105] neg_lo:[0,1] neg_hi:[0,1]
	v_pk_add_f32 v[102:103], v[108:109], v[98:99]
	v_pk_add_f32 v[100:101], v[108:109], v[98:99] neg_lo:[0,1] neg_hi:[0,1]
	v_xor_b32_e32 v109, 0x80000000, v104
	v_mov_b32_e32 v108, v105
	v_pk_add_f32 v[98:99], v[110:111], v[108:109]
	v_pk_add_f32 v[104:105], v[110:111], v[108:109] neg_lo:[0,1] neg_hi:[0,1]
	v_pk_add_f32 v[108:109], v[146:147], v[148:149]
	s_mov_b32 s12, s28
	s_mov_b32 s13, s34
	s_mov_b32 s10, s34
	s_mov_b32 s11, s27
	v_pk_mul_f32 v[110:111], v[108:109], s[12:13] op_sel:[1,0]
	v_pk_add_f32 v[106:107], v[114:115], v[106:107]
	v_pk_fma_f32 v[108:109], v[108:109], s[10:11], v[110:111] op_sel_hi:[0,1,1]
	v_pk_add_f32 v[110:111], v[136:137], v[138:139]
	v_pk_add_f32 v[112:113], v[142:143], v[112:113]
	v_pk_mul_f32 v[114:115], v[110:111], s[34:35] op_sel:[1,0]
	s_nop 0
	v_pk_fma_f32 v[110:111], v[110:111], s[28:29], v[114:115] op_sel_hi:[0,1,1]
	v_mul_f32_e32 v114, 0xbf3504f3, v113
	v_pk_fma_f32 v[112:113], v[112:113], s[8:9], v[114:115] op_sel_hi:[0,1,0]
	v_pk_add_f32 v[114:115], v[106:107], v[112:113]
	v_pk_add_f32 v[136:137], v[106:107], v[112:113] neg_lo:[0,1] neg_hi:[0,1]
	v_pk_add_f32 v[106:107], v[110:111], v[108:109]
	v_pk_add_f32 v[110:111], v[110:111], v[108:109] neg_lo:[0,1] neg_hi:[0,1]
	v_pk_add_f32 v[108:109], v[114:115], v[106:107]
	v_pk_add_f32 v[106:107], v[114:115], v[106:107] neg_lo:[0,1] neg_hi:[0,1]
	v_xor_b32_e32 v115, 0x80000000, v110
	v_mov_b32_e32 v114, v111
	v_pk_add_f32 v[112:113], v[136:137], v[114:115]
	v_pk_add_f32 v[110:111], v[136:137], v[114:115] neg_lo:[0,1] neg_hi:[0,1]

.LBB0_1673:
	s_or_b64 exec, exec, s[6:7]
	s_waitcnt lgkmcnt(0)
	s_barrier
	s_and_saveexec_b64 s[6:7], vcc
	s_cbranch_execz .LBB0_1675
	ds_read_b64 v[172:173], v27 offset:61440
	ds_read_b64 v[174:175], v63 offset:57344
	ds_read_b64 v[176:177], v117 offset:53248
	ds_read_b64 v[178:179], v124 offset:49152
	ds_read_b64 v[180:181], v127 offset:45056
	ds_read_b64 v[182:183], v129 offset:40960
	ds_read_b64 v[184:185], v134
	ds_read_b64 v[186:187], v125 offset:4096
	ds_read_b64 v[188:189], v122 offset:8192
	ds_read_b64 v[190:191], v65 offset:12288
	ds_read_b64 v[192:193], v31 offset:16384
	ds_read_b64 v[194:195], v19 offset:20480
	ds_read_b64 v[196:197], v11 offset:24576
	ds_read_b64 v[198:199], v7 offset:28672
	ds_read_b64 v[200:201], v133 offset:32768
	v_cvt_f32_ubyte0_e32 v70, v130
	v_mul_f32_e32 v70, 0x39800000, v70
	v_cos_f32_e32 v96, v70
	v_sin_f32_e32 v97, v70
	s_mov_b32 s10, s27
	v_mov_b32_e32 v99, v96
	v_xor_b32_e32 v98, 0x80000000, v97
	v_mov_b32_e32 v70, v97
	v_pk_mul_f32 v[70:71], v[98:99], v[70:71] op_sel_hi:[1,0]
	s_mov_b32 s11, s26
	v_pk_fma_f32 v[104:105], v[96:97], v[96:97], v[70:71] op_sel_hi:[1,0,1]
	s_mov_b32 s8, s26
	v_pk_mul_f32 v[70:71], v[98:99], v[104:105] op_sel:[0,1]
	s_mov_b32 s9, s28
	v_pk_fma_f32 v[108:109], v[96:97], v[104:105], v[70:71] op_sel_hi:[1,0,1]
	s_mov_b32 s35, s28
	v_pk_mul_f32 v[70:71], v[98:99], v[108:109] op_sel:[0,1]
	s_mov_b32 s29, s26
	v_pk_fma_f32 v[110:111], v[96:97], v[108:109], v[70:71] op_sel_hi:[1,0,1]
	s_mov_b32 s12, s21
	v_pk_mul_f32 v[70:71], v[98:99], v[110:111] op_sel:[0,1]
	s_mov_b32 s13, s20
	v_pk_fma_f32 v[112:113], v[96:97], v[110:111], v[70:71] op_sel_hi:[1,0,1]
	s_nop 0
	v_pk_mul_f32 v[70:71], v[98:99], v[112:113] op_sel:[0,1]
	s_nop 0
	v_pk_fma_f32 v[136:137], v[96:97], v[112:113], v[70:71] op_sel_hi:[1,0,1]
	s_nop 0
	v_pk_mul_f32 v[70:71], v[98:99], v[136:137] op_sel:[0,1]
	s_nop 0
	v_pk_fma_f32 v[138:139], v[96:97], v[136:137], v[70:71] op_sel_hi:[1,0,1]
	s_nop 0
	v_pk_mul_f32 v[70:71], v[98:99], v[138:139] op_sel:[0,1]
	v_mov_b32_e32 v135, v138
	v_pk_fma_f32 v[100:101], v[96:97], v[138:139], v[70:71] op_sel_hi:[1,0,1]
	s_nop 0
	v_pk_mul_f32 v[70:71], v[98:99], v[100:101] op_sel:[0,1]
	s_nop 0
	v_pk_fma_f32 v[84:85], v[96:97], v[100:101], v[70:71] op_sel_hi:[1,0,1]
	s_nop 0
	v_pk_mul_f32 v[70:71], v[98:99], v[84:85] op_sel:[0,1]
	s_nop 0
	v_pk_fma_f32 v[94:95], v[96:97], v[84:85], v[70:71] op_sel_hi:[1,0,1]
	s_nop 0
	v_pk_mul_f32 v[70:71], v[98:99], v[94:95] op_sel:[0,1]
	s_nop 0
	v_pk_fma_f32 v[90:91], v[96:97], v[94:95], v[70:71] op_sel_hi:[1,0,1]
	s_nop 0
	v_pk_mul_f32 v[70:71], v[98:99], v[90:91] op_sel:[0,1]
	s_nop 0
	v_pk_fma_f32 v[92:93], v[96:97], v[90:91], v[70:71] op_sel_hi:[1,0,1]
	s_nop 0
	v_pk_mul_f32 v[70:71], v[98:99], v[92:93] op_sel:[0,1]
	s_nop 0
	v_pk_fma_f32 v[88:89], v[96:97], v[92:93], v[70:71] op_sel_hi:[1,0,1]
	s_nop 0
	v_pk_mul_f32 v[70:71], v[98:99], v[88:89] op_sel:[0,1]
	s_nop 0
	v_pk_fma_f32 v[86:87], v[96:97], v[88:89], v[70:71] op_sel_hi:[1,0,1]
	s_nop 0
	v_pk_mul_f32 v[70:71], v[98:99], v[86:87] op_sel:[0,1]
	s_nop 0
	v_pk_fma_f32 v[70:71], v[96:97], v[86:87], v[70:71] op_sel_hi:[1,0,1]
	s_nop 0
	v_xor_b32_e32 v106, 0x80000000, v71
	v_mov_b32_e32 v107, v70
	s_waitcnt lgkmcnt(14)
	v_pk_mul_f32 v[106:107], v[106:107], v[172:173] op_sel:[0,1]
	s_nop 0
	v_pk_fma_f32 v[70:71], v[70:71], v[172:173], v[106:107] op_sel_hi:[1,0,1]
	ds_read_b64 v[172:173], v132 offset:36864
	v_xor_b32_e32 v106, 0x80000000, v87
	v_mov_b32_e32 v107, v86
	s_waitcnt lgkmcnt(14)
	v_pk_mul_f32 v[106:107], v[106:107], v[174:175] op_sel:[0,1]
	s_nop 0
	v_pk_fma_f32 v[86:87], v[86:87], v[174:175], v[106:107] op_sel_hi:[1,0,1]
	v_xor_b32_e32 v106, 0x80000000, v89
	v_mov_b32_e32 v107, v88
	s_waitcnt lgkmcnt(13)
	v_pk_mul_f32 v[106:107], v[106:107], v[176:177] op_sel:[0,1]
	s_nop 0
	v_pk_fma_f32 v[88:89], v[88:89], v[176:177], v[106:107] op_sel_hi:[1,0,1]
	v_xor_b32_e32 v106, 0x80000000, v93
	v_mov_b32_e32 v107, v92
	s_waitcnt lgkmcnt(12)
	v_pk_mul_f32 v[106:107], v[106:107], v[178:179] op_sel:[0,1]
	s_nop 0
	v_pk_fma_f32 v[92:93], v[92:93], v[178:179], v[106:107] op_sel_hi:[1,0,1]
	v_xor_b32_e32 v106, 0x80000000, v91
	v_mov_b32_e32 v107, v90
	s_waitcnt lgkmcnt(11)
	v_pk_mul_f32 v[106:107], v[106:107], v[180:181] op_sel:[0,1]
	s_nop 0
	v_pk_fma_f32 v[90:91], v[90:91], v[180:181], v[106:107] op_sel_hi:[1,0,1]
	v_xor_b32_e32 v106, 0x80000000, v95
	v_mov_b32_e32 v107, v94
	s_waitcnt lgkmcnt(10)
	v_pk_mul_f32 v[106:107], v[106:107], v[182:183] op_sel:[0,1]
	s_nop 0
	v_pk_fma_f32 v[94:95], v[94:95], v[182:183], v[106:107] op_sel_hi:[1,0,1]
	v_xor_b32_e32 v134, 0x80000000, v139
	s_waitcnt lgkmcnt(8)
	v_pk_mul_f32 v[98:99], v[98:99], v[186:187] op_sel:[0,1]
	s_nop 0
	v_pk_fma_f32 v[102:103], v[96:97], v[186:187], v[98:99] op_sel_hi:[1,0,1]
	v_xor_b32_e32 v98, 0x80000000, v105
	v_mov_b32_e32 v99, v104
	s_waitcnt lgkmcnt(7)
	v_pk_mul_f32 v[98:99], v[98:99], v[188:189] op_sel:[0,1]
	s_nop 0
	v_pk_fma_f32 v[98:99], v[104:105], v[188:189], v[98:99] op_sel_hi:[1,0,1]
	v_xor_b32_e32 v104, 0x80000000, v109
	v_mov_b32_e32 v105, v108
	v_pk_add_f32 v[142:143], v[98:99], v[94:95] neg_lo:[0,1] neg_hi:[0,1]
	s_waitcnt lgkmcnt(6)
	v_pk_mul_f32 v[104:105], v[104:105], v[190:191] op_sel:[0,1]
	s_nop 0
	v_pk_fma_f32 v[96:97], v[108:109], v[190:191], v[104:105] op_sel_hi:[1,0,1]
	v_xor_b32_e32 v108, 0x80000000, v111
	v_mov_b32_e32 v109, v110
	v_pk_add_f32 v[146:147], v[96:97], v[90:91] neg_lo:[0,1] neg_hi:[0,1]
	s_waitcnt lgkmcnt(5)
	v_pk_mul_f32 v[108:109], v[108:109], v[192:193] op_sel:[0,1]
	s_nop 0
	v_pk_fma_f32 v[108:109], v[110:111], v[192:193], v[108:109] op_sel_hi:[1,0,1]
	v_xor_b32_e32 v110, 0x80000000, v113
	v_mov_b32_e32 v111, v112
	s_waitcnt lgkmcnt(4)
	v_pk_mul_f32 v[110:111], v[110:111], v[194:195] op_sel:[0,1]
	s_nop 0
	v_pk_fma_f32 v[110:111], v[112:113], v[194:195], v[110:111] op_sel_hi:[1,0,1]
	v_xor_b32_e32 v112, 0x80000000, v137
	v_mov_b32_e32 v113, v136
	s_waitcnt lgkmcnt(3)
	v_pk_mul_f32 v[112:113], v[112:113], v[196:197] op_sel:[0,1]
	s_nop 0
	v_pk_fma_f32 v[112:113], v[136:137], v[196:197], v[112:113] op_sel_hi:[1,0,1]
	v_xor_b32_e32 v136, 0x80000000, v101
	v_mov_b32_e32 v137, v100
	s_waitcnt lgkmcnt(2)
	v_pk_mul_f32 v[134:135], v[134:135], v[198:199] op_sel:[0,1]
	s_nop 0
	v_pk_fma_f32 v[104:105], v[138:139], v[198:199], v[134:135] op_sel_hi:[1,0,1]
	s_waitcnt lgkmcnt(1)
	v_pk_mul_f32 v[136:137], v[136:137], v[200:201] op_sel:[0,1]
	s_nop 0
	v_pk_fma_f32 v[100:101], v[100:101], v[200:201], v[136:137] op_sel_hi:[1,0,1]
	v_xor_b32_e32 v136, 0x80000000, v85
	v_mov_b32_e32 v137, v84
	s_waitcnt lgkmcnt(0)
	v_pk_mul_f32 v[136:137], v[136:137], v[172:173] op_sel:[0,1]
	s_nop 0
	v_pk_fma_f32 v[84:85], v[84:85], v[172:173], v[136:137] op_sel_hi:[1,0,1]
	v_pk_add_f32 v[134:135], v[184:185], v[100:101]
	v_pk_add_f32 v[136:137], v[102:103], v[84:85]
	v_pk_add_f32 v[138:139], v[102:103], v[84:85] neg_lo:[0,1] neg_hi:[0,1]
	v_pk_add_f32 v[84:85], v[88:89], v[110:111]
	v_pk_add_f32 v[88:89], v[110:111], v[88:89] neg_lo:[0,1] neg_hi:[0,1]
	v_pk_add_f32 v[102:103], v[84:85], v[136:137]
	v_pk_add_f32 v[110:111], v[136:137], v[84:85] neg_lo:[0,1] neg_hi:[0,1]
	v_xor_b32_e32 v137, 0x80000000, v88
	v_mov_b32_e32 v136, v89
	v_pk_add_f32 v[84:85], v[94:95], v[98:99]
	v_pk_add_f32 v[88:89], v[86:87], v[112:113]
	v_pk_add_f32 v[86:87], v[112:113], v[86:87] neg_lo:[0,1] neg_hi:[0,1]
	v_pk_add_f32 v[94:95], v[84:85], v[88:89]
	v_pk_add_f32 v[98:99], v[84:85], v[88:89] neg_lo:[0,1] neg_hi:[0,1]
	v_xor_b32_e32 v113, 0x80000000, v86
	v_mov_b32_e32 v112, v87
	v_pk_add_f32 v[84:85], v[90:91], v[96:97]
	v_pk_add_f32 v[86:87], v[70:71], v[104:105]
	v_pk_add_f32 v[106:107], v[184:185], v[100:101] neg_lo:[0,1] neg_hi:[0,1]
	v_pk_add_f32 v[100:101], v[92:93], v[108:109]
	v_pk_add_f32 v[88:89], v[84:85], v[86:87]
	v_pk_add_f32 v[92:93], v[108:109], v[92:93] neg_lo:[0,1] neg_hi:[0,1]
	v_pk_add_f32 v[108:109], v[100:101], v[134:135]
	v_pk_add_f32 v[70:71], v[104:105], v[70:71] neg_lo:[0,1] neg_hi:[0,1]
	v_pk_add_f32 v[104:105], v[84:85], v[86:87] neg_lo:[0,1] neg_hi:[0,1]
	v_pk_add_f32 v[84:85], v[88:89], v[102:103]
	v_pk_add_f32 v[88:89], v[102:103], v[88:89] neg_lo:[0,1] neg_hi:[0,1]
	v_pk_add_f32 v[140:141], v[138:139], v[136:137] neg_lo:[0,1] neg_hi:[0,1]
	v_xor_b32_e32 v149, 0x80000000, v70
	v_mov_b32_e32 v148, v71
	v_pk_add_f32 v[70:71], v[94:95], v[108:109]
	v_pk_add_f32 v[94:95], v[108:109], v[94:95] neg_lo:[0,1] neg_hi:[0,1]
	v_xor_b32_e32 v97, 0x80000000, v88
	v_mov_b32_e32 v96, v89
	v_pk_add_f32 v[144:145], v[142:143], v[112:113] neg_lo:[0,1] neg_hi:[0,1]
	v_pk_add_f32 v[90:91], v[146:147], v[148:149] neg_lo:[0,1] neg_hi:[0,1]
	v_pk_add_f32 v[86:87], v[70:71], v[84:85]
	v_pk_add_f32 v[84:85], v[70:71], v[84:85] neg_lo:[0,1] neg_hi:[0,1]
	v_pk_add_f32 v[70:71], v[94:95], v[96:97]
	v_pk_add_f32 v[88:89], v[94:95], v[96:97] neg_lo:[0,1] neg_hi:[0,1]
	v_pk_mul_f32 v[94:95], v[140:141], s[10:11] op_sel:[1,0]
	v_pk_add_f32 v[100:101], v[134:135], v[100:101] neg_lo:[0,1] neg_hi:[0,1]
	v_xor_b32_e32 v135, 0x80000000, v92
	v_mov_b32_e32 v134, v93
	v_pk_fma_f32 v[94:95], v[140:141], s[8:9], v[94:95] op_sel_hi:[0,1,1]
	v_mul_f32_e32 v96, 0x3f3504f3, v144
	s_mov_b32 s8, s31
	s_mov_b32 s9, s30
	v_pk_mul_f32 v[102:103], v[90:91], s[34:35] op_sel:[1,0]
	v_pk_add_f32 v[92:93], v[106:107], v[134:135] neg_lo:[0,1] neg_hi:[0,1]
	v_pk_fma_f32 v[96:97], v[144:145], s[8:9], v[96:97] op_sel:[1,0,0] op_sel_hi:[1,1,0]
	v_pk_fma_f32 v[90:91], v[90:91], s[28:29], v[102:103] op_sel_hi:[0,1,1]
	v_pk_add_f32 v[102:103], v[92:93], v[96:97]
	v_pk_add_f32 v[96:97], v[92:93], v[96:97] neg_lo:[0,1] neg_hi:[0,1]
	v_pk_add_f32 v[92:93], v[94:95], v[90:91]
	v_pk_add_f32 v[90:91], v[94:95], v[90:91] neg_lo:[0,1] neg_hi:[0,1]
	v_pk_add_f32 v[94:95], v[102:103], v[92:93]
	v_pk_add_f32 v[92:93], v[102:103], v[92:93] neg_lo:[0,1] neg_hi:[0,1]
	v_xor_b32_e32 v103, 0x80000000, v90
	v_mov_b32_e32 v102, v91
	s_mov_b32 s10, s20
	s_mov_b32 s11, s36
	v_pk_mul_f32 v[108:109], v[98:99], s[12:13] op_sel:[1,0]
	v_pk_add_f32 v[90:91], v[96:97], v[102:103]
	v_pk_add_f32 v[96:97], v[96:97], v[102:103] neg_lo:[0,1] neg_hi:[0,1]
	v_mul_f32_e32 v102, 0x3f3504f3, v110
	v_pk_fma_f32 v[98:99], v[98:99], s[10:11], v[108:109] op_sel_hi:[0,1,1]
	v_mul_f32_e32 v108, 0xbf3504f3, v105
	v_pk_fma_f32 v[102:103], v[110:111], s[8:9], v[102:103] op_sel:[1,0,0] op_sel_hi:[1,1,0]
	v_pk_fma_f32 v[104:105], v[104:105], s[8:9], v[108:109] op_sel_hi:[0,1,0]
	v_pk_add_f32 v[108:109], v[100:101], v[98:99]
	v_pk_add_f32 v[110:111], v[100:101], v[98:99] neg_lo:[0,1] neg_hi:[0,1]
	v_pk_add_f32 v[98:99], v[104:105], v[102:103]
	v_pk_add_f32 v[104:105], v[102:103], v[104:105] neg_lo:[0,1] neg_hi:[0,1]
	v_pk_add_f32 v[102:103], v[108:109], v[98:99]
	v_pk_add_f32 v[100:101], v[108:109], v[98:99] neg_lo:[0,1] neg_hi:[0,1]
	v_xor_b32_e32 v109, 0x80000000, v104
	v_mov_b32_e32 v108, v105
	v_pk_add_f32 v[98:99], v[110:111], v[108:109]
	v_pk_add_f32 v[104:105], v[110:111], v[108:109] neg_lo:[0,1] neg_hi:[0,1]
	v_pk_add_f32 v[108:109], v[146:147], v[148:149]
	s_mov_b32 s12, s28
	s_mov_b32 s13, s34
	s_mov_b32 s10, s34
	s_mov_b32 s11, s27
	v_pk_mul_f32 v[110:111], v[108:109], s[12:13] op_sel:[1,0]
	v_pk_add_f32 v[106:107], v[134:135], v[106:107]
	v_pk_fma_f32 v[108:109], v[108:109], s[10:11], v[110:111] op_sel_hi:[0,1,1]
	v_pk_add_f32 v[110:111], v[136:137], v[138:139]
	v_pk_add_f32 v[112:113], v[142:143], v[112:113]
	v_pk_mul_f32 v[134:135], v[110:111], s[34:35] op_sel:[1,0]
	s_nop 0
	v_pk_fma_f32 v[110:111], v[110:111], s[28:29], v[134:135] op_sel_hi:[0,1,1]
	v_mul_f32_e32 v134, 0xbf3504f3, v113
	v_pk_fma_f32 v[112:113], v[112:113], s[8:9], v[134:135] op_sel_hi:[0,1,0]
	v_pk_add_f32 v[134:135], v[106:107], v[112:113]
	v_pk_add_f32 v[136:137], v[106:107], v[112:113] neg_lo:[0,1] neg_hi:[0,1]
	v_pk_add_f32 v[106:107], v[110:111], v[108:109]
	v_pk_add_f32 v[110:111], v[110:111], v[108:109] neg_lo:[0,1] neg_hi:[0,1]
	v_pk_add_f32 v[108:109], v[134:135], v[106:107]
	v_pk_add_f32 v[106:107], v[134:135], v[106:107] neg_lo:[0,1] neg_hi:[0,1]
	v_xor_b32_e32 v135, 0x80000000, v110
	v_mov_b32_e32 v134, v111
	v_pk_add_f32 v[112:113], v[136:137], v[134:135]
	v_pk_add_f32 v[110:111], v[136:137], v[134:135] neg_lo:[0,1] neg_hi:[0,1]

.LBB0_1677:
	s_or_b64 exec, exec, s[6:7]
	s_waitcnt lgkmcnt(0)
	s_barrier
	s_and_saveexec_b64 s[6:7], vcc
	s_cbranch_execz .LBB0_1679
	ds_read_b64 v[172:173], v133 offset:32768
	v_cvt_f32_i32_e32 v84, v130
	v_lshlrev_b32_e32 v86, 3, v131
	v_lshlrev_b32_e32 v87, 3, v130
	v_mul_f32_e32 v84, 0x39000000, v84
	v_sin_f32_e32 v85, v84
	v_cos_f32_e32 v84, v84
	v_add3_u32 v90, 0, v86, v87
	ds_read_b64 v[174:175], v90
	v_xor_b32_e32 v88, 0x80000000, v85
	v_mov_b32_e32 v89, v84
	v_cvt_f32_i32_e32 v91, v128
	s_waitcnt lgkmcnt(1)
	v_pk_mul_f32 v[88:89], v[88:89], v[172:173] op_sel:[0,1]
	v_cvt_f32_i32_e32 v59, v59
	v_pk_fma_f32 v[70:71], v[84:85], v[172:173], v[88:89] op_sel_hi:[1,0,1]
	v_cvt_f32_i32_e32 v23, v23
	s_waitcnt lgkmcnt(0)
	v_pk_add_f32 v[70:71], v[174:175], v[70:71]
	ds_write_b64 v90, v[70:71]
	ds_read_b64 v[172:173], v132 offset:36864
	ds_read_b64 v[174:175], v125 offset:4096
	v_mul_f32_e32 v71, 0x39000000, v91
	v_cos_f32_e32 v70, v71
	v_sin_f32_e32 v71, v71
	v_cvt_f32_i32_e32 v90, v126
	v_mov_b32_e32 v89, v70
	v_xor_b32_e32 v88, 0x80000000, v71
	s_waitcnt lgkmcnt(1)
	v_pk_mul_f32 v[88:89], v[88:89], v[172:173] op_sel:[0,1]
	v_cvt_f32_i32_e32 v15, v15
	v_pk_fma_f32 v[70:71], v[70:71], v[172:173], v[88:89] op_sel_hi:[1,0,1]
	s_waitcnt lgkmcnt(0)
	v_pk_add_f32 v[70:71], v[174:175], v[70:71]
	ds_write_b64 v125, v[70:71] offset:4096
	ds_read_b64 v[172:173], v129 offset:40960
	ds_read_b64 v[174:175], v122 offset:8192
	v_mul_f32_e32 v71, 0x39000000, v90
	v_cos_f32_e32 v70, v71
	v_sin_f32_e32 v71, v71
	v_cvt_f32_i32_e32 v90, v123
	v_mov_b32_e32 v89, v70
	v_xor_b32_e32 v88, 0x80000000, v71
	s_waitcnt lgkmcnt(1)
	v_pk_mul_f32 v[88:89], v[88:89], v[172:173] op_sel:[0,1]
	s_nop 0
	v_pk_fma_f32 v[70:71], v[70:71], v[172:173], v[88:89] op_sel_hi:[1,0,1]
	s_waitcnt lgkmcnt(0)
	v_pk_add_f32 v[70:71], v[174:175], v[70:71]
	ds_write_b64 v122, v[70:71] offset:8192
	ds_read_b64 v[172:173], v127 offset:45056
	ds_read_b64 v[174:175], v65 offset:12288
	v_mul_f32_e32 v71, 0x39000000, v90
	v_cos_f32_e32 v70, v71
	v_sin_f32_e32 v71, v71
	v_cvt_f32_i32_e32 v90, v116
	v_mov_b32_e32 v89, v70
	v_xor_b32_e32 v88, 0x80000000, v71
	s_waitcnt lgkmcnt(1)
	v_pk_mul_f32 v[88:89], v[88:89], v[172:173] op_sel:[0,1]
	s_nop 0
	v_pk_fma_f32 v[70:71], v[70:71], v[172:173], v[88:89] op_sel_hi:[1,0,1]
	s_waitcnt lgkmcnt(0)
	v_pk_add_f32 v[70:71], v[174:175], v[70:71]
	ds_write_b64 v65, v[70:71] offset:12288
	ds_read_b64 v[172:173], v124 offset:49152
	ds_read_b64 v[174:175], v31 offset:16384
	v_mul_f32_e32 v65, 0x39000000, v90
	v_cos_f32_e32 v70, v65
	v_sin_f32_e32 v71, v65
	v_mov_b32_e32 v89, v70
	v_xor_b32_e32 v88, 0x80000000, v71
	s_waitcnt lgkmcnt(1)
	v_pk_mul_f32 v[88:89], v[88:89], v[172:173] op_sel:[0,1]
	s_nop 0
	v_pk_fma_f32 v[70:71], v[70:71], v[172:173], v[88:89] op_sel_hi:[1,0,1]
	s_waitcnt lgkmcnt(0)
	v_pk_add_f32 v[70:71], v[174:175], v[70:71]
	ds_write_b64 v31, v[70:71] offset:16384
	ds_read_b64 v[172:173], v117 offset:53248
	ds_read_b64 v[174:175], v19 offset:20480
	v_mul_f32_e32 v31, 0x39000000, v59
	v_cos_f32_e32 v70, v31
	v_sin_f32_e32 v71, v31
	v_mov_b32_e32 v89, v70
	v_xor_b32_e32 v88, 0x80000000, v71
	s_waitcnt lgkmcnt(1)
	v_pk_mul_f32 v[88:89], v[88:89], v[172:173] op_sel:[0,1]
	s_nop 0
	v_pk_fma_f32 v[70:71], v[70:71], v[172:173], v[88:89] op_sel_hi:[1,0,1]
	s_waitcnt lgkmcnt(0)
	v_pk_add_f32 v[70:71], v[174:175], v[70:71]
	ds_write_b64 v19, v[70:71] offset:20480
	ds_read_b64 v[172:173], v63 offset:57344
	ds_read_b64 v[174:175], v11 offset:24576
	v_mul_f32_e32 v19, 0x39000000, v23
	v_cos_f32_e32 v70, v19
	v_sin_f32_e32 v71, v19
	v_mov_b32_e32 v89, v70
	v_xor_b32_e32 v88, 0x80000000, v71
	s_waitcnt lgkmcnt(1)
	v_pk_mul_f32 v[88:89], v[88:89], v[172:173] op_sel:[0,1]
	s_nop 0
	v_pk_fma_f32 v[70:71], v[70:71], v[172:173], v[88:89] op_sel_hi:[1,0,1]
	s_waitcnt lgkmcnt(0)
	v_pk_add_f32 v[70:71], v[174:175], v[70:71]
	ds_write_b64 v11, v[70:71] offset:24576
	v_mul_f32_e32 v11, 0x39000000, v15
	v_cos_f32_e32 v70, v11
	v_sin_f32_e32 v71, v11
	ds_read_b64 v[84:85], v27 offset:61440
	ds_read_b64 v[86:87], v7 offset:28672
	v_mov_b32_e32 v89, v70
	v_xor_b32_e32 v88, 0x80000000, v71
	s_waitcnt lgkmcnt(1)
	v_pk_mul_f32 v[88:89], v[88:89], v[84:85] op_sel:[0,1]
	s_nop 0
	v_pk_fma_f32 v[70:71], v[70:71], v[84:85], v[88:89] op_sel_hi:[1,0,1]
	s_waitcnt lgkmcnt(0)
	v_pk_add_f32 v[70:71], v[86:87], v[70:71]
	ds_write_b64 v7, v[70:71] offset:28672

.LBB0_1697:
	s_mul_i32 s14, s12, 0x4400
	s_add_i32 s5, s12, 0x800
	s_add_i32 s3, s14, 0x2200000
	s_mul_hi_i32 s2, s5, 0x4400
	s_add_u32 s3, s92, s3
	s_addc_u32 s4, s93, s2
	s_add_u32 s2, s3, 0x4000
	s_addc_u32 s3, s4, 0
	global_load_dword v0, v7, s[2:3]
	s_ashr_i32 s13, s12, 31
	global_load_dword v1, v11, s[2:3]
	global_load_dword v2, v15, s[2:3]
	global_load_dword v4, v19, s[2:3]
	s_mul_hi_i32 s2, s12, 0x4400
	s_add_u32 s3, s92, s14
	s_addc_u32 s4, s93, s2
	s_add_u32 s2, s3, 0x4000
	s_addc_u32 s3, s4, 0
	global_load_dword v5, v64, s[2:3]
	global_load_dword v6, v23, s[2:3]
	global_load_dword v8, v27, s[2:3]
	global_load_dword v9, v31, s[2:3]
	s_add_i32 s2, s12, 0x1800
	s_add_i32 s3, s14, 0x6600000
	s_mul_hi_i32 s2, s2, 0x4400
	s_add_u32 s3, s92, s3
	s_addc_u32 s4, s93, s2
	s_add_u32 s2, s3, 0x4000
	s_addc_u32 s3, s4, 0
	global_load_dword v10, v7, s[2:3]
	s_add_i32 s4, s12, 0x1000
	s_add_i32 s14, s14, 0x4400000
	global_load_dword v12, v11, s[2:3]
	global_load_dword v13, v15, s[2:3]
	global_load_dword v14, v19, s[2:3]
	s_mul_hi_i32 s2, s4, 0x4400
	s_add_u32 s3, s92, s14
	s_addc_u32 s14, s93, s2
	s_add_u32 s2, s3, 0x4000
	s_addc_u32 s3, s14, 0
	global_load_dword v16, v64, s[2:3]
	global_load_dword v17, v23, s[2:3]
	global_load_dword v18, v27, s[2:3]
	global_load_dword v20, v31, s[2:3]
	v_mbcnt_lo_u32_b32 v24, -1, 0
	v_mbcnt_hi_u32_b32 v24, -1, v24
	v_readlane_b32 s16, v240, 49
	v_readlane_b32 s26, v240, 59
	v_lshlrev_b32_e32 v24, 2, v24
	v_xor_b32_e32 v25, 0x80, v24
	v_readlane_b32 s27, v240, 60
	v_readlane_b32 s30, v240, 63
	v_readlane_b32 s31, v239, 0
	s_mov_b64 s[26:27], s[30:31]
	v_readlane_b32 s17, v240, 50
	v_readlane_b32 s18, v240, 51
	v_readlane_b32 s36, v239, 19
	v_readlane_b32 s19, v240, 52
	v_readlane_b32 s37, v239, 20
	v_readlane_b32 s20, v240, 53
	v_readlane_b32 s21, v240, 54
	s_mul_hi_i32 s5, s5, 0x8800
	v_readlane_b32 s22, v240, 55
	v_readlane_b32 s23, v240, 56
	v_readlane_b32 s24, v240, 57
	v_readlane_b32 s25, v240, 58
	v_readlane_b32 s28, v240, 61
	v_readlane_b32 s29, v240, 62
	v_mov_b32_e32 v86, 0
	v_mov_b32_e32 v87, v65
	v_mov_b32_e32 v92, 0
	v_mov_b32_e32 v93, v65
	v_mov_b32_e32 v90, 0
	v_mov_b32_e32 v91, v65
	v_mov_b32_e32 v88, 0
	v_mov_b32_e32 v89, v65
	v_readlane_b32 s38, v239, 21
	v_readlane_b32 s39, v239, 22
	v_readlane_b32 s40, v239, 23
	v_readlane_b32 s41, v239, 24
	v_readlane_b32 s42, v239, 25
	v_readlane_b32 s43, v239, 26
	v_readlane_b32 s44, v239, 27
	v_readlane_b32 s45, v239, 28
	v_readlane_b32 s46, v239, 29
	v_readlane_b32 s47, v239, 30
	v_readlane_b32 s48, v239, 31
	v_readlane_b32 s49, v239, 32
	v_readlane_b32 s50, v239, 33
	v_readlane_b32 s51, v239, 34
	s_waitcnt vmcnt(15)
	v_cndmask_b32_e64 v0, v0, 0, s[6:7]
	s_waitcnt vmcnt(14)
	v_add_f32_e64 v21, |v0|, |v1|
	s_waitcnt vmcnt(13)
	v_add_f32_e64 v21, v21, |v2|
	s_waitcnt vmcnt(12)
	v_add_f32_e64 v21, v21, |v4|
	s_waitcnt vmcnt(11)
	v_add_f32_e64 v21, v21, |v5|
	s_waitcnt vmcnt(10)
	v_add_f32_e64 v21, v21, |v6|
	s_waitcnt vmcnt(9)
	v_add_f32_e64 v21, v21, |v8|
	s_waitcnt vmcnt(8)
	v_add_f32_e64 v21, v21, |v9|
	ds_bpermute_b32 v25, v25, v21
	s_waitcnt lgkmcnt(0)
	v_add_f32_e32 v21, v21, v25
	v_xor_b32_e32 v25, 64, v24
	ds_bpermute_b32 v25, v25, v21
	s_waitcnt vmcnt(7)
	v_cndmask_b32_e64 v10, v10, 0, s[6:7]
	s_waitcnt vmcnt(6)
	v_add_f32_e64 v22, |v10|, |v12|
	s_waitcnt vmcnt(5)
	v_add_f32_e64 v22, v22, |v13|
	s_waitcnt vmcnt(4)
	v_add_f32_e64 v22, v22, |v14|
	s_waitcnt lgkmcnt(0)
	v_add_f32_e32 v21, v21, v25
	v_xor_b32_e32 v25, 32, v24
	ds_bpermute_b32 v25, v25, v21
	s_waitcnt vmcnt(3)
	v_add_f32_e64 v22, v22, |v16|
	s_waitcnt vmcnt(2)
	v_add_f32_e64 v22, v22, |v17|
	s_waitcnt vmcnt(1)
	v_add_f32_e64 v22, v22, |v18|
	s_waitcnt vmcnt(0)
	v_add_f32_e64 v22, v22, |v20|
	s_waitcnt lgkmcnt(0)
	v_add_f32_e32 v21, v21, v25
	v_xor_b32_e32 v25, 16, v24
	ds_bpermute_b32 v25, v25, v21
	s_waitcnt lgkmcnt(0)
	v_add_f32_e32 v21, v21, v25
	v_xor_b32_e32 v25, 8, v24
	ds_bpermute_b32 v25, v25, v21
	v_xor_b32_e32 v24, 4, v24
	s_waitcnt lgkmcnt(0)
	v_add_f32_e32 v21, v21, v25
	ds_bpermute_b32 v24, v24, v21
	s_waitcnt lgkmcnt(0)
	v_add_f32_e32 v21, v21, v24
	v_mbcnt_lo_u32_b32 v24, -1, 0
	v_mbcnt_hi_u32_b32 v24, -1, v24
	s_nop 0
	v_lshlrev_b32_e32 v24, 2, v24
	v_xor_b32_e32 v25, 0x80, v24
	ds_bpermute_b32 v25, v25, v22
	s_waitcnt lgkmcnt(0)
	v_add_f32_e32 v22, v22, v25
	v_xor_b32_e32 v25, 64, v24
	ds_bpermute_b32 v25, v25, v22
	s_waitcnt lgkmcnt(0)
	v_add_f32_e32 v22, v22, v25
	v_xor_b32_e32 v25, 32, v24
	ds_bpermute_b32 v25, v25, v22
	s_waitcnt lgkmcnt(0)
	v_add_f32_e32 v22, v22, v25
	v_xor_b32_e32 v25, 16, v24
	ds_bpermute_b32 v25, v25, v22
	s_waitcnt lgkmcnt(0)
	v_add_f32_e32 v22, v22, v25
	v_xor_b32_e32 v25, 8, v24
	ds_bpermute_b32 v25, v25, v22
	v_xor_b32_e32 v24, 4, v24
	s_waitcnt lgkmcnt(0)
	v_add_f32_e32 v22, v22, v25
	ds_bpermute_b32 v24, v24, v22
	s_waitcnt lgkmcnt(0)
	v_add_f32_e32 v22, v22, v24
	v_div_scale_f32 v24, s[2:3], v21, v21, 1.0
	v_rcp_f32_e32 v25, v24
	s_nop 0
	v_fma_f32 v26, -v24, v25, 1.0
	v_fmac_f32_e32 v25, v26, v25
	v_div_scale_f32 v26, vcc, 1.0, v21, 1.0
	v_mul_f32_e32 v28, v26, v25
	v_fma_f32 v29, -v24, v28, v26
	v_fmac_f32_e32 v28, v29, v25
	v_fma_f32 v24, -v24, v28, v26
	v_div_fmas_f32 v24, v24, v25, v28
	v_div_fixup_f32 v21, v24, v21, 1.0
	v_div_scale_f32 v24, s[2:3], v22, v22, 1.0
	v_rcp_f32_e32 v25, v24
	v_mul_f32_e32 v0, v0, v21
	v_mul_f32_e32 v1, v1, v21
	ds_write2st64_b32 v3, v0, v1 offset1:1
	v_fma_f32 v26, -v24, v25, 1.0
	v_fmac_f32_e32 v25, v26, v25
	v_div_scale_f32 v26, vcc, 1.0, v22, 1.0
	v_mul_f32_e32 v28, v26, v25
	v_fma_f32 v29, -v24, v28, v26
	v_fmac_f32_e32 v28, v29, v25
	v_fma_f32 v24, -v24, v28, v26
	v_div_fmas_f32 v24, v24, v25, v28
	v_div_fixup_f32 v22, v24, v22, 1.0
	v_mul_f32_e32 v10, v10, v22
	v_mul_f32_e32 v0, v12, v22
	ds_write2st64_b32 v3, v10, v0 offset0:8 offset1:9
	v_mul_f32_e32 v0, v2, v21
	v_mul_f32_e32 v2, v4, v21
	v_mul_f32_e32 v1, v13, v22
	ds_write2st64_b32 v3, v0, v2 offset0:2 offset1:3
	v_mul_f32_e32 v0, v14, v22
	ds_write2st64_b32 v3, v1, v0 offset0:10 offset1:11
	v_mul_f32_e32 v0, v5, v21
	v_mul_f32_e32 v2, v6, v21
	v_mul_f32_e32 v1, v16, v22
	ds_write2st64_b32 v3, v0, v2 offset0:4 offset1:5
	v_mul_f32_e32 v0, v17, v22
	s_mul_i32 s3, s12, 0x8800
	ds_write2st64_b32 v3, v1, v0 offset0:12 offset1:13
	v_mul_f32_e32 v0, v8, v21
	v_mul_f32_e32 v2, v9, v21
	s_mul_hi_i32 s2, s12, 0x8800
	s_add_u32 s14, s60, s3
	v_mul_f32_e32 v1, v18, v22
	ds_write2st64_b32 v3, v0, v2 offset0:6 offset1:7
	v_mul_f32_e32 v0, v20, v22
	s_addc_u32 s15, s61, s2
	ds_write2st64_b32 v3, v1, v0 offset0:14 offset1:15
	v_lshl_add_u64 v[0:1], s[14:15], 0, v[64:65]
	s_lshl_b64 s[14:15], s[12:13], 2
	s_add_u32 s16, s26, s14
	s_addc_u32 s17, s27, s15
	global_load_dword v62, v65, s[16:17]
	global_load_dword v80, v47, s[16:17]
	global_load_dword v60, v51, s[16:17]
	s_add_u32 s18, s36, s14
	v_lshl_add_u64 v[4:5], v[0:1], 0, s[10:11]
	s_addc_u32 s19, s37, s15
	global_load_dword v82, v65, s[18:19]
	global_load_dwordx3 v[24:26], v[4:5], off offset:1020
	global_load_dwordx3 v[28:30], v[4:5], off offset:-4
	global_load_dwordx3 v[16:18], v[4:5], off offset:1276
	global_load_dwordx3 v[20:22], v[4:5], off offset:252
	global_load_dwordx3 v[8:10], v[4:5], off offset:1532
	global_load_dwordx3 v[12:14], v[4:5], off offset:508
	global_load_dwordx3 v[0:2], v[4:5], off offset:1788
	global_load_dwordx3 v[4:6], v[4:5], off offset:764
	s_add_i32 s13, s3, 0x4400000
	s_add_u32 s20, s60, s13
	s_addc_u32 s21, s61, s5
	s_mul_hi_i32 s5, s4, 0x8800
	s_add_i32 s4, s3, 0x8800000
	s_add_u32 s4, s60, s4
	s_addc_u32 s5, s61, s5
	v_lshl_add_u64 v[32:33], s[20:21], 0, v[64:65]
	v_lshl_add_u64 v[84:85], v[32:33], 0, s[10:11]
	global_load_dword v66, v55, s[16:17]
	global_load_dword v70, v59, s[16:17]
	global_load_dword v68, v63, s[16:17]
	global_load_dword v72, v55, s[18:19]
	global_load_dwordx3 v[32:34], v[84:85], off offset:1020
	s_waitcnt vmcnt(12)
	v_cndmask_b32_e64 v37, v24, 0, s[6:7]
	s_waitcnt vmcnt(11)
	v_mov_b32_e32 v24, v29
	v_cndmask_b32_e64 v36, v28, 0, s[6:7]
	v_pk_fma_f32 v[24:25], v[80:81], v[24:25], v[82:83] op_sel_hi:[0,1,0]
	v_pk_fma_f32 v[24:25], v[62:63], v[36:37], v[24:25] op_sel_hi:[0,1,1]
	v_mov_b32_e32 v28, v30
	v_mov_b32_e32 v29, v26
	v_pk_fma_f32 v[74:75], v[60:61], v[28:29], v[24:25] op_sel_hi:[0,1,1]
	s_waitcnt vmcnt(10)
	v_mov_b32_e32 v25, v16
	s_waitcnt vmcnt(9)
	v_mov_b32_e32 v16, v21
	v_mov_b32_e32 v24, v20
	v_pk_fma_f32 v[16:17], v[80:81], v[16:17], v[82:83] op_sel_hi:[0,1,0]
	v_pk_fma_f32 v[16:17], v[62:63], v[24:25], v[16:17] op_sel_hi:[0,1,1]
	v_mov_b32_e32 v20, v22
	v_mov_b32_e32 v21, v18
	v_pk_fma_f32 v[76:77], v[60:61], v[20:21], v[16:17] op_sel_hi:[0,1,1]
	s_waitcnt vmcnt(8)
	v_mov_b32_e32 v17, v8
	s_waitcnt vmcnt(7)
	v_mov_b32_e32 v8, v13
	v_mov_b32_e32 v16, v12
	v_pk_fma_f32 v[8:9], v[80:81], v[8:9], v[82:83] op_sel_hi:[0,1,0]
	v_pk_fma_f32 v[8:9], v[62:63], v[16:17], v[8:9] op_sel_hi:[0,1,1]
	v_mov_b32_e32 v12, v14
	v_mov_b32_e32 v13, v10
	v_pk_fma_f32 v[78:79], v[60:61], v[12:13], v[8:9] op_sel_hi:[0,1,1]
	s_waitcnt vmcnt(6)
	v_mov_b32_e32 v9, v0
	s_waitcnt vmcnt(5)
	v_mov_b32_e32 v0, v5
	v_mov_b32_e32 v8, v4
	v_pk_fma_f32 v[0:1], v[80:81], v[0:1], v[82:83] op_sel_hi:[0,1,0]
	v_pk_fma_f32 v[0:1], v[62:63], v[8:9], v[0:1] op_sel_hi:[0,1,1]
	v_cndmask_b32_e64 v5, v2, 0, s[8:9]
	v_cndmask_b32_e64 v4, v6, 0, s[8:9]
	v_pk_fma_f32 v[80:81], v[60:61], v[4:5], v[0:1] op_sel_hi:[0,1,1]
	v_lshl_add_u64 v[0:1], s[4:5], 0, v[64:65]
	v_lshl_add_u64 v[28:29], v[0:1], 0, s[10:11]
	global_load_dwordx3 v[36:38], v[84:85], off offset:-4
	global_load_dwordx3 v[40:42], v[84:85], off offset:1276
	global_load_dwordx3 v[44:46], v[84:85], off offset:252
	global_load_dwordx3 v[52:54], v[84:85], off offset:1532
	global_load_dwordx3 v[48:50], v[84:85], off offset:508
	global_load_dwordx3 v[56:58], v[84:85], off offset:1788
	global_load_dwordx3 v[60:62], v[84:85], off offset:764
	global_load_dword v94, v67, s[16:17]
	global_load_dword v96, v69, s[16:17]
	global_load_dword v95, v71, s[16:17]
	global_load_dword v83, v67, s[18:19]
	global_load_dwordx3 v[0:2], v[28:29], off offset:1020
	global_load_dwordx3 v[4:6], v[28:29], off offset:-4
	global_load_dwordx3 v[8:10], v[28:29], off offset:1276
	global_load_dwordx3 v[12:14], v[28:29], off offset:252
	global_load_dwordx3 v[16:18], v[28:29], off offset:1532
	global_load_dwordx3 v[20:22], v[28:29], off offset:508
	global_load_dwordx3 v[24:26], v[28:29], off offset:1788
	global_load_dwordx3 v[28:30], v[28:29], off offset:764
	v_readlane_b32 s16, v239, 35
	v_readlane_b32 s18, v239, 37
	v_readlane_b32 s19, v239, 38
	s_add_u32 s4, s18, s14
	s_addc_u32 s5, s19, s15
	global_load_dword v82, v65, s[4:5]
	global_load_dword v97, v55, s[4:5]
	ds_write2st64_b64 v73, v[74:75], v[76:77] offset0:8 offset1:9
	ds_write2st64_b64 v73, v[78:79], v[80:81] offset0:10 offset1:11
	s_waitcnt lgkmcnt(0)
	s_movk_i32 s4, 0x3f4
	s_mov_b32 s5, s1
	v_readlane_b32 s17, v239, 36
	v_readlane_b32 s20, v239, 39
	v_readlane_b32 s21, v239, 40
	v_readlane_b32 s22, v239, 41
	v_readlane_b32 s23, v239, 42
	v_readlane_b32 s24, v239, 43
	v_readlane_b32 s25, v239, 44
	v_readlane_b32 s26, v239, 45
	v_readlane_b32 s27, v239, 46
	v_readlane_b32 s28, v239, 47
	v_readlane_b32 s29, v239, 48
	v_readlane_b32 s30, v239, 49
	v_readlane_b32 s31, v239, 50
.LBB0_1698:
	v_mov_b32_e32 v35, s5
	ds_read_b128 v[172:175], v35
	ds_read_b128 v[102:105], v35 offset:16
	v_add_u32_e32 v35, s4, v3
	ds_read2_b32 v[176:177], v35 offset0:2 offset1:3
	ds_read2_b32 v[178:179], v35 offset0:66 offset1:67
	ds_read2_b32 v[180:181], v35 offset1:1
	ds_read2_b32 v[108:109], v35 offset0:130 offset1:131
	ds_read2_b32 v[110:111], v35 offset0:194 offset1:195
	s_add_i32 s5, s5, 32
	s_waitcnt lgkmcnt(4)
	v_pk_fma_f32 v[92:93], v[172:173], v[176:177], v[92:93] op_sel:[0,1,0]
	s_waitcnt lgkmcnt(3)
	v_pk_fma_f32 v[90:91], v[172:173], v[178:179], v[90:91] op_sel:[0,1,0]
	s_waitcnt lgkmcnt(1)
	v_pk_fma_f32 v[88:89], v[172:173], v[108:109], v[88:89] op_sel:[0,1,0]
	s_waitcnt lgkmcnt(0)
	v_pk_fma_f32 v[86:87], v[172:173], v[110:111], v[86:87] op_sel:[0,1,0]
	v_pk_fma_f32 v[84:85], v[174:175], v[176:177], v[92:93] op_sel_hi:[1,0,1]
	v_pk_fma_f32 v[90:91], v[174:175], v[178:179], v[90:91] op_sel_hi:[1,0,1]
	v_pk_fma_f32 v[88:89], v[174:175], v[108:109], v[88:89] op_sel_hi:[1,0,1]
	v_pk_fma_f32 v[86:87], v[174:175], v[110:111], v[86:87] op_sel_hi:[1,0,1]
	ds_read2_b32 v[98:99], v35 offset0:64 offset1:65
	ds_read2_b32 v[100:101], v35 offset0:128 offset1:129
	ds_read2_b32 v[106:107], v35 offset0:192 offset1:193
	s_add_i32 s4, s4, -16
	v_pk_fma_f32 v[84:85], v[102:103], v[180:181], v[84:85] op_sel:[0,1,0]
	s_waitcnt lgkmcnt(2)
	v_pk_fma_f32 v[90:91], v[102:103], v[98:99], v[90:91] op_sel:[0,1,0]
	s_waitcnt lgkmcnt(1)
	v_pk_fma_f32 v[88:89], v[102:103], v[100:101], v[88:89] op_sel:[0,1,0]
	s_waitcnt lgkmcnt(0)
	v_pk_fma_f32 v[86:87], v[102:103], v[106:107], v[86:87] op_sel:[0,1,0]
	v_pk_fma_f32 v[92:93], v[104:105], v[180:181], v[84:85] op_sel_hi:[1,0,1]
	v_pk_fma_f32 v[90:91], v[104:105], v[98:99], v[90:91] op_sel_hi:[1,0,1]
	v_pk_fma_f32 v[88:89], v[104:105], v[100:101], v[88:89] op_sel_hi:[1,0,1]
	v_pk_fma_f32 v[86:87], v[104:105], v[106:107], v[86:87] op_sel_hi:[1,0,1]
	s_cmp_eq_u32 s4, -12
	s_cbranch_scc0 .LBB0_1698
	s_waitcnt vmcnt(20)
	v_mov_b32_e32 v98, v37
	v_mov_b32_e32 v99, v33
	v_cndmask_b32_e64 v33, v32, 0, s[6:7]
	v_cndmask_b32_e64 v32, v36, 0, s[6:7]
	v_mov_b32_e32 v36, v38
	v_pk_fma_f32 v[38:39], v[70:71], v[98:99], v[72:73] op_sel_hi:[0,1,0]
	v_mov_b32_e32 v37, v34
	v_pk_fma_f32 v[32:33], v[66:67], v[32:33], v[38:39] op_sel_hi:[0,1,1]
	s_waitcnt vmcnt(18)
	v_mov_b32_e32 v100, v45
	v_mov_b32_e32 v101, v41
	v_pk_fma_f32 v[32:33], v[68:69], v[36:37], v[32:33] op_sel_hi:[0,1,1]
	s_waitcnt vmcnt(1)
	v_pk_fma_f32 v[36:37], v[74:75], v[82:83], v[92:93] op_sel_hi:[1,0,1]
	v_mov_b32_e32 v45, v40
	v_pk_mul_f32 v[38:39], v[32:33], v[36:37]
	v_pk_fma_f32 v[32:33], v[70:71], v[100:101], v[72:73] op_sel_hi:[0,1,0]
	v_mov_b32_e32 v34, v46
	v_mov_b32_e32 v35, v42
	v_pk_fma_f32 v[32:33], v[66:67], v[44:45], v[32:33] op_sel_hi:[0,1,1]
	v_mov_b32_e32 v102, v49
	v_mov_b32_e32 v103, v53
	v_pk_fma_f32 v[32:33], v[68:69], v[34:35], v[32:33] op_sel_hi:[0,1,1]
	v_pk_fma_f32 v[34:35], v[76:77], v[82:83], v[90:91] op_sel_hi:[1,0,1]
	v_mov_b32_e32 v49, v52
	v_pk_mul_f32 v[36:37], v[32:33], v[34:35]
	v_pk_fma_f32 v[32:33], v[70:71], v[102:103], v[72:73] op_sel_hi:[0,1,0]
	v_mov_b32_e32 v42, v50
	v_mov_b32_e32 v43, v54
	v_pk_fma_f32 v[32:33], v[66:67], v[48:49], v[32:33] op_sel_hi:[0,1,1]
	v_mov_b32_e32 v104, v61
	v_mov_b32_e32 v105, v57
	v_pk_fma_f32 v[32:33], v[68:69], v[42:43], v[32:33] op_sel_hi:[0,1,1]
	v_pk_fma_f32 v[34:35], v[78:79], v[82:83], v[88:89] op_sel_hi:[1,0,1]
	v_mov_b32_e32 v61, v56
	v_pk_mul_f32 v[34:35], v[32:33], v[34:35]
	v_pk_fma_f32 v[32:33], v[70:71], v[104:105], v[72:73] op_sel_hi:[0,1,0]
	v_cndmask_b32_e64 v107, v58, 0, s[8:9]
	v_cndmask_b32_e64 v106, v62, 0, s[8:9]
	v_pk_fma_f32 v[32:33], v[66:67], v[60:61], v[32:33] op_sel_hi:[0,1,1]
	v_pk_fma_f32 v[32:33], v[68:69], v[106:107], v[32:33] op_sel_hi:[0,1,1]
	v_pk_fma_f32 v[40:41], v[80:81], v[82:83], v[86:87] op_sel_hi:[1,0,1]
	s_waitcnt lgkmcnt(0)
	v_mov_b32_e32 v84, 0
	v_pk_mul_f32 v[32:33], v[32:33], v[40:41]
	ds_write2st64_b64 v73, v[38:39], v[36:37] offset0:8 offset1:9
	ds_write2st64_b64 v73, v[34:35], v[32:33] offset0:10 offset1:11
	s_waitcnt lgkmcnt(0)
	s_movk_i32 s4, 0xbf4
	s_mov_b32 s5, s1
	v_mov_b32_e32 v85, v84
	v_mov_b32_e32 v44, v84
	v_mov_b32_e32 v45, v84
	v_mov_b32_e32 v42, v84
	v_mov_b32_e32 v43, v84
	v_mov_b32_e32 v40, v84
	v_mov_b32_e32 v41, v84
.LBB0_1700:
	v_mov_b32_e32 v46, s5
	ds_read_b128 v[74:77], v46
	ds_read_b128 v[78:81], v46 offset:16
	v_add_u32_e32 v46, s4, v3
	ds_read2_b32 v[172:173], v46 offset0:130 offset1:131
	ds_read2_b32 v[174:175], v46 offset0:194 offset1:195
	ds_read2_b32 v[176:177], v46 offset0:66 offset1:67
	ds_read2_b32 v[178:179], v46 offset0:2 offset1:3
	s_add_i32 s5, s5, 32
	s_waitcnt lgkmcnt(3)
	v_pk_fma_f32 v[40:41], v[74:75], v[172:173], v[40:41] op_sel:[0,1,0]
	s_add_i32 s4, s4, -16
	v_pk_fma_f32 v[40:41], v[76:77], v[172:173], v[40:41] op_sel_hi:[1,0,1]
	ds_read2_b32 v[56:57], v46 offset0:64 offset1:65
	s_waitcnt lgkmcnt(2)
	v_pk_fma_f32 v[42:43], v[74:75], v[176:177], v[42:43] op_sel:[0,1,0]
	s_cmpk_lg_i32 s4, 0x7f4
	v_pk_fma_f32 v[42:43], v[76:77], v[176:177], v[42:43] op_sel_hi:[1,0,1]
	ds_read2_b32 v[52:53], v46 offset1:1
	s_waitcnt lgkmcnt(2)
	v_pk_fma_f32 v[44:45], v[74:75], v[178:179], v[44:45] op_sel:[0,1,0]
	v_pk_fma_f32 v[74:75], v[74:75], v[174:175], v[84:85] op_sel:[0,1,0]
	v_pk_fma_f32 v[44:45], v[76:77], v[178:179], v[44:45] op_sel_hi:[1,0,1]
	v_pk_fma_f32 v[48:49], v[76:77], v[174:175], v[74:75] op_sel_hi:[1,0,1]
	ds_read2_b32 v[60:61], v46 offset0:128 offset1:129
	ds_read2_b32 v[74:75], v46 offset0:192 offset1:193
	s_waitcnt lgkmcnt(2)
	v_pk_fma_f32 v[44:45], v[78:79], v[52:53], v[44:45] op_sel:[0,1,0]
	v_pk_fma_f32 v[42:43], v[78:79], v[56:57], v[42:43] op_sel:[0,1,0]
	v_pk_fma_f32 v[44:45], v[80:81], v[52:53], v[44:45] op_sel_hi:[1,0,1]
	s_waitcnt lgkmcnt(1)
	v_pk_fma_f32 v[40:41], v[78:79], v[60:61], v[40:41] op_sel:[0,1,0]
	s_waitcnt lgkmcnt(0)
	v_pk_fma_f32 v[48:49], v[78:79], v[74:75], v[48:49] op_sel:[0,1,0]
	v_pk_fma_f32 v[42:43], v[80:81], v[56:57], v[42:43] op_sel_hi:[1,0,1]
	v_pk_fma_f32 v[40:41], v[80:81], v[60:61], v[40:41] op_sel_hi:[1,0,1]
	v_pk_fma_f32 v[84:85], v[80:81], v[74:75], v[48:49] op_sel_hi:[1,0,1]
	s_cbranch_scc1 .LBB0_1700
	s_add_u32 s4, s66, s3
	s_addc_u32 s5, s67, s2
	s_add_u32 s2, s4, 0x8400
	v_cndmask_b32_e64 v4, v4, 0, s[6:7]
	v_fma_f32 v5, v96, v5, v83
	s_addc_u32 s3, s5, 0
	v_fma_f32 v29, v96, v29, v83
	v_fma_f32 v25, v96, v25, v83
	v_fma_f32 v21, v96, v21, v83
	v_fma_f32 v17, v96, v17, v83
	v_fma_f32 v13, v96, v13, v83
	v_fma_f32 v9, v96, v9, v83
	v_fmac_f32_e32 v5, v94, v4
	v_cndmask_b32_e64 v0, v0, 0, s[6:7]
	v_fmac_f32_e32 v83, v96, v1
	s_add_u32 s4, s4, 0x8000
	v_fmac_f32_e32 v5, v95, v6
	v_fmac_f32_e32 v83, v94, v0
	s_waitcnt vmcnt(0)
	v_fma_f32 v0, v97, v38, v44
	s_addc_u32 s5, s5, 0
	v_fmac_f32_e32 v83, v95, v2
	v_mul_f32_e32 v0, v5, v0
	v_fmac_f32_e32 v45, v97, v39
	v_fmac_f32_e32 v13, v94, v12
	global_store_dword v64, v0, s[4:5]
	v_mul_f32_e32 v0, v83, v45
	v_fmac_f32_e32 v13, v95, v14
	v_fmac_f32_e32 v9, v94, v8
	global_store_dword v64, v0, s[2:3]
	v_fma_f32 v0, v97, v36, v42
	v_fmac_f32_e32 v9, v95, v10
	v_mul_f32_e32 v0, v13, v0
	v_fmac_f32_e32 v43, v97, v37
	v_fmac_f32_e32 v21, v94, v20
	global_store_dword v23, v0, s[4:5]
	v_mul_f32_e32 v0, v9, v43
	v_fmac_f32_e32 v21, v95, v22
	v_fmac_f32_e32 v17, v94, v16
	global_store_dword v23, v0, s[2:3]
	v_fma_f32 v0, v97, v34, v40
	v_fmac_f32_e32 v17, v95, v18
	v_mul_f32_e32 v0, v21, v0
	v_fmac_f32_e32 v41, v97, v35
	v_fmac_f32_e32 v29, v94, v28
	v_cndmask_b32_e64 v28, v30, 0, s[8:9]
	global_store_dword v27, v0, s[4:5]
	v_mul_f32_e32 v0, v17, v41
	v_fmac_f32_e32 v29, v95, v28
	global_store_dword v27, v0, s[2:3]
	v_fma_f32 v0, v97, v32, v84
	v_mul_f32_e32 v0, v29, v0
	v_fmac_f32_e32 v25, v94, v24
	v_cndmask_b32_e64 v24, v26, 0, s[8:9]
	global_store_dword v31, v0, s[4:5]
	v_readlane_b32 s4, v238, 3
	v_fmac_f32_e32 v25, v95, v24
	v_fmac_f32_e32 v85, v97, v33
	s_add_i32 s12, s12, s4
	v_mul_f32_e32 v0, v25, v85
	s_cmpk_lt_i32 s12, 0x800
	v_readlane_b32 s5, v238, 4
	global_store_dword v31, v0, s[2:3]
	s_cbranch_scc1 .LBB0_1697

.LBB0_2081:
	ds_read_b128 v[128:131], v151
	ds_read_b128 v[144:147], v151 offset:1024
	ds_read_b128 v[154:157], v151 offset:2048
	ds_read_b128 v[158:161], v151 offset:3072
	s_add_u32 s18, s16, 0x100
	s_addc_u32 s19, s17, 0
	s_cmpk_eq_i32 s42, 0x54
	s_cselect_b32 s23, s11, s19
	s_cselect_b32 s22, s10, s18
	s_cselect_b32 s21, s13, s41
	s_cselect_b32 s20, s12, s40
	v_lshl_add_u64 v[194:195], s[16:17], 0, v[136:137]
	s_add_i32 m0, s4, 0xc000
	ds_read_b128 v[162:165], v152
	ds_read_b128 v[166:169], v152 offset:1024
	ds_read_b128 v[170:173], v152 offset:2048
	ds_read_b128 v[174:177], v152 offset:3072
	ds_read_b128 v[178:181], v152 offset:4096
	ds_read_b128 v[182:185], v152 offset:5120
	ds_read_b128 v[186:189], v152 offset:6144
	ds_read_b128 v[190:193], v152 offset:7168
	global_load_lds_dwordx4 v[194:195], off
	v_lshl_add_u64 v[194:195], s[16:17], 0, v[138:139]
	s_add_i32 m0, s4, 0xe000
	s_nop 0
	global_load_lds_dwordx4 v[194:195], off
	s_waitcnt lgkmcnt(8)
	s_barrier
	s_waitcnt lgkmcnt(0)
	s_setprio 1
	s_waitcnt lgkmcnt(0)
	v_mfma_f32_16x16x32_bf16 v[124:127], v[128:131], v[162:165], v[124:127]
	v_mfma_f32_16x16x32_bf16 v[92:95], v[154:157], v[162:165], v[92:95]
	v_mfma_f32_16x16x32_bf16 v[120:123], v[128:131], v[170:173], v[120:123]
	v_mfma_f32_16x16x32_bf16 v[88:91], v[154:157], v[170:173], v[88:91]
	v_mfma_f32_16x16x32_bf16 v[116:119], v[128:131], v[178:181], v[116:119]
	v_mfma_f32_16x16x32_bf16 v[84:87], v[154:157], v[178:181], v[84:87]
	v_mfma_f32_16x16x32_bf16 v[112:115], v[128:131], v[186:189], v[112:115]
	v_mfma_f32_16x16x32_bf16 v[80:83], v[154:157], v[186:189], v[80:83]
	v_mfma_f32_16x16x32_bf16 v[124:127], v[144:147], v[166:169], v[124:127]
	v_mfma_f32_16x16x32_bf16 v[92:95], v[158:161], v[166:169], v[92:95]
	v_mfma_f32_16x16x32_bf16 v[120:123], v[144:147], v[174:177], v[120:123]
	v_mfma_f32_16x16x32_bf16 v[88:91], v[158:161], v[174:177], v[88:91]
	v_mfma_f32_16x16x32_bf16 v[116:119], v[144:147], v[182:185], v[116:119]
	v_mfma_f32_16x16x32_bf16 v[84:87], v[158:161], v[182:185], v[84:87]
	v_mfma_f32_16x16x32_bf16 v[112:115], v[144:147], v[190:193], v[112:115]
	v_mfma_f32_16x16x32_bf16 v[80:83], v[158:161], v[190:193], v[80:83]
	s_setprio 0
	s_barrier
	s_add_i32 s16, s34, s3
	v_lshl_add_u64 v[210:211], s[20:21], 0, v[132:133]
	s_mov_b32 m0, s16
	ds_read_b128 v[194:197], v153
	ds_read_b128 v[198:201], v153 offset:1024
	ds_read_b128 v[202:205], v153 offset:2048
	ds_read_b128 v[206:209], v153 offset:3072
	global_load_lds_dwordx4 v[210:211], off
	v_lshl_add_u64 v[212:213], s[20:21], 0, v[134:135]
	s_add_i32 m0, s16, 0x2000
	s_nop 0
	global_load_lds_dwordx4 v[212:213], off
	s_barrier
	s_waitcnt lgkmcnt(0)
	s_setprio 1
	s_waitcnt lgkmcnt(0)
	v_mfma_f32_16x16x32_bf16 v[76:79], v[194:197], v[162:165], v[76:79]
	v_mfma_f32_16x16x32_bf16 v[48:51], v[202:205], v[162:165], v[48:51]
	v_mfma_f32_16x16x32_bf16 v[68:71], v[194:197], v[170:173], v[68:71]
	v_mfma_f32_16x16x32_bf16 v[40:43], v[202:205], v[170:173], v[40:43]
	v_mfma_f32_16x16x32_bf16 v[60:63], v[194:197], v[178:181], v[60:63]
	v_mfma_f32_16x16x32_bf16 v[36:39], v[202:205], v[178:181], v[36:39]
	v_mfma_f32_16x16x32_bf16 v[52:55], v[194:197], v[186:189], v[52:55]
	v_mfma_f32_16x16x32_bf16 v[28:31], v[202:205], v[186:189], v[28:31]
	v_mfma_f32_16x16x32_bf16 v[76:79], v[198:201], v[166:169], v[76:79]
	v_mfma_f32_16x16x32_bf16 v[48:51], v[206:209], v[166:169], v[48:51]
	v_mfma_f32_16x16x32_bf16 v[68:71], v[198:201], v[174:177], v[68:71]
	v_mfma_f32_16x16x32_bf16 v[40:43], v[206:209], v[174:177], v[40:43]
	v_mfma_f32_16x16x32_bf16 v[60:63], v[198:201], v[182:185], v[60:63]
	v_mfma_f32_16x16x32_bf16 v[36:39], v[206:209], v[182:185], v[36:39]
	v_mfma_f32_16x16x32_bf16 v[52:55], v[198:201], v[190:193], v[52:55]
	v_mfma_f32_16x16x32_bf16 v[28:31], v[206:209], v[190:193], v[28:31]
	s_setprio 0
	s_mov_b32 m0, s4
	v_lshl_add_u64 v[214:215], s[22:23], 0, v[132:133]
	s_barrier
	ds_read_b128 v[162:165], v152 offset:16384
	ds_read_b128 v[166:169], v152 offset:17408
	ds_read_b128 v[170:173], v152 offset:18432
	ds_read_b128 v[174:177], v152 offset:19456
	ds_read_b128 v[178:181], v152 offset:20480
	ds_read_b128 v[182:185], v152 offset:21504
	ds_read_b128 v[186:189], v152 offset:22528
	ds_read_b128 v[190:193], v152 offset:23552
	global_load_lds_dwordx4 v[214:215], off
	v_lshl_add_u64 v[216:217], s[22:23], 0, v[134:135]
	s_mov_b32 m0, s5
	s_nop 0
	global_load_lds_dwordx4 v[216:217], off
	s_barrier
	s_waitcnt lgkmcnt(0)
	s_setprio 1
	s_waitcnt lgkmcnt(0)
	v_mfma_f32_16x16x32_bf16 v[108:111], v[128:131], v[162:165], v[108:111]
	v_mfma_f32_16x16x32_bf16 v[72:75], v[154:157], v[162:165], v[72:75]
	v_mfma_f32_16x16x32_bf16 v[104:107], v[128:131], v[170:173], v[104:107]
	v_mfma_f32_16x16x32_bf16 v[64:67], v[154:157], v[170:173], v[64:67]
	v_mfma_f32_16x16x32_bf16 v[100:103], v[128:131], v[178:181], v[100:103]
	v_mfma_f32_16x16x32_bf16 v[56:59], v[154:157], v[178:181], v[56:59]
	v_mfma_f32_16x16x32_bf16 v[96:99], v[128:131], v[186:189], v[96:99]
	v_mfma_f32_16x16x32_bf16 v[44:47], v[154:157], v[186:189], v[44:47]
	v_mfma_f32_16x16x32_bf16 v[108:111], v[144:147], v[166:169], v[108:111]
	v_mfma_f32_16x16x32_bf16 v[72:75], v[158:161], v[166:169], v[72:75]
	v_mfma_f32_16x16x32_bf16 v[104:107], v[144:147], v[174:177], v[104:107]
	v_mfma_f32_16x16x32_bf16 v[64:67], v[158:161], v[174:177], v[64:67]
	v_mfma_f32_16x16x32_bf16 v[100:103], v[144:147], v[182:185], v[100:103]
	v_mfma_f32_16x16x32_bf16 v[56:59], v[158:161], v[182:185], v[56:59]
	v_mfma_f32_16x16x32_bf16 v[96:99], v[144:147], v[190:193], v[96:99]
	v_mfma_f32_16x16x32_bf16 v[44:47], v[158:161], v[190:193], v[44:47]
	s_setprio 0
	s_barrier
	s_add_u32 s16, s20, 0x160000
	s_addc_u32 s17, s21, 0
	s_add_i32 s43, s35, s3
	v_lshl_add_u64 v[128:129], s[16:17], 0, v[132:133]
	s_mov_b32 m0, s43
	s_nop 0
	global_load_lds_dwordx4 v[128:129], off
	v_lshl_add_u64 v[128:129], s[16:17], 0, v[134:135]
	s_add_i32 m0, s43, 0x2000
	s_nop 0
	global_load_lds_dwordx4 v[128:129], off
	s_waitcnt vmcnt(6)
	s_barrier
	s_setprio 1
	v_mfma_f32_16x16x32_bf16 v[32:35], v[194:197], v[162:165], v[32:35]
	v_mfma_f32_16x16x32_bf16 v[12:15], v[202:205], v[162:165], v[12:15]
	v_mfma_f32_16x16x32_bf16 v[24:27], v[194:197], v[170:173], v[24:27]
	v_mfma_f32_16x16x32_bf16 v[8:11], v[202:205], v[170:173], v[8:11]
	v_mfma_f32_16x16x32_bf16 v[20:23], v[194:197], v[178:181], v[20:23]
	v_mfma_f32_16x16x32_bf16 v[4:7], v[202:205], v[178:181], v[4:7]
	v_mfma_f32_16x16x32_bf16 v[16:19], v[194:197], v[186:189], v[16:19]
	v_mfma_f32_16x16x32_bf16 v[0:3], v[202:205], v[186:189], v[0:3]
	v_mfma_f32_16x16x32_bf16 v[32:35], v[198:201], v[166:169], v[32:35]
	v_mfma_f32_16x16x32_bf16 v[12:15], v[206:209], v[166:169], v[12:15]
	v_mfma_f32_16x16x32_bf16 v[24:27], v[198:201], v[174:177], v[24:27]
	v_mfma_f32_16x16x32_bf16 v[8:11], v[206:209], v[174:177], v[8:11]
	v_mfma_f32_16x16x32_bf16 v[20:23], v[198:201], v[182:185], v[20:23]
	v_mfma_f32_16x16x32_bf16 v[4:7], v[206:209], v[182:185], v[4:7]
	v_mfma_f32_16x16x32_bf16 v[16:19], v[198:201], v[190:193], v[16:19]
	v_mfma_f32_16x16x32_bf16 v[0:3], v[206:209], v[190:193], v[0:3]
	s_setprio 0
	s_add_i32 s43, 0, 0x18000
	v_add_u32_e32 v158, s43, v149
	s_barrier
	ds_read_b128 v[128:131], v158
	ds_read_b128 v[144:147], v158 offset:1024
	ds_read_b128 v[154:157], v158 offset:2048
	ds_read_b128 v[158:161], v158 offset:3072
	s_add_u32 s16, s22, 0x160000
	s_addc_u32 s17, s23, 0
	s_mov_b32 m0, s24
	v_lshl_add_u64 v[194:195], s[16:17], 0, v[132:133]
	ds_read_b128 v[162:165], v152 offset:32768
	ds_read_b128 v[166:169], v152 offset:33792
	ds_read_b128 v[170:173], v152 offset:34816
	ds_read_b128 v[174:177], v152 offset:35840
	ds_read_b128 v[178:181], v152 offset:36864
	ds_read_b128 v[182:185], v152 offset:37888
	ds_read_b128 v[186:189], v152 offset:38912
	ds_read_b128 v[190:193], v152 offset:39936
	global_load_lds_dwordx4 v[194:195], off
	v_lshl_add_u64 v[194:195], s[16:17], 0, v[134:135]
	s_mov_b32 m0, s25
	s_nop 0
	global_load_lds_dwordx4 v[194:195], off
	s_waitcnt lgkmcnt(8)
	s_barrier
	s_waitcnt lgkmcnt(0)
	s_setprio 1
	s_waitcnt lgkmcnt(0)
	v_mfma_f32_16x16x32_bf16 v[124:127], v[128:131], v[162:165], v[124:127]
	v_mfma_f32_16x16x32_bf16 v[92:95], v[154:157], v[162:165], v[92:95]
	v_mfma_f32_16x16x32_bf16 v[120:123], v[128:131], v[170:173], v[120:123]
	v_mfma_f32_16x16x32_bf16 v[88:91], v[154:157], v[170:173], v[88:91]
	v_mfma_f32_16x16x32_bf16 v[116:119], v[128:131], v[178:181], v[116:119]
	v_mfma_f32_16x16x32_bf16 v[84:87], v[154:157], v[178:181], v[84:87]
	v_mfma_f32_16x16x32_bf16 v[112:115], v[128:131], v[186:189], v[112:115]
	v_mfma_f32_16x16x32_bf16 v[80:83], v[154:157], v[186:189], v[80:83]
	v_mfma_f32_16x16x32_bf16 v[124:127], v[144:147], v[166:169], v[124:127]
	v_mfma_f32_16x16x32_bf16 v[92:95], v[158:161], v[166:169], v[92:95]
	v_mfma_f32_16x16x32_bf16 v[120:123], v[144:147], v[174:177], v[120:123]
	v_mfma_f32_16x16x32_bf16 v[88:91], v[158:161], v[174:177], v[88:91]
	v_mfma_f32_16x16x32_bf16 v[116:119], v[144:147], v[182:185], v[116:119]
	v_mfma_f32_16x16x32_bf16 v[84:87], v[158:161], v[182:185], v[84:87]
	v_mfma_f32_16x16x32_bf16 v[112:115], v[144:147], v[190:193], v[112:115]
	v_mfma_f32_16x16x32_bf16 v[80:83], v[158:161], v[190:193], v[80:83]
	s_setprio 0
	s_barrier
	s_add_i32 s22, 0, 0x1c000
	s_add_i32 s16, s43, s3
	v_add_u32_e32 v206, s22, v149
	v_lshl_add_u64 v[210:211], v[210:211], 0, s[14:15]
	s_mov_b32 m0, s16
	ds_read_b128 v[194:197], v206
	ds_read_b128 v[198:201], v206 offset:1024
	ds_read_b128 v[202:205], v206 offset:2048
	ds_read_b128 v[206:209], v206 offset:3072
	global_load_lds_dwordx4 v[210:211], off
	v_lshl_add_u64 v[210:211], v[212:213], 0, s[14:15]
	s_add_i32 m0, s16, 0x2000
	s_nop 0
	global_load_lds_dwordx4 v[210:211], off
	s_barrier
	s_waitcnt lgkmcnt(0)
	s_setprio 1
	s_waitcnt lgkmcnt(0)
	v_mfma_f32_16x16x32_bf16 v[76:79], v[194:197], v[162:165], v[76:79]
	v_mfma_f32_16x16x32_bf16 v[48:51], v[202:205], v[162:165], v[48:51]
	v_mfma_f32_16x16x32_bf16 v[68:71], v[194:197], v[170:173], v[68:71]
	v_mfma_f32_16x16x32_bf16 v[40:43], v[202:205], v[170:173], v[40:43]
	v_mfma_f32_16x16x32_bf16 v[60:63], v[194:197], v[178:181], v[60:63]
	v_mfma_f32_16x16x32_bf16 v[36:39], v[202:205], v[178:181], v[36:39]
	v_mfma_f32_16x16x32_bf16 v[52:55], v[194:197], v[186:189], v[52:55]
	v_mfma_f32_16x16x32_bf16 v[28:31], v[202:205], v[186:189], v[28:31]
	v_mfma_f32_16x16x32_bf16 v[76:79], v[198:201], v[166:169], v[76:79]
	v_mfma_f32_16x16x32_bf16 v[48:51], v[206:209], v[166:169], v[48:51]
	v_mfma_f32_16x16x32_bf16 v[68:71], v[198:201], v[174:177], v[68:71]
	v_mfma_f32_16x16x32_bf16 v[40:43], v[206:209], v[174:177], v[40:43]
	v_mfma_f32_16x16x32_bf16 v[60:63], v[198:201], v[182:185], v[60:63]
	v_mfma_f32_16x16x32_bf16 v[36:39], v[206:209], v[182:185], v[36:39]
	v_mfma_f32_16x16x32_bf16 v[52:55], v[198:201], v[190:193], v[52:55]
	v_mfma_f32_16x16x32_bf16 v[28:31], v[206:209], v[190:193], v[28:31]
	s_setprio 0
	s_mov_b32 m0, s27
	v_lshl_add_u64 v[210:211], v[214:215], 0, s[14:15]
	s_barrier
	ds_read_b128 v[162:165], v152 offset:49152
	ds_read_b128 v[166:169], v152 offset:50176
	ds_read_b128 v[170:173], v152 offset:51200
	ds_read_b128 v[174:177], v152 offset:52224
	ds_read_b128 v[178:181], v152 offset:53248
	ds_read_b128 v[182:185], v152 offset:54272
	ds_read_b128 v[186:189], v152 offset:55296
	ds_read_b128 v[190:193], v152 offset:56320
	global_load_lds_dwordx4 v[210:211], off
	v_lshl_add_u64 v[210:211], v[216:217], 0, s[14:15]
	s_mov_b32 m0, s28
	s_nop 0
	global_load_lds_dwordx4 v[210:211], off
	s_barrier
	s_waitcnt lgkmcnt(0)
	s_setprio 1
	s_waitcnt lgkmcnt(0)
	v_mfma_f32_16x16x32_bf16 v[108:111], v[128:131], v[162:165], v[108:111]
	v_mfma_f32_16x16x32_bf16 v[72:75], v[154:157], v[162:165], v[72:75]
	v_mfma_f32_16x16x32_bf16 v[104:107], v[128:131], v[170:173], v[104:107]
	v_mfma_f32_16x16x32_bf16 v[64:67], v[154:157], v[170:173], v[64:67]
	v_mfma_f32_16x16x32_bf16 v[100:103], v[128:131], v[178:181], v[100:103]
	v_mfma_f32_16x16x32_bf16 v[56:59], v[154:157], v[178:181], v[56:59]
	v_mfma_f32_16x16x32_bf16 v[96:99], v[128:131], v[186:189], v[96:99]
	v_mfma_f32_16x16x32_bf16 v[44:47], v[154:157], v[186:189], v[44:47]
	v_mfma_f32_16x16x32_bf16 v[108:111], v[144:147], v[166:169], v[108:111]
	v_mfma_f32_16x16x32_bf16 v[72:75], v[158:161], v[166:169], v[72:75]
	v_mfma_f32_16x16x32_bf16 v[104:107], v[144:147], v[174:177], v[104:107]
	v_mfma_f32_16x16x32_bf16 v[64:67], v[158:161], v[174:177], v[64:67]
	v_mfma_f32_16x16x32_bf16 v[100:103], v[144:147], v[182:185], v[100:103]
	v_mfma_f32_16x16x32_bf16 v[56:59], v[158:161], v[182:185], v[56:59]
	v_mfma_f32_16x16x32_bf16 v[96:99], v[144:147], v[190:193], v[96:99]
	v_mfma_f32_16x16x32_bf16 v[44:47], v[158:161], v[190:193], v[44:47]
	s_setprio 0
	s_barrier
	s_add_u32 s16, s20, 0x160080
	s_addc_u32 s17, s21, 0
	s_add_i32 s20, s22, s3
	v_lshl_add_u64 v[128:129], s[16:17], 0, v[132:133]
	s_mov_b32 m0, s20
	s_nop 0
	global_load_lds_dwordx4 v[128:129], off
	v_lshl_add_u64 v[128:129], s[16:17], 0, v[134:135]
	s_add_i32 m0, s20, 0x2000
	s_nop 0
	global_load_lds_dwordx4 v[128:129], off
	s_waitcnt vmcnt(6)
	s_barrier
	s_setprio 1
	v_mfma_f32_16x16x32_bf16 v[32:35], v[194:197], v[162:165], v[32:35]
	v_mfma_f32_16x16x32_bf16 v[12:15], v[202:205], v[162:165], v[12:15]
	v_mfma_f32_16x16x32_bf16 v[24:27], v[194:197], v[170:173], v[24:27]
	v_mfma_f32_16x16x32_bf16 v[8:11], v[202:205], v[170:173], v[8:11]
	v_mfma_f32_16x16x32_bf16 v[20:23], v[194:197], v[178:181], v[20:23]
	v_mfma_f32_16x16x32_bf16 v[4:7], v[202:205], v[178:181], v[4:7]
	v_mfma_f32_16x16x32_bf16 v[16:19], v[194:197], v[186:189], v[16:19]
	v_mfma_f32_16x16x32_bf16 v[0:3], v[202:205], v[186:189], v[0:3]
	v_mfma_f32_16x16x32_bf16 v[32:35], v[198:201], v[166:169], v[32:35]
	v_mfma_f32_16x16x32_bf16 v[12:15], v[206:209], v[166:169], v[12:15]
	v_mfma_f32_16x16x32_bf16 v[24:27], v[198:201], v[174:177], v[24:27]
	v_mfma_f32_16x16x32_bf16 v[8:11], v[206:209], v[174:177], v[8:11]
	v_mfma_f32_16x16x32_bf16 v[20:23], v[198:201], v[182:185], v[20:23]
	v_mfma_f32_16x16x32_bf16 v[4:7], v[206:209], v[182:185], v[4:7]
	v_mfma_f32_16x16x32_bf16 v[16:19], v[198:201], v[190:193], v[16:19]
	v_mfma_f32_16x16x32_bf16 v[0:3], v[206:209], v[190:193], v[0:3]
	s_setprio 0
	s_add_i32 s42, s42, 2
	s_add_u32 s40, s40, 0x100
	s_addc_u32 s41, s41, 0
	s_cmpk_gt_u32 s42, 0x55
	s_mov_b64 s[16:17], s[18:19]
	s_barrier
	s_cbranch_scc0 .LBB0_2081
	s_cmp_lt_u32 s38, 32
	s_movk_i32 s16, 0x3000
	s_cselect_b32 s16, s16, 0x6000
	s_cmp_gt_i32 s38, 15
	v_lshl_add_u32 v158, s38, 8, v148
	s_cselect_b32 s16, s16, 0
	v_lshl_or_b32 v128, s39, 8, v150
	s_lshl_b32 s16, s16, 2
	v_ashrrev_i32_e32 v159, 31, v158
	s_add_u32 s16, s30, s16
	v_ashrrev_i32_e32 v129, 31, v128
	v_lshlrev_b64 v[146:147], 13, v[158:159]
	s_addc_u32 s17, s31, 0
	v_lshlrev_b64 v[160:161], 2, v[128:129]
	v_lshl_add_u64 v[146:147], s[56:57], 0, v[146:147]
	v_lshl_add_u64 v[144:145], s[16:17], 0, v[160:161]
	v_lshl_add_u64 v[146:147], v[146:147], 0, v[160:161]
	s_mov_b64 s[16:17], 0x100000
	s_mov_b32 s39, s36
	s_mov_b32 s38, s37
	s_mov_b64 s[18:19], s[12:13]
	v_or_b32_e32 v162, 16, v158
	v_ashrrev_i32_e32 v163, 31, v162
	v_lshlrev_b64 v[164:165], 13, v[162:163]
	v_lshl_add_u64 v[162:163], s[56:57], 0, v[164:165]
	v_lshl_add_u64 v[164:165], v[162:163], 0, v[160:161]
	v_or_b32_e32 v162, 32, v158
	v_ashrrev_i32_e32 v163, 31, v162
	v_lshlrev_b64 v[166:167], 13, v[162:163]
	v_lshl_add_u64 v[162:163], s[56:57], 0, v[166:167]
	v_lshl_add_u64 v[166:167], v[162:163], 0, v[160:161]
	v_or_b32_e32 v162, 48, v158
	v_ashrrev_i32_e32 v163, 31, v162
	v_lshlrev_b64 v[168:169], 13, v[162:163]
	v_lshl_add_u64 v[162:163], s[56:57], 0, v[168:169]
	v_lshl_add_u64 v[168:169], v[162:163], 0, v[160:161]
	v_lshl_add_u64 v[162:163], v[146:147], 0, s[16:17]
	s_mov_b32 s16, 0x100000
	v_add_co_u32_e32 v170, vcc, s16, v146
	s_mov_b64 s[16:17], 0x120000
	s_nop 0
	v_addc_co_u32_e32 v171, vcc, 0, v147, vcc
	v_lshl_add_u64 v[172:173], v[146:147], 0, s[16:17]
	s_mov_b32 s16, 0x120000
	v_add_co_u32_e32 v174, vcc, s16, v146
	s_mov_b64 s[16:17], 0x140000
	s_nop 0
	v_addc_co_u32_e32 v175, vcc, 0, v147, vcc
	v_lshl_add_u64 v[176:177], v[146:147], 0, s[16:17]
	s_mov_b32 s16, 0x140000
	v_add_co_u32_e32 v178, vcc, s16, v146
	s_mov_b64 s[16:17], 0x160000
	s_nop 0
	v_addc_co_u32_e32 v179, vcc, 0, v147, vcc
	v_lshl_add_u64 v[180:181], v[146:147], 0, s[16:17]
	s_mov_b32 s16, 0x160000
	v_add_co_u32_e32 v182, vcc, s16, v146
	s_mov_b64 s[16:17], s[10:11]
	s_nop 0
	v_addc_co_u32_e32 v183, vcc, 0, v147, vcc
	s_and_b64 vcc, exec, s[6:7]
	global_load_dwordx4 v[184:187], v[144:145], off
	global_load_dwordx4 v[188:191], v[146:147], off
	v_pk_add_f32 v[126:127], v[126:127], 0 op_sel_hi:[1,0]
	v_pk_add_f32 v[124:125], v[124:125], 0 op_sel_hi:[1,0]
	v_pk_add_f32 v[122:123], v[122:123], 0 op_sel_hi:[1,0]
	v_pk_add_f32 v[120:121], v[120:121], 0 op_sel_hi:[1,0]
	v_pk_add_f32 v[118:119], v[118:119], 0 op_sel_hi:[1,0]
	v_pk_add_f32 v[116:117], v[116:117], 0 op_sel_hi:[1,0]
	v_pk_add_f32 v[114:115], v[114:115], 0 op_sel_hi:[1,0]
	v_pk_add_f32 v[112:113], v[112:113], 0 op_sel_hi:[1,0]
	v_pk_add_f32 v[110:111], v[110:111], 0 op_sel_hi:[1,0]
	v_pk_add_f32 v[108:109], v[108:109], 0 op_sel_hi:[1,0]
	v_pk_add_f32 v[106:107], v[106:107], 0 op_sel_hi:[1,0]
	v_pk_add_f32 v[104:105], v[104:105], 0 op_sel_hi:[1,0]
	v_pk_add_f32 v[102:103], v[102:103], 0 op_sel_hi:[1,0]
	v_pk_add_f32 v[100:101], v[100:101], 0 op_sel_hi:[1,0]
	v_pk_add_f32 v[98:99], v[98:99], 0 op_sel_hi:[1,0]
	v_pk_add_f32 v[96:97], v[96:97], 0 op_sel_hi:[1,0]
	v_pk_add_f32 v[94:95], v[94:95], 0 op_sel_hi:[1,0]
	v_pk_add_f32 v[92:93], v[92:93], 0 op_sel_hi:[1,0]
	v_pk_add_f32 v[90:91], v[90:91], 0 op_sel_hi:[1,0]
	v_pk_add_f32 v[88:89], v[88:89], 0 op_sel_hi:[1,0]
	v_pk_add_f32 v[86:87], v[86:87], 0 op_sel_hi:[1,0]
	v_pk_add_f32 v[84:85], v[84:85], 0 op_sel_hi:[1,0]
	v_pk_add_f32 v[82:83], v[82:83], 0 op_sel_hi:[1,0]
	v_pk_add_f32 v[80:81], v[80:81], 0 op_sel_hi:[1,0]
	v_pk_add_f32 v[74:75], v[74:75], 0 op_sel_hi:[1,0]
	v_pk_add_f32 v[72:73], v[72:73], 0 op_sel_hi:[1,0]
	v_pk_add_f32 v[66:67], v[66:67], 0 op_sel_hi:[1,0]
	v_pk_add_f32 v[64:65], v[64:65], 0 op_sel_hi:[1,0]
	v_pk_add_f32 v[58:59], v[58:59], 0 op_sel_hi:[1,0]
	v_pk_add_f32 v[56:57], v[56:57], 0 op_sel_hi:[1,0]
	v_pk_add_f32 v[46:47], v[46:47], 0 op_sel_hi:[1,0]
	v_pk_add_f32 v[44:45], v[44:45], 0 op_sel_hi:[1,0]
	v_pk_add_f32 v[62:63], v[62:63], 0 op_sel_hi:[1,0]
	v_pk_add_f32 v[60:61], v[60:61], 0 op_sel_hi:[1,0]
	v_pk_add_f32 v[54:55], v[54:55], 0 op_sel_hi:[1,0]
	v_pk_add_f32 v[52:53], v[52:53], 0 op_sel_hi:[1,0]
	v_pk_add_f32 v[34:35], v[34:35], 0 op_sel_hi:[1,0]
	v_pk_add_f32 v[32:33], v[32:33], 0 op_sel_hi:[1,0]
	v_pk_add_f32 v[26:27], v[26:27], 0 op_sel_hi:[1,0]
	v_pk_add_f32 v[24:25], v[24:25], 0 op_sel_hi:[1,0]
	v_pk_add_f32 v[22:23], v[22:23], 0 op_sel_hi:[1,0]
	v_pk_add_f32 v[20:21], v[20:21], 0 op_sel_hi:[1,0]
	v_pk_add_f32 v[18:19], v[18:19], 0 op_sel_hi:[1,0]
	v_pk_add_f32 v[16:17], v[16:17], 0 op_sel_hi:[1,0]
	v_pk_add_f32 v[14:15], v[14:15], 0 op_sel_hi:[1,0]
	v_pk_add_f32 v[12:13], v[12:13], 0 op_sel_hi:[1,0]
	v_pk_add_f32 v[10:11], v[10:11], 0 op_sel_hi:[1,0]
	v_pk_add_f32 v[8:9], v[8:9], 0 op_sel_hi:[1,0]
	v_pk_add_f32 v[6:7], v[6:7], 0 op_sel_hi:[1,0]
	v_pk_add_f32 v[4:5], v[4:5], 0 op_sel_hi:[1,0]
	v_pk_add_f32 v[2:3], v[2:3], 0 op_sel_hi:[1,0]
	v_pk_add_f32 v[0:1], v[0:1], 0 op_sel_hi:[1,0]
	s_waitcnt vmcnt(0)
	v_pk_fma_f32 v[126:127], v[126:127], v[186:187], v[190:191]
	v_pk_fma_f32 v[124:125], v[124:125], v[184:185], v[188:189]
	global_store_dwordx4 v[146:147], v[124:127], off
	global_load_dwordx4 v[188:191], v[164:165], off
	global_load_dwordx4 v[192:195], v[166:167], off
	global_load_dwordx4 v[196:199], v[168:169], off
	global_load_dwordx4 v[200:203], v[170:171], off
	global_load_dwordx4 v[204:207], v[174:175], off
	global_load_dwordx4 v[208:211], v[178:179], off
	global_load_dwordx4 v[212:215], v[182:183], off
	global_load_dwordx4 v[216:219], v[144:145], off offset:64
	global_load_dwordx4 v[220:223], v[146:147], off offset:64
	global_load_dwordx4 v[224:227], v[164:165], off offset:64
	global_load_dwordx4 v[228:231], v[166:167], off offset:64
	global_load_dwordx4 v[232:235], v[168:169], off offset:64
	s_waitcnt vmcnt(11)
	v_pk_fma_f32 v[122:123], v[122:123], v[186:187], v[190:191]
	v_pk_fma_f32 v[120:121], v[120:121], v[184:185], v[188:189]
	global_store_dwordx4 v[164:165], v[120:123], off
	global_load_dwordx4 v[188:191], v[162:163], off offset:64
	s_waitcnt vmcnt(12)
	v_pk_fma_f32 v[118:119], v[118:119], v[186:187], v[194:195]
	v_pk_fma_f32 v[116:117], v[116:117], v[184:185], v[192:193]
	global_store_dwordx4 v[166:167], v[116:119], off
	global_load_dwordx4 v[192:195], v[172:173], off offset:64
	s_waitcnt vmcnt(13)
	v_pk_fma_f32 v[114:115], v[114:115], v[186:187], v[198:199]
	v_pk_fma_f32 v[112:113], v[112:113], v[184:185], v[196:197]
	global_store_dwordx4 v[168:169], v[112:115], off
	global_load_dwordx4 v[196:199], v[176:177], off offset:64
	s_waitcnt vmcnt(14)
	v_pk_fma_f32 v[110:111], v[110:111], v[186:187], v[202:203]
	v_pk_fma_f32 v[108:109], v[108:109], v[184:185], v[200:201]
	global_store_dwordx4 v[170:171], v[108:111], off
	global_load_dwordx4 v[200:203], v[180:181], off offset:64
	s_waitcnt vmcnt(15)
	v_pk_fma_f32 v[106:107], v[106:107], v[186:187], v[206:207]
	v_pk_fma_f32 v[104:105], v[104:105], v[184:185], v[204:205]
	global_store_dwordx4 v[174:175], v[104:107], off
	global_load_dwordx4 v[204:207], v[144:145], off offset:512
	s_waitcnt vmcnt(16)
	v_pk_fma_f32 v[102:103], v[102:103], v[186:187], v[210:211]
	v_pk_fma_f32 v[100:101], v[100:101], v[184:185], v[208:209]
	global_store_dwordx4 v[178:179], v[100:103], off
	global_load_dwordx4 v[208:211], v[146:147], off offset:512
	s_waitcnt vmcnt(17)
	v_pk_fma_f32 v[98:99], v[98:99], v[186:187], v[214:215]
	v_pk_fma_f32 v[96:97], v[96:97], v[184:185], v[212:213]
	global_store_dwordx4 v[182:183], v[96:99], off
	global_load_dwordx4 v[184:187], v[164:165], off offset:512
	s_waitcnt vmcnt(17)
	v_pk_fma_f32 v[94:95], v[94:95], v[218:219], v[222:223]
	v_pk_fma_f32 v[92:93], v[92:93], v[216:217], v[220:221]
	global_store_dwordx4 v[146:147], v[92:95], off offset:64
	global_load_dwordx4 v[212:215], v[166:167], off offset:512
	global_load_dwordx4 v[220:223], v[168:169], off offset:512
	s_waitcnt vmcnt(19)
	v_pk_fma_f32 v[90:91], v[90:91], v[218:219], v[226:227]
	v_pk_fma_f32 v[88:89], v[88:89], v[216:217], v[224:225]
	global_store_dwordx4 v[164:165], v[88:91], off offset:64
	global_load_dwordx4 v[224:227], v[162:163], off offset:512
	s_waitcnt vmcnt(20)
	v_pk_fma_f32 v[86:87], v[86:87], v[218:219], v[230:231]
	v_pk_fma_f32 v[84:85], v[84:85], v[216:217], v[228:229]
	global_store_dwordx4 v[166:167], v[84:87], off offset:64
	global_load_dwordx4 v[228:231], v[172:173], off offset:512
	s_waitcnt vmcnt(21)
	v_pk_fma_f32 v[82:83], v[82:83], v[218:219], v[234:235]
	v_pk_fma_f32 v[80:81], v[80:81], v[216:217], v[232:233]
	global_store_dwordx4 v[168:169], v[80:83], off offset:64
	global_load_dwordx4 v[232:235], v[176:177], off offset:512
	s_waitcnt vmcnt(21)
	v_pk_fma_f32 v[74:75], v[74:75], v[218:219], v[190:191]
	v_pk_fma_f32 v[72:73], v[72:73], v[216:217], v[188:189]
	global_store_dwordx4 v[162:163], v[72:75], off offset:64
	global_load_dwordx4 v[188:191], v[180:181], off offset:512
	s_waitcnt vmcnt(21)
	v_pk_fma_f32 v[66:67], v[66:67], v[218:219], v[194:195]
	v_pk_fma_f32 v[64:65], v[64:65], v[216:217], v[192:193]
	global_store_dwordx4 v[172:173], v[64:67], off offset:64
	global_load_dwordx4 v[192:195], v[144:145], off offset:576
	s_waitcnt vmcnt(21)
	v_pk_fma_f32 v[58:59], v[58:59], v[218:219], v[198:199]
	v_pk_fma_f32 v[56:57], v[56:57], v[216:217], v[196:197]
	global_store_dwordx4 v[176:177], v[56:59], off offset:64
	global_load_dwordx4 v[196:199], v[146:147], off offset:576
	v_pk_add_f32 v[64:65], v[78:79], 0 op_sel_hi:[1,0]
	v_pk_add_f32 v[66:67], v[76:77], 0 op_sel_hi:[1,0]
	s_waitcnt vmcnt(21)
	v_pk_fma_f32 v[46:47], v[46:47], v[218:219], v[202:203]
	v_pk_fma_f32 v[44:45], v[44:45], v[216:217], v[200:201]
	global_store_dwordx4 v[180:181], v[44:47], off offset:64
	global_load_dwordx4 v[200:203], v[164:165], off offset:576
	s_waitcnt vmcnt(19)
	v_pk_fma_f32 v[58:59], v[64:65], v[206:207], v[210:211]
	v_pk_fma_f32 v[56:57], v[66:67], v[204:205], v[208:209]
	global_store_dwordx4 v[146:147], v[56:59], off offset:512
	global_load_dwordx4 v[208:211], v[166:167], off offset:576
	global_load_dwordx4 v[216:219], v[168:169], off offset:576
	v_pk_add_f32 v[64:65], v[70:71], 0 op_sel_hi:[1,0]
	v_pk_add_f32 v[66:67], v[68:69], 0 op_sel_hi:[1,0]
	s_waitcnt vmcnt(20)
	v_pk_fma_f32 v[58:59], v[64:65], v[206:207], v[186:187]
	v_pk_fma_f32 v[56:57], v[66:67], v[204:205], v[184:185]
	global_store_dwordx4 v[164:165], v[56:59], off offset:512
	global_load_dwordx4 v[184:187], v[162:163], off offset:576
	s_waitcnt vmcnt(20)
	v_pk_fma_f32 v[58:59], v[62:63], v[206:207], v[214:215]
	v_pk_fma_f32 v[56:57], v[60:61], v[204:205], v[212:213]
	global_store_dwordx4 v[166:167], v[56:59], off offset:512
	global_load_dwordx4 v[212:215], v[172:173], off offset:576
	s_waitcnt vmcnt(21)
	v_pk_fma_f32 v[54:55], v[54:55], v[206:207], v[222:223]
	v_pk_fma_f32 v[52:53], v[52:53], v[204:205], v[220:221]
	global_store_dwordx4 v[168:169], v[52:55], off offset:512
	global_load_dwordx4 v[220:223], v[176:177], off offset:576
	s_waitcnt vmcnt(21)
	v_pk_fma_f32 v[34:35], v[34:35], v[206:207], v[226:227]
	v_pk_fma_f32 v[32:33], v[32:33], v[204:205], v[224:225]
	global_store_dwordx4 v[162:163], v[32:35], off offset:512
	global_load_dwordx4 v[224:227], v[180:181], off offset:576
	s_waitcnt vmcnt(21)
	v_pk_fma_f32 v[26:27], v[26:27], v[206:207], v[230:231]
	v_pk_fma_f32 v[24:25], v[24:25], v[204:205], v[228:229]
	global_store_dwordx4 v[172:173], v[24:27], off offset:512
	s_waitcnt vmcnt(20)
	v_pk_fma_f32 v[22:23], v[22:23], v[206:207], v[234:235]
	v_pk_fma_f32 v[20:21], v[20:21], v[204:205], v[232:233]
	global_store_dwordx4 v[176:177], v[20:23], off offset:512
	v_pk_add_f32 v[24:25], v[50:51], 0 op_sel_hi:[1,0]
	v_pk_add_f32 v[26:27], v[48:49], 0 op_sel_hi:[1,0]
	s_waitcnt vmcnt(19)
	v_pk_fma_f32 v[18:19], v[18:19], v[206:207], v[190:191]
	v_pk_fma_f32 v[16:17], v[16:17], v[204:205], v[188:189]
	global_store_dwordx4 v[180:181], v[16:19], off offset:512
	s_waitcnt vmcnt(16)
	v_pk_fma_f32 v[22:23], v[24:25], v[194:195], v[198:199]
	v_pk_fma_f32 v[20:21], v[26:27], v[192:193], v[196:197]
	global_store_dwordx4 v[146:147], v[20:23], off offset:576
	v_pk_add_f32 v[24:25], v[42:43], 0 op_sel_hi:[1,0]
	v_pk_add_f32 v[26:27], v[40:41], 0 op_sel_hi:[1,0]
	s_waitcnt vmcnt(15)
	v_pk_fma_f32 v[22:23], v[24:25], v[194:195], v[202:203]
	v_pk_fma_f32 v[20:21], v[26:27], v[192:193], v[200:201]
	global_store_dwordx4 v[164:165], v[20:23], off offset:576
	v_pk_add_f32 v[24:25], v[38:39], 0 op_sel_hi:[1,0]
	v_pk_add_f32 v[26:27], v[36:37], 0 op_sel_hi:[1,0]
	s_waitcnt vmcnt(14)
	v_pk_fma_f32 v[22:23], v[24:25], v[194:195], v[210:211]
	v_pk_fma_f32 v[20:21], v[26:27], v[192:193], v[208:209]
	global_store_dwordx4 v[166:167], v[20:23], off offset:576
	v_pk_add_f32 v[24:25], v[30:31], 0 op_sel_hi:[1,0]
	v_pk_add_f32 v[26:27], v[28:29], 0 op_sel_hi:[1,0]
	s_waitcnt vmcnt(14)
	v_pk_fma_f32 v[22:23], v[24:25], v[194:195], v[218:219]
	v_pk_fma_f32 v[20:21], v[26:27], v[192:193], v[216:217]
	global_store_dwordx4 v[168:169], v[20:23], off offset:576
	s_waitcnt vmcnt(13)
	v_pk_fma_f32 v[14:15], v[14:15], v[194:195], v[186:187]
	v_pk_fma_f32 v[12:13], v[12:13], v[192:193], v[184:185]
	global_store_dwordx4 v[162:163], v[12:15], off offset:576
	s_waitcnt vmcnt(12)
	v_pk_fma_f32 v[10:11], v[10:11], v[194:195], v[214:215]
	v_pk_fma_f32 v[8:9], v[8:9], v[192:193], v[212:213]
	global_store_dwordx4 v[172:173], v[8:11], off offset:576
	s_waitcnt vmcnt(11)
	v_pk_fma_f32 v[6:7], v[6:7], v[194:195], v[222:223]
	v_pk_fma_f32 v[4:5], v[4:5], v[192:193], v[220:221]
	global_store_dwordx4 v[176:177], v[4:7], off offset:576
	s_waitcnt vmcnt(10)
	v_pk_fma_f32 v[2:3], v[2:3], v[194:195], v[226:227]
	v_pk_fma_f32 v[0:1], v[0:1], v[192:193], v[224:225]
	global_store_dwordx4 v[180:181], v[0:3], off offset:576
	s_cbranch_vccz .LBB0_2070
	s_waitcnt vmcnt(0)
	s_cmpk_gt_u32 s1, 0xff
	s_cbranch_scc1 .LBB0_2085
	s_barrier

.LBB0_2460:
	ds_read_b128 v[188:191], v33
	ds_read_b128 v[192:195], v105
	ds_read_b128 v[196:199], v33 offset:64
	ds_read_b128 v[200:203], v105 offset:64
	ds_read_b128 v[204:207], v33 offset:128
	ds_read_b128 v[208:211], v105 offset:128
	ds_read_b128 v[212:215], v33 offset:192
	ds_read_b128 v[216:219], v105 offset:192
	s_ashr_i32 s40, s46, 4
	s_mul_hi_i32 s41, s40, 0x78787879
	s_lshr_b32 s47, s41, 31
	s_ashr_i32 s41, s41, 5
	s_waitcnt lgkmcnt(6)
	v_mfma_f32_16x16x32_bf16 v[108:111], v[188:191], v[192:195], 0
	s_add_i32 s41, s41, s47
	s_mulk_i32 s41, 0x44
	s_sub_i32 s63, s40, s41
	s_waitcnt lgkmcnt(4)
	s_nop 1
	v_mfma_f32_16x16x32_bf16 v[108:111], v[196:199], v[200:203], v[108:111]
	s_mul_hi_i32 s40, s46, 0x78787879
	s_lshr_b32 s41, s40, 31
	s_waitcnt lgkmcnt(2)
	s_nop 1
	v_mfma_f32_16x16x32_bf16 v[108:111], v[204:207], v[208:211], v[108:111]
	s_ashr_i32 s64, s40, 9
	s_add_i32 s64, s64, s41
	s_waitcnt lgkmcnt(0)
	s_nop 1
	v_mfma_f32_16x16x32_bf16 v[108:111], v[212:215], v[216:219], v[108:111]
	s_nop 7
	ds_write_b32 v106, v108
	ds_write_b32 v106, v109 offset:260
	ds_write_b32 v106, v110 offset:520
	ds_write_b32 v106, v111 offset:780
	ds_read_b128 v[188:191], v33
	ds_read_b128 v[192:195], v105 offset:4352
	ds_read_b128 v[196:199], v33 offset:64
	ds_read_b128 v[200:203], v105 offset:4416
	ds_read_b128 v[204:207], v33 offset:128
	ds_read_b128 v[208:211], v105 offset:4480
	ds_read_b128 v[212:215], v33 offset:192
	ds_read_b128 v[216:219], v105 offset:4544
	s_mov_b64 s[40:41], -1
	s_waitcnt lgkmcnt(6)
	v_mfma_f32_16x16x32_bf16 v[108:111], v[188:191], v[192:195], 0
	s_cmp_gt_i32 s63, 3
	s_waitcnt lgkmcnt(4)
	s_nop 1
	v_mfma_f32_16x16x32_bf16 v[108:111], v[196:199], v[200:203], v[108:111]
	s_waitcnt lgkmcnt(2)
	s_nop 1
	v_mfma_f32_16x16x32_bf16 v[108:111], v[204:207], v[208:211], v[108:111]
	s_waitcnt lgkmcnt(0)
	s_nop 1
	v_mfma_f32_16x16x32_bf16 v[108:111], v[212:215], v[216:219], v[108:111]
	s_nop 7
	ds_write_b32 v106, v108 offset:64
	ds_write_b32 v106, v109 offset:324
	ds_write_b32 v106, v110 offset:584
	ds_write_b32 v106, v111 offset:844
	ds_read_b128 v[188:191], v33
	ds_read_b128 v[192:195], v105 offset:8704
	ds_read_b128 v[196:199], v33 offset:64
	ds_read_b128 v[200:203], v105 offset:8768
	ds_read_b128 v[204:207], v33 offset:128
	ds_read_b128 v[208:211], v105 offset:8832
	ds_read_b128 v[212:215], v33 offset:192
	ds_read_b128 v[216:219], v105 offset:8896
	s_waitcnt lgkmcnt(6)
	v_mfma_f32_16x16x32_bf16 v[108:111], v[188:191], v[192:195], 0
	s_waitcnt lgkmcnt(4)
	s_nop 1
	v_mfma_f32_16x16x32_bf16 v[108:111], v[196:199], v[200:203], v[108:111]
	s_waitcnt lgkmcnt(2)
	s_nop 1
	v_mfma_f32_16x16x32_bf16 v[108:111], v[204:207], v[208:211], v[108:111]
	s_waitcnt lgkmcnt(0)
	s_nop 1
	v_mfma_f32_16x16x32_bf16 v[108:111], v[212:215], v[216:219], v[108:111]
	s_nop 7
	ds_write_b32 v106, v108 offset:128
	ds_write_b32 v106, v109 offset:388
	ds_write_b32 v106, v110 offset:648
	ds_write_b32 v106, v111 offset:908
	ds_read_b128 v[188:191], v33
	ds_read_b128 v[192:195], v105 offset:13056
	ds_read_b128 v[196:199], v33 offset:64
	ds_read_b128 v[200:203], v105 offset:13120
	ds_read_b128 v[204:207], v33 offset:128
	ds_read_b128 v[208:211], v105 offset:13184
	s_waitcnt lgkmcnt(4)
	v_mfma_f32_16x16x32_bf16 v[108:111], v[188:191], v[192:195], 0
	s_waitcnt lgkmcnt(2)
	s_nop 1
	v_mfma_f32_16x16x32_bf16 v[108:111], v[196:199], v[200:203], v[108:111]
	s_waitcnt lgkmcnt(0)
	s_nop 1
	v_mfma_f32_16x16x32_bf16 v[108:111], v[204:207], v[208:211], v[108:111]
	ds_read_b128 v[112:115], v33 offset:192
	ds_read_b128 v[116:119], v105 offset:13248
	s_waitcnt lgkmcnt(0)
	v_mfma_f32_16x16x32_bf16 v[108:111], v[112:115], v[116:119], v[108:111]
	s_nop 7
	ds_write_b32 v106, v108 offset:192
	ds_write_b32 v106, v109 offset:452
	ds_write_b32 v106, v110 offset:712
	ds_write_b32 v106, v111 offset:972
	s_waitcnt lgkmcnt(0)
	s_barrier
	s_cbranch_scc0 .LBB0_2462
	s_lshl_b32 s40, s64, 12
	s_lshl_b32 s41, s63, 6
	s_add_i32 s40, s40, s41
	s_add_i32 s47, s40, 0xffffff00
	s_mov_b64 s[40:41], 0

.LBB0_2464:
	v_add_u32_e32 v30, s47, v34
	s_lshl_b32 s40, s46, 1
	v_ashrrev_i32_e32 v31, 31, v30
	s_and_b32 s40, s40, 30
	v_lshlrev_b64 v[30:31], 6, v[30:31]
	s_or_b32 s40, s40, s3
	v_or_b32_e32 v30, s5, v30
	v_readlane_b32 s44, v239, 51
	v_or_b32_e32 v30, s40, v30
	v_readlane_b32 s45, v239, 52
	s_mul_i32 s41, s64, 0x44
	s_add_i32 s41, s41, s63
	v_lshl_add_u64 v[108:109], v[30:31], 2, s[44:45]
	global_load_dword v107, v[108:109], off
	s_lshl_b32 s41, s41, 6
	s_lshl_b32 s40, s40, 1
	v_readlane_b32 s46, v239, 53
	v_readlane_b32 s47, v239, 54
	s_or_b32 s40, s41, s40
	s_andn2_b64 vcc, exec, s[36:37]
	s_or_b32 s40, s40, s2
	s_mov_b64 s[46:47], -1
	v_readlane_b32 s48, v239, 55
	v_readlane_b32 s49, v239, 56
	v_readlane_b32 s50, v239, 57
	v_readlane_b32 s51, v239, 58
	v_readlane_b32 s52, v239, 59
	v_readlane_b32 s53, v239, 60
	v_readlane_b32 s54, v239, 61
	v_readlane_b32 s55, v239, 62
	v_readlane_b32 s56, v239, 63
	v_readlane_b32 s57, v238, 0
	v_readlane_b32 s58, v238, 1
	v_readlane_b32 s59, v238, 2
	s_waitcnt vmcnt(0)
	ds_bpermute_b32 v187, v17, v107
	s_waitcnt lgkmcnt(0)
	v_add_f32_e32 v108, v107, v187
	v_cndmask_b32_e64 v107, v108, v107, s[12:13]
	ds_bpermute_b32 v187, v25, v107
	s_waitcnt lgkmcnt(0)
	v_add_f32_e32 v108, v107, v187
	v_cndmask_b32_e64 v107, v108, v107, s[14:15]
	ds_bpermute_b32 v187, v27, v107
	s_waitcnt lgkmcnt(0)
	v_add_f32_e32 v108, v107, v187
	v_cndmask_b32_e64 v107, v108, v107, s[16:17]
	ds_bpermute_b32 v187, v36, v107
	s_waitcnt lgkmcnt(0)
	v_add_f32_e32 v108, v107, v187
	v_cndmask_b32_e64 v107, v108, v107, s[18:19]
	ds_bpermute_b32 v187, v37, v107
	s_waitcnt lgkmcnt(0)
	v_add_f32_e32 v108, v107, v187
	v_cndmask_b32_e64 v107, v108, v107, s[20:21]
	ds_bpermute_b32 v187, v38, v107
	s_waitcnt lgkmcnt(0)
	v_add_f32_e32 v108, v107, v187
	v_cndmask_b32_e64 v107, v108, v107, s[22:23]
	s_cbranch_vccnz .LBB0_2476
	v_readlane_b32 s44, v239, 51
	v_readlane_b32 s46, v239, 53
	v_readlane_b32 s47, v239, 54
	s_mov_b32 s41, 3
	s_mov_b32 s65, 60
	v_lshl_add_u64 v[30:31], v[30:31], 2, s[46:47]
	global_load_dword v30, v[30:31], off
	v_mov_b32_e32 v31, v104
	v_readlane_b32 s45, v239, 52
	v_readlane_b32 s48, v239, 55
	v_readlane_b32 s49, v239, 56
	v_readlane_b32 s50, v239, 57
	v_readlane_b32 s51, v239, 58
	v_readlane_b32 s52, v239, 59
	v_readlane_b32 s53, v239, 60
	v_readlane_b32 s54, v239, 61
	v_readlane_b32 s55, v239, 62
	v_readlane_b32 s56, v239, 63
	v_readlane_b32 s57, v238, 0
	v_readlane_b32 s58, v238, 1
	v_readlane_b32 s59, v238, 2
	s_branch .LBB0_2467

.LBB0_2550:
	s_add_i32 s40, s27, 1
	s_cmpk_lg_i32 s39, 0xffbe
	s_cselect_b32 s41, s40, 0x43
	s_cmp_gt_u32 s41, 3
	s_cselect_b32 s42, 0x47, 3
	s_sub_i32 s42, s42, s41
	s_and_b64 s[46:47], s[12:13], exec
	s_cselect_b32 s41, s41, s42
	s_add_i32 s42, s41, s2
	s_lshl_b32 s42, s42, 6
	s_or_b32 s46, s42, s38
	s_ashr_i32 s47, s46, 31
	s_lshl_b64 s[62:63], s[46:47], 8
	s_add_u32 s62, s34, s62
	s_addc_u32 s63, s35, s63
	s_lshl_b32 s42, s41, 6
	s_cmp_lt_i32 s41, 4
	s_movk_i32 s64, 0xff00
	s_cselect_b32 s64, 0x2000, s64
	s_cselect_b32 s65, s4, s21
	s_cselect_b32 s41, s3, s5
	s_add_i32 s65, s65, s42
	s_add_i32 s42, s64, s42
	s_add_i32 s42, s42, s41
	s_lshl_b64 s[46:47], s[46:47], 13
	s_add_i32 s41, s27, -1
	s_cmp_gt_u32 s27, 4
	s_cselect_b32 s27, 0x47, 3
	s_add_i32 s27, s27, s39
	v_lshl_add_u64 v[24:25], v[72:73], 0, s[46:47]
	v_lshl_add_u64 v[28:29], v[74:75], 0, s[46:47]
	s_and_b64 s[46:47], s[12:13], exec
	s_cselect_b32 s27, s41, s27
	s_lshl_b32 s41, s27, 6
	s_cmp_lt_i32 s27, 4
	s_cselect_b32 s27, s4, s21
	s_add_i32 s27, s27, s41
	v_add_u32_e32 v56, s27, v141
	v_ashrrev_i32_e32 v57, 31, v56
	v_lshl_add_u64 v[56:57], v[56:57], 0, s[16:17]
	v_lshlrev_b64 v[56:57], 13, v[56:57]
	v_cvt_pk_bf16_f32 v48, v48, s0
	v_lshl_add_u64 v[56:57], v[88:89], 0, v[56:57]
	s_waitcnt lgkmcnt(0)
	s_barrier
	ds_read_b128 v[168:171], v115
	ds_read_b128 v[172:175], v116
	ds_read_b128 v[176:179], v130
	ds_read_b128 v[180:183], v117
	ds_read_b128 v[184:187], v117 offset:17408
	ds_read_b128 v[188:191], v130 offset:64
	ds_read_b128 v[192:195], v117 offset:64
	ds_read_b128 v[196:199], v117 offset:17472
	ds_read_b128 v[200:203], v130 offset:128
	ds_read_b128 v[204:207], v117 offset:128
	ds_read_b128 v[208:211], v117 offset:17536
	ds_read_b128 v[212:215], v130 offset:192
	ds_read_b128 v[216:219], v117 offset:192
	ds_read_b128 v[220:223], v117 offset:17600
	ds_read_u16 v166, v131 offset:44032
	s_waitcnt lgkmcnt(14)
	ds_read_u16 v167, v131 offset:44176
	s_waitcnt lgkmcnt(14)
	ds_read_u16 v224, v131 offset:44320
	s_waitcnt lgkmcnt(14)
	ds_read_u16 v225, v131 offset:44464
	global_store_short v[56:57], v48, off
	v_add_u32_e32 v48, s27, v140
	v_cvt_pk_bf16_f32 v58, v49, s0
	v_ashrrev_i32_e32 v49, 31, v48
	v_lshl_add_u64 v[48:49], v[48:49], 0, s[16:17]
	v_lshlrev_b64 v[48:49], 13, v[48:49]
	v_lshl_add_u64 v[48:49], v[88:89], 0, v[48:49]
	global_store_short v[48:49], v58, off
	v_add_u32_e32 v58, s27, v139
	v_ashrrev_i32_e32 v59, 31, v58
	v_lshl_add_u64 v[58:59], v[58:59], 0, s[16:17]
	v_add_u32_e32 v4, s65, v138
	v_lshlrev_b64 v[58:59], 13, v[58:59]
	v_ashrrev_i32_e32 v5, 31, v4
	v_cvt_pk_bf16_f32 v50, v50, s0
	v_lshl_add_u64 v[58:59], v[88:89], 0, v[58:59]
	v_lshlrev_b64 v[4:5], 8, v[4:5]
	global_store_short v[58:59], v50, off
	v_add_u32_e32 v50, s27, v87
	v_lshl_add_u64 v[4:5], s[36:37], 0, v[4:5]
	v_cvt_pk_bf16_f32 v60, v51, s0
	v_ashrrev_i32_e32 v51, 31, v50
	v_cvt_pk_bf16_f32 v52, v52, s0
	global_load_dword v143, v[4:5], off
	v_add_u32_e32 v4, s42, v136
	v_add_u32_e32 v12, s42, v137
	v_add_u32_e32 v20, s42, v85
	v_lshl_add_u64 v[50:51], v[50:51], 0, s[16:17]
	global_store_short v[56:57], v52, off offset:32
	v_cvt_pk_bf16_f32 v52, v53, s0
	v_ashrrev_i32_e32 v5, 31, v4
	v_ashrrev_i32_e32 v13, 31, v12
	v_ashrrev_i32_e32 v21, 31, v20
	v_lshlrev_b64 v[50:51], 13, v[50:51]
	global_store_short v[48:49], v52, off offset:32
	v_cvt_pk_bf16_f32 v48, v54, s0
	v_lshlrev_b64 v[8:9], 12, v[4:5]
	v_lshlrev_b64 v[16:17], 12, v[12:13]
	v_lshlrev_b64 v[20:21], 13, v[20:21]
	v_lshl_add_u64 v[50:51], v[88:89], 0, v[50:51]
	global_store_short v[58:59], v48, off offset:32
	v_cvt_pk_bf16_f32 v48, v55, s0
	v_lshl_add_u64 v[6:7], v[68:69], 2, s[62:63]
	v_lshl_add_u64 v[4:5], v[90:91], 0, v[8:9]
	v_lshl_add_u64 v[8:9], v[92:93], 0, v[8:9]
	v_lshl_add_u64 v[12:13], v[90:91], 0, v[16:17]
	v_lshl_add_u64 v[16:17], v[92:93], 0, v[16:17]
	v_lshl_add_u64 v[20:21], v[94:95], 0, v[20:21]
	global_store_short v[50:51], v60, off
	global_store_short v[50:51], v48, off offset:32
	global_load_dword v153, v71, s[62:63] offset:252
	global_load_dword v142, v[6:7], off
	s_add_i32 s39, s39, -1
	global_load_dwordx4 v[8:11], v[8:9], off
	s_cmpk_eq_i32 s40, 0x44
	global_load_dwordx4 v[12:15], v[12:13], off
	global_load_dwordx4 v[4:7], v[4:5], off
	global_load_dwordx4 v[16:19], v[16:17], off
	global_load_dwordx4 v[20:23], v[20:21], off
	global_load_dwordx4 v[24:27], v[24:25], off
	global_load_dwordx4 v[28:31], v[28:29], off
	s_waitcnt lgkmcnt(14)
	v_mfma_f32_16x16x32_bf16 v[60:63], v[180:183], v[176:179], 0
	ds_read_b128 v[180:183], v132
	s_waitcnt lgkmcnt(14)
	v_mfma_f32_16x16x32_bf16 v[56:59], v[184:187], v[176:179], 0
	ds_read_b128 v[176:179], v117
	s_waitcnt lgkmcnt(14)
	ds_read_b128 v[184:187], v117 offset:17408
	s_waitcnt lgkmcnt(14)
	v_mfma_f32_16x16x32_bf16 v[60:63], v[192:195], v[188:191], v[60:63]
	ds_read_b128 v[192:195], v132 offset:64
	s_waitcnt lgkmcnt(14)
	v_mfma_f32_16x16x32_bf16 v[56:59], v[196:199], v[188:191], v[56:59]
	ds_read_b128 v[188:191], v117 offset:64
	s_waitcnt lgkmcnt(14)
	ds_read_b128 v[196:199], v117 offset:17472
	s_waitcnt lgkmcnt(14)
	v_mfma_f32_16x16x32_bf16 v[60:63], v[204:207], v[200:203], v[60:63]
	ds_read_b128 v[204:207], v132 offset:128
	s_waitcnt lgkmcnt(14)
	v_mfma_f32_16x16x32_bf16 v[56:59], v[208:211], v[200:203], v[56:59]
	ds_read_b128 v[200:203], v117 offset:128
	s_waitcnt lgkmcnt(14)
	ds_read_b128 v[208:211], v117 offset:17536
	s_waitcnt lgkmcnt(14)
	v_mfma_f32_16x16x32_bf16 v[60:63], v[216:219], v[212:215], v[60:63]
	ds_read_b128 v[216:219], v117 offset:192
	s_waitcnt lgkmcnt(14)
	v_mfma_f32_16x16x32_bf16 v[56:59], v[220:223], v[212:215], v[56:59]
	ds_read_u16 v212, v131 offset:44064
	s_waitcnt lgkmcnt(14)
	ds_read_u16 v213, v131 offset:44208
	v_lshlrev_b32_e32 v64, 16, v166
	s_waitcnt lgkmcnt(14)
	ds_read_u16 v166, v131 offset:44352
	v_lshlrev_b32_e32 v65, 16, v167
	s_waitcnt lgkmcnt(14)
	ds_read_u16 v167, v131 offset:44496
	s_waitcnt lgkmcnt(14)
	v_lshlrev_b32_e32 v67, 16, v225
	ds_read_b128 v[220:223], v133
	v_lshlrev_b32_e32 v66, 16, v224
	s_waitcnt lgkmcnt(14)
	ds_read_b128 v[224:227], v133 offset:4352
	v_pk_fma_f32 v[60:61], v[168:169], v[60:61], v[64:65] neg_lo:[1,0,0] neg_hi:[1,0,0]
	v_pk_fma_f32 v[62:63], v[170:171], v[62:63], v[66:67] neg_lo:[1,0,0] neg_hi:[1,0,0]
	v_pk_mul_f32 v[64:65], v[172:173], v[60:61]
	v_pk_mul_f32 v[62:63], v[174:175], v[62:63]
	v_cvt_pk_bf16_f32 v64, v64, v65
	v_cvt_pk_bf16_f32 v65, v62, v63
	s_waitcnt lgkmcnt(14)
	ds_write_b64 v145, v[64:65]
	v_mfma_f32_16x16x32_bf16 v[154:157], v[176:179], v[180:183], 0
	s_waitcnt lgkmcnt(14)
	ds_read_b128 v[176:179], v133 offset:8704
	v_mul_f32_e64 v60, v168, s20
	v_mul_f32_e64 v61, v169, s20
	v_pk_mul_f32 v[66:67], v[170:171], s[20:21] op_sel_hi:[1,0]
	v_pk_mul_f32 v[56:57], v[60:61], v[56:57]
	v_mfma_f32_16x16x32_bf16 v[62:65], v[184:187], v[180:183], 0
	s_waitcnt lgkmcnt(14)
	ds_read_b128 v[180:183], v133 offset:13056
	v_pk_mul_f32 v[58:59], v[66:67], v[58:59]
	s_waitcnt lgkmcnt(14)
	v_mfma_f32_16x16x32_bf16 v[154:157], v[188:191], v[192:195], v[154:157]
	s_waitcnt lgkmcnt(13)
	s_nop 0
	v_mfma_f32_16x16x32_bf16 v[62:65], v[196:199], v[192:195], v[62:65]
	s_waitcnt lgkmcnt(11)
	s_nop 1
	v_mfma_f32_16x16x32_bf16 v[154:157], v[200:203], v[204:207], v[154:157]
	s_waitcnt lgkmcnt(10)
	s_nop 0
	v_mfma_f32_16x16x32_bf16 v[62:65], v[208:211], v[204:207], v[62:65]
	ds_read_b128 v[158:161], v132 offset:192
	s_waitcnt lgkmcnt(0)
	s_nop 0
	v_mfma_f32_16x16x32_bf16 v[154:157], v[216:219], v[158:161], v[154:157]
	ds_read_b128 v[162:165], v117 offset:17600
	s_waitcnt lgkmcnt(0)
	v_mfma_f32_16x16x32_bf16 v[62:65], v[162:165], v[158:161], v[62:65]
	v_lshlrev_b32_e32 v158, 16, v212
	v_lshlrev_b32_e32 v159, 16, v213
	s_nop 3
	v_pk_fma_f32 v[48:49], v[168:169], v[154:155], v[158:159] neg_lo:[1,0,0] neg_hi:[1,0,0]
	s_nop 0
	v_pk_mul_f32 v[48:49], v[172:173], v[48:49]
	s_nop 0
	v_cvt_pk_bf16_f32 v48, v48, v49
	v_lshlrev_b32_e32 v52, 16, v166
	v_lshlrev_b32_e32 v53, 16, v167
	s_nop 2
	v_pk_fma_f32 v[50:51], v[170:171], v[156:157], v[52:53] neg_lo:[1,0,0] neg_hi:[1,0,0]
	v_pk_mul_f32 v[52:53], v[60:61], v[62:63]
	v_pk_mul_f32 v[50:51], v[174:175], v[50:51]
	v_pk_mul_f32 v[54:55], v[66:67], v[64:65]
	v_cvt_pk_bf16_f32 v49, v50, v51
	ds_write_b64 v146, v[48:49]
	v_mfma_f32_16x16x32_bf16 v[48:51], v[220:223], v[0:3], 0
	s_nop 7
	v_cvt_pk_bf16_f32 v60, v48, v49
	v_cvt_pk_bf16_f32 v61, v50, v51
	s_nop 1
	v_mfma_f32_16x16x32_bf16 v[48:51], v[224:227], v[0:3], 0
	s_nop 7
	v_cvt_pk_bf16_f32 v62, v48, v49
	v_cvt_pk_bf16_f32 v63, v50, v51
	s_nop 1
	v_mfma_f32_16x16x32_bf16 v[48:51], v[176:179], v[0:3], 0
	s_nop 7
	v_cvt_pk_bf16_f32 v64, v48, v49
	v_cvt_pk_bf16_f32 v65, v50, v51
	s_nop 1
	v_mfma_f32_16x16x32_bf16 v[48:51], v[180:183], v[0:3], 0
	s_waitcnt lgkmcnt(0)
	s_barrier
	ds_read_b128 v[168:171], v119
	ds_read_b128 v[172:175], v120 offset:53248
	ds_read_b128 v[176:179], v122
	ds_read_b128 v[180:183], v120 offset:53312
	ds_read_b128 v[184:187], v122 offset:64
	ds_read_b128 v[188:191], v120 offset:53248
	ds_read_b128 v[192:195], v125
	v_cvt_pk_bf16_f32 v66, v48, v49
	v_cvt_pk_bf16_f32 v67, v50, v51
	s_waitcnt lgkmcnt(4)
	v_mfma_f32_16x16x32_bf16 v[154:157], v[172:175], v[176:179], 0
	s_waitcnt lgkmcnt(2)
	s_nop 1
	v_mfma_f32_16x16x32_bf16 v[154:157], v[180:183], v[184:187], v[154:157]
	s_nop 7
	v_cvt_pk_bf16_f32 v158, v154, v155
	v_cvt_pk_bf16_f32 v159, v156, v157
	v_pk_mul_f32 v[154:155], v[168:169], v[154:155]
	v_pk_mul_f32 v[156:157], v[170:171], v[156:157]
	v_cvt_pk_bf16_f32 v154, v154, v155
	v_cvt_pk_bf16_f32 v155, v156, v157
	ds_write_b64 v123, v[158:159]
	ds_write_b64 v124, v[154:155] offset:34816
	s_waitcnt lgkmcnt(2)
	s_nop 1
	v_mfma_f32_16x16x32_bf16 v[154:157], v[188:191], v[192:195], 0
	ds_read_b128 v[158:161], v120 offset:53312
	ds_read_b128 v[162:165], v125 offset:64
	s_waitcnt lgkmcnt(0)
	v_mfma_f32_16x16x32_bf16 v[154:157], v[158:161], v[162:165], v[154:157]
	s_nop 7
	v_pk_mul_f32 v[48:49], v[168:169], v[154:155]
	v_pk_mul_f32 v[50:51], v[170:171], v[156:157]
	v_cvt_pk_bf16_f32 v158, v154, v155
	v_cvt_pk_bf16_f32 v159, v156, v157
	v_cvt_pk_bf16_f32 v48, v48, v49
	v_cvt_pk_bf16_f32 v49, v50, v51
	ds_write_b64 v126, v[158:159]
	ds_write_b64 v127, v[48:49] offset:34816
	s_waitcnt lgkmcnt(0)
	s_barrier
	ds_read_b128 v[168:171], v120 offset:62464
	ds_read_b128 v[172:175], v147
	ds_read_b128 v[176:179], v120 offset:62528
	ds_read_b128 v[180:183], v147 offset:64
	ds_read2_b64 v[184:187], v149 offset1:4
	ds_read2_b64 v[188:191], v149 offset0:8 offset1:12
	ds_read2_b64 v[192:195], v150 offset0:32 offset1:36
	ds_read2_b64 v[196:199], v150 offset0:40 offset1:44
	ds_read2_b64 v[200:203], v151 offset0:64 offset1:68
	ds_read2_b64 v[204:207], v151 offset0:72 offset1:76
	ds_read2_b64 v[208:211], v152 offset0:96 offset1:100
	s_waitcnt lgkmcnt(9)
	v_mfma_f32_16x16x32_bf16 v[48:51], v[168:171], v[172:175], v[56:59]
	s_waitcnt lgkmcnt(7)
	s_nop 4
	v_mfma_f32_16x16x32_bf16 v[48:51], v[176:179], v[180:183], v[48:51]
	ds_read_b128 v[158:161], v148
	s_waitcnt lgkmcnt(0)
	v_mfma_f32_16x16x32_bf16 v[52:55], v[168:171], v[158:161], v[52:55]
	ds_read_b128 v[154:157], v148 offset:64
	s_waitcnt lgkmcnt(0)
	v_mfma_f32_16x16x32_bf16 v[52:55], v[176:179], v[154:157], v[52:55]
	v_mul_f32_e32 v56, 0x3fb8aa3b, v144
	v_exp_f32_e32 v144, v56
	s_nop 0
	v_pk_mul_f32 v[34:35], v[34:35], v[144:145] op_sel_hi:[1,0]
	v_pk_mul_f32 v[32:33], v[32:33], v[144:145] op_sel_hi:[1,0]
	v_pk_mul_f32 v[38:39], v[38:39], v[144:145] op_sel_hi:[1,0]
	v_pk_mul_f32 v[36:37], v[36:37], v[144:145] op_sel_hi:[1,0]
	v_mfma_f32_16x16x32_bf16 v[32:35], v[60:63], v[184:187], v[32:35]
	v_pk_mul_f32 v[42:43], v[42:43], v[144:145] op_sel_hi:[1,0]
	v_pk_mul_f32 v[40:41], v[40:41], v[144:145] op_sel_hi:[1,0]
	s_nop 1
	v_mfma_f32_16x16x32_bf16 v[32:35], v[64:67], v[188:191], v[32:35]
	v_mul_f32_e64 v46, v46, v144
	v_mul_f32_e64 v47, v47, v144
	v_pk_mul_f32 v[44:45], v[44:45], v[144:145] op_sel_hi:[1,0]
	s_nop 4
	v_cvt_pk_bf16_f32 v56, v32, v33
	v_cvt_pk_bf16_f32 v57, v34, v35
	ds_write_b64 v135, v[56:57]
	v_mfma_f32_16x16x32_bf16 v[36:39], v[60:63], v[192:195], v[36:39]
	s_nop 1
	v_mfma_f32_16x16x32_bf16 v[36:39], v[64:67], v[196:199], v[36:39]
	s_nop 7
	v_cvt_pk_bf16_f32 v56, v36, v37
	v_cvt_pk_bf16_f32 v57, v38, v39
	ds_write_b64 v135, v[56:57] offset:4352
	v_mfma_f32_16x16x32_bf16 v[40:43], v[60:63], v[200:203], v[40:43]
	s_nop 1
	v_mfma_f32_16x16x32_bf16 v[40:43], v[64:67], v[204:207], v[40:43]
	s_nop 7
	v_cvt_pk_bf16_f32 v56, v40, v41
	v_cvt_pk_bf16_f32 v57, v42, v43
	ds_write_b64 v135, v[56:57] offset:8704
	v_mfma_f32_16x16x32_bf16 v[44:47], v[60:63], v[208:211], v[44:47]
	ds_read2_b64 v[56:59], v152 offset0:104 offset1:108
	s_waitcnt lgkmcnt(0)
	v_mfma_f32_16x16x32_bf16 v[44:47], v[64:67], v[56:59], v[44:47]
	s_nop 7
	v_cvt_pk_bf16_f32 v56, v44, v45
	v_cvt_pk_bf16_f32 v57, v46, v47
	ds_write_b64 v135, v[56:57] offset:13056
	s_waitcnt lgkmcnt(0)
	s_barrier
	s_cbranch_scc1 .LBB0_2541
	s_mov_b32 s27, s40
	s_waitcnt vmcnt(8)
	v_mov_b32_e32 v144, v153
	s_branch .LBB0_2548

.LBB0_2676:
	ds_read_b128 v[128:131], v151
	ds_read_b128 v[144:147], v151 offset:1024
	ds_read_b128 v[154:157], v151 offset:2048
	ds_read_b128 v[158:161], v151 offset:3072
	s_add_u32 s28, s26, 0x100
	s_addc_u32 s29, s27, 0
	s_cmp_eq_u32 s62, 60
	s_cselect_b32 s35, s17, s29
	s_cselect_b32 s34, s52, s28
	s_cselect_b32 s31, s15, s57
	s_cselect_b32 s30, s53, s56
	v_lshl_add_u64 v[194:195], s[26:27], 0, v[136:137]
	s_add_i32 m0, s4, 0xc000
	ds_read_b128 v[162:165], v152
	ds_read_b128 v[166:169], v152 offset:1024
	ds_read_b128 v[170:173], v152 offset:2048
	ds_read_b128 v[174:177], v152 offset:3072
	ds_read_b128 v[178:181], v152 offset:4096
	ds_read_b128 v[182:185], v152 offset:5120
	ds_read_b128 v[186:189], v152 offset:6144
	ds_read_b128 v[190:193], v152 offset:7168
	global_load_lds_dwordx4 v[194:195], off
	v_lshl_add_u64 v[194:195], s[26:27], 0, v[138:139]
	s_add_i32 m0, s4, 0xe000
	s_nop 0
	global_load_lds_dwordx4 v[194:195], off
	s_waitcnt lgkmcnt(8)
	s_barrier
	s_waitcnt lgkmcnt(0)
	s_setprio 1
	s_waitcnt lgkmcnt(0)
	v_mfma_f32_16x16x32_bf16 v[124:127], v[128:131], v[162:165], v[124:127]
	v_mfma_f32_16x16x32_bf16 v[92:95], v[154:157], v[162:165], v[92:95]
	v_mfma_f32_16x16x32_bf16 v[120:123], v[128:131], v[170:173], v[120:123]
	v_mfma_f32_16x16x32_bf16 v[88:91], v[154:157], v[170:173], v[88:91]
	v_mfma_f32_16x16x32_bf16 v[116:119], v[128:131], v[178:181], v[116:119]
	v_mfma_f32_16x16x32_bf16 v[84:87], v[154:157], v[178:181], v[84:87]
	v_mfma_f32_16x16x32_bf16 v[112:115], v[128:131], v[186:189], v[112:115]
	v_mfma_f32_16x16x32_bf16 v[80:83], v[154:157], v[186:189], v[80:83]
	v_mfma_f32_16x16x32_bf16 v[124:127], v[144:147], v[166:169], v[124:127]
	v_mfma_f32_16x16x32_bf16 v[92:95], v[158:161], v[166:169], v[92:95]
	v_mfma_f32_16x16x32_bf16 v[120:123], v[144:147], v[174:177], v[120:123]
	v_mfma_f32_16x16x32_bf16 v[88:91], v[158:161], v[174:177], v[88:91]
	v_mfma_f32_16x16x32_bf16 v[116:119], v[144:147], v[182:185], v[116:119]
	v_mfma_f32_16x16x32_bf16 v[84:87], v[158:161], v[182:185], v[84:87]
	v_mfma_f32_16x16x32_bf16 v[112:115], v[144:147], v[190:193], v[112:115]
	v_mfma_f32_16x16x32_bf16 v[80:83], v[158:161], v[190:193], v[80:83]
	s_setprio 0
	s_barrier
	s_add_i32 s26, s43, s3
	v_lshl_add_u64 v[210:211], s[30:31], 0, v[132:133]
	s_mov_b32 m0, s26
	ds_read_b128 v[194:197], v153
	ds_read_b128 v[198:201], v153 offset:1024
	ds_read_b128 v[202:205], v153 offset:2048
	ds_read_b128 v[206:209], v153 offset:3072
	global_load_lds_dwordx4 v[210:211], off
	v_lshl_add_u64 v[212:213], s[30:31], 0, v[134:135]
	s_add_i32 m0, s26, 0x2000
	s_nop 0
	global_load_lds_dwordx4 v[212:213], off
	s_barrier
	s_waitcnt lgkmcnt(0)
	s_setprio 1
	s_waitcnt lgkmcnt(0)
	v_mfma_f32_16x16x32_bf16 v[76:79], v[194:197], v[162:165], v[76:79]
	v_mfma_f32_16x16x32_bf16 v[48:51], v[202:205], v[162:165], v[48:51]
	v_mfma_f32_16x16x32_bf16 v[68:71], v[194:197], v[170:173], v[68:71]
	v_mfma_f32_16x16x32_bf16 v[40:43], v[202:205], v[170:173], v[40:43]
	v_mfma_f32_16x16x32_bf16 v[60:63], v[194:197], v[178:181], v[60:63]
	v_mfma_f32_16x16x32_bf16 v[36:39], v[202:205], v[178:181], v[36:39]
	v_mfma_f32_16x16x32_bf16 v[52:55], v[194:197], v[186:189], v[52:55]
	v_mfma_f32_16x16x32_bf16 v[28:31], v[202:205], v[186:189], v[28:31]
	v_mfma_f32_16x16x32_bf16 v[76:79], v[198:201], v[166:169], v[76:79]
	v_mfma_f32_16x16x32_bf16 v[48:51], v[206:209], v[166:169], v[48:51]
	v_mfma_f32_16x16x32_bf16 v[68:71], v[198:201], v[174:177], v[68:71]
	v_mfma_f32_16x16x32_bf16 v[40:43], v[206:209], v[174:177], v[40:43]
	v_mfma_f32_16x16x32_bf16 v[60:63], v[198:201], v[182:185], v[60:63]
	v_mfma_f32_16x16x32_bf16 v[36:39], v[206:209], v[182:185], v[36:39]
	v_mfma_f32_16x16x32_bf16 v[52:55], v[198:201], v[190:193], v[52:55]
	v_mfma_f32_16x16x32_bf16 v[28:31], v[206:209], v[190:193], v[28:31]
	s_setprio 0
	s_mov_b32 m0, s4
	v_lshl_add_u64 v[214:215], s[34:35], 0, v[132:133]
	s_barrier
	ds_read_b128 v[162:165], v152 offset:16384
	ds_read_b128 v[166:169], v152 offset:17408
	ds_read_b128 v[170:173], v152 offset:18432
	ds_read_b128 v[174:177], v152 offset:19456
	ds_read_b128 v[178:181], v152 offset:20480
	ds_read_b128 v[182:185], v152 offset:21504
	ds_read_b128 v[186:189], v152 offset:22528
	ds_read_b128 v[190:193], v152 offset:23552
	global_load_lds_dwordx4 v[214:215], off
	v_lshl_add_u64 v[216:217], s[34:35], 0, v[134:135]
	s_mov_b32 m0, s5
	s_nop 0
	global_load_lds_dwordx4 v[216:217], off
	s_barrier
	s_waitcnt lgkmcnt(0)
	s_setprio 1
	s_waitcnt lgkmcnt(0)
	v_mfma_f32_16x16x32_bf16 v[108:111], v[128:131], v[162:165], v[108:111]
	v_mfma_f32_16x16x32_bf16 v[72:75], v[154:157], v[162:165], v[72:75]
	v_mfma_f32_16x16x32_bf16 v[104:107], v[128:131], v[170:173], v[104:107]
	v_mfma_f32_16x16x32_bf16 v[64:67], v[154:157], v[170:173], v[64:67]
	v_mfma_f32_16x16x32_bf16 v[100:103], v[128:131], v[178:181], v[100:103]
	v_mfma_f32_16x16x32_bf16 v[56:59], v[154:157], v[178:181], v[56:59]
	v_mfma_f32_16x16x32_bf16 v[96:99], v[128:131], v[186:189], v[96:99]
	v_mfma_f32_16x16x32_bf16 v[44:47], v[154:157], v[186:189], v[44:47]
	v_mfma_f32_16x16x32_bf16 v[108:111], v[144:147], v[166:169], v[108:111]
	v_mfma_f32_16x16x32_bf16 v[72:75], v[158:161], v[166:169], v[72:75]
	v_mfma_f32_16x16x32_bf16 v[104:107], v[144:147], v[174:177], v[104:107]
	v_mfma_f32_16x16x32_bf16 v[64:67], v[158:161], v[174:177], v[64:67]
	v_mfma_f32_16x16x32_bf16 v[100:103], v[144:147], v[182:185], v[100:103]
	v_mfma_f32_16x16x32_bf16 v[56:59], v[158:161], v[182:185], v[56:59]
	v_mfma_f32_16x16x32_bf16 v[96:99], v[144:147], v[190:193], v[96:99]
	v_mfma_f32_16x16x32_bf16 v[44:47], v[158:161], v[190:193], v[44:47]
	s_setprio 0
	s_barrier
	s_add_u32 s26, s30, 0x100000
	s_addc_u32 s27, s31, 0
	s_add_i32 s63, s46, s3
	v_lshl_add_u64 v[128:129], s[26:27], 0, v[132:133]
	s_mov_b32 m0, s63
	s_nop 0
	global_load_lds_dwordx4 v[128:129], off
	v_lshl_add_u64 v[128:129], s[26:27], 0, v[134:135]
	s_add_i32 m0, s63, 0x2000
	s_nop 0
	global_load_lds_dwordx4 v[128:129], off
	s_waitcnt vmcnt(6)
	s_barrier
	s_setprio 1
	v_mfma_f32_16x16x32_bf16 v[32:35], v[194:197], v[162:165], v[32:35]
	v_mfma_f32_16x16x32_bf16 v[12:15], v[202:205], v[162:165], v[12:15]
	v_mfma_f32_16x16x32_bf16 v[24:27], v[194:197], v[170:173], v[24:27]
	v_mfma_f32_16x16x32_bf16 v[8:11], v[202:205], v[170:173], v[8:11]
	v_mfma_f32_16x16x32_bf16 v[20:23], v[194:197], v[178:181], v[20:23]
	v_mfma_f32_16x16x32_bf16 v[4:7], v[202:205], v[178:181], v[4:7]
	v_mfma_f32_16x16x32_bf16 v[16:19], v[194:197], v[186:189], v[16:19]
	v_mfma_f32_16x16x32_bf16 v[0:3], v[202:205], v[186:189], v[0:3]
	v_mfma_f32_16x16x32_bf16 v[32:35], v[198:201], v[166:169], v[32:35]
	v_mfma_f32_16x16x32_bf16 v[12:15], v[206:209], v[166:169], v[12:15]
	v_mfma_f32_16x16x32_bf16 v[24:27], v[198:201], v[174:177], v[24:27]
	v_mfma_f32_16x16x32_bf16 v[8:11], v[206:209], v[174:177], v[8:11]
	v_mfma_f32_16x16x32_bf16 v[20:23], v[198:201], v[182:185], v[20:23]
	v_mfma_f32_16x16x32_bf16 v[4:7], v[206:209], v[182:185], v[4:7]
	v_mfma_f32_16x16x32_bf16 v[16:19], v[198:201], v[190:193], v[16:19]
	v_mfma_f32_16x16x32_bf16 v[0:3], v[206:209], v[190:193], v[0:3]
	s_setprio 0
	s_add_i32 s63, 0, 0x18000
	v_add_u32_e32 v158, s63, v149
	s_barrier
	ds_read_b128 v[128:131], v158
	ds_read_b128 v[144:147], v158 offset:1024
	ds_read_b128 v[154:157], v158 offset:2048
	ds_read_b128 v[158:161], v158 offset:3072
	s_add_u32 s26, s34, 0x100000
	s_addc_u32 s27, s35, 0
	s_mov_b32 m0, s23
	v_lshl_add_u64 v[194:195], s[26:27], 0, v[132:133]
	ds_read_b128 v[162:165], v152 offset:32768
	ds_read_b128 v[166:169], v152 offset:33792
	ds_read_b128 v[170:173], v152 offset:34816
	ds_read_b128 v[174:177], v152 offset:35840
	ds_read_b128 v[178:181], v152 offset:36864
	ds_read_b128 v[182:185], v152 offset:37888
	ds_read_b128 v[186:189], v152 offset:38912
	ds_read_b128 v[190:193], v152 offset:39936
	global_load_lds_dwordx4 v[194:195], off
	v_lshl_add_u64 v[194:195], s[26:27], 0, v[134:135]
	s_mov_b32 m0, s36
	s_nop 0
	global_load_lds_dwordx4 v[194:195], off
	s_waitcnt lgkmcnt(8)
	s_barrier
	s_waitcnt lgkmcnt(0)
	s_setprio 1
	s_waitcnt lgkmcnt(0)
	v_mfma_f32_16x16x32_bf16 v[124:127], v[128:131], v[162:165], v[124:127]
	v_mfma_f32_16x16x32_bf16 v[92:95], v[154:157], v[162:165], v[92:95]
	v_mfma_f32_16x16x32_bf16 v[120:123], v[128:131], v[170:173], v[120:123]
	v_mfma_f32_16x16x32_bf16 v[88:91], v[154:157], v[170:173], v[88:91]
	v_mfma_f32_16x16x32_bf16 v[116:119], v[128:131], v[178:181], v[116:119]
	v_mfma_f32_16x16x32_bf16 v[84:87], v[154:157], v[178:181], v[84:87]
	v_mfma_f32_16x16x32_bf16 v[112:115], v[128:131], v[186:189], v[112:115]
	v_mfma_f32_16x16x32_bf16 v[80:83], v[154:157], v[186:189], v[80:83]
	v_mfma_f32_16x16x32_bf16 v[124:127], v[144:147], v[166:169], v[124:127]
	v_mfma_f32_16x16x32_bf16 v[92:95], v[158:161], v[166:169], v[92:95]
	v_mfma_f32_16x16x32_bf16 v[120:123], v[144:147], v[174:177], v[120:123]
	v_mfma_f32_16x16x32_bf16 v[88:91], v[158:161], v[174:177], v[88:91]
	v_mfma_f32_16x16x32_bf16 v[116:119], v[144:147], v[182:185], v[116:119]
	v_mfma_f32_16x16x32_bf16 v[84:87], v[158:161], v[182:185], v[84:87]
	v_mfma_f32_16x16x32_bf16 v[112:115], v[144:147], v[190:193], v[112:115]
	v_mfma_f32_16x16x32_bf16 v[80:83], v[158:161], v[190:193], v[80:83]
	s_setprio 0
	s_barrier
	s_add_i32 s34, 0, 0x1c000
	s_add_i32 s26, s63, s3
	v_add_u32_e32 v206, s34, v149
	v_lshl_add_u64 v[210:211], v[210:211], 0, s[12:13]
	s_mov_b32 m0, s26
	ds_read_b128 v[194:197], v206
	ds_read_b128 v[198:201], v206 offset:1024
	ds_read_b128 v[202:205], v206 offset:2048
	ds_read_b128 v[206:209], v206 offset:3072
	global_load_lds_dwordx4 v[210:211], off
	v_lshl_add_u64 v[210:211], v[212:213], 0, s[12:13]
	s_add_i32 m0, s26, 0x2000
	s_nop 0
	global_load_lds_dwordx4 v[210:211], off
	s_barrier
	s_waitcnt lgkmcnt(0)
	s_setprio 1
	s_waitcnt lgkmcnt(0)
	v_mfma_f32_16x16x32_bf16 v[76:79], v[194:197], v[162:165], v[76:79]
	v_mfma_f32_16x16x32_bf16 v[48:51], v[202:205], v[162:165], v[48:51]
	v_mfma_f32_16x16x32_bf16 v[68:71], v[194:197], v[170:173], v[68:71]
	v_mfma_f32_16x16x32_bf16 v[40:43], v[202:205], v[170:173], v[40:43]
	v_mfma_f32_16x16x32_bf16 v[60:63], v[194:197], v[178:181], v[60:63]
	v_mfma_f32_16x16x32_bf16 v[36:39], v[202:205], v[178:181], v[36:39]
	v_mfma_f32_16x16x32_bf16 v[52:55], v[194:197], v[186:189], v[52:55]
	v_mfma_f32_16x16x32_bf16 v[28:31], v[202:205], v[186:189], v[28:31]
	v_mfma_f32_16x16x32_bf16 v[76:79], v[198:201], v[166:169], v[76:79]
	v_mfma_f32_16x16x32_bf16 v[48:51], v[206:209], v[166:169], v[48:51]
	v_mfma_f32_16x16x32_bf16 v[68:71], v[198:201], v[174:177], v[68:71]
	v_mfma_f32_16x16x32_bf16 v[40:43], v[206:209], v[174:177], v[40:43]
	v_mfma_f32_16x16x32_bf16 v[60:63], v[198:201], v[182:185], v[60:63]
	v_mfma_f32_16x16x32_bf16 v[36:39], v[206:209], v[182:185], v[36:39]
	v_mfma_f32_16x16x32_bf16 v[52:55], v[198:201], v[190:193], v[52:55]
	v_mfma_f32_16x16x32_bf16 v[28:31], v[206:209], v[190:193], v[28:31]
	s_setprio 0
	s_mov_b32 m0, s38
	v_lshl_add_u64 v[210:211], v[214:215], 0, s[12:13]
	s_barrier
	ds_read_b128 v[162:165], v152 offset:49152
	ds_read_b128 v[166:169], v152 offset:50176
	ds_read_b128 v[170:173], v152 offset:51200
	ds_read_b128 v[174:177], v152 offset:52224
	ds_read_b128 v[178:181], v152 offset:53248
	ds_read_b128 v[182:185], v152 offset:54272
	ds_read_b128 v[186:189], v152 offset:55296
	ds_read_b128 v[190:193], v152 offset:56320
	global_load_lds_dwordx4 v[210:211], off
	v_lshl_add_u64 v[210:211], v[216:217], 0, s[12:13]
	s_mov_b32 m0, s39
	s_nop 0
	global_load_lds_dwordx4 v[210:211], off
	s_barrier
	s_waitcnt lgkmcnt(0)
	s_setprio 1
	s_waitcnt lgkmcnt(0)
	v_mfma_f32_16x16x32_bf16 v[108:111], v[128:131], v[162:165], v[108:111]
	v_mfma_f32_16x16x32_bf16 v[72:75], v[154:157], v[162:165], v[72:75]
	v_mfma_f32_16x16x32_bf16 v[104:107], v[128:131], v[170:173], v[104:107]
	v_mfma_f32_16x16x32_bf16 v[64:67], v[154:157], v[170:173], v[64:67]
	v_mfma_f32_16x16x32_bf16 v[100:103], v[128:131], v[178:181], v[100:103]
	v_mfma_f32_16x16x32_bf16 v[56:59], v[154:157], v[178:181], v[56:59]
	v_mfma_f32_16x16x32_bf16 v[96:99], v[128:131], v[186:189], v[96:99]
	v_mfma_f32_16x16x32_bf16 v[44:47], v[154:157], v[186:189], v[44:47]
	v_mfma_f32_16x16x32_bf16 v[108:111], v[144:147], v[166:169], v[108:111]
	v_mfma_f32_16x16x32_bf16 v[72:75], v[158:161], v[166:169], v[72:75]
	v_mfma_f32_16x16x32_bf16 v[104:107], v[144:147], v[174:177], v[104:107]
	v_mfma_f32_16x16x32_bf16 v[64:67], v[158:161], v[174:177], v[64:67]
	v_mfma_f32_16x16x32_bf16 v[100:103], v[144:147], v[182:185], v[100:103]
	v_mfma_f32_16x16x32_bf16 v[56:59], v[158:161], v[182:185], v[56:59]
	v_mfma_f32_16x16x32_bf16 v[96:99], v[144:147], v[190:193], v[96:99]
	v_mfma_f32_16x16x32_bf16 v[44:47], v[158:161], v[190:193], v[44:47]
	s_setprio 0
	s_barrier
	s_add_u32 s26, s30, 0x100080
	s_addc_u32 s27, s31, 0
	s_add_i32 s30, s34, s3
	v_lshl_add_u64 v[128:129], s[26:27], 0, v[132:133]
	s_mov_b32 m0, s30
	s_nop 0
	global_load_lds_dwordx4 v[128:129], off
	v_lshl_add_u64 v[128:129], s[26:27], 0, v[134:135]
	s_add_i32 m0, s30, 0x2000
	s_nop 0
	global_load_lds_dwordx4 v[128:129], off
	s_waitcnt vmcnt(6)
	s_barrier
	s_setprio 1
	v_mfma_f32_16x16x32_bf16 v[32:35], v[194:197], v[162:165], v[32:35]
	v_mfma_f32_16x16x32_bf16 v[12:15], v[202:205], v[162:165], v[12:15]
	v_mfma_f32_16x16x32_bf16 v[24:27], v[194:197], v[170:173], v[24:27]
	v_mfma_f32_16x16x32_bf16 v[8:11], v[202:205], v[170:173], v[8:11]
	v_mfma_f32_16x16x32_bf16 v[20:23], v[194:197], v[178:181], v[20:23]
	v_mfma_f32_16x16x32_bf16 v[4:7], v[202:205], v[178:181], v[4:7]
	v_mfma_f32_16x16x32_bf16 v[16:19], v[194:197], v[186:189], v[16:19]
	v_mfma_f32_16x16x32_bf16 v[0:3], v[202:205], v[186:189], v[0:3]
	v_mfma_f32_16x16x32_bf16 v[32:35], v[198:201], v[166:169], v[32:35]
	v_mfma_f32_16x16x32_bf16 v[12:15], v[206:209], v[166:169], v[12:15]
	v_mfma_f32_16x16x32_bf16 v[24:27], v[198:201], v[174:177], v[24:27]
	v_mfma_f32_16x16x32_bf16 v[8:11], v[206:209], v[174:177], v[8:11]
	v_mfma_f32_16x16x32_bf16 v[20:23], v[198:201], v[182:185], v[20:23]
	v_mfma_f32_16x16x32_bf16 v[4:7], v[206:209], v[182:185], v[4:7]
	v_mfma_f32_16x16x32_bf16 v[16:19], v[198:201], v[190:193], v[16:19]
	v_mfma_f32_16x16x32_bf16 v[0:3], v[206:209], v[190:193], v[0:3]
	s_setprio 0
	s_add_i32 s62, s62, 2
	s_add_u32 s56, s56, 0x100
	s_addc_u32 s57, s57, 0
	s_cmp_gt_u32 s62, 61
	s_mov_b64 s[26:27], s[28:29]
	s_barrier
	s_cbranch_scc0 .LBB0_2676
	s_cmp_lt_u32 s22, 32
	s_movk_i32 s15, 0x3000
	s_cselect_b32 s15, s15, 0x6000
	s_cmp_gt_i32 s22, 15
	v_lshl_add_u32 v158, s22, 8, v148
	s_cselect_b32 s15, s15, 0
	v_readlane_b32 s48, v240, 22
	v_lshl_or_b32 v128, s47, 8, v150
	s_lshl_b32 s15, s15, 2
	v_ashrrev_i32_e32 v159, 31, v158
	v_readlane_b32 s49, v240, 23
	v_readlane_b32 s50, v240, 24
	v_readlane_b32 s51, v240, 25
	v_readlane_b32 s52, v240, 26
	v_readlane_b32 s53, v240, 27
	s_add_u32 s26, s41, s15
	v_ashrrev_i32_e32 v129, 31, v128
	v_lshlrev_b64 v[146:147], 13, v[158:159]
	v_readlane_b32 s54, v240, 28
	v_readlane_b32 s55, v240, 29
	s_mov_b64 s[44:45], s[48:49]
	s_mov_b64 s[48:49], s[52:53]
	s_addc_u32 s27, s42, 0
	v_lshlrev_b64 v[160:161], 2, v[128:129]
	v_lshl_add_u64 v[146:147], s[48:49], 0, v[146:147]
	v_lshl_add_u64 v[144:145], s[26:27], 0, v[160:161]
	v_lshl_add_u64 v[146:147], v[146:147], 0, v[160:161]
	s_mov_b32 s15, 0x100000
	s_mov_b64 s[26:27], 0x100000
	v_readlane_b32 s58, v240, 32
	v_readlane_b32 s59, v240, 33
	v_readlane_b32 s62, v240, 36
	v_readlane_b32 s63, v240, 37
	s_mov_b32 s47, s14
	s_mov_b32 s22, s16
	s_mov_b64 s[28:29], s[20:21]
	v_readlane_b32 s56, v240, 30
	v_readlane_b32 s57, v240, 31
	v_readlane_b32 s60, v240, 34
	v_readlane_b32 s61, v240, 35
	s_mov_b64 s[50:51], s[54:55]
	v_or_b32_e32 v162, 16, v158
	v_ashrrev_i32_e32 v163, 31, v162
	v_lshlrev_b64 v[164:165], 13, v[162:163]
	v_lshl_add_u64 v[162:163], s[48:49], 0, v[164:165]
	v_lshl_add_u64 v[164:165], v[162:163], 0, v[160:161]
	v_or_b32_e32 v162, 32, v158
	v_ashrrev_i32_e32 v163, 31, v162
	v_lshlrev_b64 v[166:167], 13, v[162:163]
	v_lshl_add_u64 v[162:163], s[48:49], 0, v[166:167]
	v_lshl_add_u64 v[166:167], v[162:163], 0, v[160:161]
	v_or_b32_e32 v162, 48, v158
	v_ashrrev_i32_e32 v163, 31, v162
	v_lshlrev_b64 v[168:169], 13, v[162:163]
	v_lshl_add_u64 v[162:163], s[48:49], 0, v[168:169]
	v_lshl_add_u64 v[168:169], v[162:163], 0, v[160:161]
	v_add_co_u32_e32 v162, vcc, s15, v146
	s_mov_b32 s15, 0x120000
	s_nop 0
	v_addc_co_u32_e32 v163, vcc, 0, v147, vcc
	v_lshl_add_u64 v[170:171], v[146:147], 0, s[26:27]
	s_mov_b64 s[26:27], 0x120000
	v_add_co_u32_e32 v172, vcc, s15, v146
	s_mov_b32 s15, 0x140000
	s_nop 0
	v_addc_co_u32_e32 v173, vcc, 0, v147, vcc
	v_lshl_add_u64 v[174:175], v[146:147], 0, s[26:27]
	s_mov_b64 s[26:27], 0x140000
	v_add_co_u32_e32 v176, vcc, s15, v146
	s_mov_b32 s15, 0x160000
	s_nop 0
	v_addc_co_u32_e32 v177, vcc, 0, v147, vcc
	v_lshl_add_u64 v[178:179], v[146:147], 0, s[26:27]
	s_mov_b64 s[26:27], 0x160000
	v_add_co_u32_e32 v180, vcc, s15, v146
	v_lshl_add_u64 v[182:183], v[146:147], 0, s[26:27]
	s_nop 0
	v_addc_co_u32_e32 v181, vcc, 0, v147, vcc
	s_and_b64 vcc, exec, s[10:11]
	s_mov_b64 s[26:27], s[18:19]
	global_load_dwordx4 v[184:187], v[144:145], off
	global_load_dwordx4 v[188:191], v[146:147], off
	v_pk_add_f32 v[126:127], v[126:127], 0 op_sel_hi:[1,0]
	v_pk_add_f32 v[124:125], v[124:125], 0 op_sel_hi:[1,0]
	v_pk_add_f32 v[122:123], v[122:123], 0 op_sel_hi:[1,0]
	v_pk_add_f32 v[120:121], v[120:121], 0 op_sel_hi:[1,0]
	v_pk_add_f32 v[118:119], v[118:119], 0 op_sel_hi:[1,0]
	v_pk_add_f32 v[116:117], v[116:117], 0 op_sel_hi:[1,0]
	v_pk_add_f32 v[114:115], v[114:115], 0 op_sel_hi:[1,0]
	v_pk_add_f32 v[112:113], v[112:113], 0 op_sel_hi:[1,0]
	v_pk_add_f32 v[110:111], v[110:111], 0 op_sel_hi:[1,0]
	v_pk_add_f32 v[108:109], v[108:109], 0 op_sel_hi:[1,0]
	v_pk_add_f32 v[106:107], v[106:107], 0 op_sel_hi:[1,0]
	v_pk_add_f32 v[104:105], v[104:105], 0 op_sel_hi:[1,0]
	v_pk_add_f32 v[102:103], v[102:103], 0 op_sel_hi:[1,0]
	v_pk_add_f32 v[100:101], v[100:101], 0 op_sel_hi:[1,0]
	v_pk_add_f32 v[98:99], v[98:99], 0 op_sel_hi:[1,0]
	v_pk_add_f32 v[96:97], v[96:97], 0 op_sel_hi:[1,0]
	v_pk_add_f32 v[94:95], v[94:95], 0 op_sel_hi:[1,0]
	v_pk_add_f32 v[92:93], v[92:93], 0 op_sel_hi:[1,0]
	v_pk_add_f32 v[90:91], v[90:91], 0 op_sel_hi:[1,0]
	v_pk_add_f32 v[88:89], v[88:89], 0 op_sel_hi:[1,0]
	v_pk_add_f32 v[86:87], v[86:87], 0 op_sel_hi:[1,0]
	v_pk_add_f32 v[84:85], v[84:85], 0 op_sel_hi:[1,0]
	v_pk_add_f32 v[82:83], v[82:83], 0 op_sel_hi:[1,0]
	v_pk_add_f32 v[80:81], v[80:81], 0 op_sel_hi:[1,0]
	v_pk_add_f32 v[74:75], v[74:75], 0 op_sel_hi:[1,0]
	v_pk_add_f32 v[72:73], v[72:73], 0 op_sel_hi:[1,0]
	v_pk_add_f32 v[66:67], v[66:67], 0 op_sel_hi:[1,0]
	v_pk_add_f32 v[64:65], v[64:65], 0 op_sel_hi:[1,0]
	v_pk_add_f32 v[58:59], v[58:59], 0 op_sel_hi:[1,0]
	v_pk_add_f32 v[56:57], v[56:57], 0 op_sel_hi:[1,0]
	v_pk_add_f32 v[46:47], v[46:47], 0 op_sel_hi:[1,0]
	v_pk_add_f32 v[44:45], v[44:45], 0 op_sel_hi:[1,0]
	v_pk_add_f32 v[62:63], v[62:63], 0 op_sel_hi:[1,0]
	v_pk_add_f32 v[60:61], v[60:61], 0 op_sel_hi:[1,0]
	v_pk_add_f32 v[54:55], v[54:55], 0 op_sel_hi:[1,0]
	v_pk_add_f32 v[52:53], v[52:53], 0 op_sel_hi:[1,0]
	v_pk_add_f32 v[34:35], v[34:35], 0 op_sel_hi:[1,0]
	v_pk_add_f32 v[32:33], v[32:33], 0 op_sel_hi:[1,0]
	v_pk_add_f32 v[26:27], v[26:27], 0 op_sel_hi:[1,0]
	v_pk_add_f32 v[24:25], v[24:25], 0 op_sel_hi:[1,0]
	v_pk_add_f32 v[22:23], v[22:23], 0 op_sel_hi:[1,0]
	v_pk_add_f32 v[20:21], v[20:21], 0 op_sel_hi:[1,0]
	v_pk_add_f32 v[18:19], v[18:19], 0 op_sel_hi:[1,0]
	v_pk_add_f32 v[16:17], v[16:17], 0 op_sel_hi:[1,0]
	v_pk_add_f32 v[14:15], v[14:15], 0 op_sel_hi:[1,0]
	v_pk_add_f32 v[12:13], v[12:13], 0 op_sel_hi:[1,0]
	v_pk_add_f32 v[10:11], v[10:11], 0 op_sel_hi:[1,0]
	v_pk_add_f32 v[8:9], v[8:9], 0 op_sel_hi:[1,0]
	v_pk_add_f32 v[6:7], v[6:7], 0 op_sel_hi:[1,0]
	v_pk_add_f32 v[4:5], v[4:5], 0 op_sel_hi:[1,0]
	v_pk_add_f32 v[2:3], v[2:3], 0 op_sel_hi:[1,0]
	v_pk_add_f32 v[0:1], v[0:1], 0 op_sel_hi:[1,0]
	s_waitcnt vmcnt(0)
	v_pk_fma_f32 v[126:127], v[126:127], v[186:187], v[190:191]
	v_pk_fma_f32 v[124:125], v[124:125], v[184:185], v[188:189]
	global_store_dwordx4 v[146:147], v[124:127], off
	global_load_dwordx4 v[188:191], v[164:165], off
	global_load_dwordx4 v[192:195], v[166:167], off
	global_load_dwordx4 v[196:199], v[168:169], off
	global_load_dwordx4 v[200:203], v[162:163], off
	global_load_dwordx4 v[204:207], v[172:173], off
	global_load_dwordx4 v[208:211], v[176:177], off
	global_load_dwordx4 v[212:215], v[180:181], off
	global_load_dwordx4 v[216:219], v[144:145], off offset:64
	global_load_dwordx4 v[220:223], v[146:147], off offset:64
	global_load_dwordx4 v[224:227], v[164:165], off offset:64
	global_load_dwordx4 v[228:231], v[166:167], off offset:64
	global_load_dwordx4 v[232:235], v[168:169], off offset:64
	s_waitcnt vmcnt(11)
	v_pk_fma_f32 v[122:123], v[122:123], v[186:187], v[190:191]
	v_pk_fma_f32 v[120:121], v[120:121], v[184:185], v[188:189]
	global_store_dwordx4 v[164:165], v[120:123], off
	global_load_dwordx4 v[188:191], v[170:171], off offset:64
	s_waitcnt vmcnt(12)
	v_pk_fma_f32 v[118:119], v[118:119], v[186:187], v[194:195]
	v_pk_fma_f32 v[116:117], v[116:117], v[184:185], v[192:193]
	global_store_dwordx4 v[166:167], v[116:119], off
	global_load_dwordx4 v[192:195], v[174:175], off offset:64
	s_waitcnt vmcnt(13)
	v_pk_fma_f32 v[114:115], v[114:115], v[186:187], v[198:199]
	v_pk_fma_f32 v[112:113], v[112:113], v[184:185], v[196:197]
	global_store_dwordx4 v[168:169], v[112:115], off
	global_load_dwordx4 v[196:199], v[178:179], off offset:64
	s_waitcnt vmcnt(14)
	v_pk_fma_f32 v[110:111], v[110:111], v[186:187], v[202:203]
	v_pk_fma_f32 v[108:109], v[108:109], v[184:185], v[200:201]
	global_store_dwordx4 v[162:163], v[108:111], off
	global_load_dwordx4 v[200:203], v[182:183], off offset:64
	s_waitcnt vmcnt(15)
	v_pk_fma_f32 v[106:107], v[106:107], v[186:187], v[206:207]
	v_pk_fma_f32 v[104:105], v[104:105], v[184:185], v[204:205]
	global_store_dwordx4 v[172:173], v[104:107], off
	global_load_dwordx4 v[204:207], v[144:145], off offset:512
	s_waitcnt vmcnt(16)
	v_pk_fma_f32 v[102:103], v[102:103], v[186:187], v[210:211]
	v_pk_fma_f32 v[100:101], v[100:101], v[184:185], v[208:209]
	global_store_dwordx4 v[176:177], v[100:103], off
	global_load_dwordx4 v[208:211], v[146:147], off offset:512
	s_waitcnt vmcnt(17)
	v_pk_fma_f32 v[98:99], v[98:99], v[186:187], v[214:215]
	v_pk_fma_f32 v[96:97], v[96:97], v[184:185], v[212:213]
	global_store_dwordx4 v[180:181], v[96:99], off
	global_load_dwordx4 v[184:187], v[164:165], off offset:512
	s_waitcnt vmcnt(17)
	v_pk_fma_f32 v[94:95], v[94:95], v[218:219], v[222:223]
	v_pk_fma_f32 v[92:93], v[92:93], v[216:217], v[220:221]
	global_store_dwordx4 v[146:147], v[92:95], off offset:64
	global_load_dwordx4 v[212:215], v[166:167], off offset:512
	global_load_dwordx4 v[220:223], v[168:169], off offset:512
	s_waitcnt vmcnt(19)
	v_pk_fma_f32 v[90:91], v[90:91], v[218:219], v[226:227]
	v_pk_fma_f32 v[88:89], v[88:89], v[216:217], v[224:225]
	global_store_dwordx4 v[164:165], v[88:91], off offset:64
	global_load_dwordx4 v[224:227], v[170:171], off offset:512
	s_waitcnt vmcnt(20)
	v_pk_fma_f32 v[86:87], v[86:87], v[218:219], v[230:231]
	v_pk_fma_f32 v[84:85], v[84:85], v[216:217], v[228:229]
	global_store_dwordx4 v[166:167], v[84:87], off offset:64
	global_load_dwordx4 v[228:231], v[174:175], off offset:512
	s_waitcnt vmcnt(21)
	v_pk_fma_f32 v[82:83], v[82:83], v[218:219], v[234:235]
	v_pk_fma_f32 v[80:81], v[80:81], v[216:217], v[232:233]
	global_store_dwordx4 v[168:169], v[80:83], off offset:64
	global_load_dwordx4 v[232:235], v[178:179], off offset:512
	s_waitcnt vmcnt(21)
	v_pk_fma_f32 v[74:75], v[74:75], v[218:219], v[190:191]
	v_pk_fma_f32 v[72:73], v[72:73], v[216:217], v[188:189]
	global_store_dwordx4 v[170:171], v[72:75], off offset:64
	global_load_dwordx4 v[188:191], v[182:183], off offset:512
	s_waitcnt vmcnt(21)
	v_pk_fma_f32 v[66:67], v[66:67], v[218:219], v[194:195]
	v_pk_fma_f32 v[64:65], v[64:65], v[216:217], v[192:193]
	global_store_dwordx4 v[174:175], v[64:67], off offset:64
	global_load_dwordx4 v[192:195], v[144:145], off offset:576
	s_waitcnt vmcnt(21)
	v_pk_fma_f32 v[58:59], v[58:59], v[218:219], v[198:199]
	v_pk_fma_f32 v[56:57], v[56:57], v[216:217], v[196:197]
	global_store_dwordx4 v[178:179], v[56:59], off offset:64
	global_load_dwordx4 v[196:199], v[146:147], off offset:576
	v_pk_add_f32 v[64:65], v[78:79], 0 op_sel_hi:[1,0]
	v_pk_add_f32 v[66:67], v[76:77], 0 op_sel_hi:[1,0]
	s_waitcnt vmcnt(21)
	v_pk_fma_f32 v[46:47], v[46:47], v[218:219], v[202:203]
	v_pk_fma_f32 v[44:45], v[44:45], v[216:217], v[200:201]
	global_store_dwordx4 v[182:183], v[44:47], off offset:64
	global_load_dwordx4 v[200:203], v[164:165], off offset:576
	s_waitcnt vmcnt(19)
	v_pk_fma_f32 v[58:59], v[64:65], v[206:207], v[210:211]
	v_pk_fma_f32 v[56:57], v[66:67], v[204:205], v[208:209]
	global_store_dwordx4 v[146:147], v[56:59], off offset:512
	global_load_dwordx4 v[208:211], v[166:167], off offset:576
	global_load_dwordx4 v[216:219], v[168:169], off offset:576
	v_pk_add_f32 v[64:65], v[70:71], 0 op_sel_hi:[1,0]
	v_pk_add_f32 v[66:67], v[68:69], 0 op_sel_hi:[1,0]
	s_waitcnt vmcnt(20)
	v_pk_fma_f32 v[58:59], v[64:65], v[206:207], v[186:187]
	v_pk_fma_f32 v[56:57], v[66:67], v[204:205], v[184:185]
	global_store_dwordx4 v[164:165], v[56:59], off offset:512
	global_load_dwordx4 v[184:187], v[170:171], off offset:576
	s_waitcnt vmcnt(20)
	v_pk_fma_f32 v[58:59], v[62:63], v[206:207], v[214:215]
	v_pk_fma_f32 v[56:57], v[60:61], v[204:205], v[212:213]
	global_store_dwordx4 v[166:167], v[56:59], off offset:512
	global_load_dwordx4 v[212:215], v[174:175], off offset:576
	s_waitcnt vmcnt(21)
	v_pk_fma_f32 v[54:55], v[54:55], v[206:207], v[222:223]
	v_pk_fma_f32 v[52:53], v[52:53], v[204:205], v[220:221]
	global_store_dwordx4 v[168:169], v[52:55], off offset:512
	global_load_dwordx4 v[220:223], v[178:179], off offset:576
	s_waitcnt vmcnt(21)
	v_pk_fma_f32 v[34:35], v[34:35], v[206:207], v[226:227]
	v_pk_fma_f32 v[32:33], v[32:33], v[204:205], v[224:225]
	global_store_dwordx4 v[170:171], v[32:35], off offset:512
	global_load_dwordx4 v[224:227], v[182:183], off offset:576
	s_waitcnt vmcnt(21)
	v_pk_fma_f32 v[26:27], v[26:27], v[206:207], v[230:231]
	v_pk_fma_f32 v[24:25], v[24:25], v[204:205], v[228:229]
	global_store_dwordx4 v[174:175], v[24:27], off offset:512
	s_waitcnt vmcnt(20)
	v_pk_fma_f32 v[22:23], v[22:23], v[206:207], v[234:235]
	v_pk_fma_f32 v[20:21], v[20:21], v[204:205], v[232:233]
	global_store_dwordx4 v[178:179], v[20:23], off offset:512
	v_pk_add_f32 v[24:25], v[50:51], 0 op_sel_hi:[1,0]
	v_pk_add_f32 v[26:27], v[48:49], 0 op_sel_hi:[1,0]
	s_waitcnt vmcnt(19)
	v_pk_fma_f32 v[18:19], v[18:19], v[206:207], v[190:191]
	v_pk_fma_f32 v[16:17], v[16:17], v[204:205], v[188:189]
	global_store_dwordx4 v[182:183], v[16:19], off offset:512
	s_waitcnt vmcnt(16)
	v_pk_fma_f32 v[22:23], v[24:25], v[194:195], v[198:199]
	v_pk_fma_f32 v[20:21], v[26:27], v[192:193], v[196:197]
	global_store_dwordx4 v[146:147], v[20:23], off offset:576
	v_pk_add_f32 v[24:25], v[42:43], 0 op_sel_hi:[1,0]
	v_pk_add_f32 v[26:27], v[40:41], 0 op_sel_hi:[1,0]
	s_waitcnt vmcnt(15)
	v_pk_fma_f32 v[22:23], v[24:25], v[194:195], v[202:203]
	v_pk_fma_f32 v[20:21], v[26:27], v[192:193], v[200:201]
	global_store_dwordx4 v[164:165], v[20:23], off offset:576
	v_pk_add_f32 v[24:25], v[38:39], 0 op_sel_hi:[1,0]
	v_pk_add_f32 v[26:27], v[36:37], 0 op_sel_hi:[1,0]
	s_waitcnt vmcnt(14)
	v_pk_fma_f32 v[22:23], v[24:25], v[194:195], v[210:211]
	v_pk_fma_f32 v[20:21], v[26:27], v[192:193], v[208:209]
	global_store_dwordx4 v[166:167], v[20:23], off offset:576
	v_pk_add_f32 v[24:25], v[30:31], 0 op_sel_hi:[1,0]
	v_pk_add_f32 v[26:27], v[28:29], 0 op_sel_hi:[1,0]
	s_waitcnt vmcnt(14)
	v_pk_fma_f32 v[22:23], v[24:25], v[194:195], v[218:219]
	v_pk_fma_f32 v[20:21], v[26:27], v[192:193], v[216:217]
	global_store_dwordx4 v[168:169], v[20:23], off offset:576
	s_waitcnt vmcnt(13)
	v_pk_fma_f32 v[14:15], v[14:15], v[194:195], v[186:187]
	v_pk_fma_f32 v[12:13], v[12:13], v[192:193], v[184:185]
	global_store_dwordx4 v[170:171], v[12:15], off offset:576
	s_waitcnt vmcnt(12)
	v_pk_fma_f32 v[10:11], v[10:11], v[194:195], v[214:215]
	v_pk_fma_f32 v[8:9], v[8:9], v[192:193], v[212:213]
	global_store_dwordx4 v[174:175], v[8:11], off offset:576
	s_waitcnt vmcnt(11)
	v_pk_fma_f32 v[6:7], v[6:7], v[194:195], v[222:223]
	v_pk_fma_f32 v[4:5], v[4:5], v[192:193], v[220:221]
	global_store_dwordx4 v[178:179], v[4:7], off offset:576
	s_waitcnt vmcnt(10)
	v_pk_fma_f32 v[2:3], v[2:3], v[194:195], v[226:227]
	v_pk_fma_f32 v[0:1], v[0:1], v[192:193], v[224:225]
	global_store_dwordx4 v[182:183], v[0:3], off offset:576
	s_cbranch_vccz .LBB0_2669
	s_waitcnt vmcnt(0)
	s_mov_b64 s[54:55], s[58:59]
	s_mov_b64 s[58:59], s[62:63]
	s_cmpk_gt_u32 s1, 0xff
	s_cbranch_scc1 .LBB0_2680
	s_barrier

.LBB0_2911:
	ds_read_b128 v[128:131], v151
	ds_read_b128 v[144:147], v151 offset:1024
	ds_read_b128 v[154:157], v151 offset:2048
	ds_read_b128 v[158:161], v151 offset:3072
	s_add_u32 s18, s16, 0x100
	s_addc_u32 s19, s17, 0
	s_cmpk_eq_i32 s46, 0x54
	s_cselect_b32 s23, s11, s19
	s_cselect_b32 s22, s10, s18
	s_cselect_b32 s21, s13, s43
	s_cselect_b32 s20, s12, s42
	v_lshl_add_u64 v[194:195], s[16:17], 0, v[136:137]
	s_add_i32 m0, s4, 0xc000
	ds_read_b128 v[162:165], v152
	ds_read_b128 v[166:169], v152 offset:1024
	ds_read_b128 v[170:173], v152 offset:2048
	ds_read_b128 v[174:177], v152 offset:3072
	ds_read_b128 v[178:181], v152 offset:4096
	ds_read_b128 v[182:185], v152 offset:5120
	ds_read_b128 v[186:189], v152 offset:6144
	ds_read_b128 v[190:193], v152 offset:7168
	global_load_lds_dwordx4 v[194:195], off
	v_lshl_add_u64 v[194:195], s[16:17], 0, v[138:139]
	s_add_i32 m0, s4, 0xe000
	s_nop 0
	global_load_lds_dwordx4 v[194:195], off
	s_waitcnt lgkmcnt(8)
	s_barrier
	s_waitcnt lgkmcnt(0)
	s_setprio 1
	s_waitcnt lgkmcnt(0)
	v_mfma_f32_16x16x32_bf16 v[124:127], v[128:131], v[162:165], v[124:127]
	v_mfma_f32_16x16x32_bf16 v[92:95], v[154:157], v[162:165], v[92:95]
	v_mfma_f32_16x16x32_bf16 v[120:123], v[128:131], v[170:173], v[120:123]
	v_mfma_f32_16x16x32_bf16 v[88:91], v[154:157], v[170:173], v[88:91]
	v_mfma_f32_16x16x32_bf16 v[116:119], v[128:131], v[178:181], v[116:119]
	v_mfma_f32_16x16x32_bf16 v[84:87], v[154:157], v[178:181], v[84:87]
	v_mfma_f32_16x16x32_bf16 v[112:115], v[128:131], v[186:189], v[112:115]
	v_mfma_f32_16x16x32_bf16 v[80:83], v[154:157], v[186:189], v[80:83]
	v_mfma_f32_16x16x32_bf16 v[124:127], v[144:147], v[166:169], v[124:127]
	v_mfma_f32_16x16x32_bf16 v[92:95], v[158:161], v[166:169], v[92:95]
	v_mfma_f32_16x16x32_bf16 v[120:123], v[144:147], v[174:177], v[120:123]
	v_mfma_f32_16x16x32_bf16 v[88:91], v[158:161], v[174:177], v[88:91]
	v_mfma_f32_16x16x32_bf16 v[116:119], v[144:147], v[182:185], v[116:119]
	v_mfma_f32_16x16x32_bf16 v[84:87], v[158:161], v[182:185], v[84:87]
	v_mfma_f32_16x16x32_bf16 v[112:115], v[144:147], v[190:193], v[112:115]
	v_mfma_f32_16x16x32_bf16 v[80:83], v[158:161], v[190:193], v[80:83]
	s_setprio 0
	s_barrier
	s_add_i32 s16, s36, s3
	v_lshl_add_u64 v[210:211], s[20:21], 0, v[132:133]
	s_mov_b32 m0, s16
	ds_read_b128 v[194:197], v153
	ds_read_b128 v[198:201], v153 offset:1024
	ds_read_b128 v[202:205], v153 offset:2048
	ds_read_b128 v[206:209], v153 offset:3072
	global_load_lds_dwordx4 v[210:211], off
	v_lshl_add_u64 v[212:213], s[20:21], 0, v[134:135]
	s_add_i32 m0, s16, 0x2000
	s_nop 0
	global_load_lds_dwordx4 v[212:213], off
	s_barrier
	s_waitcnt lgkmcnt(0)
	s_setprio 1
	s_waitcnt lgkmcnt(0)
	v_mfma_f32_16x16x32_bf16 v[76:79], v[194:197], v[162:165], v[76:79]
	v_mfma_f32_16x16x32_bf16 v[48:51], v[202:205], v[162:165], v[48:51]
	v_mfma_f32_16x16x32_bf16 v[68:71], v[194:197], v[170:173], v[68:71]
	v_mfma_f32_16x16x32_bf16 v[40:43], v[202:205], v[170:173], v[40:43]
	v_mfma_f32_16x16x32_bf16 v[60:63], v[194:197], v[178:181], v[60:63]
	v_mfma_f32_16x16x32_bf16 v[36:39], v[202:205], v[178:181], v[36:39]
	v_mfma_f32_16x16x32_bf16 v[52:55], v[194:197], v[186:189], v[52:55]
	v_mfma_f32_16x16x32_bf16 v[28:31], v[202:205], v[186:189], v[28:31]
	v_mfma_f32_16x16x32_bf16 v[76:79], v[198:201], v[166:169], v[76:79]
	v_mfma_f32_16x16x32_bf16 v[48:51], v[206:209], v[166:169], v[48:51]
	v_mfma_f32_16x16x32_bf16 v[68:71], v[198:201], v[174:177], v[68:71]
	v_mfma_f32_16x16x32_bf16 v[40:43], v[206:209], v[174:177], v[40:43]
	v_mfma_f32_16x16x32_bf16 v[60:63], v[198:201], v[182:185], v[60:63]
	v_mfma_f32_16x16x32_bf16 v[36:39], v[206:209], v[182:185], v[36:39]
	v_mfma_f32_16x16x32_bf16 v[52:55], v[198:201], v[190:193], v[52:55]
	v_mfma_f32_16x16x32_bf16 v[28:31], v[206:209], v[190:193], v[28:31]
	s_setprio 0
	s_mov_b32 m0, s4
	v_lshl_add_u64 v[214:215], s[22:23], 0, v[132:133]
	s_barrier
	ds_read_b128 v[162:165], v152 offset:16384
	ds_read_b128 v[166:169], v152 offset:17408
	ds_read_b128 v[170:173], v152 offset:18432
	ds_read_b128 v[174:177], v152 offset:19456
	ds_read_b128 v[178:181], v152 offset:20480
	ds_read_b128 v[182:185], v152 offset:21504
	ds_read_b128 v[186:189], v152 offset:22528
	ds_read_b128 v[190:193], v152 offset:23552
	global_load_lds_dwordx4 v[214:215], off
	v_lshl_add_u64 v[216:217], s[22:23], 0, v[134:135]
	s_mov_b32 m0, s5
	s_nop 0
	global_load_lds_dwordx4 v[216:217], off
	s_barrier
	s_waitcnt lgkmcnt(0)
	s_setprio 1
	s_waitcnt lgkmcnt(0)
	v_mfma_f32_16x16x32_bf16 v[108:111], v[128:131], v[162:165], v[108:111]
	v_mfma_f32_16x16x32_bf16 v[72:75], v[154:157], v[162:165], v[72:75]
	v_mfma_f32_16x16x32_bf16 v[104:107], v[128:131], v[170:173], v[104:107]
	v_mfma_f32_16x16x32_bf16 v[64:67], v[154:157], v[170:173], v[64:67]
	v_mfma_f32_16x16x32_bf16 v[100:103], v[128:131], v[178:181], v[100:103]
	v_mfma_f32_16x16x32_bf16 v[56:59], v[154:157], v[178:181], v[56:59]
	v_mfma_f32_16x16x32_bf16 v[96:99], v[128:131], v[186:189], v[96:99]
	v_mfma_f32_16x16x32_bf16 v[44:47], v[154:157], v[186:189], v[44:47]
	v_mfma_f32_16x16x32_bf16 v[108:111], v[144:147], v[166:169], v[108:111]
	v_mfma_f32_16x16x32_bf16 v[72:75], v[158:161], v[166:169], v[72:75]
	v_mfma_f32_16x16x32_bf16 v[104:107], v[144:147], v[174:177], v[104:107]
	v_mfma_f32_16x16x32_bf16 v[64:67], v[158:161], v[174:177], v[64:67]
	v_mfma_f32_16x16x32_bf16 v[100:103], v[144:147], v[182:185], v[100:103]
	v_mfma_f32_16x16x32_bf16 v[56:59], v[158:161], v[182:185], v[56:59]
	v_mfma_f32_16x16x32_bf16 v[96:99], v[144:147], v[190:193], v[96:99]
	v_mfma_f32_16x16x32_bf16 v[44:47], v[158:161], v[190:193], v[44:47]
	s_setprio 0
	s_barrier
	s_add_u32 s16, s20, 0x160000
	s_addc_u32 s17, s21, 0
	s_add_i32 s47, s37, s3
	v_lshl_add_u64 v[128:129], s[16:17], 0, v[132:133]
	s_mov_b32 m0, s47
	s_nop 0
	global_load_lds_dwordx4 v[128:129], off
	v_lshl_add_u64 v[128:129], s[16:17], 0, v[134:135]
	s_add_i32 m0, s47, 0x2000
	s_nop 0
	global_load_lds_dwordx4 v[128:129], off
	s_waitcnt vmcnt(6)
	s_barrier
	s_setprio 1
	v_mfma_f32_16x16x32_bf16 v[32:35], v[194:197], v[162:165], v[32:35]
	v_mfma_f32_16x16x32_bf16 v[12:15], v[202:205], v[162:165], v[12:15]
	v_mfma_f32_16x16x32_bf16 v[24:27], v[194:197], v[170:173], v[24:27]
	v_mfma_f32_16x16x32_bf16 v[8:11], v[202:205], v[170:173], v[8:11]
	v_mfma_f32_16x16x32_bf16 v[20:23], v[194:197], v[178:181], v[20:23]
	v_mfma_f32_16x16x32_bf16 v[4:7], v[202:205], v[178:181], v[4:7]
	v_mfma_f32_16x16x32_bf16 v[16:19], v[194:197], v[186:189], v[16:19]
	v_mfma_f32_16x16x32_bf16 v[0:3], v[202:205], v[186:189], v[0:3]
	v_mfma_f32_16x16x32_bf16 v[32:35], v[198:201], v[166:169], v[32:35]
	v_mfma_f32_16x16x32_bf16 v[12:15], v[206:209], v[166:169], v[12:15]
	v_mfma_f32_16x16x32_bf16 v[24:27], v[198:201], v[174:177], v[24:27]
	v_mfma_f32_16x16x32_bf16 v[8:11], v[206:209], v[174:177], v[8:11]
	v_mfma_f32_16x16x32_bf16 v[20:23], v[198:201], v[182:185], v[20:23]
	v_mfma_f32_16x16x32_bf16 v[4:7], v[206:209], v[182:185], v[4:7]
	v_mfma_f32_16x16x32_bf16 v[16:19], v[198:201], v[190:193], v[16:19]
	v_mfma_f32_16x16x32_bf16 v[0:3], v[206:209], v[190:193], v[0:3]
	s_setprio 0
	s_add_i32 s47, 0, 0x18000
	v_add_u32_e32 v158, s47, v149
	s_barrier
	ds_read_b128 v[128:131], v158
	ds_read_b128 v[144:147], v158 offset:1024
	ds_read_b128 v[154:157], v158 offset:2048
	ds_read_b128 v[158:161], v158 offset:3072
	s_add_u32 s16, s22, 0x160000
	s_addc_u32 s17, s23, 0
	s_mov_b32 m0, s26
	v_lshl_add_u64 v[194:195], s[16:17], 0, v[132:133]
	ds_read_b128 v[162:165], v152 offset:32768
	ds_read_b128 v[166:169], v152 offset:33792
	ds_read_b128 v[170:173], v152 offset:34816
	ds_read_b128 v[174:177], v152 offset:35840
	ds_read_b128 v[178:181], v152 offset:36864
	ds_read_b128 v[182:185], v152 offset:37888
	ds_read_b128 v[186:189], v152 offset:38912
	ds_read_b128 v[190:193], v152 offset:39936
	global_load_lds_dwordx4 v[194:195], off
	v_lshl_add_u64 v[194:195], s[16:17], 0, v[134:135]
	s_mov_b32 m0, s27
	s_nop 0
	global_load_lds_dwordx4 v[194:195], off
	s_waitcnt lgkmcnt(8)
	s_barrier
	s_waitcnt lgkmcnt(0)
	s_setprio 1
	s_waitcnt lgkmcnt(0)
	v_mfma_f32_16x16x32_bf16 v[124:127], v[128:131], v[162:165], v[124:127]
	v_mfma_f32_16x16x32_bf16 v[92:95], v[154:157], v[162:165], v[92:95]
	v_mfma_f32_16x16x32_bf16 v[120:123], v[128:131], v[170:173], v[120:123]
	v_mfma_f32_16x16x32_bf16 v[88:91], v[154:157], v[170:173], v[88:91]
	v_mfma_f32_16x16x32_bf16 v[116:119], v[128:131], v[178:181], v[116:119]
	v_mfma_f32_16x16x32_bf16 v[84:87], v[154:157], v[178:181], v[84:87]
	v_mfma_f32_16x16x32_bf16 v[112:115], v[128:131], v[186:189], v[112:115]
	v_mfma_f32_16x16x32_bf16 v[80:83], v[154:157], v[186:189], v[80:83]
	v_mfma_f32_16x16x32_bf16 v[124:127], v[144:147], v[166:169], v[124:127]
	v_mfma_f32_16x16x32_bf16 v[92:95], v[158:161], v[166:169], v[92:95]
	v_mfma_f32_16x16x32_bf16 v[120:123], v[144:147], v[174:177], v[120:123]
	v_mfma_f32_16x16x32_bf16 v[88:91], v[158:161], v[174:177], v[88:91]
	v_mfma_f32_16x16x32_bf16 v[116:119], v[144:147], v[182:185], v[116:119]
	v_mfma_f32_16x16x32_bf16 v[84:87], v[158:161], v[182:185], v[84:87]
	v_mfma_f32_16x16x32_bf16 v[112:115], v[144:147], v[190:193], v[112:115]
	v_mfma_f32_16x16x32_bf16 v[80:83], v[158:161], v[190:193], v[80:83]
	s_setprio 0
	s_barrier
	s_add_i32 s22, 0, 0x1c000
	s_add_i32 s16, s47, s3
	v_add_u32_e32 v206, s22, v149
	v_lshl_add_u64 v[210:211], v[210:211], 0, s[14:15]
	s_mov_b32 m0, s16
	ds_read_b128 v[194:197], v206
	ds_read_b128 v[198:201], v206 offset:1024
	ds_read_b128 v[202:205], v206 offset:2048
	ds_read_b128 v[206:209], v206 offset:3072
	global_load_lds_dwordx4 v[210:211], off
	v_lshl_add_u64 v[210:211], v[212:213], 0, s[14:15]
	s_add_i32 m0, s16, 0x2000
	s_nop 0
	global_load_lds_dwordx4 v[210:211], off
	s_barrier
	s_waitcnt lgkmcnt(0)
	s_setprio 1
	s_waitcnt lgkmcnt(0)
	v_mfma_f32_16x16x32_bf16 v[76:79], v[194:197], v[162:165], v[76:79]
	v_mfma_f32_16x16x32_bf16 v[48:51], v[202:205], v[162:165], v[48:51]
	v_mfma_f32_16x16x32_bf16 v[68:71], v[194:197], v[170:173], v[68:71]
	v_mfma_f32_16x16x32_bf16 v[40:43], v[202:205], v[170:173], v[40:43]
	v_mfma_f32_16x16x32_bf16 v[60:63], v[194:197], v[178:181], v[60:63]
	v_mfma_f32_16x16x32_bf16 v[36:39], v[202:205], v[178:181], v[36:39]
	v_mfma_f32_16x16x32_bf16 v[52:55], v[194:197], v[186:189], v[52:55]
	v_mfma_f32_16x16x32_bf16 v[28:31], v[202:205], v[186:189], v[28:31]
	v_mfma_f32_16x16x32_bf16 v[76:79], v[198:201], v[166:169], v[76:79]
	v_mfma_f32_16x16x32_bf16 v[48:51], v[206:209], v[166:169], v[48:51]
	v_mfma_f32_16x16x32_bf16 v[68:71], v[198:201], v[174:177], v[68:71]
	v_mfma_f32_16x16x32_bf16 v[40:43], v[206:209], v[174:177], v[40:43]
	v_mfma_f32_16x16x32_bf16 v[60:63], v[198:201], v[182:185], v[60:63]
	v_mfma_f32_16x16x32_bf16 v[36:39], v[206:209], v[182:185], v[36:39]
	v_mfma_f32_16x16x32_bf16 v[52:55], v[198:201], v[190:193], v[52:55]
	v_mfma_f32_16x16x32_bf16 v[28:31], v[206:209], v[190:193], v[28:31]
	s_setprio 0
	s_mov_b32 m0, s29
	v_lshl_add_u64 v[210:211], v[214:215], 0, s[14:15]
	s_barrier
	ds_read_b128 v[162:165], v152 offset:49152
	ds_read_b128 v[166:169], v152 offset:50176
	ds_read_b128 v[170:173], v152 offset:51200
	ds_read_b128 v[174:177], v152 offset:52224
	ds_read_b128 v[178:181], v152 offset:53248
	ds_read_b128 v[182:185], v152 offset:54272
	ds_read_b128 v[186:189], v152 offset:55296
	ds_read_b128 v[190:193], v152 offset:56320
	global_load_lds_dwordx4 v[210:211], off
	v_lshl_add_u64 v[210:211], v[216:217], 0, s[14:15]
	s_mov_b32 m0, s30
	s_nop 0
	global_load_lds_dwordx4 v[210:211], off
	s_barrier
	s_waitcnt lgkmcnt(0)
	s_setprio 1
	s_waitcnt lgkmcnt(0)
	v_mfma_f32_16x16x32_bf16 v[108:111], v[128:131], v[162:165], v[108:111]
	v_mfma_f32_16x16x32_bf16 v[72:75], v[154:157], v[162:165], v[72:75]
	v_mfma_f32_16x16x32_bf16 v[104:107], v[128:131], v[170:173], v[104:107]
	v_mfma_f32_16x16x32_bf16 v[64:67], v[154:157], v[170:173], v[64:67]
	v_mfma_f32_16x16x32_bf16 v[100:103], v[128:131], v[178:181], v[100:103]
	v_mfma_f32_16x16x32_bf16 v[56:59], v[154:157], v[178:181], v[56:59]
	v_mfma_f32_16x16x32_bf16 v[96:99], v[128:131], v[186:189], v[96:99]
	v_mfma_f32_16x16x32_bf16 v[44:47], v[154:157], v[186:189], v[44:47]
	v_mfma_f32_16x16x32_bf16 v[108:111], v[144:147], v[166:169], v[108:111]
	v_mfma_f32_16x16x32_bf16 v[72:75], v[158:161], v[166:169], v[72:75]
	v_mfma_f32_16x16x32_bf16 v[104:107], v[144:147], v[174:177], v[104:107]
	v_mfma_f32_16x16x32_bf16 v[64:67], v[158:161], v[174:177], v[64:67]
	v_mfma_f32_16x16x32_bf16 v[100:103], v[144:147], v[182:185], v[100:103]
	v_mfma_f32_16x16x32_bf16 v[56:59], v[158:161], v[182:185], v[56:59]
	v_mfma_f32_16x16x32_bf16 v[96:99], v[144:147], v[190:193], v[96:99]
	v_mfma_f32_16x16x32_bf16 v[44:47], v[158:161], v[190:193], v[44:47]
	s_setprio 0
	s_barrier
	s_add_u32 s16, s20, 0x160080
	s_addc_u32 s17, s21, 0
	s_add_i32 s20, s22, s3
	v_lshl_add_u64 v[128:129], s[16:17], 0, v[132:133]
	s_mov_b32 m0, s20
	s_nop 0
	global_load_lds_dwordx4 v[128:129], off
	v_lshl_add_u64 v[128:129], s[16:17], 0, v[134:135]
	s_add_i32 m0, s20, 0x2000
	s_nop 0
	global_load_lds_dwordx4 v[128:129], off
	s_waitcnt vmcnt(6)
	s_barrier
	s_setprio 1
	v_mfma_f32_16x16x32_bf16 v[32:35], v[194:197], v[162:165], v[32:35]
	v_mfma_f32_16x16x32_bf16 v[12:15], v[202:205], v[162:165], v[12:15]
	v_mfma_f32_16x16x32_bf16 v[24:27], v[194:197], v[170:173], v[24:27]
	v_mfma_f32_16x16x32_bf16 v[8:11], v[202:205], v[170:173], v[8:11]
	v_mfma_f32_16x16x32_bf16 v[20:23], v[194:197], v[178:181], v[20:23]
	v_mfma_f32_16x16x32_bf16 v[4:7], v[202:205], v[178:181], v[4:7]
	v_mfma_f32_16x16x32_bf16 v[16:19], v[194:197], v[186:189], v[16:19]
	v_mfma_f32_16x16x32_bf16 v[0:3], v[202:205], v[186:189], v[0:3]
	v_mfma_f32_16x16x32_bf16 v[32:35], v[198:201], v[166:169], v[32:35]
	v_mfma_f32_16x16x32_bf16 v[12:15], v[206:209], v[166:169], v[12:15]
	v_mfma_f32_16x16x32_bf16 v[24:27], v[198:201], v[174:177], v[24:27]
	v_mfma_f32_16x16x32_bf16 v[8:11], v[206:209], v[174:177], v[8:11]
	v_mfma_f32_16x16x32_bf16 v[20:23], v[198:201], v[182:185], v[20:23]
	v_mfma_f32_16x16x32_bf16 v[4:7], v[206:209], v[182:185], v[4:7]
	v_mfma_f32_16x16x32_bf16 v[16:19], v[198:201], v[190:193], v[16:19]
	v_mfma_f32_16x16x32_bf16 v[0:3], v[206:209], v[190:193], v[0:3]
	s_setprio 0
	s_add_i32 s46, s46, 2
	s_add_u32 s42, s42, 0x100
	s_addc_u32 s43, s43, 0
	s_cmpk_gt_u32 s46, 0x55
	s_mov_b64 s[16:17], s[18:19]
	s_barrier
	s_cbranch_scc0 .LBB0_2911
	s_cmp_lt_u32 s40, 32
	s_movk_i32 s16, 0x3000
	s_cselect_b32 s16, s16, 0x6000
	s_cmp_gt_i32 s40, 15
	v_lshl_add_u32 v158, s40, 8, v148
	s_cselect_b32 s16, s16, 0
	v_lshl_or_b32 v128, s41, 8, v150
	s_lshl_b32 s16, s16, 2
	v_ashrrev_i32_e32 v159, 31, v158
	s_add_u32 s16, s34, s16
	v_ashrrev_i32_e32 v129, 31, v128
	v_lshlrev_b64 v[146:147], 13, v[158:159]
	s_addc_u32 s17, s35, 0
	v_lshlrev_b64 v[160:161], 2, v[128:129]
	v_lshl_add_u64 v[146:147], s[48:49], 0, v[146:147]
	v_lshl_add_u64 v[144:145], s[16:17], 0, v[160:161]
	v_lshl_add_u64 v[146:147], v[146:147], 0, v[160:161]
	s_mov_b64 s[16:17], 0x100000
	s_mov_b32 s41, s38
	s_mov_b32 s40, s39
	s_mov_b64 s[18:19], s[12:13]
	v_or_b32_e32 v162, 16, v158
	v_ashrrev_i32_e32 v163, 31, v162
	v_lshlrev_b64 v[164:165], 13, v[162:163]
	v_lshl_add_u64 v[162:163], s[48:49], 0, v[164:165]
	v_lshl_add_u64 v[164:165], v[162:163], 0, v[160:161]
	v_or_b32_e32 v162, 32, v158
	v_ashrrev_i32_e32 v163, 31, v162
	v_lshlrev_b64 v[166:167], 13, v[162:163]
	v_lshl_add_u64 v[162:163], s[48:49], 0, v[166:167]
	v_lshl_add_u64 v[166:167], v[162:163], 0, v[160:161]
	v_or_b32_e32 v162, 48, v158
	v_ashrrev_i32_e32 v163, 31, v162
	v_lshlrev_b64 v[168:169], 13, v[162:163]
	v_lshl_add_u64 v[162:163], s[48:49], 0, v[168:169]
	v_lshl_add_u64 v[168:169], v[162:163], 0, v[160:161]
	v_lshl_add_u64 v[162:163], v[146:147], 0, s[16:17]
	s_mov_b32 s16, 0x100000
	v_add_co_u32_e32 v170, vcc, s16, v146
	s_mov_b64 s[16:17], 0x120000
	s_nop 0
	v_addc_co_u32_e32 v171, vcc, 0, v147, vcc
	v_lshl_add_u64 v[172:173], v[146:147], 0, s[16:17]
	s_mov_b32 s16, 0x120000
	v_add_co_u32_e32 v174, vcc, s16, v146
	s_mov_b64 s[16:17], 0x140000
	s_nop 0
	v_addc_co_u32_e32 v175, vcc, 0, v147, vcc
	v_lshl_add_u64 v[176:177], v[146:147], 0, s[16:17]
	s_mov_b32 s16, 0x140000
	v_add_co_u32_e32 v178, vcc, s16, v146
	s_mov_b64 s[16:17], 0x160000
	s_nop 0
	v_addc_co_u32_e32 v179, vcc, 0, v147, vcc
	v_lshl_add_u64 v[180:181], v[146:147], 0, s[16:17]
	s_mov_b32 s16, 0x160000
	v_add_co_u32_e32 v182, vcc, s16, v146
	s_mov_b64 s[16:17], s[10:11]
	s_nop 0
	v_addc_co_u32_e32 v183, vcc, 0, v147, vcc
	s_and_b64 vcc, exec, s[8:9]
	global_load_dwordx4 v[184:187], v[144:145], off
	global_load_dwordx4 v[188:191], v[146:147], off
	v_pk_add_f32 v[126:127], v[126:127], 0 op_sel_hi:[1,0]
	v_pk_add_f32 v[124:125], v[124:125], 0 op_sel_hi:[1,0]
	v_pk_add_f32 v[122:123], v[122:123], 0 op_sel_hi:[1,0]
	v_pk_add_f32 v[120:121], v[120:121], 0 op_sel_hi:[1,0]
	v_pk_add_f32 v[118:119], v[118:119], 0 op_sel_hi:[1,0]
	v_pk_add_f32 v[116:117], v[116:117], 0 op_sel_hi:[1,0]
	v_pk_add_f32 v[114:115], v[114:115], 0 op_sel_hi:[1,0]
	v_pk_add_f32 v[112:113], v[112:113], 0 op_sel_hi:[1,0]
	v_pk_add_f32 v[110:111], v[110:111], 0 op_sel_hi:[1,0]
	v_pk_add_f32 v[108:109], v[108:109], 0 op_sel_hi:[1,0]
	v_pk_add_f32 v[106:107], v[106:107], 0 op_sel_hi:[1,0]
	v_pk_add_f32 v[104:105], v[104:105], 0 op_sel_hi:[1,0]
	v_pk_add_f32 v[102:103], v[102:103], 0 op_sel_hi:[1,0]
	v_pk_add_f32 v[100:101], v[100:101], 0 op_sel_hi:[1,0]
	v_pk_add_f32 v[98:99], v[98:99], 0 op_sel_hi:[1,0]
	v_pk_add_f32 v[96:97], v[96:97], 0 op_sel_hi:[1,0]
	v_pk_add_f32 v[94:95], v[94:95], 0 op_sel_hi:[1,0]
	v_pk_add_f32 v[92:93], v[92:93], 0 op_sel_hi:[1,0]
	v_pk_add_f32 v[90:91], v[90:91], 0 op_sel_hi:[1,0]
	v_pk_add_f32 v[88:89], v[88:89], 0 op_sel_hi:[1,0]
	v_pk_add_f32 v[86:87], v[86:87], 0 op_sel_hi:[1,0]
	v_pk_add_f32 v[84:85], v[84:85], 0 op_sel_hi:[1,0]
	v_pk_add_f32 v[82:83], v[82:83], 0 op_sel_hi:[1,0]
	v_pk_add_f32 v[80:81], v[80:81], 0 op_sel_hi:[1,0]
	v_pk_add_f32 v[74:75], v[74:75], 0 op_sel_hi:[1,0]
	v_pk_add_f32 v[72:73], v[72:73], 0 op_sel_hi:[1,0]
	v_pk_add_f32 v[66:67], v[66:67], 0 op_sel_hi:[1,0]
	v_pk_add_f32 v[64:65], v[64:65], 0 op_sel_hi:[1,0]
	v_pk_add_f32 v[58:59], v[58:59], 0 op_sel_hi:[1,0]
	v_pk_add_f32 v[56:57], v[56:57], 0 op_sel_hi:[1,0]
	v_pk_add_f32 v[46:47], v[46:47], 0 op_sel_hi:[1,0]
	v_pk_add_f32 v[44:45], v[44:45], 0 op_sel_hi:[1,0]
	v_pk_add_f32 v[62:63], v[62:63], 0 op_sel_hi:[1,0]
	v_pk_add_f32 v[60:61], v[60:61], 0 op_sel_hi:[1,0]
	v_pk_add_f32 v[54:55], v[54:55], 0 op_sel_hi:[1,0]
	v_pk_add_f32 v[52:53], v[52:53], 0 op_sel_hi:[1,0]
	v_pk_add_f32 v[34:35], v[34:35], 0 op_sel_hi:[1,0]
	v_pk_add_f32 v[32:33], v[32:33], 0 op_sel_hi:[1,0]
	v_pk_add_f32 v[26:27], v[26:27], 0 op_sel_hi:[1,0]
	v_pk_add_f32 v[24:25], v[24:25], 0 op_sel_hi:[1,0]
	v_pk_add_f32 v[22:23], v[22:23], 0 op_sel_hi:[1,0]
	v_pk_add_f32 v[20:21], v[20:21], 0 op_sel_hi:[1,0]
	v_pk_add_f32 v[18:19], v[18:19], 0 op_sel_hi:[1,0]
	v_pk_add_f32 v[16:17], v[16:17], 0 op_sel_hi:[1,0]
	v_pk_add_f32 v[14:15], v[14:15], 0 op_sel_hi:[1,0]
	v_pk_add_f32 v[12:13], v[12:13], 0 op_sel_hi:[1,0]
	v_pk_add_f32 v[10:11], v[10:11], 0 op_sel_hi:[1,0]
	v_pk_add_f32 v[8:9], v[8:9], 0 op_sel_hi:[1,0]
	v_pk_add_f32 v[6:7], v[6:7], 0 op_sel_hi:[1,0]
	v_pk_add_f32 v[4:5], v[4:5], 0 op_sel_hi:[1,0]
	v_pk_add_f32 v[2:3], v[2:3], 0 op_sel_hi:[1,0]
	v_pk_add_f32 v[0:1], v[0:1], 0 op_sel_hi:[1,0]
	s_waitcnt vmcnt(0)
	v_pk_fma_f32 v[126:127], v[126:127], v[186:187], v[190:191]
	v_pk_fma_f32 v[124:125], v[124:125], v[184:185], v[188:189]
	global_store_dwordx4 v[146:147], v[124:127], off
	global_load_dwordx4 v[188:191], v[164:165], off
	global_load_dwordx4 v[192:195], v[166:167], off
	global_load_dwordx4 v[196:199], v[168:169], off
	global_load_dwordx4 v[200:203], v[170:171], off
	global_load_dwordx4 v[204:207], v[174:175], off
	global_load_dwordx4 v[208:211], v[178:179], off
	global_load_dwordx4 v[212:215], v[182:183], off
	global_load_dwordx4 v[216:219], v[144:145], off offset:64
	global_load_dwordx4 v[220:223], v[146:147], off offset:64
	global_load_dwordx4 v[224:227], v[164:165], off offset:64
	global_load_dwordx4 v[228:231], v[166:167], off offset:64
	global_load_dwordx4 v[232:235], v[168:169], off offset:64
	s_waitcnt vmcnt(11)
	v_pk_fma_f32 v[122:123], v[122:123], v[186:187], v[190:191]
	v_pk_fma_f32 v[120:121], v[120:121], v[184:185], v[188:189]
	global_store_dwordx4 v[164:165], v[120:123], off
	global_load_dwordx4 v[188:191], v[162:163], off offset:64
	s_waitcnt vmcnt(12)
	v_pk_fma_f32 v[118:119], v[118:119], v[186:187], v[194:195]
	v_pk_fma_f32 v[116:117], v[116:117], v[184:185], v[192:193]
	global_store_dwordx4 v[166:167], v[116:119], off
	global_load_dwordx4 v[192:195], v[172:173], off offset:64
	s_waitcnt vmcnt(13)
	v_pk_fma_f32 v[114:115], v[114:115], v[186:187], v[198:199]
	v_pk_fma_f32 v[112:113], v[112:113], v[184:185], v[196:197]
	global_store_dwordx4 v[168:169], v[112:115], off
	global_load_dwordx4 v[196:199], v[176:177], off offset:64
	s_waitcnt vmcnt(14)
	v_pk_fma_f32 v[110:111], v[110:111], v[186:187], v[202:203]
	v_pk_fma_f32 v[108:109], v[108:109], v[184:185], v[200:201]
	global_store_dwordx4 v[170:171], v[108:111], off
	global_load_dwordx4 v[200:203], v[180:181], off offset:64
	s_waitcnt vmcnt(15)
	v_pk_fma_f32 v[106:107], v[106:107], v[186:187], v[206:207]
	v_pk_fma_f32 v[104:105], v[104:105], v[184:185], v[204:205]
	global_store_dwordx4 v[174:175], v[104:107], off
	global_load_dwordx4 v[204:207], v[144:145], off offset:512
	s_waitcnt vmcnt(16)
	v_pk_fma_f32 v[102:103], v[102:103], v[186:187], v[210:211]
	v_pk_fma_f32 v[100:101], v[100:101], v[184:185], v[208:209]
	global_store_dwordx4 v[178:179], v[100:103], off
	global_load_dwordx4 v[208:211], v[146:147], off offset:512
	s_waitcnt vmcnt(17)
	v_pk_fma_f32 v[98:99], v[98:99], v[186:187], v[214:215]
	v_pk_fma_f32 v[96:97], v[96:97], v[184:185], v[212:213]
	global_store_dwordx4 v[182:183], v[96:99], off
	global_load_dwordx4 v[184:187], v[164:165], off offset:512
	s_waitcnt vmcnt(17)
	v_pk_fma_f32 v[94:95], v[94:95], v[218:219], v[222:223]
	v_pk_fma_f32 v[92:93], v[92:93], v[216:217], v[220:221]
	global_store_dwordx4 v[146:147], v[92:95], off offset:64
	global_load_dwordx4 v[212:215], v[166:167], off offset:512
	global_load_dwordx4 v[220:223], v[168:169], off offset:512
	s_waitcnt vmcnt(19)
	v_pk_fma_f32 v[90:91], v[90:91], v[218:219], v[226:227]
	v_pk_fma_f32 v[88:89], v[88:89], v[216:217], v[224:225]
	global_store_dwordx4 v[164:165], v[88:91], off offset:64
	global_load_dwordx4 v[224:227], v[162:163], off offset:512
	s_waitcnt vmcnt(20)
	v_pk_fma_f32 v[86:87], v[86:87], v[218:219], v[230:231]
	v_pk_fma_f32 v[84:85], v[84:85], v[216:217], v[228:229]
	global_store_dwordx4 v[166:167], v[84:87], off offset:64
	global_load_dwordx4 v[228:231], v[172:173], off offset:512
	s_waitcnt vmcnt(21)
	v_pk_fma_f32 v[82:83], v[82:83], v[218:219], v[234:235]
	v_pk_fma_f32 v[80:81], v[80:81], v[216:217], v[232:233]
	global_store_dwordx4 v[168:169], v[80:83], off offset:64
	global_load_dwordx4 v[232:235], v[176:177], off offset:512
	s_waitcnt vmcnt(21)
	v_pk_fma_f32 v[74:75], v[74:75], v[218:219], v[190:191]
	v_pk_fma_f32 v[72:73], v[72:73], v[216:217], v[188:189]
	global_store_dwordx4 v[162:163], v[72:75], off offset:64
	global_load_dwordx4 v[188:191], v[180:181], off offset:512
	s_waitcnt vmcnt(21)
	v_pk_fma_f32 v[66:67], v[66:67], v[218:219], v[194:195]
	v_pk_fma_f32 v[64:65], v[64:65], v[216:217], v[192:193]
	global_store_dwordx4 v[172:173], v[64:67], off offset:64
	global_load_dwordx4 v[192:195], v[144:145], off offset:576
	s_waitcnt vmcnt(21)
	v_pk_fma_f32 v[58:59], v[58:59], v[218:219], v[198:199]
	v_pk_fma_f32 v[56:57], v[56:57], v[216:217], v[196:197]
	global_store_dwordx4 v[176:177], v[56:59], off offset:64
	global_load_dwordx4 v[196:199], v[146:147], off offset:576
	v_pk_add_f32 v[64:65], v[78:79], 0 op_sel_hi:[1,0]
	v_pk_add_f32 v[66:67], v[76:77], 0 op_sel_hi:[1,0]
	s_waitcnt vmcnt(21)
	v_pk_fma_f32 v[46:47], v[46:47], v[218:219], v[202:203]
	v_pk_fma_f32 v[44:45], v[44:45], v[216:217], v[200:201]
	global_store_dwordx4 v[180:181], v[44:47], off offset:64
	global_load_dwordx4 v[200:203], v[164:165], off offset:576
	s_waitcnt vmcnt(19)
	v_pk_fma_f32 v[58:59], v[64:65], v[206:207], v[210:211]
	v_pk_fma_f32 v[56:57], v[66:67], v[204:205], v[208:209]
	global_store_dwordx4 v[146:147], v[56:59], off offset:512
	global_load_dwordx4 v[208:211], v[166:167], off offset:576
	global_load_dwordx4 v[216:219], v[168:169], off offset:576
	v_pk_add_f32 v[64:65], v[70:71], 0 op_sel_hi:[1,0]
	v_pk_add_f32 v[66:67], v[68:69], 0 op_sel_hi:[1,0]
	s_waitcnt vmcnt(20)
	v_pk_fma_f32 v[58:59], v[64:65], v[206:207], v[186:187]
	v_pk_fma_f32 v[56:57], v[66:67], v[204:205], v[184:185]
	global_store_dwordx4 v[164:165], v[56:59], off offset:512
	global_load_dwordx4 v[184:187], v[162:163], off offset:576
	s_waitcnt vmcnt(20)
	v_pk_fma_f32 v[58:59], v[62:63], v[206:207], v[214:215]
	v_pk_fma_f32 v[56:57], v[60:61], v[204:205], v[212:213]
	global_store_dwordx4 v[166:167], v[56:59], off offset:512
	global_load_dwordx4 v[212:215], v[172:173], off offset:576
	s_waitcnt vmcnt(21)
	v_pk_fma_f32 v[54:55], v[54:55], v[206:207], v[222:223]
	v_pk_fma_f32 v[52:53], v[52:53], v[204:205], v[220:221]
	global_store_dwordx4 v[168:169], v[52:55], off offset:512
	global_load_dwordx4 v[220:223], v[176:177], off offset:576
	s_waitcnt vmcnt(21)
	v_pk_fma_f32 v[34:35], v[34:35], v[206:207], v[226:227]
	v_pk_fma_f32 v[32:33], v[32:33], v[204:205], v[224:225]
	global_store_dwordx4 v[162:163], v[32:35], off offset:512
	global_load_dwordx4 v[224:227], v[180:181], off offset:576
	s_waitcnt vmcnt(21)
	v_pk_fma_f32 v[26:27], v[26:27], v[206:207], v[230:231]
	v_pk_fma_f32 v[24:25], v[24:25], v[204:205], v[228:229]
	global_store_dwordx4 v[172:173], v[24:27], off offset:512
	s_waitcnt vmcnt(20)
	v_pk_fma_f32 v[22:23], v[22:23], v[206:207], v[234:235]
	v_pk_fma_f32 v[20:21], v[20:21], v[204:205], v[232:233]
	global_store_dwordx4 v[176:177], v[20:23], off offset:512
	v_pk_add_f32 v[24:25], v[50:51], 0 op_sel_hi:[1,0]
	v_pk_add_f32 v[26:27], v[48:49], 0 op_sel_hi:[1,0]
	s_waitcnt vmcnt(19)
	v_pk_fma_f32 v[18:19], v[18:19], v[206:207], v[190:191]
	v_pk_fma_f32 v[16:17], v[16:17], v[204:205], v[188:189]
	global_store_dwordx4 v[180:181], v[16:19], off offset:512
	s_waitcnt vmcnt(16)
	v_pk_fma_f32 v[22:23], v[24:25], v[194:195], v[198:199]
	v_pk_fma_f32 v[20:21], v[26:27], v[192:193], v[196:197]
	global_store_dwordx4 v[146:147], v[20:23], off offset:576
	v_pk_add_f32 v[24:25], v[42:43], 0 op_sel_hi:[1,0]
	v_pk_add_f32 v[26:27], v[40:41], 0 op_sel_hi:[1,0]
	s_waitcnt vmcnt(15)
	v_pk_fma_f32 v[22:23], v[24:25], v[194:195], v[202:203]
	v_pk_fma_f32 v[20:21], v[26:27], v[192:193], v[200:201]
	global_store_dwordx4 v[164:165], v[20:23], off offset:576
	v_pk_add_f32 v[24:25], v[38:39], 0 op_sel_hi:[1,0]
	v_pk_add_f32 v[26:27], v[36:37], 0 op_sel_hi:[1,0]
	s_waitcnt vmcnt(14)
	v_pk_fma_f32 v[22:23], v[24:25], v[194:195], v[210:211]
	v_pk_fma_f32 v[20:21], v[26:27], v[192:193], v[208:209]
	global_store_dwordx4 v[166:167], v[20:23], off offset:576
	v_pk_add_f32 v[24:25], v[30:31], 0 op_sel_hi:[1,0]
	v_pk_add_f32 v[26:27], v[28:29], 0 op_sel_hi:[1,0]
	s_waitcnt vmcnt(14)
	v_pk_fma_f32 v[22:23], v[24:25], v[194:195], v[218:219]
	v_pk_fma_f32 v[20:21], v[26:27], v[192:193], v[216:217]
	global_store_dwordx4 v[168:169], v[20:23], off offset:576
	s_waitcnt vmcnt(13)
	v_pk_fma_f32 v[14:15], v[14:15], v[194:195], v[186:187]
	v_pk_fma_f32 v[12:13], v[12:13], v[192:193], v[184:185]
	global_store_dwordx4 v[162:163], v[12:15], off offset:576
	s_waitcnt vmcnt(12)
	v_pk_fma_f32 v[10:11], v[10:11], v[194:195], v[214:215]
	v_pk_fma_f32 v[8:9], v[8:9], v[192:193], v[212:213]
	global_store_dwordx4 v[172:173], v[8:11], off offset:576
	s_waitcnt vmcnt(11)
	v_pk_fma_f32 v[6:7], v[6:7], v[194:195], v[222:223]
	v_pk_fma_f32 v[4:5], v[4:5], v[192:193], v[220:221]
	global_store_dwordx4 v[176:177], v[4:7], off offset:576
	s_waitcnt vmcnt(10)
	v_pk_fma_f32 v[2:3], v[2:3], v[194:195], v[226:227]
	v_pk_fma_f32 v[0:1], v[0:1], v[192:193], v[224:225]
	global_store_dwordx4 v[180:181], v[0:3], off offset:576
	s_cbranch_vccz .LBB0_2900
	s_waitcnt vmcnt(0)
	s_cmpk_gt_u32 s1, 0xff
	s_cbranch_scc1 .LBB0_2915
	s_barrier

.LBB0_3098:
	s_or_b64 exec, exec, s[6:7]
	s_lshr_b32 s16, s39, 3
	s_ashr_i32 s10, s39, 7
	s_lshl_b32 s6, s27, 17
	s_add_u32 s6, s50, s6
	s_addc_u32 s7, s51, 0
	s_mul_i32 s27, s27, 0x88100
	s_add_u32 s11, s54, s27
	s_addc_u32 s12, s55, 0
	s_mul_i32 s40, s10, 0x44000
	s_mul_hi_i32 s27, s10, 0x44000
	s_add_u32 s22, s11, s40
	s_addc_u32 s23, s12, s27
	v_lshl_add_u64 v[0:1], s[22:23], 0, v[80:81]
	v_lshl_add_u64 v[0:1], v[0:1], 0, v[74:75]
	global_load_dwordx4 v[110:113], v[0:1], off
	v_lshl_add_u64 v[0:1], s[6:7], 0, v[76:77]
	v_lshl_add_u64 v[0:1], v[0:1], 0, v[106:107]
	global_load_dwordx4 v[56:59], v[0:1], off
	v_lshl_add_u64 v[2:3], s[6:7], 0, v[78:79]
	v_lshl_add_u64 v[2:3], v[2:3], 0, v[106:107]
	global_load_dwordx4 v[60:63], v[2:3], off
	global_load_dwordx4 v[48:51], v[0:1], off offset:64
	global_load_dwordx4 v[52:55], v[2:3], off offset:64
	global_load_dwordx4 v[40:43], v[0:1], off offset:128
	global_load_dwordx4 v[44:47], v[2:3], off offset:128
	global_load_dwordx4 v[32:35], v[0:1], off offset:192
	global_load_dwordx4 v[36:39], v[2:3], off offset:192
	global_load_dwordx4 v[24:27], v[0:1], off offset:256
	global_load_dwordx4 v[28:31], v[2:3], off offset:256
	global_load_dwordx4 v[20:23], v[0:1], off offset:320
	global_load_dwordx4 v[8:11], v[2:3], off offset:320
	global_load_dwordx4 v[16:19], v[0:1], off offset:384
	global_load_dwordx4 v[4:7], v[2:3], off offset:384
	global_load_dwordx4 v[12:15], v[0:1], off offset:448
	s_nop 0
	global_load_dwordx4 v[0:3], v[2:3], off offset:448
	s_waitcnt lgkmcnt(0)
	s_barrier
	v_add_u32_e32 v163, s24, v150
	s_waitcnt vmcnt(17)
	v_mul_f32_e32 v67, 0x41800000, v67
	v_lshlrev_b32_e32 v71, 30, v69
	v_and_b32_e32 v109, 1, v69
	v_xor_b32_e32 v122, v68, v64
	v_mul_f32_e32 v124, v66, v67
	v_mul_f32_e32 v70, v65, v65
	v_fmamk_f32 v123, v70, 0xb94c1982, v157
	v_fmamk_f32 v125, v70, 0x37d75334, v158
	v_fmaak_f32 v123, v70, v123, 0xbe2aaa9d
	v_fmaak_f32 v125, v70, v125, 0x3d2aabf7
	v_mul_f32_e32 v126, 0x3fb8aa3b, v124
	v_mul_f32_e32 v123, v70, v123
	v_fmaak_f32 v125, v70, v125, 0xbf000004
	v_fma_f32 v127, v124, s34, -v126
	v_rndne_f32_e32 v128, v126
	v_fmac_f32_e32 v65, v65, v123
	v_fma_f32 v70, v70, v125, 1.0
	v_cmp_eq_u32_e64 s[6:7], 0, v109
	v_fmac_f32_e32 v127, 0x32a5705f, v124
	v_sub_f32_e32 v126, v126, v128
	v_cndmask_b32_e64 v109, v70, v65, s[6:7]
	v_xor_b32_e32 v65, 0x80000000, v65
	v_and_b32_e32 v71, 0x80000000, v71
	v_add_f32_e32 v123, v126, v127
	v_cndmask_b32_e64 v65, v65, v70, s[6:7]
	v_cvt_i32_f32_e32 v128, v128
	v_exp_f32_e32 v125, v123
	v_xor_b32_e32 v65, v65, v71
	v_cmp_class_f32_e64 s[6:7], v64, s38
	v_xor_b32_e32 v109, v122, v109
	v_xor_b32_e32 v70, v109, v71
	v_cndmask_b32_e64 v122, v162, v65, s[6:7]
	v_cndmask_b32_e64 v123, v162, v70, s[6:7]
	v_cmp_ngt_f32_e64 s[6:7], s35, v124
	s_cmp_eq_u32 s4, 1
	v_readlane_b32 s94, v239, 1
	s_waitcnt vmcnt(16)
	ds_write_b128 v73, v[110:113]
	ds_write_b128 v73, v[110:113] offset:8448
	s_waitcnt lgkmcnt(0)
	s_barrier
	ds_read_b128 v[168:171], v163
	ds_read_b128 v[172:175], v163 offset:64
	s_waitcnt vmcnt(15)
	ds_read_b128 v[176:179], v163 offset:128
	s_waitcnt lgkmcnt(2)
	v_mfma_f32_16x16x32_bf16 v[118:121], v[168:171], v[56:59], 0
	s_waitcnt vmcnt(14)
	v_mfma_f32_16x16x32_bf16 v[110:113], v[168:171], v[60:63], 0
	s_waitcnt vmcnt(13)
	s_waitcnt lgkmcnt(1)
	v_mfma_f32_16x16x32_bf16 v[118:121], v[172:175], v[48:51], v[118:121]
	s_waitcnt vmcnt(12)
	ds_read_b128 v[168:171], v163 offset:192
	v_mfma_f32_16x16x32_bf16 v[110:113], v[172:175], v[52:55], v[110:113]
	s_waitcnt vmcnt(11)
	s_waitcnt lgkmcnt(1)
	v_mfma_f32_16x16x32_bf16 v[118:121], v[176:179], v[40:43], v[118:121]
	s_waitcnt vmcnt(10)
	ds_read_b128 v[172:175], v163 offset:256
	v_mfma_f32_16x16x32_bf16 v[66:69], v[176:179], v[44:47], v[110:113]
	s_waitcnt vmcnt(9)
	s_waitcnt lgkmcnt(1)
	s_nop 1
	v_mfma_f32_16x16x32_bf16 v[118:121], v[168:171], v[32:35], v[118:121]
	s_waitcnt vmcnt(8)
	ds_read_b128 v[176:179], v163 offset:320
	v_mfma_f32_16x16x32_bf16 v[66:69], v[168:171], v[36:39], v[66:69]
	s_waitcnt vmcnt(7)
	s_waitcnt lgkmcnt(1)
	v_mfma_f32_16x16x32_bf16 v[118:121], v[172:175], v[24:27], v[118:121]
	s_waitcnt vmcnt(6)
	v_mfma_f32_16x16x32_bf16 v[66:69], v[172:175], v[28:31], v[66:69]
	ds_read_b128 v[110:113], v163 offset:384
	s_waitcnt vmcnt(5)
	s_waitcnt lgkmcnt(1)
	v_mfma_f32_16x16x32_bf16 v[118:121], v[176:179], v[20:23], v[118:121]
	s_waitcnt vmcnt(4)
	ds_read_b128 v[168:171], v163 offset:448
	v_mfma_f32_16x16x32_bf16 v[66:69], v[176:179], v[8:11], v[66:69]
	s_waitcnt vmcnt(3)
	s_waitcnt lgkmcnt(1)
	v_mfma_f32_16x16x32_bf16 v[118:121], v[110:113], v[16:19], v[118:121]
	s_waitcnt vmcnt(2)
	v_mfma_f32_16x16x32_bf16 v[64:67], v[110:113], v[4:7], v[66:69]
	s_nop 2
	v_ldexp_f32 v68, v125, v128
	v_cndmask_b32_e64 v109, 0, v68, s[6:7]
	s_waitcnt vmcnt(1)
	s_waitcnt lgkmcnt(0)
	v_mfma_f32_16x16x32_bf16 v[68:71], v[168:171], v[12:15], v[118:121]
	v_cmp_nlt_f32_e64 s[6:7], s36, v124
	s_waitcnt vmcnt(0)
	v_mfma_f32_16x16x32_bf16 v[64:67], v[168:171], v[0:3], v[64:67]
	v_cndmask_b32_e64 v110, v159, v109, s[6:7]
	s_cselect_b64 s[6:7], -1, 0
	s_cmp_eq_u32 s4, 2
	s_nop 1
	v_cndmask_b32_e64 v109, v68, v69, s[6:7]
	s_cselect_b64 s[10:11], -1, 0
	s_cmp_eq_u32 s4, 3
	v_cndmask_b32_e64 v112, v64, v65, s[6:7]
	v_cndmask_b32_e64 v109, v109, v70, s[10:11]
	s_cselect_b64 s[6:7], -1, 0
	v_cndmask_b32_e64 v112, v112, v66, s[10:11]
	s_cmp_eq_u32 s5, 1
	v_cndmask_b32_e64 v120, v109, v71, s[6:7]
	v_cndmask_b32_e64 v121, v112, v67, s[6:7]
	s_cselect_b64 s[6:7], -1, 0
	s_cmp_eq_u32 s5, 2
	v_cndmask_b32_e64 v109, v68, v69, s[6:7]
	s_cselect_b64 s[10:11], -1, 0
	s_cmp_eq_u32 s5, 3
	v_cndmask_b32_e64 v109, v109, v70, s[10:11]
	v_cndmask_b32_e64 v112, v64, v65, s[6:7]
	s_cselect_b64 s[6:7], -1, 0
	v_cndmask_b32_e64 v136, v109, v71, s[6:7]
	v_cndmask_b32_e64 v109, v112, v66, s[10:11]
	s_cmp_eq_u32 s28, 1
	v_cndmask_b32_e64 v137, v109, v67, s[6:7]
	s_cselect_b64 s[6:7], -1, 0
	s_cmp_eq_u32 s28, 2
	v_cndmask_b32_e64 v109, v68, v69, s[6:7]
	s_cselect_b64 s[10:11], -1, 0
	s_cmp_eq_u32 s28, 3
	v_cndmask_b32_e64 v109, v109, v70, s[10:11]
	s_cselect_b64 s[12:13], -1, 0
	s_cmp_eq_u32 s29, 1
	v_cndmask_b32_e64 v131, v109, v71, s[12:13]
	v_cndmask_b32_e64 v109, v64, v65, s[6:7]
	s_cselect_b64 s[6:7], -1, 0
	s_cmp_eq_u32 s29, 2
	v_cndmask_b32_e64 v109, v109, v66, s[10:11]
	v_cndmask_b32_e64 v68, v68, v69, s[6:7]
	s_cselect_b64 s[10:11], -1, 0
	s_cmp_eq_u32 s29, 3
	v_cndmask_b32_e64 v64, v64, v65, s[6:7]
	v_cndmask_b32_e64 v130, v109, v67, s[12:13]
	v_cndmask_b32_e64 v68, v68, v70, s[10:11]
	s_cselect_b64 s[12:13], -1, 0
	v_cndmask_b32_e64 v64, v64, v66, s[10:11]
	v_pk_mul_f32 v[110:111], v[110:111], v[122:123] op_sel_hi:[0,1]
	v_cndmask_b32_e64 v70, v68, v71, s[12:13]
	v_cndmask_b32_e64 v71, v64, v67, s[12:13]
	v_mov_b32_e32 v66, v121
	v_mov_b32_e32 v67, v120
	v_pk_mul_f32 v[64:65], v[110:111], v[120:121]
	v_pk_mul_f32 v[66:67], v[110:111], v[66:67]
	v_sub_f32_e32 v64, v64, v65
	v_add_f32_e32 v65, v67, v66
	v_add_f32_e32 v66, v137, v65
	v_add_f32_e32 v64, v136, v64
	v_pk_mul_f32 v[66:67], v[110:111], v[66:67] op_sel_hi:[1,0]
	v_xor_b32_e32 v112, 0x80000000, v111
	v_pk_fma_f32 v[68:69], v[110:111], v[64:65], v[66:67] op_sel:[1,0,0] op_sel_hi:[0,1,1]
	v_pk_fma_f32 v[64:65], v[110:111], v[64:65], v[66:67] op_sel:[1,0,0] op_sel_hi:[0,0,1] neg_lo:[0,0,1] neg_hi:[0,0,1]
	v_mov_b32_e32 v69, v65
	v_pk_add_f32 v[64:65], v[130:131], v[68:69]
	v_mov_b32_e32 v113, v110
	v_pk_mul_f32 v[66:67], v[110:111], v[64:65] op_sel:[0,1] op_sel_hi:[1,0]
	v_pk_mul_f32 v[64:65], v[110:111], v[64:65]
	v_sub_f32_e32 v66, v66, v67
	v_add_f32_e32 v64, v64, v65
	v_add_f32_e32 v64, v71, v64
	v_add_f32_e32 v66, v70, v66
	ds_bpermute_b32 v123, v153, v64
	ds_bpermute_b32 v119, v154, v64
	ds_bpermute_b32 v117, v155, v64
	ds_bpermute_b32 v125, v156, v64
	v_lshl_add_u64 v[64:65], s[22:23], 0, v[74:75]
	ds_bpermute_b32 v122, v153, v66
	ds_bpermute_b32 v118, v154, v66
	ds_bpermute_b32 v116, v155, v66
	ds_bpermute_b32 v124, v156, v66
	v_lshl_add_u64 v[66:67], v[64:65], 0, v[82:83]
	v_lshl_add_u64 v[68:69], v[64:65], 0, v[84:85]
	global_load_dwordx4 v[64:67], v[66:67], off
	global_load_dwordx4 v[68:71], v[68:69], off
	v_pk_mul_f32 v[112:113], v[110:111], v[112:113] op_sel:[1,0]
	v_pk_mov_b32 v[114:115], v[110:111], v[110:111] op_sel:[1,0]
	v_pk_fma_f32 v[112:113], v[110:111], v[110:111], v[112:113] op_sel_hi:[0,1,1]
	v_xor_b32_e32 v126, 0x80000000, v113
	v_mov_b32_e32 v127, v112
	v_pk_mul_f32 v[126:127], v[112:113], v[126:127] op_sel:[1,0]
	v_cmp_lt_i32_e64 s[6:7], 0, v151
	v_pk_fma_f32 v[112:113], v[112:113], v[112:113], v[126:127] op_sel_hi:[1,0,1]
	s_mov_b64 s[10:11], 0
	v_mul_f32_e32 v109, 0, v112
	v_mul_f32_e32 v127, 0, v113
	v_sub_f32_e32 v126, v109, v127
	v_fmac_f32_e32 v127, 0, v112
	s_waitcnt lgkmcnt(3)
	v_pk_add_f32 v[122:123], v[126:127], v[122:123]
	s_and_saveexec_b64 s[12:13], s[6:7]
	s_xor_b64 s[12:13], exec, s[12:13]
	s_cbranch_execz .LBB0_3102
	v_cmp_eq_u32_e64 s[6:7], 1, v151
	s_mov_b64 s[10:11], -1
	s_and_saveexec_b64 s[14:15], s[6:7]
	s_xor_b64 s[10:11], exec, -1
	v_mov_b32_e32 v133, v123
	v_mov_b32_e32 v132, v122
	s_or_b64 exec, exec, s[14:15]
	s_and_b64 s[10:11], s[10:11], exec

.LBB0_3108:
	s_add_i32 s10, s40, -2
	s_and_b32 s10, s10, 2
	s_add_i32 s10, s10, s0
	s_mulk_i32 s10, 0x2100
	v_add_u32_e32 v109, s10, v150
	ds_read_b128 v[168:171], v109
	ds_read_b128 v[172:175], v109 offset:64
	ds_read_b128 v[176:179], v109 offset:128
	ds_read_b128 v[180:183], v109 offset:192
	ds_read_b128 v[184:187], v109 offset:256
	ds_read_b128 v[188:191], v109 offset:320
	ds_read_b128 v[192:195], v109 offset:384
	ds_read_b128 v[196:199], v109 offset:448
	s_cmp_eq_u32 s4, 1
	s_cselect_b64 s[10:11], -1, 0
	s_cmp_eq_u32 s4, 2
	s_cselect_b64 s[12:13], -1, 0
	s_cmp_eq_u32 s4, 3
	s_cselect_b64 s[14:15], -1, 0
	s_cmp_eq_u32 s5, 1
	s_waitcnt lgkmcnt(7)
	v_mfma_f32_16x16x32_bf16 v[68:71], v[168:171], v[56:59], 0
	v_mfma_f32_16x16x32_bf16 v[64:67], v[168:171], v[60:63], 0
	s_waitcnt lgkmcnt(6)
	v_mfma_f32_16x16x32_bf16 v[68:71], v[172:175], v[48:51], v[68:71]
	v_mfma_f32_16x16x32_bf16 v[64:67], v[172:175], v[52:55], v[64:67]
	s_waitcnt lgkmcnt(5)
	s_nop 0
	v_mfma_f32_16x16x32_bf16 v[68:71], v[176:179], v[40:43], v[68:71]
	v_mfma_f32_16x16x32_bf16 v[64:67], v[176:179], v[44:47], v[64:67]
	s_waitcnt lgkmcnt(4)
	s_nop 0
	v_mfma_f32_16x16x32_bf16 v[68:71], v[180:183], v[32:35], v[68:71]
	v_mfma_f32_16x16x32_bf16 v[64:67], v[180:183], v[36:39], v[64:67]
	s_waitcnt lgkmcnt(3)
	s_nop 0
	v_mfma_f32_16x16x32_bf16 v[68:71], v[184:187], v[24:27], v[68:71]
	v_mfma_f32_16x16x32_bf16 v[64:67], v[184:187], v[28:31], v[64:67]
	s_waitcnt lgkmcnt(2)
	s_nop 0
	v_mfma_f32_16x16x32_bf16 v[68:71], v[188:191], v[20:23], v[68:71]
	v_mfma_f32_16x16x32_bf16 v[64:67], v[188:191], v[8:11], v[64:67]
	s_waitcnt lgkmcnt(1)
	s_nop 0
	v_mfma_f32_16x16x32_bf16 v[68:71], v[192:195], v[16:19], v[68:71]
	v_mfma_f32_16x16x32_bf16 v[64:67], v[192:195], v[4:7], v[64:67]
	s_waitcnt lgkmcnt(0)
	s_nop 0
	v_mfma_f32_16x16x32_bf16 v[68:71], v[196:199], v[12:15], v[68:71]
	s_nop 7
	v_cndmask_b32_e64 v109, v68, v69, s[10:11]
	v_mfma_f32_16x16x32_bf16 v[64:67], v[196:199], v[0:3], v[64:67]
	v_cndmask_b32_e64 v109, v109, v70, s[12:13]
	v_cndmask_b32_e64 v138, v109, v71, s[14:15]
	s_nop 5
	v_cndmask_b32_e64 v109, v64, v65, s[10:11]
	v_cndmask_b32_e64 v109, v109, v66, s[12:13]
	s_cselect_b64 s[10:11], -1, 0
	s_cmp_eq_u32 s5, 2
	v_cndmask_b32_e64 v139, v109, v67, s[14:15]
	v_cndmask_b32_e64 v109, v68, v69, s[10:11]
	s_cselect_b64 s[12:13], -1, 0
	s_cmp_eq_u32 s5, 3
	v_cndmask_b32_e64 v109, v109, v70, s[12:13]
	s_cselect_b64 s[14:15], -1, 0
	s_cmp_eq_u32 s28, 1
	v_cndmask_b32_e64 v121, v109, v71, s[14:15]
	v_cndmask_b32_e64 v109, v64, v65, s[10:11]
	s_cselect_b64 s[10:11], -1, 0
	s_cmp_eq_u32 s28, 2
	v_cndmask_b32_e64 v109, v109, v66, s[12:13]
	v_cndmask_b32_e64 v136, v68, v69, s[10:11]
	s_cselect_b64 s[12:13], -1, 0
	s_cmp_eq_u32 s28, 3
	v_cndmask_b32_e64 v109, v109, v67, s[14:15]
	v_cndmask_b32_e64 v136, v136, v70, s[12:13]
	s_cselect_b64 s[14:15], -1, 0
	s_cmp_eq_u32 s29, 1
	v_cndmask_b32_e64 v137, v136, v71, s[14:15]
	v_cndmask_b32_e64 v136, v64, v65, s[10:11]
	s_cselect_b64 s[10:11], -1, 0
	s_cmp_eq_u32 s29, 2
	v_cndmask_b32_e64 v136, v136, v66, s[12:13]
	v_cndmask_b32_e64 v68, v68, v69, s[10:11]
	s_cselect_b64 s[12:13], -1, 0
	s_cmp_eq_u32 s29, 3
	v_cndmask_b32_e64 v64, v64, v65, s[10:11]
	v_cndmask_b32_e64 v136, v136, v67, s[14:15]
	v_cndmask_b32_e64 v68, v68, v70, s[12:13]
	s_cselect_b64 s[14:15], -1, 0
	v_cndmask_b32_e64 v64, v64, v66, s[12:13]
	v_cndmask_b32_e64 v70, v68, v71, s[14:15]
	v_cndmask_b32_e64 v71, v64, v67, s[14:15]
	v_mov_b32_e32 v66, v139
	v_mov_b32_e32 v67, v138
	v_pk_mul_f32 v[64:65], v[110:111], v[138:139]
	v_pk_mul_f32 v[66:67], v[110:111], v[66:67]
	v_sub_f32_e32 v64, v64, v65
	v_add_f32_e32 v65, v67, v66
	v_add_f32_e32 v66, v109, v65
	v_add_f32_e32 v64, v121, v64
	v_pk_mul_f32 v[66:67], v[110:111], v[66:67] op_sel_hi:[1,0]
	v_cmp_lt_i32_e64 s[10:11], 0, v151
	v_pk_fma_f32 v[68:69], v[114:115], v[64:65], v[66:67]
	v_pk_fma_f32 v[64:65], v[114:115], v[64:65], v[66:67] op_sel_hi:[1,0,1] neg_lo:[0,0,1] neg_hi:[0,0,1]
	s_mov_b64 s[12:13], 0
	v_mov_b32_e32 v69, v65
	v_pk_add_f32 v[64:65], v[136:137], v[68:69]
	s_nop 0
	v_pk_mul_f32 v[66:67], v[110:111], v[64:65] op_sel:[0,1] op_sel_hi:[1,0]
	v_pk_mul_f32 v[64:65], v[110:111], v[64:65]
	v_sub_f32_e32 v66, v66, v67
	v_add_f32_e32 v64, v64, v65
	v_add_f32_e32 v66, v70, v66
	v_add_f32_e32 v64, v71, v64
	ds_bpermute_b32 v146, v153, v66
	ds_bpermute_b32 v147, v153, v64
	ds_bpermute_b32 v144, v154, v66
	ds_bpermute_b32 v145, v154, v64
	ds_bpermute_b32 v142, v155, v66
	ds_bpermute_b32 v143, v155, v64
	ds_bpermute_b32 v140, v156, v66
	ds_bpermute_b32 v141, v156, v64
	global_load_dwordx4 v[64:67], v[134:135], off
	global_load_dwordx4 v[68:71], v[132:133], off
	s_and_saveexec_b64 s[14:15], s[10:11]
	s_xor_b64 s[14:15], exec, s[14:15]
	s_cbranch_execz .LBB0_3112
	v_cmp_eq_u32_e64 s[10:11], 1, v151
	s_mov_b64 s[12:13], -1
	s_and_saveexec_b64 s[26:27], s[10:11]
	s_xor_b64 s[12:13], exec, -1
	s_or_b64 exec, exec, s[26:27]
	s_and_b64 s[12:13], s[12:13], exec

.LBB0_3116:
	ds_read_b128 v[64:67], v163
	ds_read_b128 v[68:71], v163 offset:64
	s_cmp_eq_u32 s4, 1
	s_cselect_b64 s[10:11], -1, 0
	s_cmp_eq_u32 s4, 2
	s_waitcnt lgkmcnt(1)
	v_mfma_f32_16x16x32_bf16 v[56:59], v[64:67], v[56:59], 0
	s_cselect_b64 s[12:13], -1, 0
	s_cmp_eq_u32 s4, 3
	s_cselect_b64 s[14:15], -1, 0
	v_mfma_f32_16x16x32_bf16 v[60:63], v[64:67], v[60:63], 0
	s_cmp_eq_u32 s5, 1
	s_waitcnt lgkmcnt(0)
	v_mfma_f32_16x16x32_bf16 v[48:51], v[68:71], v[48:51], v[56:59]
	v_mfma_f32_16x16x32_bf16 v[52:55], v[68:71], v[52:55], v[60:63]
	ds_read_b128 v[56:59], v163 offset:128
	ds_read_b128 v[60:63], v163 offset:192
	s_waitcnt lgkmcnt(1)
	s_nop 2
	v_mfma_f32_16x16x32_bf16 v[40:43], v[56:59], v[40:43], v[48:51]
	v_mfma_f32_16x16x32_bf16 v[44:47], v[56:59], v[44:47], v[52:55]
	s_waitcnt lgkmcnt(0)
	v_mfma_f32_16x16x32_bf16 v[32:35], v[60:63], v[32:35], v[40:43]
	v_mfma_f32_16x16x32_bf16 v[36:39], v[60:63], v[36:39], v[44:47]
	ds_read_b128 v[40:43], v163 offset:256
	ds_read_b128 v[44:47], v163 offset:320
	s_waitcnt lgkmcnt(1)
	s_nop 3
	v_mfma_f32_16x16x32_bf16 v[24:27], v[40:43], v[24:27], v[32:35]
	ds_read_b128 v[32:35], v163 offset:384
	s_nop 2
	v_mfma_f32_16x16x32_bf16 v[28:31], v[40:43], v[28:31], v[36:39]
	s_waitcnt lgkmcnt(1)
	v_mfma_f32_16x16x32_bf16 v[20:23], v[44:47], v[20:23], v[24:27]
	ds_read_b128 v[24:27], v163 offset:448
	s_nop 2
	v_mfma_f32_16x16x32_bf16 v[8:11], v[44:47], v[8:11], v[28:31]
	s_waitcnt lgkmcnt(1)
	v_mfma_f32_16x16x32_bf16 v[6:9], v[32:35], v[4:7], v[8:11]
	v_mfma_f32_16x16x32_bf16 v[16:19], v[32:35], v[16:19], v[20:23]
	s_waitcnt lgkmcnt(0)
	v_mfma_f32_16x16x32_bf16 v[8:11], v[24:27], v[0:3], v[6:9]
	v_mfma_f32_16x16x32_bf16 v[12:15], v[24:27], v[12:15], v[16:19]
	s_nop 6
	v_cndmask_b32_e64 v0, v8, v9, s[10:11]
	v_cndmask_b32_e64 v16, v12, v13, s[10:11]
	v_cndmask_b32_e64 v0, v0, v10, s[12:13]
	s_cselect_b64 s[10:11], -1, 0
	s_cmp_eq_u32 s5, 2
	v_cndmask_b32_e64 v16, v16, v14, s[12:13]
	v_cndmask_b32_e64 v6, v0, v11, s[14:15]
	v_cndmask_b32_e64 v0, v12, v13, s[10:11]
	s_cselect_b64 s[12:13], -1, 0
	s_cmp_eq_u32 s5, 3
	v_cndmask_b32_e64 v4, v16, v15, s[14:15]
	v_cndmask_b32_e64 v0, v0, v14, s[12:13]
	s_cselect_b64 s[14:15], -1, 0
	v_cndmask_b32_e64 v3, v0, v15, s[14:15]
	v_cndmask_b32_e64 v0, v8, v9, s[10:11]
	s_cmp_eq_u32 s28, 1
	v_cndmask_b32_e64 v0, v0, v10, s[12:13]
	s_cselect_b64 s[10:11], -1, 0
	s_cmp_eq_u32 s28, 2
	v_cndmask_b32_e64 v2, v0, v11, s[14:15]
	v_cndmask_b32_e64 v0, v12, v13, s[10:11]
	s_cselect_b64 s[12:13], -1, 0
	s_cmp_eq_u32 s28, 3
	v_cndmask_b32_e64 v0, v0, v14, s[12:13]
	s_cselect_b64 s[14:15], -1, 0
	s_cmp_eq_u32 s29, 1
	v_cndmask_b32_e64 v1, v0, v15, s[14:15]
	v_cndmask_b32_e64 v0, v8, v9, s[10:11]
	s_cselect_b64 s[10:11], -1, 0
	s_cmp_eq_u32 s29, 2
	v_cndmask_b32_e64 v0, v0, v10, s[12:13]
	s_cselect_b64 s[12:13], -1, 0
	s_cmp_eq_u32 s29, 3
	v_cndmask_b32_e64 v7, v8, v9, s[10:11]
	v_cndmask_b32_e64 v0, v0, v11, s[14:15]
	v_cndmask_b32_e64 v5, v12, v13, s[10:11]
	s_cselect_b64 s[14:15], -1, 0
	v_cndmask_b32_e64 v7, v7, v10, s[12:13]
	v_cndmask_b32_e64 v5, v5, v14, s[12:13]
	v_cndmask_b32_e64 v7, v7, v11, s[14:15]
	v_cndmask_b32_e64 v5, v5, v15, s[14:15]
	v_pk_mul_f32 v[8:9], v[110:111], v[6:7] op_sel_hi:[1,0]
	v_cmp_lt_i32_e64 s[10:11], 0, v151
	v_pk_fma_f32 v[10:11], v[114:115], v[4:5], v[8:9]
	v_pk_fma_f32 v[8:9], v[114:115], v[4:5], v[8:9] op_sel_hi:[1,0,1] neg_lo:[0,0,1] neg_hi:[0,0,1]
	s_mov_b64 s[12:13], 0
	v_mov_b32_e32 v11, v9
	v_pk_add_f32 v[8:9], v[2:3], v[10:11]
	s_nop 0
	v_pk_mul_f32 v[10:11], v[128:129], v[8:9] op_sel:[0,1] op_sel_hi:[1,0]
	s_nop 0
	v_pk_fma_f32 v[12:13], v[126:127], v[8:9], v[10:11]
	v_pk_fma_f32 v[8:9], v[126:127], v[8:9], v[10:11] neg_lo:[0,0,1] neg_hi:[0,0,1]
	s_nop 0
	v_mov_b32_e32 v13, v9
	v_pk_add_f32 v[8:9], v[0:1], v[12:13]
	s_nop 0
	v_pk_mul_f32 v[10:11], v[110:111], v[8:9] op_sel:[0,1] op_sel_hi:[1,0]
	v_pk_mul_f32 v[8:9], v[110:111], v[8:9]
	v_sub_f32_e32 v10, v10, v11
	v_add_f32_e32 v8, v8, v9
	v_add_f32_e32 v5, v5, v10
	v_add_f32_e32 v7, v7, v8
	ds_bpermute_b32 v12, v153, v5
	ds_bpermute_b32 v13, v153, v7
	ds_bpermute_b32 v10, v154, v5
	ds_bpermute_b32 v11, v154, v7
	ds_bpermute_b32 v8, v155, v5
	ds_bpermute_b32 v9, v155, v7
	s_and_saveexec_b64 s[14:15], s[10:11]
	s_xor_b64 s[14:15], exec, s[14:15]
	s_cbranch_execz .LBB0_3120
	v_cmp_eq_u32_e64 s[10:11], 1, v151
	s_mov_b64 s[12:13], -1
	s_and_saveexec_b64 s[26:27], s[10:11]
	s_xor_b64 s[12:13], exec, -1
	s_or_b64 exec, exec, s[26:27]
	s_and_b64 s[12:13], s[12:13], exec

.LBB0_3178:
	ds_read_b128 v[128:131], v170
	ds_read_b128 v[132:135], v170 offset:64
	s_addk_i32 s35, 0x2000
	s_add_i32 s31, s31, s33
	s_add_i32 s4, s4, s5
	s_waitcnt lgkmcnt(1)
	v_mfma_f32_16x16x32_bf16 v[96:99], v[128:131], v[96:99], 0
	s_cmpk_gt_i32 s31, 0xff
	v_mfma_f32_16x16x32_bf16 v[120:123], v[128:131], v[120:123], 0
	s_waitcnt lgkmcnt(0)
	v_mfma_f32_16x16x32_bf16 v[92:95], v[132:135], v[92:95], v[96:99]
	v_mfma_f32_16x16x32_bf16 v[96:99], v[132:135], v[116:119], v[120:123]
	ds_read_b128 v[116:119], v170 offset:128
	ds_read_b128 v[120:123], v170 offset:192
	s_waitcnt lgkmcnt(1)
	s_nop 3
	v_mfma_f32_16x16x32_bf16 v[80:83], v[116:119], v[80:83], v[92:95]
	v_mfma_f32_16x16x32_bf16 v[92:95], v[116:119], v[112:115], v[96:99]
	s_waitcnt lgkmcnt(0)
	v_mfma_f32_16x16x32_bf16 v[76:79], v[120:123], v[76:79], v[80:83]
	v_mfma_f32_16x16x32_bf16 v[80:83], v[120:123], v[108:111], v[92:95]
	ds_read_b128 v[92:95], v170 offset:256
	ds_read_b128 v[96:99], v170 offset:320
	s_waitcnt lgkmcnt(1)
	s_nop 4
	v_mfma_f32_16x16x32_bf16 v[72:75], v[92:95], v[72:75], v[76:79]
	v_mfma_f32_16x16x32_bf16 v[76:79], v[92:95], v[104:107], v[80:83]
	s_waitcnt lgkmcnt(0)
	v_mfma_f32_16x16x32_bf16 v[64:67], v[96:99], v[64:67], v[72:75]
	v_mfma_f32_16x16x32_bf16 v[72:75], v[96:99], v[100:103], v[76:79]
	ds_read_b128 v[76:79], v170 offset:384
	ds_read_b128 v[80:83], v170 offset:448
	s_waitcnt lgkmcnt(1)
	s_nop 4
	v_mfma_f32_16x16x32_bf16 v[56:59], v[76:79], v[56:59], v[64:67]
	v_mfma_f32_16x16x32_bf16 v[64:67], v[76:79], v[88:91], v[72:75]
	s_waitcnt lgkmcnt(0)
	v_mfma_f32_16x16x32_bf16 v[48:51], v[80:83], v[48:51], v[56:59]
	v_mfma_f32_16x16x32_bf16 v[56:59], v[80:83], v[84:87], v[64:67]
	ds_read_b128 v[64:67], v170 offset:512
	ds_read_b128 v[72:75], v170 offset:576
	s_waitcnt lgkmcnt(1)
	s_nop 4
	v_mfma_f32_16x16x32_bf16 v[40:43], v[64:67], v[40:43], v[48:51]
	v_mfma_f32_16x16x32_bf16 v[48:51], v[64:67], v[124:127], v[56:59]
	ds_read_b128 v[56:59], v170 offset:640
	s_waitcnt lgkmcnt(1)
	s_nop 2
	v_mfma_f32_16x16x32_bf16 v[28:31], v[72:75], v[28:31], v[40:43]
	ds_read_b128 v[40:43], v170 offset:704
	s_waitcnt lgkmcnt(1)
	s_nop 2
	v_mfma_f32_16x16x32_bf16 v[20:23], v[56:59], v[20:23], v[28:31]
	ds_read_b128 v[28:31], v170 offset:768
	s_waitcnt lgkmcnt(1)
	s_nop 2
	v_mfma_f32_16x16x32_bf16 v[16:19], v[40:43], v[16:19], v[20:23]
	ds_read_b128 v[20:23], v170 offset:832
	s_waitcnt lgkmcnt(1)
	s_nop 2
	v_mfma_f32_16x16x32_bf16 v[12:15], v[28:31], v[12:15], v[16:19]
	ds_read_b128 v[16:19], v170 offset:896
	s_waitcnt lgkmcnt(1)
	s_nop 2
	v_mfma_f32_16x16x32_bf16 v[8:11], v[20:23], v[8:11], v[12:15]
	ds_read_b128 v[12:15], v170 offset:960
	s_waitcnt lgkmcnt(1)
	s_nop 2
	v_mfma_f32_16x16x32_bf16 v[0:3], v[16:19], v[0:3], v[8:11]
	s_nop 2
	v_add_u32_e32 v9, s35, v172
	s_waitcnt lgkmcnt(0)
	v_mfma_f32_16x16x32_bf16 v[0:3], v[12:15], v[4:7], v[0:3]
	v_mfma_f32_16x16x32_bf16 v[4:7], v[72:75], v[68:71], v[48:51]
	s_nop 6
	v_mul_f32_e32 v8, 0x3d372713, v0
	v_mul_f32_e32 v8, v0, v8
	v_fma_f32 v8, v0, v8, v0
	v_mfma_f32_16x16x32_bf16 v[4:7], v[56:59], v[60:63], v[4:7]
	v_mul_f32_e32 v8, 0x3f4c422a, v8
	v_add_f32_e32 v8, v8, v8
	v_mul_f32_e32 v8, 0x3fb8aa3b, v8
	v_mfma_f32_16x16x32_bf16 v[4:7], v[40:43], v[52:55], v[4:7]
	v_exp_f32_e32 v8, v8
	v_mul_f32_e32 v0, 0.5, v0
	v_add_f32_e32 v8, 1.0, v8
	v_mfma_f32_16x16x32_bf16 v[4:7], v[28:31], v[44:47], v[4:7]
	v_rcp_f32_e32 v10, v8
	v_add_u32_e32 v8, s34, v173
	v_cndmask_b32_e64 v8, v8, v9, s[20:21]
	v_mfma_f32_16x16x32_bf16 v[4:7], v[20:23], v[36:39], v[4:7]
	v_fma_f32 v9, v10, -2.0, 1.0
	v_add_f32_e32 v9, 1.0, v9
	v_mul_f32_e32 v0, v0, v9
	v_mfma_f32_16x16x32_bf16 v[4:7], v[16:19], v[32:35], v[4:7]
	v_ashrrev_i32_e32 v9, 31, v8
	v_lshlrev_b64 v[8:9], 12, v[8:9]
	v_cvt_pk_bf16_f32 v0, v0, s0
	v_mfma_f32_16x16x32_bf16 v[4:7], v[12:15], v[24:27], v[4:7]
	v_lshl_add_u64 v[8:9], v[162:163], 0, v[8:9]
	global_store_short v[8:9], v0, off
	v_add_u32_e32 v8, s35, v174
	v_add_u32_e32 v9, s34, v175
	v_cndmask_b32_e64 v8, v9, v8, s[6:7]
	s_nop 2
	v_mul_f32_e32 v10, 0x3d372713, v4
	v_mul_f32_e32 v10, v4, v10
	v_fma_f32 v10, v4, v10, v4
	v_mul_f32_e32 v10, 0x3f4c422a, v10
	v_add_f32_e32 v10, v10, v10
	v_mul_f32_e32 v10, 0x3fb8aa3b, v10
	v_exp_f32_e32 v10, v10
	v_mul_f32_e32 v4, 0.5, v4
	v_ashrrev_i32_e32 v9, 31, v8
	v_lshlrev_b64 v[8:9], 12, v[8:9]
	v_add_f32_e32 v0, 1.0, v10
	v_rcp_f32_e32 v0, v0
	v_lshl_add_u64 v[8:9], v[162:163], 0, v[8:9]
	v_fma_f32 v0, v0, -2.0, 1.0
	v_add_f32_e32 v0, 1.0, v0
	v_mul_f32_e32 v0, v4, v0
	v_mul_f32_e32 v4, 0x3d372713, v1
	v_mul_f32_e32 v4, v1, v4
	v_fma_f32 v4, v1, v4, v1
	v_mul_f32_e32 v4, 0x3f4c422a, v4
	v_add_f32_e32 v4, v4, v4
	v_mul_f32_e32 v4, 0x3fb8aa3b, v4
	v_exp_f32_e32 v4, v4
	v_cvt_pk_bf16_f32 v0, v0, s0
	global_store_short v[8:9], v0, off
	v_add_u32_e32 v8, s34, v177
	v_add_f32_e32 v0, 1.0, v4
	v_rcp_f32_e32 v4, v0
	v_add_u32_e32 v0, s35, v176
	v_cndmask_b32_e64 v0, v8, v0, s[8:9]
	v_mul_f32_e32 v8, 0x3d372713, v5
	v_mul_f32_e32 v8, v5, v8
	v_fma_f32 v8, v5, v8, v5
	v_mul_f32_e32 v8, 0x3f4c422a, v8
	v_fma_f32 v4, v4, -2.0, 1.0
	v_add_f32_e32 v8, v8, v8
	v_mul_f32_e32 v1, 0.5, v1
	v_add_f32_e32 v4, 1.0, v4
	v_mul_f32_e32 v8, 0x3fb8aa3b, v8
	v_mul_f32_e32 v1, v1, v4
	v_exp_f32_e32 v8, v8
	v_cvt_pk_bf16_f32 v4, v1, s0
	v_ashrrev_i32_e32 v1, 31, v0
	v_lshlrev_b64 v[0:1], 12, v[0:1]
	v_lshl_add_u64 v[0:1], v[162:163], 0, v[0:1]
	global_store_short v[0:1], v4, off
	v_add_f32_e32 v0, 1.0, v8
	v_rcp_f32_e32 v1, v0
	v_add_u32_e32 v0, s35, v178
	v_add_u32_e32 v4, s34, v179
	v_cndmask_b32_e64 v0, v4, v0, s[10:11]
	v_mul_f32_e32 v4, 0.5, v5
	v_mul_f32_e32 v5, 0x3d372713, v2
	v_mul_f32_e32 v5, v2, v5
	v_fma_f32 v5, v2, v5, v2
	v_mul_f32_e32 v5, 0x3f4c422a, v5
	v_fma_f32 v1, v1, -2.0, 1.0
	v_add_f32_e32 v5, v5, v5
	v_add_f32_e32 v1, 1.0, v1
	v_mul_f32_e32 v5, 0x3fb8aa3b, v5
	v_mul_f32_e32 v1, v4, v1
	v_exp_f32_e32 v5, v5
	v_cvt_pk_bf16_f32 v4, v1, s0
	v_ashrrev_i32_e32 v1, 31, v0
	v_lshlrev_b64 v[0:1], 12, v[0:1]
	v_lshl_add_u64 v[0:1], v[162:163], 0, v[0:1]
	global_store_short v[0:1], v4, off
	v_add_f32_e32 v0, 1.0, v5
	v_rcp_f32_e32 v1, v0
	v_add_u32_e32 v0, s35, v180
	v_add_u32_e32 v4, s34, v181
	v_cndmask_b32_e64 v0, v4, v0, s[12:13]
	v_mul_f32_e32 v4, 0x3d372713, v6
	v_mul_f32_e32 v4, v6, v4
	v_fma_f32 v4, v6, v4, v6
	v_mul_f32_e32 v4, 0x3f4c422a, v4
	v_fma_f32 v1, v1, -2.0, 1.0
	v_add_f32_e32 v4, v4, v4
	v_mul_f32_e32 v2, 0.5, v2
	v_add_f32_e32 v1, 1.0, v1
	v_mul_f32_e32 v4, 0x3fb8aa3b, v4
	v_mul_f32_e32 v1, v2, v1
	v_exp_f32_e32 v4, v4
	v_cvt_pk_bf16_f32 v2, v1, s0
	v_ashrrev_i32_e32 v1, 31, v0
	v_lshlrev_b64 v[0:1], 12, v[0:1]
	v_lshl_add_u64 v[0:1], v[162:163], 0, v[0:1]
	global_store_short v[0:1], v2, off
	v_add_f32_e32 v0, 1.0, v4
	v_rcp_f32_e32 v1, v0
	v_mul_f32_e32 v4, 0x3d372713, v3
	v_mul_f32_e32 v4, v3, v4
	v_fma_f32 v4, v3, v4, v3
	v_mul_f32_e32 v4, 0x3f4c422a, v4
	v_add_u32_e32 v0, s35, v182
	v_add_u32_e32 v2, s34, v183
	v_fma_f32 v1, v1, -2.0, 1.0
	v_add_f32_e32 v4, v4, v4
	v_cndmask_b32_e64 v0, v2, v0, s[14:15]
	v_mul_f32_e32 v2, 0.5, v6
	v_add_f32_e32 v1, 1.0, v1
	v_mul_f32_e32 v4, 0x3fb8aa3b, v4
	v_mul_f32_e32 v1, v2, v1
	v_exp_f32_e32 v4, v4
	v_cvt_pk_bf16_f32 v2, v1, s0
	v_ashrrev_i32_e32 v1, 31, v0
	v_lshlrev_b64 v[0:1], 12, v[0:1]
	v_lshl_add_u64 v[0:1], v[162:163], 0, v[0:1]
	global_store_short v[0:1], v2, off
	v_add_f32_e32 v0, 1.0, v4
	v_rcp_f32_e32 v1, v0
	v_add_u32_e32 v0, s35, v184
	v_add_u32_e32 v2, s34, v185
	v_cndmask_b32_e64 v0, v2, v0, s[16:17]
	v_mul_f32_e32 v2, 0.5, v3
	v_mul_f32_e32 v3, 0x3d372713, v7
	v_mul_f32_e32 v3, v7, v3
	v_fma_f32 v3, v7, v3, v7
	v_mul_f32_e32 v3, 0x3f4c422a, v3
	v_fma_f32 v1, v1, -2.0, 1.0
	v_add_f32_e32 v3, v3, v3
	v_add_f32_e32 v1, 1.0, v1
	v_mul_f32_e32 v3, 0x3fb8aa3b, v3
	v_mul_f32_e32 v1, v2, v1
	v_exp_f32_e32 v3, v3
	v_cvt_pk_bf16_f32 v2, v1, s0
	v_ashrrev_i32_e32 v1, 31, v0
	v_lshlrev_b64 v[0:1], 12, v[0:1]
	v_lshl_add_u64 v[0:1], v[162:163], 0, v[0:1]
	global_store_short v[0:1], v2, off
	v_add_f32_e32 v0, 1.0, v3
	v_rcp_f32_e32 v1, v0
	v_add_u32_e32 v0, s35, v186
	v_add_u32_e32 v2, s34, v187
	v_cndmask_b32_e64 v0, v2, v0, s[18:19]
	v_fma_f32 v1, v1, -2.0, 1.0
	v_mul_f32_e32 v2, 0.5, v7
	v_add_f32_e32 v1, 1.0, v1
	v_mul_f32_e32 v1, v2, v1
	v_cvt_pk_bf16_f32 v2, v1, s0
	v_ashrrev_i32_e32 v1, 31, v0
	v_lshlrev_b64 v[0:1], 12, v[0:1]
	v_lshl_add_u64 v[0:1], v[162:163], 0, v[0:1]
	global_store_short v[0:1], v2, off
	s_waitcnt lgkmcnt(0)
	s_barrier
	s_cbranch_scc1 .LBB0_3209

.LBB0_3181:
	s_bitcmp1_b32 s37, 0
	s_cselect_b32 s28, 0x4100, 0
	v_add_u32_e32 v222, s28, v170
	ds_read_b128 v[228:231], v222
	ds_read_b128 v[232:235], v222 offset:64
	v_lshl_add_u64 v[166:167], v[164:165], 0, s[26:27]
	v_add_co_u32_e32 v198, vcc, 0x4000, v166
	s_waitcnt lgkmcnt(1)
	v_mfma_f32_16x16x32_bf16 v[136:139], v[228:231], v[96:99], 0
	v_addc_co_u32_e32 v199, vcc, 0, v167, vcc
	v_add_co_u32_e32 v166, vcc, 0x6000, v166
	v_mfma_f32_16x16x32_bf16 v[128:131], v[228:231], v[120:123], 0
	ds_read_b128 v[228:231], v222 offset:128
	v_addc_co_u32_e32 v167, vcc, 0, v167, vcc
	s_waitcnt lgkmcnt(1)
	v_mfma_f32_16x16x32_bf16 v[136:139], v[232:235], v[92:95], v[136:139]
	v_mfma_f32_16x16x32_bf16 v[128:131], v[232:235], v[116:119], v[128:131]
	ds_read_b128 v[232:235], v222 offset:192
	s_waitcnt lgkmcnt(1)
	s_nop 0
	v_mfma_f32_16x16x32_bf16 v[136:139], v[228:231], v[80:83], v[136:139]
	v_mfma_f32_16x16x32_bf16 v[128:131], v[228:231], v[112:115], v[128:131]
	ds_read_b128 v[228:231], v222 offset:256
	s_waitcnt lgkmcnt(1)
	v_mfma_f32_16x16x32_bf16 v[132:135], v[232:235], v[76:79], v[136:139]
	v_mfma_f32_16x16x32_bf16 v[128:131], v[232:235], v[108:111], v[128:131]
	ds_read_b128 v[232:235], v222 offset:320
	ds_read_b128 v[194:197], v222 offset:512
	s_waitcnt lgkmcnt(2)
	s_nop 4
	v_mfma_f32_16x16x32_bf16 v[132:135], v[228:231], v[72:75], v[132:135]
	v_mfma_f32_16x16x32_bf16 v[128:131], v[228:231], v[104:107], v[128:131]
	ds_read_b128 v[228:231], v222 offset:384
	s_waitcnt lgkmcnt(2)
	v_mfma_f32_16x16x32_bf16 v[132:135], v[232:235], v[64:67], v[132:135]
	v_mfma_f32_16x16x32_bf16 v[128:131], v[232:235], v[100:103], v[128:131]
	ds_read_b128 v[232:235], v222 offset:448
	s_waitcnt lgkmcnt(1)
	v_mfma_f32_16x16x32_bf16 v[132:135], v[228:231], v[56:59], v[132:135]
	v_mfma_f32_16x16x32_bf16 v[136:139], v[228:231], v[88:91], v[128:131]
	s_waitcnt lgkmcnt(0)
	v_mfma_f32_16x16x32_bf16 v[190:193], v[232:235], v[48:51], v[132:135]
	s_nop 1
	global_load_dwordx4 v[128:131], v[198:199], off
	s_nop 1
	global_load_dwordx4 v[132:135], v[166:167], off
	ds_read_b128 v[198:201], v222 offset:576
	ds_read_b128 v[202:205], v222 offset:640
	v_mfma_f32_16x16x32_bf16 v[136:139], v[232:235], v[84:87], v[136:139]
	ds_read_b128 v[206:209], v222 offset:704
	ds_read_b128 v[210:213], v222 offset:768
	ds_read_b128 v[214:217], v222 offset:832
	ds_read_b128 v[218:221], v222 offset:896
	v_mfma_f32_16x16x32_bf16 v[140:143], v[194:197], v[40:43], v[190:193]
	ds_read_b128 v[222:225], v222 offset:960
	s_waitcnt lgkmcnt(6)
	v_mfma_f32_16x16x32_bf16 v[140:143], v[198:201], v[28:31], v[140:143]
	v_add_u32_e32 v191, s36, v171
	v_add_u32_e32 v167, 0xffffff00, v191
	v_add_u32_e32 v190, s36, v189
	s_waitcnt lgkmcnt(5)
	v_mfma_f32_16x16x32_bf16 v[140:143], v[202:205], v[20:23], v[140:143]
	v_lshrrev_b32_e32 v167, 6, v167
	v_add_u32_e32 v166, 0x2000, v190
	v_add_u32_e32 v167, s22, v167
	s_waitcnt lgkmcnt(4)
	v_mfma_f32_16x16x32_bf16 v[140:143], v[206:209], v[16:19], v[140:143]
	v_cmp_gt_i32_e32 vcc, s2, v191
	s_waitcnt lgkmcnt(3)
	v_mfma_f32_16x16x32_bf16 v[140:143], v[210:213], v[12:15], v[140:143]
	v_cndmask_b32_e32 v166, v167, v166, vcc
	s_waitcnt lgkmcnt(2)
	v_mfma_f32_16x16x32_bf16 v[140:143], v[214:217], v[8:11], v[140:143]
	s_waitcnt vmcnt(9)
	v_mfma_f32_16x16x32_bf16 v[136:139], v[194:197], v[124:127], v[136:139]
	s_waitcnt lgkmcnt(1)
	v_mfma_f32_16x16x32_bf16 v[140:143], v[218:221], v[0:3], v[140:143]
	s_waitcnt vmcnt(8)
	v_mfma_f32_16x16x32_bf16 v[136:139], v[198:201], v[68:71], v[136:139]
	s_waitcnt lgkmcnt(0)
	v_mfma_f32_16x16x32_bf16 v[140:143], v[222:225], v[4:7], v[140:143]
	s_waitcnt vmcnt(7)
	v_mfma_f32_16x16x32_bf16 v[136:139], v[202:205], v[60:63], v[136:139]
	s_waitcnt vmcnt(6)
	v_mfma_f32_16x16x32_bf16 v[136:139], v[206:209], v[52:55], v[136:139]
	s_nop 3
	v_mul_f32_e32 v192, 0x3d372713, v140
	v_mul_f32_e32 v192, v140, v192
	v_fma_f32 v192, v140, v192, v140
	v_mul_f32_e32 v192, 0x3f4c422a, v192
	v_add_f32_e32 v192, v192, v192
	v_mul_f32_e32 v192, 0x3fb8aa3b, v192
	v_exp_f32_e32 v192, v192
	s_waitcnt vmcnt(5)
	v_mfma_f32_16x16x32_bf16 v[136:139], v[210:213], v[44:47], v[136:139]
	v_mul_f32_e32 v140, 0.5, v140
	v_add_f32_e32 v192, 1.0, v192
	s_waitcnt vmcnt(4)
	v_mfma_f32_16x16x32_bf16 v[136:139], v[214:217], v[36:39], v[136:139]
	v_rcp_f32_e32 v192, v192
	s_nop 0
	v_fma_f32 v167, v192, -2.0, 1.0
	s_waitcnt vmcnt(3)
	v_mfma_f32_16x16x32_bf16 v[136:139], v[218:221], v[32:35], v[136:139]
	v_add_f32_e32 v167, 1.0, v167
	v_mul_f32_e32 v140, v140, v167
	v_ashrrev_i32_e32 v167, 31, v166
	v_lshlrev_b64 v[166:167], 12, v[166:167]
	s_waitcnt vmcnt(2)
	v_mfma_f32_16x16x32_bf16 v[136:139], v[222:225], v[24:27], v[136:139]
	v_cvt_pk_bf16_f32 v140, v140, s0
	v_lshl_add_u64 v[166:167], v[162:163], 0, v[166:167]
	global_store_short v[166:167], v140, off
	v_add_u32_e32 v140, 1, v191
	v_cmp_lt_i32_e32 vcc, s30, v140
	s_and_saveexec_b64 s[28:29], vcc
	s_xor_b64 s[28:29], exec, s[28:29]
	v_add_u32_e32 v140, 0xffffff01, v191
	v_add3_u32 v166, v158, s26, 64
	v_and_b32_e32 v166, 0xfc0, v166
	v_lshrrev_b32_e32 v140, 6, v140
	v_add3_u32 v166, v140, s34, v166
	s_andn2_saveexec_b64 s[28:29], s[28:29]
	v_add_u32_e32 v166, 0x2001, v190
	s_or_b64 exec, exec, s[28:29]
	v_mul_f32_e32 v140, 0x3d372713, v136
	v_mul_f32_e32 v140, v136, v140
	v_fma_f32 v140, v136, v140, v136
	v_mul_f32_e32 v140, 0x3f4c422a, v140
	v_add_f32_e32 v140, v140, v140
	v_mul_f32_e32 v140, 0x3fb8aa3b, v140
	v_exp_f32_e32 v140, v140
	v_mul_f32_e32 v136, 0.5, v136
	v_ashrrev_i32_e32 v167, 31, v166
	v_lshlrev_b64 v[166:167], 12, v[166:167]
	v_add_f32_e32 v140, 1.0, v140
	v_rcp_f32_e32 v140, v140
	v_add_u32_e32 v192, 16, v191
	v_lshl_add_u64 v[166:167], v[162:163], 0, v[166:167]
	v_cmp_lt_i32_e32 vcc, s30, v192
	v_fma_f32 v140, v140, -2.0, 1.0
	v_add_f32_e32 v140, 1.0, v140
	v_mul_f32_e32 v136, v136, v140
	v_cvt_pk_bf16_f32 v136, v136, s0
	global_store_short v[166:167], v136, off
	v_add_u32_e32 v166, s26, v158
	s_and_saveexec_b64 s[28:29], vcc
	s_xor_b64 s[28:29], exec, s[28:29]
	v_add_u32_e32 v136, 0xffffff10, v191
	v_add_u32_e32 v140, 0x400, v166
	v_and_b32_e32 v140, 0xf80, v140
	v_lshrrev_b32_e32 v136, 6, v136
	v_add3_u32 v140, v136, s34, v140
	s_andn2_saveexec_b64 s[28:29], s[28:29]
	v_add_u32_e32 v140, 0x2010, v190
	s_or_b64 exec, exec, s[28:29]
	v_mul_f32_e32 v136, 0x3d372713, v141
	v_mul_f32_e32 v136, v141, v136
	v_fma_f32 v136, v141, v136, v141
	v_mul_f32_e32 v136, 0x3f4c422a, v136
	v_add_f32_e32 v136, v136, v136
	v_mul_f32_e32 v136, 0x3fb8aa3b, v136
	v_exp_f32_e32 v136, v136
	v_mul_f32_e32 v167, 0.5, v141
	v_ashrrev_i32_e32 v141, 31, v140
	v_add_u32_e32 v192, 17, v191
	v_add_f32_e32 v136, 1.0, v136
	v_rcp_f32_e32 v136, v136
	v_lshlrev_b64 v[140:141], 12, v[140:141]
	v_lshl_add_u64 v[140:141], v[162:163], 0, v[140:141]
	v_cmp_lt_i32_e32 vcc, s30, v192
	v_fma_f32 v136, v136, -2.0, 1.0
	v_add_f32_e32 v136, 1.0, v136
	v_mul_f32_e32 v136, v167, v136
	v_cvt_pk_bf16_f32 v136, v136, s0
	global_store_short v[140:141], v136, off
	s_and_saveexec_b64 s[28:29], vcc
	s_xor_b64 s[28:29], exec, s[28:29]
	v_add_u32_e32 v136, 0xffffff11, v191
	v_add_u32_e32 v140, 0x440, v166
	v_and_b32_e32 v140, 0xfc0, v140
	v_lshrrev_b32_e32 v136, 6, v136
	v_add3_u32 v136, v136, s34, v140
	s_andn2_saveexec_b64 s[28:29], s[28:29]
	v_add_u32_e32 v136, 0x2011, v190
	s_or_b64 exec, exec, s[28:29]
	v_mul_f32_e32 v140, 0x3d372713, v137
	v_mul_f32_e32 v140, v137, v140
	v_fma_f32 v140, v137, v140, v137
	v_mul_f32_e32 v140, 0x3f4c422a, v140
	v_add_f32_e32 v140, v140, v140
	v_mul_f32_e32 v140, 0x3fb8aa3b, v140
	v_exp_f32_e32 v140, v140
	v_mul_f32_e32 v141, 0.5, v137
	v_ashrrev_i32_e32 v137, 31, v136
	v_add_u32_e32 v167, 32, v191
	v_add_f32_e32 v140, 1.0, v140
	v_rcp_f32_e32 v140, v140
	v_lshlrev_b64 v[136:137], 12, v[136:137]
	v_lshl_add_u64 v[136:137], v[162:163], 0, v[136:137]
	v_cmp_lt_i32_e32 vcc, s30, v167
	v_fma_f32 v140, v140, -2.0, 1.0
	v_add_f32_e32 v140, 1.0, v140
	v_mul_f32_e32 v140, v141, v140
	v_cvt_pk_bf16_f32 v140, v140, s0
	global_store_short v[136:137], v140, off
	s_and_saveexec_b64 s[28:29], vcc
	s_xor_b64 s[28:29], exec, s[28:29]
	v_add_u32_e32 v136, 0xffffff20, v191
	v_add_u32_e32 v137, 0x800, v166
	v_and_b32_e32 v137, 0xf80, v137
	v_lshrrev_b32_e32 v136, 6, v136
	v_add3_u32 v136, v136, s34, v137
	s_andn2_saveexec_b64 s[28:29], s[28:29]
	v_add_u32_e32 v136, 0x2020, v190
	s_or_b64 exec, exec, s[28:29]
	v_mul_f32_e32 v137, 0x3d372713, v142
	v_mul_f32_e32 v137, v142, v137
	v_fma_f32 v137, v142, v137, v142
	v_mul_f32_e32 v137, 0x3f4c422a, v137
	v_add_f32_e32 v137, v137, v137
	v_mul_f32_e32 v137, 0x3fb8aa3b, v137
	v_exp_f32_e32 v140, v137
	v_mul_f32_e32 v141, 0.5, v142
	v_ashrrev_i32_e32 v137, 31, v136
	v_add_u32_e32 v142, 33, v191
	v_add_f32_e32 v140, 1.0, v140
	v_rcp_f32_e32 v140, v140
	v_lshlrev_b64 v[136:137], 12, v[136:137]
	v_lshl_add_u64 v[136:137], v[162:163], 0, v[136:137]
	v_cmp_lt_i32_e32 vcc, s30, v142
	v_fma_f32 v140, v140, -2.0, 1.0
	v_add_f32_e32 v140, 1.0, v140
	v_mul_f32_e32 v140, v141, v140
	v_cvt_pk_bf16_f32 v140, v140, s0
	global_store_short v[136:137], v140, off
	s_and_saveexec_b64 s[28:29], vcc
	s_xor_b64 s[28:29], exec, s[28:29]
	v_add_u32_e32 v136, 0xffffff21, v191
	v_add_u32_e32 v137, 0x840, v166
	v_and_b32_e32 v137, 0xfc0, v137
	v_lshrrev_b32_e32 v136, 6, v136
	v_add3_u32 v136, v136, s34, v137
	s_andn2_saveexec_b64 s[28:29], s[28:29]
	v_add_u32_e32 v136, 0x2021, v190
	s_or_b64 exec, exec, s[28:29]
	v_mul_f32_e32 v137, 0x3d372713, v138
	v_mul_f32_e32 v137, v138, v137
	v_fma_f32 v137, v138, v137, v138
	v_mul_f32_e32 v137, 0x3f4c422a, v137
	v_add_f32_e32 v137, v137, v137
	v_mul_f32_e32 v137, 0x3fb8aa3b, v137
	v_exp_f32_e32 v140, v137
	v_mul_f32_e32 v138, 0.5, v138
	v_ashrrev_i32_e32 v137, 31, v136
	v_add_u32_e32 v141, 48, v191
	v_add_f32_e32 v140, 1.0, v140
	v_rcp_f32_e32 v140, v140
	v_lshlrev_b64 v[136:137], 12, v[136:137]
	v_lshl_add_u64 v[136:137], v[162:163], 0, v[136:137]
	v_cmp_lt_i32_e32 vcc, s30, v141
	v_fma_f32 v140, v140, -2.0, 1.0
	v_add_f32_e32 v140, 1.0, v140
	v_mul_f32_e32 v138, v138, v140
	v_cvt_pk_bf16_f32 v138, v138, s0
	global_store_short v[136:137], v138, off
	s_and_saveexec_b64 s[28:29], vcc
	s_xor_b64 s[28:29], exec, s[28:29]
	v_add_u32_e32 v136, 0xffffff30, v191
	v_add_u32_e32 v137, 0xc00, v166
	v_and_b32_e32 v137, 0xf80, v137
	v_lshrrev_b32_e32 v136, 6, v136
	v_add3_u32 v136, v136, s34, v137
	s_andn2_saveexec_b64 s[28:29], s[28:29]
	v_add_u32_e32 v136, 0x2030, v190
	s_or_b64 exec, exec, s[28:29]
	v_mul_f32_e32 v137, 0x3d372713, v143
	v_mul_f32_e32 v137, v143, v137
	v_fma_f32 v137, v143, v137, v143
	v_mul_f32_e32 v137, 0x3f4c422a, v137
	v_add_f32_e32 v137, v137, v137
	v_mul_f32_e32 v137, 0x3fb8aa3b, v137
	v_exp_f32_e32 v138, v137
	v_mul_f32_e32 v140, 0.5, v143
	v_ashrrev_i32_e32 v137, 31, v136
	v_add_u32_e32 v141, 49, v191
	v_add_f32_e32 v138, 1.0, v138
	v_rcp_f32_e32 v138, v138
	v_lshlrev_b64 v[136:137], 12, v[136:137]
	v_lshl_add_u64 v[136:137], v[162:163], 0, v[136:137]
	v_cmp_lt_i32_e32 vcc, s30, v141
	v_fma_f32 v138, v138, -2.0, 1.0
	v_add_f32_e32 v138, 1.0, v138
	v_mul_f32_e32 v138, v140, v138
	v_cvt_pk_bf16_f32 v138, v138, s0
	global_store_short v[136:137], v138, off
	s_and_saveexec_b64 s[28:29], vcc
	s_xor_b64 s[28:29], exec, s[28:29]
	v_add_u32_e32 v136, 0xffffff31, v191
	v_add_u32_e32 v137, 0xc40, v166
	v_and_b32_e32 v137, 0xfc0, v137
	v_lshrrev_b32_e32 v136, 6, v136
	v_add3_u32 v136, v136, s34, v137
	s_andn2_saveexec_b64 s[28:29], s[28:29]
	s_cbranch_execz .LBB0_3180
	v_add_u32_e32 v136, 0x2031, v190
	s_branch .LBB0_3180
